# experiment: sc1 (write-through) on all non-nt global stores so the barrier L2 write-back has nothing dirty
# baseline (speedup 1.0000x reference)
.Lmp_lo:
	s_waitcnt lgkmcnt(0)
	s_barrier
	s_cmp_lg_u32 s5, 0
	s_cbranch_scc1 .LBB0_24
	ds_read_b32 v34, v33
	ds_read_b32 v35, v33 offset:1024
	ds_read_b32 v36, v33 offset:2048
	ds_read_b32 v37, v33 offset:3072
	ds_read_b32 v38, v33 offset:4096
	s_mul_i32 s8, s4, 0x1e000
	s_lshl_b32 s9, s6, 8
	s_add_u32 s8, s8, s9
	s_add_u32 s8, s8, 0x1410000
	s_add_u32 s28, s24, s8
	s_addc_u32 s29, s25, 0
	s_waitcnt lgkmcnt(0)
	v_add_f32_e32 v10, v10, v34
	v_add_f32_e32 v11, v11, v35
	v_add_f32_e32 v8, v8, v36
	v_add_f32_e32 v9, v9, v37
	v_add_f32_e32 v22, v22, v38
	global_store_dword v27, v10, s[28:29] sc1
	s_add_u32 s28, s28, 0x3000
	s_addc_u32 s29, s29, 0
	global_store_dword v27, v11, s[28:29] sc1
	s_add_u32 s28, s28, 0x3000
	s_addc_u32 s29, s29, 0
	global_store_dword v27, v8, s[28:29] sc1
	s_add_u32 s28, s28, 0x3000
	s_addc_u32 s29, s29, 0
	global_store_dword v27, v9, s[28:29] sc1
	s_add_u32 s28, s28, 0x3000
	s_addc_u32 s29, s29, 0
	global_store_dword v27, v22, s[28:29] sc1
	s_branch .LBB0_24

.LBB0_21:
	v_readfirstlane_b32 s98, v12
	v_readfirstlane_b32 s99, v13
	v_and_b32_e32 v27, 63, v18
	v_lshlrev_b32_e32 v27, 2, v27
	s_nop 3
	global_load_dword v132, v27, s[98:99] nt
	s_add_u32 s98, s98, 0x3000
	s_addc_u32 s99, s99, 0
	global_load_dword v133, v27, s[98:99] nt
	s_add_u32 s98, s98, 0x3000
	s_addc_u32 s99, s99, 0
	global_load_dword v134, v27, s[98:99] nt
	s_add_u32 s98, s98, 0x3000
	s_addc_u32 s99, s99, 0
	global_load_dword v135, v27, s[98:99] nt
	s_add_u32 s98, s98, 0x3000
	s_addc_u32 s99, s99, 0
	global_load_dword v136, v27, s[98:99] nt
	s_add_u32 s98, s98, 0x3000
	s_addc_u32 s99, s99, 0
	global_load_dword v137, v27, s[98:99] nt
	s_add_u32 s98, s98, 0x3000
	s_addc_u32 s99, s99, 0
	global_load_dword v138, v27, s[98:99] nt
	s_add_u32 s98, s98, 0x3000
	s_addc_u32 s99, s99, 0
	global_load_dword v139, v27, s[98:99] nt
	s_add_u32 s98, s98, 0x3000
	s_addc_u32 s99, s99, 0
	global_load_dword v140, v27, s[98:99] nt
	s_add_u32 s98, s98, 0x3000
	s_addc_u32 s99, s99, 0
	global_load_dword v141, v27, s[98:99] nt
	s_add_u32 s98, s98, 0x3000
	s_addc_u32 s99, s99, 0
	global_load_dword v142, v27, s[98:99] nt
	s_add_u32 s98, s98, 0x3000
	s_addc_u32 s99, s99, 0
	global_load_dword v143, v27, s[98:99] nt
	s_add_u32 s98, s98, 0x3000
	s_addc_u32 s99, s99, 0
	global_load_dword v144, v27, s[98:99] nt
	s_add_u32 s98, s98, 0x3000
	s_addc_u32 s99, s99, 0
	global_load_dword v145, v27, s[98:99] nt
	s_add_u32 s98, s98, 0x3000
	s_addc_u32 s99, s99, 0
	global_load_dword v146, v27, s[98:99] nt
	s_add_u32 s98, s98, 0x3000
	s_addc_u32 s99, s99, 0
	global_load_dword v147, v27, s[98:99] nt
	s_add_u32 s98, s98, 0x3000
	s_addc_u32 s99, s99, 0
	global_load_dword v148, v27, s[98:99] nt
	s_add_u32 s98, s98, 0x3000
	s_addc_u32 s99, s99, 0
	global_load_dword v149, v27, s[98:99] nt
	s_add_u32 s98, s98, 0x3000
	s_addc_u32 s99, s99, 0
	global_load_dword v150, v27, s[98:99] nt
	s_add_u32 s98, s98, 0x3000
	s_addc_u32 s99, s99, 0
	global_load_dword v151, v27, s[98:99] nt
	s_add_u32 s98, s98, 0x3000
	s_addc_u32 s99, s99, 0
	global_load_dword v152, v27, s[98:99] nt
	s_add_u32 s98, s98, 0x3000
	s_addc_u32 s99, s99, 0
	global_load_dword v153, v27, s[98:99] nt
	s_add_u32 s98, s98, 0x3000
	s_addc_u32 s99, s99, 0
	global_load_dword v154, v27, s[98:99] nt
	s_add_u32 s98, s98, 0x3000
	s_addc_u32 s99, s99, 0
	global_load_dword v155, v27, s[98:99] nt
	s_add_u32 s98, s98, 0x3000
	s_addc_u32 s99, s99, 0
	global_load_dword v156, v27, s[98:99] nt
	s_add_u32 s98, s98, 0x3000
	s_addc_u32 s99, s99, 0
	global_load_dword v157, v27, s[98:99] nt
	s_add_u32 s98, s98, 0x3000
	s_addc_u32 s99, s99, 0
	global_load_dword v158, v27, s[98:99] nt
	s_add_u32 s98, s98, 0x3000
	s_addc_u32 s99, s99, 0
	global_load_dword v159, v27, s[98:99] nt
	s_add_u32 s98, s98, 0x3000
	s_addc_u32 s99, s99, 0
	global_load_dword v160, v27, s[98:99] nt
	s_add_u32 s98, s98, 0x3000
	s_addc_u32 s99, s99, 0
	global_load_dword v161, v27, s[98:99] nt
	s_add_u32 s98, s98, 0x3000
	s_addc_u32 s99, s99, 0
	global_load_dword v162, v27, s[98:99] nt
	s_add_u32 s98, s98, 0x3000
	s_addc_u32 s99, s99, 0
	global_load_dword v163, v27, s[98:99] nt
	s_add_u32 s98, s98, 0x3000
	s_addc_u32 s99, s99, 0
	global_load_dword v164, v27, s[98:99] nt
	s_add_u32 s98, s98, 0x3000
	s_addc_u32 s99, s99, 0
	global_load_dword v165, v27, s[98:99] nt
	s_add_u32 s98, s98, 0x3000
	s_addc_u32 s99, s99, 0
	global_load_dword v166, v27, s[98:99] nt
	s_add_u32 s98, s98, 0x3000
	s_addc_u32 s99, s99, 0
	global_load_dword v167, v27, s[98:99] nt
	s_add_u32 s98, s98, 0x3000
	s_addc_u32 s99, s99, 0
	global_load_dword v168, v27, s[98:99] nt
	s_add_u32 s98, s98, 0x3000
	s_addc_u32 s99, s99, 0
	global_load_dword v169, v27, s[98:99] nt
	s_add_u32 s98, s98, 0x3000
	s_addc_u32 s99, s99, 0
	global_load_dword v170, v27, s[98:99] nt
	s_add_u32 s98, s98, 0x3000
	s_addc_u32 s99, s99, 0
	global_load_dword v171, v27, s[98:99] nt
	s_add_u32 s98, s98, 0x3000
	s_addc_u32 s99, s99, 0
	global_load_dword v172, v27, s[98:99] nt
	s_add_u32 s98, s98, 0x3000
	s_addc_u32 s99, s99, 0
	global_load_dword v173, v27, s[98:99] nt
	s_add_u32 s98, s98, 0x3000
	s_addc_u32 s99, s99, 0
	global_load_dword v174, v27, s[98:99] nt
	s_add_u32 s98, s98, 0x3000
	s_addc_u32 s99, s99, 0
	global_load_dword v175, v27, s[98:99] nt
	s_add_u32 s98, s98, 0x3000
	s_addc_u32 s99, s99, 0
	global_load_dword v176, v27, s[98:99] nt
	s_add_u32 s98, s98, 0x3000
	s_addc_u32 s99, s99, 0
	global_load_dword v177, v27, s[98:99] nt
	s_add_u32 s98, s98, 0x3000
	s_addc_u32 s99, s99, 0
	global_load_dword v178, v27, s[98:99] nt
	s_add_u32 s98, s98, 0x3000
	s_addc_u32 s99, s99, 0
	global_load_dword v179, v27, s[98:99] nt
	s_add_u32 s98, s98, 0x3000
	s_addc_u32 s99, s99, 0
	global_load_dword v180, v27, s[98:99] nt
	s_add_u32 s98, s98, 0x3000
	s_addc_u32 s99, s99, 0
	global_load_dword v181, v27, s[98:99] nt
	s_add_u32 s98, s98, 0x3000
	s_addc_u32 s99, s99, 0
	global_load_dword v182, v27, s[98:99] nt
	s_add_u32 s98, s98, 0x3000
	s_addc_u32 s99, s99, 0
	global_load_dword v183, v27, s[98:99] nt
	s_add_u32 s98, s98, 0x3000
	s_addc_u32 s99, s99, 0
	global_load_dword v184, v27, s[98:99] nt
	s_add_u32 s98, s98, 0x3000
	s_addc_u32 s99, s99, 0
	global_load_dword v185, v27, s[98:99] nt
	s_add_u32 s98, s98, 0x3000
	s_addc_u32 s99, s99, 0
	global_load_dword v186, v27, s[98:99] nt
	s_add_u32 s98, s98, 0x3000
	s_addc_u32 s99, s99, 0
	global_load_dword v187, v27, s[98:99] nt
	s_add_u32 s98, s98, 0x3000
	s_addc_u32 s99, s99, 0
	global_load_dword v188, v27, s[98:99] nt
	s_add_u32 s98, s98, 0x3000
	s_addc_u32 s99, s99, 0
	global_load_dword v189, v27, s[98:99] nt
	s_add_u32 s98, s98, 0x3000
	s_addc_u32 s99, s99, 0
	global_load_dword v190, v27, s[98:99] nt
	s_add_u32 s98, s98, 0x3000
	s_addc_u32 s99, s99, 0
	global_load_dword v191, v27, s[98:99] nt
	s_add_u32 s98, s98, 0x3000
	s_addc_u32 s99, s99, 0
	global_load_dword v192, v27, s[98:99] nt
	s_add_u32 s98, s98, 0x3000
	s_addc_u32 s99, s99, 0
	global_load_dword v193, v27, s[98:99] nt
	s_add_u32 s98, s98, 0x3000
	s_addc_u32 s99, s99, 0
	global_load_dword v194, v27, s[98:99] nt
	s_add_u32 s98, s98, 0x3000
	s_addc_u32 s99, s99, 0
	global_load_dword v195, v27, s[98:99] nt
	v_readlane_b32 s12, v0, 0
	v_readlane_b32 s13, v23, 0
	v_readlane_b32 s14, v24, 0
	v_readlane_b32 s15, v25, 0
	v_readlane_b32 s16, v26, 0
	s_waitcnt vmcnt(63)
	v_pk_fma_f32 v[10:11], v[132:133], s[12:13], v[10:11] op_sel_hi:[0,1,1]
	v_pk_fma_f32 v[8:9], v[132:133], s[14:15], v[8:9] op_sel_hi:[0,1,1]
	v_fmac_f32_e32 v22, s16, v132
	v_readlane_b32 s12, v0, 1
	v_readlane_b32 s13, v23, 1
	v_readlane_b32 s14, v24, 1
	v_readlane_b32 s15, v25, 1
	v_readlane_b32 s16, v26, 1
	s_waitcnt vmcnt(62)
	v_pk_fma_f32 v[10:11], v[132:133], s[12:13], v[10:11] op_sel:[1,0,0] op_sel_hi:[1,1,1]
	v_pk_fma_f32 v[8:9], v[132:133], s[14:15], v[8:9] op_sel:[1,0,0] op_sel_hi:[1,1,1]
	v_fmac_f32_e32 v22, s16, v133
	v_readlane_b32 s12, v0, 2
	v_readlane_b32 s13, v23, 2
	v_readlane_b32 s14, v24, 2
	v_readlane_b32 s15, v25, 2
	v_readlane_b32 s16, v26, 2
	s_waitcnt vmcnt(61)
	v_pk_fma_f32 v[10:11], v[134:135], s[12:13], v[10:11] op_sel_hi:[0,1,1]
	v_pk_fma_f32 v[8:9], v[134:135], s[14:15], v[8:9] op_sel_hi:[0,1,1]
	v_fmac_f32_e32 v22, s16, v134
	v_readlane_b32 s12, v0, 3
	v_readlane_b32 s13, v23, 3
	v_readlane_b32 s14, v24, 3
	v_readlane_b32 s15, v25, 3
	v_readlane_b32 s16, v26, 3
	s_waitcnt vmcnt(60)
	v_pk_fma_f32 v[10:11], v[134:135], s[12:13], v[10:11] op_sel:[1,0,0] op_sel_hi:[1,1,1]
	v_pk_fma_f32 v[8:9], v[134:135], s[14:15], v[8:9] op_sel:[1,0,0] op_sel_hi:[1,1,1]
	v_fmac_f32_e32 v22, s16, v135
	v_readlane_b32 s12, v0, 4
	v_readlane_b32 s13, v23, 4
	v_readlane_b32 s14, v24, 4
	v_readlane_b32 s15, v25, 4
	v_readlane_b32 s16, v26, 4
	s_waitcnt vmcnt(59)
	v_pk_fma_f32 v[10:11], v[136:137], s[12:13], v[10:11] op_sel_hi:[0,1,1]
	v_pk_fma_f32 v[8:9], v[136:137], s[14:15], v[8:9] op_sel_hi:[0,1,1]
	v_fmac_f32_e32 v22, s16, v136
	v_readlane_b32 s12, v0, 5
	v_readlane_b32 s13, v23, 5
	v_readlane_b32 s14, v24, 5
	v_readlane_b32 s15, v25, 5
	v_readlane_b32 s16, v26, 5
	s_waitcnt vmcnt(58)
	v_pk_fma_f32 v[10:11], v[136:137], s[12:13], v[10:11] op_sel:[1,0,0] op_sel_hi:[1,1,1]
	v_pk_fma_f32 v[8:9], v[136:137], s[14:15], v[8:9] op_sel:[1,0,0] op_sel_hi:[1,1,1]
	v_fmac_f32_e32 v22, s16, v137
	v_readlane_b32 s12, v0, 6
	v_readlane_b32 s13, v23, 6
	v_readlane_b32 s14, v24, 6
	v_readlane_b32 s15, v25, 6
	v_readlane_b32 s16, v26, 6
	s_waitcnt vmcnt(57)
	v_pk_fma_f32 v[10:11], v[138:139], s[12:13], v[10:11] op_sel_hi:[0,1,1]
	v_pk_fma_f32 v[8:9], v[138:139], s[14:15], v[8:9] op_sel_hi:[0,1,1]
	v_fmac_f32_e32 v22, s16, v138
	v_readlane_b32 s12, v0, 7
	v_readlane_b32 s13, v23, 7
	v_readlane_b32 s14, v24, 7
	v_readlane_b32 s15, v25, 7
	v_readlane_b32 s16, v26, 7
	s_waitcnt vmcnt(56)
	v_pk_fma_f32 v[10:11], v[138:139], s[12:13], v[10:11] op_sel:[1,0,0] op_sel_hi:[1,1,1]
	v_pk_fma_f32 v[8:9], v[138:139], s[14:15], v[8:9] op_sel:[1,0,0] op_sel_hi:[1,1,1]
	v_fmac_f32_e32 v22, s16, v139
	v_readlane_b32 s12, v0, 8
	v_readlane_b32 s13, v23, 8
	v_readlane_b32 s14, v24, 8
	v_readlane_b32 s15, v25, 8
	v_readlane_b32 s16, v26, 8
	s_waitcnt vmcnt(55)
	v_pk_fma_f32 v[10:11], v[140:141], s[12:13], v[10:11] op_sel_hi:[0,1,1]
	v_pk_fma_f32 v[8:9], v[140:141], s[14:15], v[8:9] op_sel_hi:[0,1,1]
	v_fmac_f32_e32 v22, s16, v140
	v_readlane_b32 s12, v0, 9
	v_readlane_b32 s13, v23, 9
	v_readlane_b32 s14, v24, 9
	v_readlane_b32 s15, v25, 9
	v_readlane_b32 s16, v26, 9
	s_waitcnt vmcnt(54)
	v_pk_fma_f32 v[10:11], v[140:141], s[12:13], v[10:11] op_sel:[1,0,0] op_sel_hi:[1,1,1]
	v_pk_fma_f32 v[8:9], v[140:141], s[14:15], v[8:9] op_sel:[1,0,0] op_sel_hi:[1,1,1]
	v_fmac_f32_e32 v22, s16, v141
	v_readlane_b32 s12, v0, 10
	v_readlane_b32 s13, v23, 10
	v_readlane_b32 s14, v24, 10
	v_readlane_b32 s15, v25, 10
	v_readlane_b32 s16, v26, 10
	s_waitcnt vmcnt(53)
	v_pk_fma_f32 v[10:11], v[142:143], s[12:13], v[10:11] op_sel_hi:[0,1,1]
	v_pk_fma_f32 v[8:9], v[142:143], s[14:15], v[8:9] op_sel_hi:[0,1,1]
	v_fmac_f32_e32 v22, s16, v142
	v_readlane_b32 s12, v0, 11
	v_readlane_b32 s13, v23, 11
	v_readlane_b32 s14, v24, 11
	v_readlane_b32 s15, v25, 11
	v_readlane_b32 s16, v26, 11
	s_waitcnt vmcnt(52)
	v_pk_fma_f32 v[10:11], v[142:143], s[12:13], v[10:11] op_sel:[1,0,0] op_sel_hi:[1,1,1]
	v_pk_fma_f32 v[8:9], v[142:143], s[14:15], v[8:9] op_sel:[1,0,0] op_sel_hi:[1,1,1]
	v_fmac_f32_e32 v22, s16, v143
	v_readlane_b32 s12, v0, 12
	v_readlane_b32 s13, v23, 12
	v_readlane_b32 s14, v24, 12
	v_readlane_b32 s15, v25, 12
	v_readlane_b32 s16, v26, 12
	s_waitcnt vmcnt(51)
	v_pk_fma_f32 v[10:11], v[144:145], s[12:13], v[10:11] op_sel_hi:[0,1,1]
	v_pk_fma_f32 v[8:9], v[144:145], s[14:15], v[8:9] op_sel_hi:[0,1,1]
	v_fmac_f32_e32 v22, s16, v144
	v_readlane_b32 s12, v0, 13
	v_readlane_b32 s13, v23, 13
	v_readlane_b32 s14, v24, 13
	v_readlane_b32 s15, v25, 13
	v_readlane_b32 s16, v26, 13
	s_waitcnt vmcnt(50)
	v_pk_fma_f32 v[10:11], v[144:145], s[12:13], v[10:11] op_sel:[1,0,0] op_sel_hi:[1,1,1]
	v_pk_fma_f32 v[8:9], v[144:145], s[14:15], v[8:9] op_sel:[1,0,0] op_sel_hi:[1,1,1]
	v_fmac_f32_e32 v22, s16, v145
	v_readlane_b32 s12, v0, 14
	v_readlane_b32 s13, v23, 14
	v_readlane_b32 s14, v24, 14
	v_readlane_b32 s15, v25, 14
	v_readlane_b32 s16, v26, 14
	s_waitcnt vmcnt(49)
	v_pk_fma_f32 v[10:11], v[146:147], s[12:13], v[10:11] op_sel_hi:[0,1,1]
	v_pk_fma_f32 v[8:9], v[146:147], s[14:15], v[8:9] op_sel_hi:[0,1,1]
	v_fmac_f32_e32 v22, s16, v146
	v_readlane_b32 s12, v0, 15
	v_readlane_b32 s13, v23, 15
	v_readlane_b32 s14, v24, 15
	v_readlane_b32 s15, v25, 15
	v_readlane_b32 s16, v26, 15
	s_waitcnt vmcnt(48)
	v_pk_fma_f32 v[10:11], v[146:147], s[12:13], v[10:11] op_sel:[1,0,0] op_sel_hi:[1,1,1]
	v_pk_fma_f32 v[8:9], v[146:147], s[14:15], v[8:9] op_sel:[1,0,0] op_sel_hi:[1,1,1]
	v_fmac_f32_e32 v22, s16, v147
	v_readlane_b32 s12, v0, 16
	v_readlane_b32 s13, v23, 16
	v_readlane_b32 s14, v24, 16
	v_readlane_b32 s15, v25, 16
	v_readlane_b32 s16, v26, 16
	s_waitcnt vmcnt(47)
	v_pk_fma_f32 v[10:11], v[148:149], s[12:13], v[10:11] op_sel_hi:[0,1,1]
	v_pk_fma_f32 v[8:9], v[148:149], s[14:15], v[8:9] op_sel_hi:[0,1,1]
	v_fmac_f32_e32 v22, s16, v148
	v_readlane_b32 s12, v0, 17
	v_readlane_b32 s13, v23, 17
	v_readlane_b32 s14, v24, 17
	v_readlane_b32 s15, v25, 17
	v_readlane_b32 s16, v26, 17
	s_waitcnt vmcnt(46)
	v_pk_fma_f32 v[10:11], v[148:149], s[12:13], v[10:11] op_sel:[1,0,0] op_sel_hi:[1,1,1]
	v_pk_fma_f32 v[8:9], v[148:149], s[14:15], v[8:9] op_sel:[1,0,0] op_sel_hi:[1,1,1]
	v_fmac_f32_e32 v22, s16, v149
	v_readlane_b32 s12, v0, 18
	v_readlane_b32 s13, v23, 18
	v_readlane_b32 s14, v24, 18
	v_readlane_b32 s15, v25, 18
	v_readlane_b32 s16, v26, 18
	s_waitcnt vmcnt(45)
	v_pk_fma_f32 v[10:11], v[150:151], s[12:13], v[10:11] op_sel_hi:[0,1,1]
	v_pk_fma_f32 v[8:9], v[150:151], s[14:15], v[8:9] op_sel_hi:[0,1,1]
	v_fmac_f32_e32 v22, s16, v150
	v_readlane_b32 s12, v0, 19
	v_readlane_b32 s13, v23, 19
	v_readlane_b32 s14, v24, 19
	v_readlane_b32 s15, v25, 19
	v_readlane_b32 s16, v26, 19
	s_waitcnt vmcnt(44)
	v_pk_fma_f32 v[10:11], v[150:151], s[12:13], v[10:11] op_sel:[1,0,0] op_sel_hi:[1,1,1]
	v_pk_fma_f32 v[8:9], v[150:151], s[14:15], v[8:9] op_sel:[1,0,0] op_sel_hi:[1,1,1]
	v_fmac_f32_e32 v22, s16, v151
	v_readlane_b32 s12, v0, 20
	v_readlane_b32 s13, v23, 20
	v_readlane_b32 s14, v24, 20
	v_readlane_b32 s15, v25, 20
	v_readlane_b32 s16, v26, 20
	s_waitcnt vmcnt(43)
	v_pk_fma_f32 v[10:11], v[152:153], s[12:13], v[10:11] op_sel_hi:[0,1,1]
	v_pk_fma_f32 v[8:9], v[152:153], s[14:15], v[8:9] op_sel_hi:[0,1,1]
	v_fmac_f32_e32 v22, s16, v152
	v_readlane_b32 s12, v0, 21
	v_readlane_b32 s13, v23, 21
	v_readlane_b32 s14, v24, 21
	v_readlane_b32 s15, v25, 21
	v_readlane_b32 s16, v26, 21
	s_waitcnt vmcnt(42)
	v_pk_fma_f32 v[10:11], v[152:153], s[12:13], v[10:11] op_sel:[1,0,0] op_sel_hi:[1,1,1]
	v_pk_fma_f32 v[8:9], v[152:153], s[14:15], v[8:9] op_sel:[1,0,0] op_sel_hi:[1,1,1]
	v_fmac_f32_e32 v22, s16, v153
	v_readlane_b32 s12, v0, 22
	v_readlane_b32 s13, v23, 22
	v_readlane_b32 s14, v24, 22
	v_readlane_b32 s15, v25, 22
	v_readlane_b32 s16, v26, 22
	s_waitcnt vmcnt(41)
	v_pk_fma_f32 v[10:11], v[154:155], s[12:13], v[10:11] op_sel_hi:[0,1,1]
	v_pk_fma_f32 v[8:9], v[154:155], s[14:15], v[8:9] op_sel_hi:[0,1,1]
	v_fmac_f32_e32 v22, s16, v154
	v_readlane_b32 s12, v0, 23
	v_readlane_b32 s13, v23, 23
	v_readlane_b32 s14, v24, 23
	v_readlane_b32 s15, v25, 23
	v_readlane_b32 s16, v26, 23
	s_waitcnt vmcnt(40)
	v_pk_fma_f32 v[10:11], v[154:155], s[12:13], v[10:11] op_sel:[1,0,0] op_sel_hi:[1,1,1]
	v_pk_fma_f32 v[8:9], v[154:155], s[14:15], v[8:9] op_sel:[1,0,0] op_sel_hi:[1,1,1]
	v_fmac_f32_e32 v22, s16, v155
	v_readlane_b32 s12, v0, 24
	v_readlane_b32 s13, v23, 24
	v_readlane_b32 s14, v24, 24
	v_readlane_b32 s15, v25, 24
	v_readlane_b32 s16, v26, 24
	s_waitcnt vmcnt(39)
	v_pk_fma_f32 v[10:11], v[156:157], s[12:13], v[10:11] op_sel_hi:[0,1,1]
	v_pk_fma_f32 v[8:9], v[156:157], s[14:15], v[8:9] op_sel_hi:[0,1,1]
	v_fmac_f32_e32 v22, s16, v156
	v_readlane_b32 s12, v0, 25
	v_readlane_b32 s13, v23, 25
	v_readlane_b32 s14, v24, 25
	v_readlane_b32 s15, v25, 25
	v_readlane_b32 s16, v26, 25
	s_waitcnt vmcnt(38)
	v_pk_fma_f32 v[10:11], v[156:157], s[12:13], v[10:11] op_sel:[1,0,0] op_sel_hi:[1,1,1]
	v_pk_fma_f32 v[8:9], v[156:157], s[14:15], v[8:9] op_sel:[1,0,0] op_sel_hi:[1,1,1]
	v_fmac_f32_e32 v22, s16, v157
	v_readlane_b32 s12, v0, 26
	v_readlane_b32 s13, v23, 26
	v_readlane_b32 s14, v24, 26
	v_readlane_b32 s15, v25, 26
	v_readlane_b32 s16, v26, 26
	s_waitcnt vmcnt(37)
	v_pk_fma_f32 v[10:11], v[158:159], s[12:13], v[10:11] op_sel_hi:[0,1,1]
	v_pk_fma_f32 v[8:9], v[158:159], s[14:15], v[8:9] op_sel_hi:[0,1,1]
	v_fmac_f32_e32 v22, s16, v158
	v_readlane_b32 s12, v0, 27
	v_readlane_b32 s13, v23, 27
	v_readlane_b32 s14, v24, 27
	v_readlane_b32 s15, v25, 27
	v_readlane_b32 s16, v26, 27
	s_waitcnt vmcnt(36)
	v_pk_fma_f32 v[10:11], v[158:159], s[12:13], v[10:11] op_sel:[1,0,0] op_sel_hi:[1,1,1]
	v_pk_fma_f32 v[8:9], v[158:159], s[14:15], v[8:9] op_sel:[1,0,0] op_sel_hi:[1,1,1]
	v_fmac_f32_e32 v22, s16, v159
	v_readlane_b32 s12, v0, 28
	v_readlane_b32 s13, v23, 28
	v_readlane_b32 s14, v24, 28
	v_readlane_b32 s15, v25, 28
	v_readlane_b32 s16, v26, 28
	s_waitcnt vmcnt(35)
	v_pk_fma_f32 v[10:11], v[160:161], s[12:13], v[10:11] op_sel_hi:[0,1,1]
	v_pk_fma_f32 v[8:9], v[160:161], s[14:15], v[8:9] op_sel_hi:[0,1,1]
	v_fmac_f32_e32 v22, s16, v160
	v_readlane_b32 s12, v0, 29
	v_readlane_b32 s13, v23, 29
	v_readlane_b32 s14, v24, 29
	v_readlane_b32 s15, v25, 29
	v_readlane_b32 s16, v26, 29
	s_waitcnt vmcnt(34)
	v_pk_fma_f32 v[10:11], v[160:161], s[12:13], v[10:11] op_sel:[1,0,0] op_sel_hi:[1,1,1]
	v_pk_fma_f32 v[8:9], v[160:161], s[14:15], v[8:9] op_sel:[1,0,0] op_sel_hi:[1,1,1]
	v_fmac_f32_e32 v22, s16, v161
	v_readlane_b32 s12, v0, 30
	v_readlane_b32 s13, v23, 30
	v_readlane_b32 s14, v24, 30
	v_readlane_b32 s15, v25, 30
	v_readlane_b32 s16, v26, 30
	s_waitcnt vmcnt(33)
	v_pk_fma_f32 v[10:11], v[162:163], s[12:13], v[10:11] op_sel_hi:[0,1,1]
	v_pk_fma_f32 v[8:9], v[162:163], s[14:15], v[8:9] op_sel_hi:[0,1,1]
	v_fmac_f32_e32 v22, s16, v162
	v_readlane_b32 s12, v0, 31
	v_readlane_b32 s13, v23, 31
	v_readlane_b32 s14, v24, 31
	v_readlane_b32 s15, v25, 31
	v_readlane_b32 s16, v26, 31
	s_waitcnt vmcnt(32)
	v_pk_fma_f32 v[10:11], v[162:163], s[12:13], v[10:11] op_sel:[1,0,0] op_sel_hi:[1,1,1]
	v_pk_fma_f32 v[8:9], v[162:163], s[14:15], v[8:9] op_sel:[1,0,0] op_sel_hi:[1,1,1]
	v_fmac_f32_e32 v22, s16, v163
	v_readlane_b32 s12, v0, 32
	v_readlane_b32 s13, v23, 32
	v_readlane_b32 s14, v24, 32
	v_readlane_b32 s15, v25, 32
	v_readlane_b32 s16, v26, 32
	s_waitcnt vmcnt(31)
	v_pk_fma_f32 v[10:11], v[164:165], s[12:13], v[10:11] op_sel_hi:[0,1,1]
	v_pk_fma_f32 v[8:9], v[164:165], s[14:15], v[8:9] op_sel_hi:[0,1,1]
	v_fmac_f32_e32 v22, s16, v164
	v_readlane_b32 s12, v0, 33
	v_readlane_b32 s13, v23, 33
	v_readlane_b32 s14, v24, 33
	v_readlane_b32 s15, v25, 33
	v_readlane_b32 s16, v26, 33
	s_waitcnt vmcnt(30)
	v_pk_fma_f32 v[10:11], v[164:165], s[12:13], v[10:11] op_sel:[1,0,0] op_sel_hi:[1,1,1]
	v_pk_fma_f32 v[8:9], v[164:165], s[14:15], v[8:9] op_sel:[1,0,0] op_sel_hi:[1,1,1]
	v_fmac_f32_e32 v22, s16, v165
	v_readlane_b32 s12, v0, 34
	v_readlane_b32 s13, v23, 34
	v_readlane_b32 s14, v24, 34
	v_readlane_b32 s15, v25, 34
	v_readlane_b32 s16, v26, 34
	s_waitcnt vmcnt(29)
	v_pk_fma_f32 v[10:11], v[166:167], s[12:13], v[10:11] op_sel_hi:[0,1,1]
	v_pk_fma_f32 v[8:9], v[166:167], s[14:15], v[8:9] op_sel_hi:[0,1,1]
	v_fmac_f32_e32 v22, s16, v166
	v_readlane_b32 s12, v0, 35
	v_readlane_b32 s13, v23, 35
	v_readlane_b32 s14, v24, 35
	v_readlane_b32 s15, v25, 35
	v_readlane_b32 s16, v26, 35
	s_waitcnt vmcnt(28)
	v_pk_fma_f32 v[10:11], v[166:167], s[12:13], v[10:11] op_sel:[1,0,0] op_sel_hi:[1,1,1]
	v_pk_fma_f32 v[8:9], v[166:167], s[14:15], v[8:9] op_sel:[1,0,0] op_sel_hi:[1,1,1]
	v_fmac_f32_e32 v22, s16, v167
	v_readlane_b32 s12, v0, 36
	v_readlane_b32 s13, v23, 36
	v_readlane_b32 s14, v24, 36
	v_readlane_b32 s15, v25, 36
	v_readlane_b32 s16, v26, 36
	s_waitcnt vmcnt(27)
	v_pk_fma_f32 v[10:11], v[168:169], s[12:13], v[10:11] op_sel_hi:[0,1,1]
	v_pk_fma_f32 v[8:9], v[168:169], s[14:15], v[8:9] op_sel_hi:[0,1,1]
	v_fmac_f32_e32 v22, s16, v168
	v_readlane_b32 s12, v0, 37
	v_readlane_b32 s13, v23, 37
	v_readlane_b32 s14, v24, 37
	v_readlane_b32 s15, v25, 37
	v_readlane_b32 s16, v26, 37
	s_waitcnt vmcnt(26)
	v_pk_fma_f32 v[10:11], v[168:169], s[12:13], v[10:11] op_sel:[1,0,0] op_sel_hi:[1,1,1]
	v_pk_fma_f32 v[8:9], v[168:169], s[14:15], v[8:9] op_sel:[1,0,0] op_sel_hi:[1,1,1]
	v_fmac_f32_e32 v22, s16, v169
	v_readlane_b32 s12, v0, 38
	v_readlane_b32 s13, v23, 38
	v_readlane_b32 s14, v24, 38
	v_readlane_b32 s15, v25, 38
	v_readlane_b32 s16, v26, 38
	s_waitcnt vmcnt(25)
	v_pk_fma_f32 v[10:11], v[170:171], s[12:13], v[10:11] op_sel_hi:[0,1,1]
	v_pk_fma_f32 v[8:9], v[170:171], s[14:15], v[8:9] op_sel_hi:[0,1,1]
	v_fmac_f32_e32 v22, s16, v170
	v_readlane_b32 s12, v0, 39
	v_readlane_b32 s13, v23, 39
	v_readlane_b32 s14, v24, 39
	v_readlane_b32 s15, v25, 39
	v_readlane_b32 s16, v26, 39
	s_waitcnt vmcnt(24)
	v_pk_fma_f32 v[10:11], v[170:171], s[12:13], v[10:11] op_sel:[1,0,0] op_sel_hi:[1,1,1]
	v_pk_fma_f32 v[8:9], v[170:171], s[14:15], v[8:9] op_sel:[1,0,0] op_sel_hi:[1,1,1]
	v_fmac_f32_e32 v22, s16, v171
	v_readlane_b32 s12, v0, 40
	v_readlane_b32 s13, v23, 40
	v_readlane_b32 s14, v24, 40
	v_readlane_b32 s15, v25, 40
	v_readlane_b32 s16, v26, 40
	s_waitcnt vmcnt(23)
	v_pk_fma_f32 v[10:11], v[172:173], s[12:13], v[10:11] op_sel_hi:[0,1,1]
	v_pk_fma_f32 v[8:9], v[172:173], s[14:15], v[8:9] op_sel_hi:[0,1,1]
	v_fmac_f32_e32 v22, s16, v172
	v_readlane_b32 s12, v0, 41
	v_readlane_b32 s13, v23, 41
	v_readlane_b32 s14, v24, 41
	v_readlane_b32 s15, v25, 41
	v_readlane_b32 s16, v26, 41
	s_waitcnt vmcnt(22)
	v_pk_fma_f32 v[10:11], v[172:173], s[12:13], v[10:11] op_sel:[1,0,0] op_sel_hi:[1,1,1]
	v_pk_fma_f32 v[8:9], v[172:173], s[14:15], v[8:9] op_sel:[1,0,0] op_sel_hi:[1,1,1]
	v_fmac_f32_e32 v22, s16, v173
	v_readlane_b32 s12, v0, 42
	v_readlane_b32 s13, v23, 42
	v_readlane_b32 s14, v24, 42
	v_readlane_b32 s15, v25, 42
	v_readlane_b32 s16, v26, 42
	s_waitcnt vmcnt(21)
	v_pk_fma_f32 v[10:11], v[174:175], s[12:13], v[10:11] op_sel_hi:[0,1,1]
	v_pk_fma_f32 v[8:9], v[174:175], s[14:15], v[8:9] op_sel_hi:[0,1,1]
	v_fmac_f32_e32 v22, s16, v174
	v_readlane_b32 s12, v0, 43
	v_readlane_b32 s13, v23, 43
	v_readlane_b32 s14, v24, 43
	v_readlane_b32 s15, v25, 43
	v_readlane_b32 s16, v26, 43
	s_waitcnt vmcnt(20)
	v_pk_fma_f32 v[10:11], v[174:175], s[12:13], v[10:11] op_sel:[1,0,0] op_sel_hi:[1,1,1]
	v_pk_fma_f32 v[8:9], v[174:175], s[14:15], v[8:9] op_sel:[1,0,0] op_sel_hi:[1,1,1]
	v_fmac_f32_e32 v22, s16, v175
	v_readlane_b32 s12, v0, 44
	v_readlane_b32 s13, v23, 44
	v_readlane_b32 s14, v24, 44
	v_readlane_b32 s15, v25, 44
	v_readlane_b32 s16, v26, 44
	s_waitcnt vmcnt(19)
	v_pk_fma_f32 v[10:11], v[176:177], s[12:13], v[10:11] op_sel_hi:[0,1,1]
	v_pk_fma_f32 v[8:9], v[176:177], s[14:15], v[8:9] op_sel_hi:[0,1,1]
	v_fmac_f32_e32 v22, s16, v176
	v_readlane_b32 s12, v0, 45
	v_readlane_b32 s13, v23, 45
	v_readlane_b32 s14, v24, 45
	v_readlane_b32 s15, v25, 45
	v_readlane_b32 s16, v26, 45
	s_waitcnt vmcnt(18)
	v_pk_fma_f32 v[10:11], v[176:177], s[12:13], v[10:11] op_sel:[1,0,0] op_sel_hi:[1,1,1]
	v_pk_fma_f32 v[8:9], v[176:177], s[14:15], v[8:9] op_sel:[1,0,0] op_sel_hi:[1,1,1]
	v_fmac_f32_e32 v22, s16, v177
	v_readlane_b32 s12, v0, 46
	v_readlane_b32 s13, v23, 46
	v_readlane_b32 s14, v24, 46
	v_readlane_b32 s15, v25, 46
	v_readlane_b32 s16, v26, 46
	s_waitcnt vmcnt(17)
	v_pk_fma_f32 v[10:11], v[178:179], s[12:13], v[10:11] op_sel_hi:[0,1,1]
	v_pk_fma_f32 v[8:9], v[178:179], s[14:15], v[8:9] op_sel_hi:[0,1,1]
	v_fmac_f32_e32 v22, s16, v178
	v_readlane_b32 s12, v0, 47
	v_readlane_b32 s13, v23, 47
	v_readlane_b32 s14, v24, 47
	v_readlane_b32 s15, v25, 47
	v_readlane_b32 s16, v26, 47
	s_waitcnt vmcnt(16)
	v_pk_fma_f32 v[10:11], v[178:179], s[12:13], v[10:11] op_sel:[1,0,0] op_sel_hi:[1,1,1]
	v_pk_fma_f32 v[8:9], v[178:179], s[14:15], v[8:9] op_sel:[1,0,0] op_sel_hi:[1,1,1]
	v_fmac_f32_e32 v22, s16, v179
	v_readlane_b32 s12, v0, 48
	v_readlane_b32 s13, v23, 48
	v_readlane_b32 s14, v24, 48
	v_readlane_b32 s15, v25, 48
	v_readlane_b32 s16, v26, 48
	s_waitcnt vmcnt(15)
	v_pk_fma_f32 v[10:11], v[180:181], s[12:13], v[10:11] op_sel_hi:[0,1,1]
	v_pk_fma_f32 v[8:9], v[180:181], s[14:15], v[8:9] op_sel_hi:[0,1,1]
	v_fmac_f32_e32 v22, s16, v180
	v_readlane_b32 s12, v0, 49
	v_readlane_b32 s13, v23, 49
	v_readlane_b32 s14, v24, 49
	v_readlane_b32 s15, v25, 49
	v_readlane_b32 s16, v26, 49
	s_waitcnt vmcnt(14)
	v_pk_fma_f32 v[10:11], v[180:181], s[12:13], v[10:11] op_sel:[1,0,0] op_sel_hi:[1,1,1]
	v_pk_fma_f32 v[8:9], v[180:181], s[14:15], v[8:9] op_sel:[1,0,0] op_sel_hi:[1,1,1]
	v_fmac_f32_e32 v22, s16, v181
	v_readlane_b32 s12, v0, 50
	v_readlane_b32 s13, v23, 50
	v_readlane_b32 s14, v24, 50
	v_readlane_b32 s15, v25, 50
	v_readlane_b32 s16, v26, 50
	s_waitcnt vmcnt(13)
	v_pk_fma_f32 v[10:11], v[182:183], s[12:13], v[10:11] op_sel_hi:[0,1,1]
	v_pk_fma_f32 v[8:9], v[182:183], s[14:15], v[8:9] op_sel_hi:[0,1,1]
	v_fmac_f32_e32 v22, s16, v182
	v_readlane_b32 s12, v0, 51
	v_readlane_b32 s13, v23, 51
	v_readlane_b32 s14, v24, 51
	v_readlane_b32 s15, v25, 51
	v_readlane_b32 s16, v26, 51
	s_waitcnt vmcnt(12)
	v_pk_fma_f32 v[10:11], v[182:183], s[12:13], v[10:11] op_sel:[1,0,0] op_sel_hi:[1,1,1]
	v_pk_fma_f32 v[8:9], v[182:183], s[14:15], v[8:9] op_sel:[1,0,0] op_sel_hi:[1,1,1]
	v_fmac_f32_e32 v22, s16, v183
	v_readlane_b32 s12, v0, 52
	v_readlane_b32 s13, v23, 52
	v_readlane_b32 s14, v24, 52
	v_readlane_b32 s15, v25, 52
	v_readlane_b32 s16, v26, 52
	s_waitcnt vmcnt(11)
	v_pk_fma_f32 v[10:11], v[184:185], s[12:13], v[10:11] op_sel_hi:[0,1,1]
	v_pk_fma_f32 v[8:9], v[184:185], s[14:15], v[8:9] op_sel_hi:[0,1,1]
	v_fmac_f32_e32 v22, s16, v184
	v_readlane_b32 s12, v0, 53
	v_readlane_b32 s13, v23, 53
	v_readlane_b32 s14, v24, 53
	v_readlane_b32 s15, v25, 53
	v_readlane_b32 s16, v26, 53
	s_waitcnt vmcnt(10)
	v_pk_fma_f32 v[10:11], v[184:185], s[12:13], v[10:11] op_sel:[1,0,0] op_sel_hi:[1,1,1]
	v_pk_fma_f32 v[8:9], v[184:185], s[14:15], v[8:9] op_sel:[1,0,0] op_sel_hi:[1,1,1]
	v_fmac_f32_e32 v22, s16, v185
	v_readlane_b32 s12, v0, 54
	v_readlane_b32 s13, v23, 54
	v_readlane_b32 s14, v24, 54
	v_readlane_b32 s15, v25, 54
	v_readlane_b32 s16, v26, 54
	s_waitcnt vmcnt(9)
	v_pk_fma_f32 v[10:11], v[186:187], s[12:13], v[10:11] op_sel_hi:[0,1,1]
	v_pk_fma_f32 v[8:9], v[186:187], s[14:15], v[8:9] op_sel_hi:[0,1,1]
	v_fmac_f32_e32 v22, s16, v186
	v_readlane_b32 s12, v0, 55
	v_readlane_b32 s13, v23, 55
	v_readlane_b32 s14, v24, 55
	v_readlane_b32 s15, v25, 55
	v_readlane_b32 s16, v26, 55
	s_waitcnt vmcnt(8)
	v_pk_fma_f32 v[10:11], v[186:187], s[12:13], v[10:11] op_sel:[1,0,0] op_sel_hi:[1,1,1]
	v_pk_fma_f32 v[8:9], v[186:187], s[14:15], v[8:9] op_sel:[1,0,0] op_sel_hi:[1,1,1]
	v_fmac_f32_e32 v22, s16, v187
	v_readlane_b32 s12, v0, 56
	v_readlane_b32 s13, v23, 56
	v_readlane_b32 s14, v24, 56
	v_readlane_b32 s15, v25, 56
	v_readlane_b32 s16, v26, 56
	s_waitcnt vmcnt(7)
	v_pk_fma_f32 v[10:11], v[188:189], s[12:13], v[10:11] op_sel_hi:[0,1,1]
	v_pk_fma_f32 v[8:9], v[188:189], s[14:15], v[8:9] op_sel_hi:[0,1,1]
	v_fmac_f32_e32 v22, s16, v188
	v_readlane_b32 s12, v0, 57
	v_readlane_b32 s13, v23, 57
	v_readlane_b32 s14, v24, 57
	v_readlane_b32 s15, v25, 57
	v_readlane_b32 s16, v26, 57
	s_waitcnt vmcnt(6)
	v_pk_fma_f32 v[10:11], v[188:189], s[12:13], v[10:11] op_sel:[1,0,0] op_sel_hi:[1,1,1]
	v_pk_fma_f32 v[8:9], v[188:189], s[14:15], v[8:9] op_sel:[1,0,0] op_sel_hi:[1,1,1]
	v_fmac_f32_e32 v22, s16, v189
	v_readlane_b32 s12, v0, 58
	v_readlane_b32 s13, v23, 58
	v_readlane_b32 s14, v24, 58
	v_readlane_b32 s15, v25, 58
	v_readlane_b32 s16, v26, 58
	s_waitcnt vmcnt(5)
	v_pk_fma_f32 v[10:11], v[190:191], s[12:13], v[10:11] op_sel_hi:[0,1,1]
	v_pk_fma_f32 v[8:9], v[190:191], s[14:15], v[8:9] op_sel_hi:[0,1,1]
	v_fmac_f32_e32 v22, s16, v190
	v_readlane_b32 s12, v0, 59
	v_readlane_b32 s13, v23, 59
	v_readlane_b32 s14, v24, 59
	v_readlane_b32 s15, v25, 59
	v_readlane_b32 s16, v26, 59
	s_waitcnt vmcnt(4)
	v_pk_fma_f32 v[10:11], v[190:191], s[12:13], v[10:11] op_sel:[1,0,0] op_sel_hi:[1,1,1]
	v_pk_fma_f32 v[8:9], v[190:191], s[14:15], v[8:9] op_sel:[1,0,0] op_sel_hi:[1,1,1]
	v_fmac_f32_e32 v22, s16, v191
	v_readlane_b32 s12, v0, 60
	v_readlane_b32 s13, v23, 60
	v_readlane_b32 s14, v24, 60
	v_readlane_b32 s15, v25, 60
	v_readlane_b32 s16, v26, 60
	s_waitcnt vmcnt(3)
	v_pk_fma_f32 v[10:11], v[192:193], s[12:13], v[10:11] op_sel_hi:[0,1,1]
	v_pk_fma_f32 v[8:9], v[192:193], s[14:15], v[8:9] op_sel_hi:[0,1,1]
	v_fmac_f32_e32 v22, s16, v192
	v_readlane_b32 s12, v0, 61
	v_readlane_b32 s13, v23, 61
	v_readlane_b32 s14, v24, 61
	v_readlane_b32 s15, v25, 61
	v_readlane_b32 s16, v26, 61
	s_waitcnt vmcnt(2)
	v_pk_fma_f32 v[10:11], v[192:193], s[12:13], v[10:11] op_sel:[1,0,0] op_sel_hi:[1,1,1]
	v_pk_fma_f32 v[8:9], v[192:193], s[14:15], v[8:9] op_sel:[1,0,0] op_sel_hi:[1,1,1]
	v_fmac_f32_e32 v22, s16, v193
	v_readlane_b32 s12, v0, 62
	v_readlane_b32 s13, v23, 62
	v_readlane_b32 s14, v24, 62
	v_readlane_b32 s15, v25, 62
	v_readlane_b32 s16, v26, 62
	s_waitcnt vmcnt(1)
	v_pk_fma_f32 v[10:11], v[194:195], s[12:13], v[10:11] op_sel_hi:[0,1,1]
	v_pk_fma_f32 v[8:9], v[194:195], s[14:15], v[8:9] op_sel_hi:[0,1,1]
	v_fmac_f32_e32 v22, s16, v194
	v_readlane_b32 s12, v0, 63
	v_readlane_b32 s13, v23, 63
	v_readlane_b32 s14, v24, 63
	v_readlane_b32 s15, v25, 63
	v_readlane_b32 s16, v26, 63
	s_waitcnt vmcnt(0)
	v_pk_fma_f32 v[10:11], v[194:195], s[12:13], v[10:11] op_sel:[1,0,0] op_sel_hi:[1,1,1]
	v_pk_fma_f32 v[8:9], v[194:195], s[14:15], v[8:9] op_sel:[1,0,0] op_sel_hi:[1,1,1]
	v_fmac_f32_e32 v22, s16, v195
	s_movk_i32 s12, 0x6000
	s_mov_b32 s13, 0x9000
	s_mov_b32 s14, 0xc000
	s_mov_b32 s15, 0xf000
	s_mov_b32 s16, 0x12000
	s_mov_b32 s70, 64
	s_mov_b64 s[8:9], 0
	s_and_b64 vcc, exec, s[6:7]
	s_cbranch_vccz .LBB0_20
	v_lshlrev_b32_e32 v0, 3, v17
	v_and_b32_e32 v6, 0xffffffc0, v0
	v_ashrrev_i32_e32 v7, 31, v6
	v_lshl_add_u64 v[6:7], v[6:7], 2, v[2:3]
	v_add_co_u32_e32 v12, vcc, 0x3000, v6
	global_store_dword v[6:7], v10, off sc1
	s_nop 0
	v_addc_co_u32_e32 v13, vcc, 0, v7, vcc
	v_add_co_u32_e32 v10, vcc, 0x6000, v6
	global_store_dword v[12:13], v11, off sc1
	s_nop 0
	v_addc_co_u32_e32 v11, vcc, 0, v7, vcc
	global_store_dword v[10:11], v8, off sc1
	v_add_co_u32_e32 v10, vcc, 0x9000, v6
	v_add_u32_e32 v17, s33, v17
	s_nop 0
	v_addc_co_u32_e32 v11, vcc, 0, v7, vcc
	v_add_co_u32_e32 v6, vcc, 0xc000, v6
	v_add_u32_e32 v19, s3, v19
	s_nop 0
	v_addc_co_u32_e32 v7, vcc, 0, v7, vcc
	v_cmp_lt_i32_e32 vcc, s69, v17
	s_or_b64 s[4:5], vcc, s[4:5]
	global_store_dword v[10:11], v9, off sc1
	global_store_dword v[6:7], v22, off sc1
	s_andn2_b64 exec, exec, s[4:5]
	s_cbranch_execnz .LBB0_19

.LBB0_26:
	v_and_b32_e32 v8, 62, v1
	v_cvt_f32_ubyte0_e32 v8, v8
	v_mul_f32_e32 v10, 0xbe549a78, v8
	v_cmp_gt_f32_e64 s[0:1], s14, v10
	v_ashrrev_i32_e32 v7, 5, v0
	v_cvt_f32_i32_e32 v9, v7
	v_cndmask_b32_e64 v10, 0, v4, s[0:1]
	v_fmac_f32_e32 v10, 0xbe549a78, v8
	v_exp_f32_e32 v8, v10
	v_cndmask_b32_e64 v10, 0, v5, s[0:1]
	v_add_co_u32_e32 v6, vcc, 0x2000, v2
	v_ldexp_f32 v8, v8, v10
	v_mul_f32_e32 v8, v8, v9
	v_cvt_f64_f32_e32 v[8:9], v8
	v_mul_f64 v[10:11], v[8:9], s[10:11]
	v_rndne_f64_e32 v[10:11], v[10:11]
	v_fmac_f64_e32 v[8:9], s[12:13], v[10:11]
	v_cvt_f32_f64_e32 v8, v[8:9]
	v_mul_f32_e32 v8, 0.15915494, v8
	v_cos_f32_e32 v9, v8
	v_sin_f32_e32 v8, v8
	v_add_u32_e32 v0, s68, v0
	v_addc_co_u32_e32 v7, vcc, 0, v3, vcc
	v_cmp_lt_i32_e32 vcc, s15, v0
	v_add_u32_e32 v1, s3, v1
	s_or_b64 s[8:9], vcc, s[8:9]
	global_store_dword v[2:3], v9, off sc1
	global_store_dword v[6:7], v8, off sc1
	v_lshl_add_u64 v[2:3], v[2:3], 0, s[6:7]
	s_andn2_b64 exec, exec, s[8:9]
	s_cbranch_execnz .LBB0_26

.LBB0_38:
	s_or_b64 exec, exec, s[4:5]
	v_mul_lo_u32 v18, v21, s11
	v_add3_u32 v16, 0, v16, v18
	s_waitcnt vmcnt(0)
	ds_write2_b32 v16, v0, v1 offset1:1
	ds_write2_b32 v16, v2, v3 offset0:2 offset1:3
	v_add_u32_e32 v0, 0x2080, v16
	ds_write2_b32 v0, v8, v9 offset1:1
	v_add_u32_e32 v0, 0x2088, v16
	ds_write2_b32 v0, v10, v11 offset1:1
	v_add_u32_e32 v0, 0x4100, v16
	ds_write2_b32 v0, v4, v5 offset1:1
	v_add_u32_e32 v0, 0x4108, v16
	ds_write2_b32 v0, v6, v7 offset1:1
	v_add_u32_e32 v0, 0x6180, v16
	ds_write2_b32 v0, v12, v13 offset1:1
	v_add_u32_e32 v0, 0x6188, v16
	ds_write2_b32 v0, v14, v15 offset1:1
	v_ashrrev_i32_e32 v3, 3, v20
	v_lshlrev_b32_e32 v0, 3, v20
	s_mulk_i32 s1, 0x1040
	v_and_b32_e32 v1, 56, v0
	v_subrev_u32_e32 v0, s1, v3
	v_lshl_add_u32 v2, v3, 2, 0
	v_add_u32_e32 v0, s7, v0
	v_cmp_gt_i32_e32 vcc, s9, v0
	v_mad_u32_u24 v2, v1, s11, v2
	v_lshlrev_b32_e32 v16, 1, v1
	s_waitcnt lgkmcnt(0)
	s_barrier
	s_and_saveexec_b64 s[4:5], vcc
	s_cbranch_execz .LBB0_40
	v_add_u32_e32 v1, 0x400, v2
	ds_read2_b32 v[4:5], v2 offset1:65
	ds_read2_b32 v[6:7], v2 offset0:130 offset1:195
	ds_read2_b32 v[8:9], v1 offset0:4 offset1:69
	ds_read2_b32 v[10:11], v1 offset0:134 offset1:199
	v_ashrrev_i32_e32 v1, 31, v0
	v_lshlrev_b64 v[0:1], 11, v[0:1]
	v_lshl_add_u64 v[0:1], s[24:25], 0, v[0:1]
	s_ashr_i32 s1, s0, 31
	v_lshl_add_u64 v[0:1], s[0:1], 1, v[0:1]
	s_waitcnt lgkmcnt(3)
	v_cvt_pk_bf16_f32 v4, v4, v5
	s_waitcnt lgkmcnt(2)
	v_cvt_pk_bf16_f32 v5, v6, v7
	s_waitcnt lgkmcnt(1)
	v_cvt_pk_bf16_f32 v6, v8, v9
	s_waitcnt lgkmcnt(0)
	v_cvt_pk_bf16_f32 v7, v10, v11
	v_lshl_add_u64 v[0:1], v[0:1], 0, v[16:17]
	global_store_dwordx4 v[0:1], v[4:7], off sc1
.LBB0_40:
	s_or_b64 exec, exec, s[4:5]
	s_cmpk_lt_i32 s12, 0x410
	s_mul_hi_i32 s4, s12, 0x7e07e07f
	s_cselect_b64 s[0:1], -1, 0
	s_lshr_b32 s5, s4, 31
	s_ashr_i32 s4, s4, 5
	s_add_i32 s4, s4, s5
	s_mul_i32 s5, s4, 0x41
	s_sub_i32 s5, s12, s5
	v_lshl_add_u32 v0, s5, 6, v3
	v_cmp_gt_i32_e32 vcc, s9, v0
	s_and_b64 s[12:13], s[0:1], vcc
	s_and_saveexec_b64 s[0:1], s[12:13]
	s_cbranch_execz .LBB0_29
	v_add_u32_e32 v1, 0x4000, v2
	ds_read2_b32 v[4:5], v1 offset0:64 offset1:129
	v_add_u32_e32 v1, 0x4200, v2
	ds_read2_b32 v[6:7], v1 offset0:66 offset1:131
	v_add_u32_e32 v1, 0x4400, v2
	ds_read2_b32 v[8:9], v1 offset0:68 offset1:133
	v_add_u32_e32 v1, 0x4600, v2
	ds_read2_b32 v[10:11], v1 offset0:70 offset1:135
	v_ashrrev_i32_e32 v1, 31, v0
	s_lshl_b32 s4, s4, 6
	v_lshlrev_b64 v[0:1], 11, v[0:1]
	v_lshl_add_u64 v[0:1], s[24:25], 0, v[0:1]
	s_ashr_i32 s5, s4, 31
	v_lshl_add_u64 v[0:1], s[4:5], 1, v[0:1]
	s_waitcnt lgkmcnt(3)
	v_cvt_pk_bf16_f32 v2, v4, v5
	s_waitcnt lgkmcnt(2)
	v_cvt_pk_bf16_f32 v3, v6, v7
	s_waitcnt lgkmcnt(1)
	v_cvt_pk_bf16_f32 v4, v8, v9
	s_waitcnt lgkmcnt(0)
	v_cvt_pk_bf16_f32 v5, v10, v11
	v_lshl_add_u64 v[0:1], v[0:1], 0, v[16:17]
	global_store_dwordx4 v[0:1], v[2:5], off sc1
	s_branch .LBB0_29

.LBB0_96:
	v_add_co_u32_e32 v4, vcc, s10, v2
	v_mul_hi_i32 v11, v0, s8
	s_nop 0
	v_addc_co_u32_e32 v5, vcc, 0, v3, vcc
	v_add_co_u32_e32 v6, vcc, s11, v2
	v_mul_hi_i32 v1, v0, s3
	s_nop 0
	v_addc_co_u32_e32 v7, vcc, 0, v3, vcc
	v_add_co_u32_e32 v8, vcc, s12, v2
	v_lshrrev_b32_e32 v13, 31, v11
	s_nop 0
	v_addc_co_u32_e32 v9, vcc, 0, v3, vcc
	v_add_co_u32_e32 v10, vcc, s13, v2
	v_ashrrev_i32_e32 v14, 9, v11
	s_nop 0
	v_addc_co_u32_e32 v11, vcc, 0, v3, vcc
	global_load_dword v12, v[2:3], off
	v_add_u32_e32 v1, v1, v0
	global_load_dword v15, v[4:5], off
	global_load_dword v17, v[6:7], off
	s_nop 0
	global_load_dword v8, v[8:9], off
	v_add_co_u32_e32 v4, vcc, s14, v2
	v_add_u32_e32 v9, v14, v13
	v_lshrrev_b32_e32 v7, 31, v1
	v_ashrrev_i32_e32 v1, 13, v1
	v_addc_co_u32_e32 v5, vcc, 0, v3, vcc
	v_mul_i32_i24_e32 v9, 0xc00, v9
	global_load_dword v10, v[10:11], off
	v_add_u32_e32 v1, v1, v7
	global_load_dword v11, v[4:5], off
	v_sub_u32_e32 v4, v0, v9
	v_mad_i32_i24 v4, v1, s9, v4
	v_ashrrev_i32_e32 v5, 31, v4
	v_lshl_add_u64 v[4:5], v[4:5], 2, s[54:55]
	global_load_dword v1, v[4:5], off
	v_add_co_u32_e32 v6, vcc, s15, v2
	v_add_u32_e32 v0, s68, v0
	s_nop 0
	v_addc_co_u32_e32 v7, vcc, 0, v3, vcc
	v_add_co_u32_e32 v4, vcc, 0xd2000, v2
	s_waitcnt vmcnt(0)
	v_add_f32_e32 v1, v1, v12
	v_addc_co_u32_e32 v5, vcc, 0, v3, vcc
	global_load_dword v6, v[6:7], off
	s_nop 0
	global_load_dword v7, v[4:5], off
	v_add_f32_e32 v1, v1, v15
	v_add_f32_e32 v1, v1, v17
	v_add_f32_e32 v1, v1, v8
	v_add_co_u32_e32 v4, vcc, 0xf0000, v2
	v_add_f32_e32 v1, v1, v10
	s_nop 0
	v_addc_co_u32_e32 v5, vcc, 0, v3, vcc
	v_add_f32_e32 v1, v1, v11
	v_cmp_lt_i32_e32 vcc, s16, v0
	v_lshl_add_u64 v[2:3], v[2:3], 0, s[4:5]
	s_or_b64 s[6:7], vcc, s[6:7]
	s_waitcnt vmcnt(1)
	v_add_f32_e32 v1, v1, v6
	s_waitcnt vmcnt(0)
	v_add_f32_e32 v1, v1, v7
	global_store_dword v[4:5], v1, off sc1
	s_andn2_b64 exec, exec, s[6:7]
	s_cbranch_execnz .LBB0_96

.LBB0_99:
	s_or_b64 exec, exec, s[8:9]
	s_waitcnt vmcnt(7)
	v_mov_b32_e32 v50, v37
	s_waitcnt vmcnt(6)
	v_mov_b32_e32 v51, v33
	v_mov_b32_e32 v48, v36
	v_mov_b32_e32 v49, v32
	v_pk_mul_f32 v[50:51], v[50:51], v[50:51]
	s_waitcnt vmcnt(5)
	v_mov_b32_e32 v52, v29
	v_pk_fma_f32 v[48:49], v[48:49], v[48:49], v[50:51]
	v_mov_b32_e32 v50, v38
	v_mov_b32_e32 v51, v34
	v_pk_fma_f32 v[48:49], v[50:51], v[50:51], v[48:49]
	v_mov_b32_e32 v50, v39
	v_mov_b32_e32 v51, v35
	s_waitcnt vmcnt(4)
	v_mov_b32_e32 v53, v25
	v_pk_fma_f32 v[48:49], v[50:51], v[50:51], v[48:49]
	v_mov_b32_e32 v50, v28
	v_mov_b32_e32 v51, v24
	v_pk_mul_f32 v[52:53], v[52:53], v[52:53]
	v_add_f32_e32 v48, v48, v49
	v_pk_fma_f32 v[50:51], v[50:51], v[50:51], v[52:53]
	v_mov_b32_e32 v52, v30
	v_mov_b32_e32 v53, v26
	v_pk_fma_f32 v[50:51], v[52:53], v[52:53], v[50:51]
	v_mov_b32_e32 v52, v31
	v_mov_b32_e32 v53, v27
	v_pk_fma_f32 v[50:51], v[52:53], v[52:53], v[50:51]
	v_ashrrev_i32_e32 v163, 31, v162
	v_add_f32_e32 v48, v48, v50
	v_add_f32_e32 v48, v48, v51
	ds_bpermute_b32 v49, v178, v48
	v_lshlrev_b64 v[52:53], 11, v[162:163]
	v_lshl_add_u64 v[52:53], v[148:149], 0, v[52:53]
	s_waitcnt lgkmcnt(0)
	v_add_f32_e32 v48, v48, v49
	ds_bpermute_b32 v49, v179, v48
	s_waitcnt lgkmcnt(0)
	v_add_f32_e32 v48, v48, v49
	ds_bpermute_b32 v49, v180, v48
	s_waitcnt lgkmcnt(0)
	v_add_f32_e32 v48, v48, v49
	ds_bpermute_b32 v49, v181, v48
	s_waitcnt lgkmcnt(0)
	v_add_f32_e32 v48, v48, v49
	ds_bpermute_b32 v49, v182, v48
	s_waitcnt lgkmcnt(0)
	v_add_f32_e32 v50, v48, v49
	ds_bpermute_b32 v51, v183, v50
	v_pk_add_f32 v[48:49], v[22:23], 1.0 op_sel_hi:[1,0]
	s_waitcnt lgkmcnt(0)
	v_add_f32_e32 v50, v50, v51
	v_fmamk_f32 v50, v50, 0x3a800000, v184
	v_mul_f32_e32 v51, 0x4b800000, v50
	v_cmp_gt_f32_e32 vcc, s14, v50
	s_nop 1
	v_cndmask_b32_e32 v50, v50, v51, vcc
	v_rsq_f32_e32 v54, v50
	v_pk_add_f32 v[50:51], v[20:21], 1.0 op_sel_hi:[1,0]
	v_mul_f32_e32 v55, 0x45800000, v54
	v_cndmask_b32_e32 v54, v54, v55, vcc
	v_pk_mul_f32 v[38:39], v[38:39], v[54:55] op_sel_hi:[1,0]
	v_pk_mul_f32 v[36:37], v[36:37], v[54:55] op_sel_hi:[1,0]
	v_pk_mul_f32 v[38:39], v[2:3], v[38:39]
	v_pk_mul_f32 v[36:37], v[0:1], v[36:37]
	v_pk_fma_f32 v[38:39], v[48:49], v[38:39], v[18:19]
	v_pk_fma_f32 v[36:37], v[50:51], v[36:37], v[16:17]
	v_pk_mul_f32 v[34:35], v[34:35], v[54:55] op_sel_hi:[1,0]
	v_cvt_pk_bf16_f32 v36, v36, v37
	v_cvt_pk_bf16_f32 v37, v38, v39
	v_pk_mul_f32 v[32:33], v[32:33], v[54:55] op_sel_hi:[1,0]
	global_store_dwordx2 v[52:53], v[36:37], off sc1
	v_pk_mul_f32 v[32:33], v[4:5], v[32:33]
	v_pk_mul_f32 v[34:35], v[6:7], v[34:35]
	v_pk_add_f32 v[36:37], v[46:47], 1.0 op_sel_hi:[1,0]
	v_pk_add_f32 v[38:39], v[44:45], 1.0 op_sel_hi:[1,0]
	v_pk_fma_f32 v[34:35], v[36:37], v[34:35], v[42:43]
	v_pk_fma_f32 v[32:33], v[38:39], v[32:33], v[40:41]
	v_pk_mul_f32 v[30:31], v[30:31], v[54:55] op_sel_hi:[1,0]
	v_cvt_pk_bf16_f32 v32, v32, v33
	v_cvt_pk_bf16_f32 v33, v34, v35
	v_pk_mul_f32 v[28:29], v[28:29], v[54:55] op_sel_hi:[1,0]
	global_store_dwordx2 v[52:53], v[32:33], off offset:512 sc1
	v_pk_mul_f32 v[28:29], v[8:9], v[28:29]
	v_pk_mul_f32 v[30:31], v[10:11], v[30:31]
	v_pk_add_f32 v[32:33], v[70:71], 1.0 op_sel_hi:[1,0]
	v_pk_add_f32 v[34:35], v[68:69], 1.0 op_sel_hi:[1,0]
	v_pk_fma_f32 v[30:31], v[32:33], v[30:31], v[66:67]
	v_pk_fma_f32 v[28:29], v[34:35], v[28:29], v[64:65]
	v_pk_mul_f32 v[26:27], v[26:27], v[54:55] op_sel_hi:[1,0]
	v_cvt_pk_bf16_f32 v28, v28, v29
	v_cvt_pk_bf16_f32 v29, v30, v31
	v_pk_mul_f32 v[24:25], v[24:25], v[54:55] op_sel_hi:[1,0]
	global_store_dwordx2 v[52:53], v[28:29], off offset:1024 sc1
	v_pk_mul_f32 v[24:25], v[12:13], v[24:25]
	v_pk_mul_f32 v[26:27], v[14:15], v[26:27]
	v_pk_add_f32 v[28:29], v[94:95], 1.0 op_sel_hi:[1,0]
	v_pk_add_f32 v[30:31], v[92:93], 1.0 op_sel_hi:[1,0]
	v_pk_fma_f32 v[26:27], v[28:29], v[26:27], v[90:91]
	v_pk_fma_f32 v[24:25], v[30:31], v[24:25], v[88:89]
	s_nop 0
	v_cvt_pk_bf16_f32 v24, v24, v25
	v_cvt_pk_bf16_f32 v25, v26, v27
	global_store_dwordx2 v[52:53], v[24:25], off offset:1536 sc1

.LBB0_111:
	s_or_b64 exec, exec, s[6:7]
	s_waitcnt vmcnt(23)
	v_mov_b32_e32 v174, v141
	s_waitcnt vmcnt(22)
	v_mov_b32_e32 v175, v137
	v_mov_b32_e32 v172, v140
	v_mov_b32_e32 v173, v136
	v_pk_mul_f32 v[174:175], v[174:175], v[174:175]
	s_waitcnt vmcnt(21)
	v_mov_b32_e32 v186, v133
	v_pk_fma_f32 v[172:173], v[172:173], v[172:173], v[174:175]
	v_mov_b32_e32 v174, v142
	v_mov_b32_e32 v175, v138
	v_pk_fma_f32 v[172:173], v[174:175], v[174:175], v[172:173]
	v_mov_b32_e32 v174, v143
	v_mov_b32_e32 v175, v139
	s_waitcnt vmcnt(20)
	v_mov_b32_e32 v187, v129
	v_pk_fma_f32 v[172:173], v[174:175], v[174:175], v[172:173]
	v_mov_b32_e32 v174, v132
	v_mov_b32_e32 v175, v128
	v_pk_mul_f32 v[186:187], v[186:187], v[186:187]
	v_add_f32_e32 v145, v172, v173
	v_pk_fma_f32 v[174:175], v[174:175], v[174:175], v[186:187]
	v_mov_b32_e32 v186, v134
	v_mov_b32_e32 v187, v130
	v_pk_fma_f32 v[174:175], v[186:187], v[186:187], v[174:175]
	v_mov_b32_e32 v186, v135
	v_mov_b32_e32 v187, v131
	v_pk_fma_f32 v[174:175], v[186:187], v[186:187], v[174:175]
	v_pk_add_f32 v[172:173], v[22:23], 1.0 op_sel_hi:[1,0]
	v_add_f32_e32 v145, v145, v174
	v_add_f32_e32 v145, v145, v175
	ds_bpermute_b32 v163, v178, v145
	v_pk_add_f32 v[174:175], v[20:21], 1.0 op_sel_hi:[1,0]
	s_waitcnt lgkmcnt(0)
	v_add_f32_e32 v145, v145, v163
	ds_bpermute_b32 v163, v179, v145
	s_waitcnt lgkmcnt(0)
	v_add_f32_e32 v145, v145, v163
	ds_bpermute_b32 v163, v180, v145
	s_waitcnt lgkmcnt(0)
	v_add_f32_e32 v145, v145, v163
	ds_bpermute_b32 v163, v181, v145
	s_waitcnt lgkmcnt(0)
	v_add_f32_e32 v145, v145, v163
	ds_bpermute_b32 v163, v182, v145
	s_waitcnt lgkmcnt(0)
	v_add_f32_e32 v163, v145, v163
	ds_bpermute_b32 v165, v183, v163
	v_ashrrev_i32_e32 v145, 31, v144
	v_lshlrev_b64 v[186:187], 11, v[144:145]
	v_lshl_add_u64 v[186:187], v[148:149], 0, v[186:187]
	s_waitcnt lgkmcnt(0)
	v_add_f32_e32 v163, v163, v165
	v_fmamk_f32 v163, v163, 0x3a800000, v184
	v_mul_f32_e32 v165, 0x4b800000, v163
	v_cmp_gt_f32_e32 vcc, s14, v163
	s_nop 1
	v_cndmask_b32_e32 v163, v163, v165, vcc
	v_rsq_f32_e32 v163, v163
	s_nop 0
	v_mul_f32_e32 v145, 0x45800000, v163
	v_cndmask_b32_e32 v188, v163, v145, vcc
	v_pk_mul_f32 v[142:143], v[142:143], v[188:189] op_sel_hi:[1,0]
	v_pk_mul_f32 v[140:141], v[140:141], v[188:189] op_sel_hi:[1,0]
	v_pk_mul_f32 v[142:143], v[2:3], v[142:143]
	v_pk_mul_f32 v[140:141], v[0:1], v[140:141]
	v_pk_fma_f32 v[142:143], v[172:173], v[142:143], v[18:19]
	v_pk_fma_f32 v[140:141], v[174:175], v[140:141], v[16:17]
	v_pk_mul_f32 v[138:139], v[138:139], v[188:189] op_sel_hi:[1,0]
	v_cvt_pk_bf16_f32 v140, v140, v141
	v_cvt_pk_bf16_f32 v141, v142, v143
	v_pk_mul_f32 v[136:137], v[136:137], v[188:189] op_sel_hi:[1,0]
	global_store_dwordx2 v[186:187], v[140:141], off sc1
	v_pk_mul_f32 v[140:141], v[4:5], v[136:137]
	v_pk_mul_f32 v[142:143], v[6:7], v[138:139]
	v_pk_add_f32 v[136:137], v[46:47], 1.0 op_sel_hi:[1,0]
	v_pk_add_f32 v[138:139], v[44:45], 1.0 op_sel_hi:[1,0]
	v_pk_fma_f32 v[142:143], v[136:137], v[142:143], v[42:43]
	v_pk_fma_f32 v[140:141], v[138:139], v[140:141], v[40:41]
	v_pk_mul_f32 v[134:135], v[134:135], v[188:189] op_sel_hi:[1,0]
	v_cvt_pk_bf16_f32 v140, v140, v141
	v_cvt_pk_bf16_f32 v141, v142, v143
	v_pk_mul_f32 v[132:133], v[132:133], v[188:189] op_sel_hi:[1,0]
	global_store_dwordx2 v[186:187], v[140:141], off offset:512 sc1
	v_pk_mul_f32 v[140:141], v[8:9], v[132:133]
	v_pk_mul_f32 v[142:143], v[10:11], v[134:135]
	v_pk_add_f32 v[132:133], v[70:71], 1.0 op_sel_hi:[1,0]
	v_pk_add_f32 v[134:135], v[68:69], 1.0 op_sel_hi:[1,0]
	v_pk_fma_f32 v[142:143], v[132:133], v[142:143], v[66:67]
	v_pk_fma_f32 v[140:141], v[134:135], v[140:141], v[64:65]
	v_pk_mul_f32 v[130:131], v[130:131], v[188:189] op_sel_hi:[1,0]
	v_cvt_pk_bf16_f32 v140, v140, v141
	v_cvt_pk_bf16_f32 v141, v142, v143
	v_pk_mul_f32 v[128:129], v[128:129], v[188:189] op_sel_hi:[1,0]
	global_store_dwordx2 v[186:187], v[140:141], off offset:1024 sc1
	v_pk_mul_f32 v[140:141], v[12:13], v[128:129]
	v_pk_mul_f32 v[142:143], v[14:15], v[130:131]
	v_pk_add_f32 v[128:129], v[94:95], 1.0 op_sel_hi:[1,0]
	v_pk_add_f32 v[130:131], v[92:93], 1.0 op_sel_hi:[1,0]
	v_pk_fma_f32 v[142:143], v[128:129], v[142:143], v[90:91]
	v_pk_fma_f32 v[140:141], v[130:131], v[140:141], v[88:89]
	v_cmp_lt_i32_e32 vcc, v170, v176
	v_cvt_pk_bf16_f32 v140, v140, v141
	v_cvt_pk_bf16_f32 v141, v142, v143
	global_store_dwordx2 v[186:187], v[140:141], off offset:1536 sc1
	s_and_saveexec_b64 s[6:7], vcc
	s_cbranch_execz .LBB0_136
	v_add_u32_e32 v140, 0xffffe001, v144
	v_ashrrev_i32_e32 v140, 10, v140
	v_add_u32_e32 v140, 1, v140
	v_cmp_lt_i32_e32 vcc, s15, v144
	s_nop 1
	v_cndmask_b32_e32 v140, 0, v140, vcc
	v_cmp_ne_u32_e32 vcc, v140, v185
	s_and_saveexec_b64 s[8:9], vcc
	s_cbranch_execz .LBB0_122
	global_load_dwordx4 v[16:19], v[150:151], off
	global_load_dwordx4 v[20:23], v[152:153], off
	v_mad_i64_i32 v[128:129], s[10:11], v140, s3, v[160:161]
	s_mov_b64 s[10:11], 0

.LBB0_122:
	s_or_b64 exec, exec, s[8:9]
	s_waitcnt vmcnt(23)
	v_mov_b32_e32 v142, v125
	s_waitcnt vmcnt(22)
	v_mov_b32_e32 v143, v121
	v_mov_b32_e32 v140, v124
	v_mov_b32_e32 v141, v120
	v_pk_mul_f32 v[142:143], v[142:143], v[142:143]
	s_waitcnt vmcnt(21)
	v_mov_b32_e32 v186, v117
	v_pk_fma_f32 v[140:141], v[140:141], v[140:141], v[142:143]
	v_mov_b32_e32 v142, v126
	v_mov_b32_e32 v143, v122
	v_pk_fma_f32 v[140:141], v[142:143], v[142:143], v[140:141]
	v_mov_b32_e32 v142, v127
	v_mov_b32_e32 v143, v123
	s_waitcnt vmcnt(20)
	v_mov_b32_e32 v187, v113
	v_pk_fma_f32 v[140:141], v[142:143], v[142:143], v[140:141]
	v_mov_b32_e32 v142, v116
	v_mov_b32_e32 v143, v112
	v_pk_mul_f32 v[186:187], v[186:187], v[186:187]
	v_add_f32_e32 v140, v140, v141
	v_pk_fma_f32 v[142:143], v[142:143], v[142:143], v[186:187]
	v_mov_b32_e32 v186, v118
	v_mov_b32_e32 v187, v114
	v_pk_fma_f32 v[142:143], v[186:187], v[186:187], v[142:143]
	v_mov_b32_e32 v186, v119
	v_mov_b32_e32 v187, v115
	v_pk_fma_f32 v[142:143], v[186:187], v[186:187], v[142:143]
	v_ashrrev_i32_e32 v171, 31, v170
	v_add_f32_e32 v140, v140, v142
	v_add_f32_e32 v140, v140, v143
	ds_bpermute_b32 v141, v178, v140
	s_waitcnt lgkmcnt(0)
	v_add_f32_e32 v140, v140, v141
	ds_bpermute_b32 v141, v179, v140
	s_waitcnt lgkmcnt(0)
	v_add_f32_e32 v140, v140, v141
	ds_bpermute_b32 v141, v180, v140
	s_waitcnt lgkmcnt(0)
	v_add_f32_e32 v140, v140, v141
	ds_bpermute_b32 v141, v181, v140
	s_waitcnt lgkmcnt(0)
	v_add_f32_e32 v140, v140, v141
	ds_bpermute_b32 v141, v182, v140
	s_waitcnt lgkmcnt(0)
	v_add_f32_e32 v140, v140, v141
	ds_bpermute_b32 v141, v183, v140
	s_waitcnt lgkmcnt(0)
	v_add_f32_e32 v140, v140, v141
	v_fmamk_f32 v140, v140, 0x3a800000, v184
	v_mul_f32_e32 v141, 0x4b800000, v140
	v_cmp_gt_f32_e32 vcc, s14, v140
	s_nop 1
	v_cndmask_b32_e32 v140, v140, v141, vcc
	v_rsq_f32_e32 v142, v140
	v_lshlrev_b64 v[140:141], 11, v[170:171]
	v_lshl_add_u64 v[140:141], v[148:149], 0, v[140:141]
	v_mul_f32_e32 v143, 0x45800000, v142
	v_cndmask_b32_e32 v142, v142, v143, vcc
	v_pk_mul_f32 v[126:127], v[126:127], v[142:143] op_sel_hi:[1,0]
	v_pk_mul_f32 v[124:125], v[124:125], v[142:143] op_sel_hi:[1,0]
	v_pk_mul_f32 v[122:123], v[122:123], v[142:143] op_sel_hi:[1,0]
	v_pk_mul_f32 v[120:121], v[120:121], v[142:143] op_sel_hi:[1,0]
	v_pk_mul_f32 v[118:119], v[118:119], v[142:143] op_sel_hi:[1,0]
	v_pk_mul_f32 v[116:117], v[116:117], v[142:143] op_sel_hi:[1,0]
	v_pk_mul_f32 v[114:115], v[114:115], v[142:143] op_sel_hi:[1,0]
	v_pk_mul_f32 v[112:113], v[112:113], v[142:143] op_sel_hi:[1,0]
	v_pk_mul_f32 v[124:125], v[0:1], v[124:125]
	v_pk_mul_f32 v[126:127], v[2:3], v[126:127]
	v_pk_mul_f32 v[120:121], v[4:5], v[120:121]
	v_pk_mul_f32 v[122:123], v[6:7], v[122:123]
	v_pk_mul_f32 v[116:117], v[8:9], v[116:117]
	v_pk_mul_f32 v[118:119], v[10:11], v[118:119]
	v_pk_mul_f32 v[112:113], v[12:13], v[112:113]
	v_pk_mul_f32 v[114:115], v[14:15], v[114:115]
	v_pk_fma_f32 v[126:127], v[172:173], v[126:127], v[18:19]
	v_pk_fma_f32 v[124:125], v[174:175], v[124:125], v[16:17]
	v_pk_fma_f32 v[122:123], v[136:137], v[122:123], v[42:43]
	v_pk_fma_f32 v[120:121], v[138:139], v[120:121], v[40:41]
	v_pk_fma_f32 v[118:119], v[132:133], v[118:119], v[66:67]
	v_pk_fma_f32 v[116:117], v[134:135], v[116:117], v[64:65]
	v_pk_fma_f32 v[114:115], v[128:129], v[114:115], v[90:91]
	v_pk_fma_f32 v[112:113], v[130:131], v[112:113], v[88:89]
	v_cvt_pk_bf16_f32 v124, v124, v125
	v_cvt_pk_bf16_f32 v125, v126, v127
	v_cvt_pk_bf16_f32 v120, v120, v121
	v_cvt_pk_bf16_f32 v121, v122, v123
	v_cvt_pk_bf16_f32 v116, v116, v117
	v_cvt_pk_bf16_f32 v117, v118, v119
	v_cvt_pk_bf16_f32 v112, v112, v113
	v_cvt_pk_bf16_f32 v113, v114, v115
	global_store_dwordx2 v[140:141], v[124:125], off sc1
	global_store_dwordx2 v[140:141], v[120:121], off offset:512 sc1
	global_store_dwordx2 v[140:141], v[116:117], off offset:1024 sc1
	global_store_dwordx2 v[140:141], v[112:113], off offset:1536 sc1
	s_or_b64 exec, exec, s[6:7]
	v_cmp_lt_i32_e32 vcc, v168, v176
	s_and_saveexec_b64 s[6:7], vcc
	s_cbranch_execnz .LBB0_137

.LBB0_134:
	s_or_b64 exec, exec, s[8:9]
	s_waitcnt vmcnt(15)
	v_mov_b32_e32 v98, v85
	s_waitcnt vmcnt(14)
	v_mov_b32_e32 v99, v81
	v_mov_b32_e32 v96, v84
	v_mov_b32_e32 v97, v80
	v_pk_mul_f32 v[98:99], v[98:99], v[98:99]
	s_waitcnt vmcnt(13)
	v_mov_b32_e32 v100, v77
	v_pk_fma_f32 v[96:97], v[96:97], v[96:97], v[98:99]
	v_mov_b32_e32 v98, v86
	v_mov_b32_e32 v99, v82
	v_pk_fma_f32 v[96:97], v[98:99], v[98:99], v[96:97]
	v_mov_b32_e32 v98, v87
	v_mov_b32_e32 v99, v83
	s_waitcnt vmcnt(12)
	v_mov_b32_e32 v101, v73
	v_pk_fma_f32 v[96:97], v[98:99], v[98:99], v[96:97]
	v_mov_b32_e32 v98, v76
	v_mov_b32_e32 v99, v72
	v_pk_mul_f32 v[100:101], v[100:101], v[100:101]
	v_add_f32_e32 v96, v96, v97
	v_pk_fma_f32 v[98:99], v[98:99], v[98:99], v[100:101]
	v_mov_b32_e32 v100, v78
	v_mov_b32_e32 v101, v74
	v_pk_fma_f32 v[98:99], v[100:101], v[100:101], v[98:99]
	v_mov_b32_e32 v100, v79
	v_mov_b32_e32 v101, v75
	v_pk_fma_f32 v[98:99], v[100:101], v[100:101], v[98:99]
	v_ashrrev_i32_e32 v167, 31, v166
	v_add_f32_e32 v96, v96, v98
	v_add_f32_e32 v96, v96, v99
	ds_bpermute_b32 v97, v178, v96
	v_lshlrev_b64 v[100:101], 11, v[166:167]
	v_lshl_add_u64 v[100:101], v[148:149], 0, v[100:101]
	s_waitcnt lgkmcnt(0)
	v_add_f32_e32 v96, v96, v97
	ds_bpermute_b32 v97, v179, v96
	s_waitcnt lgkmcnt(0)
	v_add_f32_e32 v96, v96, v97
	ds_bpermute_b32 v97, v180, v96
	s_waitcnt lgkmcnt(0)
	v_add_f32_e32 v96, v96, v97
	ds_bpermute_b32 v97, v181, v96
	s_waitcnt lgkmcnt(0)
	v_add_f32_e32 v96, v96, v97
	ds_bpermute_b32 v97, v182, v96
	s_waitcnt lgkmcnt(0)
	v_add_f32_e32 v98, v96, v97
	ds_bpermute_b32 v99, v183, v98
	v_pk_add_f32 v[96:97], v[22:23], 1.0 op_sel_hi:[1,0]
	s_waitcnt lgkmcnt(0)
	v_add_f32_e32 v98, v98, v99
	v_fmamk_f32 v98, v98, 0x3a800000, v184
	v_mul_f32_e32 v99, 0x4b800000, v98
	v_cmp_gt_f32_e32 vcc, s14, v98
	s_nop 1
	v_cndmask_b32_e32 v98, v98, v99, vcc
	v_rsq_f32_e32 v102, v98
	v_pk_add_f32 v[98:99], v[20:21], 1.0 op_sel_hi:[1,0]
	v_mul_f32_e32 v103, 0x45800000, v102
	v_cndmask_b32_e32 v102, v102, v103, vcc
	v_pk_mul_f32 v[86:87], v[86:87], v[102:103] op_sel_hi:[1,0]
	v_pk_mul_f32 v[84:85], v[84:85], v[102:103] op_sel_hi:[1,0]
	v_pk_mul_f32 v[86:87], v[2:3], v[86:87]
	v_pk_mul_f32 v[84:85], v[0:1], v[84:85]
	v_pk_fma_f32 v[86:87], v[96:97], v[86:87], v[18:19]
	v_pk_fma_f32 v[84:85], v[98:99], v[84:85], v[16:17]
	v_pk_mul_f32 v[82:83], v[82:83], v[102:103] op_sel_hi:[1,0]
	v_cvt_pk_bf16_f32 v84, v84, v85
	v_cvt_pk_bf16_f32 v85, v86, v87
	v_pk_mul_f32 v[80:81], v[80:81], v[102:103] op_sel_hi:[1,0]
	global_store_dwordx2 v[100:101], v[84:85], off sc1
	v_pk_mul_f32 v[80:81], v[4:5], v[80:81]
	v_pk_mul_f32 v[82:83], v[6:7], v[82:83]
	v_pk_add_f32 v[84:85], v[46:47], 1.0 op_sel_hi:[1,0]
	v_pk_add_f32 v[86:87], v[44:45], 1.0 op_sel_hi:[1,0]
	v_pk_fma_f32 v[82:83], v[84:85], v[82:83], v[42:43]
	v_pk_fma_f32 v[80:81], v[86:87], v[80:81], v[40:41]
	v_pk_mul_f32 v[78:79], v[78:79], v[102:103] op_sel_hi:[1,0]
	v_cvt_pk_bf16_f32 v80, v80, v81
	v_cvt_pk_bf16_f32 v81, v82, v83
	v_pk_mul_f32 v[76:77], v[76:77], v[102:103] op_sel_hi:[1,0]
	global_store_dwordx2 v[100:101], v[80:81], off offset:512 sc1
	v_pk_mul_f32 v[76:77], v[8:9], v[76:77]
	v_pk_mul_f32 v[78:79], v[10:11], v[78:79]
	v_pk_add_f32 v[80:81], v[70:71], 1.0 op_sel_hi:[1,0]
	v_pk_add_f32 v[82:83], v[68:69], 1.0 op_sel_hi:[1,0]
	v_pk_fma_f32 v[78:79], v[80:81], v[78:79], v[66:67]
	v_pk_fma_f32 v[76:77], v[82:83], v[76:77], v[64:65]
	v_pk_mul_f32 v[74:75], v[74:75], v[102:103] op_sel_hi:[1,0]
	v_cvt_pk_bf16_f32 v76, v76, v77
	v_cvt_pk_bf16_f32 v77, v78, v79
	v_pk_mul_f32 v[72:73], v[72:73], v[102:103] op_sel_hi:[1,0]
	global_store_dwordx2 v[100:101], v[76:77], off offset:1024 sc1
	v_pk_mul_f32 v[72:73], v[12:13], v[72:73]
	v_pk_mul_f32 v[74:75], v[14:15], v[74:75]
	v_pk_add_f32 v[76:77], v[94:95], 1.0 op_sel_hi:[1,0]
	v_pk_add_f32 v[78:79], v[92:93], 1.0 op_sel_hi:[1,0]
	v_pk_fma_f32 v[74:75], v[76:77], v[74:75], v[90:91]
	v_pk_fma_f32 v[72:73], v[78:79], v[72:73], v[88:89]
	s_nop 0
	v_cvt_pk_bf16_f32 v72, v72, v73
	v_cvt_pk_bf16_f32 v73, v74, v75
	global_store_dwordx2 v[100:101], v[72:73], off offset:1536 sc1
	s_or_b64 exec, exec, s[6:7]
	v_cmp_lt_i32_e32 vcc, v164, v176
	s_and_saveexec_b64 s[6:7], vcc
	s_cbranch_execnz .LBB0_149

.LBB0_147:
	s_or_b64 exec, exec, s[8:9]
	s_waitcnt vmcnt(19)
	v_mov_b32_e32 v114, v109
	s_waitcnt vmcnt(18)
	v_mov_b32_e32 v115, v105
	v_mov_b32_e32 v112, v108
	v_mov_b32_e32 v113, v104
	v_pk_mul_f32 v[114:115], v[114:115], v[114:115]
	s_waitcnt vmcnt(17)
	v_mov_b32_e32 v116, v101
	v_pk_fma_f32 v[112:113], v[112:113], v[112:113], v[114:115]
	v_mov_b32_e32 v114, v110
	v_mov_b32_e32 v115, v106
	v_pk_fma_f32 v[112:113], v[114:115], v[114:115], v[112:113]
	v_mov_b32_e32 v114, v111
	v_mov_b32_e32 v115, v107
	s_waitcnt vmcnt(16)
	v_mov_b32_e32 v117, v97
	v_pk_fma_f32 v[112:113], v[114:115], v[114:115], v[112:113]
	v_mov_b32_e32 v114, v100
	v_mov_b32_e32 v115, v96
	v_pk_mul_f32 v[116:117], v[116:117], v[116:117]
	v_add_f32_e32 v112, v112, v113
	v_pk_fma_f32 v[114:115], v[114:115], v[114:115], v[116:117]
	v_mov_b32_e32 v116, v102
	v_mov_b32_e32 v117, v98
	v_pk_fma_f32 v[114:115], v[116:117], v[116:117], v[114:115]
	v_mov_b32_e32 v116, v103
	v_mov_b32_e32 v117, v99
	v_pk_fma_f32 v[114:115], v[116:117], v[116:117], v[114:115]
	v_ashrrev_i32_e32 v169, 31, v168
	v_add_f32_e32 v112, v112, v114
	v_add_f32_e32 v112, v112, v115
	ds_bpermute_b32 v113, v178, v112
	v_lshlrev_b64 v[116:117], 11, v[168:169]
	v_lshl_add_u64 v[116:117], v[148:149], 0, v[116:117]
	s_waitcnt lgkmcnt(0)
	v_add_f32_e32 v112, v112, v113
	ds_bpermute_b32 v113, v179, v112
	s_waitcnt lgkmcnt(0)
	v_add_f32_e32 v112, v112, v113
	ds_bpermute_b32 v113, v180, v112
	s_waitcnt lgkmcnt(0)
	v_add_f32_e32 v112, v112, v113
	ds_bpermute_b32 v113, v181, v112
	s_waitcnt lgkmcnt(0)
	v_add_f32_e32 v112, v112, v113
	ds_bpermute_b32 v113, v182, v112
	s_waitcnt lgkmcnt(0)
	v_add_f32_e32 v114, v112, v113
	ds_bpermute_b32 v115, v183, v114
	v_pk_add_f32 v[112:113], v[22:23], 1.0 op_sel_hi:[1,0]
	s_waitcnt lgkmcnt(0)
	v_add_f32_e32 v114, v114, v115
	v_fmamk_f32 v114, v114, 0x3a800000, v184
	v_mul_f32_e32 v115, 0x4b800000, v114
	v_cmp_gt_f32_e32 vcc, s14, v114
	s_nop 1
	v_cndmask_b32_e32 v114, v114, v115, vcc
	v_rsq_f32_e32 v118, v114
	v_pk_add_f32 v[114:115], v[20:21], 1.0 op_sel_hi:[1,0]
	v_mul_f32_e32 v119, 0x45800000, v118
	v_cndmask_b32_e32 v118, v118, v119, vcc
	v_pk_mul_f32 v[110:111], v[110:111], v[118:119] op_sel_hi:[1,0]
	v_pk_mul_f32 v[108:109], v[108:109], v[118:119] op_sel_hi:[1,0]
	v_pk_mul_f32 v[110:111], v[2:3], v[110:111]
	v_pk_mul_f32 v[108:109], v[0:1], v[108:109]
	v_pk_fma_f32 v[110:111], v[112:113], v[110:111], v[18:19]
	v_pk_fma_f32 v[108:109], v[114:115], v[108:109], v[16:17]
	v_pk_mul_f32 v[106:107], v[106:107], v[118:119] op_sel_hi:[1,0]
	v_cvt_pk_bf16_f32 v108, v108, v109
	v_cvt_pk_bf16_f32 v109, v110, v111
	v_pk_mul_f32 v[104:105], v[104:105], v[118:119] op_sel_hi:[1,0]
	global_store_dwordx2 v[116:117], v[108:109], off sc1
	v_pk_mul_f32 v[104:105], v[4:5], v[104:105]
	v_pk_mul_f32 v[106:107], v[6:7], v[106:107]
	v_pk_add_f32 v[108:109], v[46:47], 1.0 op_sel_hi:[1,0]
	v_pk_add_f32 v[110:111], v[44:45], 1.0 op_sel_hi:[1,0]
	v_pk_fma_f32 v[106:107], v[108:109], v[106:107], v[42:43]
	v_pk_fma_f32 v[104:105], v[110:111], v[104:105], v[40:41]
	v_pk_mul_f32 v[102:103], v[102:103], v[118:119] op_sel_hi:[1,0]
	v_cvt_pk_bf16_f32 v104, v104, v105
	v_cvt_pk_bf16_f32 v105, v106, v107
	v_pk_mul_f32 v[100:101], v[100:101], v[118:119] op_sel_hi:[1,0]
	global_store_dwordx2 v[116:117], v[104:105], off offset:512 sc1
	v_pk_mul_f32 v[100:101], v[8:9], v[100:101]
	v_pk_mul_f32 v[102:103], v[10:11], v[102:103]
	v_pk_add_f32 v[104:105], v[70:71], 1.0 op_sel_hi:[1,0]
	v_pk_add_f32 v[106:107], v[68:69], 1.0 op_sel_hi:[1,0]
	v_pk_fma_f32 v[102:103], v[104:105], v[102:103], v[66:67]
	v_pk_fma_f32 v[100:101], v[106:107], v[100:101], v[64:65]
	v_pk_mul_f32 v[98:99], v[98:99], v[118:119] op_sel_hi:[1,0]
	v_cvt_pk_bf16_f32 v100, v100, v101
	v_cvt_pk_bf16_f32 v101, v102, v103
	v_pk_mul_f32 v[96:97], v[96:97], v[118:119] op_sel_hi:[1,0]
	global_store_dwordx2 v[116:117], v[100:101], off offset:1024 sc1
	v_pk_mul_f32 v[96:97], v[12:13], v[96:97]
	v_pk_mul_f32 v[98:99], v[14:15], v[98:99]
	v_pk_add_f32 v[100:101], v[94:95], 1.0 op_sel_hi:[1,0]
	v_pk_add_f32 v[102:103], v[92:93], 1.0 op_sel_hi:[1,0]
	v_pk_fma_f32 v[98:99], v[100:101], v[98:99], v[90:91]
	v_pk_fma_f32 v[96:97], v[102:103], v[96:97], v[88:89]
	s_nop 0
	v_cvt_pk_bf16_f32 v96, v96, v97
	v_cvt_pk_bf16_f32 v97, v98, v99
	global_store_dwordx2 v[116:117], v[96:97], off offset:1536 sc1
	s_or_b64 exec, exec, s[6:7]
	v_cmp_lt_i32_e32 vcc, v166, v176
	s_and_saveexec_b64 s[6:7], vcc
	s_cbranch_execnz .LBB0_124

.LBB0_159:
	s_or_b64 exec, exec, s[8:9]
	s_waitcnt vmcnt(11)
	v_mov_b32_e32 v74, v61
	s_waitcnt vmcnt(10)
	v_mov_b32_e32 v75, v57
	v_mov_b32_e32 v72, v60
	v_mov_b32_e32 v73, v56
	v_pk_mul_f32 v[74:75], v[74:75], v[74:75]
	s_waitcnt vmcnt(9)
	v_mov_b32_e32 v76, v53
	v_pk_fma_f32 v[72:73], v[72:73], v[72:73], v[74:75]
	v_mov_b32_e32 v74, v62
	v_mov_b32_e32 v75, v58
	v_pk_fma_f32 v[72:73], v[74:75], v[74:75], v[72:73]
	v_mov_b32_e32 v74, v63
	v_mov_b32_e32 v75, v59
	s_waitcnt vmcnt(8)
	v_mov_b32_e32 v77, v49
	v_pk_fma_f32 v[72:73], v[74:75], v[74:75], v[72:73]
	v_mov_b32_e32 v74, v52
	v_mov_b32_e32 v75, v48
	v_pk_mul_f32 v[76:77], v[76:77], v[76:77]
	v_add_f32_e32 v72, v72, v73
	v_pk_fma_f32 v[74:75], v[74:75], v[74:75], v[76:77]
	v_mov_b32_e32 v76, v54
	v_mov_b32_e32 v77, v50
	v_pk_fma_f32 v[74:75], v[76:77], v[76:77], v[74:75]
	v_mov_b32_e32 v76, v55
	v_mov_b32_e32 v77, v51
	v_pk_fma_f32 v[74:75], v[76:77], v[76:77], v[74:75]
	v_ashrrev_i32_e32 v165, 31, v164
	v_add_f32_e32 v72, v72, v74
	v_add_f32_e32 v72, v72, v75
	ds_bpermute_b32 v73, v178, v72
	v_lshlrev_b64 v[76:77], 11, v[164:165]
	v_lshl_add_u64 v[76:77], v[148:149], 0, v[76:77]
	s_waitcnt lgkmcnt(0)
	v_add_f32_e32 v72, v72, v73
	ds_bpermute_b32 v73, v179, v72
	s_waitcnt lgkmcnt(0)
	v_add_f32_e32 v72, v72, v73
	ds_bpermute_b32 v73, v180, v72
	s_waitcnt lgkmcnt(0)
	v_add_f32_e32 v72, v72, v73
	ds_bpermute_b32 v73, v181, v72
	s_waitcnt lgkmcnt(0)
	v_add_f32_e32 v72, v72, v73
	ds_bpermute_b32 v73, v182, v72
	s_waitcnt lgkmcnt(0)
	v_add_f32_e32 v74, v72, v73
	ds_bpermute_b32 v75, v183, v74
	v_pk_add_f32 v[72:73], v[22:23], 1.0 op_sel_hi:[1,0]
	s_waitcnt lgkmcnt(0)
	v_add_f32_e32 v74, v74, v75
	v_fmamk_f32 v74, v74, 0x3a800000, v184
	v_mul_f32_e32 v75, 0x4b800000, v74
	v_cmp_gt_f32_e32 vcc, s14, v74
	s_nop 1
	v_cndmask_b32_e32 v74, v74, v75, vcc
	v_rsq_f32_e32 v78, v74
	v_pk_add_f32 v[74:75], v[20:21], 1.0 op_sel_hi:[1,0]
	v_mul_f32_e32 v79, 0x45800000, v78
	v_cndmask_b32_e32 v78, v78, v79, vcc
	v_pk_mul_f32 v[62:63], v[62:63], v[78:79] op_sel_hi:[1,0]
	v_pk_mul_f32 v[60:61], v[60:61], v[78:79] op_sel_hi:[1,0]
	v_pk_mul_f32 v[62:63], v[2:3], v[62:63]
	v_pk_mul_f32 v[60:61], v[0:1], v[60:61]
	v_pk_fma_f32 v[62:63], v[72:73], v[62:63], v[18:19]
	v_pk_fma_f32 v[60:61], v[74:75], v[60:61], v[16:17]
	v_pk_mul_f32 v[58:59], v[58:59], v[78:79] op_sel_hi:[1,0]
	v_cvt_pk_bf16_f32 v60, v60, v61
	v_cvt_pk_bf16_f32 v61, v62, v63
	v_pk_mul_f32 v[56:57], v[56:57], v[78:79] op_sel_hi:[1,0]
	global_store_dwordx2 v[76:77], v[60:61], off sc1
	v_pk_mul_f32 v[56:57], v[4:5], v[56:57]
	v_pk_mul_f32 v[58:59], v[6:7], v[58:59]
	v_pk_add_f32 v[60:61], v[46:47], 1.0 op_sel_hi:[1,0]
	v_pk_add_f32 v[62:63], v[44:45], 1.0 op_sel_hi:[1,0]
	v_pk_fma_f32 v[58:59], v[60:61], v[58:59], v[42:43]
	v_pk_fma_f32 v[56:57], v[62:63], v[56:57], v[40:41]
	v_pk_mul_f32 v[54:55], v[54:55], v[78:79] op_sel_hi:[1,0]
	v_cvt_pk_bf16_f32 v56, v56, v57
	v_cvt_pk_bf16_f32 v57, v58, v59
	v_pk_mul_f32 v[52:53], v[52:53], v[78:79] op_sel_hi:[1,0]
	global_store_dwordx2 v[76:77], v[56:57], off offset:512 sc1
	v_pk_mul_f32 v[52:53], v[8:9], v[52:53]
	v_pk_mul_f32 v[54:55], v[10:11], v[54:55]
	v_pk_add_f32 v[56:57], v[70:71], 1.0 op_sel_hi:[1,0]
	v_pk_add_f32 v[58:59], v[68:69], 1.0 op_sel_hi:[1,0]
	v_pk_fma_f32 v[54:55], v[56:57], v[54:55], v[66:67]
	v_pk_fma_f32 v[52:53], v[58:59], v[52:53], v[64:65]
	v_pk_mul_f32 v[50:51], v[50:51], v[78:79] op_sel_hi:[1,0]
	v_cvt_pk_bf16_f32 v52, v52, v53
	v_cvt_pk_bf16_f32 v53, v54, v55
	v_pk_mul_f32 v[48:49], v[48:49], v[78:79] op_sel_hi:[1,0]
	global_store_dwordx2 v[76:77], v[52:53], off offset:1024 sc1
	v_pk_mul_f32 v[48:49], v[12:13], v[48:49]
	v_pk_mul_f32 v[50:51], v[14:15], v[50:51]
	v_pk_add_f32 v[52:53], v[94:95], 1.0 op_sel_hi:[1,0]
	v_pk_add_f32 v[54:55], v[92:93], 1.0 op_sel_hi:[1,0]
	v_pk_fma_f32 v[50:51], v[52:53], v[50:51], v[90:91]
	v_pk_fma_f32 v[48:49], v[54:55], v[48:49], v[88:89]
	s_nop 0
	v_cvt_pk_bf16_f32 v48, v48, v49
	v_cvt_pk_bf16_f32 v49, v50, v51
	global_store_dwordx2 v[76:77], v[48:49], off offset:1536 sc1
	s_or_b64 exec, exec, s[6:7]
	v_cmp_lt_i32_e32 vcc, v162, v176
	s_and_saveexec_b64 s[6:7], vcc
	s_cbranch_execz .LBB0_100

.LBB0_229:
	ds_read_b128 v[42:45], v40
	ds_read_b128 v[46:49], v40 offset:16
	ds_read_b128 v[50:53], v40 offset:32
	ds_read_b128 v[54:57], v40 offset:48
	ds_read_b128 v[58:61], v40 offset:144
	ds_read_b128 v[62:65], v40 offset:160
	ds_read_b128 v[66:69], v40 offset:176
	ds_read_b128 v[70:73], v40 offset:192
	ds_read_b128 v[74:77], v40 offset:288
	ds_read_b128 v[78:81], v40 offset:304
	ds_read_b128 v[82:85], v40 offset:320
	ds_read_b128 v[86:89], v40 offset:336
	ds_read_b128 v[90:93], v40 offset:432
	ds_read_b128 v[94:97], v40 offset:448
	ds_read_b128 v[98:101], v40 offset:464
	ds_read_b128 v[102:105], v40 offset:480
	s_waitcnt lgkmcnt(14)
	v_pk_mul_f32 v[44:45], v[10:11], v[44:45]
	v_pk_mul_f32 v[48:49], v[12:13], v[48:49]
	s_waitcnt lgkmcnt(11)
	v_pk_mul_f32 v[60:61], v[10:11], v[60:61]
	s_waitcnt lgkmcnt(10)
	v_pk_mul_f32 v[64:65], v[12:13], v[64:65]
	s_waitcnt lgkmcnt(7)
	v_pk_mul_f32 v[76:77], v[10:11], v[76:77]
	s_waitcnt lgkmcnt(6)
	v_pk_mul_f32 v[80:81], v[12:13], v[80:81]
	s_waitcnt lgkmcnt(3)
	v_pk_mul_f32 v[92:93], v[10:11], v[92:93]
	s_waitcnt lgkmcnt(2)
	v_pk_mul_f32 v[96:97], v[12:13], v[96:97]
	v_pk_fma_f32 v[42:43], v[8:9], v[42:43], v[44:45]
	v_pk_fma_f32 v[44:45], v[2:3], v[46:47], v[48:49]
	v_pk_fma_f32 v[46:47], v[8:9], v[58:59], v[60:61]
	v_pk_fma_f32 v[48:49], v[2:3], v[62:63], v[64:65]
	v_pk_fma_f32 v[58:59], v[8:9], v[74:75], v[76:77]
	v_pk_fma_f32 v[60:61], v[2:3], v[78:79], v[80:81]
	v_pk_fma_f32 v[62:63], v[8:9], v[90:91], v[92:93]
	v_pk_fma_f32 v[64:65], v[2:3], v[94:95], v[96:97]
	v_pk_fma_f32 v[42:43], v[4:5], v[50:51], v[42:43]
	v_pk_fma_f32 v[44:45], v[14:15], v[54:55], v[44:45]
	v_pk_fma_f32 v[46:47], v[4:5], v[66:67], v[46:47]
	v_pk_fma_f32 v[48:49], v[14:15], v[70:71], v[48:49]
	v_pk_fma_f32 v[50:51], v[4:5], v[82:83], v[58:59]
	v_pk_fma_f32 v[54:55], v[14:15], v[86:87], v[60:61]
	s_waitcnt lgkmcnt(1)
	v_pk_fma_f32 v[58:59], v[4:5], v[98:99], v[62:63]
	s_waitcnt lgkmcnt(0)
	v_pk_fma_f32 v[60:61], v[14:15], v[102:103], v[64:65]
	v_pk_fma_f32 v[42:43], v[6:7], v[52:53], v[42:43]
	v_pk_fma_f32 v[44:45], v[16:17], v[56:57], v[44:45]
	v_pk_fma_f32 v[46:47], v[6:7], v[68:69], v[46:47]
	v_pk_fma_f32 v[48:49], v[16:17], v[72:73], v[48:49]
	v_pk_fma_f32 v[50:51], v[6:7], v[84:85], v[50:51]
	v_pk_fma_f32 v[52:53], v[16:17], v[88:89], v[54:55]
	v_pk_fma_f32 v[54:55], v[6:7], v[100:101], v[58:59]
	v_pk_fma_f32 v[56:57], v[16:17], v[104:105], v[60:61]
	v_pk_add_f32 v[42:43], v[42:43], v[44:45]
	v_pk_add_f32 v[44:45], v[46:47], v[48:49]
	v_pk_add_f32 v[46:47], v[50:51], v[52:53]
	v_pk_add_f32 v[48:49], v[54:55], v[56:57]
	v_add_f32_e32 v41, v42, v43
	v_add_f32_e32 v42, v44, v45
	v_add_f32_e32 v43, v46, v47
	v_add_f32_e32 v44, v48, v49
	v_add_f32_e32 v41, v33, v41
	v_add_f32_e32 v42, v33, v42
	v_add_f32_e32 v43, v33, v43
	v_add_f32_e32 v44, v33, v44
	v_min_f32_e32 v45, 0, v41
	v_mul_f32_e64 v41, |v41|, s13
	v_min_f32_e32 v46, 0, v42
	v_mul_f32_e64 v42, |v42|, s13
	v_min_f32_e32 v47, 0, v43
	v_mul_f32_e64 v43, |v43|, s13
	v_min_f32_e32 v48, 0, v44
	v_mul_f32_e64 v44, |v44|, s13
	v_exp_f32_e32 v41, v41
	v_exp_f32_e32 v42, v42
	v_exp_f32_e32 v43, v43
	v_exp_f32_e32 v44, v44
	s_add_i32 s4, s10, s28
	s_ashr_i32 s5, s4, 31
	s_add_i32 s6, s4, 1
	s_add_i32 s8, s4, 2
	s_add_i32 s56, s4, 3
	s_lshl_b64 s[4:5], s[4:5], 10
	s_ashr_i32 s7, s6, 31
	s_ashr_i32 s9, s8, 31
	s_ashr_i32 s57, s56, 31
	v_add_f32_e32 v41, 1.0, v41
	v_lshl_add_u64 v[106:107], v[24:25], 0, s[4:5]
	s_lshl_b64 s[4:5], s[6:7], 10
	s_lshl_b64 s[6:7], s[8:9], 10
	s_lshl_b64 s[8:9], s[56:57], 10
	v_add_f32_e32 v42, 1.0, v42
	v_add_f32_e32 v43, 1.0, v43
	v_add_f32_e32 v44, 1.0, v44
	v_lshl_add_u64 v[108:109], v[24:25], 0, s[4:5]
	v_lshl_add_u64 v[110:111], v[24:25], 0, s[6:7]
	v_lshl_add_u64 v[112:113], v[24:25], 0, s[8:9]
	v_log_f32_e32 v41, v41
	v_log_f32_e32 v42, v42
	v_log_f32_e32 v43, v43
	v_log_f32_e32 v44, v44
	v_mul_f32_e32 v53, 0x3f317217, v41
	v_mul_f32_e32 v54, 0x3f317217, v42
	v_mul_f32_e32 v55, 0x3f317217, v43
	v_mul_f32_e32 v56, 0x3f317217, v44
	v_fma_f32 v53, v41, s15, -v53
	v_fma_f32 v54, v42, s15, -v54
	v_fma_f32 v55, v43, s15, -v55
	v_fma_f32 v56, v44, s15, -v56
	v_fmac_f32_e32 v53, 0x3377d1cf, v41
	v_fmac_f32_e32 v54, 0x3377d1cf, v42
	v_fmac_f32_e32 v55, 0x3377d1cf, v43
	v_fmac_f32_e32 v56, 0x3377d1cf, v44
	v_fmac_f32_e32 v53, 0x3f317217, v41
	v_fmac_f32_e32 v54, 0x3f317217, v42
	v_fmac_f32_e32 v55, 0x3f317217, v43
	v_fmac_f32_e32 v56, 0x3f317217, v44
	s_add_i32 s28, s28, 4
	v_sub_f32_e32 v41, v45, v53
	v_add_u32_e32 v40, 0x240, v40
	s_cmp_eq_u32 s28, 48
	v_sub_f32_e32 v42, v46, v54
	v_sub_f32_e32 v43, v47, v55
	v_sub_f32_e32 v44, v48, v56
	v_fma_mixlo_f16 v41, v41, s17, 0
	v_fma_mixlo_f16 v42, v42, s17, 0
	v_fma_mixlo_f16 v43, v43, s17, 0
	v_fma_mixlo_f16 v44, v44, s17, 0
	global_store_short v[106:107], v41, off sc1
	global_store_short v[108:109], v42, off sc1
	global_store_short v[110:111], v43, off sc1
	global_store_short v[112:113], v44, off sc1
	s_cbranch_scc0 .LBB0_229
	s_add_i32 s19, s19, s26
	s_add_i32 s10, s10, s34
	s_cmpk_gt_i32 s19, 0xff
	s_barrier
	s_cbranch_scc0 .LBB0_225

.LBB0_275:
	v_lshl_or_b32 v147, s0, 8, v168
	v_add_u32_e32 v156, 0xfffffc00, v147
	v_cmp_gt_i32_e32 vcc, s70, v147
	v_cvt_pk_bf16_f32 v157, v150, v151
	v_cvt_pk_bf16_f32 v158, v152, v153
	v_cndmask_b32_e32 v164, v156, v147, vcc
	v_cvt_pk_bf16_f32 v156, v148, v149
	v_mov_b64_e32 v[148:149], s[60:61]
	v_ashrrev_i32_e32 v165, 31, v164
	v_mad_i64_i32 v[148:149], s[16:17], v146, s79, v[148:149]
	v_cvt_pk_bf16_f32 v159, v154, v155
	v_lshl_add_u64 v[150:151], v[164:165], 1, v[148:149]
	s_and_b64 vcc, exec, s[6:7]
	s_mov_b64 s[16:17], -1
	global_store_dwordx4 v[150:151], v[156:159], off sc1
	s_cbranch_vccnz .LBB0_291
	v_mul_f32_e32 v150, v136, v116
	s_cbranch_execz .LBB0_292

.LBB0_307:
	v_cvt_pk_bf16_f32 v158, v150, v151
	v_cvt_pk_bf16_f32 v159, v152, v153
	v_or_b32_e32 v152, 16, v146
	v_mov_b64_e32 v[150:151], s[60:61]
	v_mad_i64_i32 v[150:151], s[16:17], v152, s79, v[150:151]
	v_cvt_pk_bf16_f32 v160, v154, v155
	v_cvt_pk_bf16_f32 v161, v156, v157
	v_lshl_add_u64 v[152:153], v[164:165], 1, v[150:151]
	s_and_b64 vcc, exec, s[6:7]
	s_mov_b64 s[16:17], -1
	global_store_dwordx4 v[152:153], v[158:161], off sc1
	s_cbranch_vccnz .LBB0_323
	v_mul_f32_e32 v152, v136, v108
	s_cbranch_execz .LBB0_324

.LBB0_339:
	v_cvt_pk_bf16_f32 v160, v152, v153
	v_cvt_pk_bf16_f32 v161, v154, v155
	v_or_b32_e32 v154, 32, v146
	v_mov_b64_e32 v[152:153], s[60:61]
	v_mad_i64_i32 v[152:153], s[16:17], v154, s79, v[152:153]
	v_cvt_pk_bf16_f32 v162, v156, v157
	v_cvt_pk_bf16_f32 v163, v158, v159
	v_lshl_add_u64 v[154:155], v[164:165], 1, v[152:153]
	s_and_b64 vcc, exec, s[6:7]
	s_mov_b64 s[16:17], -1
	global_store_dwordx4 v[154:155], v[160:163], off sc1
	s_cbranch_vccnz .LBB0_355
	v_mul_f32_e32 v154, v136, v100
	s_cbranch_execz .LBB0_356

.LBB0_371:
	v_cvt_pk_bf16_f32 v176, v154, v155
	v_cvt_pk_bf16_f32 v177, v156, v157
	v_or_b32_e32 v156, 48, v146
	v_mov_b64_e32 v[154:155], s[60:61]
	v_mad_i64_i32 v[154:155], s[16:17], v156, s79, v[154:155]
	v_cvt_pk_bf16_f32 v178, v158, v159
	v_cvt_pk_bf16_f32 v179, v160, v161
	v_lshl_add_u64 v[156:157], v[164:165], 1, v[154:155]
	s_and_b64 vcc, exec, s[6:7]
	s_mov_b64 s[16:17], -1
	global_store_dwordx4 v[156:157], v[176:179], off sc1
	s_cbranch_vccnz .LBB0_387
	v_mul_f32_e32 v156, v136, v92
	s_cbranch_execz .LBB0_388

.LBB0_403:
	v_add_u32_e32 v180, 0x80, v146
	v_cvt_pk_bf16_f32 v176, v156, v157
	v_mov_b64_e32 v[156:157], s[60:61]
	v_mad_i64_i32 v[156:157], s[16:17], v180, s79, v[156:157]
	v_cvt_pk_bf16_f32 v177, v158, v159
	v_cvt_pk_bf16_f32 v178, v160, v161
	v_cvt_pk_bf16_f32 v179, v162, v163
	v_lshl_add_u64 v[158:159], v[164:165], 1, v[156:157]
	s_and_b64 vcc, exec, s[6:7]
	s_mov_b64 s[16:17], -1
	global_store_dwordx4 v[158:159], v[176:179], off sc1
	s_cbranch_vccnz .LBB0_419
	v_mul_f32_e32 v158, v136, v84
	s_cbranch_execz .LBB0_420

.LBB0_435:
	v_cvt_pk_bf16_f32 v178, v158, v159
	v_cvt_pk_bf16_f32 v179, v160, v161
	v_add_u32_e32 v160, 0x90, v146
	v_mov_b64_e32 v[158:159], s[60:61]
	v_mad_i64_i32 v[158:159], s[16:17], v160, s79, v[158:159]
	v_cvt_pk_bf16_f32 v180, v162, v163
	v_cvt_pk_bf16_f32 v181, v176, v177
	v_lshl_add_u64 v[160:161], v[164:165], 1, v[158:159]
	s_and_b64 vcc, exec, s[6:7]
	s_mov_b64 s[16:17], -1
	global_store_dwordx4 v[160:161], v[178:181], off sc1
	s_cbranch_vccnz .LBB0_451
	v_mul_f32_e32 v160, v136, v76
	s_cbranch_execz .LBB0_452

.LBB0_467:
	v_cvt_pk_bf16_f32 v180, v160, v161
	v_cvt_pk_bf16_f32 v181, v162, v163
	v_add_u32_e32 v162, 0xa0, v146
	v_mov_b64_e32 v[160:161], s[60:61]
	v_mad_i64_i32 v[160:161], s[16:17], v162, s79, v[160:161]
	v_cvt_pk_bf16_f32 v182, v176, v177
	v_cvt_pk_bf16_f32 v183, v178, v179
	v_lshl_add_u64 v[162:163], v[164:165], 1, v[160:161]
	s_and_b64 vcc, exec, s[6:7]
	s_mov_b64 s[16:17], -1
	global_store_dwordx4 v[162:163], v[180:183], off sc1
	s_cbranch_vccnz .LBB0_483
	v_mul_f32_e32 v162, v136, v68
	s_cbranch_execz .LBB0_484

.LBB0_499:
	v_cvt_pk_bf16_f32 v182, v162, v163
	v_cvt_pk_bf16_f32 v183, v176, v177
	v_add_u32_e32 v176, 0xb0, v146
	v_mov_b64_e32 v[162:163], s[60:61]
	v_mad_i64_i32 v[162:163], s[16:17], v176, s79, v[162:163]
	v_cvt_pk_bf16_f32 v184, v178, v179
	v_cvt_pk_bf16_f32 v185, v180, v181
	v_lshl_add_u64 v[164:165], v[164:165], 1, v[162:163]
	s_and_b64 vcc, exec, s[6:7]
	s_mov_b64 s[16:17], -1
	global_store_dwordx4 v[164:165], v[182:185], off sc1
	s_cbranch_vccnz .LBB0_515
	v_mul_f32_e32 v176, v136, v60
	s_cbranch_execz .LBB0_516

.LBB0_531:
	v_or_b32_e32 v164, 0x80, v147
	v_add_u32_e32 v147, 0xfffffc80, v147
	v_cmp_gt_i32_e32 vcc, s70, v164
	v_cvt_pk_bf16_f32 v176, v176, v177
	v_cvt_pk_bf16_f32 v177, v178, v179
	v_cndmask_b32_e32 v164, v147, v164, vcc
	v_ashrrev_i32_e32 v165, 31, v164
	v_cvt_pk_bf16_f32 v178, v180, v181
	v_cvt_pk_bf16_f32 v179, v182, v183
	v_lshl_add_u64 v[148:149], v[164:165], 1, v[148:149]
	s_and_b64 vcc, exec, s[6:7]
	s_mov_b64 s[16:17], -1
	global_store_dwordx4 v[148:149], v[176:179], off sc1
	s_cbranch_vccnz .LBB0_547
	v_mul_f32_e32 v147, v136, v52
	s_cbranch_execz .LBB0_548

.LBB0_563:
	v_cvt_pk_bf16_f32 v182, v147, v148
	v_cvt_pk_bf16_f32 v183, v149, v176
	v_cvt_pk_bf16_f32 v184, v177, v178
	v_cvt_pk_bf16_f32 v185, v179, v180
	v_lshl_add_u64 v[148:149], v[164:165], 1, v[150:151]
	s_and_b64 vcc, exec, s[6:7]
	s_mov_b64 s[16:17], -1
	global_store_dwordx4 v[148:149], v[182:185], off sc1
	s_cbranch_vccnz .LBB0_579
	v_mul_f32_e32 v147, v136, v44
	s_cbranch_execz .LBB0_580

.LBB0_595:
	v_cvt_pk_bf16_f32 v148, v147, v148
	v_cvt_pk_bf16_f32 v149, v149, v150
	v_cvt_pk_bf16_f32 v150, v151, v176
	v_cvt_pk_bf16_f32 v151, v177, v178
	v_lshl_add_u64 v[152:153], v[164:165], 1, v[152:153]
	s_and_b64 vcc, exec, s[6:7]
	s_mov_b64 s[16:17], -1
	global_store_dwordx4 v[152:153], v[148:151], off sc1
	s_cbranch_vccnz .LBB0_611
	v_mul_f32_e32 v147, v136, v36
	s_cbranch_execz .LBB0_612

.LBB0_627:
	v_cvt_pk_bf16_f32 v148, v147, v148
	v_cvt_pk_bf16_f32 v149, v149, v150
	v_cvt_pk_bf16_f32 v150, v151, v152
	v_cvt_pk_bf16_f32 v151, v153, v176
	v_lshl_add_u64 v[152:153], v[164:165], 1, v[154:155]
	s_and_b64 vcc, exec, s[6:7]
	s_mov_b64 s[16:17], -1
	global_store_dwordx4 v[152:153], v[148:151], off sc1
	s_cbranch_vccnz .LBB0_643
	v_mul_f32_e32 v147, v136, v28
	s_cbranch_execz .LBB0_644

.LBB0_659:
	v_cvt_pk_bf16_f32 v148, v147, v148
	v_cvt_pk_bf16_f32 v149, v149, v150
	v_cvt_pk_bf16_f32 v150, v151, v152
	v_cvt_pk_bf16_f32 v151, v153, v154
	v_lshl_add_u64 v[152:153], v[164:165], 1, v[156:157]
	s_and_b64 vcc, exec, s[6:7]
	s_mov_b64 s[16:17], -1
	global_store_dwordx4 v[152:153], v[148:151], off sc1
	s_cbranch_vccnz .LBB0_675
	v_mul_f32_e32 v147, v136, v20
	s_cbranch_execz .LBB0_676

.LBB0_691:
	v_cvt_pk_bf16_f32 v148, v147, v148
	v_cvt_pk_bf16_f32 v149, v149, v150
	v_cvt_pk_bf16_f32 v150, v151, v152
	v_cvt_pk_bf16_f32 v151, v153, v154
	v_lshl_add_u64 v[152:153], v[164:165], 1, v[158:159]
	s_and_b64 vcc, exec, s[6:7]
	s_mov_b64 s[16:17], -1
	global_store_dwordx4 v[152:153], v[148:151], off sc1
	s_cbranch_vccnz .LBB0_707
	v_mul_f32_e32 v147, v136, v12
	s_cbranch_execz .LBB0_708

.LBB0_723:
	v_cvt_pk_bf16_f32 v148, v147, v148
	v_cvt_pk_bf16_f32 v149, v149, v150
	v_cvt_pk_bf16_f32 v150, v151, v152
	v_cvt_pk_bf16_f32 v151, v153, v154
	v_lshl_add_u64 v[152:153], v[164:165], 1, v[160:161]
	s_and_b64 vcc, exec, s[6:7]
	s_mov_b64 s[16:17], -1
	global_store_dwordx4 v[152:153], v[148:151], off sc1
	s_cbranch_vccnz .LBB0_739
	v_mul_f32_e32 v147, v136, v4
	s_cbranch_execz .LBB0_740

.LBB0_755:
	v_cvt_pk_bf16_f32 v148, v147, v148
	v_cvt_pk_bf16_f32 v149, v149, v150
	v_cvt_pk_bf16_f32 v150, v151, v152
	v_cvt_pk_bf16_f32 v151, v153, v154
	v_lshl_add_u64 v[152:153], v[164:165], 1, v[162:163]
	s_mov_b64 s[6:7], 0
	global_store_dwordx4 v[152:153], v[148:151], off sc1
.LBB0_756:
	s_and_b64 vcc, exec, s[6:7]
	s_cbranch_vccz .LBB0_237
	s_lshl_b32 s0, s0, 8
	v_bitop3_b32 v136, s0, v173, v168 bitop3:0xc8
	v_lshlrev_b32_e32 v136, 2, v136
	global_load_dwordx4 v[160:163], v136, s[58:59] offset:2064
	global_load_dwordx4 v[152:155], v136, s[58:59] offset:2048
	global_load_dwordx4 v[176:179], v136, s[58:59] offset:16
	global_load_dwordx4 v[180:183], v136, s[58:59]
	v_mul_f32_e32 v124, 0xbfb8aa3b, v124
	v_exp_f32_e32 v124, v124
	v_ashrrev_i32_e32 v147, 31, v146
	v_lshlrev_b64 v[148:149], 11, v[146:147]
	v_mul_f32_e32 v125, 0xbfb8aa3b, v125
	v_add_f32_e32 v124, 1.0, v124
	v_rcp_f32_e32 v147, v124
	v_exp_f32_e32 v125, v125
	v_mul_f32_e32 v126, 0xbfb8aa3b, v126
	v_exp_f32_e32 v126, v126
	v_mul_f32_e32 v127, 0xbfb8aa3b, v127
	v_add_f32_e32 v125, 1.0, v125
	v_exp_f32_e32 v127, v127
	v_add_f32_e32 v126, 1.0, v126
	v_mul_f32_e32 v120, 0xbfb8aa3b, v120
	v_exp_f32_e32 v120, v120
	v_add_f32_e32 v127, 1.0, v127
	v_mul_f32_e32 v121, 0xbfb8aa3b, v121
	v_exp_f32_e32 v121, v121
	v_add_f32_e32 v120, 1.0, v120
	v_rcp_f32_e32 v120, v120
	v_mul_f32_e32 v122, 0xbfb8aa3b, v122
	v_add_f32_e32 v121, 1.0, v121
	v_rcp_f32_e32 v121, v121
	v_exp_f32_e32 v122, v122
	v_mul_f32_e32 v116, 0xbfb8aa3b, v116
	v_exp_f32_e32 v116, v116
	v_mul_f32_e32 v117, 0xbfb8aa3b, v117
	v_add_f32_e32 v122, 1.0, v122
	v_rcp_f32_e32 v122, v122
	v_add_f32_e32 v116, 1.0, v116
	v_rcp_f32_e32 v116, v116
	v_exp_f32_e32 v117, v117
	v_mul_f32_e32 v118, 0xbfb8aa3b, v118
	v_exp_f32_e32 v118, v118
	v_mul_f32_e32 v119, 0xbfb8aa3b, v119
	v_add_f32_e32 v117, 1.0, v117
	v_rcp_f32_e32 v117, v117
	v_add_f32_e32 v118, 1.0, v118
	v_rcp_f32_e32 v118, v118
	v_exp_f32_e32 v119, v119
	v_mul_f32_e32 v112, 0xbfb8aa3b, v112
	v_exp_f32_e32 v112, v112
	v_mul_f32_e32 v113, 0xbfb8aa3b, v113
	v_add_f32_e32 v119, 1.0, v119
	v_rcp_f32_e32 v119, v119
	v_add_f32_e32 v112, 1.0, v112
	v_rcp_f32_e32 v112, v112
	v_exp_f32_e32 v113, v113
	v_mul_f32_e32 v114, 0xbfb8aa3b, v114
	v_exp_f32_e32 v114, v114
	v_mul_f32_e32 v115, 0xbfb8aa3b, v115
	v_add_f32_e32 v113, 1.0, v113
	v_rcp_f32_e32 v113, v113
	v_add_f32_e32 v114, 1.0, v114
	v_rcp_f32_e32 v114, v114
	v_exp_f32_e32 v115, v115
	v_mul_f32_e32 v108, 0xbfb8aa3b, v108
	v_exp_f32_e32 v108, v108
	v_or_b32_e32 v150, s0, v168
	v_add_f32_e32 v115, 1.0, v115
	v_rcp_f32_e32 v115, v115
	v_add_f32_e32 v108, 1.0, v108
	v_rcp_f32_e32 v108, v108
	v_mul_f32_e32 v109, 0xbfb8aa3b, v109
	v_exp_f32_e32 v109, v109
	v_mul_f32_e32 v110, 0xbfb8aa3b, v110
	v_exp_f32_e32 v110, v110
	v_mul_f32_e32 v111, 0xbfb8aa3b, v111
	v_add_f32_e32 v109, 1.0, v109
	v_rcp_f32_e32 v109, v109
	v_add_f32_e32 v110, 1.0, v110
	v_rcp_f32_e32 v110, v110
	v_exp_f32_e32 v111, v111
	v_mul_f32_e32 v104, 0xbfb8aa3b, v104
	v_exp_f32_e32 v104, v104
	v_mul_f32_e32 v105, 0xbfb8aa3b, v105
	v_add_f32_e32 v111, 1.0, v111
	v_rcp_f32_e32 v111, v111
	s_waitcnt vmcnt(0)
	v_sub_f32_e32 v136, v152, v180
	v_mul_f32_e32 v136, 0x3fb8aa3b, v136
	v_exp_f32_e32 v136, v136
	v_add_f32_e32 v104, 1.0, v104
	v_rcp_f32_e32 v104, v104
	v_exp_f32_e32 v105, v105
	v_add_f32_e32 v136, 1.0, v136
	v_rcp_f32_e32 v158, v136
	v_sub_f32_e32 v136, v153, v181
	v_mul_f32_e32 v136, 0x3fb8aa3b, v136
	v_exp_f32_e32 v136, v136
	v_sub_f32_e32 v124, 1.0, v158
	v_fma_f32 v147, v147, v124, v158
	v_cmp_gt_f32_e32 vcc, s86, v147
	v_add_f32_e32 v136, 1.0, v136
	v_rcp_f32_e32 v157, v136
	v_sub_f32_e32 v136, v154, v182
	v_mul_f32_e32 v136, 0x3fb8aa3b, v136
	v_exp_f32_e32 v136, v136
	v_cndmask_b32_e64 v159, 0, 32, vcc
	v_ldexp_f32 v147, v147, v159
	v_log_f32_e32 v147, v147
	v_add_f32_e32 v136, 1.0, v136
	v_rcp_f32_e32 v156, v136
	v_sub_f32_e32 v136, v155, v183
	v_mul_f32_e32 v136, 0x3fb8aa3b, v136
	v_exp_f32_e32 v136, v136
	v_mul_f32_e32 v159, 0x3f317217, v147
	v_fma_f32 v159, v147, s87, -v159
	v_fmac_f32_e32 v159, 0x3377d1cf, v147
	v_add_f32_e32 v136, 1.0, v136
	v_rcp_f32_e32 v155, v136
	v_sub_f32_e32 v136, v160, v176
	v_mul_f32_e32 v136, 0x3fb8aa3b, v136
	v_exp_f32_e32 v136, v136
	v_fmac_f32_e32 v159, 0x3f317217, v147
	v_cmp_lt_f32_e64 s[6:7], |v147|, s88
	v_fma_f32 v116, v116, v124, v158
	v_add_f32_e32 v136, 1.0, v136
	v_cndmask_b32_e64 v147, v147, v159, s[6:7]
	v_cndmask_b32_e32 v159, 0, v174, vcc
	v_rcp_f32_e32 v154, v136
	v_sub_f32_e32 v136, v161, v177
	v_sub_f32_e32 v161, v147, v159
	v_rcp_f32_e32 v147, v125
	v_sub_f32_e32 v125, 1.0, v157
	v_mul_f32_e32 v136, 0x3fb8aa3b, v136
	v_exp_f32_e32 v136, v136
	v_fma_f32 v147, v147, v125, v157
	v_cmp_gt_f32_e32 vcc, s86, v147
	v_sub_f32_e32 v160, 1.0, v154
	v_add_f32_e32 v136, 1.0, v136
	v_cndmask_b32_e64 v159, 0, 32, vcc
	v_ldexp_f32 v147, v147, v159
	v_log_f32_e32 v147, v147
	v_rcp_f32_e32 v153, v136
	v_sub_f32_e32 v136, v162, v178
	v_mul_f32_e32 v136, 0x3fb8aa3b, v136
	v_mul_f32_e32 v159, 0x3f317217, v147
	v_fma_f32 v159, v147, s87, -v159
	v_fmac_f32_e32 v159, 0x3377d1cf, v147
	v_fmac_f32_e32 v159, 0x3f317217, v147
	v_cmp_lt_f32_e64 s[6:7], |v147|, s88
	v_exp_f32_e32 v136, v136
	v_fma_f32 v120, v120, v160, v154
	v_cndmask_b32_e64 v147, v147, v159, s[6:7]
	v_cndmask_b32_e32 v159, 0, v174, vcc
	v_sub_f32_e32 v162, v147, v159
	v_rcp_f32_e32 v147, v126
	v_sub_f32_e32 v126, 1.0, v156
	v_add_f32_e32 v136, 1.0, v136
	v_rcp_f32_e32 v152, v136
	v_fma_f32 v147, v147, v126, v156
	v_cmp_gt_f32_e32 vcc, s86, v147
	v_sub_f32_e32 v136, v163, v179
	v_mul_f32_e32 v136, 0x3fb8aa3b, v136
	v_cndmask_b32_e64 v159, 0, 32, vcc
	v_ldexp_f32 v147, v147, v159
	v_log_f32_e32 v147, v147
	v_exp_f32_e32 v136, v136
	v_fma_f32 v117, v117, v125, v157
	v_fma_f32 v118, v118, v126, v156
	v_mul_f32_e32 v159, 0x3f317217, v147
	v_fma_f32 v159, v147, s87, -v159
	v_fmac_f32_e32 v159, 0x3377d1cf, v147
	v_fmac_f32_e32 v159, 0x3f317217, v147
	v_cmp_lt_f32_e64 s[6:7], |v147|, s88
	v_add_f32_e32 v136, 1.0, v136
	v_rcp_f32_e32 v151, v136
	v_cndmask_b32_e64 v147, v147, v159, s[6:7]
	v_cndmask_b32_e32 v159, 0, v174, vcc
	v_sub_f32_e32 v163, v147, v159
	v_rcp_f32_e32 v147, v127
	v_sub_f32_e32 v127, 1.0, v155
	v_fma_f32 v119, v119, v127, v155
	v_fma_f32 v112, v112, v160, v154
	v_fma_f32 v147, v147, v127, v155
	v_cmp_gt_f32_e32 vcc, s86, v147
	v_lshlrev_b32_e32 v136, 1, v150
	v_fma_f32 v108, v108, v124, v158
	v_cndmask_b32_e64 v159, 0, 32, vcc
	v_ldexp_f32 v147, v147, v159
	v_log_f32_e32 v147, v147
	v_fma_f32 v109, v109, v125, v157
	v_fma_f32 v110, v110, v126, v156
	v_fma_f32 v111, v111, v127, v155
	v_mul_f32_e32 v159, 0x3f317217, v147
	v_fma_f32 v159, v147, s87, -v159
	v_fmac_f32_e32 v159, 0x3377d1cf, v147
	v_fmac_f32_e32 v159, 0x3f317217, v147
	v_cmp_lt_f32_e64 s[6:7], |v147|, s88
	v_fma_f32 v104, v104, v160, v154
	v_add_f32_e32 v105, 1.0, v105
	v_cndmask_b32_e64 v147, v147, v159, s[6:7]
	v_cndmask_b32_e32 v159, 0, v174, vcc
	v_cmp_gt_f32_e32 vcc, s86, v120
	v_sub_f32_e32 v176, v147, v159
	v_rcp_f32_e32 v105, v105
	v_cndmask_b32_e64 v147, 0, 32, vcc
	v_ldexp_f32 v120, v120, v147
	v_log_f32_e32 v120, v120
	v_mul_f32_e32 v106, 0xbfb8aa3b, v106
	v_exp_f32_e32 v106, v106
	v_mul_f32_e32 v107, 0xbfb8aa3b, v107
	v_mul_f32_e32 v147, 0x3f317217, v120
	v_fma_f32 v147, v120, s87, -v147
	v_fmac_f32_e32 v147, 0x3377d1cf, v120
	v_fmac_f32_e32 v147, 0x3f317217, v120
	v_cmp_lt_f32_e64 s[6:7], |v120|, s88
	v_add_f32_e32 v106, 1.0, v106
	v_rcp_f32_e32 v106, v106
	v_cndmask_b32_e64 v120, v120, v147, s[6:7]
	v_cndmask_b32_e32 v147, 0, v174, vcc
	v_sub_f32_e32 v120, v120, v147
	v_sub_f32_e32 v147, 1.0, v153
	v_fma_f32 v121, v121, v147, v153
	v_cmp_gt_f32_e32 vcc, s86, v121
	v_fma_f32 v113, v113, v147, v153
	v_fma_f32 v105, v105, v147, v153
	v_cndmask_b32_e64 v159, 0, 32, vcc
	v_ldexp_f32 v121, v121, v159
	v_log_f32_e32 v121, v121
	v_exp_f32_e32 v107, v107
	v_mul_f32_e32 v100, 0xbfb8aa3b, v100
	v_exp_f32_e32 v100, v100
	v_mul_f32_e32 v159, 0x3f317217, v121
	v_fma_f32 v159, v121, s87, -v159
	v_fmac_f32_e32 v159, 0x3377d1cf, v121
	v_fmac_f32_e32 v159, 0x3f317217, v121
	v_cmp_lt_f32_e64 s[6:7], |v121|, s88
	v_add_f32_e32 v107, 1.0, v107
	v_rcp_f32_e32 v107, v107
	v_cndmask_b32_e64 v121, v121, v159, s[6:7]
	v_cndmask_b32_e32 v159, 0, v174, vcc
	v_sub_f32_e32 v121, v121, v159
	v_sub_f32_e32 v159, 1.0, v152
	v_fma_f32 v122, v122, v159, v152
	v_cmp_gt_f32_e32 vcc, s86, v122
	v_fma_f32 v114, v114, v159, v152
	v_fma_f32 v106, v106, v159, v152
	v_cndmask_b32_e64 v164, 0, 32, vcc
	v_ldexp_f32 v122, v122, v164
	v_log_f32_e32 v122, v122
	v_add_f32_e32 v100, 1.0, v100
	v_rcp_f32_e32 v100, v100
	v_mul_f32_e32 v101, 0xbfb8aa3b, v101
	v_mul_f32_e32 v164, 0x3f317217, v122
	v_fma_f32 v164, v122, s87, -v164
	v_fmac_f32_e32 v164, 0x3377d1cf, v122
	v_fmac_f32_e32 v164, 0x3f317217, v122
	v_cmp_lt_f32_e64 s[6:7], |v122|, s88
	v_fma_f32 v100, v100, v124, v158
	v_exp_f32_e32 v101, v101
	v_cndmask_b32_e64 v122, v122, v164, s[6:7]
	v_cndmask_b32_e32 v164, 0, v174, vcc
	v_sub_f32_e32 v164, v122, v164
	v_mul_f32_e32 v122, 0xbfb8aa3b, v123
	v_exp_f32_e32 v122, v122
	v_add_f32_e32 v101, 1.0, v101
	v_rcp_f32_e32 v101, v101
	v_mul_f32_e32 v102, 0xbfb8aa3b, v102
	v_add_f32_e32 v122, 1.0, v122
	v_rcp_f32_e32 v123, v122
	v_sub_f32_e32 v122, 1.0, v151
	v_fma_f32 v115, v115, v122, v151
	v_fma_f32 v107, v107, v122, v151
	v_fma_f32 v123, v123, v122, v151
	v_cmp_gt_f32_e32 vcc, s86, v123
	v_fma_f32 v101, v101, v125, v157
	v_exp_f32_e32 v102, v102
	v_cndmask_b32_e64 v165, 0, 32, vcc
	v_ldexp_f32 v123, v123, v165
	v_log_f32_e32 v123, v123
	v_add_f32_e32 v102, 1.0, v102
	v_rcp_f32_e32 v102, v102
	v_mul_f32_e32 v103, 0xbfb8aa3b, v103
	v_mul_f32_e32 v165, 0x3f317217, v123
	v_fma_f32 v165, v123, s87, -v165
	v_fmac_f32_e32 v165, 0x3377d1cf, v123
	v_fmac_f32_e32 v165, 0x3f317217, v123
	v_cmp_lt_f32_e64 s[6:7], |v123|, s88
	v_fma_f32 v102, v102, v126, v156
	v_exp_f32_e32 v103, v103
	v_cndmask_b32_e64 v123, v123, v165, s[6:7]
	v_cndmask_b32_e32 v165, 0, v174, vcc
	v_sub_f32_e32 v123, v123, v165
	v_cmp_gt_f32_e32 vcc, s86, v116
	v_cvt_pk_f16_f32 v165, v164, v123
	v_cvt_pk_f16_f32 v164, v120, v121
	v_cndmask_b32_e64 v123, 0, 32, vcc
	v_ldexp_f32 v116, v116, v123
	v_log_f32_e32 v116, v116
	v_or_b32_e32 v120, 16, v146
	v_ashrrev_i32_e32 v121, 31, v120
	v_lshlrev_b64 v[120:121], 11, v[120:121]
	v_mul_f32_e32 v123, 0x3f317217, v116
	v_fma_f32 v123, v116, s87, -v123
	v_fmac_f32_e32 v123, 0x3377d1cf, v116
	v_fmac_f32_e32 v123, 0x3f317217, v116
	v_cmp_lt_f32_e64 s[6:7], |v116|, s88
	v_lshl_add_u64 v[120:121], s[84:85], 0, v[120:121]
	v_lshl_add_u64 v[120:121], v[120:121], 0, v[136:137]
	v_cndmask_b32_e64 v116, v116, v123, s[6:7]
	v_cndmask_b32_e32 v123, 0, v174, vcc
	v_cmp_gt_f32_e32 vcc, s86, v117
	v_sub_f32_e32 v116, v116, v123
	v_add_f32_e32 v103, 1.0, v103
	v_cndmask_b32_e64 v123, 0, 32, vcc
	v_ldexp_f32 v117, v117, v123
	v_log_f32_e32 v117, v117
	v_rcp_f32_e32 v103, v103
	v_mul_f32_e32 v96, 0xbfb8aa3b, v96
	v_exp_f32_e32 v96, v96
	v_mul_f32_e32 v123, 0x3f317217, v117
	v_fma_f32 v123, v117, s87, -v123
	v_fmac_f32_e32 v123, 0x3377d1cf, v117
	v_fmac_f32_e32 v123, 0x3f317217, v117
	v_cmp_lt_f32_e64 s[6:7], |v117|, s88
	v_fma_f32 v103, v103, v127, v155
	v_add_f32_e32 v96, 1.0, v96
	v_cndmask_b32_e64 v117, v117, v123, s[6:7]
	v_cndmask_b32_e32 v123, 0, v174, vcc
	v_cmp_gt_f32_e32 vcc, s86, v118
	v_sub_f32_e32 v117, v117, v123
	v_rcp_f32_e32 v96, v96
	v_cndmask_b32_e64 v123, 0, 32, vcc
	v_ldexp_f32 v118, v118, v123
	v_log_f32_e32 v118, v118
	v_fma_f32 v96, v96, v160, v154
	v_mul_f32_e32 v97, 0xbfb8aa3b, v97
	v_exp_f32_e32 v97, v97
	v_mul_f32_e32 v123, 0x3f317217, v118
	v_fma_f32 v123, v118, s87, -v123
	v_fmac_f32_e32 v123, 0x3377d1cf, v118
	v_fmac_f32_e32 v123, 0x3f317217, v118
	v_cmp_lt_f32_e64 s[6:7], |v118|, s88
	v_add_f32_e32 v97, 1.0, v97
	v_rcp_f32_e32 v97, v97
	v_cndmask_b32_e64 v118, v118, v123, s[6:7]
	v_cndmask_b32_e32 v123, 0, v174, vcc
	v_cmp_gt_f32_e32 vcc, s86, v119
	v_sub_f32_e32 v118, v118, v123
	v_fma_f32 v97, v97, v147, v153
	v_cndmask_b32_e64 v123, 0, 32, vcc
	v_ldexp_f32 v119, v119, v123
	v_log_f32_e32 v119, v119
	v_mul_f32_e32 v98, 0xbfb8aa3b, v98
	v_exp_f32_e32 v98, v98
	v_mul_f32_e32 v99, 0xbfb8aa3b, v99
	v_mul_f32_e32 v123, 0x3f317217, v119
	v_fma_f32 v123, v119, s87, -v123
	v_fmac_f32_e32 v123, 0x3377d1cf, v119
	v_fmac_f32_e32 v123, 0x3f317217, v119
	v_cmp_lt_f32_e64 s[6:7], |v119|, s88
	v_add_f32_e32 v98, 1.0, v98
	v_rcp_f32_e32 v98, v98
	v_cndmask_b32_e64 v119, v119, v123, s[6:7]
	v_cndmask_b32_e32 v123, 0, v174, vcc
	v_cmp_gt_f32_e32 vcc, s86, v112
	v_sub_f32_e32 v119, v119, v123
	v_fma_f32 v98, v98, v159, v152
	v_cndmask_b32_e64 v123, 0, 32, vcc
	v_ldexp_f32 v112, v112, v123
	v_log_f32_e32 v112, v112
	v_exp_f32_e32 v99, v99
	v_mul_f32_e32 v92, 0xbfb8aa3b, v92
	v_exp_f32_e32 v92, v92
	v_mul_f32_e32 v123, 0x3f317217, v112
	v_fma_f32 v123, v112, s87, -v123
	v_fmac_f32_e32 v123, 0x3377d1cf, v112
	v_fmac_f32_e32 v123, 0x3f317217, v112
	v_cmp_lt_f32_e64 s[6:7], |v112|, s88
	v_add_f32_e32 v99, 1.0, v99
	v_rcp_f32_e32 v99, v99
	v_cndmask_b32_e64 v112, v112, v123, s[6:7]
	v_cndmask_b32_e32 v123, 0, v174, vcc
	v_cmp_gt_f32_e32 vcc, s86, v113
	v_sub_f32_e32 v112, v112, v123
	v_fma_f32 v99, v99, v122, v151
	v_cndmask_b32_e64 v123, 0, 32, vcc
	v_ldexp_f32 v113, v113, v123
	v_log_f32_e32 v113, v113
	v_add_f32_e32 v92, 1.0, v92
	v_rcp_f32_e32 v92, v92
	v_mul_f32_e32 v93, 0xbfb8aa3b, v93
	v_mul_f32_e32 v123, 0x3f317217, v113
	v_fma_f32 v123, v113, s87, -v123
	v_fmac_f32_e32 v123, 0x3377d1cf, v113
	v_fmac_f32_e32 v123, 0x3f317217, v113
	v_cmp_lt_f32_e64 s[6:7], |v113|, s88
	v_fma_f32 v92, v92, v124, v158
	v_exp_f32_e32 v93, v93
	v_cndmask_b32_e64 v113, v113, v123, s[6:7]
	v_cndmask_b32_e32 v123, 0, v174, vcc
	v_cmp_gt_f32_e32 vcc, s86, v114
	v_sub_f32_e32 v113, v113, v123
	v_add_f32_e32 v93, 1.0, v93
	v_cndmask_b32_e64 v123, 0, 32, vcc
	v_ldexp_f32 v114, v114, v123
	v_log_f32_e32 v114, v114
	v_rcp_f32_e32 v93, v93
	v_lshl_add_u64 v[148:149], s[84:85], 0, v[148:149]
	v_lshl_add_u64 v[148:149], v[148:149], 0, v[136:137]
	v_mul_f32_e32 v123, 0x3f317217, v114
	v_fma_f32 v123, v114, s87, -v123
	v_fmac_f32_e32 v123, 0x3377d1cf, v114
	v_fmac_f32_e32 v123, 0x3f317217, v114
	v_cmp_lt_f32_e64 s[6:7], |v114|, s88
	v_fma_f32 v93, v93, v125, v157
	v_mul_f32_e32 v94, 0xbfb8aa3b, v94
	v_cndmask_b32_e64 v114, v114, v123, s[6:7]
	v_cndmask_b32_e32 v123, 0, v174, vcc
	v_cmp_gt_f32_e32 vcc, s86, v115
	v_sub_f32_e32 v114, v114, v123
	v_exp_f32_e32 v94, v94
	v_cndmask_b32_e64 v123, 0, 32, vcc
	v_ldexp_f32 v115, v115, v123
	v_log_f32_e32 v115, v115
	v_add_f32_e32 v94, 1.0, v94
	v_rcp_f32_e32 v94, v94
	v_mul_f32_e32 v95, 0xbfb8aa3b, v95
	v_mul_f32_e32 v123, 0x3f317217, v115
	v_fma_f32 v123, v115, s87, -v123
	v_fmac_f32_e32 v123, 0x3377d1cf, v115
	v_fmac_f32_e32 v123, 0x3f317217, v115
	v_cmp_lt_f32_e64 s[6:7], |v115|, s88
	v_fma_f32 v94, v94, v126, v156
	v_exp_f32_e32 v95, v95
	v_cndmask_b32_e64 v115, v115, v123, s[6:7]
	v_cndmask_b32_e32 v123, 0, v174, vcc
	v_sub_f32_e32 v115, v115, v123
	v_cvt_pk_f16_f32 v115, v114, v115
	v_cvt_pk_f16_f32 v114, v112, v113
	v_cvt_pk_f16_f32 v113, v118, v119
	v_cvt_pk_f16_f32 v112, v116, v117
	v_cmp_gt_f32_e32 vcc, s86, v108
	global_store_dwordx4 v[120:121], v[112:115], off offset:-2048 sc1
	v_add_f32_e32 v95, 1.0, v95
	v_rcp_f32_e32 v95, v95
	v_cndmask_b32_e64 v114, 0, 32, vcc
	v_ldexp_f32 v108, v108, v114
	v_log_f32_e32 v108, v108
	v_or_b32_e32 v112, 32, v146
	v_ashrrev_i32_e32 v113, 31, v112
	v_lshlrev_b64 v[112:113], 11, v[112:113]
	v_mul_f32_e32 v114, 0x3f317217, v108
	v_fma_f32 v114, v108, s87, -v114
	v_fmac_f32_e32 v114, 0x3377d1cf, v108
	v_fmac_f32_e32 v114, 0x3f317217, v108
	v_cmp_lt_f32_e64 s[6:7], |v108|, s88
	v_lshl_add_u64 v[112:113], s[84:85], 0, v[112:113]
	v_lshl_add_u64 v[112:113], v[112:113], 0, v[136:137]
	v_cndmask_b32_e64 v108, v108, v114, s[6:7]
	v_cndmask_b32_e32 v114, 0, v174, vcc
	v_cmp_gt_f32_e32 vcc, s86, v109
	v_sub_f32_e32 v108, v108, v114
	v_fma_f32 v95, v95, v127, v155
	v_cndmask_b32_e64 v114, 0, 32, vcc
	v_ldexp_f32 v109, v109, v114
	v_log_f32_e32 v109, v109
	v_mul_f32_e32 v88, 0xbfb8aa3b, v88
	v_exp_f32_e32 v88, v88
	v_mul_f32_e32 v89, 0xbfb8aa3b, v89
	v_mul_f32_e32 v114, 0x3f317217, v109
	v_fma_f32 v114, v109, s87, -v114
	v_fmac_f32_e32 v114, 0x3377d1cf, v109
	v_fmac_f32_e32 v114, 0x3f317217, v109
	v_cmp_lt_f32_e64 s[6:7], |v109|, s88
	v_add_f32_e32 v88, 1.0, v88
	v_rcp_f32_e32 v88, v88
	v_cndmask_b32_e64 v109, v109, v114, s[6:7]
	v_cndmask_b32_e32 v114, 0, v174, vcc
	v_cmp_gt_f32_e32 vcc, s86, v110
	v_sub_f32_e32 v109, v109, v114
	v_fma_f32 v88, v88, v160, v154
	v_cndmask_b32_e64 v114, 0, 32, vcc
	v_ldexp_f32 v110, v110, v114
	v_log_f32_e32 v110, v110
	v_exp_f32_e32 v89, v89
	v_mul_f32_e32 v90, 0xbfb8aa3b, v90
	v_exp_f32_e32 v90, v90
	v_mul_f32_e32 v114, 0x3f317217, v110
	v_fma_f32 v114, v110, s87, -v114
	v_fmac_f32_e32 v114, 0x3377d1cf, v110
	v_fmac_f32_e32 v114, 0x3f317217, v110
	v_cmp_lt_f32_e64 s[6:7], |v110|, s88
	v_add_f32_e32 v89, 1.0, v89
	v_rcp_f32_e32 v89, v89
	v_cndmask_b32_e64 v110, v110, v114, s[6:7]
	v_cndmask_b32_e32 v114, 0, v174, vcc
	v_cmp_gt_f32_e32 vcc, s86, v111
	v_sub_f32_e32 v110, v110, v114
	v_fma_f32 v89, v89, v147, v153
	v_cndmask_b32_e64 v114, 0, 32, vcc
	v_ldexp_f32 v111, v111, v114
	v_log_f32_e32 v111, v111
	v_add_f32_e32 v90, 1.0, v90
	v_rcp_f32_e32 v90, v90
	v_mul_f32_e32 v91, 0xbfb8aa3b, v91
	v_mul_f32_e32 v114, 0x3f317217, v111
	v_fma_f32 v114, v111, s87, -v114
	v_fmac_f32_e32 v114, 0x3377d1cf, v111
	v_fmac_f32_e32 v114, 0x3f317217, v111
	v_cmp_lt_f32_e64 s[6:7], |v111|, s88
	v_fma_f32 v90, v90, v159, v152
	v_exp_f32_e32 v91, v91
	v_cndmask_b32_e64 v111, v111, v114, s[6:7]
	v_cndmask_b32_e32 v114, 0, v174, vcc
	v_cmp_gt_f32_e32 vcc, s86, v104
	v_sub_f32_e32 v111, v111, v114
	v_add_f32_e32 v91, 1.0, v91
	v_cndmask_b32_e64 v114, 0, 32, vcc
	v_ldexp_f32 v104, v104, v114
	v_log_f32_e32 v104, v104
	v_rcp_f32_e32 v91, v91
	v_mul_f32_e32 v84, 0xbfb8aa3b, v84
	v_exp_f32_e32 v84, v84
	v_mul_f32_e32 v114, 0x3f317217, v104
	v_fma_f32 v114, v104, s87, -v114
	v_fmac_f32_e32 v114, 0x3377d1cf, v104
	v_fmac_f32_e32 v114, 0x3f317217, v104
	v_cmp_lt_f32_e64 s[6:7], |v104|, s88
	v_fma_f32 v91, v91, v122, v151
	v_add_f32_e32 v84, 1.0, v84
	v_cndmask_b32_e64 v104, v104, v114, s[6:7]
	v_cndmask_b32_e32 v114, 0, v174, vcc
	v_cmp_gt_f32_e32 vcc, s86, v105
	v_sub_f32_e32 v104, v104, v114
	v_rcp_f32_e32 v84, v84
	v_cndmask_b32_e64 v114, 0, 32, vcc
	v_ldexp_f32 v105, v105, v114
	v_log_f32_e32 v105, v105
	v_fma_f32 v84, v84, v124, v158
	v_mul_f32_e32 v85, 0xbfb8aa3b, v85
	v_exp_f32_e32 v85, v85
	v_mul_f32_e32 v114, 0x3f317217, v105
	v_fma_f32 v114, v105, s87, -v114
	v_fmac_f32_e32 v114, 0x3377d1cf, v105
	v_fmac_f32_e32 v114, 0x3f317217, v105
	v_cmp_lt_f32_e64 s[6:7], |v105|, s88
	v_add_f32_e32 v85, 1.0, v85
	v_rcp_f32_e32 v85, v85
	v_cndmask_b32_e64 v105, v105, v114, s[6:7]
	v_cndmask_b32_e32 v114, 0, v174, vcc
	v_cmp_gt_f32_e32 vcc, s86, v106
	v_sub_f32_e32 v105, v105, v114
	v_fma_f32 v85, v85, v125, v157
	v_cndmask_b32_e64 v114, 0, 32, vcc
	v_ldexp_f32 v106, v106, v114
	v_log_f32_e32 v106, v106
	v_mul_f32_e32 v86, 0xbfb8aa3b, v86
	v_exp_f32_e32 v86, v86
	v_mul_f32_e32 v87, 0xbfb8aa3b, v87
	v_mul_f32_e32 v114, 0x3f317217, v106
	v_fma_f32 v114, v106, s87, -v114
	v_fmac_f32_e32 v114, 0x3377d1cf, v106
	v_fmac_f32_e32 v114, 0x3f317217, v106
	v_cmp_lt_f32_e64 s[6:7], |v106|, s88
	v_add_f32_e32 v86, 1.0, v86
	v_rcp_f32_e32 v86, v86
	v_cndmask_b32_e64 v106, v106, v114, s[6:7]
	v_cndmask_b32_e32 v114, 0, v174, vcc
	v_cmp_gt_f32_e32 vcc, s86, v107
	v_sub_f32_e32 v106, v106, v114
	v_fma_f32 v86, v86, v126, v156
	v_cndmask_b32_e64 v114, 0, 32, vcc
	v_ldexp_f32 v107, v107, v114
	v_log_f32_e32 v107, v107
	v_exp_f32_e32 v87, v87
	v_mul_f32_e32 v80, 0xbfb8aa3b, v80
	v_exp_f32_e32 v80, v80
	v_mul_f32_e32 v114, 0x3f317217, v107
	v_fma_f32 v114, v107, s87, -v114
	v_fmac_f32_e32 v114, 0x3377d1cf, v107
	v_fmac_f32_e32 v114, 0x3f317217, v107
	v_cmp_lt_f32_e64 s[6:7], |v107|, s88
	v_add_f32_e32 v87, 1.0, v87
	v_rcp_f32_e32 v87, v87
	v_cndmask_b32_e64 v107, v107, v114, s[6:7]
	v_cndmask_b32_e32 v114, 0, v174, vcc
	v_sub_f32_e32 v107, v107, v114
	v_cvt_pk_f16_f32 v107, v106, v107
	v_cvt_pk_f16_f32 v106, v104, v105
	v_cvt_pk_f16_f32 v105, v110, v111
	v_cvt_pk_f16_f32 v104, v108, v109
	v_cmp_gt_f32_e32 vcc, s86, v100
	global_store_dwordx4 v[112:113], v[104:107], off offset:-2048 sc1
	v_fma_f32 v87, v87, v127, v155
	v_add_f32_e32 v80, 1.0, v80
	v_cndmask_b32_e64 v106, 0, 32, vcc
	v_ldexp_f32 v100, v100, v106
	v_log_f32_e32 v100, v100
	v_or_b32_e32 v104, 48, v146
	v_ashrrev_i32_e32 v105, 31, v104
	v_lshlrev_b64 v[104:105], 11, v[104:105]
	v_mul_f32_e32 v106, 0x3f317217, v100
	v_fma_f32 v106, v100, s87, -v106
	v_fmac_f32_e32 v106, 0x3377d1cf, v100
	v_fmac_f32_e32 v106, 0x3f317217, v100
	v_cmp_lt_f32_e64 s[6:7], |v100|, s88
	v_lshl_add_u64 v[104:105], s[84:85], 0, v[104:105]
	v_lshl_add_u64 v[104:105], v[104:105], 0, v[136:137]
	v_cndmask_b32_e64 v100, v100, v106, s[6:7]
	v_cndmask_b32_e32 v106, 0, v174, vcc
	v_cmp_gt_f32_e32 vcc, s86, v101
	v_sub_f32_e32 v100, v100, v106
	v_rcp_f32_e32 v80, v80
	v_cndmask_b32_e64 v106, 0, 32, vcc
	v_ldexp_f32 v101, v101, v106
	v_log_f32_e32 v101, v101
	v_fma_f32 v80, v80, v160, v154
	v_mul_f32_e32 v81, 0xbfb8aa3b, v81
	v_exp_f32_e32 v81, v81
	v_mul_f32_e32 v106, 0x3f317217, v101
	v_fma_f32 v106, v101, s87, -v106
	v_fmac_f32_e32 v106, 0x3377d1cf, v101
	v_fmac_f32_e32 v106, 0x3f317217, v101
	v_cmp_lt_f32_e64 s[6:7], |v101|, s88
	v_add_f32_e32 v81, 1.0, v81
	v_rcp_f32_e32 v81, v81
	v_cndmask_b32_e64 v101, v101, v106, s[6:7]
	v_cndmask_b32_e32 v106, 0, v174, vcc
	v_cmp_gt_f32_e32 vcc, s86, v102
	v_sub_f32_e32 v101, v101, v106
	v_fma_f32 v81, v81, v147, v153
	v_cndmask_b32_e64 v106, 0, 32, vcc
	v_ldexp_f32 v102, v102, v106
	v_log_f32_e32 v102, v102
	v_mul_f32_e32 v82, 0xbfb8aa3b, v82
	v_exp_f32_e32 v82, v82
	v_mul_f32_e32 v83, 0xbfb8aa3b, v83
	v_mul_f32_e32 v106, 0x3f317217, v102
	v_fma_f32 v106, v102, s87, -v106
	v_fmac_f32_e32 v106, 0x3377d1cf, v102
	v_fmac_f32_e32 v106, 0x3f317217, v102
	v_cmp_lt_f32_e64 s[6:7], |v102|, s88
	v_add_f32_e32 v82, 1.0, v82
	v_rcp_f32_e32 v82, v82
	v_cndmask_b32_e64 v102, v102, v106, s[6:7]
	v_cndmask_b32_e32 v106, 0, v174, vcc
	v_cmp_gt_f32_e32 vcc, s86, v103
	v_sub_f32_e32 v102, v102, v106
	v_fma_f32 v82, v82, v159, v152
	v_cndmask_b32_e64 v106, 0, 32, vcc
	v_ldexp_f32 v103, v103, v106
	v_log_f32_e32 v103, v103
	v_exp_f32_e32 v83, v83
	v_mul_f32_e32 v76, 0xbfb8aa3b, v76
	v_exp_f32_e32 v76, v76
	v_mul_f32_e32 v106, 0x3f317217, v103
	v_fma_f32 v106, v103, s87, -v106
	v_fmac_f32_e32 v106, 0x3377d1cf, v103
	v_fmac_f32_e32 v106, 0x3f317217, v103
	v_cmp_lt_f32_e64 s[6:7], |v103|, s88
	v_add_f32_e32 v83, 1.0, v83
	v_rcp_f32_e32 v83, v83
	v_cndmask_b32_e64 v103, v103, v106, s[6:7]
	v_cndmask_b32_e32 v106, 0, v174, vcc
	v_cmp_gt_f32_e32 vcc, s86, v96
	v_sub_f32_e32 v103, v103, v106
	v_fma_f32 v83, v83, v122, v151
	v_cndmask_b32_e64 v106, 0, 32, vcc
	v_ldexp_f32 v96, v96, v106
	v_log_f32_e32 v96, v96
	v_add_f32_e32 v76, 1.0, v76
	v_rcp_f32_e32 v76, v76
	v_mul_f32_e32 v77, 0xbfb8aa3b, v77
	v_mul_f32_e32 v106, 0x3f317217, v96
	v_fma_f32 v106, v96, s87, -v106
	v_fmac_f32_e32 v106, 0x3377d1cf, v96
	v_fmac_f32_e32 v106, 0x3f317217, v96
	v_cmp_lt_f32_e64 s[6:7], |v96|, s88
	v_fma_f32 v76, v76, v124, v158
	v_exp_f32_e32 v77, v77
	v_cndmask_b32_e64 v96, v96, v106, s[6:7]
	v_cndmask_b32_e32 v106, 0, v174, vcc
	v_cmp_gt_f32_e32 vcc, s86, v97
	v_sub_f32_e32 v96, v96, v106
	v_add_f32_e32 v77, 1.0, v77
	v_cndmask_b32_e64 v106, 0, 32, vcc
	v_ldexp_f32 v97, v97, v106
	v_log_f32_e32 v97, v97
	v_rcp_f32_e32 v77, v77
	v_mul_f32_e32 v78, 0xbfb8aa3b, v78
	v_exp_f32_e32 v78, v78
	v_mul_f32_e32 v106, 0x3f317217, v97
	v_fma_f32 v106, v97, s87, -v106
	v_fmac_f32_e32 v106, 0x3377d1cf, v97
	v_fmac_f32_e32 v106, 0x3f317217, v97
	v_cmp_lt_f32_e64 s[6:7], |v97|, s88
	v_fma_f32 v77, v77, v125, v157
	v_add_f32_e32 v78, 1.0, v78
	v_cndmask_b32_e64 v97, v97, v106, s[6:7]
	v_cndmask_b32_e32 v106, 0, v174, vcc
	v_cmp_gt_f32_e32 vcc, s86, v98
	v_sub_f32_e32 v97, v97, v106
	v_rcp_f32_e32 v78, v78
	v_cndmask_b32_e64 v106, 0, 32, vcc
	v_ldexp_f32 v98, v98, v106
	v_log_f32_e32 v98, v98
	v_fma_f32 v78, v78, v126, v156
	v_mul_f32_e32 v79, 0xbfb8aa3b, v79
	v_exp_f32_e32 v79, v79
	v_mul_f32_e32 v106, 0x3f317217, v98
	v_fma_f32 v106, v98, s87, -v106
	v_fmac_f32_e32 v106, 0x3377d1cf, v98
	v_fmac_f32_e32 v106, 0x3f317217, v98
	v_cmp_lt_f32_e64 s[6:7], |v98|, s88
	v_add_f32_e32 v79, 1.0, v79
	v_rcp_f32_e32 v79, v79
	v_cndmask_b32_e64 v98, v98, v106, s[6:7]
	v_cndmask_b32_e32 v106, 0, v174, vcc
	v_cmp_gt_f32_e32 vcc, s86, v99
	v_sub_f32_e32 v98, v98, v106
	v_fma_f32 v79, v79, v127, v155
	v_cndmask_b32_e64 v106, 0, 32, vcc
	v_ldexp_f32 v99, v99, v106
	v_log_f32_e32 v99, v99
	v_mul_f32_e32 v72, 0xbfb8aa3b, v72
	v_exp_f32_e32 v72, v72
	v_mul_f32_e32 v73, 0xbfb8aa3b, v73
	v_mul_f32_e32 v106, 0x3f317217, v99
	v_fma_f32 v106, v99, s87, -v106
	v_fmac_f32_e32 v106, 0x3377d1cf, v99
	v_fmac_f32_e32 v106, 0x3f317217, v99
	v_cmp_lt_f32_e64 s[6:7], |v99|, s88
	v_add_f32_e32 v72, 1.0, v72
	v_rcp_f32_e32 v72, v72
	v_cndmask_b32_e64 v99, v99, v106, s[6:7]
	v_cndmask_b32_e32 v106, 0, v174, vcc
	v_sub_f32_e32 v99, v99, v106
	v_cvt_pk_f16_f32 v99, v98, v99
	v_cvt_pk_f16_f32 v98, v96, v97
	v_cvt_pk_f16_f32 v97, v102, v103
	v_cvt_pk_f16_f32 v96, v100, v101
	v_cmp_gt_f32_e32 vcc, s86, v92
	global_store_dwordx4 v[104:105], v[96:99], off offset:-2048 sc1
	s_mov_b64 s[6:7], 0x40000
	v_fma_f32 v72, v72, v160, v154
	v_cndmask_b32_e64 v98, 0, 32, vcc
	v_ldexp_f32 v92, v92, v98
	v_log_f32_e32 v92, v92
	v_lshl_add_u64 v[96:97], v[148:149], 0, s[6:7]
	v_exp_f32_e32 v73, v73
	v_mul_f32_e32 v74, 0xbfb8aa3b, v74
	v_mul_f32_e32 v98, 0x3f317217, v92
	v_fma_f32 v98, v92, s87, -v98
	v_fmac_f32_e32 v98, 0x3377d1cf, v92
	v_fmac_f32_e32 v98, 0x3f317217, v92
	v_cmp_lt_f32_e64 s[6:7], |v92|, s88
	v_add_f32_e32 v73, 1.0, v73
	v_rcp_f32_e32 v73, v73
	v_cndmask_b32_e64 v92, v92, v98, s[6:7]
	v_cndmask_b32_e32 v98, 0, v174, vcc
	v_cmp_gt_f32_e32 vcc, s86, v93
	v_sub_f32_e32 v92, v92, v98
	v_fma_f32 v73, v73, v147, v153
	v_cndmask_b32_e64 v98, 0, 32, vcc
	v_ldexp_f32 v93, v93, v98
	v_log_f32_e32 v93, v93
	v_exp_f32_e32 v74, v74
	v_mul_f32_e32 v75, 0xbfb8aa3b, v75
	v_exp_f32_e32 v75, v75
	v_mul_f32_e32 v98, 0x3f317217, v93
	v_fma_f32 v98, v93, s87, -v98
	v_fmac_f32_e32 v98, 0x3377d1cf, v93
	v_fmac_f32_e32 v98, 0x3f317217, v93
	v_cmp_lt_f32_e64 s[6:7], |v93|, s88
	v_add_f32_e32 v74, 1.0, v74
	v_rcp_f32_e32 v74, v74
	v_cndmask_b32_e64 v93, v93, v98, s[6:7]
	v_cndmask_b32_e32 v98, 0, v174, vcc
	v_cmp_gt_f32_e32 vcc, s86, v94
	v_sub_f32_e32 v93, v93, v98
	v_fma_f32 v74, v74, v159, v152
	v_cndmask_b32_e64 v98, 0, 32, vcc
	v_ldexp_f32 v94, v94, v98
	v_log_f32_e32 v94, v94
	v_add_f32_e32 v75, 1.0, v75
	v_rcp_f32_e32 v75, v75
	v_mul_f32_e32 v68, 0xbfb8aa3b, v68
	v_mul_f32_e32 v98, 0x3f317217, v94
	v_fma_f32 v98, v94, s87, -v98
	v_fmac_f32_e32 v98, 0x3377d1cf, v94
	v_fmac_f32_e32 v98, 0x3f317217, v94
	v_cmp_lt_f32_e64 s[6:7], |v94|, s88
	v_fma_f32 v75, v75, v122, v151
	v_exp_f32_e32 v68, v68
	v_cndmask_b32_e64 v94, v94, v98, s[6:7]
	v_cndmask_b32_e32 v98, 0, v174, vcc
	v_cmp_gt_f32_e32 vcc, s86, v95
	v_sub_f32_e32 v94, v94, v98
	v_add_f32_e32 v68, 1.0, v68
	v_cndmask_b32_e64 v98, 0, 32, vcc
	v_ldexp_f32 v95, v95, v98
	v_log_f32_e32 v95, v95
	v_rcp_f32_e32 v68, v68
	v_mul_f32_e32 v69, 0xbfb8aa3b, v69
	v_exp_f32_e32 v69, v69
	v_mul_f32_e32 v98, 0x3f317217, v95
	v_fma_f32 v98, v95, s87, -v98
	v_fmac_f32_e32 v98, 0x3377d1cf, v95
	v_fmac_f32_e32 v98, 0x3f317217, v95
	v_cmp_lt_f32_e64 s[6:7], |v95|, s88
	v_fmac_f32_e32 v158, v68, v124
	v_add_f32_e32 v69, 1.0, v69
	v_cndmask_b32_e64 v95, v95, v98, s[6:7]
	v_cndmask_b32_e32 v98, 0, v174, vcc
	v_cmp_gt_f32_e32 vcc, s86, v88
	v_sub_f32_e32 v95, v95, v98
	v_rcp_f32_e32 v69, v69
	v_cndmask_b32_e64 v98, 0, 32, vcc
	v_ldexp_f32 v88, v88, v98
	v_log_f32_e32 v88, v88
	v_fmac_f32_e32 v157, v69, v125
	v_mul_f32_e32 v70, 0xbfb8aa3b, v70
	v_exp_f32_e32 v70, v70
	v_mul_f32_e32 v98, 0x3f317217, v88
	v_fma_f32 v98, v88, s87, -v98
	v_fmac_f32_e32 v98, 0x3377d1cf, v88
	v_fmac_f32_e32 v98, 0x3f317217, v88
	v_cmp_lt_f32_e64 s[6:7], |v88|, s88
	v_add_f32_e32 v70, 1.0, v70
	v_rcp_f32_e32 v70, v70
	v_cndmask_b32_e64 v88, v88, v98, s[6:7]
	v_cndmask_b32_e32 v98, 0, v174, vcc
	v_cmp_gt_f32_e32 vcc, s86, v89
	v_sub_f32_e32 v88, v88, v98
	v_fmac_f32_e32 v156, v70, v126
	v_cndmask_b32_e64 v98, 0, 32, vcc
	v_ldexp_f32 v89, v89, v98
	v_log_f32_e32 v89, v89
	v_mul_f32_e32 v71, 0xbfb8aa3b, v71
	v_exp_f32_e32 v71, v71
	v_mul_f32_e32 v64, 0xbfb8aa3b, v64
	v_mul_f32_e32 v98, 0x3f317217, v89
	v_fma_f32 v98, v89, s87, -v98
	v_fmac_f32_e32 v98, 0x3377d1cf, v89
	v_fmac_f32_e32 v98, 0x3f317217, v89
	v_cmp_lt_f32_e64 s[6:7], |v89|, s88
	v_add_f32_e32 v71, 1.0, v71
	v_rcp_f32_e32 v71, v71
	v_cndmask_b32_e64 v89, v89, v98, s[6:7]
	v_cndmask_b32_e32 v98, 0, v174, vcc
	v_cmp_gt_f32_e32 vcc, s86, v90
	v_sub_f32_e32 v89, v89, v98
	v_fmac_f32_e32 v155, v71, v127
	v_cndmask_b32_e64 v98, 0, 32, vcc
	v_ldexp_f32 v90, v90, v98
	v_log_f32_e32 v90, v90
	v_exp_f32_e32 v64, v64
	v_mul_f32_e32 v65, 0xbfb8aa3b, v65
	v_exp_f32_e32 v65, v65
	v_mul_f32_e32 v98, 0x3f317217, v90
	v_fma_f32 v98, v90, s87, -v98
	v_fmac_f32_e32 v98, 0x3377d1cf, v90
	v_fmac_f32_e32 v98, 0x3f317217, v90
	v_cmp_lt_f32_e64 s[6:7], |v90|, s88
	v_add_f32_e32 v64, 1.0, v64
	v_rcp_f32_e32 v64, v64
	v_cndmask_b32_e64 v90, v90, v98, s[6:7]
	v_cndmask_b32_e32 v98, 0, v174, vcc
	v_cmp_gt_f32_e32 vcc, s86, v91
	v_sub_f32_e32 v90, v90, v98
	v_fmac_f32_e32 v154, v64, v160
	v_cndmask_b32_e64 v98, 0, 32, vcc
	v_ldexp_f32 v91, v91, v98
	v_log_f32_e32 v91, v91
	v_add_f32_e32 v65, 1.0, v65
	v_rcp_f32_e32 v65, v65
	v_mul_f32_e32 v66, 0xbfb8aa3b, v66
	v_mul_f32_e32 v98, 0x3f317217, v91
	v_fma_f32 v98, v91, s87, -v98
	v_fmac_f32_e32 v98, 0x3377d1cf, v91
	v_fmac_f32_e32 v98, 0x3f317217, v91
	v_cmp_lt_f32_e64 s[6:7], |v91|, s88
	v_fmac_f32_e32 v153, v65, v147
	v_exp_f32_e32 v66, v66
	v_cndmask_b32_e64 v91, v91, v98, s[6:7]
	v_cndmask_b32_e32 v98, 0, v174, vcc
	v_sub_f32_e32 v91, v91, v98
	v_cvt_pk_f16_f32 v91, v90, v91
	v_cvt_pk_f16_f32 v90, v88, v89
	v_cvt_pk_f16_f32 v89, v94, v95
	v_cvt_pk_f16_f32 v88, v92, v93
	v_cmp_gt_f32_e32 vcc, s86, v84
	global_store_dwordx4 v[96:97], v[88:91], off offset:-2048 sc1
	s_mov_b64 s[6:7], 0x48000
	v_add_f32_e32 v66, 1.0, v66
	v_cndmask_b32_e64 v90, 0, 32, vcc
	v_ldexp_f32 v84, v84, v90
	v_log_f32_e32 v84, v84
	v_lshl_add_u64 v[88:89], v[148:149], 0, s[6:7]
	v_rcp_f32_e32 v66, v66
	v_mul_f32_e32 v67, 0xbfb8aa3b, v67
	v_mul_f32_e32 v90, 0x3f317217, v84
	v_fma_f32 v90, v84, s87, -v90
	v_fmac_f32_e32 v90, 0x3377d1cf, v84
	v_fmac_f32_e32 v90, 0x3f317217, v84
	v_cmp_lt_f32_e64 s[6:7], |v84|, s88
	v_fmac_f32_e32 v152, v66, v159
	v_exp_f32_e32 v67, v67
	v_cndmask_b32_e64 v84, v84, v90, s[6:7]
	v_cndmask_b32_e32 v90, 0, v174, vcc
	v_cmp_gt_f32_e32 vcc, s86, v85
	v_sub_f32_e32 v84, v84, v90
	v_add_f32_e32 v67, 1.0, v67
	v_cndmask_b32_e64 v90, 0, 32, vcc
	v_ldexp_f32 v85, v85, v90
	v_log_f32_e32 v85, v85
	v_rcp_f32_e32 v67, v67
	s_movk_i32 s0, 0x1f8
	v_cvt_pk_f16_f32 v163, v163, v176
	v_mul_f32_e32 v90, 0x3f317217, v85
	v_fma_f32 v90, v85, s87, -v90
	v_fmac_f32_e32 v90, 0x3377d1cf, v85
	v_fmac_f32_e32 v90, 0x3f317217, v85
	v_cmp_lt_f32_e64 s[6:7], |v85|, s88
	v_fmac_f32_e32 v151, v67, v122
	v_cvt_pk_f16_f32 v162, v161, v162
	v_cndmask_b32_e64 v85, v85, v90, s[6:7]
	v_cndmask_b32_e32 v90, 0, v174, vcc
	v_cmp_gt_f32_e32 vcc, s86, v86
	v_sub_f32_e32 v85, v85, v90
	global_store_dwordx4 v[148:149], v[162:165], off offset:-2048 sc1
	v_cndmask_b32_e64 v90, 0, 32, vcc
	v_ldexp_f32 v86, v86, v90
	v_log_f32_e32 v86, v86
	v_mul_f32_e32 v60, 0xbfb8aa3b, v60
	v_exp_f32_e32 v60, v60
	v_mul_f32_e32 v56, 0xbfb8aa3b, v56
	v_mul_f32_e32 v90, 0x3f317217, v86
	v_fma_f32 v90, v86, s87, -v90
	v_fmac_f32_e32 v90, 0x3377d1cf, v86
	v_fmac_f32_e32 v90, 0x3f317217, v86
	v_cmp_lt_f32_e64 s[6:7], |v86|, s88
	v_add_f32_e32 v60, 1.0, v60
	v_rcp_f32_e32 v60, v60
	v_cndmask_b32_e64 v86, v86, v90, s[6:7]
	v_cndmask_b32_e32 v90, 0, v174, vcc
	v_cmp_gt_f32_e32 vcc, s86, v87
	v_sub_f32_e32 v86, v86, v90
	v_exp_f32_e32 v56, v56
	v_cndmask_b32_e64 v90, 0, 32, vcc
	v_ldexp_f32 v87, v87, v90
	v_log_f32_e32 v87, v87
	v_add_f32_e32 v56, 1.0, v56
	v_rcp_f32_e32 v56, v56
	v_mul_f32_e32 v52, 0xbfb8aa3b, v52
	v_mul_f32_e32 v90, 0x3f317217, v87
	v_fma_f32 v90, v87, s87, -v90
	v_fmac_f32_e32 v90, 0x3377d1cf, v87
	v_fmac_f32_e32 v90, 0x3f317217, v87
	v_cmp_lt_f32_e64 s[6:7], |v87|, s88
	v_exp_f32_e32 v52, v52
	v_mul_f32_e32 v53, 0xbfb8aa3b, v53
	v_cndmask_b32_e64 v87, v87, v90, s[6:7]
	v_cndmask_b32_e32 v90, 0, v174, vcc
	v_cmp_gt_f32_e32 vcc, s86, v80
	v_sub_f32_e32 v87, v87, v90
	v_add_f32_e32 v52, 1.0, v52
	v_cndmask_b32_e64 v90, 0, 32, vcc
	v_ldexp_f32 v80, v80, v90
	v_log_f32_e32 v80, v80
	v_rcp_f32_e32 v52, v52
	v_exp_f32_e32 v53, v53
	v_mul_f32_e32 v54, 0xbfb8aa3b, v54
	v_mul_f32_e32 v90, 0x3f317217, v80
	v_fma_f32 v90, v80, s87, -v90
	v_fmac_f32_e32 v90, 0x3377d1cf, v80
	v_fmac_f32_e32 v90, 0x3f317217, v80
	v_cmp_lt_f32_e64 s[6:7], |v80|, s88
	v_add_f32_e32 v53, 1.0, v53
	v_rcp_f32_e32 v53, v53
	v_cndmask_b32_e64 v80, v80, v90, s[6:7]
	v_cndmask_b32_e32 v90, 0, v174, vcc
	v_cmp_gt_f32_e32 vcc, s86, v81
	v_sub_f32_e32 v80, v80, v90
	v_exp_f32_e32 v54, v54
	v_cndmask_b32_e64 v90, 0, 32, vcc
	v_ldexp_f32 v81, v81, v90
	v_log_f32_e32 v81, v81
	v_add_f32_e32 v54, 1.0, v54
	v_rcp_f32_e32 v54, v54
	v_mul_f32_e32 v55, 0xbfb8aa3b, v55
	v_mul_f32_e32 v90, 0x3f317217, v81
	v_fma_f32 v90, v81, s87, -v90
	v_fmac_f32_e32 v90, 0x3377d1cf, v81
	v_fmac_f32_e32 v90, 0x3f317217, v81
	v_cmp_lt_f32_e64 s[6:7], |v81|, s88
	v_exp_f32_e32 v55, v55
	v_mul_f32_e32 v48, 0xbfb8aa3b, v48
	v_cndmask_b32_e64 v81, v81, v90, s[6:7]
	v_cndmask_b32_e32 v90, 0, v174, vcc
	v_cmp_gt_f32_e32 vcc, s86, v82
	v_sub_f32_e32 v81, v81, v90
	v_add_f32_e32 v55, 1.0, v55
	v_cndmask_b32_e64 v90, 0, 32, vcc
	v_ldexp_f32 v82, v82, v90
	v_log_f32_e32 v82, v82
	v_rcp_f32_e32 v55, v55
	v_exp_f32_e32 v48, v48
	v_mul_f32_e32 v49, 0xbfb8aa3b, v49
	v_mul_f32_e32 v90, 0x3f317217, v82
	v_fma_f32 v90, v82, s87, -v90
	v_fmac_f32_e32 v90, 0x3377d1cf, v82
	v_fmac_f32_e32 v90, 0x3f317217, v82
	v_cmp_lt_f32_e64 s[6:7], |v82|, s88
	v_add_f32_e32 v48, 1.0, v48
	v_rcp_f32_e32 v48, v48
	v_cndmask_b32_e64 v82, v82, v90, s[6:7]
	v_cndmask_b32_e32 v90, 0, v174, vcc
	v_cmp_gt_f32_e32 vcc, s86, v83
	v_sub_f32_e32 v82, v82, v90
	v_exp_f32_e32 v49, v49
	v_cndmask_b32_e64 v90, 0, 32, vcc
	v_ldexp_f32 v83, v83, v90
	v_log_f32_e32 v83, v83
	v_add_f32_e32 v49, 1.0, v49
	v_rcp_f32_e32 v49, v49
	v_mul_f32_e32 v50, 0xbfb8aa3b, v50
	v_mul_f32_e32 v90, 0x3f317217, v83
	v_fma_f32 v90, v83, s87, -v90
	v_fmac_f32_e32 v90, 0x3377d1cf, v83
	v_fmac_f32_e32 v90, 0x3f317217, v83
	v_cmp_lt_f32_e64 s[6:7], |v83|, s88
	v_exp_f32_e32 v50, v50
	v_mul_f32_e32 v51, 0xbfb8aa3b, v51
	v_cndmask_b32_e64 v83, v83, v90, s[6:7]
	v_cndmask_b32_e32 v90, 0, v174, vcc
	v_sub_f32_e32 v83, v83, v90
	v_cvt_pk_f16_f32 v83, v82, v83
	v_cvt_pk_f16_f32 v82, v80, v81
	v_cvt_pk_f16_f32 v81, v86, v87
	v_cvt_pk_f16_f32 v80, v84, v85
	v_cmp_gt_f32_e32 vcc, s86, v76
	global_store_dwordx4 v[88:89], v[80:83], off offset:-2048 sc1
	s_mov_b64 s[6:7], 0x50000
	v_add_f32_e32 v50, 1.0, v50
	v_cndmask_b32_e64 v82, 0, 32, vcc
	v_ldexp_f32 v76, v76, v82
	v_log_f32_e32 v76, v76
	v_lshl_add_u64 v[80:81], v[148:149], 0, s[6:7]
	v_rcp_f32_e32 v50, v50
	v_exp_f32_e32 v51, v51
	v_mul_f32_e32 v82, 0x3f317217, v76
	v_fma_f32 v82, v76, s87, -v82
	v_fmac_f32_e32 v82, 0x3377d1cf, v76
	v_fmac_f32_e32 v82, 0x3f317217, v76
	v_cmp_lt_f32_e64 s[6:7], |v76|, s88
	v_add_f32_e32 v51, 1.0, v51
	v_rcp_f32_e32 v51, v51
	v_cndmask_b32_e64 v76, v76, v82, s[6:7]
	v_cndmask_b32_e32 v82, 0, v174, vcc
	v_cmp_gt_f32_e32 vcc, s86, v77
	v_sub_f32_e32 v76, v76, v82
	v_mul_f32_e32 v44, 0xbfb8aa3b, v44
	v_cndmask_b32_e64 v82, 0, 32, vcc
	v_ldexp_f32 v77, v77, v82
	v_log_f32_e32 v77, v77
	v_exp_f32_e32 v44, v44
	v_mul_f32_e32 v45, 0xbfb8aa3b, v45
	v_exp_f32_e32 v45, v45
	v_mul_f32_e32 v82, 0x3f317217, v77
	v_fma_f32 v82, v77, s87, -v82
	v_fmac_f32_e32 v82, 0x3377d1cf, v77
	v_fmac_f32_e32 v82, 0x3f317217, v77
	v_cmp_lt_f32_e64 s[6:7], |v77|, s88
	v_add_f32_e32 v44, 1.0, v44
	v_rcp_f32_e32 v44, v44
	v_cndmask_b32_e64 v77, v77, v82, s[6:7]
	v_cndmask_b32_e32 v82, 0, v174, vcc
	v_cmp_gt_f32_e32 vcc, s86, v78
	v_sub_f32_e32 v77, v77, v82
	v_add_f32_e32 v45, 1.0, v45
	v_cndmask_b32_e64 v82, 0, 32, vcc
	v_ldexp_f32 v78, v78, v82
	v_log_f32_e32 v78, v78
	v_rcp_f32_e32 v45, v45
	v_mul_f32_e32 v46, 0xbfb8aa3b, v46
	v_exp_f32_e32 v46, v46
	v_mul_f32_e32 v82, 0x3f317217, v78
	v_fma_f32 v82, v78, s87, -v82
	v_fmac_f32_e32 v82, 0x3377d1cf, v78
	v_fmac_f32_e32 v82, 0x3f317217, v78
	v_cmp_lt_f32_e64 s[6:7], |v78|, s88
	v_add_f32_e32 v46, 1.0, v46
	v_rcp_f32_e32 v46, v46
	v_cndmask_b32_e64 v78, v78, v82, s[6:7]
	v_cndmask_b32_e32 v82, 0, v174, vcc
	v_cmp_gt_f32_e32 vcc, s86, v79
	v_sub_f32_e32 v78, v78, v82
	v_mul_f32_e32 v47, 0xbfb8aa3b, v47
	v_cndmask_b32_e64 v82, 0, 32, vcc
	v_ldexp_f32 v79, v79, v82
	v_log_f32_e32 v79, v79
	v_exp_f32_e32 v47, v47
	v_mul_f32_e32 v40, 0xbfb8aa3b, v40
	v_exp_f32_e32 v40, v40
	v_mul_f32_e32 v82, 0x3f317217, v79
	v_fma_f32 v82, v79, s87, -v82
	v_fmac_f32_e32 v82, 0x3377d1cf, v79
	v_fmac_f32_e32 v82, 0x3f317217, v79
	v_cmp_lt_f32_e64 s[6:7], |v79|, s88
	v_add_f32_e32 v47, 1.0, v47
	v_rcp_f32_e32 v47, v47
	v_cndmask_b32_e64 v79, v79, v82, s[6:7]
	v_cndmask_b32_e32 v82, 0, v174, vcc
	v_cmp_gt_f32_e32 vcc, s86, v72
	v_sub_f32_e32 v79, v79, v82
	v_add_f32_e32 v40, 1.0, v40
	v_cndmask_b32_e64 v82, 0, 32, vcc
	v_ldexp_f32 v72, v72, v82
	v_log_f32_e32 v72, v72
	v_rcp_f32_e32 v40, v40
	v_mul_f32_e32 v41, 0xbfb8aa3b, v41
	v_exp_f32_e32 v41, v41
	v_mul_f32_e32 v82, 0x3f317217, v72
	v_fma_f32 v82, v72, s87, -v82
	v_fmac_f32_e32 v82, 0x3377d1cf, v72
	v_fmac_f32_e32 v82, 0x3f317217, v72
	v_cmp_lt_f32_e64 s[6:7], |v72|, s88
	v_add_f32_e32 v41, 1.0, v41
	v_rcp_f32_e32 v41, v41
	v_cndmask_b32_e64 v72, v72, v82, s[6:7]
	v_cndmask_b32_e32 v82, 0, v174, vcc
	v_cmp_gt_f32_e32 vcc, s86, v73
	v_sub_f32_e32 v72, v72, v82
	v_mul_f32_e32 v42, 0xbfb8aa3b, v42
	v_cndmask_b32_e64 v82, 0, 32, vcc
	v_ldexp_f32 v73, v73, v82
	v_log_f32_e32 v73, v73
	v_exp_f32_e32 v42, v42
	v_mul_f32_e32 v43, 0xbfb8aa3b, v43
	v_exp_f32_e32 v43, v43
	v_mul_f32_e32 v82, 0x3f317217, v73
	v_fma_f32 v82, v73, s87, -v82
	v_fmac_f32_e32 v82, 0x3377d1cf, v73
	v_fmac_f32_e32 v82, 0x3f317217, v73
	v_cmp_lt_f32_e64 s[6:7], |v73|, s88
	v_add_f32_e32 v42, 1.0, v42
	v_rcp_f32_e32 v42, v42
	v_cndmask_b32_e64 v73, v73, v82, s[6:7]
	v_cndmask_b32_e32 v82, 0, v174, vcc
	v_cmp_gt_f32_e32 vcc, s86, v74
	v_sub_f32_e32 v73, v73, v82
	v_add_f32_e32 v43, 1.0, v43
	v_cndmask_b32_e64 v82, 0, 32, vcc
	v_ldexp_f32 v74, v74, v82
	v_log_f32_e32 v74, v74
	v_rcp_f32_e32 v43, v43
	v_mul_f32_e32 v36, 0xbfb8aa3b, v36
	v_exp_f32_e32 v36, v36
	v_mul_f32_e32 v82, 0x3f317217, v74
	v_fma_f32 v82, v74, s87, -v82
	v_fmac_f32_e32 v82, 0x3377d1cf, v74
	v_fmac_f32_e32 v82, 0x3f317217, v74
	v_cmp_lt_f32_e64 s[6:7], |v74|, s88
	v_add_f32_e32 v36, 1.0, v36
	v_rcp_f32_e32 v36, v36
	v_cndmask_b32_e64 v74, v74, v82, s[6:7]
	v_cndmask_b32_e32 v82, 0, v174, vcc
	v_cmp_gt_f32_e32 vcc, s86, v75
	v_sub_f32_e32 v74, v74, v82
	v_mul_f32_e32 v37, 0xbfb8aa3b, v37
	v_cndmask_b32_e64 v82, 0, 32, vcc
	v_ldexp_f32 v75, v75, v82
	v_log_f32_e32 v75, v75
	v_exp_f32_e32 v37, v37
	v_mul_f32_e32 v38, 0xbfb8aa3b, v38
	v_exp_f32_e32 v38, v38
	v_mul_f32_e32 v82, 0x3f317217, v75
	v_fma_f32 v82, v75, s87, -v82
	v_fmac_f32_e32 v82, 0x3377d1cf, v75
	v_fmac_f32_e32 v82, 0x3f317217, v75
	v_cmp_lt_f32_e64 s[6:7], |v75|, s88
	v_add_f32_e32 v37, 1.0, v37
	v_rcp_f32_e32 v37, v37
	v_cndmask_b32_e64 v75, v75, v82, s[6:7]
	v_cndmask_b32_e32 v82, 0, v174, vcc
	v_cmp_gt_f32_e32 vcc, s86, v158
	v_sub_f32_e32 v75, v75, v82
	v_cvt_pk_f16_f32 v75, v74, v75
	v_cndmask_b32_e64 v68, 0, 32, vcc
	v_ldexp_f32 v68, v158, v68
	v_log_f32_e32 v68, v68
	v_cvt_pk_f16_f32 v74, v72, v73
	v_cvt_pk_f16_f32 v73, v78, v79
	v_cvt_pk_f16_f32 v72, v76, v77
	global_store_dwordx4 v[80:81], v[72:75], off offset:-2048 sc1
	s_mov_b64 s[6:7], 0x58000
	v_add_f32_e32 v38, 1.0, v38
	v_mul_f32_e32 v74, 0x3f317217, v68
	v_fma_f32 v74, v68, s87, -v74
	v_fmac_f32_e32 v74, 0x3377d1cf, v68
	v_lshl_add_u64 v[72:73], v[148:149], 0, s[6:7]
	v_fmac_f32_e32 v74, 0x3f317217, v68
	v_cmp_lt_f32_e64 s[6:7], |v68|, s88
	v_rcp_f32_e32 v38, v38
	v_mul_f32_e32 v39, 0xbfb8aa3b, v39
	v_cndmask_b32_e64 v68, v68, v74, s[6:7]
	v_cndmask_b32_e32 v74, 0, v174, vcc
	v_cmp_gt_f32_e32 vcc, s86, v157
	v_sub_f32_e32 v68, v68, v74
	v_exp_f32_e32 v39, v39
	v_cndmask_b32_e64 v69, 0, 32, vcc
	v_ldexp_f32 v69, v157, v69
	v_log_f32_e32 v69, v69
	v_add_f32_e32 v39, 1.0, v39
	v_rcp_f32_e32 v39, v39
	v_mul_f32_e32 v32, 0xbfb8aa3b, v32
	v_mul_f32_e32 v74, 0x3f317217, v69
	v_fma_f32 v74, v69, s87, -v74
	v_fmac_f32_e32 v74, 0x3377d1cf, v69
	v_fmac_f32_e32 v74, 0x3f317217, v69
	v_cmp_lt_f32_e64 s[6:7], |v69|, s88
	v_exp_f32_e32 v32, v32
	v_mul_f32_e32 v33, 0xbfb8aa3b, v33
	v_cndmask_b32_e64 v69, v69, v74, s[6:7]
	v_cndmask_b32_e32 v74, 0, v174, vcc
	v_cmp_gt_f32_e32 vcc, s86, v156
	v_sub_f32_e32 v69, v69, v74
	v_add_f32_e32 v32, 1.0, v32
	v_cndmask_b32_e64 v70, 0, 32, vcc
	v_ldexp_f32 v70, v156, v70
	v_log_f32_e32 v70, v70
	v_rcp_f32_e32 v32, v32
	v_exp_f32_e32 v33, v33
	v_mul_f32_e32 v34, 0xbfb8aa3b, v34
	v_mul_f32_e32 v74, 0x3f317217, v70
	v_fma_f32 v74, v70, s87, -v74
	v_fmac_f32_e32 v74, 0x3377d1cf, v70
	v_fmac_f32_e32 v74, 0x3f317217, v70
	v_cmp_lt_f32_e64 s[6:7], |v70|, s88
	v_add_f32_e32 v33, 1.0, v33
	v_rcp_f32_e32 v33, v33
	v_cndmask_b32_e64 v70, v70, v74, s[6:7]
	v_cndmask_b32_e32 v74, 0, v174, vcc
	v_cmp_gt_f32_e32 vcc, s86, v155
	v_sub_f32_e32 v70, v70, v74
	v_exp_f32_e32 v34, v34
	v_cndmask_b32_e64 v71, 0, 32, vcc
	v_ldexp_f32 v71, v155, v71
	v_log_f32_e32 v71, v71
	v_add_f32_e32 v34, 1.0, v34
	v_rcp_f32_e32 v34, v34
	v_mul_f32_e32 v35, 0xbfb8aa3b, v35
	v_mul_f32_e32 v74, 0x3f317217, v71
	v_fma_f32 v74, v71, s87, -v74
	v_fmac_f32_e32 v74, 0x3377d1cf, v71
	v_fmac_f32_e32 v74, 0x3f317217, v71
	v_cmp_lt_f32_e64 s[6:7], |v71|, s88
	v_exp_f32_e32 v35, v35
	v_mul_f32_e32 v28, 0xbfb8aa3b, v28
	v_cndmask_b32_e64 v71, v71, v74, s[6:7]
	v_cndmask_b32_e32 v74, 0, v174, vcc
	v_cmp_gt_f32_e32 vcc, s86, v154
	v_sub_f32_e32 v71, v71, v74
	v_add_f32_e32 v35, 1.0, v35
	v_cndmask_b32_e64 v64, 0, 32, vcc
	v_ldexp_f32 v64, v154, v64
	v_log_f32_e32 v64, v64
	v_rcp_f32_e32 v35, v35
	v_exp_f32_e32 v28, v28
	v_mul_f32_e32 v29, 0xbfb8aa3b, v29
	v_mul_f32_e32 v74, 0x3f317217, v64
	v_fma_f32 v74, v64, s87, -v74
	v_fmac_f32_e32 v74, 0x3377d1cf, v64
	v_fmac_f32_e32 v74, 0x3f317217, v64
	v_cmp_lt_f32_e64 s[6:7], |v64|, s88
	v_add_f32_e32 v28, 1.0, v28
	v_rcp_f32_e32 v28, v28
	v_cndmask_b32_e64 v64, v64, v74, s[6:7]
	v_cndmask_b32_e32 v74, 0, v174, vcc
	v_cmp_gt_f32_e32 vcc, s86, v153
	v_sub_f32_e32 v64, v64, v74
	v_exp_f32_e32 v29, v29
	v_cndmask_b32_e64 v65, 0, 32, vcc
	v_ldexp_f32 v65, v153, v65
	v_log_f32_e32 v65, v65
	v_add_f32_e32 v29, 1.0, v29
	v_rcp_f32_e32 v29, v29
	v_mul_f32_e32 v30, 0xbfb8aa3b, v30
	v_mul_f32_e32 v74, 0x3f317217, v65
	v_fma_f32 v74, v65, s87, -v74
	v_fmac_f32_e32 v74, 0x3377d1cf, v65
	v_fmac_f32_e32 v74, 0x3f317217, v65
	v_cmp_lt_f32_e64 s[6:7], |v65|, s88
	v_exp_f32_e32 v30, v30
	v_mul_f32_e32 v31, 0xbfb8aa3b, v31
	v_cndmask_b32_e64 v65, v65, v74, s[6:7]
	v_cndmask_b32_e32 v74, 0, v174, vcc
	v_cmp_gt_f32_e32 vcc, s86, v152
	v_sub_f32_e32 v65, v65, v74
	v_add_f32_e32 v30, 1.0, v30
	v_cndmask_b32_e64 v66, 0, 32, vcc
	v_ldexp_f32 v66, v152, v66
	v_log_f32_e32 v66, v66
	v_rcp_f32_e32 v30, v30
	v_exp_f32_e32 v31, v31
	v_mul_f32_e32 v24, 0xbfb8aa3b, v24
	v_mul_f32_e32 v74, 0x3f317217, v66
	v_fma_f32 v74, v66, s87, -v74
	v_fmac_f32_e32 v74, 0x3377d1cf, v66
	v_fmac_f32_e32 v74, 0x3f317217, v66
	v_cmp_lt_f32_e64 s[6:7], |v66|, s88
	v_add_f32_e32 v31, 1.0, v31
	v_rcp_f32_e32 v31, v31
	v_cndmask_b32_e64 v66, v66, v74, s[6:7]
	v_cndmask_b32_e32 v74, 0, v174, vcc
	v_cmp_gt_f32_e32 vcc, s86, v151
	v_sub_f32_e32 v66, v66, v74
	v_exp_f32_e32 v24, v24
	v_cndmask_b32_e64 v67, 0, 32, vcc
	v_ldexp_f32 v67, v151, v67
	v_log_f32_e32 v67, v67
	v_add_f32_e32 v24, 1.0, v24
	v_rcp_f32_e32 v24, v24
	v_mul_f32_e32 v25, 0xbfb8aa3b, v25
	v_mul_f32_e32 v74, 0x3f317217, v67
	v_fma_f32 v74, v67, s87, -v74
	v_fmac_f32_e32 v74, 0x3377d1cf, v67
	v_fmac_f32_e32 v74, 0x3f317217, v67
	v_cmp_lt_f32_e64 s[6:7], |v67|, s88
	v_exp_f32_e32 v25, v25
	v_mul_f32_e32 v26, 0xbfb8aa3b, v26
	v_cndmask_b32_e64 v67, v67, v74, s[6:7]
	v_cndmask_b32_e32 v74, 0, v174, vcc
	v_sub_f32_e32 v67, v67, v74
	v_cvt_pk_f16_f32 v67, v66, v67
	v_cvt_pk_f16_f32 v66, v64, v65
	v_cvt_pk_f16_f32 v65, v70, v71
	v_cvt_pk_f16_f32 v64, v68, v69
	global_store_dwordx4 v[72:73], v[64:67], off offset:-2048 sc1
	v_add_f32_e32 v25, 1.0, v25
	v_rcp_f32_e32 v25, v25
	v_bitop3_b32 v64, v150, s0, v175 bitop3:0xc8
	v_lshlrev_b32_e32 v68, 2, v64
	global_load_dwordx4 v[74:77], v68, s[58:59] offset:2064
	global_load_dwordx4 v[64:67], v68, s[58:59] offset:2048
	global_load_dwordx4 v[82:85], v68, s[58:59] offset:16
	global_load_dwordx4 v[90:93], v68, s[58:59]
	v_exp_f32_e32 v26, v26
	v_mul_f32_e32 v27, 0xbfb8aa3b, v27
	v_exp_f32_e32 v27, v27
	v_mul_f32_e32 v20, 0xbfb8aa3b, v20
	v_add_f32_e32 v26, 1.0, v26
	v_rcp_f32_e32 v26, v26
	v_add_f32_e32 v27, 1.0, v27
	v_rcp_f32_e32 v27, v27
	v_exp_f32_e32 v20, v20
	v_mul_f32_e32 v21, 0xbfb8aa3b, v21
	v_exp_f32_e32 v21, v21
	v_mul_f32_e32 v22, 0xbfb8aa3b, v22
	v_add_f32_e32 v20, 1.0, v20
	v_rcp_f32_e32 v20, v20
	v_add_f32_e32 v21, 1.0, v21
	v_rcp_f32_e32 v21, v21
	v_exp_f32_e32 v22, v22
	v_mul_f32_e32 v23, 0xbfb8aa3b, v23
	v_exp_f32_e32 v23, v23
	v_mul_f32_e32 v16, 0xbfb8aa3b, v16
	v_add_f32_e32 v22, 1.0, v22
	v_rcp_f32_e32 v22, v22
	v_add_f32_e32 v23, 1.0, v23
	v_rcp_f32_e32 v23, v23
	v_exp_f32_e32 v16, v16
	v_mul_f32_e32 v17, 0xbfb8aa3b, v17
	v_exp_f32_e32 v17, v17
	v_mul_f32_e32 v18, 0xbfb8aa3b, v18
	v_add_f32_e32 v16, 1.0, v16
	v_rcp_f32_e32 v16, v16
	v_add_f32_e32 v17, 1.0, v17
	v_rcp_f32_e32 v17, v17
	v_exp_f32_e32 v18, v18
	v_mul_f32_e32 v19, 0xbfb8aa3b, v19
	v_exp_f32_e32 v19, v19
	v_mul_f32_e32 v12, 0xbfb8aa3b, v12
	v_add_f32_e32 v18, 1.0, v18
	v_rcp_f32_e32 v18, v18
	v_add_f32_e32 v19, 1.0, v19
	v_rcp_f32_e32 v19, v19
	v_exp_f32_e32 v12, v12
	v_mul_f32_e32 v13, 0xbfb8aa3b, v13
	v_exp_f32_e32 v13, v13
	v_mul_f32_e32 v14, 0xbfb8aa3b, v14
	v_add_f32_e32 v12, 1.0, v12
	v_rcp_f32_e32 v12, v12
	v_add_f32_e32 v13, 1.0, v13
	v_rcp_f32_e32 v13, v13
	v_exp_f32_e32 v14, v14
	v_mul_f32_e32 v15, 0xbfb8aa3b, v15
	v_exp_f32_e32 v15, v15
	v_mul_f32_e32 v8, 0xbfb8aa3b, v8
	v_add_f32_e32 v14, 1.0, v14
	v_rcp_f32_e32 v14, v14
	v_add_f32_e32 v15, 1.0, v15
	v_rcp_f32_e32 v15, v15
	v_exp_f32_e32 v8, v8
	v_mul_f32_e32 v9, 0xbfb8aa3b, v9
	v_exp_f32_e32 v9, v9
	v_mul_f32_e32 v10, 0xbfb8aa3b, v10
	v_add_f32_e32 v8, 1.0, v8
	v_rcp_f32_e32 v8, v8
	v_add_f32_e32 v9, 1.0, v9
	v_rcp_f32_e32 v9, v9
	v_exp_f32_e32 v10, v10
	v_mul_f32_e32 v11, 0xbfb8aa3b, v11
	v_exp_f32_e32 v11, v11
	v_mul_f32_e32 v4, 0xbfb8aa3b, v4
	v_add_f32_e32 v10, 1.0, v10
	v_rcp_f32_e32 v10, v10
	v_add_f32_e32 v11, 1.0, v11
	v_rcp_f32_e32 v11, v11
	v_exp_f32_e32 v4, v4
	v_mul_f32_e32 v5, 0xbfb8aa3b, v5
	v_exp_f32_e32 v5, v5
	v_mul_f32_e32 v6, 0xbfb8aa3b, v6
	v_add_f32_e32 v4, 1.0, v4
	v_rcp_f32_e32 v4, v4
	v_add_f32_e32 v5, 1.0, v5
	s_waitcnt vmcnt(0)
	v_sub_f32_e32 v64, v64, v90
	v_mul_f32_e32 v64, 0x3fb8aa3b, v64
	v_exp_f32_e32 v64, v64
	v_rcp_f32_e32 v5, v5
	v_exp_f32_e32 v6, v6
	v_mul_f32_e32 v7, 0xbfb8aa3b, v7
	v_add_f32_e32 v64, 1.0, v64
	v_rcp_f32_e32 v71, v64
	v_sub_f32_e32 v64, v65, v91
	v_mul_f32_e32 v64, 0x3fb8aa3b, v64
	v_exp_f32_e32 v64, v64
	v_add_f32_e32 v6, 1.0, v6
	v_rcp_f32_e32 v6, v6
	v_exp_f32_e32 v7, v7
	v_add_f32_e32 v64, 1.0, v64
	v_rcp_f32_e32 v70, v64
	v_sub_f32_e32 v64, v66, v92
	v_mul_f32_e32 v64, 0x3fb8aa3b, v64
	v_exp_f32_e32 v64, v64
	v_add_f32_e32 v7, 1.0, v7
	v_rcp_f32_e32 v7, v7
	v_mul_f32_e32 v0, 0xbfb8aa3b, v0
	v_add_f32_e32 v64, 1.0, v64
	v_rcp_f32_e32 v69, v64
	v_sub_f32_e32 v64, v67, v93
	v_mul_f32_e32 v64, 0x3fb8aa3b, v64
	v_exp_f32_e32 v64, v64
	v_exp_f32_e32 v0, v0
	v_mul_f32_e32 v1, 0xbfb8aa3b, v1
	v_exp_f32_e32 v1, v1
	v_add_f32_e32 v64, 1.0, v64
	v_rcp_f32_e32 v68, v64
	v_sub_f32_e32 v64, v74, v82
	v_mul_f32_e32 v64, 0x3fb8aa3b, v64
	v_exp_f32_e32 v64, v64
	v_add_f32_e32 v0, 1.0, v0
	v_rcp_f32_e32 v0, v0
	v_add_f32_e32 v1, 1.0, v1
	v_add_f32_e32 v64, 1.0, v64
	v_rcp_f32_e32 v67, v64
	v_sub_f32_e32 v64, v75, v83
	v_sub_f32_e32 v75, 1.0, v71
	v_fma_f32 v60, v60, v75, v71
	v_cmp_gt_f32_e32 vcc, s86, v60
	v_mul_f32_e32 v64, 0x3fb8aa3b, v64
	v_exp_f32_e32 v64, v64
	v_cndmask_b32_e64 v74, 0, 32, vcc
	v_ldexp_f32 v60, v60, v74
	v_log_f32_e32 v60, v60
	v_add_f32_e32 v64, 1.0, v64
	v_rcp_f32_e32 v66, v64
	v_sub_f32_e32 v64, v76, v84
	v_mul_f32_e32 v74, 0x3f317217, v60
	v_fma_f32 v74, v60, s87, -v74
	v_fmac_f32_e32 v74, 0x3377d1cf, v60
	v_fmac_f32_e32 v74, 0x3f317217, v60
	v_cmp_lt_f32_e64 s[6:7], |v60|, s88
	v_mul_f32_e32 v64, 0x3fb8aa3b, v64
	v_exp_f32_e32 v64, v64
	v_cndmask_b32_e64 v60, v60, v74, s[6:7]
	v_cndmask_b32_e32 v74, 0, v174, vcc
	v_sub_f32_e32 v76, v60, v74
	v_mul_f32_e32 v60, 0xbfb8aa3b, v61
	v_exp_f32_e32 v60, v60
	v_sub_f32_e32 v74, 1.0, v70
	v_add_f32_e32 v64, 1.0, v64
	v_rcp_f32_e32 v65, v64
	v_add_f32_e32 v60, 1.0, v60
	v_rcp_f32_e32 v60, v60
	v_sub_f32_e32 v64, v77, v85
	v_mul_f32_e32 v64, 0x3fb8aa3b, v64
	v_exp_f32_e32 v64, v64
	v_fma_f32 v60, v60, v74, v70
	v_cmp_gt_f32_e32 vcc, s86, v60
	v_fma_f32 v52, v52, v75, v71
	v_add_f32_e32 v64, 1.0, v64
	v_cndmask_b32_e64 v61, 0, 32, vcc
	v_ldexp_f32 v60, v60, v61
	v_log_f32_e32 v60, v60
	v_rcp_f32_e32 v64, v64
	v_fma_f32 v53, v53, v74, v70
	v_fma_f32 v44, v44, v75, v71
	v_mul_f32_e32 v61, 0x3f317217, v60
	v_fma_f32 v61, v60, s87, -v61
	v_fmac_f32_e32 v61, 0x3377d1cf, v60
	v_fmac_f32_e32 v61, 0x3f317217, v60
	v_cmp_lt_f32_e64 s[6:7], |v60|, s88
	v_fma_f32 v45, v45, v74, v70
	v_fma_f32 v36, v36, v75, v71
	v_cndmask_b32_e64 v60, v60, v61, s[6:7]
	v_cndmask_b32_e32 v61, 0, v174, vcc
	v_sub_f32_e32 v82, v60, v61
	v_mul_f32_e32 v60, 0xbfb8aa3b, v62
	v_exp_f32_e32 v60, v60
	v_sub_f32_e32 v61, 1.0, v69
	v_fma_f32 v54, v54, v61, v69
	v_fma_f32 v46, v46, v61, v69
	v_add_f32_e32 v60, 1.0, v60
	v_rcp_f32_e32 v60, v60
	v_fma_f32 v37, v37, v74, v70
	v_fma_f32 v38, v38, v61, v69
	v_fma_f32 v28, v28, v75, v71
	v_fma_f32 v60, v60, v61, v69
	v_cmp_gt_f32_e32 vcc, s86, v60
	v_fma_f32 v29, v29, v74, v70
	v_fma_f32 v30, v30, v61, v69
	v_cndmask_b32_e64 v62, 0, 32, vcc
	v_ldexp_f32 v60, v60, v62
	v_log_f32_e32 v60, v60
	v_fma_f32 v20, v20, v75, v71
	v_fma_f32 v21, v21, v74, v70
	v_fma_f32 v22, v22, v61, v69
	v_mul_f32_e32 v62, 0x3f317217, v60
	v_fma_f32 v62, v60, s87, -v62
	v_fmac_f32_e32 v62, 0x3377d1cf, v60
	v_fmac_f32_e32 v62, 0x3f317217, v60
	v_cmp_lt_f32_e64 s[6:7], |v60|, s88
	v_fma_f32 v12, v12, v75, v71
	v_fma_f32 v13, v13, v74, v70
	v_cndmask_b32_e64 v60, v60, v62, s[6:7]
	v_cndmask_b32_e32 v62, 0, v174, vcc
	v_sub_f32_e32 v77, v60, v62
	v_mul_f32_e32 v60, 0xbfb8aa3b, v63
	v_exp_f32_e32 v60, v60
	v_fma_f32 v14, v14, v61, v69
	v_fmac_f32_e32 v71, v4, v75
	v_fmac_f32_e32 v70, v5, v74
	v_add_f32_e32 v60, 1.0, v60
	v_rcp_f32_e32 v62, v60
	v_sub_f32_e32 v60, 1.0, v68
	v_fma_f32 v55, v55, v60, v68
	v_fma_f32 v47, v47, v60, v68
	v_fma_f32 v62, v62, v60, v68
	v_cmp_gt_f32_e32 vcc, s86, v62
	v_fma_f32 v39, v39, v60, v68
	v_fma_f32 v31, v31, v60, v68
	v_cndmask_b32_e64 v63, 0, 32, vcc
	v_ldexp_f32 v62, v62, v63
	v_log_f32_e32 v62, v62
	v_fma_f32 v23, v23, v60, v68
	v_fma_f32 v15, v15, v60, v68
	v_fmac_f32_e32 v69, v6, v61
	v_mul_f32_e32 v63, 0x3f317217, v62
	v_fma_f32 v63, v62, s87, -v63
	v_fmac_f32_e32 v63, 0x3377d1cf, v62
	v_fmac_f32_e32 v63, 0x3f317217, v62
	v_cmp_lt_f32_e64 s[6:7], |v62|, s88
	v_fmac_f32_e32 v68, v7, v60
	v_rcp_f32_e32 v1, v1
	v_cndmask_b32_e64 v62, v62, v63, s[6:7]
	v_cndmask_b32_e32 v63, 0, v174, vcc
	v_sub_f32_e32 v63, v62, v63
	v_sub_f32_e32 v62, 1.0, v67
	v_fma_f32 v56, v56, v62, v67
	v_cmp_gt_f32_e32 vcc, s86, v56
	v_fma_f32 v48, v48, v62, v67
	v_fma_f32 v40, v40, v62, v67
	v_cndmask_b32_e64 v78, 0, 32, vcc
	v_ldexp_f32 v56, v56, v78
	v_log_f32_e32 v56, v56
	v_fma_f32 v32, v32, v62, v67
	v_fma_f32 v24, v24, v62, v67
	v_fma_f32 v16, v16, v62, v67
	v_mul_f32_e32 v78, 0x3f317217, v56
	v_fma_f32 v78, v56, s87, -v78
	v_fmac_f32_e32 v78, 0x3377d1cf, v56
	v_fmac_f32_e32 v78, 0x3f317217, v56
	v_cmp_lt_f32_e64 s[6:7], |v56|, s88
	v_fma_f32 v8, v8, v62, v67
	v_fmac_f32_e32 v67, v0, v62
	v_cndmask_b32_e64 v56, v56, v78, s[6:7]
	v_cndmask_b32_e32 v78, 0, v174, vcc
	v_sub_f32_e32 v78, v56, v78
	v_mul_f32_e32 v56, 0xbfb8aa3b, v57
	v_exp_f32_e32 v56, v56
	v_mul_f32_e32 v2, 0xbfb8aa3b, v2
	v_exp_f32_e32 v2, v2
	v_mul_f32_e32 v3, 0xbfb8aa3b, v3
	v_add_f32_e32 v56, 1.0, v56
	v_rcp_f32_e32 v57, v56
	v_sub_f32_e32 v56, 1.0, v66
	v_fma_f32 v49, v49, v56, v66
	v_fma_f32 v41, v41, v56, v66
	v_fma_f32 v57, v57, v56, v66
	v_cmp_gt_f32_e32 vcc, s86, v57
	v_fma_f32 v33, v33, v56, v66
	v_fma_f32 v25, v25, v56, v66
	v_cndmask_b32_e64 v79, 0, 32, vcc
	v_ldexp_f32 v57, v57, v79
	v_log_f32_e32 v57, v57
	v_fma_f32 v17, v17, v56, v66
	v_fma_f32 v9, v9, v56, v66
	v_fmac_f32_e32 v66, v1, v56
	v_mul_f32_e32 v79, 0x3f317217, v57
	v_fma_f32 v79, v57, s87, -v79
	v_fmac_f32_e32 v79, 0x3377d1cf, v57
	v_fmac_f32_e32 v79, 0x3f317217, v57
	v_cmp_lt_f32_e64 s[6:7], |v57|, s88
	v_add_f32_e32 v2, 1.0, v2
	v_rcp_f32_e32 v2, v2
	v_cndmask_b32_e64 v57, v57, v79, s[6:7]
	v_cndmask_b32_e32 v79, 0, v174, vcc
	v_sub_f32_e32 v83, v57, v79
	v_mul_f32_e32 v57, 0xbfb8aa3b, v58
	v_exp_f32_e32 v57, v57
	v_sub_f32_e32 v58, 1.0, v65
	v_fma_f32 v50, v50, v58, v65
	v_fma_f32 v42, v42, v58, v65
	v_add_f32_e32 v57, 1.0, v57
	v_rcp_f32_e32 v57, v57
	v_fma_f32 v34, v34, v58, v65
	v_fma_f32 v26, v26, v58, v65
	v_fma_f32 v18, v18, v58, v65
	v_fma_f32 v57, v57, v58, v65
	v_cmp_gt_f32_e32 vcc, s86, v57
	v_fma_f32 v10, v10, v58, v65
	v_fmac_f32_e32 v65, v2, v58
	v_cndmask_b32_e64 v79, 0, 32, vcc
	v_ldexp_f32 v57, v57, v79
	v_log_f32_e32 v57, v57
	v_exp_f32_e32 v3, v3
	v_cvt_pk_f16_f32 v78, v78, v83
	v_cvt_pk_f16_f32 v77, v77, v63
	v_mul_f32_e32 v79, 0x3f317217, v57
	v_fma_f32 v79, v57, s87, -v79
	v_fmac_f32_e32 v79, 0x3377d1cf, v57
	v_fmac_f32_e32 v79, 0x3f317217, v57
	v_cmp_lt_f32_e64 s[6:7], |v57|, s88
	v_add_f32_e32 v3, 1.0, v3
	v_rcp_f32_e32 v3, v3
	v_cndmask_b32_e64 v57, v57, v79, s[6:7]
	v_cndmask_b32_e32 v79, 0, v174, vcc
	v_sub_f32_e32 v79, v57, v79
	v_mul_f32_e32 v57, 0xbfb8aa3b, v59
	v_exp_f32_e32 v57, v57
	v_cvt_pk_f16_f32 v76, v76, v82
	v_add_f32_e32 v57, 1.0, v57
	v_rcp_f32_e32 v59, v57
	v_sub_f32_e32 v57, 1.0, v64
	v_fma_f32 v51, v51, v57, v64
	v_fma_f32 v43, v43, v57, v64
	v_fma_f32 v59, v59, v57, v64
	v_cmp_gt_f32_e32 vcc, s86, v59
	v_fma_f32 v35, v35, v57, v64
	v_fma_f32 v27, v27, v57, v64
	v_cndmask_b32_e64 v84, 0, 32, vcc
	v_ldexp_f32 v59, v59, v84
	v_log_f32_e32 v59, v59
	v_fma_f32 v19, v19, v57, v64
	v_fma_f32 v11, v11, v57, v64
	v_fmac_f32_e32 v64, v3, v57
	v_mul_f32_e32 v84, 0x3f317217, v59
	v_fma_f32 v84, v59, s87, -v84
	v_fmac_f32_e32 v84, 0x3377d1cf, v59
	v_fmac_f32_e32 v84, 0x3f317217, v59
	v_cmp_lt_f32_e64 s[6:7], |v59|, s88
	s_nop 1
	v_cndmask_b32_e64 v59, v59, v84, s[6:7]
	v_cndmask_b32_e32 v84, 0, v174, vcc
	v_sub_f32_e32 v59, v59, v84
	v_cmp_gt_f32_e32 vcc, s86, v52
	v_cvt_pk_f16_f32 v79, v79, v59
	global_store_dwordx4 v[148:149], v[76:79], off offset:-1792 sc1
	v_cndmask_b32_e64 v59, 0, 32, vcc
	v_ldexp_f32 v52, v52, v59
	v_log_f32_e32 v52, v52
	s_nop 0
	v_mul_f32_e32 v59, 0x3f317217, v52
	v_fma_f32 v59, v52, s87, -v59
	v_fmac_f32_e32 v59, 0x3377d1cf, v52
	v_fmac_f32_e32 v59, 0x3f317217, v52
	v_cmp_lt_f32_e64 s[6:7], |v52|, s88
	s_nop 1
	v_cndmask_b32_e64 v52, v52, v59, s[6:7]
	v_cndmask_b32_e32 v59, 0, v174, vcc
	v_cmp_gt_f32_e32 vcc, s86, v53
	v_sub_f32_e32 v52, v52, v59
	s_nop 0
	v_cndmask_b32_e64 v59, 0, 32, vcc
	v_ldexp_f32 v53, v53, v59
	v_log_f32_e32 v53, v53
	s_nop 0
	v_mul_f32_e32 v59, 0x3f317217, v53
	v_fma_f32 v59, v53, s87, -v59
	v_fmac_f32_e32 v59, 0x3377d1cf, v53
	v_fmac_f32_e32 v59, 0x3f317217, v53
	v_cmp_lt_f32_e64 s[6:7], |v53|, s88
	s_nop 1
	v_cndmask_b32_e64 v53, v53, v59, s[6:7]
	v_cndmask_b32_e32 v59, 0, v174, vcc
	v_cmp_gt_f32_e32 vcc, s86, v54
	v_sub_f32_e32 v53, v53, v59
	s_nop 0
	v_cndmask_b32_e64 v59, 0, 32, vcc
	v_ldexp_f32 v54, v54, v59
	v_log_f32_e32 v54, v54
	s_nop 0
	v_mul_f32_e32 v59, 0x3f317217, v54
	v_fma_f32 v59, v54, s87, -v59
	v_fmac_f32_e32 v59, 0x3377d1cf, v54
	v_fmac_f32_e32 v59, 0x3f317217, v54
	v_cmp_lt_f32_e64 s[6:7], |v54|, s88
	s_nop 1
	v_cndmask_b32_e64 v54, v54, v59, s[6:7]
	v_cndmask_b32_e32 v59, 0, v174, vcc
	v_cmp_gt_f32_e32 vcc, s86, v55
	v_sub_f32_e32 v54, v54, v59
	s_nop 0
	v_cndmask_b32_e64 v59, 0, 32, vcc
	v_ldexp_f32 v55, v55, v59
	v_log_f32_e32 v55, v55
	s_nop 0
	v_mul_f32_e32 v59, 0x3f317217, v55
	v_fma_f32 v59, v55, s87, -v59
	v_fmac_f32_e32 v59, 0x3377d1cf, v55
	v_fmac_f32_e32 v59, 0x3f317217, v55
	v_cmp_lt_f32_e64 s[6:7], |v55|, s88
	s_nop 1
	v_cndmask_b32_e64 v55, v55, v59, s[6:7]
	v_cndmask_b32_e32 v59, 0, v174, vcc
	v_cmp_gt_f32_e32 vcc, s86, v48
	v_sub_f32_e32 v55, v55, v59
	s_nop 0
	v_cndmask_b32_e64 v59, 0, 32, vcc
	v_ldexp_f32 v48, v48, v59
	v_log_f32_e32 v48, v48
	s_nop 0
	v_mul_f32_e32 v59, 0x3f317217, v48
	v_fma_f32 v59, v48, s87, -v59
	v_fmac_f32_e32 v59, 0x3377d1cf, v48
	v_fmac_f32_e32 v59, 0x3f317217, v48
	v_cmp_lt_f32_e64 s[6:7], |v48|, s88
	s_nop 1
	v_cndmask_b32_e64 v48, v48, v59, s[6:7]
	v_cndmask_b32_e32 v59, 0, v174, vcc
	v_cmp_gt_f32_e32 vcc, s86, v49
	v_sub_f32_e32 v48, v48, v59
	s_nop 0
	v_cndmask_b32_e64 v59, 0, 32, vcc
	v_ldexp_f32 v49, v49, v59
	v_log_f32_e32 v49, v49
	s_nop 0
	v_mul_f32_e32 v59, 0x3f317217, v49
	v_fma_f32 v59, v49, s87, -v59
	v_fmac_f32_e32 v59, 0x3377d1cf, v49
	v_fmac_f32_e32 v59, 0x3f317217, v49
	v_cmp_lt_f32_e64 s[6:7], |v49|, s88
	s_nop 1
	v_cndmask_b32_e64 v49, v49, v59, s[6:7]
	v_cndmask_b32_e32 v59, 0, v174, vcc
	v_cmp_gt_f32_e32 vcc, s86, v50
	v_sub_f32_e32 v49, v49, v59
	s_nop 0
	v_cndmask_b32_e64 v59, 0, 32, vcc
	v_ldexp_f32 v50, v50, v59
	v_log_f32_e32 v50, v50
	s_nop 0
	v_mul_f32_e32 v59, 0x3f317217, v50
	v_fma_f32 v59, v50, s87, -v59
	v_fmac_f32_e32 v59, 0x3377d1cf, v50
	v_fmac_f32_e32 v59, 0x3f317217, v50
	v_cmp_lt_f32_e64 s[6:7], |v50|, s88
	s_nop 1
	v_cndmask_b32_e64 v50, v50, v59, s[6:7]
	v_cndmask_b32_e32 v59, 0, v174, vcc
	v_cmp_gt_f32_e32 vcc, s86, v51
	v_sub_f32_e32 v50, v50, v59
	s_nop 0
	v_cndmask_b32_e64 v59, 0, 32, vcc
	v_ldexp_f32 v51, v51, v59
	v_log_f32_e32 v51, v51
	s_nop 0
	v_mul_f32_e32 v59, 0x3f317217, v51
	v_fma_f32 v59, v51, s87, -v59
	v_fmac_f32_e32 v59, 0x3377d1cf, v51
	v_fmac_f32_e32 v59, 0x3f317217, v51
	v_cmp_lt_f32_e64 s[6:7], |v51|, s88
	s_nop 1
	v_cndmask_b32_e64 v51, v51, v59, s[6:7]
	v_cndmask_b32_e32 v59, 0, v174, vcc
	v_sub_f32_e32 v51, v51, v59
	v_cvt_pk_f16_f32 v51, v50, v51
	v_cvt_pk_f16_f32 v50, v48, v49
	v_cvt_pk_f16_f32 v49, v54, v55
	v_cvt_pk_f16_f32 v48, v52, v53
	v_cmp_gt_f32_e32 vcc, s86, v44
	global_store_dwordx4 v[120:121], v[48:51], off offset:-1792 sc1
	s_nop 1
	v_cndmask_b32_e64 v48, 0, 32, vcc
	v_ldexp_f32 v44, v44, v48
	v_log_f32_e32 v44, v44
	s_nop 0
	v_mul_f32_e32 v48, 0x3f317217, v44
	v_fma_f32 v48, v44, s87, -v48
	v_fmac_f32_e32 v48, 0x3377d1cf, v44
	v_fmac_f32_e32 v48, 0x3f317217, v44
	v_cmp_lt_f32_e64 s[6:7], |v44|, s88
	s_nop 1
	v_cndmask_b32_e64 v44, v44, v48, s[6:7]
	v_cndmask_b32_e32 v48, 0, v174, vcc
	v_cmp_gt_f32_e32 vcc, s86, v45
	v_sub_f32_e32 v44, v44, v48
	s_nop 0
	v_cndmask_b32_e64 v48, 0, 32, vcc
	v_ldexp_f32 v45, v45, v48
	v_log_f32_e32 v45, v45
	s_nop 0
	v_mul_f32_e32 v48, 0x3f317217, v45
	v_fma_f32 v48, v45, s87, -v48
	v_fmac_f32_e32 v48, 0x3377d1cf, v45
	v_fmac_f32_e32 v48, 0x3f317217, v45
	v_cmp_lt_f32_e64 s[6:7], |v45|, s88
	s_nop 1
	v_cndmask_b32_e64 v45, v45, v48, s[6:7]
	v_cndmask_b32_e32 v48, 0, v174, vcc
	v_cmp_gt_f32_e32 vcc, s86, v46
	v_sub_f32_e32 v45, v45, v48
	s_nop 0
	v_cndmask_b32_e64 v48, 0, 32, vcc
	v_ldexp_f32 v46, v46, v48
	v_log_f32_e32 v46, v46
	s_nop 0
	v_mul_f32_e32 v48, 0x3f317217, v46
	v_fma_f32 v48, v46, s87, -v48
	v_fmac_f32_e32 v48, 0x3377d1cf, v46
	v_fmac_f32_e32 v48, 0x3f317217, v46
	v_cmp_lt_f32_e64 s[6:7], |v46|, s88
	s_nop 1
	v_cndmask_b32_e64 v46, v46, v48, s[6:7]
	v_cndmask_b32_e32 v48, 0, v174, vcc
	v_cmp_gt_f32_e32 vcc, s86, v47
	v_sub_f32_e32 v46, v46, v48
	s_nop 0
	v_cndmask_b32_e64 v48, 0, 32, vcc
	v_ldexp_f32 v47, v47, v48
	v_log_f32_e32 v47, v47
	s_nop 0
	v_mul_f32_e32 v48, 0x3f317217, v47
	v_fma_f32 v48, v47, s87, -v48
	v_fmac_f32_e32 v48, 0x3377d1cf, v47
	v_fmac_f32_e32 v48, 0x3f317217, v47
	v_cmp_lt_f32_e64 s[6:7], |v47|, s88
	s_nop 1
	v_cndmask_b32_e64 v47, v47, v48, s[6:7]
	v_cndmask_b32_e32 v48, 0, v174, vcc
	v_cmp_gt_f32_e32 vcc, s86, v40
	v_sub_f32_e32 v47, v47, v48
	s_nop 0
	v_cndmask_b32_e64 v48, 0, 32, vcc
	v_ldexp_f32 v40, v40, v48
	v_log_f32_e32 v40, v40
	s_nop 0
	v_mul_f32_e32 v48, 0x3f317217, v40
	v_fma_f32 v48, v40, s87, -v48
	v_fmac_f32_e32 v48, 0x3377d1cf, v40
	v_fmac_f32_e32 v48, 0x3f317217, v40
	v_cmp_lt_f32_e64 s[6:7], |v40|, s88
	s_nop 1
	v_cndmask_b32_e64 v40, v40, v48, s[6:7]
	v_cndmask_b32_e32 v48, 0, v174, vcc
	v_cmp_gt_f32_e32 vcc, s86, v41
	v_sub_f32_e32 v40, v40, v48
	s_nop 0
	v_cndmask_b32_e64 v48, 0, 32, vcc
	v_ldexp_f32 v41, v41, v48
	v_log_f32_e32 v41, v41
	s_nop 0
	v_mul_f32_e32 v48, 0x3f317217, v41
	v_fma_f32 v48, v41, s87, -v48
	v_fmac_f32_e32 v48, 0x3377d1cf, v41
	v_fmac_f32_e32 v48, 0x3f317217, v41
	v_cmp_lt_f32_e64 s[6:7], |v41|, s88
	s_nop 1
	v_cndmask_b32_e64 v41, v41, v48, s[6:7]
	v_cndmask_b32_e32 v48, 0, v174, vcc
	v_cmp_gt_f32_e32 vcc, s86, v42
	v_sub_f32_e32 v41, v41, v48
	s_nop 0
	v_cndmask_b32_e64 v48, 0, 32, vcc
	v_ldexp_f32 v42, v42, v48
	v_log_f32_e32 v42, v42
	s_nop 0
	v_mul_f32_e32 v48, 0x3f317217, v42
	v_fma_f32 v48, v42, s87, -v48
	v_fmac_f32_e32 v48, 0x3377d1cf, v42
	v_fmac_f32_e32 v48, 0x3f317217, v42
	v_cmp_lt_f32_e64 s[6:7], |v42|, s88
	s_nop 1
	v_cndmask_b32_e64 v42, v42, v48, s[6:7]
	v_cndmask_b32_e32 v48, 0, v174, vcc
	v_cmp_gt_f32_e32 vcc, s86, v43
	v_sub_f32_e32 v42, v42, v48
	s_nop 0
	v_cndmask_b32_e64 v48, 0, 32, vcc
	v_ldexp_f32 v43, v43, v48
	v_log_f32_e32 v43, v43
	s_nop 0
	v_mul_f32_e32 v48, 0x3f317217, v43
	v_fma_f32 v48, v43, s87, -v48
	v_fmac_f32_e32 v48, 0x3377d1cf, v43
	v_fmac_f32_e32 v48, 0x3f317217, v43
	v_cmp_lt_f32_e64 s[6:7], |v43|, s88
	s_nop 1
	v_cndmask_b32_e64 v43, v43, v48, s[6:7]
	v_cndmask_b32_e32 v48, 0, v174, vcc
	v_sub_f32_e32 v43, v43, v48
	v_cvt_pk_f16_f32 v43, v42, v43
	v_cvt_pk_f16_f32 v42, v40, v41
	v_cvt_pk_f16_f32 v41, v46, v47
	v_cvt_pk_f16_f32 v40, v44, v45
	v_cmp_gt_f32_e32 vcc, s86, v36
	global_store_dwordx4 v[112:113], v[40:43], off offset:-1792 sc1
	s_nop 1
	v_cndmask_b32_e64 v40, 0, 32, vcc
	v_ldexp_f32 v36, v36, v40
	v_log_f32_e32 v36, v36
	s_nop 0
	v_mul_f32_e32 v40, 0x3f317217, v36
	v_fma_f32 v40, v36, s87, -v40
	v_fmac_f32_e32 v40, 0x3377d1cf, v36
	v_fmac_f32_e32 v40, 0x3f317217, v36
	v_cmp_lt_f32_e64 s[6:7], |v36|, s88
	s_nop 1
	v_cndmask_b32_e64 v36, v36, v40, s[6:7]
	v_cndmask_b32_e32 v40, 0, v174, vcc
	v_cmp_gt_f32_e32 vcc, s86, v37
	v_sub_f32_e32 v36, v36, v40
	s_nop 0
	v_cndmask_b32_e64 v40, 0, 32, vcc
	v_ldexp_f32 v37, v37, v40
	v_log_f32_e32 v37, v37
	s_nop 0
	v_mul_f32_e32 v40, 0x3f317217, v37
	v_fma_f32 v40, v37, s87, -v40
	v_fmac_f32_e32 v40, 0x3377d1cf, v37
	v_fmac_f32_e32 v40, 0x3f317217, v37
	v_cmp_lt_f32_e64 s[6:7], |v37|, s88
	s_nop 1
	v_cndmask_b32_e64 v37, v37, v40, s[6:7]
	v_cndmask_b32_e32 v40, 0, v174, vcc
	v_cmp_gt_f32_e32 vcc, s86, v38
	v_sub_f32_e32 v37, v37, v40
	s_nop 0
	v_cndmask_b32_e64 v40, 0, 32, vcc
	v_ldexp_f32 v38, v38, v40
	v_log_f32_e32 v38, v38
	s_nop 0
	v_mul_f32_e32 v40, 0x3f317217, v38
	v_fma_f32 v40, v38, s87, -v40
	v_fmac_f32_e32 v40, 0x3377d1cf, v38
	v_fmac_f32_e32 v40, 0x3f317217, v38
	v_cmp_lt_f32_e64 s[6:7], |v38|, s88
	s_nop 1
	v_cndmask_b32_e64 v38, v38, v40, s[6:7]
	v_cndmask_b32_e32 v40, 0, v174, vcc
	v_cmp_gt_f32_e32 vcc, s86, v39
	v_sub_f32_e32 v38, v38, v40
	s_nop 0
	v_cndmask_b32_e64 v40, 0, 32, vcc
	v_ldexp_f32 v39, v39, v40
	v_log_f32_e32 v39, v39
	s_nop 0
	v_mul_f32_e32 v40, 0x3f317217, v39
	v_fma_f32 v40, v39, s87, -v40
	v_fmac_f32_e32 v40, 0x3377d1cf, v39
	v_fmac_f32_e32 v40, 0x3f317217, v39
	v_cmp_lt_f32_e64 s[6:7], |v39|, s88
	s_nop 1
	v_cndmask_b32_e64 v39, v39, v40, s[6:7]
	v_cndmask_b32_e32 v40, 0, v174, vcc
	v_cmp_gt_f32_e32 vcc, s86, v32
	v_sub_f32_e32 v39, v39, v40
	s_nop 0
	v_cndmask_b32_e64 v40, 0, 32, vcc
	v_ldexp_f32 v32, v32, v40
	v_log_f32_e32 v32, v32
	s_nop 0
	v_mul_f32_e32 v40, 0x3f317217, v32
	v_fma_f32 v40, v32, s87, -v40
	v_fmac_f32_e32 v40, 0x3377d1cf, v32
	v_fmac_f32_e32 v40, 0x3f317217, v32
	v_cmp_lt_f32_e64 s[6:7], |v32|, s88
	s_nop 1
	v_cndmask_b32_e64 v32, v32, v40, s[6:7]
	v_cndmask_b32_e32 v40, 0, v174, vcc
	v_cmp_gt_f32_e32 vcc, s86, v33
	v_sub_f32_e32 v32, v32, v40
	s_nop 0
	v_cndmask_b32_e64 v40, 0, 32, vcc
	v_ldexp_f32 v33, v33, v40
	v_log_f32_e32 v33, v33
	s_nop 0
	v_mul_f32_e32 v40, 0x3f317217, v33
	v_fma_f32 v40, v33, s87, -v40
	v_fmac_f32_e32 v40, 0x3377d1cf, v33
	v_fmac_f32_e32 v40, 0x3f317217, v33
	v_cmp_lt_f32_e64 s[6:7], |v33|, s88
	s_nop 1
	v_cndmask_b32_e64 v33, v33, v40, s[6:7]
	v_cndmask_b32_e32 v40, 0, v174, vcc
	v_cmp_gt_f32_e32 vcc, s86, v34
	v_sub_f32_e32 v33, v33, v40
	s_nop 0
	v_cndmask_b32_e64 v40, 0, 32, vcc
	v_ldexp_f32 v34, v34, v40
	v_log_f32_e32 v34, v34
	s_nop 0
	v_mul_f32_e32 v40, 0x3f317217, v34
	v_fma_f32 v40, v34, s87, -v40
	v_fmac_f32_e32 v40, 0x3377d1cf, v34
	v_fmac_f32_e32 v40, 0x3f317217, v34
	v_cmp_lt_f32_e64 s[6:7], |v34|, s88
	s_nop 1
	v_cndmask_b32_e64 v34, v34, v40, s[6:7]
	v_cndmask_b32_e32 v40, 0, v174, vcc
	v_cmp_gt_f32_e32 vcc, s86, v35
	v_sub_f32_e32 v34, v34, v40
	s_nop 0
	v_cndmask_b32_e64 v40, 0, 32, vcc
	v_ldexp_f32 v35, v35, v40
	v_log_f32_e32 v35, v35
	s_nop 0
	v_mul_f32_e32 v40, 0x3f317217, v35
	v_fma_f32 v40, v35, s87, -v40
	v_fmac_f32_e32 v40, 0x3377d1cf, v35
	v_fmac_f32_e32 v40, 0x3f317217, v35
	v_cmp_lt_f32_e64 s[6:7], |v35|, s88
	s_nop 1
	v_cndmask_b32_e64 v35, v35, v40, s[6:7]
	v_cndmask_b32_e32 v40, 0, v174, vcc
	v_sub_f32_e32 v35, v35, v40
	v_cvt_pk_f16_f32 v35, v34, v35
	v_cvt_pk_f16_f32 v34, v32, v33
	v_cvt_pk_f16_f32 v33, v38, v39
	v_cvt_pk_f16_f32 v32, v36, v37
	v_cmp_gt_f32_e32 vcc, s86, v28
	global_store_dwordx4 v[104:105], v[32:35], off offset:-1792 sc1
	s_nop 1
	v_cndmask_b32_e64 v32, 0, 32, vcc
	v_ldexp_f32 v28, v28, v32
	v_log_f32_e32 v28, v28
	s_nop 0
	v_mul_f32_e32 v32, 0x3f317217, v28
	v_fma_f32 v32, v28, s87, -v32
	v_fmac_f32_e32 v32, 0x3377d1cf, v28
	v_fmac_f32_e32 v32, 0x3f317217, v28
	v_cmp_lt_f32_e64 s[6:7], |v28|, s88
	s_nop 1
	v_cndmask_b32_e64 v28, v28, v32, s[6:7]
	v_cndmask_b32_e32 v32, 0, v174, vcc
	v_cmp_gt_f32_e32 vcc, s86, v29
	v_sub_f32_e32 v28, v28, v32
	s_nop 0
	v_cndmask_b32_e64 v32, 0, 32, vcc
	v_ldexp_f32 v29, v29, v32
	v_log_f32_e32 v29, v29
	s_nop 0
	v_mul_f32_e32 v32, 0x3f317217, v29
	v_fma_f32 v32, v29, s87, -v32
	v_fmac_f32_e32 v32, 0x3377d1cf, v29
	v_fmac_f32_e32 v32, 0x3f317217, v29
	v_cmp_lt_f32_e64 s[6:7], |v29|, s88
	s_nop 1
	v_cndmask_b32_e64 v29, v29, v32, s[6:7]
	v_cndmask_b32_e32 v32, 0, v174, vcc
	v_cmp_gt_f32_e32 vcc, s86, v30
	v_sub_f32_e32 v29, v29, v32
	s_nop 0
	v_cndmask_b32_e64 v32, 0, 32, vcc
	v_ldexp_f32 v30, v30, v32
	v_log_f32_e32 v30, v30
	s_nop 0
	v_mul_f32_e32 v32, 0x3f317217, v30
	v_fma_f32 v32, v30, s87, -v32
	v_fmac_f32_e32 v32, 0x3377d1cf, v30
	v_fmac_f32_e32 v32, 0x3f317217, v30
	v_cmp_lt_f32_e64 s[6:7], |v30|, s88
	s_nop 1
	v_cndmask_b32_e64 v30, v30, v32, s[6:7]
	v_cndmask_b32_e32 v32, 0, v174, vcc
	v_cmp_gt_f32_e32 vcc, s86, v31
	v_sub_f32_e32 v30, v30, v32
	s_nop 0
	v_cndmask_b32_e64 v32, 0, 32, vcc
	v_ldexp_f32 v31, v31, v32
	v_log_f32_e32 v31, v31
	s_nop 0
	v_mul_f32_e32 v32, 0x3f317217, v31
	v_fma_f32 v32, v31, s87, -v32
	v_fmac_f32_e32 v32, 0x3377d1cf, v31
	v_fmac_f32_e32 v32, 0x3f317217, v31
	v_cmp_lt_f32_e64 s[6:7], |v31|, s88
	s_nop 1
	v_cndmask_b32_e64 v31, v31, v32, s[6:7]
	v_cndmask_b32_e32 v32, 0, v174, vcc
	v_cmp_gt_f32_e32 vcc, s86, v24
	v_sub_f32_e32 v31, v31, v32
	s_nop 0
	v_cndmask_b32_e64 v32, 0, 32, vcc
	v_ldexp_f32 v24, v24, v32
	v_log_f32_e32 v24, v24
	s_nop 0
	v_mul_f32_e32 v32, 0x3f317217, v24
	v_fma_f32 v32, v24, s87, -v32
	v_fmac_f32_e32 v32, 0x3377d1cf, v24
	v_fmac_f32_e32 v32, 0x3f317217, v24
	v_cmp_lt_f32_e64 s[6:7], |v24|, s88
	s_nop 1
	v_cndmask_b32_e64 v24, v24, v32, s[6:7]
	v_cndmask_b32_e32 v32, 0, v174, vcc
	v_cmp_gt_f32_e32 vcc, s86, v25
	v_sub_f32_e32 v24, v24, v32
	s_nop 0
	v_cndmask_b32_e64 v32, 0, 32, vcc
	v_ldexp_f32 v25, v25, v32
	v_log_f32_e32 v25, v25
	s_nop 0
	v_mul_f32_e32 v32, 0x3f317217, v25
	v_fma_f32 v32, v25, s87, -v32
	v_fmac_f32_e32 v32, 0x3377d1cf, v25
	v_fmac_f32_e32 v32, 0x3f317217, v25
	v_cmp_lt_f32_e64 s[6:7], |v25|, s88
	s_nop 1
	v_cndmask_b32_e64 v25, v25, v32, s[6:7]
	v_cndmask_b32_e32 v32, 0, v174, vcc
	v_cmp_gt_f32_e32 vcc, s86, v26
	v_sub_f32_e32 v25, v25, v32
	s_nop 0
	v_cndmask_b32_e64 v32, 0, 32, vcc
	v_ldexp_f32 v26, v26, v32
	v_log_f32_e32 v26, v26
	s_nop 0
	v_mul_f32_e32 v32, 0x3f317217, v26
	v_fma_f32 v32, v26, s87, -v32
	v_fmac_f32_e32 v32, 0x3377d1cf, v26
	v_fmac_f32_e32 v32, 0x3f317217, v26
	v_cmp_lt_f32_e64 s[6:7], |v26|, s88
	s_nop 1
	v_cndmask_b32_e64 v26, v26, v32, s[6:7]
	v_cndmask_b32_e32 v32, 0, v174, vcc
	v_cmp_gt_f32_e32 vcc, s86, v27
	v_sub_f32_e32 v26, v26, v32
	s_nop 0
	v_cndmask_b32_e64 v32, 0, 32, vcc
	v_ldexp_f32 v27, v27, v32
	v_log_f32_e32 v27, v27
	s_nop 0
	v_mul_f32_e32 v32, 0x3f317217, v27
	v_fma_f32 v32, v27, s87, -v32
	v_fmac_f32_e32 v32, 0x3377d1cf, v27
	v_fmac_f32_e32 v32, 0x3f317217, v27
	v_cmp_lt_f32_e64 s[6:7], |v27|, s88
	s_nop 1
	v_cndmask_b32_e64 v27, v27, v32, s[6:7]
	v_cndmask_b32_e32 v32, 0, v174, vcc
	v_sub_f32_e32 v27, v27, v32
	v_cvt_pk_f16_f32 v27, v26, v27
	v_cvt_pk_f16_f32 v26, v24, v25
	v_cvt_pk_f16_f32 v25, v30, v31
	v_cvt_pk_f16_f32 v24, v28, v29
	v_cmp_gt_f32_e32 vcc, s86, v20
	global_store_dwordx4 v[96:97], v[24:27], off offset:-1792 sc1
	s_nop 1
	v_cndmask_b32_e64 v24, 0, 32, vcc
	v_ldexp_f32 v20, v20, v24
	v_log_f32_e32 v20, v20
	s_nop 0
	v_mul_f32_e32 v24, 0x3f317217, v20
	v_fma_f32 v24, v20, s87, -v24
	v_fmac_f32_e32 v24, 0x3377d1cf, v20
	v_fmac_f32_e32 v24, 0x3f317217, v20
	v_cmp_lt_f32_e64 s[6:7], |v20|, s88
	s_nop 1
	v_cndmask_b32_e64 v20, v20, v24, s[6:7]
	v_cndmask_b32_e32 v24, 0, v174, vcc
	v_cmp_gt_f32_e32 vcc, s86, v21
	v_sub_f32_e32 v20, v20, v24
	s_nop 0
	v_cndmask_b32_e64 v24, 0, 32, vcc
	v_ldexp_f32 v21, v21, v24
	v_log_f32_e32 v21, v21
	s_nop 0
	v_mul_f32_e32 v24, 0x3f317217, v21
	v_fma_f32 v24, v21, s87, -v24
	v_fmac_f32_e32 v24, 0x3377d1cf, v21
	v_fmac_f32_e32 v24, 0x3f317217, v21
	v_cmp_lt_f32_e64 s[6:7], |v21|, s88
	s_nop 1
	v_cndmask_b32_e64 v21, v21, v24, s[6:7]
	v_cndmask_b32_e32 v24, 0, v174, vcc
	v_cmp_gt_f32_e32 vcc, s86, v22
	v_sub_f32_e32 v21, v21, v24
	s_nop 0
	v_cndmask_b32_e64 v24, 0, 32, vcc
	v_ldexp_f32 v22, v22, v24
	v_log_f32_e32 v22, v22
	s_nop 0
	v_mul_f32_e32 v24, 0x3f317217, v22
	v_fma_f32 v24, v22, s87, -v24
	v_fmac_f32_e32 v24, 0x3377d1cf, v22
	v_fmac_f32_e32 v24, 0x3f317217, v22
	v_cmp_lt_f32_e64 s[6:7], |v22|, s88
	s_nop 1
	v_cndmask_b32_e64 v22, v22, v24, s[6:7]
	v_cndmask_b32_e32 v24, 0, v174, vcc
	v_cmp_gt_f32_e32 vcc, s86, v23
	v_sub_f32_e32 v22, v22, v24
	s_nop 0
	v_cndmask_b32_e64 v24, 0, 32, vcc
	v_ldexp_f32 v23, v23, v24
	v_log_f32_e32 v23, v23
	s_nop 0
	v_mul_f32_e32 v24, 0x3f317217, v23
	v_fma_f32 v24, v23, s87, -v24
	v_fmac_f32_e32 v24, 0x3377d1cf, v23
	v_fmac_f32_e32 v24, 0x3f317217, v23
	v_cmp_lt_f32_e64 s[6:7], |v23|, s88
	s_nop 1
	v_cndmask_b32_e64 v23, v23, v24, s[6:7]
	v_cndmask_b32_e32 v24, 0, v174, vcc
	v_cmp_gt_f32_e32 vcc, s86, v16
	v_sub_f32_e32 v23, v23, v24
	s_nop 0
	v_cndmask_b32_e64 v24, 0, 32, vcc
	v_ldexp_f32 v16, v16, v24
	v_log_f32_e32 v16, v16
	s_nop 0
	v_mul_f32_e32 v24, 0x3f317217, v16
	v_fma_f32 v24, v16, s87, -v24
	v_fmac_f32_e32 v24, 0x3377d1cf, v16
	v_fmac_f32_e32 v24, 0x3f317217, v16
	v_cmp_lt_f32_e64 s[6:7], |v16|, s88
	s_nop 1
	v_cndmask_b32_e64 v16, v16, v24, s[6:7]
	v_cndmask_b32_e32 v24, 0, v174, vcc
	v_cmp_gt_f32_e32 vcc, s86, v17
	v_sub_f32_e32 v16, v16, v24
	s_nop 0
	v_cndmask_b32_e64 v24, 0, 32, vcc
	v_ldexp_f32 v17, v17, v24
	v_log_f32_e32 v17, v17
	s_nop 0
	v_mul_f32_e32 v24, 0x3f317217, v17
	v_fma_f32 v24, v17, s87, -v24
	v_fmac_f32_e32 v24, 0x3377d1cf, v17
	v_fmac_f32_e32 v24, 0x3f317217, v17
	v_cmp_lt_f32_e64 s[6:7], |v17|, s88
	s_nop 1
	v_cndmask_b32_e64 v17, v17, v24, s[6:7]
	v_cndmask_b32_e32 v24, 0, v174, vcc
	v_cmp_gt_f32_e32 vcc, s86, v18
	v_sub_f32_e32 v17, v17, v24
	s_nop 0
	v_cndmask_b32_e64 v24, 0, 32, vcc
	v_ldexp_f32 v18, v18, v24
	v_log_f32_e32 v18, v18
	s_nop 0
	v_mul_f32_e32 v24, 0x3f317217, v18
	v_fma_f32 v24, v18, s87, -v24
	v_fmac_f32_e32 v24, 0x3377d1cf, v18
	v_fmac_f32_e32 v24, 0x3f317217, v18
	v_cmp_lt_f32_e64 s[6:7], |v18|, s88
	s_nop 1
	v_cndmask_b32_e64 v18, v18, v24, s[6:7]
	v_cndmask_b32_e32 v24, 0, v174, vcc
	v_cmp_gt_f32_e32 vcc, s86, v19
	v_sub_f32_e32 v18, v18, v24
	s_nop 0
	v_cndmask_b32_e64 v24, 0, 32, vcc
	v_ldexp_f32 v19, v19, v24
	v_log_f32_e32 v19, v19
	s_nop 0
	v_mul_f32_e32 v24, 0x3f317217, v19
	v_fma_f32 v24, v19, s87, -v24
	v_fmac_f32_e32 v24, 0x3377d1cf, v19
	v_fmac_f32_e32 v24, 0x3f317217, v19
	v_cmp_lt_f32_e64 s[6:7], |v19|, s88
	s_nop 1
	v_cndmask_b32_e64 v19, v19, v24, s[6:7]
	v_cndmask_b32_e32 v24, 0, v174, vcc
	v_sub_f32_e32 v19, v19, v24
	v_cvt_pk_f16_f32 v19, v18, v19
	v_cvt_pk_f16_f32 v18, v16, v17
	v_cvt_pk_f16_f32 v17, v22, v23
	v_cvt_pk_f16_f32 v16, v20, v21
	v_cmp_gt_f32_e32 vcc, s86, v12
	global_store_dwordx4 v[88:89], v[16:19], off offset:-1792 sc1
	s_nop 1
	v_cndmask_b32_e64 v16, 0, 32, vcc
	v_ldexp_f32 v12, v12, v16
	v_log_f32_e32 v12, v12
	s_nop 0
	v_mul_f32_e32 v16, 0x3f317217, v12
	v_fma_f32 v16, v12, s87, -v16
	v_fmac_f32_e32 v16, 0x3377d1cf, v12
	v_fmac_f32_e32 v16, 0x3f317217, v12
	v_cmp_lt_f32_e64 s[6:7], |v12|, s88
	s_nop 1
	v_cndmask_b32_e64 v12, v12, v16, s[6:7]
	v_cndmask_b32_e32 v16, 0, v174, vcc
	v_cmp_gt_f32_e32 vcc, s86, v13
	v_sub_f32_e32 v12, v12, v16
	s_nop 0
	v_cndmask_b32_e64 v16, 0, 32, vcc
	v_ldexp_f32 v13, v13, v16
	v_log_f32_e32 v13, v13
	s_nop 0
	v_mul_f32_e32 v16, 0x3f317217, v13
	v_fma_f32 v16, v13, s87, -v16
	v_fmac_f32_e32 v16, 0x3377d1cf, v13
	v_fmac_f32_e32 v16, 0x3f317217, v13
	v_cmp_lt_f32_e64 s[6:7], |v13|, s88
	s_nop 1
	v_cndmask_b32_e64 v13, v13, v16, s[6:7]
	v_cndmask_b32_e32 v16, 0, v174, vcc
	v_cmp_gt_f32_e32 vcc, s86, v14
	v_sub_f32_e32 v13, v13, v16
	s_nop 0
	v_cndmask_b32_e64 v16, 0, 32, vcc
	v_ldexp_f32 v14, v14, v16
	v_log_f32_e32 v14, v14
	s_nop 0
	v_mul_f32_e32 v16, 0x3f317217, v14
	v_fma_f32 v16, v14, s87, -v16
	v_fmac_f32_e32 v16, 0x3377d1cf, v14
	v_fmac_f32_e32 v16, 0x3f317217, v14
	v_cmp_lt_f32_e64 s[6:7], |v14|, s88
	s_nop 1
	v_cndmask_b32_e64 v14, v14, v16, s[6:7]
	v_cndmask_b32_e32 v16, 0, v174, vcc
	v_cmp_gt_f32_e32 vcc, s86, v15
	v_sub_f32_e32 v14, v14, v16
	s_nop 0
	v_cndmask_b32_e64 v16, 0, 32, vcc
	v_ldexp_f32 v15, v15, v16
	v_log_f32_e32 v15, v15
	s_nop 0
	v_mul_f32_e32 v16, 0x3f317217, v15
	v_fma_f32 v16, v15, s87, -v16
	v_fmac_f32_e32 v16, 0x3377d1cf, v15
	v_fmac_f32_e32 v16, 0x3f317217, v15
	v_cmp_lt_f32_e64 s[6:7], |v15|, s88
	s_nop 1
	v_cndmask_b32_e64 v15, v15, v16, s[6:7]
	v_cndmask_b32_e32 v16, 0, v174, vcc
	v_cmp_gt_f32_e32 vcc, s86, v8
	v_sub_f32_e32 v15, v15, v16
	s_nop 0
	v_cndmask_b32_e64 v16, 0, 32, vcc
	v_ldexp_f32 v8, v8, v16
	v_log_f32_e32 v8, v8
	s_nop 0
	v_mul_f32_e32 v16, 0x3f317217, v8
	v_fma_f32 v16, v8, s87, -v16
	v_fmac_f32_e32 v16, 0x3377d1cf, v8
	v_fmac_f32_e32 v16, 0x3f317217, v8
	v_cmp_lt_f32_e64 s[6:7], |v8|, s88
	s_nop 1
	v_cndmask_b32_e64 v8, v8, v16, s[6:7]
	v_cndmask_b32_e32 v16, 0, v174, vcc
	v_cmp_gt_f32_e32 vcc, s86, v9
	v_sub_f32_e32 v8, v8, v16
	s_nop 0
	v_cndmask_b32_e64 v16, 0, 32, vcc
	v_ldexp_f32 v9, v9, v16
	v_log_f32_e32 v9, v9
	s_nop 0
	v_mul_f32_e32 v16, 0x3f317217, v9
	v_fma_f32 v16, v9, s87, -v16
	v_fmac_f32_e32 v16, 0x3377d1cf, v9
	v_fmac_f32_e32 v16, 0x3f317217, v9
	v_cmp_lt_f32_e64 s[6:7], |v9|, s88
	s_nop 1
	v_cndmask_b32_e64 v9, v9, v16, s[6:7]
	v_cndmask_b32_e32 v16, 0, v174, vcc
	v_cmp_gt_f32_e32 vcc, s86, v10
	v_sub_f32_e32 v9, v9, v16
	s_nop 0
	v_cndmask_b32_e64 v16, 0, 32, vcc
	v_ldexp_f32 v10, v10, v16
	v_log_f32_e32 v10, v10
	s_nop 0
	v_mul_f32_e32 v16, 0x3f317217, v10
	v_fma_f32 v16, v10, s87, -v16
	v_fmac_f32_e32 v16, 0x3377d1cf, v10
	v_fmac_f32_e32 v16, 0x3f317217, v10
	v_cmp_lt_f32_e64 s[6:7], |v10|, s88
	s_nop 1
	v_cndmask_b32_e64 v10, v10, v16, s[6:7]
	v_cndmask_b32_e32 v16, 0, v174, vcc
	v_cmp_gt_f32_e32 vcc, s86, v11
	v_sub_f32_e32 v10, v10, v16
	s_nop 0
	v_cndmask_b32_e64 v16, 0, 32, vcc
	v_ldexp_f32 v11, v11, v16
	v_log_f32_e32 v11, v11
	s_nop 0
	v_mul_f32_e32 v16, 0x3f317217, v11
	v_fma_f32 v16, v11, s87, -v16
	v_fmac_f32_e32 v16, 0x3377d1cf, v11
	v_fmac_f32_e32 v16, 0x3f317217, v11
	v_cmp_lt_f32_e64 s[6:7], |v11|, s88
	s_nop 1
	v_cndmask_b32_e64 v11, v11, v16, s[6:7]
	v_cndmask_b32_e32 v16, 0, v174, vcc
	v_cmp_gt_f32_e32 vcc, s86, v71
	v_sub_f32_e32 v11, v11, v16
	v_cvt_pk_f16_f32 v11, v10, v11
	v_cndmask_b32_e64 v4, 0, 32, vcc
	v_ldexp_f32 v4, v71, v4
	v_log_f32_e32 v4, v4
	v_cvt_pk_f16_f32 v10, v8, v9
	v_cvt_pk_f16_f32 v9, v14, v15
	v_cvt_pk_f16_f32 v8, v12, v13
	global_store_dwordx4 v[80:81], v[8:11], off offset:-1792 sc1
	v_cmp_lt_f32_e64 s[6:7], |v4|, s88
	s_nop 0
	v_mul_f32_e32 v8, 0x3f317217, v4
	v_fma_f32 v8, v4, s87, -v8
	v_fmac_f32_e32 v8, 0x3377d1cf, v4
	v_fmac_f32_e32 v8, 0x3f317217, v4
	v_cndmask_b32_e64 v4, v4, v8, s[6:7]
	v_cndmask_b32_e32 v8, 0, v174, vcc
	v_cmp_gt_f32_e32 vcc, s86, v70
	v_sub_f32_e32 v4, v4, v8
	s_nop 0
	v_cndmask_b32_e64 v5, 0, 32, vcc
	v_ldexp_f32 v5, v70, v5
	v_log_f32_e32 v5, v5
	s_nop 0
	v_mul_f32_e32 v8, 0x3f317217, v5
	v_fma_f32 v8, v5, s87, -v8
	v_fmac_f32_e32 v8, 0x3377d1cf, v5
	v_fmac_f32_e32 v8, 0x3f317217, v5
	v_cmp_lt_f32_e64 s[6:7], |v5|, s88
	s_nop 1
	v_cndmask_b32_e64 v5, v5, v8, s[6:7]
	v_cndmask_b32_e32 v8, 0, v174, vcc
	v_cmp_gt_f32_e32 vcc, s86, v69
	v_sub_f32_e32 v5, v5, v8
	s_nop 0
	v_cndmask_b32_e64 v6, 0, 32, vcc
	v_ldexp_f32 v6, v69, v6
	v_log_f32_e32 v6, v6
	s_nop 0
	v_mul_f32_e32 v8, 0x3f317217, v6
	v_fma_f32 v8, v6, s87, -v8
	v_fmac_f32_e32 v8, 0x3377d1cf, v6
	v_fmac_f32_e32 v8, 0x3f317217, v6
	v_cmp_lt_f32_e64 s[6:7], |v6|, s88
	s_nop 1
	v_cndmask_b32_e64 v6, v6, v8, s[6:7]
	v_cndmask_b32_e32 v8, 0, v174, vcc
	v_cmp_gt_f32_e32 vcc, s86, v68
	v_sub_f32_e32 v6, v6, v8
	s_nop 0
	v_cndmask_b32_e64 v7, 0, 32, vcc
	v_ldexp_f32 v7, v68, v7
	v_log_f32_e32 v7, v7
	s_nop 0
	v_mul_f32_e32 v8, 0x3f317217, v7
	v_fma_f32 v8, v7, s87, -v8
	v_fmac_f32_e32 v8, 0x3377d1cf, v7
	v_fmac_f32_e32 v8, 0x3f317217, v7
	v_cmp_lt_f32_e64 s[6:7], |v7|, s88
	s_nop 1
	v_cndmask_b32_e64 v7, v7, v8, s[6:7]
	v_cndmask_b32_e32 v8, 0, v174, vcc
	v_cmp_gt_f32_e32 vcc, s86, v67
	v_sub_f32_e32 v7, v7, v8
	s_nop 0
	v_cndmask_b32_e64 v0, 0, 32, vcc
	v_ldexp_f32 v0, v67, v0
	v_log_f32_e32 v0, v0
	s_nop 0
	v_mul_f32_e32 v8, 0x3f317217, v0
	v_fma_f32 v8, v0, s87, -v8
	v_fmac_f32_e32 v8, 0x3377d1cf, v0
	v_fmac_f32_e32 v8, 0x3f317217, v0
	v_cmp_lt_f32_e64 s[6:7], |v0|, s88
	s_nop 1
	v_cndmask_b32_e64 v0, v0, v8, s[6:7]
	v_cndmask_b32_e32 v8, 0, v174, vcc
	v_cmp_gt_f32_e32 vcc, s86, v66
	v_sub_f32_e32 v0, v0, v8
	s_nop 0
	v_cndmask_b32_e64 v1, 0, 32, vcc
	v_ldexp_f32 v1, v66, v1
	v_log_f32_e32 v1, v1
	s_nop 0
	v_mul_f32_e32 v8, 0x3f317217, v1
	v_fma_f32 v8, v1, s87, -v8
	v_fmac_f32_e32 v8, 0x3377d1cf, v1
	v_fmac_f32_e32 v8, 0x3f317217, v1
	v_cmp_lt_f32_e64 s[6:7], |v1|, s88
	s_nop 1
	v_cndmask_b32_e64 v1, v1, v8, s[6:7]
	v_cndmask_b32_e32 v8, 0, v174, vcc
	v_cmp_gt_f32_e32 vcc, s86, v65
	v_sub_f32_e32 v1, v1, v8
	s_nop 0
	v_cndmask_b32_e64 v2, 0, 32, vcc
	v_ldexp_f32 v2, v65, v2
	v_log_f32_e32 v2, v2
	s_nop 0
	v_mul_f32_e32 v8, 0x3f317217, v2
	v_fma_f32 v8, v2, s87, -v8
	v_fmac_f32_e32 v8, 0x3377d1cf, v2
	v_fmac_f32_e32 v8, 0x3f317217, v2
	v_cmp_lt_f32_e64 s[6:7], |v2|, s88
	s_nop 1
	v_cndmask_b32_e64 v2, v2, v8, s[6:7]
	v_cndmask_b32_e32 v8, 0, v174, vcc
	v_cmp_gt_f32_e32 vcc, s86, v64
	v_sub_f32_e32 v2, v2, v8
	s_nop 0
	v_cndmask_b32_e64 v3, 0, 32, vcc
	v_ldexp_f32 v3, v64, v3
	v_log_f32_e32 v3, v3
	s_nop 0
	v_mul_f32_e32 v8, 0x3f317217, v3
	v_fma_f32 v8, v3, s87, -v8
	v_fmac_f32_e32 v8, 0x3377d1cf, v3
	v_fmac_f32_e32 v8, 0x3f317217, v3
	v_cmp_lt_f32_e64 s[6:7], |v3|, s88
	s_nop 1
	v_cndmask_b32_e64 v3, v3, v8, s[6:7]
	v_cndmask_b32_e32 v8, 0, v174, vcc
	v_sub_f32_e32 v3, v3, v8
	v_cvt_pk_f16_f32 v3, v2, v3
	v_cvt_pk_f16_f32 v2, v0, v1
	v_cvt_pk_f16_f32 v1, v6, v7
	v_cvt_pk_f16_f32 v0, v4, v5
	global_store_dwordx4 v[72:73], v[0:3], off offset:-1792 sc1
	s_branch .LBB0_237

.LBB0_854:
	s_or_b64 exec, exec, s[96:97]
	s_min_i32 s16, s77, s3
	s_lshl_b32 s16, s16, 5
	v_or_b32_e32 v0, s16, v191
	v_xad_u32 v1, v0, -1, s74
	v_cndmask_b32_e64 v0, v1, v0, s[4:5]
	v_add_u32_e32 v1, s16, v192
	v_xad_u32 v3, v1, -1, s74
	v_add_u32_e32 v0, s73, v0
	v_cndmask_b32_e64 v3, v3, v1, s[4:5]
	v_ashrrev_i32_e32 v1, 31, v0
	s_waitcnt vmcnt(7)
	ds_write_b128 v197, v[4:7] offset:61952
	v_mad_i64_i32 v[4:5], s[16:17], v0, s89, v[180:181]
	v_lshlrev_b64 v[0:1], 11, v[0:1]
	v_lshl_add_u64 v[0:1], v[182:183], 0, v[0:1]
	global_load_dwordx4 v[12:15], v[4:5], off
	global_load_dwordx4 v[20:23], v[0:1], off
	v_add_u32_e32 v0, s73, v3
	v_mad_i64_i32 v[0:1], s[16:17], v0, s89, v[184:185]
	global_load_dwordx4 v[4:7], v[0:1], off
	v_add_u32_e32 v0, 0x8800, v205
	s_waitcnt lgkmcnt(0)
	s_barrier
	ds_read_b64_tr_b16 v[92:93], v204
	ds_read_b64_tr_b16 v[94:95], v204 offset:4352
	ds_read_b64 v[88:89], v0 offset:1024
	ds_read_b64 v[90:91], v0 offset:1056
	ds_read_b64 v[80:81], v0 offset:1088
	ds_read_b64 v[82:83], v0 offset:1120
	ds_read_b64 v[72:73], v0 offset:1152
	ds_read_b64 v[74:75], v0 offset:1184
	ds_read_b64 v[60:61], v0 offset:1216
	ds_read_b64 v[62:63], v0 offset:1248
	v_add_u32_e32 v0, 0x9800, v205
	v_add_u32_e32 v1, 0xb800, v201
	ds_read_b64 v[84:85], v0 offset:1280
	ds_read_b64 v[86:87], v0 offset:1312
	ds_read_b64 v[76:77], v0 offset:1344
	ds_read_b64 v[78:79], v0 offset:1376
	ds_read_b64 v[68:69], v0 offset:1408
	ds_read_b64 v[70:71], v0 offset:1440
	ds_read_b64 v[64:65], v0 offset:1472
	ds_read_b64 v[66:67], v0 offset:1504
	ds_read_b64 v[100:101], v1 offset:1792
	ds_read_b64 v[102:103], v1 offset:1824
	v_add_u32_e32 v0, 0xa800, v201
	ds_read_b64 v[96:97], v0 offset:1536
	ds_read_b64 v[98:99], v0 offset:1568
	ds_read_b64 v[108:109], v0 offset:1600
	ds_read_b64 v[110:111], v0 offset:1632
	ds_read_b64 v[112:113], v1 offset:1856
	ds_read_b64 v[114:115], v1 offset:1888
	s_waitcnt lgkmcnt(6)
	v_mfma_f32_16x16x32_bf16 v[100:103], v[100:103], v[84:87], 0
	s_add_i32 s77, s77, 2
	v_subrev_u32_e32 v222, 64, v222
	s_cmp_ge_u32 s78, s35
	s_waitcnt lgkmcnt(4)
	v_mfma_f32_16x16x32_bf16 v[104:107], v[96:99], v[88:91], 0
	s_waitcnt lgkmcnt(0)
	v_mfma_f32_16x16x32_bf16 v[100:103], v[112:115], v[76:79], v[100:103]
	ds_read_b64 v[112:113], v0 offset:1664
	ds_read_b64 v[114:115], v0 offset:1696
	ds_read_b64 v[116:117], v1 offset:1920
	ds_read_b64 v[118:119], v1 offset:1952
	v_mfma_f32_16x16x32_bf16 v[104:107], v[108:111], v[80:83], v[104:107]
	s_waitcnt lgkmcnt(0)
	v_mfma_f32_16x16x32_bf16 v[100:103], v[116:119], v[68:71], v[100:103]
	ds_read_b64 v[116:117], v0 offset:1728
	ds_read_b64 v[118:119], v0 offset:1760
	ds_read_b64 v[226:227], v1 offset:1984
	ds_read_b64 v[228:229], v1 offset:2016
	v_mov_b32_e32 v0, s93
	v_mfma_f32_16x16x32_bf16 v[96:99], v[96:99], v[84:87], 0
	v_mfma_f32_16x16x32_bf16 v[104:107], v[112:115], v[72:75], v[104:107]
	v_mfma_f32_16x16x32_bf16 v[96:99], v[108:111], v[76:79], v[96:99]
	s_waitcnt lgkmcnt(2)
	v_mfma_f32_16x16x32_bf16 v[104:107], v[116:119], v[60:63], v[104:107]
	s_waitcnt lgkmcnt(0)
	v_mfma_f32_16x16x32_bf16 v[100:103], v[226:229], v[64:67], v[100:103]
	v_mov_b32_e32 v226, s93
	s_nop 4
	v_cndmask_b32_e64 v0, v104, v0, s[8:9]
	v_cndmask_b32_e64 v0, v0, v104, s[10:11]
	v_mfma_f32_16x16x32_bf16 v[96:99], v[112:115], v[68:71], v[96:99]
	v_cndmask_b32_e64 v3, v106, 0, s[12:13]
	v_cndmask_b32_e64 v1, v100, v226, s[8:9]
	v_cndmask_b32_e64 v100, v1, v100, s[10:11]
	v_cndmask_b32_e64 v1, 0, v105, s[10:11]
	v_cndmask_b32_e64 v104, v107, 0, s[14:15]
	v_cvt_pk_bf16_f32 v0, v0, v1
	v_cvt_pk_bf16_f32 v1, v3, v104
	ds_read_b128 v[104:107], v206
	ds_read_b128 v[108:111], v207
	v_mfma_f32_16x16x32_bf16 v[96:99], v[116:119], v[64:67], v[96:99]
	v_cndmask_b32_e64 v101, 0, v101, s[10:11]
	v_cndmask_b32_e64 v102, v102, 0, s[12:13]
	v_cndmask_b32_e64 v103, v103, 0, s[14:15]
	v_mov_b32_e32 v3, v2
	s_waitcnt lgkmcnt(0)
	v_pk_mul_f32 v[110:111], v[54:55], v[110:111]
	s_nop 1
	v_cvt_pk_bf16_f32 v96, v96, v97
	v_cvt_pk_bf16_f32 v97, v98, v99
	v_cvt_pk_bf16_f32 v98, v100, v101
	v_cvt_pk_bf16_f32 v99, v102, v103
	v_mfma_f32_16x16x32_bf16 v[100:103], v[92:95], v[0:3], 0
	v_mul_f32_e64 v0, v58, v106
	v_mul_f32_e64 v1, v59, v107
	v_pk_mul_f32 v[106:107], v[52:53], v[108:109]
	v_pk_mul_f32 v[104:105], v[56:57], v[104:105]
	v_cvt_pk_bf16_f32 v106, v106, v107
	v_cvt_pk_bf16_f32 v107, v110, v111
	ds_read_b128 v[108:111], v208
	ds_read_b128 v[112:115], v209
	v_cvt_pk_bf16_f32 v104, v104, v105
	v_cvt_pk_bf16_f32 v105, v0, v1
	v_mfma_f32_16x16x32_bf16 v[96:99], v[92:95], v[96:99], 0
	s_waitcnt lgkmcnt(1)
	v_pk_mul_f32 v[0:1], v[50:51], v[110:111]
	v_pk_mul_f32 v[108:109], v[48:49], v[108:109]
	s_waitcnt lgkmcnt(0)
	v_pk_mul_f32 v[110:111], v[46:47], v[114:115]
	v_pk_mul_f32 v[112:113], v[44:45], v[112:113]
	v_cvt_pk_bf16_f32 v116, v108, v109
	v_cvt_pk_bf16_f32 v118, v112, v113
	v_cvt_pk_bf16_f32 v119, v110, v111
	ds_read_b128 v[108:111], v210
	ds_read_b128 v[112:115], v211
	v_cvt_pk_bf16_f32 v117, v0, v1
	v_mfma_f32_16x16x32_bf16 v[88:91], v[104:107], v[88:91], v[100:103]
	v_xor_b32_e32 v3, 0xffffffdf, v190
	s_waitcnt lgkmcnt(1)
	v_pk_mul_f32 v[0:1], v[42:43], v[110:111]
	s_waitcnt lgkmcnt(0)
	v_pk_mul_f32 v[114:115], v[38:39], v[114:115]
	v_pk_mul_f32 v[110:111], v[36:37], v[112:113]
	v_pk_mul_f32 v[108:109], v[40:41], v[108:109]
	v_cvt_pk_bf16_f32 v110, v110, v111
	v_cvt_pk_bf16_f32 v111, v114, v115
	ds_read_b128 v[112:115], v212
	ds_read_b128 v[226:229], v213
	v_cvt_pk_bf16_f32 v108, v108, v109
	v_cvt_pk_bf16_f32 v109, v0, v1
	v_mfma_f32_16x16x32_bf16 v[84:87], v[104:107], v[84:87], v[96:99]
	s_waitcnt lgkmcnt(1)
	v_pk_mul_f32 v[0:1], v[34:35], v[114:115]
	s_waitcnt lgkmcnt(0)
	v_pk_mul_f32 v[228:229], v[30:31], v[228:229]
	v_pk_mul_f32 v[114:115], v[28:29], v[226:227]
	v_mfma_f32_16x16x32_bf16 v[80:83], v[116:119], v[80:83], v[88:91]
	v_cvt_pk_bf16_f32 v114, v114, v115
	v_cvt_pk_bf16_f32 v115, v228, v229
	ds_read_b128 v[226:229], v214
	ds_read_b64_tr_b16 v[232:233], v198 offset:57600
	ds_read_b64_tr_b16 v[230:231], v198 offset:53248
	ds_read_b64_tr_b16 v[234:235], v198 offset:53280
	v_pk_mul_f32 v[112:113], v[32:33], v[112:113]
	s_waitcnt lgkmcnt(3)
	v_pk_mul_f32 v[58:59], v[58:59], v[228:229]
	v_pk_mul_f32 v[56:57], v[56:57], v[226:227]
	ds_read_b128 v[226:229], v215
	ds_read_b64_tr_b16 v[236:237], v198 offset:57632
	s_waitcnt lgkmcnt(3)
	v_mfma_f32_16x16x32_bf16 v[56:59], v[230:233], v[92:95], v[56:59]
	v_cvt_pk_bf16_f32 v112, v112, v113
	v_cvt_pk_bf16_f32 v113, v0, v1
	s_waitcnt lgkmcnt(1)
	v_pk_mul_f32 v[54:55], v[54:55], v[228:229]
	v_pk_mul_f32 v[52:53], v[52:53], v[226:227]
	ds_read_b128 v[226:229], v216
	ds_read_b64_tr_b16 v[230:231], v198 offset:53312
	ds_read_b64_tr_b16 v[232:233], v198 offset:57664
	v_mfma_f32_16x16x32_bf16 v[76:79], v[116:119], v[76:79], v[84:87]
	v_add_u32_e32 v0, 32, v190
	s_waitcnt lgkmcnt(2)
	v_pk_mul_f32 v[50:51], v[50:51], v[228:229]
	v_pk_mul_f32 v[48:49], v[48:49], v[226:227]
	v_mfma_f32_16x16x32_bf16 v[72:75], v[108:111], v[72:75], v[80:83]
	v_add_u32_e32 v3, s74, v3
	v_cndmask_b32_e64 v3, v3, v0, s[4:5]
	v_xor_b32_e32 v0, 0xffffffcf, v190
	s_waitcnt lgkmcnt(0)
	v_mfma_f32_16x16x32_bf16 v[48:51], v[230:233], v[92:95], v[48:51]
	ds_read_b128 v[226:229], v217
	ds_read_b64_tr_b16 v[230:231], v198 offset:53344
	ds_read_b64_tr_b16 v[232:233], v198 offset:57696
	v_add_u32_e32 v1, 48, v190
	v_add_u32_e32 v0, s74, v0
	s_waitcnt lgkmcnt(2)
	v_pk_mul_f32 v[46:47], v[46:47], v[228:229]
	v_pk_mul_f32 v[44:45], v[44:45], v[226:227]
	v_mfma_f32_16x16x32_bf16 v[68:71], v[108:111], v[68:71], v[76:79]
	v_add_u32_e32 v190, 64, v190
	s_waitcnt lgkmcnt(0)
	v_mfma_f32_16x16x32_bf16 v[44:47], v[230:233], v[92:95], v[44:47]
	ds_read_b128 v[226:229], v218
	ds_read_b64_tr_b16 v[230:231], v198 offset:53376
	ds_read_b64_tr_b16 v[232:233], v198 offset:57728
	s_waitcnt lgkmcnt(2)
	v_pk_mul_f32 v[42:43], v[42:43], v[228:229]
	v_pk_mul_f32 v[40:41], v[40:41], v[226:227]
	v_mfma_f32_16x16x32_bf16 v[60:63], v[112:115], v[60:63], v[72:75]
	s_waitcnt lgkmcnt(0)
	v_mfma_f32_16x16x32_bf16 v[40:43], v[230:233], v[92:95], v[40:43]
	ds_read_b128 v[226:229], v219
	ds_read_b64_tr_b16 v[230:231], v198 offset:53408
	ds_read_b64_tr_b16 v[232:233], v198 offset:57760
	s_waitcnt lgkmcnt(2)
	v_pk_mul_f32 v[38:39], v[38:39], v[228:229]
	v_pk_mul_f32 v[36:37], v[36:37], v[226:227]
	v_mfma_f32_16x16x32_bf16 v[64:67], v[112:115], v[64:67], v[68:71]
	s_waitcnt lgkmcnt(0)
	v_mfma_f32_16x16x32_bf16 v[36:39], v[230:233], v[92:95], v[36:39]
	ds_read_b128 v[226:229], v220
	ds_read_b64_tr_b16 v[230:231], v198 offset:53440
	ds_read_b64_tr_b16 v[232:233], v198 offset:57792
	v_cndmask_b32_e64 v68, v0, v1, s[4:5]
	v_cvt_pk_bf16_f32 v1, v62, v63
	s_waitcnt lgkmcnt(2)
	v_pk_mul_f32 v[34:35], v[34:35], v[228:229]
	v_pk_mul_f32 v[32:33], v[32:33], v[226:227]
	v_add_u32_e32 v62, s73, v3
	v_ashrrev_i32_e32 v63, 31, v62
	s_waitcnt lgkmcnt(0)
	v_mfma_f32_16x16x32_bf16 v[32:35], v[230:233], v[92:95], v[32:35]
	ds_read_b128 v[226:229], v221
	ds_read_b64_tr_b16 v[230:231], v198 offset:53472
	ds_read_b64_tr_b16 v[232:233], v198 offset:57824
	v_lshlrev_b64 v[62:63], 11, v[62:63]
	v_cvt_pk_bf16_f32 v0, v60, v61
	s_waitcnt lgkmcnt(2)
	v_pk_mul_f32 v[30:31], v[30:31], v[228:229]
	v_pk_mul_f32 v[28:29], v[28:29], v[226:227]
	v_lshl_add_u64 v[62:63], v[186:187], 0, v[62:63]
	v_mfma_f32_16x16x32_bf16 v[52:55], v[234:237], v[92:95], v[52:55]
	global_store_dwordx2 v[62:63], v[0:1], off sc1
	v_add_u32_e32 v0, s73, v68
	v_ashrrev_i32_e32 v1, 31, v0
	s_waitcnt lgkmcnt(0)
	v_mfma_f32_16x16x32_bf16 v[28:31], v[230:233], v[92:95], v[28:31]
	v_lshlrev_b64 v[0:1], 11, v[0:1]
	v_cvt_pk_bf16_f32 v60, v64, v65
	v_cvt_pk_bf16_f32 v61, v66, v67
	v_lshl_add_u64 v[0:1], v[186:187], 0, v[0:1]
	global_store_dwordx2 v[0:1], v[60:61], off sc1
	s_cbranch_scc1 .LBB0_862

.LBB0_859:
	s_or_b64 exec, exec, s[96:97]
	s_add_i32 s78, s77, -1
	s_min_i32 s16, s78, s3
	s_lshl_b32 s16, s16, 5
	v_or_b32_e32 v0, s16, v191
	v_xad_u32 v1, v0, -1, s74
	v_cndmask_b32_e64 v0, v1, v0, s[4:5]
	v_add_u32_e32 v1, s16, v192
	v_xad_u32 v3, v1, -1, s74
	v_add_u32_e32 v0, s73, v0
	v_cndmask_b32_e64 v3, v3, v1, s[4:5]
	v_ashrrev_i32_e32 v1, 31, v0
	s_waitcnt vmcnt(7)
	ds_write_b128 v197, v[8:11] offset:26112
	v_mad_i64_i32 v[8:9], s[16:17], v0, s89, v[180:181]
	v_lshlrev_b64 v[0:1], 11, v[0:1]
	v_lshl_add_u64 v[0:1], v[182:183], 0, v[0:1]
	global_load_dwordx4 v[16:19], v[8:9], off
	global_load_dwordx4 v[24:27], v[0:1], off
	v_add_u32_e32 v0, s73, v3
	v_mad_i64_i32 v[0:1], s[16:17], v0, s89, v[184:185]
	global_load_dwordx4 v[8:11], v[0:1], off
	v_add_u32_e32 v0, 0x1000, v200
	v_add_u32_e32 v1, 0x3000, v201
	s_waitcnt lgkmcnt(0)
	s_barrier
	ds_read_b64_tr_b16 v[92:93], v199 offset:26112
	ds_read_b64_tr_b16 v[94:95], v199 offset:30464
	ds_read_b64 v[88:89], v200
	ds_read_b64 v[90:91], v200 offset:32
	ds_read_b64 v[80:81], v200 offset:64
	ds_read_b64 v[82:83], v200 offset:96
	ds_read_b64 v[72:73], v200 offset:128
	ds_read_b64 v[74:75], v200 offset:160
	ds_read_b64 v[60:61], v200 offset:192
	ds_read_b64 v[62:63], v200 offset:224
	ds_read_b64 v[84:85], v0 offset:256
	ds_read_b64 v[86:87], v0 offset:288
	ds_read_b64 v[76:77], v0 offset:320
	ds_read_b64 v[78:79], v0 offset:352
	ds_read_b64 v[68:69], v0 offset:384
	ds_read_b64 v[70:71], v0 offset:416
	ds_read_b64 v[64:65], v0 offset:448
	ds_read_b64 v[66:67], v0 offset:480
	ds_read_b64 v[100:101], v1 offset:768
	ds_read_b64 v[102:103], v1 offset:800
	v_add_u32_e32 v0, 0x2000, v201
	ds_read_b64 v[96:97], v0 offset:512
	ds_read_b64 v[98:99], v0 offset:544
	ds_read_b64 v[108:109], v0 offset:576
	ds_read_b64 v[110:111], v0 offset:608
	ds_read_b64 v[112:113], v1 offset:832
	ds_read_b64 v[114:115], v1 offset:864
	s_waitcnt lgkmcnt(6)
	v_mfma_f32_16x16x32_bf16 v[100:103], v[100:103], v[84:87], 0
	s_waitcnt lgkmcnt(4)
	v_mfma_f32_16x16x32_bf16 v[104:107], v[96:99], v[88:91], 0
	s_waitcnt lgkmcnt(0)
	v_mfma_f32_16x16x32_bf16 v[100:103], v[112:115], v[76:79], v[100:103]
	ds_read_b64 v[112:113], v0 offset:640
	ds_read_b64 v[114:115], v0 offset:672
	ds_read_b64 v[116:117], v1 offset:896
	ds_read_b64 v[118:119], v1 offset:928
	v_mfma_f32_16x16x32_bf16 v[104:107], v[108:111], v[80:83], v[104:107]
	s_waitcnt lgkmcnt(0)
	v_mfma_f32_16x16x32_bf16 v[100:103], v[116:119], v[68:71], v[100:103]
	ds_read_b64 v[116:117], v0 offset:704
	ds_read_b64 v[118:119], v0 offset:736
	ds_read_b64 v[226:227], v1 offset:960
	ds_read_b64 v[228:229], v1 offset:992
	v_mov_b32_e32 v0, s93
	v_mfma_f32_16x16x32_bf16 v[96:99], v[96:99], v[84:87], 0
	v_mfma_f32_16x16x32_bf16 v[104:107], v[112:115], v[72:75], v[104:107]
	v_mfma_f32_16x16x32_bf16 v[96:99], v[108:111], v[76:79], v[96:99]
	s_waitcnt lgkmcnt(2)
	v_mfma_f32_16x16x32_bf16 v[104:107], v[116:119], v[60:63], v[104:107]
	s_waitcnt lgkmcnt(0)
	v_mfma_f32_16x16x32_bf16 v[100:103], v[226:229], v[64:67], v[100:103]
	v_mov_b32_e32 v226, s93
	s_nop 4
	v_cndmask_b32_e64 v0, v104, v0, s[8:9]
	v_cndmask_b32_e64 v0, v0, v104, s[10:11]
	v_mfma_f32_16x16x32_bf16 v[96:99], v[112:115], v[68:71], v[96:99]
	v_cndmask_b32_e64 v3, v106, 0, s[12:13]
	v_cndmask_b32_e64 v1, v100, v226, s[8:9]
	v_cndmask_b32_e64 v100, v1, v100, s[10:11]
	v_cndmask_b32_e64 v1, 0, v105, s[10:11]
	v_cndmask_b32_e64 v104, v107, 0, s[14:15]
	v_cvt_pk_bf16_f32 v0, v0, v1
	v_cvt_pk_bf16_f32 v1, v3, v104
	ds_read_b128 v[104:107], v202 offset:35328
	ds_read_b128 v[108:111], v202 offset:35392
	v_mfma_f32_16x16x32_bf16 v[96:99], v[116:119], v[64:67], v[96:99]
	v_cndmask_b32_e64 v101, 0, v101, s[10:11]
	v_cndmask_b32_e64 v102, v102, 0, s[12:13]
	v_cndmask_b32_e64 v103, v103, 0, s[14:15]
	v_mov_b32_e32 v3, v2
	s_waitcnt lgkmcnt(0)
	v_pk_mul_f32 v[110:111], v[54:55], v[110:111]
	s_nop 1
	v_cvt_pk_bf16_f32 v96, v96, v97
	v_cvt_pk_bf16_f32 v97, v98, v99
	v_cvt_pk_bf16_f32 v98, v100, v101
	v_cvt_pk_bf16_f32 v99, v102, v103
	v_mfma_f32_16x16x32_bf16 v[100:103], v[92:95], v[0:3], 0
	v_mul_f32_e64 v0, v58, v106
	v_mul_f32_e64 v1, v59, v107
	v_pk_mul_f32 v[106:107], v[52:53], v[108:109]
	v_pk_mul_f32 v[104:105], v[56:57], v[104:105]
	v_cvt_pk_bf16_f32 v106, v106, v107
	v_cvt_pk_bf16_f32 v107, v110, v111
	ds_read_b128 v[108:111], v202 offset:35456
	ds_read_b128 v[112:115], v202 offset:35520
	v_cvt_pk_bf16_f32 v104, v104, v105
	v_cvt_pk_bf16_f32 v105, v0, v1
	v_mfma_f32_16x16x32_bf16 v[96:99], v[92:95], v[96:99], 0
	s_waitcnt lgkmcnt(1)
	v_pk_mul_f32 v[0:1], v[50:51], v[110:111]
	v_pk_mul_f32 v[108:109], v[48:49], v[108:109]
	s_waitcnt lgkmcnt(0)
	v_pk_mul_f32 v[110:111], v[46:47], v[114:115]
	v_pk_mul_f32 v[112:113], v[44:45], v[112:113]
	v_cvt_pk_bf16_f32 v116, v108, v109
	v_cvt_pk_bf16_f32 v118, v112, v113
	v_cvt_pk_bf16_f32 v119, v110, v111
	ds_read_b128 v[108:111], v202 offset:35584
	ds_read_b128 v[112:115], v202 offset:35648
	v_cvt_pk_bf16_f32 v117, v0, v1
	v_mfma_f32_16x16x32_bf16 v[88:91], v[104:107], v[88:91], v[100:103]
	v_cndmask_b32_e64 v3, v222, v190, s[4:5]
	s_waitcnt lgkmcnt(1)
	v_pk_mul_f32 v[0:1], v[42:43], v[110:111]
	s_waitcnt lgkmcnt(0)
	v_pk_mul_f32 v[114:115], v[38:39], v[114:115]
	v_pk_mul_f32 v[110:111], v[36:37], v[112:113]
	v_pk_mul_f32 v[108:109], v[40:41], v[108:109]
	v_cvt_pk_bf16_f32 v110, v110, v111
	v_cvt_pk_bf16_f32 v111, v114, v115
	ds_read_b128 v[112:115], v202 offset:35712
	ds_read_b128 v[226:229], v202 offset:35776
	v_cvt_pk_bf16_f32 v108, v108, v109
	v_cvt_pk_bf16_f32 v109, v0, v1
	v_mfma_f32_16x16x32_bf16 v[84:87], v[104:107], v[84:87], v[96:99]
	s_waitcnt lgkmcnt(1)
	v_pk_mul_f32 v[0:1], v[34:35], v[114:115]
	s_waitcnt lgkmcnt(0)
	v_pk_mul_f32 v[228:229], v[30:31], v[228:229]
	v_pk_mul_f32 v[114:115], v[28:29], v[226:227]
	v_mfma_f32_16x16x32_bf16 v[80:83], v[116:119], v[80:83], v[88:91]
	v_cvt_pk_bf16_f32 v114, v114, v115
	v_cvt_pk_bf16_f32 v115, v228, v229
	ds_read_b128 v[226:229], v202 offset:34816
	ds_read_b64_tr_b16 v[232:233], v198 offset:21760
	ds_read_b64_tr_b16 v[230:231], v198 offset:17408
	ds_read_b64_tr_b16 v[234:235], v198 offset:17440
	v_pk_mul_f32 v[112:113], v[32:33], v[112:113]
	s_waitcnt lgkmcnt(3)
	v_pk_mul_f32 v[58:59], v[58:59], v[228:229]
	v_pk_mul_f32 v[56:57], v[56:57], v[226:227]
	ds_read_b128 v[226:229], v202 offset:34880
	ds_read_b64_tr_b16 v[236:237], v198 offset:21792
	s_waitcnt lgkmcnt(3)
	v_mfma_f32_16x16x32_bf16 v[56:59], v[230:233], v[92:95], v[56:59]
	v_cvt_pk_bf16_f32 v112, v112, v113
	v_cvt_pk_bf16_f32 v113, v0, v1
	s_waitcnt lgkmcnt(1)
	v_pk_mul_f32 v[54:55], v[54:55], v[228:229]
	v_pk_mul_f32 v[52:53], v[52:53], v[226:227]
	ds_read_b128 v[226:229], v202 offset:34944
	ds_read_b64_tr_b16 v[230:231], v198 offset:17472
	ds_read_b64_tr_b16 v[232:233], v198 offset:21824
	v_mfma_f32_16x16x32_bf16 v[76:79], v[116:119], v[76:79], v[84:87]
	v_xor_b32_e32 v1, 0xffffffef, v190
	s_waitcnt lgkmcnt(2)
	v_pk_mul_f32 v[50:51], v[50:51], v[228:229]
	v_pk_mul_f32 v[48:49], v[48:49], v[226:227]
	v_mfma_f32_16x16x32_bf16 v[72:75], v[108:111], v[72:75], v[80:83]
	v_add_u32_e32 v0, 16, v190
	v_add_u32_e32 v1, s74, v1
	s_waitcnt lgkmcnt(0)
	v_mfma_f32_16x16x32_bf16 v[48:51], v[230:233], v[92:95], v[48:51]
	ds_read_b128 v[226:229], v202 offset:35008
	ds_read_b64_tr_b16 v[230:231], v198 offset:17504
	ds_read_b64_tr_b16 v[232:233], v198 offset:21856
	s_waitcnt lgkmcnt(2)
	v_pk_mul_f32 v[46:47], v[46:47], v[228:229]
	v_pk_mul_f32 v[44:45], v[44:45], v[226:227]
	v_mfma_f32_16x16x32_bf16 v[68:71], v[108:111], v[68:71], v[76:79]
	s_waitcnt lgkmcnt(0)
	v_mfma_f32_16x16x32_bf16 v[44:47], v[230:233], v[92:95], v[44:47]
	ds_read_b128 v[226:229], v202 offset:35072
	ds_read_b64_tr_b16 v[230:231], v198 offset:17536
	ds_read_b64_tr_b16 v[232:233], v198 offset:21888
	s_waitcnt lgkmcnt(2)
	v_pk_mul_f32 v[42:43], v[42:43], v[228:229]
	v_pk_mul_f32 v[40:41], v[40:41], v[226:227]
	v_mfma_f32_16x16x32_bf16 v[60:63], v[112:115], v[60:63], v[72:75]
	s_waitcnt lgkmcnt(0)
	v_mfma_f32_16x16x32_bf16 v[40:43], v[230:233], v[92:95], v[40:43]
	ds_read_b128 v[226:229], v202 offset:35136
	ds_read_b64_tr_b16 v[230:231], v198 offset:17568
	ds_read_b64_tr_b16 v[232:233], v198 offset:21920
	s_waitcnt lgkmcnt(2)
	v_pk_mul_f32 v[38:39], v[38:39], v[228:229]
	v_pk_mul_f32 v[36:37], v[36:37], v[226:227]
	v_mfma_f32_16x16x32_bf16 v[64:67], v[112:115], v[64:67], v[68:71]
	s_waitcnt lgkmcnt(0)
	v_mfma_f32_16x16x32_bf16 v[36:39], v[230:233], v[92:95], v[36:39]
	ds_read_b128 v[226:229], v202 offset:35200
	ds_read_b64_tr_b16 v[230:231], v198 offset:17600
	ds_read_b64_tr_b16 v[232:233], v198 offset:21952
	v_cndmask_b32_e64 v68, v1, v0, s[4:5]
	v_cvt_pk_bf16_f32 v1, v62, v63
	s_waitcnt lgkmcnt(2)
	v_pk_mul_f32 v[34:35], v[34:35], v[228:229]
	v_pk_mul_f32 v[32:33], v[32:33], v[226:227]
	v_add_u32_e32 v62, s73, v3
	v_ashrrev_i32_e32 v63, 31, v62
	s_waitcnt lgkmcnt(0)
	v_mfma_f32_16x16x32_bf16 v[32:35], v[230:233], v[92:95], v[32:35]
	ds_read_b128 v[226:229], v202 offset:35264
	ds_read_b64_tr_b16 v[230:231], v198 offset:17632
	ds_read_b64_tr_b16 v[232:233], v198 offset:21984
	v_lshlrev_b64 v[62:63], 11, v[62:63]
	v_cvt_pk_bf16_f32 v0, v60, v61
	s_waitcnt lgkmcnt(2)
	v_pk_mul_f32 v[30:31], v[30:31], v[228:229]
	v_pk_mul_f32 v[28:29], v[28:29], v[226:227]
	v_lshl_add_u64 v[62:63], v[186:187], 0, v[62:63]
	v_mfma_f32_16x16x32_bf16 v[52:55], v[234:237], v[92:95], v[52:55]
	global_store_dwordx2 v[62:63], v[0:1], off sc1
	v_add_u32_e32 v0, s73, v68
	v_ashrrev_i32_e32 v1, 31, v0
	s_waitcnt lgkmcnt(0)
	v_mfma_f32_16x16x32_bf16 v[28:31], v[230:233], v[92:95], v[28:31]
	v_lshlrev_b64 v[0:1], 11, v[0:1]
	v_cvt_pk_bf16_f32 v60, v64, v65
	v_cvt_pk_bf16_f32 v61, v66, v67
	v_lshl_add_u64 v[0:1], v[186:187], 0, v[0:1]
	global_store_dwordx2 v[0:1], v[60:61], off sc1
	s_and_saveexec_b64 s[96:97], vcc
	s_cbranch_execz .LBB0_854
	s_waitcnt vmcnt(8)
	v_cvt_f32_f16_e32 v76, v20
	v_cvt_f32_f16_sdwa v75, v20 dst_sel:DWORD dst_unused:UNUSED_PAD src0_sel:WORD_1
	v_cvt_f32_f16_e32 v74, v21
	v_cvt_f32_f16_sdwa v73, v21 dst_sel:DWORD dst_unused:UNUSED_PAD src0_sel:WORD_1
	v_add_f32_dpp v0, v76, v76 row_shr:1 row_mask:0xf bank_mask:0xf bound_ctrl:1
	v_add_f32_dpp v1, v75, v75 row_shr:1 row_mask:0xf bank_mask:0xf bound_ctrl:1
	v_mov_b32_e32 v62, v2
	v_add_f32_dpp v0, v0, v0 row_shr:2 row_mask:0xf bank_mask:0xf bound_ctrl:1
	v_add_f32_dpp v1, v1, v1 row_shr:2 row_mask:0xf bank_mask:0xf bound_ctrl:1
	v_cvt_f32_f16_e32 v72, v22
	v_add_f32_dpp v0, v0, v0 row_shr:4 row_mask:0xf bank_mask:0xf bound_ctrl:1
	v_add_f32_dpp v20, v74, v74 row_shr:1 row_mask:0xf bank_mask:0xf bound_ctrl:1
	v_add_f32_dpp v1, v1, v1 row_shr:4 row_mask:0xf bank_mask:0xf bound_ctrl:1
	v_add_f32_dpp v0, v0, v0 row_shr:8 row_mask:0xf bank_mask:0xf bound_ctrl:1
	v_add_f32_dpp v20, v20, v20 row_shr:2 row_mask:0xf bank_mask:0xf bound_ctrl:1
	v_add_f32_dpp v1, v1, v1 row_shr:8 row_mask:0xf bank_mask:0xf bound_ctrl:1
	v_mov_b32_dpp v62, v0 row_bcast:15 row_mask:0xa bank_mask:0xf
	v_add_f32_e32 v78, v0, v62
	v_mov_b32_e32 v0, v2
	v_cvt_f32_f16_sdwa v71, v22 dst_sel:DWORD dst_unused:UNUSED_PAD src0_sel:WORD_1
	v_add_f32_dpp v21, v73, v73 row_shr:1 row_mask:0xf bank_mask:0xf bound_ctrl:1
	v_add_f32_dpp v20, v20, v20 row_shr:4 row_mask:0xf bank_mask:0xf bound_ctrl:1
	v_mov_b32_dpp v0, v1 row_bcast:15 row_mask:0xa bank_mask:0xf
	v_add_f32_dpp v21, v21, v21 row_shr:2 row_mask:0xf bank_mask:0xf bound_ctrl:1
	v_add_f32_dpp v20, v20, v20 row_shr:8 row_mask:0xf bank_mask:0xf bound_ctrl:1
	v_add_f32_e32 v79, v1, v0
	v_mov_b32_e32 v0, v2
	v_cvt_f32_f16_e32 v70, v23
	v_add_f32_dpp v22, v72, v72 row_shr:1 row_mask:0xf bank_mask:0xf bound_ctrl:1
	v_add_f32_dpp v21, v21, v21 row_shr:4 row_mask:0xf bank_mask:0xf bound_ctrl:1
	v_mov_b32_dpp v0, v20 row_bcast:15 row_mask:0xa bank_mask:0xf
	v_add_f32_dpp v22, v22, v22 row_shr:2 row_mask:0xf bank_mask:0xf bound_ctrl:1
	v_add_f32_dpp v21, v21, v21 row_shr:8 row_mask:0xf bank_mask:0xf bound_ctrl:1
	v_add_f32_e32 v80, v20, v0
	v_mov_b32_e32 v0, v2
	v_cvt_f32_f16_sdwa v3, v23 dst_sel:DWORD dst_unused:UNUSED_PAD src0_sel:WORD_1
	v_add_f32_dpp v23, v71, v71 row_shr:1 row_mask:0xf bank_mask:0xf bound_ctrl:1
	v_add_f32_dpp v22, v22, v22 row_shr:4 row_mask:0xf bank_mask:0xf bound_ctrl:1
	v_mov_b32_dpp v0, v21 row_bcast:15 row_mask:0xa bank_mask:0xf
	v_add_f32_dpp v23, v23, v23 row_shr:2 row_mask:0xf bank_mask:0xf bound_ctrl:1
	v_add_f32_dpp v22, v22, v22 row_shr:8 row_mask:0xf bank_mask:0xf bound_ctrl:1
	v_add_f32_e32 v81, v21, v0
	v_mov_b32_e32 v0, v2
	v_add_f32_dpp v60, v70, v70 row_shr:1 row_mask:0xf bank_mask:0xf bound_ctrl:1
	v_add_f32_dpp v23, v23, v23 row_shr:4 row_mask:0xf bank_mask:0xf bound_ctrl:1
	v_mov_b32_dpp v0, v22 row_bcast:15 row_mask:0xa bank_mask:0xf
	ds_bpermute_b32 v1, v193, v78
	v_add_f32_dpp v60, v60, v60 row_shr:2 row_mask:0xf bank_mask:0xf bound_ctrl:1
	v_add_f32_dpp v23, v23, v23 row_shr:8 row_mask:0xf bank_mask:0xf bound_ctrl:1
	v_add_f32_e32 v77, v22, v0
	v_mov_b32_e32 v0, v2
	v_add_f32_dpp v60, v60, v60 row_shr:4 row_mask:0xf bank_mask:0xf bound_ctrl:1
	v_add_f32_dpp v61, v3, v3 row_shr:1 row_mask:0xf bank_mask:0xf bound_ctrl:1
	v_mov_b32_dpp v0, v23 row_bcast:15 row_mask:0xa bank_mask:0xf
	v_add_f32_dpp v60, v60, v60 row_shr:8 row_mask:0xf bank_mask:0xf bound_ctrl:1
	v_add_f32_e32 v82, v23, v0
	v_mov_b32_e32 v0, v2
	v_add_f32_dpp v61, v61, v61 row_shr:2 row_mask:0xf bank_mask:0xf bound_ctrl:1
	ds_bpermute_b32 v22, v193, v80
	v_mov_b32_dpp v0, v60 row_bcast:15 row_mask:0xa bank_mask:0xf
	v_add_f32_e32 v83, v60, v0
	s_waitcnt lgkmcnt(1)
	v_sub_f32_e32 v0, v78, v1
	ds_bpermute_b32 v1, v193, v79
	v_med3_f32 v0, v0, s69, v189
	v_add_f32_dpp v61, v61, v61 row_shr:4 row_mask:0xf bank_mask:0xf bound_ctrl:1
	v_mul_f32_e32 v0, 0x3fb8aa3b, v0
	v_exp_f32_e32 v20, v0
	v_add_f32_dpp v61, v61, v61 row_shr:8 row_mask:0xf bank_mask:0xf bound_ctrl:1
	v_mov_b32_e32 v0, v2
	s_waitcnt lgkmcnt(0)
	v_sub_f32_e32 v1, v79, v1
	v_med3_f32 v1, v1, s69, v189
	v_mov_b32_dpp v0, v61 row_bcast:15 row_mask:0xa bank_mask:0xf
	v_add_f32_e32 v84, v61, v0
	v_mul_f32_e32 v1, 0x3fb8aa3b, v1
	v_exp_f32_e32 v21, v1
	ds_bpermute_b32 v1, v193, v81
	ds_bpermute_b32 v62, v193, v77
	ds_bpermute_b32 v63, v193, v82
	ds_bpermute_b32 v64, v193, v83
	ds_bpermute_b32 v65, v193, v84
	v_sub_f32_e32 v22, v80, v22
	s_waitcnt lgkmcnt(4)
	v_sub_f32_e32 v1, v81, v1
	s_waitcnt lgkmcnt(3)
	v_sub_f32_e32 v62, v77, v62
	s_waitcnt lgkmcnt(2)
	v_sub_f32_e32 v63, v82, v63
	s_waitcnt lgkmcnt(1)
	v_sub_f32_e32 v64, v83, v64
	s_waitcnt lgkmcnt(0)
	v_sub_f32_e32 v65, v84, v65
	v_med3_f32 v22, v22, s69, v189
	v_med3_f32 v1, v1, s69, v189
	v_med3_f32 v62, v62, s69, v189
	v_med3_f32 v63, v63, s69, v189
	v_med3_f32 v64, v64, s69, v189
	v_med3_f32 v65, v65, s69, v189
	v_mul_f32_e32 v22, 0x3fb8aa3b, v22
	v_mul_f32_e32 v1, 0x3fb8aa3b, v1
	v_mul_f32_e32 v62, 0x3fb8aa3b, v62
	v_mul_f32_e32 v63, 0x3fb8aa3b, v63
	v_mul_f32_e32 v64, 0x3fb8aa3b, v64
	v_mul_f32_e32 v65, 0x3fb8aa3b, v65
	v_exp_f32_e32 v60, v22
	v_exp_f32_e32 v61, v1
	v_exp_f32_e32 v62, v62
	v_exp_f32_e32 v63, v63
	v_exp_f32_e32 v64, v64
	v_exp_f32_e32 v65, v65
	ds_bpermute_b32 v0, v194, v20
	ds_bpermute_b32 v1, v194, v21
	ds_bpermute_b32 v22, v194, v60
	ds_bpermute_b32 v23, v194, v61
	ds_bpermute_b32 v68, v194, v62
	ds_bpermute_b32 v69, v194, v63
	ds_bpermute_b32 v66, v194, v64
	ds_bpermute_b32 v67, v194, v65
	s_and_saveexec_b64 s[16:17], s[6:7]
	s_cbranch_execz .LBB0_853
	v_mul_f32_e32 v78, 0x3fb8aa3b, v78
	v_mul_f32_e32 v79, 0x3fb8aa3b, v79
	v_mul_f32_e32 v80, 0x3fb8aa3b, v80
	v_mul_f32_e32 v81, 0x3fb8aa3b, v81
	v_exp_f32_e32 v78, v78
	v_exp_f32_e32 v79, v79
	v_exp_f32_e32 v80, v80
	v_exp_f32_e32 v81, v81
	v_mul_f32_e32 v77, 0x3fb8aa3b, v77
	ds_write_b128 v203, v[78:81]
	v_exp_f32_e32 v78, v77
	v_mul_f32_e32 v77, 0x3fb8aa3b, v82
	v_exp_f32_e32 v79, v77
	v_mul_f32_e32 v77, 0x3fb8aa3b, v83
	v_exp_f32_e32 v80, v77
	v_mul_f32_e32 v77, 0x3fb8aa3b, v84
	v_exp_f32_e32 v81, v77
	ds_write_b128 v203, v[78:81] offset:16
	s_branch .LBB0_853

.LBB0_868:
	s_or_b64 exec, exec, s[80:81]
	s_min_i32 s16, s35, s77
	s_lshl_b32 s16, s16, 5
	v_or_b32_e32 v0, s16, v127
	v_xad_u32 v1, v0, -1, s74
	v_cndmask_b32_e64 v0, v1, v0, s[4:5]
	v_add_u32_e32 v1, s16, v128
	v_xad_u32 v3, v1, -1, s74
	v_add_u32_e32 v0, s73, v0
	s_waitcnt vmcnt(8)
	ds_write_b128 v133, v[4:7] offset:61952
	v_cndmask_b32_e64 v3, v3, v1, s[4:5]
	v_ashrrev_i32_e32 v1, 31, v0
	v_mad_i64_i32 v[4:5], s[16:17], v0, s89, v[116:117]
	global_load_dwordx4 v[20:23], v[4:5], off
	v_lshlrev_b64 v[4:5], 10, v[0:1]
	v_lshl_add_u64 v[4:5], v[118:119], 0, v[4:5]
	v_mad_i64_i32 v[0:1], s[16:17], v0, s89, v[120:121]
	global_load_dwordx4 v[28:31], v[4:5], off
	global_load_dwordx4 v[12:15], v[0:1], off
	v_add_u32_e32 v0, s73, v3
	v_mad_i64_i32 v[0:1], s[16:17], v0, s89, v[122:123]
	global_load_dwordx4 v[4:7], v[0:1], off
	v_add_u32_e32 v0, 0x8800, v135
	s_waitcnt lgkmcnt(0)
	s_barrier
	ds_read_b64_tr_b16 v[68:69], v140
	ds_read_b64_tr_b16 v[70:71], v140 offset:4352
	ds_read_b64 v[64:65], v0 offset:1024
	ds_read_b64 v[66:67], v0 offset:1056
	ds_read_b64 v[52:53], v0 offset:1088
	ds_read_b64 v[54:55], v0 offset:1120
	v_add_u32_e32 v0, 0x9000, v135
	ds_read_b64 v[60:61], v0 offset:1280
	ds_read_b64 v[62:63], v0 offset:1312
	ds_read_b64 v[56:57], v0 offset:1344
	ds_read_b64 v[58:59], v0 offset:1376
	v_add_u32_e32 v0, 0xa800, v136
	v_add_u32_e32 v1, 0xb000, v136
	ds_read_b64 v[72:73], v0 offset:1536
	ds_read_b64 v[74:75], v0 offset:1568
	ds_read_b64 v[76:77], v1 offset:1792
	ds_read_b64 v[78:79], v1 offset:1824
	ds_read_b64 v[84:85], v0 offset:1600
	ds_read_b64 v[86:87], v0 offset:1632
	ds_read_b64 v[150:151], v1 offset:1856
	ds_read_b64 v[152:153], v1 offset:1888
	s_waitcnt lgkmcnt(6)
	v_mfma_f32_16x16x32_bf16 v[80:83], v[72:75], v[64:67], 0
	v_mov_b32_e32 v0, s93
	s_add_i32 s35, s35, 2
	v_subrev_u32_e32 v149, 64, v149
	s_waitcnt lgkmcnt(4)
	v_mfma_f32_16x16x32_bf16 v[76:79], v[76:79], v[60:63], 0
	s_cmp_ge_u32 s78, s3
	s_waitcnt lgkmcnt(2)
	v_mfma_f32_16x16x32_bf16 v[80:83], v[84:87], v[52:55], v[80:83]
	s_waitcnt lgkmcnt(0)
	v_mfma_f32_16x16x32_bf16 v[76:79], v[150:153], v[56:59], v[76:79]
	v_mov_b32_e32 v150, s93
	s_nop 4
	v_cndmask_b32_e64 v0, v80, v0, s[8:9]
	v_cndmask_b32_e64 v0, v0, v80, s[10:11]
	v_mfma_f32_16x16x32_bf16 v[72:75], v[72:75], v[60:63], 0
	v_cndmask_b32_e64 v3, v82, 0, s[12:13]
	v_cndmask_b32_e64 v1, v76, v150, s[8:9]
	v_cndmask_b32_e64 v76, v1, v76, s[10:11]
	v_cndmask_b32_e64 v1, 0, v81, s[10:11]
	v_cndmask_b32_e64 v80, v83, 0, s[14:15]
	v_mfma_f32_16x16x32_bf16 v[72:75], v[84:87], v[56:59], v[72:75]
	v_cvt_pk_bf16_f32 v0, v0, v1
	v_cvt_pk_bf16_f32 v1, v3, v80
	ds_read_b128 v[80:83], v141
	ds_read_b128 v[84:87], v142
	v_cndmask_b32_e64 v77, 0, v77, s[10:11]
	v_cndmask_b32_e64 v78, v78, 0, s[12:13]
	v_cndmask_b32_e64 v79, v79, 0, s[14:15]
	v_mov_b32_e32 v3, v2
	v_cvt_pk_bf16_f32 v72, v72, v73
	v_cvt_pk_bf16_f32 v73, v74, v75
	v_cvt_pk_bf16_f32 v74, v76, v77
	v_cvt_pk_bf16_f32 v75, v78, v79
	v_mfma_f32_16x16x32_bf16 v[76:79], v[68:71], v[0:3], 0
	s_waitcnt lgkmcnt(1)
	v_pk_mul_f32 v[0:1], v[50:51], v[82:83]
	s_waitcnt lgkmcnt(0)
	v_pk_mul_f32 v[86:87], v[46:47], v[86:87]
	v_pk_mul_f32 v[82:83], v[44:45], v[84:85]
	v_pk_mul_f32 v[80:81], v[48:49], v[80:81]
	v_cvt_pk_bf16_f32 v82, v82, v83
	v_cvt_pk_bf16_f32 v83, v86, v87
	ds_read_b128 v[84:87], v143
	ds_read_b128 v[150:153], v144
	v_cvt_pk_bf16_f32 v80, v80, v81
	v_cvt_pk_bf16_f32 v81, v0, v1
	v_mfma_f32_16x16x32_bf16 v[72:75], v[68:71], v[72:75], 0
	s_waitcnt lgkmcnt(1)
	v_pk_mul_f32 v[0:1], v[42:43], v[86:87]
	s_waitcnt lgkmcnt(0)
	v_pk_mul_f32 v[152:153], v[38:39], v[152:153]
	v_pk_mul_f32 v[86:87], v[36:37], v[150:151]
	v_pk_mul_f32 v[84:85], v[40:41], v[84:85]
	v_cvt_pk_bf16_f32 v86, v86, v87
	v_cvt_pk_bf16_f32 v87, v152, v153
	ds_read_b128 v[150:153], v145
	ds_read_b64_tr_b16 v[156:157], v138 offset:55552
	ds_read_b64_tr_b16 v[154:155], v138 offset:53248
	ds_read_b64_tr_b16 v[158:159], v138 offset:53280
	v_cvt_pk_bf16_f32 v84, v84, v85
	s_waitcnt lgkmcnt(3)
	v_pk_mul_f32 v[50:51], v[50:51], v[152:153]
	v_pk_mul_f32 v[48:49], v[48:49], v[150:151]
	ds_read_b128 v[150:153], v146
	ds_read_b64_tr_b16 v[160:161], v138 offset:55584
	v_cvt_pk_bf16_f32 v85, v0, v1
	v_mfma_f32_16x16x32_bf16 v[64:67], v[80:83], v[64:67], v[76:79]
	v_xor_b32_e32 v3, 0xffffffdf, v126
	s_waitcnt lgkmcnt(1)
	v_pk_mul_f32 v[46:47], v[46:47], v[152:153]
	v_pk_mul_f32 v[44:45], v[44:45], v[150:151]
	v_mfma_f32_16x16x32_bf16 v[48:51], v[154:157], v[68:71], v[48:51]
	ds_read_b128 v[150:153], v147
	ds_read_b64_tr_b16 v[154:155], v138 offset:53312
	ds_read_b64_tr_b16 v[156:157], v138 offset:55616
	v_add_u32_e32 v0, 32, v126
	v_add_u32_e32 v3, s74, v3
	v_mfma_f32_16x16x32_bf16 v[60:63], v[80:83], v[60:63], v[72:75]
	s_waitcnt lgkmcnt(2)
	v_pk_mul_f32 v[42:43], v[42:43], v[152:153]
	v_pk_mul_f32 v[40:41], v[40:41], v[150:151]
	v_cndmask_b32_e64 v3, v3, v0, s[4:5]
	v_mfma_f32_16x16x32_bf16 v[52:55], v[84:87], v[52:55], v[64:67]
	v_xor_b32_e32 v0, 0xffffffcf, v126
	v_add_u32_e32 v1, 48, v126
	v_add_u32_e32 v0, s74, v0
	s_waitcnt lgkmcnt(0)
	v_mfma_f32_16x16x32_bf16 v[40:43], v[154:157], v[68:71], v[40:43]
	ds_read_b128 v[150:153], v148
	ds_read_b64_tr_b16 v[154:155], v138 offset:53344
	ds_read_b64_tr_b16 v[156:157], v138 offset:55648
	v_add_u32_e32 v126, 64, v126
	s_waitcnt lgkmcnt(2)
	v_pk_mul_f32 v[38:39], v[38:39], v[152:153]
	v_mfma_f32_16x16x32_bf16 v[56:59], v[84:87], v[56:59], v[60:63]
	v_mul_f32_e64 v36, v36, v150
	v_mul_f32_e64 v37, v37, v151
	s_nop 0
	v_cndmask_b32_e64 v60, v0, v1, s[4:5]
	v_cvt_pk_bf16_f32 v1, v54, v55
	v_add_u32_e32 v54, s73, v3
	v_ashrrev_i32_e32 v55, 31, v54
	v_lshlrev_b64 v[54:55], 11, v[54:55]
	v_cvt_pk_bf16_f32 v0, v52, v53
	v_lshl_add_u64 v[54:55], v[124:125], 0, v[54:55]
	v_mfma_f32_16x16x32_bf16 v[44:47], v[158:161], v[68:71], v[44:47]
	global_store_dwordx2 v[54:55], v[0:1], off offset:1024 sc1
	v_add_u32_e32 v0, s73, v60
	v_ashrrev_i32_e32 v1, 31, v0
	s_waitcnt lgkmcnt(0)
	v_mfma_f32_16x16x32_bf16 v[36:39], v[154:157], v[68:71], v[36:39]
	v_lshlrev_b64 v[0:1], 11, v[0:1]
	v_cvt_pk_bf16_f32 v52, v56, v57
	v_cvt_pk_bf16_f32 v53, v58, v59
	v_lshl_add_u64 v[0:1], v[124:125], 0, v[0:1]
	global_store_dwordx2 v[0:1], v[52:53], off offset:1024 sc1
	s_cbranch_scc1 .LBB0_876

.LBB0_873:
	s_or_b64 exec, exec, s[80:81]
	s_add_i32 s78, s35, -1
	s_min_i32 s16, s78, s77
	s_lshl_b32 s16, s16, 5
	v_or_b32_e32 v0, s16, v127
	v_xad_u32 v1, v0, -1, s74
	v_cndmask_b32_e64 v0, v1, v0, s[4:5]
	v_add_u32_e32 v1, s16, v128
	v_xad_u32 v3, v1, -1, s74
	v_add_u32_e32 v0, s73, v0
	s_waitcnt vmcnt(8)
	ds_write_b128 v133, v[8:11] offset:26112
	v_cndmask_b32_e64 v3, v3, v1, s[4:5]
	v_ashrrev_i32_e32 v1, 31, v0
	v_mad_i64_i32 v[8:9], s[16:17], v0, s89, v[116:117]
	global_load_dwordx4 v[24:27], v[8:9], off
	v_lshlrev_b64 v[8:9], 10, v[0:1]
	v_lshl_add_u64 v[8:9], v[118:119], 0, v[8:9]
	v_mad_i64_i32 v[0:1], s[16:17], v0, s89, v[120:121]
	global_load_dwordx4 v[32:35], v[8:9], off
	global_load_dwordx4 v[16:19], v[0:1], off
	v_add_u32_e32 v0, s73, v3
	v_mad_i64_i32 v[0:1], s[16:17], v0, s89, v[122:123]
	global_load_dwordx4 v[8:11], v[0:1], off
	v_add_u32_e32 v0, 0x800, v135
	s_waitcnt lgkmcnt(0)
	s_barrier
	ds_read_b64_tr_b16 v[68:69], v134 offset:26112
	ds_read_b64_tr_b16 v[70:71], v134 offset:30464
	ds_read_b64 v[64:65], v135
	ds_read_b64 v[66:67], v135 offset:32
	ds_read_b64 v[52:53], v135 offset:64
	ds_read_b64 v[54:55], v135 offset:96
	ds_read_b64 v[60:61], v0 offset:256
	ds_read_b64 v[62:63], v0 offset:288
	ds_read_b64 v[56:57], v0 offset:320
	ds_read_b64 v[58:59], v0 offset:352
	v_add_u32_e32 v0, 0x2000, v136
	v_add_u32_e32 v1, 0x2800, v136
	ds_read_b64 v[72:73], v0 offset:512
	ds_read_b64 v[74:75], v0 offset:544
	ds_read_b64 v[76:77], v1 offset:768
	ds_read_b64 v[78:79], v1 offset:800
	ds_read_b64 v[84:85], v0 offset:576
	ds_read_b64 v[86:87], v0 offset:608
	ds_read_b64 v[150:151], v1 offset:832
	ds_read_b64 v[152:153], v1 offset:864
	s_waitcnt lgkmcnt(6)
	v_mfma_f32_16x16x32_bf16 v[80:83], v[72:75], v[64:67], 0
	v_mov_b32_e32 v0, s93
	s_waitcnt lgkmcnt(4)
	v_mfma_f32_16x16x32_bf16 v[76:79], v[76:79], v[60:63], 0
	s_waitcnt lgkmcnt(2)
	v_mfma_f32_16x16x32_bf16 v[80:83], v[84:87], v[52:55], v[80:83]
	s_waitcnt lgkmcnt(0)
	v_mfma_f32_16x16x32_bf16 v[76:79], v[150:153], v[56:59], v[76:79]
	v_mov_b32_e32 v150, s93
	s_nop 4
	v_cndmask_b32_e64 v0, v80, v0, s[8:9]
	v_cndmask_b32_e64 v0, v0, v80, s[10:11]
	v_mfma_f32_16x16x32_bf16 v[72:75], v[72:75], v[60:63], 0
	v_cndmask_b32_e64 v3, v82, 0, s[12:13]
	v_cndmask_b32_e64 v1, v76, v150, s[8:9]
	v_cndmask_b32_e64 v76, v1, v76, s[10:11]
	v_cndmask_b32_e64 v1, 0, v81, s[10:11]
	v_cndmask_b32_e64 v80, v83, 0, s[14:15]
	v_mfma_f32_16x16x32_bf16 v[72:75], v[84:87], v[56:59], v[72:75]
	v_cvt_pk_bf16_f32 v0, v0, v1
	v_cvt_pk_bf16_f32 v1, v3, v80
	ds_read_b128 v[80:83], v137 offset:35328
	ds_read_b128 v[84:87], v137 offset:35392
	v_cndmask_b32_e64 v77, 0, v77, s[10:11]
	v_cndmask_b32_e64 v78, v78, 0, s[12:13]
	v_cndmask_b32_e64 v79, v79, 0, s[14:15]
	v_mov_b32_e32 v3, v2
	v_cvt_pk_bf16_f32 v72, v72, v73
	v_cvt_pk_bf16_f32 v73, v74, v75
	v_cvt_pk_bf16_f32 v74, v76, v77
	v_cvt_pk_bf16_f32 v75, v78, v79
	v_mfma_f32_16x16x32_bf16 v[76:79], v[68:71], v[0:3], 0
	s_waitcnt lgkmcnt(1)
	v_pk_mul_f32 v[0:1], v[50:51], v[82:83]
	s_waitcnt lgkmcnt(0)
	v_pk_mul_f32 v[86:87], v[46:47], v[86:87]
	v_pk_mul_f32 v[82:83], v[44:45], v[84:85]
	v_pk_mul_f32 v[80:81], v[48:49], v[80:81]
	v_cvt_pk_bf16_f32 v82, v82, v83
	v_cvt_pk_bf16_f32 v83, v86, v87
	ds_read_b128 v[84:87], v137 offset:35456
	ds_read_b128 v[150:153], v137 offset:35520
	v_cvt_pk_bf16_f32 v80, v80, v81
	v_cvt_pk_bf16_f32 v81, v0, v1
	v_mfma_f32_16x16x32_bf16 v[72:75], v[68:71], v[72:75], 0
	s_waitcnt lgkmcnt(1)
	v_pk_mul_f32 v[0:1], v[42:43], v[86:87]
	s_waitcnt lgkmcnt(0)
	v_pk_mul_f32 v[152:153], v[38:39], v[152:153]
	v_pk_mul_f32 v[86:87], v[36:37], v[150:151]
	v_pk_mul_f32 v[84:85], v[40:41], v[84:85]
	v_cvt_pk_bf16_f32 v86, v86, v87
	v_cvt_pk_bf16_f32 v87, v152, v153
	ds_read_b128 v[150:153], v137 offset:34816
	ds_read_b64_tr_b16 v[156:157], v138 offset:19712
	ds_read_b64_tr_b16 v[154:155], v138 offset:17408
	ds_read_b64_tr_b16 v[158:159], v138 offset:17440
	v_cvt_pk_bf16_f32 v84, v84, v85
	s_waitcnt lgkmcnt(3)
	v_pk_mul_f32 v[50:51], v[50:51], v[152:153]
	v_pk_mul_f32 v[48:49], v[48:49], v[150:151]
	ds_read_b128 v[150:153], v137 offset:34880
	ds_read_b64_tr_b16 v[160:161], v138 offset:19744
	v_cvt_pk_bf16_f32 v85, v0, v1
	v_mfma_f32_16x16x32_bf16 v[64:67], v[80:83], v[64:67], v[76:79]
	v_xor_b32_e32 v1, 0xffffffef, v126
	s_waitcnt lgkmcnt(1)
	v_pk_mul_f32 v[46:47], v[46:47], v[152:153]
	v_pk_mul_f32 v[44:45], v[44:45], v[150:151]
	v_mfma_f32_16x16x32_bf16 v[48:51], v[154:157], v[68:71], v[48:51]
	ds_read_b128 v[150:153], v137 offset:34944
	ds_read_b64_tr_b16 v[154:155], v138 offset:17472
	ds_read_b64_tr_b16 v[156:157], v138 offset:19776
	v_add_u32_e32 v0, 16, v126
	v_cndmask_b32_e64 v3, v149, v126, s[4:5]
	v_mfma_f32_16x16x32_bf16 v[60:63], v[80:83], v[60:63], v[72:75]
	s_waitcnt lgkmcnt(2)
	v_pk_mul_f32 v[42:43], v[42:43], v[152:153]
	v_pk_mul_f32 v[40:41], v[40:41], v[150:151]
	v_add_u32_e32 v1, s74, v1
	v_mfma_f32_16x16x32_bf16 v[52:55], v[84:87], v[52:55], v[64:67]
	s_waitcnt lgkmcnt(0)
	v_mfma_f32_16x16x32_bf16 v[40:43], v[154:157], v[68:71], v[40:43]
	ds_read_b128 v[150:153], v137 offset:35008
	ds_read_b64_tr_b16 v[154:155], v138 offset:17504
	ds_read_b64_tr_b16 v[156:157], v138 offset:19808
	s_waitcnt lgkmcnt(2)
	v_pk_mul_f32 v[38:39], v[38:39], v[152:153]
	v_mfma_f32_16x16x32_bf16 v[56:59], v[84:87], v[56:59], v[60:63]
	v_mul_f32_e64 v36, v36, v150
	v_mul_f32_e64 v37, v37, v151
	s_nop 0
	v_cndmask_b32_e64 v60, v1, v0, s[4:5]
	v_cvt_pk_bf16_f32 v1, v54, v55
	v_add_u32_e32 v54, s73, v3
	v_ashrrev_i32_e32 v55, 31, v54
	v_lshlrev_b64 v[54:55], 11, v[54:55]
	v_cvt_pk_bf16_f32 v0, v52, v53
	v_lshl_add_u64 v[54:55], v[124:125], 0, v[54:55]
	v_mfma_f32_16x16x32_bf16 v[44:47], v[158:161], v[68:71], v[44:47]
	global_store_dwordx2 v[54:55], v[0:1], off offset:1024 sc1
	v_add_u32_e32 v0, s73, v60
	v_ashrrev_i32_e32 v1, 31, v0
	s_waitcnt lgkmcnt(0)
	v_mfma_f32_16x16x32_bf16 v[36:39], v[154:157], v[68:71], v[36:39]
	v_lshlrev_b64 v[0:1], 11, v[0:1]
	v_cvt_pk_bf16_f32 v52, v56, v57
	v_cvt_pk_bf16_f32 v53, v58, v59
	v_lshl_add_u64 v[0:1], v[124:125], 0, v[0:1]
	global_store_dwordx2 v[0:1], v[52:53], off offset:1024 sc1
	s_and_saveexec_b64 s[80:81], vcc
	s_cbranch_execz .LBB0_868
	s_waitcnt vmcnt(10)
	v_cvt_f32_f16_e32 v0, v28
	v_cvt_f32_f16_sdwa v1, v28 dst_sel:DWORD dst_unused:UNUSED_PAD src0_sel:WORD_1
	v_cvt_f32_f16_e32 v3, v29
	v_cvt_f32_f16_sdwa v28, v29 dst_sel:DWORD dst_unused:UNUSED_PAD src0_sel:WORD_1
	v_add_f32_dpp v0, v0, v0 row_shr:1 row_mask:0xf bank_mask:0xf bound_ctrl:1
	v_add_f32_dpp v1, v1, v1 row_shr:1 row_mask:0xf bank_mask:0xf bound_ctrl:1
	v_mov_b32_e32 v53, v2
	v_add_f32_dpp v0, v0, v0 row_shr:2 row_mask:0xf bank_mask:0xf bound_ctrl:1
	v_add_f32_dpp v1, v1, v1 row_shr:2 row_mask:0xf bank_mask:0xf bound_ctrl:1
	v_cvt_f32_f16_e32 v29, v30
	v_add_f32_dpp v0, v0, v0 row_shr:4 row_mask:0xf bank_mask:0xf bound_ctrl:1
	v_add_f32_dpp v3, v3, v3 row_shr:1 row_mask:0xf bank_mask:0xf bound_ctrl:1
	v_add_f32_dpp v1, v1, v1 row_shr:4 row_mask:0xf bank_mask:0xf bound_ctrl:1
	v_add_f32_dpp v0, v0, v0 row_shr:8 row_mask:0xf bank_mask:0xf bound_ctrl:1
	v_add_f32_dpp v3, v3, v3 row_shr:2 row_mask:0xf bank_mask:0xf bound_ctrl:1
	v_add_f32_dpp v1, v1, v1 row_shr:8 row_mask:0xf bank_mask:0xf bound_ctrl:1
	v_mov_b32_dpp v53, v0 row_bcast:15 row_mask:0xa bank_mask:0xf
	v_add_f32_e32 v62, v0, v53
	v_mov_b32_e32 v0, v2
	v_cvt_f32_f16_sdwa v30, v30 dst_sel:DWORD dst_unused:UNUSED_PAD src0_sel:WORD_1
	v_add_f32_dpp v28, v28, v28 row_shr:1 row_mask:0xf bank_mask:0xf bound_ctrl:1
	v_add_f32_dpp v3, v3, v3 row_shr:4 row_mask:0xf bank_mask:0xf bound_ctrl:1
	v_mov_b32_dpp v0, v1 row_bcast:15 row_mask:0xa bank_mask:0xf
	v_add_f32_dpp v28, v28, v28 row_shr:2 row_mask:0xf bank_mask:0xf bound_ctrl:1
	v_add_f32_dpp v3, v3, v3 row_shr:8 row_mask:0xf bank_mask:0xf bound_ctrl:1
	v_add_f32_e32 v63, v1, v0
	v_mov_b32_e32 v0, v2
	v_cvt_f32_f16_e32 v52, v31
	v_add_f32_dpp v29, v29, v29 row_shr:1 row_mask:0xf bank_mask:0xf bound_ctrl:1
	v_add_f32_dpp v28, v28, v28 row_shr:4 row_mask:0xf bank_mask:0xf bound_ctrl:1
	v_mov_b32_dpp v0, v3 row_bcast:15 row_mask:0xa bank_mask:0xf
	v_add_f32_dpp v29, v29, v29 row_shr:2 row_mask:0xf bank_mask:0xf bound_ctrl:1
	v_add_f32_dpp v28, v28, v28 row_shr:8 row_mask:0xf bank_mask:0xf bound_ctrl:1
	v_add_f32_e32 v64, v3, v0
	v_mov_b32_e32 v0, v2
	v_add_f32_dpp v30, v30, v30 row_shr:1 row_mask:0xf bank_mask:0xf bound_ctrl:1
	v_add_f32_dpp v29, v29, v29 row_shr:4 row_mask:0xf bank_mask:0xf bound_ctrl:1
	v_mov_b32_dpp v0, v28 row_bcast:15 row_mask:0xa bank_mask:0xf
	v_add_f32_dpp v30, v30, v30 row_shr:2 row_mask:0xf bank_mask:0xf bound_ctrl:1
	v_add_f32_dpp v29, v29, v29 row_shr:8 row_mask:0xf bank_mask:0xf bound_ctrl:1
	v_add_f32_e32 v65, v28, v0
	v_mov_b32_e32 v0, v2
	v_add_f32_dpp v52, v52, v52 row_shr:1 row_mask:0xf bank_mask:0xf bound_ctrl:1
	v_add_f32_dpp v30, v30, v30 row_shr:4 row_mask:0xf bank_mask:0xf bound_ctrl:1
	v_mov_b32_dpp v0, v29 row_bcast:15 row_mask:0xa bank_mask:0xf
	ds_bpermute_b32 v1, v129, v62
	v_add_f32_dpp v52, v52, v52 row_shr:2 row_mask:0xf bank_mask:0xf bound_ctrl:1
	v_add_f32_dpp v30, v30, v30 row_shr:8 row_mask:0xf bank_mask:0xf bound_ctrl:1
	v_add_f32_e32 v3, v29, v0
	v_mov_b32_e32 v0, v2
	v_add_f32_dpp v52, v52, v52 row_shr:4 row_mask:0xf bank_mask:0xf bound_ctrl:1
	v_cvt_f32_f16_sdwa v31, v31 dst_sel:DWORD dst_unused:UNUSED_PAD src0_sel:WORD_1
	v_mov_b32_dpp v0, v30 row_bcast:15 row_mask:0xa bank_mask:0xf
	v_add_f32_dpp v52, v52, v52 row_shr:8 row_mask:0xf bank_mask:0xf bound_ctrl:1
	v_add_f32_e32 v66, v30, v0
	v_mov_b32_e32 v0, v2
	v_add_f32_dpp v31, v31, v31 row_shr:1 row_mask:0xf bank_mask:0xf bound_ctrl:1
	ds_bpermute_b32 v30, v129, v64
	v_mov_b32_dpp v0, v52 row_bcast:15 row_mask:0xa bank_mask:0xf
	v_add_f32_e32 v67, v52, v0
	s_waitcnt lgkmcnt(1)
	v_sub_f32_e32 v0, v62, v1
	ds_bpermute_b32 v1, v129, v63
	v_add_f32_dpp v31, v31, v31 row_shr:2 row_mask:0xf bank_mask:0xf bound_ctrl:1
	v_med3_f32 v0, v0, s69, v189
	v_mul_f32_e32 v0, 0x3fb8aa3b, v0
	v_add_f32_dpp v31, v31, v31 row_shr:4 row_mask:0xf bank_mask:0xf bound_ctrl:1
	v_exp_f32_e32 v28, v0
	v_mov_b32_e32 v0, v2
	v_add_f32_dpp v31, v31, v31 row_shr:8 row_mask:0xf bank_mask:0xf bound_ctrl:1
	s_waitcnt lgkmcnt(0)
	v_sub_f32_e32 v1, v63, v1
	ds_bpermute_b32 v56, v129, v67
	v_mov_b32_dpp v0, v31 row_bcast:15 row_mask:0xa bank_mask:0xf
	v_med3_f32 v1, v1, s69, v189
	v_add_f32_e32 v68, v31, v0
	v_mul_f32_e32 v1, 0x3fb8aa3b, v1
	v_exp_f32_e32 v29, v1
	ds_bpermute_b32 v1, v129, v65
	ds_bpermute_b32 v54, v129, v3
	ds_bpermute_b32 v55, v129, v66
	ds_bpermute_b32 v57, v129, v68
	s_waitcnt lgkmcnt(4)
	v_sub_f32_e32 v56, v67, v56
	v_med3_f32 v56, v56, s69, v189
	v_mul_f32_e32 v56, 0x3fb8aa3b, v56
	v_sub_f32_e32 v30, v64, v30
	s_waitcnt lgkmcnt(3)
	v_sub_f32_e32 v1, v65, v1
	s_waitcnt lgkmcnt(2)
	v_sub_f32_e32 v54, v3, v54
	s_waitcnt lgkmcnt(1)
	v_sub_f32_e32 v55, v66, v55
	v_exp_f32_e32 v58, v56
	s_waitcnt lgkmcnt(0)
	v_sub_f32_e32 v56, v68, v57
	v_med3_f32 v30, v30, s69, v189
	v_med3_f32 v1, v1, s69, v189
	v_med3_f32 v54, v54, s69, v189
	v_med3_f32 v55, v55, s69, v189
	v_med3_f32 v56, v56, s69, v189
	v_mul_f32_e32 v30, 0x3fb8aa3b, v30
	v_mul_f32_e32 v1, 0x3fb8aa3b, v1
	v_mul_f32_e32 v54, 0x3fb8aa3b, v54
	v_mul_f32_e32 v55, 0x3fb8aa3b, v55
	v_mul_f32_e32 v56, 0x3fb8aa3b, v56
	v_exp_f32_e32 v30, v30
	v_exp_f32_e32 v31, v1
	v_exp_f32_e32 v54, v54
	v_exp_f32_e32 v55, v55
	v_exp_f32_e32 v59, v56
	ds_bpermute_b32 v0, v130, v28
	ds_bpermute_b32 v1, v130, v29
	ds_bpermute_b32 v52, v130, v30
	ds_bpermute_b32 v53, v130, v31
	ds_bpermute_b32 v60, v130, v54
	ds_bpermute_b32 v61, v130, v55
	ds_bpermute_b32 v56, v130, v58
	ds_bpermute_b32 v57, v130, v59
	s_and_saveexec_b64 s[16:17], s[6:7]
	s_cbranch_execz .LBB0_867
	v_mul_f32_e32 v62, 0x3fb8aa3b, v62
	v_mul_f32_e32 v63, 0x3fb8aa3b, v63
	v_mul_f32_e32 v64, 0x3fb8aa3b, v64
	v_mul_f32_e32 v65, 0x3fb8aa3b, v65
	v_exp_f32_e32 v62, v62
	v_exp_f32_e32 v63, v63
	v_exp_f32_e32 v64, v64
	v_exp_f32_e32 v65, v65
	v_mul_f32_e32 v3, 0x3fb8aa3b, v3
	ds_write_b128 v139, v[62:65]
	v_exp_f32_e32 v62, v3
	v_mul_f32_e32 v3, 0x3fb8aa3b, v66
	v_exp_f32_e32 v63, v3
	v_mul_f32_e32 v3, 0x3fb8aa3b, v67
	v_exp_f32_e32 v64, v3
	v_mul_f32_e32 v3, 0x3fb8aa3b, v68
	v_exp_f32_e32 v65, v3
	ds_write_b128 v139, v[62:65] offset:16
	s_branch .LBB0_867

.LBB0_882:
	s_or_b64 exec, exec, s[56:57]
	s_min_i32 s16, s28, s35
	s_lshl_b32 s16, s16, 5
	v_or_b32_e32 v0, s16, v89
	v_xad_u32 v1, v0, -1, s74
	v_cndmask_b32_e64 v0, v1, v0, s[4:5]
	v_add_u32_e32 v1, s16, v90
	v_xad_u32 v3, v1, -1, s74
	v_add_u32_e32 v0, s73, v0
	v_cndmask_b32_e64 v3, v3, v1, s[4:5]
	v_ashrrev_i32_e32 v1, 31, v0
	s_waitcnt vmcnt(7)
	ds_write_b128 v95, v[4:7] offset:61952
	v_mad_i64_i32 v[4:5], s[16:17], v0, s89, v[80:81]
	v_lshlrev_b64 v[0:1], 11, v[0:1]
	v_lshl_add_u64 v[0:1], v[82:83], 0, v[0:1]
	global_load_dwordx4 v[12:15], v[4:5], off
	global_load_dwordx4 v[20:23], v[0:1], off
	v_add_u32_e32 v0, s73, v3
	v_mad_i64_i32 v[0:1], s[16:17], v0, s89, v[84:85]
	global_load_dwordx4 v[4:7], v[0:1], off
	v_add_u32_e32 v0, 0x8800, v97
	s_waitcnt lgkmcnt(0)
	s_barrier
	ds_read_b64_tr_b16 v[60:61], v102
	ds_read_b64_tr_b16 v[62:63], v102 offset:4352
	ds_read_b64 v[56:57], v0 offset:1024
	ds_read_b64 v[58:59], v0 offset:1056
	ds_read_b64 v[44:45], v0 offset:1088
	ds_read_b64 v[46:47], v0 offset:1120
	v_add_u32_e32 v0, 0x9000, v97
	ds_read_b64 v[52:53], v0 offset:1280
	ds_read_b64 v[54:55], v0 offset:1312
	ds_read_b64 v[48:49], v0 offset:1344
	ds_read_b64 v[50:51], v0 offset:1376
	v_add_u32_e32 v0, 0xa800, v98
	v_add_u32_e32 v1, 0xb000, v98
	ds_read_b64 v[64:65], v0 offset:1536
	ds_read_b64 v[66:67], v0 offset:1568
	ds_read_b64 v[68:69], v1 offset:1792
	ds_read_b64 v[70:71], v1 offset:1824
	ds_read_b64 v[76:77], v0 offset:1600
	ds_read_b64 v[78:79], v0 offset:1632
	ds_read_b64 v[112:113], v1 offset:1856
	ds_read_b64 v[114:115], v1 offset:1888
	s_waitcnt lgkmcnt(6)
	v_mfma_f32_16x16x32_bf16 v[72:75], v[64:67], v[56:59], 0
	v_mov_b32_e32 v0, s93
	s_add_i32 s28, s28, 2
	v_subrev_u32_e32 v111, 64, v111
	s_waitcnt lgkmcnt(4)
	v_mfma_f32_16x16x32_bf16 v[68:71], v[68:71], v[52:55], 0
	s_cmp_lt_u32 s58, s3
	s_waitcnt lgkmcnt(2)
	v_mfma_f32_16x16x32_bf16 v[72:75], v[76:79], v[44:47], v[72:75]
	s_waitcnt lgkmcnt(0)
	v_mfma_f32_16x16x32_bf16 v[68:71], v[112:115], v[48:51], v[68:71]
	v_mov_b32_e32 v112, s93
	s_nop 4
	v_cndmask_b32_e64 v0, v72, v0, s[8:9]
	v_cndmask_b32_e64 v0, v0, v72, s[10:11]
	v_mfma_f32_16x16x32_bf16 v[64:67], v[64:67], v[52:55], 0
	v_cndmask_b32_e64 v3, v74, 0, s[12:13]
	v_cndmask_b32_e64 v1, v68, v112, s[8:9]
	v_cndmask_b32_e64 v68, v1, v68, s[10:11]
	v_cndmask_b32_e64 v1, 0, v73, s[10:11]
	v_cndmask_b32_e64 v72, v75, 0, s[14:15]
	v_mfma_f32_16x16x32_bf16 v[64:67], v[76:79], v[48:51], v[64:67]
	v_cvt_pk_bf16_f32 v0, v0, v1
	v_cvt_pk_bf16_f32 v1, v3, v72
	ds_read_b128 v[72:75], v103
	ds_read_b128 v[76:79], v104
	v_cndmask_b32_e64 v69, 0, v69, s[10:11]
	v_cndmask_b32_e64 v70, v70, 0, s[12:13]
	v_cndmask_b32_e64 v71, v71, 0, s[14:15]
	v_mov_b32_e32 v3, v2
	v_cvt_pk_bf16_f32 v64, v64, v65
	v_cvt_pk_bf16_f32 v65, v66, v67
	v_cvt_pk_bf16_f32 v66, v68, v69
	v_cvt_pk_bf16_f32 v67, v70, v71
	v_mfma_f32_16x16x32_bf16 v[68:71], v[60:63], v[0:3], 0
	s_waitcnt lgkmcnt(1)
	v_pk_mul_f32 v[0:1], v[42:43], v[74:75]
	s_waitcnt lgkmcnt(0)
	v_pk_mul_f32 v[78:79], v[38:39], v[78:79]
	v_pk_mul_f32 v[74:75], v[36:37], v[76:77]
	v_pk_mul_f32 v[72:73], v[40:41], v[72:73]
	v_cvt_pk_bf16_f32 v74, v74, v75
	v_cvt_pk_bf16_f32 v75, v78, v79
	ds_read_b128 v[76:79], v105
	ds_read_b128 v[112:115], v106
	v_cvt_pk_bf16_f32 v72, v72, v73
	v_cvt_pk_bf16_f32 v73, v0, v1
	v_mfma_f32_16x16x32_bf16 v[64:67], v[60:63], v[64:67], 0
	s_waitcnt lgkmcnt(1)
	v_pk_mul_f32 v[0:1], v[30:31], v[78:79]
	s_waitcnt lgkmcnt(0)
	v_pk_mul_f32 v[114:115], v[34:35], v[114:115]
	v_pk_mul_f32 v[78:79], v[32:33], v[112:113]
	v_pk_mul_f32 v[76:77], v[28:29], v[76:77]
	v_cvt_pk_bf16_f32 v78, v78, v79
	v_cvt_pk_bf16_f32 v79, v114, v115
	ds_read_b128 v[112:115], v107
	ds_read_b64_tr_b16 v[118:119], v100 offset:55552
	ds_read_b64_tr_b16 v[116:117], v100 offset:53248
	ds_read_b64_tr_b16 v[120:121], v100 offset:53280
	v_cvt_pk_bf16_f32 v76, v76, v77
	s_waitcnt lgkmcnt(3)
	v_pk_mul_f32 v[42:43], v[42:43], v[114:115]
	v_pk_mul_f32 v[40:41], v[40:41], v[112:113]
	ds_read_b128 v[112:115], v108
	ds_read_b64_tr_b16 v[122:123], v100 offset:55584
	v_cvt_pk_bf16_f32 v77, v0, v1
	v_mfma_f32_16x16x32_bf16 v[56:59], v[72:75], v[56:59], v[68:71]
	v_xor_b32_e32 v3, 0xffffffdf, v88
	s_waitcnt lgkmcnt(1)
	v_pk_mul_f32 v[38:39], v[38:39], v[114:115]
	v_pk_mul_f32 v[36:37], v[36:37], v[112:113]
	v_mfma_f32_16x16x32_bf16 v[40:43], v[116:119], v[60:63], v[40:43]
	ds_read_b128 v[112:115], v109
	ds_read_b64_tr_b16 v[116:117], v100 offset:53312
	ds_read_b64_tr_b16 v[118:119], v100 offset:55616
	v_add_u32_e32 v0, 32, v88
	v_add_u32_e32 v3, s74, v3
	v_mfma_f32_16x16x32_bf16 v[52:55], v[72:75], v[52:55], v[64:67]
	s_waitcnt lgkmcnt(2)
	v_pk_mul_f32 v[30:31], v[30:31], v[114:115]
	v_pk_mul_f32 v[28:29], v[28:29], v[112:113]
	v_cndmask_b32_e64 v3, v3, v0, s[4:5]
	v_mfma_f32_16x16x32_bf16 v[44:47], v[76:79], v[44:47], v[56:59]
	v_xor_b32_e32 v0, 0xffffffcf, v88
	v_add_u32_e32 v1, 48, v88
	v_add_u32_e32 v0, s74, v0
	s_waitcnt lgkmcnt(0)
	v_mfma_f32_16x16x32_bf16 v[28:31], v[116:119], v[60:63], v[28:31]
	ds_read_b128 v[112:115], v110
	ds_read_b64_tr_b16 v[116:117], v100 offset:53344
	ds_read_b64_tr_b16 v[118:119], v100 offset:55648
	v_add_u32_e32 v88, 64, v88
	s_waitcnt lgkmcnt(2)
	v_pk_mul_f32 v[34:35], v[34:35], v[114:115]
	v_mfma_f32_16x16x32_bf16 v[48:51], v[76:79], v[48:51], v[52:55]
	v_mul_f32_e64 v32, v32, v112
	v_mul_f32_e64 v33, v33, v113
	s_nop 0
	v_cndmask_b32_e64 v52, v0, v1, s[4:5]
	v_cvt_pk_bf16_f32 v1, v46, v47
	v_add_u32_e32 v46, s73, v3
	v_ashrrev_i32_e32 v47, 31, v46
	v_lshlrev_b64 v[46:47], 11, v[46:47]
	v_cvt_pk_bf16_f32 v0, v44, v45
	v_lshl_add_u64 v[46:47], v[86:87], 0, v[46:47]
	v_mfma_f32_16x16x32_bf16 v[36:39], v[120:123], v[60:63], v[36:39]
	global_store_dwordx2 v[46:47], v[0:1], off sc1
	v_add_u32_e32 v0, s73, v52
	v_ashrrev_i32_e32 v1, 31, v0
	s_waitcnt lgkmcnt(0)
	v_mfma_f32_16x16x32_bf16 v[32:35], v[116:119], v[60:63], v[32:35]
	v_lshlrev_b64 v[0:1], 11, v[0:1]
	v_cvt_pk_bf16_f32 v44, v48, v49
	v_cvt_pk_bf16_f32 v45, v50, v51
	v_lshl_add_u64 v[0:1], v[86:87], 0, v[0:1]
	global_store_dwordx2 v[0:1], v[44:45], off sc1
	s_cbranch_scc0 .LBB0_815

.LBB0_887:
	s_or_b64 exec, exec, s[56:57]
	s_add_i32 s58, s28, -1
	s_min_i32 s16, s58, s35
	s_lshl_b32 s16, s16, 5
	v_or_b32_e32 v0, s16, v89
	v_xad_u32 v1, v0, -1, s74
	v_cndmask_b32_e64 v0, v1, v0, s[4:5]
	v_add_u32_e32 v1, s16, v90
	v_xad_u32 v3, v1, -1, s74
	v_add_u32_e32 v0, s73, v0
	v_cndmask_b32_e64 v3, v3, v1, s[4:5]
	v_ashrrev_i32_e32 v1, 31, v0
	s_waitcnt vmcnt(7)
	ds_write_b128 v95, v[8:11] offset:26112
	v_mad_i64_i32 v[8:9], s[16:17], v0, s89, v[80:81]
	v_lshlrev_b64 v[0:1], 11, v[0:1]
	v_lshl_add_u64 v[0:1], v[82:83], 0, v[0:1]
	global_load_dwordx4 v[16:19], v[8:9], off
	global_load_dwordx4 v[24:27], v[0:1], off
	v_add_u32_e32 v0, s73, v3
	v_mad_i64_i32 v[0:1], s[16:17], v0, s89, v[84:85]
	global_load_dwordx4 v[8:11], v[0:1], off
	v_add_u32_e32 v0, 0x800, v97
	s_waitcnt lgkmcnt(0)
	s_barrier
	ds_read_b64_tr_b16 v[60:61], v96 offset:26112
	ds_read_b64_tr_b16 v[62:63], v96 offset:30464
	ds_read_b64 v[56:57], v97
	ds_read_b64 v[58:59], v97 offset:32
	ds_read_b64 v[44:45], v97 offset:64
	ds_read_b64 v[46:47], v97 offset:96
	ds_read_b64 v[52:53], v0 offset:256
	ds_read_b64 v[54:55], v0 offset:288
	ds_read_b64 v[48:49], v0 offset:320
	ds_read_b64 v[50:51], v0 offset:352
	v_add_u32_e32 v0, 0x2000, v98
	v_add_u32_e32 v1, 0x2800, v98
	ds_read_b64 v[64:65], v0 offset:512
	ds_read_b64 v[66:67], v0 offset:544
	ds_read_b64 v[68:69], v1 offset:768
	ds_read_b64 v[70:71], v1 offset:800
	ds_read_b64 v[76:77], v0 offset:576
	ds_read_b64 v[78:79], v0 offset:608
	ds_read_b64 v[112:113], v1 offset:832
	ds_read_b64 v[114:115], v1 offset:864
	s_waitcnt lgkmcnt(6)
	v_mfma_f32_16x16x32_bf16 v[72:75], v[64:67], v[56:59], 0
	v_mov_b32_e32 v0, s93
	s_waitcnt lgkmcnt(4)
	v_mfma_f32_16x16x32_bf16 v[68:71], v[68:71], v[52:55], 0
	s_waitcnt lgkmcnt(2)
	v_mfma_f32_16x16x32_bf16 v[72:75], v[76:79], v[44:47], v[72:75]
	s_waitcnt lgkmcnt(0)
	v_mfma_f32_16x16x32_bf16 v[68:71], v[112:115], v[48:51], v[68:71]
	v_mov_b32_e32 v112, s93
	s_nop 4
	v_cndmask_b32_e64 v0, v72, v0, s[8:9]
	v_cndmask_b32_e64 v0, v0, v72, s[10:11]
	v_mfma_f32_16x16x32_bf16 v[64:67], v[64:67], v[52:55], 0
	v_cndmask_b32_e64 v3, v74, 0, s[12:13]
	v_cndmask_b32_e64 v1, v68, v112, s[8:9]
	v_cndmask_b32_e64 v68, v1, v68, s[10:11]
	v_cndmask_b32_e64 v1, 0, v73, s[10:11]
	v_cndmask_b32_e64 v72, v75, 0, s[14:15]
	v_mfma_f32_16x16x32_bf16 v[64:67], v[76:79], v[48:51], v[64:67]
	v_cvt_pk_bf16_f32 v0, v0, v1
	v_cvt_pk_bf16_f32 v1, v3, v72
	ds_read_b128 v[72:75], v99 offset:35328
	ds_read_b128 v[76:79], v99 offset:35392
	v_cndmask_b32_e64 v69, 0, v69, s[10:11]
	v_cndmask_b32_e64 v70, v70, 0, s[12:13]
	v_cndmask_b32_e64 v71, v71, 0, s[14:15]
	v_mov_b32_e32 v3, v2
	v_cvt_pk_bf16_f32 v64, v64, v65
	v_cvt_pk_bf16_f32 v65, v66, v67
	v_cvt_pk_bf16_f32 v66, v68, v69
	v_cvt_pk_bf16_f32 v67, v70, v71
	v_mfma_f32_16x16x32_bf16 v[68:71], v[60:63], v[0:3], 0
	s_waitcnt lgkmcnt(1)
	v_pk_mul_f32 v[0:1], v[42:43], v[74:75]
	s_waitcnt lgkmcnt(0)
	v_pk_mul_f32 v[78:79], v[38:39], v[78:79]
	v_pk_mul_f32 v[74:75], v[36:37], v[76:77]
	v_pk_mul_f32 v[72:73], v[40:41], v[72:73]
	v_cvt_pk_bf16_f32 v74, v74, v75
	v_cvt_pk_bf16_f32 v75, v78, v79
	ds_read_b128 v[76:79], v99 offset:35456
	ds_read_b128 v[112:115], v99 offset:35520
	v_cvt_pk_bf16_f32 v72, v72, v73
	v_cvt_pk_bf16_f32 v73, v0, v1
	v_mfma_f32_16x16x32_bf16 v[64:67], v[60:63], v[64:67], 0
	s_waitcnt lgkmcnt(1)
	v_pk_mul_f32 v[0:1], v[30:31], v[78:79]
	s_waitcnt lgkmcnt(0)
	v_pk_mul_f32 v[114:115], v[34:35], v[114:115]
	v_pk_mul_f32 v[78:79], v[32:33], v[112:113]
	v_pk_mul_f32 v[76:77], v[28:29], v[76:77]
	v_cvt_pk_bf16_f32 v78, v78, v79
	v_cvt_pk_bf16_f32 v79, v114, v115
	ds_read_b128 v[112:115], v99 offset:34816
	ds_read_b64_tr_b16 v[118:119], v100 offset:19712
	ds_read_b64_tr_b16 v[116:117], v100 offset:17408
	ds_read_b64_tr_b16 v[120:121], v100 offset:17440
	v_cvt_pk_bf16_f32 v76, v76, v77
	s_waitcnt lgkmcnt(3)
	v_pk_mul_f32 v[42:43], v[42:43], v[114:115]
	v_pk_mul_f32 v[40:41], v[40:41], v[112:113]
	ds_read_b128 v[112:115], v99 offset:34880
	ds_read_b64_tr_b16 v[122:123], v100 offset:19744
	v_cvt_pk_bf16_f32 v77, v0, v1
	v_mfma_f32_16x16x32_bf16 v[56:59], v[72:75], v[56:59], v[68:71]
	v_xor_b32_e32 v1, 0xffffffef, v88
	s_waitcnt lgkmcnt(1)
	v_pk_mul_f32 v[38:39], v[38:39], v[114:115]
	v_pk_mul_f32 v[36:37], v[36:37], v[112:113]
	v_mfma_f32_16x16x32_bf16 v[40:43], v[116:119], v[60:63], v[40:43]
	ds_read_b128 v[112:115], v99 offset:34944
	ds_read_b64_tr_b16 v[116:117], v100 offset:17472
	ds_read_b64_tr_b16 v[118:119], v100 offset:19776
	v_add_u32_e32 v0, 16, v88
	v_cndmask_b32_e64 v3, v111, v88, s[4:5]
	v_mfma_f32_16x16x32_bf16 v[52:55], v[72:75], v[52:55], v[64:67]
	s_waitcnt lgkmcnt(2)
	v_pk_mul_f32 v[30:31], v[30:31], v[114:115]
	v_pk_mul_f32 v[28:29], v[28:29], v[112:113]
	v_add_u32_e32 v1, s74, v1
	v_mfma_f32_16x16x32_bf16 v[44:47], v[76:79], v[44:47], v[56:59]
	s_waitcnt lgkmcnt(0)
	v_mfma_f32_16x16x32_bf16 v[28:31], v[116:119], v[60:63], v[28:31]
	ds_read_b128 v[112:115], v99 offset:35008
	ds_read_b64_tr_b16 v[116:117], v100 offset:17504
	ds_read_b64_tr_b16 v[118:119], v100 offset:19808
	s_waitcnt lgkmcnt(2)
	v_pk_mul_f32 v[34:35], v[34:35], v[114:115]
	v_mfma_f32_16x16x32_bf16 v[48:51], v[76:79], v[48:51], v[52:55]
	v_mul_f32_e64 v32, v32, v112
	v_mul_f32_e64 v33, v33, v113
	s_nop 0
	v_cndmask_b32_e64 v52, v1, v0, s[4:5]
	v_cvt_pk_bf16_f32 v1, v46, v47
	v_add_u32_e32 v46, s73, v3
	v_ashrrev_i32_e32 v47, 31, v46
	v_lshlrev_b64 v[46:47], 11, v[46:47]
	v_cvt_pk_bf16_f32 v0, v44, v45
	v_lshl_add_u64 v[46:47], v[86:87], 0, v[46:47]
	v_mfma_f32_16x16x32_bf16 v[36:39], v[120:123], v[60:63], v[36:39]
	global_store_dwordx2 v[46:47], v[0:1], off sc1
	v_add_u32_e32 v0, s73, v52
	v_ashrrev_i32_e32 v1, 31, v0
	s_waitcnt lgkmcnt(0)
	v_mfma_f32_16x16x32_bf16 v[32:35], v[116:119], v[60:63], v[32:35]
	v_lshlrev_b64 v[0:1], 11, v[0:1]
	v_cvt_pk_bf16_f32 v44, v48, v49
	v_cvt_pk_bf16_f32 v45, v50, v51
	v_lshl_add_u64 v[0:1], v[86:87], 0, v[0:1]
	global_store_dwordx2 v[0:1], v[44:45], off sc1
	s_and_saveexec_b64 s[56:57], vcc
	s_cbranch_execz .LBB0_882
	s_waitcnt vmcnt(8)
	v_cvt_f32_f16_e32 v60, v20
	v_cvt_f32_f16_sdwa v59, v20 dst_sel:DWORD dst_unused:UNUSED_PAD src0_sel:WORD_1
	v_cvt_f32_f16_e32 v58, v21
	v_cvt_f32_f16_sdwa v57, v21 dst_sel:DWORD dst_unused:UNUSED_PAD src0_sel:WORD_1
	v_add_f32_dpp v0, v60, v60 row_shr:1 row_mask:0xf bank_mask:0xf bound_ctrl:1
	v_add_f32_dpp v1, v59, v59 row_shr:1 row_mask:0xf bank_mask:0xf bound_ctrl:1
	v_mov_b32_e32 v46, v2
	v_add_f32_dpp v0, v0, v0 row_shr:2 row_mask:0xf bank_mask:0xf bound_ctrl:1
	v_add_f32_dpp v1, v1, v1 row_shr:2 row_mask:0xf bank_mask:0xf bound_ctrl:1
	v_cvt_f32_f16_e32 v56, v22
	v_add_f32_dpp v0, v0, v0 row_shr:4 row_mask:0xf bank_mask:0xf bound_ctrl:1
	v_add_f32_dpp v20, v58, v58 row_shr:1 row_mask:0xf bank_mask:0xf bound_ctrl:1
	v_add_f32_dpp v1, v1, v1 row_shr:4 row_mask:0xf bank_mask:0xf bound_ctrl:1
	v_add_f32_dpp v0, v0, v0 row_shr:8 row_mask:0xf bank_mask:0xf bound_ctrl:1
	v_add_f32_dpp v20, v20, v20 row_shr:2 row_mask:0xf bank_mask:0xf bound_ctrl:1
	v_add_f32_dpp v1, v1, v1 row_shr:8 row_mask:0xf bank_mask:0xf bound_ctrl:1
	v_mov_b32_dpp v46, v0 row_bcast:15 row_mask:0xa bank_mask:0xf
	v_add_f32_e32 v62, v0, v46
	v_mov_b32_e32 v0, v2
	v_cvt_f32_f16_sdwa v55, v22 dst_sel:DWORD dst_unused:UNUSED_PAD src0_sel:WORD_1
	v_add_f32_dpp v21, v57, v57 row_shr:1 row_mask:0xf bank_mask:0xf bound_ctrl:1
	v_add_f32_dpp v20, v20, v20 row_shr:4 row_mask:0xf bank_mask:0xf bound_ctrl:1
	v_mov_b32_dpp v0, v1 row_bcast:15 row_mask:0xa bank_mask:0xf
	v_add_f32_dpp v21, v21, v21 row_shr:2 row_mask:0xf bank_mask:0xf bound_ctrl:1
	v_add_f32_dpp v20, v20, v20 row_shr:8 row_mask:0xf bank_mask:0xf bound_ctrl:1
	v_add_f32_e32 v63, v1, v0
	v_mov_b32_e32 v0, v2
	v_cvt_f32_f16_e32 v54, v23
	v_add_f32_dpp v22, v56, v56 row_shr:1 row_mask:0xf bank_mask:0xf bound_ctrl:1
	v_add_f32_dpp v21, v21, v21 row_shr:4 row_mask:0xf bank_mask:0xf bound_ctrl:1
	v_mov_b32_dpp v0, v20 row_bcast:15 row_mask:0xa bank_mask:0xf
	v_add_f32_dpp v22, v22, v22 row_shr:2 row_mask:0xf bank_mask:0xf bound_ctrl:1
	v_add_f32_dpp v21, v21, v21 row_shr:8 row_mask:0xf bank_mask:0xf bound_ctrl:1
	v_add_f32_e32 v64, v20, v0
	v_mov_b32_e32 v0, v2
	v_cvt_f32_f16_sdwa v3, v23 dst_sel:DWORD dst_unused:UNUSED_PAD src0_sel:WORD_1
	v_add_f32_dpp v23, v55, v55 row_shr:1 row_mask:0xf bank_mask:0xf bound_ctrl:1
	v_add_f32_dpp v22, v22, v22 row_shr:4 row_mask:0xf bank_mask:0xf bound_ctrl:1
	v_mov_b32_dpp v0, v21 row_bcast:15 row_mask:0xa bank_mask:0xf
	v_add_f32_dpp v23, v23, v23 row_shr:2 row_mask:0xf bank_mask:0xf bound_ctrl:1
	v_add_f32_dpp v22, v22, v22 row_shr:8 row_mask:0xf bank_mask:0xf bound_ctrl:1
	v_add_f32_e32 v65, v21, v0
	v_mov_b32_e32 v0, v2
	v_add_f32_dpp v44, v54, v54 row_shr:1 row_mask:0xf bank_mask:0xf bound_ctrl:1
	v_add_f32_dpp v23, v23, v23 row_shr:4 row_mask:0xf bank_mask:0xf bound_ctrl:1
	v_mov_b32_dpp v0, v22 row_bcast:15 row_mask:0xa bank_mask:0xf
	ds_bpermute_b32 v1, v91, v62
	v_add_f32_dpp v44, v44, v44 row_shr:2 row_mask:0xf bank_mask:0xf bound_ctrl:1
	v_add_f32_dpp v23, v23, v23 row_shr:8 row_mask:0xf bank_mask:0xf bound_ctrl:1
	v_add_f32_e32 v61, v22, v0
	v_mov_b32_e32 v0, v2
	v_add_f32_dpp v44, v44, v44 row_shr:4 row_mask:0xf bank_mask:0xf bound_ctrl:1
	v_add_f32_dpp v45, v3, v3 row_shr:1 row_mask:0xf bank_mask:0xf bound_ctrl:1
	v_mov_b32_dpp v0, v23 row_bcast:15 row_mask:0xa bank_mask:0xf
	v_add_f32_dpp v44, v44, v44 row_shr:8 row_mask:0xf bank_mask:0xf bound_ctrl:1
	v_add_f32_e32 v66, v23, v0
	v_mov_b32_e32 v0, v2
	v_add_f32_dpp v45, v45, v45 row_shr:2 row_mask:0xf bank_mask:0xf bound_ctrl:1
	ds_bpermute_b32 v22, v91, v64
	v_mov_b32_dpp v0, v44 row_bcast:15 row_mask:0xa bank_mask:0xf
	v_add_f32_e32 v67, v44, v0
	s_waitcnt lgkmcnt(1)
	v_sub_f32_e32 v0, v62, v1
	ds_bpermute_b32 v1, v91, v63
	v_med3_f32 v0, v0, s69, v189
	v_add_f32_dpp v45, v45, v45 row_shr:4 row_mask:0xf bank_mask:0xf bound_ctrl:1
	v_mul_f32_e32 v0, 0x3fb8aa3b, v0
	v_exp_f32_e32 v20, v0
	v_add_f32_dpp v45, v45, v45 row_shr:8 row_mask:0xf bank_mask:0xf bound_ctrl:1
	v_mov_b32_e32 v0, v2
	s_waitcnt lgkmcnt(0)
	v_sub_f32_e32 v1, v63, v1
	v_med3_f32 v1, v1, s69, v189
	v_mov_b32_dpp v0, v45 row_bcast:15 row_mask:0xa bank_mask:0xf
	v_add_f32_e32 v68, v45, v0
	v_mul_f32_e32 v1, 0x3fb8aa3b, v1
	v_exp_f32_e32 v21, v1
	ds_bpermute_b32 v1, v91, v65
	ds_bpermute_b32 v46, v91, v61
	ds_bpermute_b32 v47, v91, v66
	ds_bpermute_b32 v48, v91, v67
	ds_bpermute_b32 v49, v91, v68
	v_sub_f32_e32 v22, v64, v22
	s_waitcnt lgkmcnt(4)
	v_sub_f32_e32 v1, v65, v1
	s_waitcnt lgkmcnt(3)
	v_sub_f32_e32 v46, v61, v46
	s_waitcnt lgkmcnt(2)
	v_sub_f32_e32 v47, v66, v47
	s_waitcnt lgkmcnt(1)
	v_sub_f32_e32 v48, v67, v48
	s_waitcnt lgkmcnt(0)
	v_sub_f32_e32 v49, v68, v49
	v_med3_f32 v22, v22, s69, v189
	v_med3_f32 v1, v1, s69, v189
	v_med3_f32 v46, v46, s69, v189
	v_med3_f32 v47, v47, s69, v189
	v_med3_f32 v48, v48, s69, v189
	v_med3_f32 v49, v49, s69, v189
	v_mul_f32_e32 v22, 0x3fb8aa3b, v22
	v_mul_f32_e32 v1, 0x3fb8aa3b, v1
	v_mul_f32_e32 v46, 0x3fb8aa3b, v46
	v_mul_f32_e32 v47, 0x3fb8aa3b, v47
	v_mul_f32_e32 v48, 0x3fb8aa3b, v48
	v_mul_f32_e32 v49, 0x3fb8aa3b, v49
	v_exp_f32_e32 v44, v22
	v_exp_f32_e32 v45, v1
	v_exp_f32_e32 v46, v46
	v_exp_f32_e32 v47, v47
	v_exp_f32_e32 v48, v48
	v_exp_f32_e32 v49, v49
	ds_bpermute_b32 v0, v92, v20
	ds_bpermute_b32 v1, v92, v21
	ds_bpermute_b32 v22, v92, v44
	ds_bpermute_b32 v23, v92, v45
	ds_bpermute_b32 v52, v92, v46
	ds_bpermute_b32 v53, v92, v47
	ds_bpermute_b32 v50, v92, v48
	ds_bpermute_b32 v51, v92, v49
	s_and_saveexec_b64 s[16:17], s[6:7]
	s_cbranch_execz .LBB0_881
	v_mul_f32_e32 v62, 0x3fb8aa3b, v62
	v_mul_f32_e32 v63, 0x3fb8aa3b, v63
	v_mul_f32_e32 v64, 0x3fb8aa3b, v64
	v_mul_f32_e32 v65, 0x3fb8aa3b, v65
	v_exp_f32_e32 v62, v62
	v_exp_f32_e32 v63, v63
	v_exp_f32_e32 v64, v64
	v_exp_f32_e32 v65, v65
	v_mul_f32_e32 v61, 0x3fb8aa3b, v61
	ds_write_b128 v101, v[62:65]
	v_exp_f32_e32 v62, v61
	v_mul_f32_e32 v61, 0x3fb8aa3b, v66
	v_exp_f32_e32 v63, v61
	v_mul_f32_e32 v61, 0x3fb8aa3b, v67
	v_exp_f32_e32 v64, v61
	v_mul_f32_e32 v61, 0x3fb8aa3b, v68
	v_exp_f32_e32 v65, v61
	ds_write_b128 v101, v[62:65] offset:16
	s_branch .LBB0_881

.LBB0_894:
	s_ashr_i32 s0, s12, 31
	s_lshr_b32 s0, s0, 26
	s_add_i32 s1, s12, s0
	s_waitcnt vmcnt(3)
	v_mov_b32_e32 v22, v224
	s_and_b32 s0, s1, 0xffffffc0
	s_lshl_b32 s1, s1, 6
	v_readlane_b32 s68, v254, 0
	v_lshlrev_b32_e32 v0, 4, v22
	s_and_b32 s1, s1, 0xfffff000
	v_and_b32_e32 v0, 0xf0, v0
	v_readlane_b32 s69, v254, 1
	s_sub_i32 s4, s13, s1
	v_ashrrev_i32_e32 v23, 4, v22
	v_lshl_add_u64 v[2:3], s[68:69], 0, v[0:1]
	s_ashr_i32 s5, s4, 31
	s_add_i32 s40, s12, 1
	s_waitcnt vmcnt(2)
	v_add_u32_e32 v4, s0, v23
	v_lshl_add_u64 v[6:7], s[4:5], 2, v[2:3]
	s_min_i32 s4, s40, 0x3ff
	v_ashrrev_i32_e32 v5, 31, v4
	s_ashr_i32 s5, s4, 31
	v_lshlrev_b64 v[4:5], 14, v[4:5]
	s_lshr_b32 s5, s5, 26
	v_lshl_add_u64 v[4:5], v[6:7], 0, v[4:5]
	s_add_i32 s5, s4, s5
	v_add_co_u32_e32 v10, vcc, s19, v4
	s_andn2_b32 s5, s5, 63
	s_nop 0
	v_addc_co_u32_e32 v11, vcc, 0, v5, vcc
	s_sub_i32 s4, s4, s5
	global_load_dwordx4 v[6:9], v[4:5], off nt
	s_nop 0
	global_load_dwordx4 v[10:13], v[10:11], off nt
	s_lshl_b32 s4, s4, 6
	v_add_u32_e32 v4, s5, v23
	s_ashr_i32 s5, s4, 31
	v_ashrrev_i32_e32 v5, 31, v4
	v_lshl_add_u64 v[2:3], s[4:5], 2, v[2:3]
	v_lshlrev_b64 v[4:5], 14, v[4:5]
	v_lshl_add_u64 v[2:3], v[2:3], 0, v[4:5]
	global_load_dwordx4 v[14:17], v[2:3], off nt
	v_add_co_u32_e32 v2, vcc, s19, v2
	v_mul_lo_u32 v4, v23, s28
	s_nop 0
	v_addc_co_u32_e32 v3, vcc, 0, v3, vcc
	global_load_dwordx4 v[18:21], v[2:3], off nt
	v_ashrrev_i32_e32 v3, 3, v22
	v_lshlrev_b32_e32 v5, 1, v3
	v_lshlrev_b32_e32 v2, 3, v22
	v_add3_u32 v0, 0, v0, v4
	v_and_b32_e32 v4, 62, v5
	v_subrev_u32_e32 v5, s1, v3
	v_and_b32_e32 v22, 56, v2
	v_lshl_add_u32 v2, v3, 2, 0
	v_lshrrev_b32_e32 v23, 5, v3
	v_add_u32_e32 v5, s13, v5
	v_mad_u32_u24 v2, v22, s28, v2
	v_add_u32_e32 v24, 0x2080, v0
	v_add_u32_e32 v25, 0x2088, v0
	v_add_u32_e32 v26, 0x4100, v0
	v_add_u32_e32 v27, 0x4108, v0
	v_add_u32_e32 v28, 0x6180, v0
	v_add_u32_e32 v29, 0x6188, v0
	v_and_or_b32 v4, v23, 1, v4
	v_cmp_gt_i32_e32 vcc, s29, v5
	v_readlane_b32 s70, v254, 2
	v_readlane_b32 s71, v254, 3
	v_readlane_b32 s72, v254, 4
	v_readlane_b32 s73, v254, 5
	v_readlane_b32 s74, v254, 6
	v_readlane_b32 s75, v254, 7
	s_waitcnt vmcnt(3)
	ds_write2_b32 v0, v6, v7 offset1:1
	ds_write2_b32 v0, v8, v9 offset0:2 offset1:3
	s_waitcnt vmcnt(2)
	ds_write2_b32 v24, v10, v11 offset1:1
	ds_write2_b32 v25, v12, v13 offset1:1
	s_waitcnt vmcnt(1)
	ds_write2_b32 v26, v14, v15 offset1:1
	ds_write2_b32 v27, v16, v17 offset1:1
	s_waitcnt vmcnt(0)
	ds_write2_b32 v28, v18, v19 offset1:1
	ds_write2_b32 v29, v20, v21 offset1:1
	v_lshlrev_b32_e32 v0, 1, v22
	s_waitcnt lgkmcnt(0)
	s_barrier
	s_and_saveexec_b64 s[4:5], vcc
	s_cbranch_execz .LBB0_896
	ds_read2_b32 v[6:7], v2 offset1:65
	ds_read2_b32 v[8:9], v2 offset0:130 offset1:195
	v_add_u32_e32 v12, 0x400, v2
	ds_read2_b32 v[10:11], v12 offset0:4 offset1:69
	ds_read2_b32 v[12:13], v12 offset0:134 offset1:199
	v_and_or_b32 v14, v5, s17, v4
	v_cmp_gt_i32_e32 vcc, s35, v5
	s_waitcnt lgkmcnt(3)
	v_cvt_pk_bf16_f32 v6, v6, v7
	s_waitcnt lgkmcnt(2)
	v_cvt_pk_bf16_f32 v7, v8, v9
	v_cndmask_b32_e32 v14, v5, v14, vcc
	v_ashrrev_i32_e32 v15, 31, v14
	s_waitcnt lgkmcnt(1)
	v_cvt_pk_bf16_f32 v8, v10, v11
	v_lshlrev_b64 v[10:11], 11, v[14:15]
	v_lshl_add_u64 v[10:11], s[14:15], 0, v[10:11]
	s_ashr_i32 s1, s0, 31
	v_lshl_add_u64 v[10:11], s[0:1], 1, v[10:11]
	s_waitcnt lgkmcnt(0)
	v_cvt_pk_bf16_f32 v9, v12, v13
	v_lshl_add_u64 v[10:11], v[10:11], 0, v[0:1]
	global_store_dwordx4 v[10:11], v[6:9], off sc1
.LBB0_896:
	s_or_b64 exec, exec, s[4:5]
	s_ashr_i32 s0, s40, 31
	s_lshr_b32 s0, s0, 26
	s_add_i32 s4, s40, s0
	s_and_b32 s0, s4, 0x3ffffc0
	s_sub_i32 s0, s40, s0
	v_lshl_add_u32 v3, s0, 6, v3
	v_cmp_gt_i32_e32 vcc, s29, v3
	s_and_saveexec_b64 s[0:1], vcc
	s_cbranch_execz .LBB0_893
	v_add_u32_e32 v5, 0x4000, v2
	ds_read2_b32 v[6:7], v5 offset0:64 offset1:129
	v_add_u32_e32 v5, 0x4200, v2
	ds_read2_b32 v[8:9], v5 offset0:66 offset1:131
	v_add_u32_e32 v5, 0x4400, v2
	v_add_u32_e32 v2, 0x4600, v2
	ds_read2_b32 v[12:13], v2 offset0:70 offset1:135
	v_and_or_b32 v2, v3, s17, v4
	v_cmp_gt_i32_e32 vcc, s35, v3
	ds_read2_b32 v[10:11], v5 offset0:68 offset1:133
	s_ashr_i32 s4, s4, 6
	v_cndmask_b32_e32 v14, v3, v2, vcc
	v_ashrrev_i32_e32 v15, 31, v14
	s_lshl_b32 s4, s4, 6
	s_waitcnt lgkmcnt(3)
	v_cvt_pk_bf16_f32 v2, v6, v7
	v_lshlrev_b64 v[6:7], 11, v[14:15]
	v_lshl_add_u64 v[6:7], s[14:15], 0, v[6:7]
	s_ashr_i32 s5, s4, 31
	v_lshl_add_u64 v[6:7], s[4:5], 1, v[6:7]
	s_waitcnt lgkmcnt(2)
	v_cvt_pk_bf16_f32 v3, v8, v9
	s_waitcnt lgkmcnt(0)
	v_cvt_pk_bf16_f32 v4, v10, v11
	v_cvt_pk_bf16_f32 v5, v12, v13
	v_lshl_add_u64 v[6:7], v[6:7], 0, v[0:1]
	global_store_dwordx4 v[6:7], v[2:5], off sc1
	s_branch .LBB0_893

.LBB0_909:
	s_or_b64 exec, exec, s[4:5]
	v_mul_lo_u32 v18, v23, s19
	v_add3_u32 v16, 0, v16, v18
	s_waitcnt vmcnt(0)
	ds_write2_b32 v16, v0, v1 offset1:1
	ds_write2_b32 v16, v2, v3 offset0:2 offset1:3
	v_add_u32_e32 v0, 0x2080, v16
	ds_write2_b32 v0, v8, v9 offset1:1
	v_add_u32_e32 v0, 0x2088, v16
	ds_write2_b32 v0, v10, v11 offset1:1
	v_add_u32_e32 v0, 0x4100, v16
	ds_write2_b32 v0, v4, v5 offset1:1
	v_add_u32_e32 v0, 0x4108, v16
	ds_write2_b32 v0, v6, v7 offset1:1
	v_add_u32_e32 v0, 0x6180, v16
	ds_write2_b32 v0, v12, v13 offset1:1
	v_add_u32_e32 v0, 0x6188, v16
	ds_write2_b32 v0, v14, v15 offset1:1
	v_ashrrev_i32_e32 v3, 3, v22
	v_lshlrev_b32_e32 v0, 3, v22
	v_and_b32_e32 v1, 56, v0
	v_subrev_u32_e32 v0, s1, v3
	v_lshl_add_u32 v2, v3, 2, 0
	v_add_u32_e32 v0, s28, v0
	v_cmp_gt_i32_e32 vcc, s17, v0
	v_mad_u32_u24 v2, v1, s19, v2
	v_lshlrev_b32_e32 v16, 1, v1
	s_waitcnt lgkmcnt(0)
	s_barrier
	s_and_saveexec_b64 s[4:5], vcc
	s_cbranch_execz .LBB0_911
	v_add_u32_e32 v1, 0x400, v2
	ds_read2_b32 v[4:5], v2 offset1:65
	ds_read2_b32 v[6:7], v2 offset0:130 offset1:195
	ds_read2_b32 v[8:9], v1 offset0:4 offset1:69
	ds_read2_b32 v[10:11], v1 offset0:134 offset1:199
	v_ashrrev_i32_e32 v1, 31, v0
	v_lshlrev_b64 v[0:1], 11, v[0:1]
	v_lshl_add_u64 v[0:1], s[8:9], 0, v[0:1]
	s_ashr_i32 s1, s0, 31
	v_lshl_add_u64 v[0:1], s[0:1], 1, v[0:1]
	s_waitcnt lgkmcnt(3)
	v_cvt_pk_bf16_f32 v4, v4, v5
	s_waitcnt lgkmcnt(2)
	v_cvt_pk_bf16_f32 v5, v6, v7
	s_waitcnt lgkmcnt(1)
	v_cvt_pk_bf16_f32 v6, v8, v9
	s_waitcnt lgkmcnt(0)
	v_cvt_pk_bf16_f32 v7, v10, v11
	v_lshl_add_u64 v[0:1], v[0:1], 0, v[16:17]
	global_store_dwordx4 v[0:1], v[4:7], off sc1
.LBB0_911:
	s_or_b64 exec, exec, s[4:5]
	s_cmpk_lt_i32 s35, 0x100
	s_cselect_b64 s[0:1], -1, 0
	s_ashr_i32 s4, s35, 31
	s_lshr_b32 s4, s4, 28
	s_add_i32 s4, s35, s4
	s_and_b32 s5, s4, 0x3fffff0
	s_sub_i32 s5, s35, s5
	v_lshl_add_u32 v0, s5, 6, v3
	v_cmp_gt_i32_e32 vcc, s17, v0
	s_and_b64 s[40:41], s[0:1], vcc
	s_and_saveexec_b64 s[0:1], s[40:41]
	s_cbranch_execz .LBB0_900
	v_add_u32_e32 v1, 0x4000, v2
	ds_read2_b32 v[4:5], v1 offset0:64 offset1:129
	v_add_u32_e32 v1, 0x4200, v2
	ds_read2_b32 v[6:7], v1 offset0:66 offset1:131
	v_add_u32_e32 v1, 0x4400, v2
	ds_read2_b32 v[8:9], v1 offset0:68 offset1:133
	v_add_u32_e32 v1, 0x4600, v2
	ds_read2_b32 v[10:11], v1 offset0:70 offset1:135
	s_ashr_i32 s4, s4, 4
	v_ashrrev_i32_e32 v1, 31, v0
	s_lshl_b32 s4, s4, 6
	v_lshlrev_b64 v[0:1], 11, v[0:1]
	v_lshl_add_u64 v[0:1], s[8:9], 0, v[0:1]
	s_ashr_i32 s5, s4, 31
	v_lshl_add_u64 v[0:1], s[4:5], 1, v[0:1]
	s_waitcnt lgkmcnt(3)
	v_cvt_pk_bf16_f32 v2, v4, v5
	s_waitcnt lgkmcnt(2)
	v_cvt_pk_bf16_f32 v3, v6, v7
	s_waitcnt lgkmcnt(1)
	v_cvt_pk_bf16_f32 v4, v8, v9
	s_waitcnt lgkmcnt(0)
	v_cvt_pk_bf16_f32 v5, v10, v11
	v_lshl_add_u64 v[0:1], v[0:1], 0, v[16:17]
	global_store_dwordx4 v[0:1], v[2:5], off sc1
	s_branch .LBB0_900

.LBB0_923:
	s_or_b64 exec, exec, s[4:5]
	v_mul_lo_u32 v18, v23, s19
	v_add3_u32 v16, 0, v16, v18
	s_waitcnt vmcnt(0)
	ds_write2_b32 v16, v0, v1 offset1:1
	ds_write2_b32 v16, v2, v3 offset0:2 offset1:3
	v_add_u32_e32 v0, 0x2080, v16
	ds_write2_b32 v0, v8, v9 offset1:1
	v_add_u32_e32 v0, 0x2088, v16
	ds_write2_b32 v0, v10, v11 offset1:1
	v_add_u32_e32 v0, 0x4100, v16
	ds_write2_b32 v0, v4, v5 offset1:1
	v_add_u32_e32 v0, 0x4108, v16
	ds_write2_b32 v0, v6, v7 offset1:1
	v_add_u32_e32 v0, 0x6180, v16
	ds_write2_b32 v0, v12, v13 offset1:1
	v_add_u32_e32 v0, 0x6188, v16
	ds_write2_b32 v0, v14, v15 offset1:1
	v_ashrrev_i32_e32 v3, 3, v22
	v_lshlrev_b32_e32 v0, 3, v22
	v_and_b32_e32 v1, 56, v0
	v_subrev_u32_e32 v0, s1, v3
	v_lshl_add_u32 v2, v3, 2, 0
	v_add_u32_e32 v0, s13, v0
	v_cmp_gt_i32_e32 vcc, s17, v0
	v_mad_u32_u24 v2, v1, s19, v2
	v_lshlrev_b32_e32 v16, 1, v1
	s_waitcnt lgkmcnt(0)
	s_barrier
	s_and_saveexec_b64 s[4:5], vcc
	s_cbranch_execz .LBB0_925
	v_add_u32_e32 v1, 0x400, v2
	ds_read2_b32 v[4:5], v2 offset1:65
	ds_read2_b32 v[6:7], v2 offset0:130 offset1:195
	ds_read2_b32 v[8:9], v1 offset0:4 offset1:69
	ds_read2_b32 v[10:11], v1 offset0:134 offset1:199
	v_ashrrev_i32_e32 v1, 31, v0
	v_lshlrev_b64 v[0:1], 11, v[0:1]
	v_lshl_add_u64 v[0:1], s[6:7], 0, v[0:1]
	s_ashr_i32 s1, s0, 31
	v_lshl_add_u64 v[0:1], s[0:1], 1, v[0:1]
	s_waitcnt lgkmcnt(3)
	v_cvt_pk_bf16_f32 v4, v4, v5
	s_waitcnt lgkmcnt(2)
	v_cvt_pk_bf16_f32 v5, v6, v7
	s_waitcnt lgkmcnt(1)
	v_cvt_pk_bf16_f32 v6, v8, v9
	s_waitcnt lgkmcnt(0)
	v_cvt_pk_bf16_f32 v7, v10, v11
	v_lshl_add_u64 v[0:1], v[0:1], 0, v[16:17]
	global_store_dwordx4 v[0:1], v[4:7], off sc1
.LBB0_925:
	s_or_b64 exec, exec, s[4:5]
	s_cmpk_lt_i32 s28, 0x100
	s_cselect_b64 s[0:1], -1, 0
	s_ashr_i32 s4, s28, 31
	s_lshr_b32 s4, s4, 28
	s_add_i32 s4, s28, s4
	s_and_b32 s5, s4, 0x3fffff0
	s_sub_i32 s5, s28, s5
	v_lshl_add_u32 v0, s5, 6, v3
	v_cmp_gt_i32_e32 vcc, s17, v0
	s_and_b64 s[28:29], s[0:1], vcc
	s_and_saveexec_b64 s[0:1], s[28:29]
	s_cbranch_execz .LBB0_914
	v_add_u32_e32 v1, 0x4000, v2
	ds_read2_b32 v[4:5], v1 offset0:64 offset1:129
	v_add_u32_e32 v1, 0x4200, v2
	ds_read2_b32 v[6:7], v1 offset0:66 offset1:131
	v_add_u32_e32 v1, 0x4400, v2
	ds_read2_b32 v[8:9], v1 offset0:68 offset1:133
	v_add_u32_e32 v1, 0x4600, v2
	ds_read2_b32 v[10:11], v1 offset0:70 offset1:135
	s_ashr_i32 s4, s4, 4
	v_ashrrev_i32_e32 v1, 31, v0
	s_lshl_b32 s4, s4, 6
	v_lshlrev_b64 v[0:1], 11, v[0:1]
	v_lshl_add_u64 v[0:1], s[6:7], 0, v[0:1]
	s_ashr_i32 s5, s4, 31
	v_lshl_add_u64 v[0:1], s[4:5], 1, v[0:1]
	s_waitcnt lgkmcnt(3)
	v_cvt_pk_bf16_f32 v2, v4, v5
	s_waitcnt lgkmcnt(2)
	v_cvt_pk_bf16_f32 v3, v6, v7
	s_waitcnt lgkmcnt(1)
	v_cvt_pk_bf16_f32 v4, v8, v9
	s_waitcnt lgkmcnt(0)
	v_cvt_pk_bf16_f32 v5, v10, v11
	v_lshl_add_u64 v[0:1], v[0:1], 0, v[16:17]
	global_store_dwordx4 v[0:1], v[2:5], off sc1
	s_branch .LBB0_914

.LBB0_931:
	v_add_co_u32_e32 v12, vcc, 0xc00000, v12
	s_nop 1
	v_addc_co_u32_e32 v13, vcc, 0, v13, vcc
	global_load_dword v132, v[12:13], off nt
	v_add_co_u32_e32 v12, vcc, 0x3000, v12
	s_nop 1
	v_addc_co_u32_e32 v13, vcc, 0, v13, vcc
	global_load_dword v133, v[12:13], off nt
	v_add_co_u32_e32 v12, vcc, 0x3000, v12
	s_nop 1
	v_addc_co_u32_e32 v13, vcc, 0, v13, vcc
	global_load_dword v134, v[12:13], off nt
	v_add_co_u32_e32 v12, vcc, 0x3000, v12
	s_nop 1
	v_addc_co_u32_e32 v13, vcc, 0, v13, vcc
	global_load_dword v135, v[12:13], off nt
	v_add_co_u32_e32 v12, vcc, 0x3000, v12
	s_nop 1
	v_addc_co_u32_e32 v13, vcc, 0, v13, vcc
	global_load_dword v136, v[12:13], off nt
	v_add_co_u32_e32 v12, vcc, 0x3000, v12
	s_nop 1
	v_addc_co_u32_e32 v13, vcc, 0, v13, vcc
	global_load_dword v137, v[12:13], off nt
	v_add_co_u32_e32 v12, vcc, 0x3000, v12
	s_nop 1
	v_addc_co_u32_e32 v13, vcc, 0, v13, vcc
	global_load_dword v138, v[12:13], off nt
	v_add_co_u32_e32 v12, vcc, 0x3000, v12
	s_nop 1
	v_addc_co_u32_e32 v13, vcc, 0, v13, vcc
	global_load_dword v139, v[12:13], off nt
	v_add_co_u32_e32 v12, vcc, 0x3000, v12
	s_nop 1
	v_addc_co_u32_e32 v13, vcc, 0, v13, vcc
	global_load_dword v140, v[12:13], off nt
	v_add_co_u32_e32 v12, vcc, 0x3000, v12
	s_nop 1
	v_addc_co_u32_e32 v13, vcc, 0, v13, vcc
	global_load_dword v141, v[12:13], off nt
	v_add_co_u32_e32 v12, vcc, 0x3000, v12
	s_nop 1
	v_addc_co_u32_e32 v13, vcc, 0, v13, vcc
	global_load_dword v142, v[12:13], off nt
	v_add_co_u32_e32 v12, vcc, 0x3000, v12
	s_nop 1
	v_addc_co_u32_e32 v13, vcc, 0, v13, vcc
	global_load_dword v143, v[12:13], off nt
	v_add_co_u32_e32 v12, vcc, 0x3000, v12
	s_nop 1
	v_addc_co_u32_e32 v13, vcc, 0, v13, vcc
	global_load_dword v144, v[12:13], off nt
	v_add_co_u32_e32 v12, vcc, 0x3000, v12
	s_nop 1
	v_addc_co_u32_e32 v13, vcc, 0, v13, vcc
	global_load_dword v145, v[12:13], off nt
	v_add_co_u32_e32 v12, vcc, 0x3000, v12
	s_nop 1
	v_addc_co_u32_e32 v13, vcc, 0, v13, vcc
	global_load_dword v146, v[12:13], off nt
	v_add_co_u32_e32 v12, vcc, 0x3000, v12
	s_nop 1
	v_addc_co_u32_e32 v13, vcc, 0, v13, vcc
	global_load_dword v147, v[12:13], off nt
	v_add_co_u32_e32 v12, vcc, 0x3000, v12
	s_nop 1
	v_addc_co_u32_e32 v13, vcc, 0, v13, vcc
	global_load_dword v148, v[12:13], off nt
	v_add_co_u32_e32 v12, vcc, 0x3000, v12
	s_nop 1
	v_addc_co_u32_e32 v13, vcc, 0, v13, vcc
	global_load_dword v149, v[12:13], off nt
	v_add_co_u32_e32 v12, vcc, 0x3000, v12
	s_nop 1
	v_addc_co_u32_e32 v13, vcc, 0, v13, vcc
	global_load_dword v150, v[12:13], off nt
	v_add_co_u32_e32 v12, vcc, 0x3000, v12
	s_nop 1
	v_addc_co_u32_e32 v13, vcc, 0, v13, vcc
	global_load_dword v151, v[12:13], off nt
	v_add_co_u32_e32 v12, vcc, 0x3000, v12
	s_nop 1
	v_addc_co_u32_e32 v13, vcc, 0, v13, vcc
	global_load_dword v152, v[12:13], off nt
	v_add_co_u32_e32 v12, vcc, 0x3000, v12
	s_nop 1
	v_addc_co_u32_e32 v13, vcc, 0, v13, vcc
	global_load_dword v153, v[12:13], off nt
	v_add_co_u32_e32 v12, vcc, 0x3000, v12
	s_nop 1
	v_addc_co_u32_e32 v13, vcc, 0, v13, vcc
	global_load_dword v154, v[12:13], off nt
	v_add_co_u32_e32 v12, vcc, 0x3000, v12
	s_nop 1
	v_addc_co_u32_e32 v13, vcc, 0, v13, vcc
	global_load_dword v155, v[12:13], off nt
	v_add_co_u32_e32 v12, vcc, 0x3000, v12
	s_nop 1
	v_addc_co_u32_e32 v13, vcc, 0, v13, vcc
	global_load_dword v156, v[12:13], off nt
	v_add_co_u32_e32 v12, vcc, 0x3000, v12
	s_nop 1
	v_addc_co_u32_e32 v13, vcc, 0, v13, vcc
	global_load_dword v157, v[12:13], off nt
	v_add_co_u32_e32 v12, vcc, 0x3000, v12
	s_nop 1
	v_addc_co_u32_e32 v13, vcc, 0, v13, vcc
	global_load_dword v158, v[12:13], off nt
	v_add_co_u32_e32 v12, vcc, 0x3000, v12
	s_nop 1
	v_addc_co_u32_e32 v13, vcc, 0, v13, vcc
	global_load_dword v159, v[12:13], off nt
	v_add_co_u32_e32 v12, vcc, 0x3000, v12
	s_nop 1
	v_addc_co_u32_e32 v13, vcc, 0, v13, vcc
	global_load_dword v160, v[12:13], off nt
	v_add_co_u32_e32 v12, vcc, 0x3000, v12
	s_nop 1
	v_addc_co_u32_e32 v13, vcc, 0, v13, vcc
	global_load_dword v161, v[12:13], off nt
	v_add_co_u32_e32 v12, vcc, 0x3000, v12
	s_nop 1
	v_addc_co_u32_e32 v13, vcc, 0, v13, vcc
	global_load_dword v162, v[12:13], off nt
	v_add_co_u32_e32 v12, vcc, 0x3000, v12
	s_nop 1
	v_addc_co_u32_e32 v13, vcc, 0, v13, vcc
	global_load_dword v163, v[12:13], off nt
	v_add_co_u32_e32 v12, vcc, 0x3000, v12
	s_nop 1
	v_addc_co_u32_e32 v13, vcc, 0, v13, vcc
	global_load_dword v164, v[12:13], off nt
	v_add_co_u32_e32 v12, vcc, 0x3000, v12
	s_nop 1
	v_addc_co_u32_e32 v13, vcc, 0, v13, vcc
	global_load_dword v165, v[12:13], off nt
	v_add_co_u32_e32 v12, vcc, 0x3000, v12
	s_nop 1
	v_addc_co_u32_e32 v13, vcc, 0, v13, vcc
	global_load_dword v166, v[12:13], off nt
	v_add_co_u32_e32 v12, vcc, 0x3000, v12
	s_nop 1
	v_addc_co_u32_e32 v13, vcc, 0, v13, vcc
	global_load_dword v167, v[12:13], off nt
	v_add_co_u32_e32 v12, vcc, 0x3000, v12
	s_nop 1
	v_addc_co_u32_e32 v13, vcc, 0, v13, vcc
	global_load_dword v168, v[12:13], off nt
	v_add_co_u32_e32 v12, vcc, 0x3000, v12
	s_nop 1
	v_addc_co_u32_e32 v13, vcc, 0, v13, vcc
	global_load_dword v169, v[12:13], off nt
	v_add_co_u32_e32 v12, vcc, 0x3000, v12
	s_nop 1
	v_addc_co_u32_e32 v13, vcc, 0, v13, vcc
	global_load_dword v170, v[12:13], off nt
	v_add_co_u32_e32 v12, vcc, 0x3000, v12
	s_nop 1
	v_addc_co_u32_e32 v13, vcc, 0, v13, vcc
	global_load_dword v171, v[12:13], off nt
	v_add_co_u32_e32 v12, vcc, 0x3000, v12
	s_nop 1
	v_addc_co_u32_e32 v13, vcc, 0, v13, vcc
	global_load_dword v172, v[12:13], off nt
	v_add_co_u32_e32 v12, vcc, 0x3000, v12
	s_nop 1
	v_addc_co_u32_e32 v13, vcc, 0, v13, vcc
	global_load_dword v173, v[12:13], off nt
	v_add_co_u32_e32 v12, vcc, 0x3000, v12
	s_nop 1
	v_addc_co_u32_e32 v13, vcc, 0, v13, vcc
	global_load_dword v174, v[12:13], off nt
	v_add_co_u32_e32 v12, vcc, 0x3000, v12
	s_nop 1
	v_addc_co_u32_e32 v13, vcc, 0, v13, vcc
	global_load_dword v175, v[12:13], off nt
	v_add_co_u32_e32 v12, vcc, 0x3000, v12
	s_nop 1
	v_addc_co_u32_e32 v13, vcc, 0, v13, vcc
	global_load_dword v176, v[12:13], off nt
	v_add_co_u32_e32 v12, vcc, 0x3000, v12
	s_nop 1
	v_addc_co_u32_e32 v13, vcc, 0, v13, vcc
	global_load_dword v177, v[12:13], off nt
	v_add_co_u32_e32 v12, vcc, 0x3000, v12
	s_nop 1
	v_addc_co_u32_e32 v13, vcc, 0, v13, vcc
	global_load_dword v178, v[12:13], off nt
	v_add_co_u32_e32 v12, vcc, 0x3000, v12
	s_nop 1
	v_addc_co_u32_e32 v13, vcc, 0, v13, vcc
	global_load_dword v179, v[12:13], off nt
	v_add_co_u32_e32 v12, vcc, 0x3000, v12
	s_nop 1
	v_addc_co_u32_e32 v13, vcc, 0, v13, vcc
	global_load_dword v180, v[12:13], off nt
	v_add_co_u32_e32 v12, vcc, 0x3000, v12
	s_nop 1
	v_addc_co_u32_e32 v13, vcc, 0, v13, vcc
	global_load_dword v181, v[12:13], off nt
	v_add_co_u32_e32 v12, vcc, 0x3000, v12
	s_nop 1
	v_addc_co_u32_e32 v13, vcc, 0, v13, vcc
	global_load_dword v182, v[12:13], off nt
	v_add_co_u32_e32 v12, vcc, 0x3000, v12
	s_nop 1
	v_addc_co_u32_e32 v13, vcc, 0, v13, vcc
	global_load_dword v183, v[12:13], off nt
	v_add_co_u32_e32 v12, vcc, 0x3000, v12
	s_nop 1
	v_addc_co_u32_e32 v13, vcc, 0, v13, vcc
	global_load_dword v184, v[12:13], off nt
	v_add_co_u32_e32 v12, vcc, 0x3000, v12
	s_nop 1
	v_addc_co_u32_e32 v13, vcc, 0, v13, vcc
	global_load_dword v185, v[12:13], off nt
	v_add_co_u32_e32 v12, vcc, 0x3000, v12
	s_nop 1
	v_addc_co_u32_e32 v13, vcc, 0, v13, vcc
	global_load_dword v186, v[12:13], off nt
	v_add_co_u32_e32 v12, vcc, 0x3000, v12
	s_nop 1
	v_addc_co_u32_e32 v13, vcc, 0, v13, vcc
	global_load_dword v187, v[12:13], off nt
	v_add_co_u32_e32 v12, vcc, 0x3000, v12
	s_nop 1
	v_addc_co_u32_e32 v13, vcc, 0, v13, vcc
	global_load_dword v188, v[12:13], off nt
	v_add_co_u32_e32 v12, vcc, 0x3000, v12
	s_nop 1
	v_addc_co_u32_e32 v13, vcc, 0, v13, vcc
	global_load_dword v189, v[12:13], off nt
	v_add_co_u32_e32 v12, vcc, 0x3000, v12
	s_nop 1
	v_addc_co_u32_e32 v13, vcc, 0, v13, vcc
	global_load_dword v190, v[12:13], off nt
	v_add_co_u32_e32 v12, vcc, 0x3000, v12
	s_nop 1
	v_addc_co_u32_e32 v13, vcc, 0, v13, vcc
	global_load_dword v191, v[12:13], off nt
	v_add_co_u32_e32 v12, vcc, 0x3000, v12
	s_nop 1
	v_addc_co_u32_e32 v13, vcc, 0, v13, vcc
	global_load_dword v192, v[12:13], off nt
	v_add_co_u32_e32 v12, vcc, 0x3000, v12
	s_nop 1
	v_addc_co_u32_e32 v13, vcc, 0, v13, vcc
	global_load_dword v193, v[12:13], off nt
	v_add_co_u32_e32 v12, vcc, 0x3000, v12
	s_nop 1
	v_addc_co_u32_e32 v13, vcc, 0, v13, vcc
	global_load_dword v194, v[12:13], off nt
	v_add_co_u32_e32 v12, vcc, 0x3000, v12
	s_nop 1
	v_addc_co_u32_e32 v13, vcc, 0, v13, vcc
	global_load_dword v195, v[12:13], off nt
	v_readlane_b32 s42, v0, 0
	v_readlane_b32 s43, v22, 0
	v_readlane_b32 s52, v23, 0
	v_readlane_b32 s53, v24, 0
	v_readlane_b32 s56, v25, 0
	s_waitcnt vmcnt(63)
	v_pk_fma_f32 v[10:11], v[132:133], s[42:43], v[10:11] op_sel_hi:[0,1,1]
	v_pk_fma_f32 v[8:9], v[132:133], s[52:53], v[8:9] op_sel_hi:[0,1,1]
	v_fmac_f32_e32 v21, s56, v132
	v_readlane_b32 s42, v0, 1
	v_readlane_b32 s43, v22, 1
	v_readlane_b32 s52, v23, 1
	v_readlane_b32 s53, v24, 1
	v_readlane_b32 s56, v25, 1
	s_waitcnt vmcnt(62)
	v_pk_fma_f32 v[10:11], v[132:133], s[42:43], v[10:11] op_sel:[1,0,0] op_sel_hi:[1,1,1]
	v_pk_fma_f32 v[8:9], v[132:133], s[52:53], v[8:9] op_sel:[1,0,0] op_sel_hi:[1,1,1]
	v_fmac_f32_e32 v21, s56, v133
	v_readlane_b32 s42, v0, 2
	v_readlane_b32 s43, v22, 2
	v_readlane_b32 s52, v23, 2
	v_readlane_b32 s53, v24, 2
	v_readlane_b32 s56, v25, 2
	s_waitcnt vmcnt(61)
	v_pk_fma_f32 v[10:11], v[134:135], s[42:43], v[10:11] op_sel_hi:[0,1,1]
	v_pk_fma_f32 v[8:9], v[134:135], s[52:53], v[8:9] op_sel_hi:[0,1,1]
	v_fmac_f32_e32 v21, s56, v134
	v_readlane_b32 s42, v0, 3
	v_readlane_b32 s43, v22, 3
	v_readlane_b32 s52, v23, 3
	v_readlane_b32 s53, v24, 3
	v_readlane_b32 s56, v25, 3
	s_waitcnt vmcnt(60)
	v_pk_fma_f32 v[10:11], v[134:135], s[42:43], v[10:11] op_sel:[1,0,0] op_sel_hi:[1,1,1]
	v_pk_fma_f32 v[8:9], v[134:135], s[52:53], v[8:9] op_sel:[1,0,0] op_sel_hi:[1,1,1]
	v_fmac_f32_e32 v21, s56, v135
	v_readlane_b32 s42, v0, 4
	v_readlane_b32 s43, v22, 4
	v_readlane_b32 s52, v23, 4
	v_readlane_b32 s53, v24, 4
	v_readlane_b32 s56, v25, 4
	s_waitcnt vmcnt(59)
	v_pk_fma_f32 v[10:11], v[136:137], s[42:43], v[10:11] op_sel_hi:[0,1,1]
	v_pk_fma_f32 v[8:9], v[136:137], s[52:53], v[8:9] op_sel_hi:[0,1,1]
	v_fmac_f32_e32 v21, s56, v136
	v_readlane_b32 s42, v0, 5
	v_readlane_b32 s43, v22, 5
	v_readlane_b32 s52, v23, 5
	v_readlane_b32 s53, v24, 5
	v_readlane_b32 s56, v25, 5
	s_waitcnt vmcnt(58)
	v_pk_fma_f32 v[10:11], v[136:137], s[42:43], v[10:11] op_sel:[1,0,0] op_sel_hi:[1,1,1]
	v_pk_fma_f32 v[8:9], v[136:137], s[52:53], v[8:9] op_sel:[1,0,0] op_sel_hi:[1,1,1]
	v_fmac_f32_e32 v21, s56, v137
	v_readlane_b32 s42, v0, 6
	v_readlane_b32 s43, v22, 6
	v_readlane_b32 s52, v23, 6
	v_readlane_b32 s53, v24, 6
	v_readlane_b32 s56, v25, 6
	s_waitcnt vmcnt(57)
	v_pk_fma_f32 v[10:11], v[138:139], s[42:43], v[10:11] op_sel_hi:[0,1,1]
	v_pk_fma_f32 v[8:9], v[138:139], s[52:53], v[8:9] op_sel_hi:[0,1,1]
	v_fmac_f32_e32 v21, s56, v138
	v_readlane_b32 s42, v0, 7
	v_readlane_b32 s43, v22, 7
	v_readlane_b32 s52, v23, 7
	v_readlane_b32 s53, v24, 7
	v_readlane_b32 s56, v25, 7
	s_waitcnt vmcnt(56)
	v_pk_fma_f32 v[10:11], v[138:139], s[42:43], v[10:11] op_sel:[1,0,0] op_sel_hi:[1,1,1]
	v_pk_fma_f32 v[8:9], v[138:139], s[52:53], v[8:9] op_sel:[1,0,0] op_sel_hi:[1,1,1]
	v_fmac_f32_e32 v21, s56, v139
	v_readlane_b32 s42, v0, 8
	v_readlane_b32 s43, v22, 8
	v_readlane_b32 s52, v23, 8
	v_readlane_b32 s53, v24, 8
	v_readlane_b32 s56, v25, 8
	s_waitcnt vmcnt(55)
	v_pk_fma_f32 v[10:11], v[140:141], s[42:43], v[10:11] op_sel_hi:[0,1,1]
	v_pk_fma_f32 v[8:9], v[140:141], s[52:53], v[8:9] op_sel_hi:[0,1,1]
	v_fmac_f32_e32 v21, s56, v140
	v_readlane_b32 s42, v0, 9
	v_readlane_b32 s43, v22, 9
	v_readlane_b32 s52, v23, 9
	v_readlane_b32 s53, v24, 9
	v_readlane_b32 s56, v25, 9
	s_waitcnt vmcnt(54)
	v_pk_fma_f32 v[10:11], v[140:141], s[42:43], v[10:11] op_sel:[1,0,0] op_sel_hi:[1,1,1]
	v_pk_fma_f32 v[8:9], v[140:141], s[52:53], v[8:9] op_sel:[1,0,0] op_sel_hi:[1,1,1]
	v_fmac_f32_e32 v21, s56, v141
	v_readlane_b32 s42, v0, 10
	v_readlane_b32 s43, v22, 10
	v_readlane_b32 s52, v23, 10
	v_readlane_b32 s53, v24, 10
	v_readlane_b32 s56, v25, 10
	s_waitcnt vmcnt(53)
	v_pk_fma_f32 v[10:11], v[142:143], s[42:43], v[10:11] op_sel_hi:[0,1,1]
	v_pk_fma_f32 v[8:9], v[142:143], s[52:53], v[8:9] op_sel_hi:[0,1,1]
	v_fmac_f32_e32 v21, s56, v142
	v_readlane_b32 s42, v0, 11
	v_readlane_b32 s43, v22, 11
	v_readlane_b32 s52, v23, 11
	v_readlane_b32 s53, v24, 11
	v_readlane_b32 s56, v25, 11
	s_waitcnt vmcnt(52)
	v_pk_fma_f32 v[10:11], v[142:143], s[42:43], v[10:11] op_sel:[1,0,0] op_sel_hi:[1,1,1]
	v_pk_fma_f32 v[8:9], v[142:143], s[52:53], v[8:9] op_sel:[1,0,0] op_sel_hi:[1,1,1]
	v_fmac_f32_e32 v21, s56, v143
	v_readlane_b32 s42, v0, 12
	v_readlane_b32 s43, v22, 12
	v_readlane_b32 s52, v23, 12
	v_readlane_b32 s53, v24, 12
	v_readlane_b32 s56, v25, 12
	s_waitcnt vmcnt(51)
	v_pk_fma_f32 v[10:11], v[144:145], s[42:43], v[10:11] op_sel_hi:[0,1,1]
	v_pk_fma_f32 v[8:9], v[144:145], s[52:53], v[8:9] op_sel_hi:[0,1,1]
	v_fmac_f32_e32 v21, s56, v144
	v_readlane_b32 s42, v0, 13
	v_readlane_b32 s43, v22, 13
	v_readlane_b32 s52, v23, 13
	v_readlane_b32 s53, v24, 13
	v_readlane_b32 s56, v25, 13
	s_waitcnt vmcnt(50)
	v_pk_fma_f32 v[10:11], v[144:145], s[42:43], v[10:11] op_sel:[1,0,0] op_sel_hi:[1,1,1]
	v_pk_fma_f32 v[8:9], v[144:145], s[52:53], v[8:9] op_sel:[1,0,0] op_sel_hi:[1,1,1]
	v_fmac_f32_e32 v21, s56, v145
	v_readlane_b32 s42, v0, 14
	v_readlane_b32 s43, v22, 14
	v_readlane_b32 s52, v23, 14
	v_readlane_b32 s53, v24, 14
	v_readlane_b32 s56, v25, 14
	s_waitcnt vmcnt(49)
	v_pk_fma_f32 v[10:11], v[146:147], s[42:43], v[10:11] op_sel_hi:[0,1,1]
	v_pk_fma_f32 v[8:9], v[146:147], s[52:53], v[8:9] op_sel_hi:[0,1,1]
	v_fmac_f32_e32 v21, s56, v146
	v_readlane_b32 s42, v0, 15
	v_readlane_b32 s43, v22, 15
	v_readlane_b32 s52, v23, 15
	v_readlane_b32 s53, v24, 15
	v_readlane_b32 s56, v25, 15
	s_waitcnt vmcnt(48)
	v_pk_fma_f32 v[10:11], v[146:147], s[42:43], v[10:11] op_sel:[1,0,0] op_sel_hi:[1,1,1]
	v_pk_fma_f32 v[8:9], v[146:147], s[52:53], v[8:9] op_sel:[1,0,0] op_sel_hi:[1,1,1]
	v_fmac_f32_e32 v21, s56, v147
	v_readlane_b32 s42, v0, 16
	v_readlane_b32 s43, v22, 16
	v_readlane_b32 s52, v23, 16
	v_readlane_b32 s53, v24, 16
	v_readlane_b32 s56, v25, 16
	s_waitcnt vmcnt(47)
	v_pk_fma_f32 v[10:11], v[148:149], s[42:43], v[10:11] op_sel_hi:[0,1,1]
	v_pk_fma_f32 v[8:9], v[148:149], s[52:53], v[8:9] op_sel_hi:[0,1,1]
	v_fmac_f32_e32 v21, s56, v148
	v_readlane_b32 s42, v0, 17
	v_readlane_b32 s43, v22, 17
	v_readlane_b32 s52, v23, 17
	v_readlane_b32 s53, v24, 17
	v_readlane_b32 s56, v25, 17
	s_waitcnt vmcnt(46)
	v_pk_fma_f32 v[10:11], v[148:149], s[42:43], v[10:11] op_sel:[1,0,0] op_sel_hi:[1,1,1]
	v_pk_fma_f32 v[8:9], v[148:149], s[52:53], v[8:9] op_sel:[1,0,0] op_sel_hi:[1,1,1]
	v_fmac_f32_e32 v21, s56, v149
	v_readlane_b32 s42, v0, 18
	v_readlane_b32 s43, v22, 18
	v_readlane_b32 s52, v23, 18
	v_readlane_b32 s53, v24, 18
	v_readlane_b32 s56, v25, 18
	s_waitcnt vmcnt(45)
	v_pk_fma_f32 v[10:11], v[150:151], s[42:43], v[10:11] op_sel_hi:[0,1,1]
	v_pk_fma_f32 v[8:9], v[150:151], s[52:53], v[8:9] op_sel_hi:[0,1,1]
	v_fmac_f32_e32 v21, s56, v150
	v_readlane_b32 s42, v0, 19
	v_readlane_b32 s43, v22, 19
	v_readlane_b32 s52, v23, 19
	v_readlane_b32 s53, v24, 19
	v_readlane_b32 s56, v25, 19
	s_waitcnt vmcnt(44)
	v_pk_fma_f32 v[10:11], v[150:151], s[42:43], v[10:11] op_sel:[1,0,0] op_sel_hi:[1,1,1]
	v_pk_fma_f32 v[8:9], v[150:151], s[52:53], v[8:9] op_sel:[1,0,0] op_sel_hi:[1,1,1]
	v_fmac_f32_e32 v21, s56, v151
	v_readlane_b32 s42, v0, 20
	v_readlane_b32 s43, v22, 20
	v_readlane_b32 s52, v23, 20
	v_readlane_b32 s53, v24, 20
	v_readlane_b32 s56, v25, 20
	s_waitcnt vmcnt(43)
	v_pk_fma_f32 v[10:11], v[152:153], s[42:43], v[10:11] op_sel_hi:[0,1,1]
	v_pk_fma_f32 v[8:9], v[152:153], s[52:53], v[8:9] op_sel_hi:[0,1,1]
	v_fmac_f32_e32 v21, s56, v152
	v_readlane_b32 s42, v0, 21
	v_readlane_b32 s43, v22, 21
	v_readlane_b32 s52, v23, 21
	v_readlane_b32 s53, v24, 21
	v_readlane_b32 s56, v25, 21
	s_waitcnt vmcnt(42)
	v_pk_fma_f32 v[10:11], v[152:153], s[42:43], v[10:11] op_sel:[1,0,0] op_sel_hi:[1,1,1]
	v_pk_fma_f32 v[8:9], v[152:153], s[52:53], v[8:9] op_sel:[1,0,0] op_sel_hi:[1,1,1]
	v_fmac_f32_e32 v21, s56, v153
	v_readlane_b32 s42, v0, 22
	v_readlane_b32 s43, v22, 22
	v_readlane_b32 s52, v23, 22
	v_readlane_b32 s53, v24, 22
	v_readlane_b32 s56, v25, 22
	s_waitcnt vmcnt(41)
	v_pk_fma_f32 v[10:11], v[154:155], s[42:43], v[10:11] op_sel_hi:[0,1,1]
	v_pk_fma_f32 v[8:9], v[154:155], s[52:53], v[8:9] op_sel_hi:[0,1,1]
	v_fmac_f32_e32 v21, s56, v154
	v_readlane_b32 s42, v0, 23
	v_readlane_b32 s43, v22, 23
	v_readlane_b32 s52, v23, 23
	v_readlane_b32 s53, v24, 23
	v_readlane_b32 s56, v25, 23
	s_waitcnt vmcnt(40)
	v_pk_fma_f32 v[10:11], v[154:155], s[42:43], v[10:11] op_sel:[1,0,0] op_sel_hi:[1,1,1]
	v_pk_fma_f32 v[8:9], v[154:155], s[52:53], v[8:9] op_sel:[1,0,0] op_sel_hi:[1,1,1]
	v_fmac_f32_e32 v21, s56, v155
	v_readlane_b32 s42, v0, 24
	v_readlane_b32 s43, v22, 24
	v_readlane_b32 s52, v23, 24
	v_readlane_b32 s53, v24, 24
	v_readlane_b32 s56, v25, 24
	s_waitcnt vmcnt(39)
	v_pk_fma_f32 v[10:11], v[156:157], s[42:43], v[10:11] op_sel_hi:[0,1,1]
	v_pk_fma_f32 v[8:9], v[156:157], s[52:53], v[8:9] op_sel_hi:[0,1,1]
	v_fmac_f32_e32 v21, s56, v156
	v_readlane_b32 s42, v0, 25
	v_readlane_b32 s43, v22, 25
	v_readlane_b32 s52, v23, 25
	v_readlane_b32 s53, v24, 25
	v_readlane_b32 s56, v25, 25
	s_waitcnt vmcnt(38)
	v_pk_fma_f32 v[10:11], v[156:157], s[42:43], v[10:11] op_sel:[1,0,0] op_sel_hi:[1,1,1]
	v_pk_fma_f32 v[8:9], v[156:157], s[52:53], v[8:9] op_sel:[1,0,0] op_sel_hi:[1,1,1]
	v_fmac_f32_e32 v21, s56, v157
	v_readlane_b32 s42, v0, 26
	v_readlane_b32 s43, v22, 26
	v_readlane_b32 s52, v23, 26
	v_readlane_b32 s53, v24, 26
	v_readlane_b32 s56, v25, 26
	s_waitcnt vmcnt(37)
	v_pk_fma_f32 v[10:11], v[158:159], s[42:43], v[10:11] op_sel_hi:[0,1,1]
	v_pk_fma_f32 v[8:9], v[158:159], s[52:53], v[8:9] op_sel_hi:[0,1,1]
	v_fmac_f32_e32 v21, s56, v158
	v_readlane_b32 s42, v0, 27
	v_readlane_b32 s43, v22, 27
	v_readlane_b32 s52, v23, 27
	v_readlane_b32 s53, v24, 27
	v_readlane_b32 s56, v25, 27
	s_waitcnt vmcnt(36)
	v_pk_fma_f32 v[10:11], v[158:159], s[42:43], v[10:11] op_sel:[1,0,0] op_sel_hi:[1,1,1]
	v_pk_fma_f32 v[8:9], v[158:159], s[52:53], v[8:9] op_sel:[1,0,0] op_sel_hi:[1,1,1]
	v_fmac_f32_e32 v21, s56, v159
	v_readlane_b32 s42, v0, 28
	v_readlane_b32 s43, v22, 28
	v_readlane_b32 s52, v23, 28
	v_readlane_b32 s53, v24, 28
	v_readlane_b32 s56, v25, 28
	s_waitcnt vmcnt(35)
	v_pk_fma_f32 v[10:11], v[160:161], s[42:43], v[10:11] op_sel_hi:[0,1,1]
	v_pk_fma_f32 v[8:9], v[160:161], s[52:53], v[8:9] op_sel_hi:[0,1,1]
	v_fmac_f32_e32 v21, s56, v160
	v_readlane_b32 s42, v0, 29
	v_readlane_b32 s43, v22, 29
	v_readlane_b32 s52, v23, 29
	v_readlane_b32 s53, v24, 29
	v_readlane_b32 s56, v25, 29
	s_waitcnt vmcnt(34)
	v_pk_fma_f32 v[10:11], v[160:161], s[42:43], v[10:11] op_sel:[1,0,0] op_sel_hi:[1,1,1]
	v_pk_fma_f32 v[8:9], v[160:161], s[52:53], v[8:9] op_sel:[1,0,0] op_sel_hi:[1,1,1]
	v_fmac_f32_e32 v21, s56, v161
	v_readlane_b32 s42, v0, 30
	v_readlane_b32 s43, v22, 30
	v_readlane_b32 s52, v23, 30
	v_readlane_b32 s53, v24, 30
	v_readlane_b32 s56, v25, 30
	s_waitcnt vmcnt(33)
	v_pk_fma_f32 v[10:11], v[162:163], s[42:43], v[10:11] op_sel_hi:[0,1,1]
	v_pk_fma_f32 v[8:9], v[162:163], s[52:53], v[8:9] op_sel_hi:[0,1,1]
	v_fmac_f32_e32 v21, s56, v162
	v_readlane_b32 s42, v0, 31
	v_readlane_b32 s43, v22, 31
	v_readlane_b32 s52, v23, 31
	v_readlane_b32 s53, v24, 31
	v_readlane_b32 s56, v25, 31
	s_waitcnt vmcnt(32)
	v_pk_fma_f32 v[10:11], v[162:163], s[42:43], v[10:11] op_sel:[1,0,0] op_sel_hi:[1,1,1]
	v_pk_fma_f32 v[8:9], v[162:163], s[52:53], v[8:9] op_sel:[1,0,0] op_sel_hi:[1,1,1]
	v_fmac_f32_e32 v21, s56, v163
	v_readlane_b32 s42, v0, 32
	v_readlane_b32 s43, v22, 32
	v_readlane_b32 s52, v23, 32
	v_readlane_b32 s53, v24, 32
	v_readlane_b32 s56, v25, 32
	s_waitcnt vmcnt(31)
	v_pk_fma_f32 v[10:11], v[164:165], s[42:43], v[10:11] op_sel_hi:[0,1,1]
	v_pk_fma_f32 v[8:9], v[164:165], s[52:53], v[8:9] op_sel_hi:[0,1,1]
	v_fmac_f32_e32 v21, s56, v164
	v_readlane_b32 s42, v0, 33
	v_readlane_b32 s43, v22, 33
	v_readlane_b32 s52, v23, 33
	v_readlane_b32 s53, v24, 33
	v_readlane_b32 s56, v25, 33
	s_waitcnt vmcnt(30)
	v_pk_fma_f32 v[10:11], v[164:165], s[42:43], v[10:11] op_sel:[1,0,0] op_sel_hi:[1,1,1]
	v_pk_fma_f32 v[8:9], v[164:165], s[52:53], v[8:9] op_sel:[1,0,0] op_sel_hi:[1,1,1]
	v_fmac_f32_e32 v21, s56, v165
	v_readlane_b32 s42, v0, 34
	v_readlane_b32 s43, v22, 34
	v_readlane_b32 s52, v23, 34
	v_readlane_b32 s53, v24, 34
	v_readlane_b32 s56, v25, 34
	s_waitcnt vmcnt(29)
	v_pk_fma_f32 v[10:11], v[166:167], s[42:43], v[10:11] op_sel_hi:[0,1,1]
	v_pk_fma_f32 v[8:9], v[166:167], s[52:53], v[8:9] op_sel_hi:[0,1,1]
	v_fmac_f32_e32 v21, s56, v166
	v_readlane_b32 s42, v0, 35
	v_readlane_b32 s43, v22, 35
	v_readlane_b32 s52, v23, 35
	v_readlane_b32 s53, v24, 35
	v_readlane_b32 s56, v25, 35
	s_waitcnt vmcnt(28)
	v_pk_fma_f32 v[10:11], v[166:167], s[42:43], v[10:11] op_sel:[1,0,0] op_sel_hi:[1,1,1]
	v_pk_fma_f32 v[8:9], v[166:167], s[52:53], v[8:9] op_sel:[1,0,0] op_sel_hi:[1,1,1]
	v_fmac_f32_e32 v21, s56, v167
	v_readlane_b32 s42, v0, 36
	v_readlane_b32 s43, v22, 36
	v_readlane_b32 s52, v23, 36
	v_readlane_b32 s53, v24, 36
	v_readlane_b32 s56, v25, 36
	s_waitcnt vmcnt(27)
	v_pk_fma_f32 v[10:11], v[168:169], s[42:43], v[10:11] op_sel_hi:[0,1,1]
	v_pk_fma_f32 v[8:9], v[168:169], s[52:53], v[8:9] op_sel_hi:[0,1,1]
	v_fmac_f32_e32 v21, s56, v168
	v_readlane_b32 s42, v0, 37
	v_readlane_b32 s43, v22, 37
	v_readlane_b32 s52, v23, 37
	v_readlane_b32 s53, v24, 37
	v_readlane_b32 s56, v25, 37
	s_waitcnt vmcnt(26)
	v_pk_fma_f32 v[10:11], v[168:169], s[42:43], v[10:11] op_sel:[1,0,0] op_sel_hi:[1,1,1]
	v_pk_fma_f32 v[8:9], v[168:169], s[52:53], v[8:9] op_sel:[1,0,0] op_sel_hi:[1,1,1]
	v_fmac_f32_e32 v21, s56, v169
	v_readlane_b32 s42, v0, 38
	v_readlane_b32 s43, v22, 38
	v_readlane_b32 s52, v23, 38
	v_readlane_b32 s53, v24, 38
	v_readlane_b32 s56, v25, 38
	s_waitcnt vmcnt(25)
	v_pk_fma_f32 v[10:11], v[170:171], s[42:43], v[10:11] op_sel_hi:[0,1,1]
	v_pk_fma_f32 v[8:9], v[170:171], s[52:53], v[8:9] op_sel_hi:[0,1,1]
	v_fmac_f32_e32 v21, s56, v170
	v_readlane_b32 s42, v0, 39
	v_readlane_b32 s43, v22, 39
	v_readlane_b32 s52, v23, 39
	v_readlane_b32 s53, v24, 39
	v_readlane_b32 s56, v25, 39
	s_waitcnt vmcnt(24)
	v_pk_fma_f32 v[10:11], v[170:171], s[42:43], v[10:11] op_sel:[1,0,0] op_sel_hi:[1,1,1]
	v_pk_fma_f32 v[8:9], v[170:171], s[52:53], v[8:9] op_sel:[1,0,0] op_sel_hi:[1,1,1]
	v_fmac_f32_e32 v21, s56, v171
	v_readlane_b32 s42, v0, 40
	v_readlane_b32 s43, v22, 40
	v_readlane_b32 s52, v23, 40
	v_readlane_b32 s53, v24, 40
	v_readlane_b32 s56, v25, 40
	s_waitcnt vmcnt(23)
	v_pk_fma_f32 v[10:11], v[172:173], s[42:43], v[10:11] op_sel_hi:[0,1,1]
	v_pk_fma_f32 v[8:9], v[172:173], s[52:53], v[8:9] op_sel_hi:[0,1,1]
	v_fmac_f32_e32 v21, s56, v172
	v_readlane_b32 s42, v0, 41
	v_readlane_b32 s43, v22, 41
	v_readlane_b32 s52, v23, 41
	v_readlane_b32 s53, v24, 41
	v_readlane_b32 s56, v25, 41
	s_waitcnt vmcnt(22)
	v_pk_fma_f32 v[10:11], v[172:173], s[42:43], v[10:11] op_sel:[1,0,0] op_sel_hi:[1,1,1]
	v_pk_fma_f32 v[8:9], v[172:173], s[52:53], v[8:9] op_sel:[1,0,0] op_sel_hi:[1,1,1]
	v_fmac_f32_e32 v21, s56, v173
	v_readlane_b32 s42, v0, 42
	v_readlane_b32 s43, v22, 42
	v_readlane_b32 s52, v23, 42
	v_readlane_b32 s53, v24, 42
	v_readlane_b32 s56, v25, 42
	s_waitcnt vmcnt(21)
	v_pk_fma_f32 v[10:11], v[174:175], s[42:43], v[10:11] op_sel_hi:[0,1,1]
	v_pk_fma_f32 v[8:9], v[174:175], s[52:53], v[8:9] op_sel_hi:[0,1,1]
	v_fmac_f32_e32 v21, s56, v174
	v_readlane_b32 s42, v0, 43
	v_readlane_b32 s43, v22, 43
	v_readlane_b32 s52, v23, 43
	v_readlane_b32 s53, v24, 43
	v_readlane_b32 s56, v25, 43
	s_waitcnt vmcnt(20)
	v_pk_fma_f32 v[10:11], v[174:175], s[42:43], v[10:11] op_sel:[1,0,0] op_sel_hi:[1,1,1]
	v_pk_fma_f32 v[8:9], v[174:175], s[52:53], v[8:9] op_sel:[1,0,0] op_sel_hi:[1,1,1]
	v_fmac_f32_e32 v21, s56, v175
	v_readlane_b32 s42, v0, 44
	v_readlane_b32 s43, v22, 44
	v_readlane_b32 s52, v23, 44
	v_readlane_b32 s53, v24, 44
	v_readlane_b32 s56, v25, 44
	s_waitcnt vmcnt(19)
	v_pk_fma_f32 v[10:11], v[176:177], s[42:43], v[10:11] op_sel_hi:[0,1,1]
	v_pk_fma_f32 v[8:9], v[176:177], s[52:53], v[8:9] op_sel_hi:[0,1,1]
	v_fmac_f32_e32 v21, s56, v176
	v_readlane_b32 s42, v0, 45
	v_readlane_b32 s43, v22, 45
	v_readlane_b32 s52, v23, 45
	v_readlane_b32 s53, v24, 45
	v_readlane_b32 s56, v25, 45
	s_waitcnt vmcnt(18)
	v_pk_fma_f32 v[10:11], v[176:177], s[42:43], v[10:11] op_sel:[1,0,0] op_sel_hi:[1,1,1]
	v_pk_fma_f32 v[8:9], v[176:177], s[52:53], v[8:9] op_sel:[1,0,0] op_sel_hi:[1,1,1]
	v_fmac_f32_e32 v21, s56, v177
	v_readlane_b32 s42, v0, 46
	v_readlane_b32 s43, v22, 46
	v_readlane_b32 s52, v23, 46
	v_readlane_b32 s53, v24, 46
	v_readlane_b32 s56, v25, 46
	s_waitcnt vmcnt(17)
	v_pk_fma_f32 v[10:11], v[178:179], s[42:43], v[10:11] op_sel_hi:[0,1,1]
	v_pk_fma_f32 v[8:9], v[178:179], s[52:53], v[8:9] op_sel_hi:[0,1,1]
	v_fmac_f32_e32 v21, s56, v178
	v_readlane_b32 s42, v0, 47
	v_readlane_b32 s43, v22, 47
	v_readlane_b32 s52, v23, 47
	v_readlane_b32 s53, v24, 47
	v_readlane_b32 s56, v25, 47
	s_waitcnt vmcnt(16)
	v_pk_fma_f32 v[10:11], v[178:179], s[42:43], v[10:11] op_sel:[1,0,0] op_sel_hi:[1,1,1]
	v_pk_fma_f32 v[8:9], v[178:179], s[52:53], v[8:9] op_sel:[1,0,0] op_sel_hi:[1,1,1]
	v_fmac_f32_e32 v21, s56, v179
	v_readlane_b32 s42, v0, 48
	v_readlane_b32 s43, v22, 48
	v_readlane_b32 s52, v23, 48
	v_readlane_b32 s53, v24, 48
	v_readlane_b32 s56, v25, 48
	s_waitcnt vmcnt(15)
	v_pk_fma_f32 v[10:11], v[180:181], s[42:43], v[10:11] op_sel_hi:[0,1,1]
	v_pk_fma_f32 v[8:9], v[180:181], s[52:53], v[8:9] op_sel_hi:[0,1,1]
	v_fmac_f32_e32 v21, s56, v180
	v_readlane_b32 s42, v0, 49
	v_readlane_b32 s43, v22, 49
	v_readlane_b32 s52, v23, 49
	v_readlane_b32 s53, v24, 49
	v_readlane_b32 s56, v25, 49
	s_waitcnt vmcnt(14)
	v_pk_fma_f32 v[10:11], v[180:181], s[42:43], v[10:11] op_sel:[1,0,0] op_sel_hi:[1,1,1]
	v_pk_fma_f32 v[8:9], v[180:181], s[52:53], v[8:9] op_sel:[1,0,0] op_sel_hi:[1,1,1]
	v_fmac_f32_e32 v21, s56, v181
	v_readlane_b32 s42, v0, 50
	v_readlane_b32 s43, v22, 50
	v_readlane_b32 s52, v23, 50
	v_readlane_b32 s53, v24, 50
	v_readlane_b32 s56, v25, 50
	s_waitcnt vmcnt(13)
	v_pk_fma_f32 v[10:11], v[182:183], s[42:43], v[10:11] op_sel_hi:[0,1,1]
	v_pk_fma_f32 v[8:9], v[182:183], s[52:53], v[8:9] op_sel_hi:[0,1,1]
	v_fmac_f32_e32 v21, s56, v182
	v_readlane_b32 s42, v0, 51
	v_readlane_b32 s43, v22, 51
	v_readlane_b32 s52, v23, 51
	v_readlane_b32 s53, v24, 51
	v_readlane_b32 s56, v25, 51
	s_waitcnt vmcnt(12)
	v_pk_fma_f32 v[10:11], v[182:183], s[42:43], v[10:11] op_sel:[1,0,0] op_sel_hi:[1,1,1]
	v_pk_fma_f32 v[8:9], v[182:183], s[52:53], v[8:9] op_sel:[1,0,0] op_sel_hi:[1,1,1]
	v_fmac_f32_e32 v21, s56, v183
	v_readlane_b32 s42, v0, 52
	v_readlane_b32 s43, v22, 52
	v_readlane_b32 s52, v23, 52
	v_readlane_b32 s53, v24, 52
	v_readlane_b32 s56, v25, 52
	s_waitcnt vmcnt(11)
	v_pk_fma_f32 v[10:11], v[184:185], s[42:43], v[10:11] op_sel_hi:[0,1,1]
	v_pk_fma_f32 v[8:9], v[184:185], s[52:53], v[8:9] op_sel_hi:[0,1,1]
	v_fmac_f32_e32 v21, s56, v184
	v_readlane_b32 s42, v0, 53
	v_readlane_b32 s43, v22, 53
	v_readlane_b32 s52, v23, 53
	v_readlane_b32 s53, v24, 53
	v_readlane_b32 s56, v25, 53
	s_waitcnt vmcnt(10)
	v_pk_fma_f32 v[10:11], v[184:185], s[42:43], v[10:11] op_sel:[1,0,0] op_sel_hi:[1,1,1]
	v_pk_fma_f32 v[8:9], v[184:185], s[52:53], v[8:9] op_sel:[1,0,0] op_sel_hi:[1,1,1]
	v_fmac_f32_e32 v21, s56, v185
	v_readlane_b32 s42, v0, 54
	v_readlane_b32 s43, v22, 54
	v_readlane_b32 s52, v23, 54
	v_readlane_b32 s53, v24, 54
	v_readlane_b32 s56, v25, 54
	s_waitcnt vmcnt(9)
	v_pk_fma_f32 v[10:11], v[186:187], s[42:43], v[10:11] op_sel_hi:[0,1,1]
	v_pk_fma_f32 v[8:9], v[186:187], s[52:53], v[8:9] op_sel_hi:[0,1,1]
	v_fmac_f32_e32 v21, s56, v186
	v_readlane_b32 s42, v0, 55
	v_readlane_b32 s43, v22, 55
	v_readlane_b32 s52, v23, 55
	v_readlane_b32 s53, v24, 55
	v_readlane_b32 s56, v25, 55
	s_waitcnt vmcnt(8)
	v_pk_fma_f32 v[10:11], v[186:187], s[42:43], v[10:11] op_sel:[1,0,0] op_sel_hi:[1,1,1]
	v_pk_fma_f32 v[8:9], v[186:187], s[52:53], v[8:9] op_sel:[1,0,0] op_sel_hi:[1,1,1]
	v_fmac_f32_e32 v21, s56, v187
	v_readlane_b32 s42, v0, 56
	v_readlane_b32 s43, v22, 56
	v_readlane_b32 s52, v23, 56
	v_readlane_b32 s53, v24, 56
	v_readlane_b32 s56, v25, 56
	s_waitcnt vmcnt(7)
	v_pk_fma_f32 v[10:11], v[188:189], s[42:43], v[10:11] op_sel_hi:[0,1,1]
	v_pk_fma_f32 v[8:9], v[188:189], s[52:53], v[8:9] op_sel_hi:[0,1,1]
	v_fmac_f32_e32 v21, s56, v188
	v_readlane_b32 s42, v0, 57
	v_readlane_b32 s43, v22, 57
	v_readlane_b32 s52, v23, 57
	v_readlane_b32 s53, v24, 57
	v_readlane_b32 s56, v25, 57
	s_waitcnt vmcnt(6)
	v_pk_fma_f32 v[10:11], v[188:189], s[42:43], v[10:11] op_sel:[1,0,0] op_sel_hi:[1,1,1]
	v_pk_fma_f32 v[8:9], v[188:189], s[52:53], v[8:9] op_sel:[1,0,0] op_sel_hi:[1,1,1]
	v_fmac_f32_e32 v21, s56, v189
	v_readlane_b32 s42, v0, 58
	v_readlane_b32 s43, v22, 58
	v_readlane_b32 s52, v23, 58
	v_readlane_b32 s53, v24, 58
	v_readlane_b32 s56, v25, 58
	s_waitcnt vmcnt(5)
	v_pk_fma_f32 v[10:11], v[190:191], s[42:43], v[10:11] op_sel_hi:[0,1,1]
	v_pk_fma_f32 v[8:9], v[190:191], s[52:53], v[8:9] op_sel_hi:[0,1,1]
	v_fmac_f32_e32 v21, s56, v190
	v_readlane_b32 s42, v0, 59
	v_readlane_b32 s43, v22, 59
	v_readlane_b32 s52, v23, 59
	v_readlane_b32 s53, v24, 59
	v_readlane_b32 s56, v25, 59
	s_waitcnt vmcnt(4)
	v_pk_fma_f32 v[10:11], v[190:191], s[42:43], v[10:11] op_sel:[1,0,0] op_sel_hi:[1,1,1]
	v_pk_fma_f32 v[8:9], v[190:191], s[52:53], v[8:9] op_sel:[1,0,0] op_sel_hi:[1,1,1]
	v_fmac_f32_e32 v21, s56, v191
	v_readlane_b32 s42, v0, 60
	v_readlane_b32 s43, v22, 60
	v_readlane_b32 s52, v23, 60
	v_readlane_b32 s53, v24, 60
	v_readlane_b32 s56, v25, 60
	s_waitcnt vmcnt(3)
	v_pk_fma_f32 v[10:11], v[192:193], s[42:43], v[10:11] op_sel_hi:[0,1,1]
	v_pk_fma_f32 v[8:9], v[192:193], s[52:53], v[8:9] op_sel_hi:[0,1,1]
	v_fmac_f32_e32 v21, s56, v192
	v_readlane_b32 s42, v0, 61
	v_readlane_b32 s43, v22, 61
	v_readlane_b32 s52, v23, 61
	v_readlane_b32 s53, v24, 61
	v_readlane_b32 s56, v25, 61
	s_waitcnt vmcnt(2)
	v_pk_fma_f32 v[10:11], v[192:193], s[42:43], v[10:11] op_sel:[1,0,0] op_sel_hi:[1,1,1]
	v_pk_fma_f32 v[8:9], v[192:193], s[52:53], v[8:9] op_sel:[1,0,0] op_sel_hi:[1,1,1]
	v_fmac_f32_e32 v21, s56, v193
	v_readlane_b32 s42, v0, 62
	v_readlane_b32 s43, v22, 62
	v_readlane_b32 s52, v23, 62
	v_readlane_b32 s53, v24, 62
	v_readlane_b32 s56, v25, 62
	s_waitcnt vmcnt(1)
	v_pk_fma_f32 v[10:11], v[194:195], s[42:43], v[10:11] op_sel_hi:[0,1,1]
	v_pk_fma_f32 v[8:9], v[194:195], s[52:53], v[8:9] op_sel_hi:[0,1,1]
	v_fmac_f32_e32 v21, s56, v194
	v_readlane_b32 s42, v0, 63
	v_readlane_b32 s43, v22, 63
	v_readlane_b32 s52, v23, 63
	v_readlane_b32 s53, v24, 63
	v_readlane_b32 s56, v25, 63
	s_waitcnt vmcnt(0)
	v_pk_fma_f32 v[10:11], v[194:195], s[42:43], v[10:11] op_sel:[1,0,0] op_sel_hi:[1,1,1]
	v_pk_fma_f32 v[8:9], v[194:195], s[52:53], v[8:9] op_sel:[1,0,0] op_sel_hi:[1,1,1]
	v_fmac_f32_e32 v21, s56, v195
	s_mov_b32 s40, 64
	s_mov_b64 s[4:5], 0
	s_and_b64 vcc, exec, s[12:13]
	s_cbranch_vccz .LBB0_930
	v_lshlrev_b32_e32 v0, 3, v16
	v_and_b32_e32 v6, 0xffffffc0, v0
	v_ashrrev_i32_e32 v7, 31, v6
	v_lshl_add_u64 v[6:7], v[6:7], 2, v[2:3]
	v_add_co_u32_e32 v12, vcc, 0x3000, v6
	global_store_dword v[6:7], v10, off sc1
	s_nop 0
	v_addc_co_u32_e32 v13, vcc, 0, v7, vcc
	v_add_co_u32_e32 v10, vcc, 0x6000, v6
	global_store_dword v[12:13], v11, off sc1
	s_nop 0
	v_addc_co_u32_e32 v11, vcc, 0, v7, vcc
	global_store_dword v[10:11], v8, off sc1
	v_add_co_u32_e32 v10, vcc, 0x9000, v6
	v_add_u32_e32 v16, s16, v16
	s_nop 0
	v_addc_co_u32_e32 v11, vcc, 0, v7, vcc
	v_add_co_u32_e32 v6, vcc, 0xc000, v6
	v_add_u32_e32 v18, s3, v18
	s_nop 0
	v_addc_co_u32_e32 v7, vcc, 0, v7, vcc
	v_cmp_lt_i32_e32 vcc, s67, v16
	s_or_b64 s[10:11], vcc, s[10:11]
	global_store_dword v[10:11], v9, off sc1
	global_store_dword v[6:7], v21, off sc1
	s_andn2_b64 exec, exec, s[10:11]
	s_cbranch_execnz .LBB0_929

.LBB0_996:
	s_or_b64 exec, exec, s[12:13]
	s_waitcnt vmcnt(27)
	v_lshlrev_b32_e32 v221, 16, v187
	v_lshlrev_b32_e32 v223, 16, v183
	v_and_b32_e32 v220, 0xffff0000, v187
	v_and_b32_e32 v222, 0xffff0000, v183
	s_waitcnt vmcnt(25)
	v_and_b32_e32 v218, 0xffff0000, v191
	v_lshlrev_b32_e32 v3, 16, v191
	v_pk_add_f32 v[220:221], v[220:221], v[222:223]
	v_lshlrev_b32_e32 v222, 16, v190
	v_and_b32_e32 v223, 0xffff0000, v190
	v_lshlrev_b32_e32 v190, 16, v186
	v_and_b32_e32 v191, 0xffff0000, v186
	v_lshlrev_b32_e32 v186, 16, v182
	v_and_b32_e32 v187, 0xffff0000, v182
	v_pk_add_f32 v[182:183], v[186:187], v[190:191]
	v_lshlrev_b32_e32 v190, 16, v189
	v_and_b32_e32 v191, 0xffff0000, v189
	v_lshlrev_b32_e32 v232, 16, v185
	v_and_b32_e32 v233, 0xffff0000, v185
	v_mul_f32_e32 v185, 0xbfb8aa3b, v190
	v_exp_f32_e32 v185, v185
	v_mul_f32_e32 v189, 0xbfb8aa3b, v191
	v_exp_f32_e32 v189, v189
	v_lshlrev_b32_e32 v234, 16, v181
	v_add_f32_e32 v185, 1.0, v185
	v_rcp_f32_e32 v236, v185
	v_add_f32_e32 v185, 1.0, v189
	v_rcp_f32_e32 v237, v185
	v_and_b32_e32 v235, 0xffff0000, v181
	v_and_b32_e32 v189, 0xffff0000, v184
	v_mad_i64_i32 v[24:25], s[12:13], v24, s19, v[202:203]
	v_pk_mul_f32 v[190:191], v[236:237], v[190:191]
	v_lshlrev_b32_e32 v236, 16, v188
	v_and_b32_e32 v237, 0xffff0000, v188
	v_mul_f32_e32 v181, 0xbfb8aa3b, v236
	v_lshlrev_b32_e32 v188, 16, v184
	v_exp_f32_e32 v181, v181
	v_mul_f32_e32 v184, 0xbfb8aa3b, v237
	v_exp_f32_e32 v185, v184
	v_lshlrev_b32_e32 v184, 16, v180
	v_add_f32_e32 v181, 1.0, v181
	v_rcp_f32_e32 v238, v181
	v_add_f32_e32 v181, 1.0, v185
	v_rcp_f32_e32 v239, v181
	v_and_b32_e32 v185, 0xffff0000, v180
	v_pk_add_f32 v[180:181], v[184:185], v[188:189]
	v_lshl_add_u64 v[28:29], v[194:195], 0, v[26:27]
	v_pk_mul_f32 v[188:189], v[238:239], v[236:237]
	s_waitcnt vmcnt(24)
	v_lshlrev_b32_e32 v236, 16, v171
	v_and_b32_e32 v237, 0xffff0000, v171
	v_mul_f32_e32 v171, 0xbfb8aa3b, v236
	v_lshl_add_u64 v[26:27], v[196:197], 0, v[26:27]
	v_lshlrev_b32_e32 v238, 16, v179
	v_and_b32_e32 v239, 0xffff0000, v179
	v_exp_f32_e32 v171, v171
	v_mul_f32_e32 v179, 0xbfb8aa3b, v237
	global_load_dwordx4 v[48:51], v[28:29], off offset:16
	global_load_dwordx4 v[32:35], v[28:29], off
	global_load_dwordx4 v[44:47], v[26:27], off offset:16
	s_nop 0
	global_load_dwordx4 v[28:31], v[26:27], off
	global_load_dwordx4 v[52:55], v[24:25], off offset:16
	s_nop 0
	global_load_dwordx4 v[24:27], v[24:25], off
	v_exp_f32_e32 v179, v179
	v_add_f32_e32 v171, 1.0, v171
	v_rcp_f32_e32 v242, v171
	v_lshlrev_b32_e32 v246, 16, v177
	v_add_f32_e32 v171, 1.0, v179
	v_rcp_f32_e32 v243, v171
	v_and_b32_e32 v247, 0xffff0000, v177
	v_lshlrev_b32_e32 v252, 16, v176
	v_and_b32_e32 v253, 0xffff0000, v176
	v_lshlrev_b32_e32 v176, 16, v172
	v_and_b32_e32 v177, 0xffff0000, v172
	v_lshlrev_b32_e32 v248, 16, v173
	v_and_b32_e32 v249, 0xffff0000, v173
	v_pk_add_f32 v[172:173], v[176:177], v[252:253]
	v_pk_mul_f32 v[236:237], v[242:243], v[236:237]
	v_lshlrev_b32_e32 v242, 16, v170
	v_pk_add_f32 v[246:247], v[248:249], v[246:247]
	v_pk_mul_f32 v[176:177], v[172:173], v[172:173]
	v_and_b32_e32 v243, 0xffff0000, v170
	v_lshlrev_b32_e32 v170, 16, v178
	v_and_b32_e32 v171, 0xffff0000, v178
	v_lshlrev_b32_e32 v178, 16, v174
	v_and_b32_e32 v179, 0xffff0000, v174
	v_mul_f32_e32 v174, 0xbfb8aa3b, v242
	v_pk_mul_f32 v[248:249], v[246:247], v[246:247]
	v_add_f32_e32 v176, v176, v177
	v_pk_add_f32 v[170:171], v[178:179], v[170:171]
	v_exp_f32_e32 v178, v174
	v_mul_f32_e32 v174, 0xbfb8aa3b, v243
	v_add_f32_e32 v176, v248, v176
	v_lshlrev_b32_e32 v240, 16, v175
	v_and_b32_e32 v241, 0xffff0000, v175
	v_exp_f32_e32 v179, v174
	v_pk_mul_f32 v[174:175], v[170:171], v[170:171]
	v_add_f32_e32 v176, v249, v176
	v_pk_add_f32 v[238:239], v[240:241], v[238:239]
	v_add_f32_e32 v174, v174, v176
	v_pk_mul_f32 v[240:241], v[238:239], v[238:239]
	v_add_f32_e32 v174, v175, v174
	v_add_f32_e32 v174, v240, v174
	v_pk_mul_f32 v[184:185], v[180:181], v[180:181]
	v_add_f32_e32 v174, v241, v174
	v_pk_add_f32 v[232:233], v[234:235], v[232:233]
	v_add_f32_e32 v174, v184, v174
	v_pk_mul_f32 v[234:235], v[232:233], v[232:233]
	v_lshlrev_b32_e32 v244, 16, v169
	v_add_f32_e32 v174, v185, v174
	v_and_b32_e32 v245, 0xffff0000, v169
	v_mul_f32_e32 v169, 0xbfb8aa3b, v244
	v_add_f32_e32 v174, v234, v174
	v_pk_mul_f32 v[186:187], v[182:183], v[182:183]
	v_exp_f32_e32 v169, v169
	v_add_f32_e32 v174, v235, v174
	v_add_f32_e32 v174, v186, v174
	v_pk_mul_f32 v[230:231], v[220:221], v[220:221]
	v_add_f32_e32 v174, v187, v174
	v_add_f32_e32 v174, v231, v174
	v_add_f32_e32 v169, 1.0, v169
	v_add_f32_e32 v176, v230, v174
	v_rcp_f32_e32 v250, v169
	v_mul_f32_e32 v169, 0xbfb8aa3b, v245
	ds_bpermute_b32 v177, v227, v176
	v_exp_f32_e32 v169, v169
	v_lshlrev_b32_e32 v174, 16, v168
	v_and_b32_e32 v175, 0xffff0000, v168
	v_add_f32_e32 v178, 1.0, v178
	v_add_f32_e32 v169, 1.0, v169
	s_waitcnt lgkmcnt(0)
	v_add_f32_e32 v168, v176, v177
	v_rcp_f32_e32 v251, v169
	ds_bpermute_b32 v169, v228, v168
	v_mul_f32_e32 v176, 0xbfb8aa3b, v174
	v_exp_f32_e32 v176, v176
	v_mul_f32_e32 v177, 0xbfb8aa3b, v175
	v_exp_f32_e32 v177, v177
	s_waitcnt lgkmcnt(0)
	v_add_f32_e32 v184, v168, v169
	ds_bpermute_b32 v185, v229, v184
	v_add_f32_e32 v168, 1.0, v176
	v_add_f32_e32 v169, 1.0, v177
	v_rcp_f32_e32 v168, v168
	v_rcp_f32_e32 v169, v169
	s_waitcnt lgkmcnt(0)
	v_add_f32_e32 v176, v184, v185
	v_fmamk_f32 v176, v176, 0x3c000000, v226
	v_mul_f32_e32 v177, 0x4b800000, v176
	v_cmp_gt_f32_e32 vcc, s29, v176
	v_add_f32_e32 v179, 1.0, v179
	v_pk_mul_f32 v[168:169], v[168:169], v[174:175]
	v_cndmask_b32_e32 v176, v176, v177, vcc
	v_rsq_f32_e32 v184, v176
	v_rcp_f32_e32 v178, v178
	v_rcp_f32_e32 v179, v179
	v_mul_f32_e32 v174, 0x45800000, v184
	v_cndmask_b32_e32 v174, v184, v174, vcc
	v_pk_mul_f32 v[172:173], v[172:173], v[174:175] op_sel_hi:[1,0]
	v_pk_mul_f32 v[170:171], v[170:171], v[174:175] op_sel_hi:[1,0]
	v_pk_mul_f32 v[172:173], v[12:13], v[172:173]
	v_pk_mul_f32 v[176:177], v[178:179], v[242:243]
	v_pk_mul_f32 v[168:169], v[168:169], v[172:173]
	v_pk_mul_f32 v[172:173], v[246:247], v[174:175] op_sel_hi:[1,0]
	v_pk_mul_f32 v[178:179], v[250:251], v[244:245]
	v_pk_mul_f32 v[172:173], v[14:15], v[172:173]
	v_pk_mul_f32 v[170:171], v[8:9], v[170:171]
	v_pk_mul_f32 v[172:173], v[178:179], v[172:173]
	v_pk_mul_f32 v[170:171], v[176:177], v[170:171]
	v_pk_mul_f32 v[176:177], v[238:239], v[174:175] op_sel_hi:[1,0]
	v_pk_mul_f32 v[178:179], v[180:181], v[174:175] op_sel_hi:[1,0]
	v_pk_mul_f32 v[180:181], v[232:233], v[174:175] op_sel_hi:[1,0]
	v_mul_f32_e32 v175, 0xbfb8aa3b, v222
	v_exp_f32_e32 v175, v175
	v_mul_f32_e32 v184, 0xbfb8aa3b, v223
	v_exp_f32_e32 v185, v184
	v_mul_f32_e32 v219, v220, v174
	v_add_f32_e32 v175, 1.0, v175
	v_rcp_f32_e32 v184, v175
	v_add_f32_e32 v175, 1.0, v185
	v_rcp_f32_e32 v185, v175
	v_pk_mul_f32 v[182:183], v[182:183], v[174:175] op_sel_hi:[1,0]
	v_mul_f32_e32 v175, 0xbfb8aa3b, v3
	v_pk_mul_f32 v[182:183], v[0:1], v[182:183]
	v_pk_mul_f32 v[184:185], v[184:185], v[222:223]
	v_exp_f32_e32 v175, v175
	v_pk_mul_f32 v[182:183], v[184:185], v[182:183]
	v_mul_f32_e32 v184, 0xbfb8aa3b, v218
	v_exp_f32_e32 v184, v184
	v_add_f32_e32 v175, 1.0, v175
	v_rcp_f32_e32 v175, v175
	v_pk_mul_f32 v[176:177], v[10:11], v[176:177]
	v_add_f32_e32 v184, 1.0, v184
	v_rcp_f32_e32 v204, v184
	v_mul_f32_e32 v185, v221, v174
	v_mul_f32_e32 v186, v175, v3
	v_pk_mul_f32 v[176:177], v[236:237], v[176:177]
	v_pk_mul_f32 v[174:175], v[204:205], v[218:219]
	v_pk_mul_f32 v[178:179], v[4:5], v[178:179]
	v_pk_mul_f32 v[180:181], v[6:7], v[180:181]
	v_mul_f32_e32 v184, v2, v185
	v_mov_b32_e32 v187, v174
	v_mov_b32_e32 v185, v175
	v_pk_mul_f32 v[178:179], v[188:189], v[178:179]
	v_pk_mul_f32 v[180:181], v[190:191], v[180:181]
	v_cvt_pk_bf16_f32 v168, v168, v169
	v_cvt_pk_bf16_f32 v169, v172, v173
	v_cvt_pk_bf16_f32 v170, v170, v171
	v_cvt_pk_bf16_f32 v171, v176, v177
	v_lshl_add_u64 v[172:173], v[192:193], 0, v[216:217]
	v_pk_mul_f32 v[174:175], v[186:187], v[184:185]
	global_store_dwordx4 v[172:173], v[168:171], off sc1
	v_cmp_gt_i32_e32 vcc, s3, v214
	s_nop 0
	v_cvt_pk_bf16_f32 v168, v178, v179
	v_cvt_pk_bf16_f32 v169, v180, v181
	v_cvt_pk_bf16_f32 v170, v182, v183
	v_cvt_pk_bf16_f32 v171, v174, v175
	global_store_dwordx4 v[172:173], v[168:171], off offset:16 sc1
	s_and_saveexec_b64 s[12:13], vcc
	s_cbranch_execz .LBB0_998
	s_waitcnt vmcnt(29)
	v_lshlrev_b32_e32 v171, 16, v163
	v_lshlrev_b32_e32 v173, 16, v159
	v_and_b32_e32 v170, 0xffff0000, v163
	v_and_b32_e32 v172, 0xffff0000, v159
	s_waitcnt vmcnt(27)
	v_and_b32_e32 v168, 0xffff0000, v167
	v_lshlrev_b32_e32 v3, 16, v167
	v_pk_add_f32 v[170:171], v[170:171], v[172:173]
	v_lshlrev_b32_e32 v172, 16, v166
	v_and_b32_e32 v173, 0xffff0000, v166
	v_lshlrev_b32_e32 v166, 16, v162
	v_and_b32_e32 v167, 0xffff0000, v162
	v_lshlrev_b32_e32 v162, 16, v158
	v_and_b32_e32 v163, 0xffff0000, v158
	v_pk_add_f32 v[158:159], v[162:163], v[166:167]
	v_lshlrev_b32_e32 v166, 16, v165
	v_and_b32_e32 v167, 0xffff0000, v165
	v_lshlrev_b32_e32 v176, 16, v161
	v_and_b32_e32 v177, 0xffff0000, v161
	v_mul_f32_e32 v161, 0xbfb8aa3b, v166
	v_exp_f32_e32 v161, v161
	v_mul_f32_e32 v165, 0xbfb8aa3b, v167
	v_exp_f32_e32 v165, v165
	v_lshlrev_b32_e32 v178, 16, v157
	v_add_f32_e32 v161, 1.0, v161
	v_rcp_f32_e32 v180, v161
	v_add_f32_e32 v161, 1.0, v165
	v_rcp_f32_e32 v181, v161
	v_and_b32_e32 v179, 0xffff0000, v157
	v_and_b32_e32 v165, 0xffff0000, v160
	v_lshlrev_b32_e32 v190, 16, v153
	v_pk_mul_f32 v[166:167], v[180:181], v[166:167]
	v_lshlrev_b32_e32 v180, 16, v164
	v_and_b32_e32 v181, 0xffff0000, v164
	v_mul_f32_e32 v157, 0xbfb8aa3b, v180
	v_lshlrev_b32_e32 v164, 16, v160
	v_exp_f32_e32 v157, v157
	v_mul_f32_e32 v160, 0xbfb8aa3b, v181
	v_exp_f32_e32 v161, v160
	v_lshlrev_b32_e32 v160, 16, v156
	v_add_f32_e32 v157, 1.0, v157
	v_rcp_f32_e32 v182, v157
	v_add_f32_e32 v157, 1.0, v161
	v_rcp_f32_e32 v183, v157
	v_and_b32_e32 v161, 0xffff0000, v156
	v_pk_add_f32 v[156:157], v[160:161], v[164:165]
	v_and_b32_e32 v191, 0xffff0000, v153
	v_pk_mul_f32 v[164:165], v[182:183], v[180:181]
	s_waitcnt vmcnt(26)
	v_lshlrev_b32_e32 v180, 16, v147
	v_and_b32_e32 v181, 0xffff0000, v147
	v_mul_f32_e32 v147, 0xbfb8aa3b, v180
	v_lshlrev_b32_e32 v182, 16, v155
	v_and_b32_e32 v183, 0xffff0000, v155
	v_exp_f32_e32 v147, v147
	v_mul_f32_e32 v155, 0xbfb8aa3b, v181
	v_exp_f32_e32 v155, v155
	v_lshlrev_b32_e32 v220, 16, v152
	v_add_f32_e32 v147, 1.0, v147
	v_rcp_f32_e32 v186, v147
	v_add_f32_e32 v147, 1.0, v155
	v_rcp_f32_e32 v187, v147
	v_and_b32_e32 v221, 0xffff0000, v152
	v_lshlrev_b32_e32 v152, 16, v148
	v_and_b32_e32 v153, 0xffff0000, v148
	v_lshlrev_b32_e32 v216, 16, v149
	v_and_b32_e32 v217, 0xffff0000, v149
	v_pk_add_f32 v[148:149], v[152:153], v[220:221]
	v_pk_mul_f32 v[180:181], v[186:187], v[180:181]
	v_lshlrev_b32_e32 v186, 16, v146
	v_pk_add_f32 v[190:191], v[216:217], v[190:191]
	v_pk_mul_f32 v[152:153], v[148:149], v[148:149]
	v_and_b32_e32 v187, 0xffff0000, v146
	v_lshlrev_b32_e32 v146, 16, v154
	v_and_b32_e32 v147, 0xffff0000, v154
	v_lshlrev_b32_e32 v154, 16, v150
	v_and_b32_e32 v155, 0xffff0000, v150
	v_mul_f32_e32 v150, 0xbfb8aa3b, v186
	v_pk_mul_f32 v[216:217], v[190:191], v[190:191]
	v_add_f32_e32 v152, v152, v153
	v_pk_add_f32 v[146:147], v[154:155], v[146:147]
	v_exp_f32_e32 v154, v150
	v_mul_f32_e32 v150, 0xbfb8aa3b, v187
	v_add_f32_e32 v152, v216, v152
	v_lshlrev_b32_e32 v184, 16, v151
	v_and_b32_e32 v185, 0xffff0000, v151
	v_exp_f32_e32 v155, v150
	v_pk_mul_f32 v[150:151], v[146:147], v[146:147]
	v_add_f32_e32 v152, v217, v152
	v_pk_add_f32 v[182:183], v[184:185], v[182:183]
	v_add_f32_e32 v150, v150, v152
	v_pk_mul_f32 v[184:185], v[182:183], v[182:183]
	v_add_f32_e32 v150, v151, v150
	v_add_f32_e32 v150, v184, v150
	v_pk_mul_f32 v[160:161], v[156:157], v[156:157]
	v_add_f32_e32 v150, v185, v150
	v_pk_add_f32 v[176:177], v[178:179], v[176:177]
	v_add_f32_e32 v150, v160, v150
	v_pk_mul_f32 v[178:179], v[176:177], v[176:177]
	v_lshlrev_b32_e32 v188, 16, v145
	v_add_f32_e32 v150, v161, v150
	v_and_b32_e32 v189, 0xffff0000, v145
	v_mul_f32_e32 v145, 0xbfb8aa3b, v188
	v_add_f32_e32 v150, v178, v150
	v_pk_mul_f32 v[162:163], v[158:159], v[158:159]
	v_exp_f32_e32 v145, v145
	v_add_f32_e32 v150, v179, v150
	v_add_f32_e32 v150, v162, v150
	v_pk_mul_f32 v[174:175], v[170:171], v[170:171]
	v_add_f32_e32 v150, v163, v150
	v_add_f32_e32 v150, v175, v150
	v_add_f32_e32 v145, 1.0, v145
	v_add_f32_e32 v152, v174, v150
	v_rcp_f32_e32 v218, v145
	v_mul_f32_e32 v145, 0xbfb8aa3b, v189
	ds_bpermute_b32 v153, v227, v152
	v_exp_f32_e32 v145, v145
	v_lshlrev_b32_e32 v150, 16, v144
	v_and_b32_e32 v151, 0xffff0000, v144
	v_add_f32_e32 v154, 1.0, v154
	v_add_f32_e32 v145, 1.0, v145
	s_waitcnt lgkmcnt(0)
	v_add_f32_e32 v144, v152, v153
	v_rcp_f32_e32 v219, v145
	ds_bpermute_b32 v145, v228, v144
	v_mul_f32_e32 v152, 0xbfb8aa3b, v150
	v_exp_f32_e32 v152, v152
	v_mul_f32_e32 v153, 0xbfb8aa3b, v151
	v_exp_f32_e32 v153, v153
	s_waitcnt lgkmcnt(0)
	v_add_f32_e32 v160, v144, v145
	ds_bpermute_b32 v161, v229, v160
	v_add_f32_e32 v144, 1.0, v152
	v_add_f32_e32 v145, 1.0, v153
	v_rcp_f32_e32 v144, v144
	v_rcp_f32_e32 v145, v145
	s_waitcnt lgkmcnt(0)
	v_add_f32_e32 v152, v160, v161
	v_fmamk_f32 v152, v152, 0x3c000000, v226
	v_mul_f32_e32 v153, 0x4b800000, v152
	v_cmp_gt_f32_e32 vcc, s29, v152
	v_add_f32_e32 v155, 1.0, v155
	v_pk_mul_f32 v[144:145], v[144:145], v[150:151]
	v_cndmask_b32_e32 v152, v152, v153, vcc
	v_rsq_f32_e32 v160, v152
	v_rcp_f32_e32 v154, v154
	v_rcp_f32_e32 v155, v155
	v_ashrrev_i32_e32 v215, 31, v214
	v_mul_f32_e32 v150, 0x45800000, v160
	v_cndmask_b32_e32 v150, v160, v150, vcc
	v_pk_mul_f32 v[148:149], v[148:149], v[150:151] op_sel_hi:[1,0]
	v_pk_mul_f32 v[146:147], v[146:147], v[150:151] op_sel_hi:[1,0]
	v_pk_mul_f32 v[148:149], v[12:13], v[148:149]
	v_pk_mul_f32 v[152:153], v[154:155], v[186:187]
	v_pk_mul_f32 v[144:145], v[144:145], v[148:149]
	v_pk_mul_f32 v[148:149], v[190:191], v[150:151] op_sel_hi:[1,0]
	v_pk_mul_f32 v[154:155], v[218:219], v[188:189]
	v_pk_mul_f32 v[148:149], v[14:15], v[148:149]
	v_pk_mul_f32 v[146:147], v[8:9], v[146:147]
	v_pk_mul_f32 v[148:149], v[154:155], v[148:149]
	v_pk_mul_f32 v[146:147], v[152:153], v[146:147]
	v_pk_mul_f32 v[152:153], v[182:183], v[150:151] op_sel_hi:[1,0]
	v_pk_mul_f32 v[154:155], v[156:157], v[150:151] op_sel_hi:[1,0]
	v_pk_mul_f32 v[156:157], v[176:177], v[150:151] op_sel_hi:[1,0]
	v_mul_f32_e32 v151, 0xbfb8aa3b, v172
	v_exp_f32_e32 v151, v151
	v_mul_f32_e32 v160, 0xbfb8aa3b, v173
	v_exp_f32_e32 v161, v160
	v_mul_f32_e32 v169, v170, v150
	v_add_f32_e32 v151, 1.0, v151
	v_rcp_f32_e32 v160, v151
	v_add_f32_e32 v151, 1.0, v161
	v_rcp_f32_e32 v161, v151
	v_pk_mul_f32 v[158:159], v[158:159], v[150:151] op_sel_hi:[1,0]
	v_mul_f32_e32 v151, 0xbfb8aa3b, v3
	v_pk_mul_f32 v[158:159], v[0:1], v[158:159]
	v_pk_mul_f32 v[160:161], v[160:161], v[172:173]
	v_exp_f32_e32 v151, v151
	v_pk_mul_f32 v[158:159], v[160:161], v[158:159]
	v_mul_f32_e32 v160, 0xbfb8aa3b, v168
	v_exp_f32_e32 v160, v160
	v_add_f32_e32 v151, 1.0, v151
	v_rcp_f32_e32 v151, v151
	v_pk_mul_f32 v[152:153], v[10:11], v[152:153]
	v_add_f32_e32 v160, 1.0, v160
	v_rcp_f32_e32 v204, v160
	v_mul_f32_e32 v161, v171, v150
	v_mul_f32_e32 v162, v151, v3
	v_pk_mul_f32 v[152:153], v[180:181], v[152:153]
	v_pk_mul_f32 v[150:151], v[204:205], v[168:169]
	v_pk_mul_f32 v[154:155], v[4:5], v[154:155]
	v_pk_mul_f32 v[156:157], v[6:7], v[156:157]
	v_mul_f32_e32 v160, v2, v161
	v_mov_b32_e32 v163, v150
	v_mov_b32_e32 v161, v151
	v_cvt_pk_bf16_f32 v144, v144, v145
	v_cvt_pk_bf16_f32 v145, v148, v149
	v_lshlrev_b64 v[148:149], 11, v[214:215]
	v_pk_mul_f32 v[154:155], v[164:165], v[154:155]
	v_pk_mul_f32 v[156:157], v[166:167], v[156:157]
	v_cvt_pk_bf16_f32 v146, v146, v147
	v_cvt_pk_bf16_f32 v147, v152, v153
	v_lshl_add_u64 v[148:149], v[192:193], 0, v[148:149]
	v_pk_mul_f32 v[150:151], v[162:163], v[160:161]
	global_store_dwordx4 v[148:149], v[144:147], off sc1
	s_nop 1
	v_cvt_pk_bf16_f32 v144, v154, v155
	v_cvt_pk_bf16_f32 v145, v156, v157
	v_cvt_pk_bf16_f32 v146, v158, v159
	v_cvt_pk_bf16_f32 v147, v150, v151
	global_store_dwordx4 v[148:149], v[144:147], off offset:16 sc1
.LBB0_998:
	s_or_b64 exec, exec, s[12:13]
	v_add_u32_e32 v3, s33, v214
	v_cmp_gt_i32_e32 vcc, s3, v3
	s_and_saveexec_b64 s[12:13], vcc
	s_cbranch_execz .LBB0_1000
	s_waitcnt vmcnt(23)
	v_lshlrev_b32_e32 v147, 16, v139
	v_lshlrev_b32_e32 v149, 16, v135
	v_and_b32_e32 v146, 0xffff0000, v139
	v_and_b32_e32 v148, 0xffff0000, v135
	s_waitcnt vmcnt(21)
	v_and_b32_e32 v144, 0xffff0000, v143
	v_lshlrev_b32_e32 v145, 16, v143
	v_pk_add_f32 v[146:147], v[146:147], v[148:149]
	v_lshlrev_b32_e32 v148, 16, v142
	v_and_b32_e32 v149, 0xffff0000, v142
	v_lshlrev_b32_e32 v142, 16, v138
	v_and_b32_e32 v143, 0xffff0000, v138
	v_lshlrev_b32_e32 v138, 16, v134
	v_and_b32_e32 v139, 0xffff0000, v134
	v_pk_add_f32 v[134:135], v[138:139], v[142:143]
	v_lshlrev_b32_e32 v142, 16, v141
	v_and_b32_e32 v143, 0xffff0000, v141
	v_lshlrev_b32_e32 v152, 16, v137
	v_and_b32_e32 v153, 0xffff0000, v137
	v_mul_f32_e32 v137, 0xbfb8aa3b, v142
	v_exp_f32_e32 v137, v137
	v_mul_f32_e32 v141, 0xbfb8aa3b, v143
	v_exp_f32_e32 v141, v141
	v_lshlrev_b32_e32 v154, 16, v133
	v_add_f32_e32 v137, 1.0, v137
	v_rcp_f32_e32 v156, v137
	v_add_f32_e32 v137, 1.0, v141
	v_rcp_f32_e32 v157, v137
	v_and_b32_e32 v155, 0xffff0000, v133
	v_and_b32_e32 v141, 0xffff0000, v136
	v_lshlrev_b32_e32 v166, 16, v129
	v_pk_mul_f32 v[142:143], v[156:157], v[142:143]
	v_lshlrev_b32_e32 v156, 16, v140
	v_and_b32_e32 v157, 0xffff0000, v140
	v_mul_f32_e32 v133, 0xbfb8aa3b, v156
	v_lshlrev_b32_e32 v140, 16, v136
	v_exp_f32_e32 v133, v133
	v_mul_f32_e32 v136, 0xbfb8aa3b, v157
	v_exp_f32_e32 v137, v136
	v_lshlrev_b32_e32 v136, 16, v132
	v_add_f32_e32 v133, 1.0, v133
	v_rcp_f32_e32 v158, v133
	v_add_f32_e32 v133, 1.0, v137
	v_rcp_f32_e32 v159, v133
	v_and_b32_e32 v137, 0xffff0000, v132
	v_pk_add_f32 v[132:133], v[136:137], v[140:141]
	v_and_b32_e32 v167, 0xffff0000, v129
	v_pk_mul_f32 v[140:141], v[158:159], v[156:157]
	s_waitcnt vmcnt(20)
	v_lshlrev_b32_e32 v156, 16, v123
	v_and_b32_e32 v157, 0xffff0000, v123
	v_mul_f32_e32 v123, 0xbfb8aa3b, v156
	v_lshlrev_b32_e32 v158, 16, v131
	v_and_b32_e32 v159, 0xffff0000, v131
	v_exp_f32_e32 v123, v123
	v_mul_f32_e32 v131, 0xbfb8aa3b, v157
	v_exp_f32_e32 v131, v131
	v_lshlrev_b32_e32 v172, 16, v128
	v_add_f32_e32 v123, 1.0, v123
	v_rcp_f32_e32 v162, v123
	v_add_f32_e32 v123, 1.0, v131
	v_rcp_f32_e32 v163, v123
	v_and_b32_e32 v173, 0xffff0000, v128
	v_lshlrev_b32_e32 v128, 16, v124
	v_and_b32_e32 v129, 0xffff0000, v124
	v_lshlrev_b32_e32 v168, 16, v125
	v_and_b32_e32 v169, 0xffff0000, v125
	v_pk_add_f32 v[124:125], v[128:129], v[172:173]
	v_pk_mul_f32 v[156:157], v[162:163], v[156:157]
	v_lshlrev_b32_e32 v162, 16, v122
	v_pk_add_f32 v[166:167], v[168:169], v[166:167]
	v_pk_mul_f32 v[128:129], v[124:125], v[124:125]
	v_and_b32_e32 v163, 0xffff0000, v122
	v_lshlrev_b32_e32 v122, 16, v130
	v_and_b32_e32 v123, 0xffff0000, v130
	v_lshlrev_b32_e32 v130, 16, v126
	v_and_b32_e32 v131, 0xffff0000, v126
	v_mul_f32_e32 v126, 0xbfb8aa3b, v162
	v_pk_mul_f32 v[168:169], v[166:167], v[166:167]
	v_add_f32_e32 v128, v128, v129
	v_pk_add_f32 v[122:123], v[130:131], v[122:123]
	v_exp_f32_e32 v130, v126
	v_mul_f32_e32 v126, 0xbfb8aa3b, v163
	v_add_f32_e32 v128, v168, v128
	v_lshlrev_b32_e32 v160, 16, v127
	v_and_b32_e32 v161, 0xffff0000, v127
	v_exp_f32_e32 v131, v126
	v_pk_mul_f32 v[126:127], v[122:123], v[122:123]
	v_add_f32_e32 v128, v169, v128
	v_pk_add_f32 v[158:159], v[160:161], v[158:159]
	v_add_f32_e32 v126, v126, v128
	v_pk_mul_f32 v[160:161], v[158:159], v[158:159]
	v_add_f32_e32 v126, v127, v126
	v_add_f32_e32 v126, v160, v126
	v_pk_mul_f32 v[136:137], v[132:133], v[132:133]
	v_add_f32_e32 v126, v161, v126
	v_pk_add_f32 v[152:153], v[154:155], v[152:153]
	v_add_f32_e32 v126, v136, v126
	v_pk_mul_f32 v[154:155], v[152:153], v[152:153]
	v_lshlrev_b32_e32 v164, 16, v121
	v_add_f32_e32 v126, v137, v126
	v_and_b32_e32 v165, 0xffff0000, v121
	v_mul_f32_e32 v121, 0xbfb8aa3b, v164
	v_add_f32_e32 v126, v154, v126
	v_pk_mul_f32 v[138:139], v[134:135], v[134:135]
	v_exp_f32_e32 v121, v121
	v_add_f32_e32 v126, v155, v126
	v_add_f32_e32 v126, v138, v126
	v_pk_mul_f32 v[150:151], v[146:147], v[146:147]
	v_add_f32_e32 v126, v139, v126
	v_add_f32_e32 v126, v151, v126
	v_add_f32_e32 v121, 1.0, v121
	v_add_f32_e32 v128, v150, v126
	v_rcp_f32_e32 v170, v121
	v_mul_f32_e32 v121, 0xbfb8aa3b, v165
	ds_bpermute_b32 v129, v227, v128
	v_exp_f32_e32 v121, v121
	v_lshlrev_b32_e32 v126, 16, v120
	v_and_b32_e32 v127, 0xffff0000, v120
	v_add_f32_e32 v130, 1.0, v130
	v_add_f32_e32 v121, 1.0, v121
	s_waitcnt lgkmcnt(0)
	v_add_f32_e32 v120, v128, v129
	v_rcp_f32_e32 v171, v121
	ds_bpermute_b32 v121, v228, v120
	v_mul_f32_e32 v128, 0xbfb8aa3b, v126
	v_exp_f32_e32 v128, v128
	v_mul_f32_e32 v129, 0xbfb8aa3b, v127
	v_exp_f32_e32 v129, v129
	s_waitcnt lgkmcnt(0)
	v_add_f32_e32 v136, v120, v121
	ds_bpermute_b32 v137, v229, v136
	v_add_f32_e32 v120, 1.0, v128
	v_add_f32_e32 v121, 1.0, v129
	v_rcp_f32_e32 v120, v120
	v_rcp_f32_e32 v121, v121
	s_waitcnt lgkmcnt(0)
	v_add_f32_e32 v128, v136, v137
	v_fmamk_f32 v128, v128, 0x3c000000, v226
	v_mul_f32_e32 v129, 0x4b800000, v128
	v_cmp_gt_f32_e32 vcc, s29, v128
	v_add_f32_e32 v131, 1.0, v131
	v_pk_mul_f32 v[120:121], v[120:121], v[126:127]
	v_cndmask_b32_e32 v128, v128, v129, vcc
	v_rsq_f32_e32 v136, v128
	v_rcp_f32_e32 v130, v130
	v_rcp_f32_e32 v131, v131
	v_ashrrev_i32_e32 v213, 31, v212
	v_mul_f32_e32 v126, 0x45800000, v136
	v_cndmask_b32_e32 v126, v136, v126, vcc
	v_pk_mul_f32 v[124:125], v[124:125], v[126:127] op_sel_hi:[1,0]
	v_pk_mul_f32 v[122:123], v[122:123], v[126:127] op_sel_hi:[1,0]
	v_pk_mul_f32 v[124:125], v[12:13], v[124:125]
	v_pk_mul_f32 v[128:129], v[130:131], v[162:163]
	v_pk_mul_f32 v[120:121], v[120:121], v[124:125]
	v_pk_mul_f32 v[124:125], v[166:167], v[126:127] op_sel_hi:[1,0]
	v_pk_mul_f32 v[130:131], v[170:171], v[164:165]
	v_pk_mul_f32 v[124:125], v[14:15], v[124:125]
	v_pk_mul_f32 v[122:123], v[8:9], v[122:123]
	v_pk_mul_f32 v[124:125], v[130:131], v[124:125]
	v_pk_mul_f32 v[122:123], v[128:129], v[122:123]
	v_pk_mul_f32 v[128:129], v[158:159], v[126:127] op_sel_hi:[1,0]
	v_pk_mul_f32 v[130:131], v[132:133], v[126:127] op_sel_hi:[1,0]
	v_pk_mul_f32 v[132:133], v[152:153], v[126:127] op_sel_hi:[1,0]
	v_mul_f32_e32 v127, 0xbfb8aa3b, v148
	v_exp_f32_e32 v127, v127
	v_mul_f32_e32 v136, 0xbfb8aa3b, v149
	v_exp_f32_e32 v137, v136
	v_pk_mul_f32 v[128:129], v[10:11], v[128:129]
	v_add_f32_e32 v127, 1.0, v127
	v_rcp_f32_e32 v136, v127
	v_add_f32_e32 v127, 1.0, v137
	v_rcp_f32_e32 v137, v127
	v_pk_mul_f32 v[134:135], v[134:135], v[126:127] op_sel_hi:[1,0]
	v_mul_f32_e32 v127, 0xbfb8aa3b, v145
	v_pk_mul_f32 v[134:135], v[0:1], v[134:135]
	v_pk_mul_f32 v[136:137], v[136:137], v[148:149]
	v_exp_f32_e32 v127, v127
	v_pk_mul_f32 v[134:135], v[136:137], v[134:135]
	v_mul_f32_e32 v136, 0xbfb8aa3b, v144
	v_exp_f32_e32 v136, v136
	v_add_f32_e32 v127, 1.0, v127
	v_rcp_f32_e32 v127, v127
	v_mul_f32_e32 v137, v147, v126
	v_add_f32_e32 v136, 1.0, v136
	v_rcp_f32_e32 v204, v136
	v_mul_f32_e32 v138, v127, v145
	v_mul_f32_e32 v145, v146, v126
	v_pk_mul_f32 v[128:129], v[156:157], v[128:129]
	v_pk_mul_f32 v[126:127], v[204:205], v[144:145]
	v_pk_mul_f32 v[130:131], v[4:5], v[130:131]
	v_pk_mul_f32 v[132:133], v[6:7], v[132:133]
	v_mul_f32_e32 v136, v2, v137
	v_mov_b32_e32 v139, v126
	v_mov_b32_e32 v137, v127
	v_cvt_pk_bf16_f32 v120, v120, v121
	v_cvt_pk_bf16_f32 v121, v124, v125
	v_lshlrev_b64 v[124:125], 11, v[212:213]
	v_pk_mul_f32 v[130:131], v[140:141], v[130:131]
	v_pk_mul_f32 v[132:133], v[142:143], v[132:133]
	v_cvt_pk_bf16_f32 v122, v122, v123
	v_cvt_pk_bf16_f32 v123, v128, v129
	v_lshl_add_u64 v[124:125], v[192:193], 0, v[124:125]
	v_pk_mul_f32 v[126:127], v[138:139], v[136:137]
	global_store_dwordx4 v[124:125], v[120:123], off sc1
	s_nop 1
	v_cvt_pk_bf16_f32 v120, v130, v131
	v_cvt_pk_bf16_f32 v121, v132, v133
	v_cvt_pk_bf16_f32 v122, v134, v135
	v_cvt_pk_bf16_f32 v123, v126, v127
	global_store_dwordx4 v[124:125], v[120:123], off offset:16 sc1
.LBB0_1000:
	s_or_b64 exec, exec, s[12:13]
	v_add_u32_e32 v3, s33, v3
	v_cmp_gt_i32_e32 vcc, s3, v3
	s_and_saveexec_b64 s[12:13], vcc
	s_cbranch_execz .LBB0_1002
	s_waitcnt vmcnt(17)
	v_lshlrev_b32_e32 v123, 16, v115
	v_lshlrev_b32_e32 v125, 16, v111
	v_and_b32_e32 v122, 0xffff0000, v115
	v_and_b32_e32 v124, 0xffff0000, v111
	s_waitcnt vmcnt(15)
	v_and_b32_e32 v120, 0xffff0000, v119
	v_lshlrev_b32_e32 v121, 16, v119
	v_pk_add_f32 v[122:123], v[122:123], v[124:125]
	v_lshlrev_b32_e32 v124, 16, v118
	v_and_b32_e32 v125, 0xffff0000, v118
	v_lshlrev_b32_e32 v118, 16, v114
	v_and_b32_e32 v119, 0xffff0000, v114
	v_lshlrev_b32_e32 v114, 16, v110
	v_and_b32_e32 v115, 0xffff0000, v110
	v_pk_add_f32 v[110:111], v[114:115], v[118:119]
	v_lshlrev_b32_e32 v118, 16, v117
	v_and_b32_e32 v119, 0xffff0000, v117
	v_lshlrev_b32_e32 v128, 16, v113
	v_and_b32_e32 v129, 0xffff0000, v113
	v_mul_f32_e32 v113, 0xbfb8aa3b, v118
	v_exp_f32_e32 v113, v113
	v_mul_f32_e32 v117, 0xbfb8aa3b, v119
	v_exp_f32_e32 v117, v117
	v_lshlrev_b32_e32 v130, 16, v109
	v_add_f32_e32 v113, 1.0, v113
	v_rcp_f32_e32 v132, v113
	v_add_f32_e32 v113, 1.0, v117
	v_rcp_f32_e32 v133, v113
	v_and_b32_e32 v131, 0xffff0000, v109
	v_and_b32_e32 v117, 0xffff0000, v112
	v_lshlrev_b32_e32 v142, 16, v105
	v_pk_mul_f32 v[118:119], v[132:133], v[118:119]
	v_lshlrev_b32_e32 v132, 16, v116
	v_and_b32_e32 v133, 0xffff0000, v116
	v_mul_f32_e32 v109, 0xbfb8aa3b, v132
	v_lshlrev_b32_e32 v116, 16, v112
	v_exp_f32_e32 v109, v109
	v_mul_f32_e32 v112, 0xbfb8aa3b, v133
	v_exp_f32_e32 v113, v112
	v_lshlrev_b32_e32 v112, 16, v108
	v_add_f32_e32 v109, 1.0, v109
	v_rcp_f32_e32 v134, v109
	v_add_f32_e32 v109, 1.0, v113
	v_rcp_f32_e32 v135, v109
	v_and_b32_e32 v113, 0xffff0000, v108
	v_pk_add_f32 v[108:109], v[112:113], v[116:117]
	v_and_b32_e32 v143, 0xffff0000, v105
	v_pk_mul_f32 v[116:117], v[134:135], v[132:133]
	s_waitcnt vmcnt(14)
	v_lshlrev_b32_e32 v132, 16, v99
	v_and_b32_e32 v133, 0xffff0000, v99
	v_mul_f32_e32 v99, 0xbfb8aa3b, v132
	v_lshlrev_b32_e32 v134, 16, v107
	v_and_b32_e32 v135, 0xffff0000, v107
	v_exp_f32_e32 v99, v99
	v_mul_f32_e32 v107, 0xbfb8aa3b, v133
	v_exp_f32_e32 v107, v107
	v_lshlrev_b32_e32 v148, 16, v104
	v_add_f32_e32 v99, 1.0, v99
	v_rcp_f32_e32 v138, v99
	v_add_f32_e32 v99, 1.0, v107
	v_rcp_f32_e32 v139, v99
	v_and_b32_e32 v149, 0xffff0000, v104
	v_lshlrev_b32_e32 v104, 16, v100
	v_and_b32_e32 v105, 0xffff0000, v100
	v_lshlrev_b32_e32 v144, 16, v101
	v_and_b32_e32 v145, 0xffff0000, v101
	v_pk_add_f32 v[100:101], v[104:105], v[148:149]
	v_pk_mul_f32 v[132:133], v[138:139], v[132:133]
	v_lshlrev_b32_e32 v138, 16, v98
	v_pk_add_f32 v[142:143], v[144:145], v[142:143]
	v_pk_mul_f32 v[104:105], v[100:101], v[100:101]
	v_and_b32_e32 v139, 0xffff0000, v98
	v_lshlrev_b32_e32 v98, 16, v106
	v_and_b32_e32 v99, 0xffff0000, v106
	v_lshlrev_b32_e32 v106, 16, v102
	v_and_b32_e32 v107, 0xffff0000, v102
	v_mul_f32_e32 v102, 0xbfb8aa3b, v138
	v_pk_mul_f32 v[144:145], v[142:143], v[142:143]
	v_add_f32_e32 v104, v104, v105
	v_pk_add_f32 v[98:99], v[106:107], v[98:99]
	v_exp_f32_e32 v106, v102
	v_mul_f32_e32 v102, 0xbfb8aa3b, v139
	v_add_f32_e32 v104, v144, v104
	v_lshlrev_b32_e32 v136, 16, v103
	v_and_b32_e32 v137, 0xffff0000, v103
	v_exp_f32_e32 v107, v102
	v_pk_mul_f32 v[102:103], v[98:99], v[98:99]
	v_add_f32_e32 v104, v145, v104
	v_pk_add_f32 v[134:135], v[136:137], v[134:135]
	v_add_f32_e32 v102, v102, v104
	v_pk_mul_f32 v[136:137], v[134:135], v[134:135]
	v_add_f32_e32 v102, v103, v102
	v_add_f32_e32 v102, v136, v102
	v_pk_mul_f32 v[112:113], v[108:109], v[108:109]
	v_add_f32_e32 v102, v137, v102
	v_pk_add_f32 v[128:129], v[130:131], v[128:129]
	v_add_f32_e32 v102, v112, v102
	v_pk_mul_f32 v[130:131], v[128:129], v[128:129]
	v_lshlrev_b32_e32 v140, 16, v97
	v_add_f32_e32 v102, v113, v102
	v_and_b32_e32 v141, 0xffff0000, v97
	v_mul_f32_e32 v97, 0xbfb8aa3b, v140
	v_add_f32_e32 v102, v130, v102
	v_pk_mul_f32 v[114:115], v[110:111], v[110:111]
	v_exp_f32_e32 v97, v97
	v_add_f32_e32 v102, v131, v102
	v_add_f32_e32 v102, v114, v102
	v_pk_mul_f32 v[126:127], v[122:123], v[122:123]
	v_add_f32_e32 v102, v115, v102
	v_add_f32_e32 v102, v127, v102
	v_add_f32_e32 v97, 1.0, v97
	v_add_f32_e32 v104, v126, v102
	v_rcp_f32_e32 v146, v97
	v_mul_f32_e32 v97, 0xbfb8aa3b, v141
	ds_bpermute_b32 v105, v227, v104
	v_exp_f32_e32 v97, v97
	v_lshlrev_b32_e32 v102, 16, v96
	v_and_b32_e32 v103, 0xffff0000, v96
	v_add_f32_e32 v106, 1.0, v106
	v_add_f32_e32 v97, 1.0, v97
	s_waitcnt lgkmcnt(0)
	v_add_f32_e32 v96, v104, v105
	v_rcp_f32_e32 v147, v97
	ds_bpermute_b32 v97, v228, v96
	v_mul_f32_e32 v104, 0xbfb8aa3b, v102
	v_exp_f32_e32 v104, v104
	v_mul_f32_e32 v105, 0xbfb8aa3b, v103
	v_exp_f32_e32 v105, v105
	s_waitcnt lgkmcnt(0)
	v_add_f32_e32 v112, v96, v97
	ds_bpermute_b32 v113, v229, v112
	v_add_f32_e32 v96, 1.0, v104
	v_add_f32_e32 v97, 1.0, v105
	v_rcp_f32_e32 v96, v96
	v_rcp_f32_e32 v97, v97
	s_waitcnt lgkmcnt(0)
	v_add_f32_e32 v104, v112, v113
	v_fmamk_f32 v104, v104, 0x3c000000, v226
	v_mul_f32_e32 v105, 0x4b800000, v104
	v_cmp_gt_f32_e32 vcc, s29, v104
	v_add_f32_e32 v107, 1.0, v107
	v_pk_mul_f32 v[96:97], v[96:97], v[102:103]
	v_cndmask_b32_e32 v104, v104, v105, vcc
	v_rsq_f32_e32 v112, v104
	v_rcp_f32_e32 v106, v106
	v_rcp_f32_e32 v107, v107
	v_ashrrev_i32_e32 v211, 31, v210
	v_mul_f32_e32 v102, 0x45800000, v112
	v_cndmask_b32_e32 v102, v112, v102, vcc
	v_pk_mul_f32 v[100:101], v[100:101], v[102:103] op_sel_hi:[1,0]
	v_pk_mul_f32 v[98:99], v[98:99], v[102:103] op_sel_hi:[1,0]
	v_pk_mul_f32 v[100:101], v[12:13], v[100:101]
	v_pk_mul_f32 v[104:105], v[106:107], v[138:139]
	v_pk_mul_f32 v[96:97], v[96:97], v[100:101]
	v_pk_mul_f32 v[100:101], v[142:143], v[102:103] op_sel_hi:[1,0]
	v_pk_mul_f32 v[106:107], v[146:147], v[140:141]
	v_pk_mul_f32 v[100:101], v[14:15], v[100:101]
	v_pk_mul_f32 v[98:99], v[8:9], v[98:99]
	v_pk_mul_f32 v[100:101], v[106:107], v[100:101]
	v_pk_mul_f32 v[98:99], v[104:105], v[98:99]
	v_pk_mul_f32 v[104:105], v[134:135], v[102:103] op_sel_hi:[1,0]
	v_pk_mul_f32 v[106:107], v[108:109], v[102:103] op_sel_hi:[1,0]
	v_pk_mul_f32 v[108:109], v[128:129], v[102:103] op_sel_hi:[1,0]
	v_mul_f32_e32 v103, 0xbfb8aa3b, v124
	v_exp_f32_e32 v103, v103
	v_mul_f32_e32 v112, 0xbfb8aa3b, v125
	v_exp_f32_e32 v113, v112
	v_pk_mul_f32 v[104:105], v[10:11], v[104:105]
	v_add_f32_e32 v103, 1.0, v103
	v_rcp_f32_e32 v112, v103
	v_add_f32_e32 v103, 1.0, v113
	v_rcp_f32_e32 v113, v103
	v_pk_mul_f32 v[110:111], v[110:111], v[102:103] op_sel_hi:[1,0]
	v_mul_f32_e32 v103, 0xbfb8aa3b, v121
	v_pk_mul_f32 v[110:111], v[0:1], v[110:111]
	v_pk_mul_f32 v[112:113], v[112:113], v[124:125]
	v_exp_f32_e32 v103, v103
	v_pk_mul_f32 v[110:111], v[112:113], v[110:111]
	v_mul_f32_e32 v112, 0xbfb8aa3b, v120
	v_exp_f32_e32 v112, v112
	v_add_f32_e32 v103, 1.0, v103
	v_rcp_f32_e32 v103, v103
	v_mul_f32_e32 v113, v123, v102
	v_add_f32_e32 v112, 1.0, v112
	v_rcp_f32_e32 v204, v112
	v_mul_f32_e32 v114, v103, v121
	v_mul_f32_e32 v121, v122, v102
	v_pk_mul_f32 v[104:105], v[132:133], v[104:105]
	v_pk_mul_f32 v[102:103], v[204:205], v[120:121]
	v_pk_mul_f32 v[106:107], v[4:5], v[106:107]
	v_pk_mul_f32 v[108:109], v[6:7], v[108:109]
	v_mul_f32_e32 v112, v2, v113
	v_mov_b32_e32 v115, v102
	v_mov_b32_e32 v113, v103
	v_cvt_pk_bf16_f32 v96, v96, v97
	v_cvt_pk_bf16_f32 v97, v100, v101
	v_lshlrev_b64 v[100:101], 11, v[210:211]
	v_pk_mul_f32 v[106:107], v[116:117], v[106:107]
	v_pk_mul_f32 v[108:109], v[118:119], v[108:109]
	v_cvt_pk_bf16_f32 v98, v98, v99
	v_cvt_pk_bf16_f32 v99, v104, v105
	v_lshl_add_u64 v[100:101], v[192:193], 0, v[100:101]
	v_pk_mul_f32 v[102:103], v[114:115], v[112:113]
	global_store_dwordx4 v[100:101], v[96:99], off sc1
	s_nop 1
	v_cvt_pk_bf16_f32 v96, v106, v107
	v_cvt_pk_bf16_f32 v97, v108, v109
	v_cvt_pk_bf16_f32 v98, v110, v111
	v_cvt_pk_bf16_f32 v99, v102, v103
	global_store_dwordx4 v[100:101], v[96:99], off offset:16 sc1
.LBB0_1002:
	s_or_b64 exec, exec, s[12:13]
	v_add_u32_e32 v3, s33, v3
	v_cmp_gt_i32_e32 vcc, s3, v3
	s_and_saveexec_b64 s[12:13], vcc
	s_cbranch_execz .LBB0_1004
	s_waitcnt vmcnt(15)
	v_and_b32_e32 v101, 0xffff0000, v83
	v_and_b32_e32 v100, 0xffff0000, v79
	s_waitcnt vmcnt(11)
	v_and_b32_e32 v103, 0xffff0000, v87
	v_and_b32_e32 v102, 0xffff0000, v91
	s_waitcnt vmcnt(9)
	v_lshlrev_b32_e32 v97, 16, v95
	v_and_b32_e32 v96, 0xffff0000, v95
	v_lshlrev_b32_e32 v95, 16, v79
	v_lshlrev_b32_e32 v98, 16, v91
	v_pk_add_f32 v[100:101], v[100:101], v[102:103]
	v_add_f32_e32 v99, v95, v98
	v_lshlrev_b32_e32 v79, 16, v83
	v_lshlrev_b32_e32 v83, 16, v87
	v_mov_b32_e32 v98, v100
	v_mov_b32_e32 v102, v101
	v_lshlrev_b32_e32 v100, 16, v94
	v_and_b32_e32 v101, 0xffff0000, v94
	v_lshlrev_b32_e32 v94, 16, v90
	v_and_b32_e32 v95, 0xffff0000, v90
	v_lshlrev_b32_e32 v90, 16, v78
	v_and_b32_e32 v91, 0xffff0000, v78
	v_add_f32_e32 v103, v79, v83
	v_pk_add_f32 v[78:79], v[90:91], v[94:95]
	v_lshlrev_b32_e32 v90, 16, v82
	v_and_b32_e32 v91, 0xffff0000, v82
	v_lshlrev_b32_e32 v82, 16, v86
	v_and_b32_e32 v83, 0xffff0000, v86
	v_pk_add_f32 v[82:83], v[90:91], v[82:83]
	v_lshlrev_b32_e32 v86, 16, v89
	v_pk_add_f32 v[78:79], v[78:79], v[82:83]
	v_lshlrev_b32_e32 v82, 16, v93
	v_and_b32_e32 v83, 0xffff0000, v93
	v_and_b32_e32 v87, 0xffff0000, v89
	v_lshlrev_b32_e32 v94, 16, v77
	v_and_b32_e32 v95, 0xffff0000, v77
	v_mul_f32_e32 v77, 0xbfb8aa3b, v82
	v_pk_add_f32 v[86:87], v[94:95], v[86:87]
	v_lshlrev_b32_e32 v94, 16, v81
	v_and_b32_e32 v95, 0xffff0000, v81
	v_exp_f32_e32 v77, v77
	v_mul_f32_e32 v81, 0xbfb8aa3b, v83
	v_exp_f32_e32 v81, v81
	v_lshlrev_b32_e32 v104, 16, v85
	v_and_b32_e32 v105, 0xffff0000, v85
	v_add_f32_e32 v77, 1.0, v77
	v_pk_add_f32 v[94:95], v[94:95], v[104:105]
	v_lshlrev_b32_e32 v104, 16, v92
	v_rcp_f32_e32 v106, v77
	v_add_f32_e32 v77, 1.0, v81
	v_and_b32_e32 v105, 0xffff0000, v92
	v_mul_f32_e32 v81, 0xbfb8aa3b, v104
	v_lshlrev_b32_e32 v92, 16, v88
	v_and_b32_e32 v93, 0xffff0000, v88
	v_lshlrev_b32_e32 v88, 16, v76
	v_and_b32_e32 v89, 0xffff0000, v76
	v_exp_f32_e32 v85, v81
	v_mul_f32_e32 v81, 0xbfb8aa3b, v105
	v_rcp_f32_e32 v107, v77
	v_pk_add_f32 v[76:77], v[88:89], v[92:93]
	v_exp_f32_e32 v92, v81
	v_lshlrev_b32_e32 v88, 16, v80
	v_and_b32_e32 v89, 0xffff0000, v80
	v_lshlrev_b32_e32 v80, 16, v84
	v_and_b32_e32 v81, 0xffff0000, v84
	v_add_f32_e32 v84, 1.0, v85
	v_add_f32_e32 v85, 1.0, v92
	v_rcp_f32_e32 v84, v84
	v_rcp_f32_e32 v85, v85
	v_pk_add_f32 v[80:81], v[88:89], v[80:81]
	s_waitcnt vmcnt(8)
	v_lshlrev_b32_e32 v88, 16, v67
	v_and_b32_e32 v89, 0xffff0000, v67
	v_pk_mul_f32 v[84:85], v[84:85], v[104:105]
	v_lshlrev_b32_e32 v92, 16, v75
	v_and_b32_e32 v93, 0xffff0000, v75
	v_lshlrev_b32_e32 v104, 16, v59
	v_and_b32_e32 v105, 0xffff0000, v59
	v_mul_f32_e32 v59, 0xbfb8aa3b, v88
	v_pk_add_f32 v[92:93], v[104:105], v[92:93]
	v_lshlrev_b32_e32 v104, 16, v63
	v_and_b32_e32 v105, 0xffff0000, v63
	v_exp_f32_e32 v59, v59
	v_mul_f32_e32 v63, 0xbfb8aa3b, v89
	v_exp_f32_e32 v63, v63
	v_pk_mul_f32 v[82:83], v[106:107], v[82:83]
	v_add_f32_e32 v59, 1.0, v59
	v_rcp_f32_e32 v108, v59
	v_add_f32_e32 v59, 1.0, v63
	v_rcp_f32_e32 v109, v59
	v_lshlrev_b32_e32 v106, 16, v71
	v_and_b32_e32 v107, 0xffff0000, v71
	v_pk_add_f32 v[104:105], v[104:105], v[106:107]
	v_lshlrev_b32_e32 v106, 16, v66
	v_and_b32_e32 v107, 0xffff0000, v66
	v_lshlrev_b32_e32 v66, 16, v74
	v_and_b32_e32 v67, 0xffff0000, v74
	v_lshlrev_b32_e32 v74, 16, v58
	v_and_b32_e32 v75, 0xffff0000, v58
	v_pk_add_f32 v[58:59], v[74:75], v[66:67]
	v_lshlrev_b32_e32 v66, 16, v62
	v_and_b32_e32 v67, 0xffff0000, v62
	v_lshlrev_b32_e32 v62, 16, v70
	v_and_b32_e32 v63, 0xffff0000, v70
	v_lshlrev_b32_e32 v70, 16, v65
	v_pk_mul_f32 v[88:89], v[108:109], v[88:89]
	v_lshlrev_b32_e32 v108, 16, v57
	v_and_b32_e32 v109, 0xffff0000, v57
	v_mul_f32_e32 v57, 0xbfb8aa3b, v70
	v_exp_f32_e32 v57, v57
	v_lshlrev_b32_e32 v74, 16, v73
	v_and_b32_e32 v75, 0xffff0000, v73
	v_and_b32_e32 v71, 0xffff0000, v65
	v_pk_add_f32 v[74:75], v[108:109], v[74:75]
	v_lshlrev_b32_e32 v108, 16, v61
	v_and_b32_e32 v109, 0xffff0000, v61
	v_lshlrev_b32_e32 v110, 16, v69
	v_and_b32_e32 v111, 0xffff0000, v69
	v_add_f32_e32 v57, 1.0, v57
	v_pk_add_f32 v[108:109], v[108:109], v[110:111]
	v_rcp_f32_e32 v110, v57
	v_mul_f32_e32 v57, 0xbfb8aa3b, v71
	v_lshlrev_b32_e32 v112, 16, v72
	v_and_b32_e32 v113, 0xffff0000, v72
	v_lshlrev_b32_e32 v72, 16, v56
	v_and_b32_e32 v73, 0xffff0000, v56
	v_exp_f32_e32 v65, v57
	v_pk_add_f32 v[56:57], v[72:73], v[112:113]
	v_lshlrev_b32_e32 v72, 16, v60
	v_and_b32_e32 v73, 0xffff0000, v60
	v_lshlrev_b32_e32 v60, 16, v68
	v_and_b32_e32 v61, 0xffff0000, v68
	v_pk_add_f32 v[60:61], v[72:73], v[60:61]
	v_pk_add_f32 v[62:63], v[66:67], v[62:63]
	v_pk_add_f32 v[56:57], v[56:57], v[60:61]
	v_pk_add_f32 v[74:75], v[74:75], v[108:109]
	v_pk_mul_f32 v[60:61], v[56:57], v[56:57]
	v_pk_add_f32 v[58:59], v[58:59], v[62:63]
	v_mul_f32_e32 v62, 0xbfb8aa3b, v106
	v_pk_mul_f32 v[108:109], v[74:75], v[74:75]
	v_add_f32_e32 v60, v60, v61
	v_exp_f32_e32 v66, v62
	v_mul_f32_e32 v62, 0xbfb8aa3b, v107
	v_add_f32_e32 v60, v108, v60
	v_exp_f32_e32 v67, v62
	v_pk_mul_f32 v[62:63], v[58:59], v[58:59]
	v_add_f32_e32 v60, v109, v60
	v_pk_add_f32 v[92:93], v[92:93], v[104:105]
	v_add_f32_e32 v60, v62, v60
	v_pk_mul_f32 v[104:105], v[92:93], v[92:93]
	v_add_f32_e32 v60, v63, v60
	v_pk_add_f32 v[76:77], v[76:77], v[80:81]
	v_add_f32_e32 v60, v104, v60
	v_pk_mul_f32 v[80:81], v[76:77], v[76:77]
	v_add_f32_e32 v60, v105, v60
	v_pk_add_f32 v[86:87], v[86:87], v[94:95]
	v_add_f32_e32 v60, v80, v60
	v_pk_mul_f32 v[94:95], v[86:87], v[86:87]
	v_add_f32_e32 v60, v81, v60
	v_add_f32_e32 v60, v94, v60
	v_pk_mul_f32 v[90:91], v[78:79], v[78:79]
	v_add_f32_e32 v60, v95, v60
	v_pk_add_f32 v[98:99], v[98:99], v[102:103]
	v_add_f32_e32 v60, v90, v60
	v_pk_mul_f32 v[102:103], v[98:99], v[98:99]
	v_add_f32_e32 v60, v91, v60
	v_add_f32_e32 v60, v103, v60
	v_add_f32_e32 v62, v102, v60
	ds_bpermute_b32 v63, v227, v62
	v_add_f32_e32 v60, 1.0, v65
	v_rcp_f32_e32 v111, v60
	v_lshlrev_b32_e32 v60, 16, v64
	v_and_b32_e32 v61, 0xffff0000, v64
	s_waitcnt lgkmcnt(0)
	v_add_f32_e32 v62, v62, v63
	ds_bpermute_b32 v63, v228, v62
	v_mul_f32_e32 v64, 0xbfb8aa3b, v60
	v_exp_f32_e32 v64, v64
	v_mul_f32_e32 v65, 0xbfb8aa3b, v61
	v_exp_f32_e32 v65, v65
	s_waitcnt lgkmcnt(0)
	v_add_f32_e32 v68, v62, v63
	ds_bpermute_b32 v69, v229, v68
	v_add_f32_e32 v62, 1.0, v64
	v_add_f32_e32 v63, 1.0, v65
	v_rcp_f32_e32 v62, v62
	v_rcp_f32_e32 v63, v63
	s_waitcnt lgkmcnt(0)
	v_add_f32_e32 v64, v68, v69
	v_fmamk_f32 v64, v64, 0x3c000000, v226
	v_mul_f32_e32 v65, 0x4b800000, v64
	v_cmp_gt_f32_e32 vcc, s29, v64
	v_add_f32_e32 v66, 1.0, v66
	v_add_f32_e32 v67, 1.0, v67
	v_cndmask_b32_e32 v64, v64, v65, vcc
	v_rsq_f32_e32 v68, v64
	v_pk_mul_f32 v[60:61], v[62:63], v[60:61]
	v_rcp_f32_e32 v66, v66
	v_rcp_f32_e32 v67, v67
	v_mul_f32_e32 v62, 0x45800000, v68
	v_cndmask_b32_e32 v62, v68, v62, vcc
	v_pk_mul_f32 v[56:57], v[56:57], v[62:63] op_sel_hi:[1,0]
	v_pk_mul_f32 v[58:59], v[58:59], v[62:63] op_sel_hi:[1,0]
	v_pk_mul_f32 v[56:57], v[12:13], v[56:57]
	v_pk_mul_f32 v[64:65], v[66:67], v[106:107]
	v_pk_mul_f32 v[56:57], v[60:61], v[56:57]
	v_pk_mul_f32 v[60:61], v[74:75], v[62:63] op_sel_hi:[1,0]
	v_pk_mul_f32 v[66:67], v[110:111], v[70:71]
	v_pk_mul_f32 v[60:61], v[14:15], v[60:61]
	v_pk_mul_f32 v[58:59], v[8:9], v[58:59]
	v_pk_mul_f32 v[60:61], v[66:67], v[60:61]
	v_pk_mul_f32 v[58:59], v[64:65], v[58:59]
	v_pk_mul_f32 v[64:65], v[92:93], v[62:63] op_sel_hi:[1,0]
	v_pk_mul_f32 v[66:67], v[76:77], v[62:63] op_sel_hi:[1,0]
	v_pk_mul_f32 v[68:69], v[86:87], v[62:63] op_sel_hi:[1,0]
	v_mul_f32_e32 v63, 0xbfb8aa3b, v100
	v_exp_f32_e32 v63, v63
	v_mul_f32_e32 v70, 0xbfb8aa3b, v101
	v_exp_f32_e32 v71, v70
	v_pk_mul_f32 v[64:65], v[10:11], v[64:65]
	v_add_f32_e32 v63, 1.0, v63
	v_rcp_f32_e32 v70, v63
	v_add_f32_e32 v63, 1.0, v71
	v_rcp_f32_e32 v71, v63
	v_pk_mul_f32 v[72:73], v[78:79], v[62:63] op_sel_hi:[1,0]
	v_mul_f32_e32 v63, 0xbfb8aa3b, v97
	v_pk_mul_f32 v[72:73], v[0:1], v[72:73]
	v_pk_mul_f32 v[70:71], v[70:71], v[100:101]
	v_exp_f32_e32 v63, v63
	v_pk_mul_f32 v[70:71], v[70:71], v[72:73]
	v_mul_f32_e32 v72, 0xbfb8aa3b, v96
	v_exp_f32_e32 v72, v72
	v_add_f32_e32 v63, 1.0, v63
	v_rcp_f32_e32 v63, v63
	v_mul_f32_e32 v73, v99, v62
	v_add_f32_e32 v72, 1.0, v72
	v_rcp_f32_e32 v204, v72
	v_mul_f32_e32 v74, v63, v97
	v_mul_f32_e32 v97, v98, v62
	v_ashrrev_i32_e32 v209, 31, v208
	v_pk_mul_f32 v[62:63], v[204:205], v[96:97]
	v_pk_mul_f32 v[64:65], v[88:89], v[64:65]
	v_pk_mul_f32 v[66:67], v[4:5], v[66:67]
	v_pk_mul_f32 v[68:69], v[6:7], v[68:69]
	v_mul_f32_e32 v72, v2, v73
	v_mov_b32_e32 v75, v62
	v_mov_b32_e32 v73, v63
	v_cvt_pk_bf16_f32 v56, v56, v57
	v_cvt_pk_bf16_f32 v57, v60, v61
	v_lshlrev_b64 v[60:61], 11, v[208:209]
	v_pk_mul_f32 v[66:67], v[84:85], v[66:67]
	v_pk_mul_f32 v[68:69], v[82:83], v[68:69]
	v_cvt_pk_bf16_f32 v58, v58, v59
	v_cvt_pk_bf16_f32 v59, v64, v65
	v_lshl_add_u64 v[60:61], v[192:193], 0, v[60:61]
	v_pk_mul_f32 v[62:63], v[74:75], v[72:73]
	global_store_dwordx4 v[60:61], v[56:59], off sc1
	s_nop 1
	v_cvt_pk_bf16_f32 v56, v66, v67
	v_cvt_pk_bf16_f32 v57, v68, v69
	v_cvt_pk_bf16_f32 v58, v70, v71
	v_cvt_pk_bf16_f32 v59, v62, v63
	global_store_dwordx4 v[60:61], v[56:59], off offset:16 sc1
.LBB0_1004:
	s_or_b64 exec, exec, s[12:13]
	v_add_u32_e32 v3, s33, v3
	v_cmp_gt_i32_e32 vcc, s3, v3
	s_and_saveexec_b64 s[12:13], vcc
	s_cbranch_execz .LBB0_991
	s_waitcnt vmcnt(9)
	v_and_b32_e32 v61, 0xffff0000, v43
	v_and_b32_e32 v60, 0xffff0000, v39
	s_waitcnt vmcnt(5)
	v_and_b32_e32 v63, 0xffff0000, v47
	v_and_b32_e32 v62, 0xffff0000, v51
	s_waitcnt vmcnt(3)
	v_lshlrev_b32_e32 v57, 16, v55
	v_and_b32_e32 v56, 0xffff0000, v55
	v_lshlrev_b32_e32 v55, 16, v39
	v_lshlrev_b32_e32 v58, 16, v51
	v_pk_add_f32 v[60:61], v[60:61], v[62:63]
	v_add_f32_e32 v59, v55, v58
	v_lshlrev_b32_e32 v39, 16, v43
	v_lshlrev_b32_e32 v43, 16, v47
	v_mov_b32_e32 v58, v60
	v_mov_b32_e32 v62, v61
	v_lshlrev_b32_e32 v60, 16, v54
	v_and_b32_e32 v61, 0xffff0000, v54
	v_lshlrev_b32_e32 v54, 16, v50
	v_and_b32_e32 v55, 0xffff0000, v50
	v_lshlrev_b32_e32 v50, 16, v38
	v_and_b32_e32 v51, 0xffff0000, v38
	v_add_f32_e32 v63, v39, v43
	v_pk_add_f32 v[38:39], v[50:51], v[54:55]
	v_lshlrev_b32_e32 v50, 16, v42
	v_and_b32_e32 v51, 0xffff0000, v42
	v_lshlrev_b32_e32 v42, 16, v46
	v_and_b32_e32 v43, 0xffff0000, v46
	v_pk_add_f32 v[42:43], v[50:51], v[42:43]
	v_lshlrev_b32_e32 v46, 16, v49
	v_pk_add_f32 v[38:39], v[38:39], v[42:43]
	v_lshlrev_b32_e32 v42, 16, v53
	v_and_b32_e32 v43, 0xffff0000, v53
	v_and_b32_e32 v47, 0xffff0000, v49
	v_lshlrev_b32_e32 v54, 16, v37
	v_and_b32_e32 v55, 0xffff0000, v37
	v_mul_f32_e32 v37, 0xbfb8aa3b, v42
	v_pk_add_f32 v[46:47], v[54:55], v[46:47]
	v_lshlrev_b32_e32 v54, 16, v41
	v_and_b32_e32 v55, 0xffff0000, v41
	v_exp_f32_e32 v37, v37
	v_mul_f32_e32 v41, 0xbfb8aa3b, v43
	v_exp_f32_e32 v41, v41
	v_lshlrev_b32_e32 v64, 16, v45
	v_and_b32_e32 v65, 0xffff0000, v45
	v_add_f32_e32 v37, 1.0, v37
	v_pk_add_f32 v[54:55], v[54:55], v[64:65]
	v_lshlrev_b32_e32 v64, 16, v52
	v_rcp_f32_e32 v66, v37
	v_add_f32_e32 v37, 1.0, v41
	v_and_b32_e32 v65, 0xffff0000, v52
	v_mul_f32_e32 v41, 0xbfb8aa3b, v64
	v_lshlrev_b32_e32 v52, 16, v48
	v_and_b32_e32 v53, 0xffff0000, v48
	v_lshlrev_b32_e32 v48, 16, v36
	v_and_b32_e32 v49, 0xffff0000, v36
	v_exp_f32_e32 v45, v41
	v_mul_f32_e32 v41, 0xbfb8aa3b, v65
	v_rcp_f32_e32 v67, v37
	v_pk_add_f32 v[36:37], v[48:49], v[52:53]
	v_exp_f32_e32 v52, v41
	v_lshlrev_b32_e32 v48, 16, v40
	v_and_b32_e32 v49, 0xffff0000, v40
	v_lshlrev_b32_e32 v40, 16, v44
	v_and_b32_e32 v41, 0xffff0000, v44
	v_add_f32_e32 v44, 1.0, v45
	v_add_f32_e32 v45, 1.0, v52
	v_rcp_f32_e32 v44, v44
	v_rcp_f32_e32 v45, v45
	v_pk_add_f32 v[40:41], v[48:49], v[40:41]
	s_waitcnt vmcnt(2)
	v_lshlrev_b32_e32 v48, 16, v27
	v_and_b32_e32 v49, 0xffff0000, v27
	v_pk_mul_f32 v[44:45], v[44:45], v[64:65]
	v_lshlrev_b32_e32 v52, 16, v35
	v_and_b32_e32 v53, 0xffff0000, v35
	v_lshlrev_b32_e32 v64, 16, v19
	v_and_b32_e32 v65, 0xffff0000, v19
	v_mul_f32_e32 v19, 0xbfb8aa3b, v48
	v_pk_add_f32 v[52:53], v[64:65], v[52:53]
	v_lshlrev_b32_e32 v64, 16, v23
	v_and_b32_e32 v65, 0xffff0000, v23
	v_exp_f32_e32 v19, v19
	v_mul_f32_e32 v23, 0xbfb8aa3b, v49
	v_exp_f32_e32 v23, v23
	v_pk_mul_f32 v[42:43], v[66:67], v[42:43]
	v_add_f32_e32 v19, 1.0, v19
	v_rcp_f32_e32 v68, v19
	v_add_f32_e32 v19, 1.0, v23
	v_rcp_f32_e32 v69, v19
	v_lshlrev_b32_e32 v66, 16, v31
	v_and_b32_e32 v67, 0xffff0000, v31
	v_pk_add_f32 v[64:65], v[64:65], v[66:67]
	v_lshlrev_b32_e32 v66, 16, v26
	v_and_b32_e32 v67, 0xffff0000, v26
	v_lshlrev_b32_e32 v26, 16, v34
	v_and_b32_e32 v27, 0xffff0000, v34
	v_lshlrev_b32_e32 v34, 16, v18
	v_and_b32_e32 v35, 0xffff0000, v18
	v_pk_add_f32 v[18:19], v[34:35], v[26:27]
	v_lshlrev_b32_e32 v26, 16, v22
	v_and_b32_e32 v27, 0xffff0000, v22
	v_lshlrev_b32_e32 v22, 16, v30
	v_and_b32_e32 v23, 0xffff0000, v30
	v_lshlrev_b32_e32 v30, 16, v25
	v_pk_mul_f32 v[48:49], v[68:69], v[48:49]
	v_lshlrev_b32_e32 v68, 16, v17
	v_and_b32_e32 v69, 0xffff0000, v17
	v_mul_f32_e32 v17, 0xbfb8aa3b, v30
	v_exp_f32_e32 v17, v17
	v_lshlrev_b32_e32 v34, 16, v33
	v_and_b32_e32 v35, 0xffff0000, v33
	v_and_b32_e32 v31, 0xffff0000, v25
	v_pk_add_f32 v[34:35], v[68:69], v[34:35]
	v_lshlrev_b32_e32 v68, 16, v21
	v_and_b32_e32 v69, 0xffff0000, v21
	v_lshlrev_b32_e32 v70, 16, v29
	v_and_b32_e32 v71, 0xffff0000, v29
	v_add_f32_e32 v17, 1.0, v17
	v_pk_add_f32 v[68:69], v[68:69], v[70:71]
	v_rcp_f32_e32 v70, v17
	v_mul_f32_e32 v17, 0xbfb8aa3b, v31
	v_lshlrev_b32_e32 v72, 16, v32
	v_and_b32_e32 v73, 0xffff0000, v32
	v_lshlrev_b32_e32 v32, 16, v16
	v_and_b32_e32 v33, 0xffff0000, v16
	v_exp_f32_e32 v25, v17
	v_pk_add_f32 v[16:17], v[32:33], v[72:73]
	v_lshlrev_b32_e32 v32, 16, v20
	v_and_b32_e32 v33, 0xffff0000, v20
	v_lshlrev_b32_e32 v20, 16, v28
	v_and_b32_e32 v21, 0xffff0000, v28
	v_pk_add_f32 v[20:21], v[32:33], v[20:21]
	v_pk_add_f32 v[22:23], v[26:27], v[22:23]
	v_pk_add_f32 v[16:17], v[16:17], v[20:21]
	v_pk_add_f32 v[34:35], v[34:35], v[68:69]
	v_pk_mul_f32 v[20:21], v[16:17], v[16:17]
	v_pk_add_f32 v[18:19], v[18:19], v[22:23]
	v_mul_f32_e32 v22, 0xbfb8aa3b, v66
	v_pk_mul_f32 v[68:69], v[34:35], v[34:35]
	v_add_f32_e32 v20, v20, v21
	v_exp_f32_e32 v26, v22
	v_mul_f32_e32 v22, 0xbfb8aa3b, v67
	v_add_f32_e32 v20, v68, v20
	v_exp_f32_e32 v27, v22
	v_pk_mul_f32 v[22:23], v[18:19], v[18:19]
	v_add_f32_e32 v20, v69, v20
	v_pk_add_f32 v[52:53], v[52:53], v[64:65]
	v_add_f32_e32 v20, v22, v20
	v_pk_mul_f32 v[64:65], v[52:53], v[52:53]
	v_add_f32_e32 v20, v23, v20
	v_pk_add_f32 v[36:37], v[36:37], v[40:41]
	v_add_f32_e32 v20, v64, v20
	v_pk_mul_f32 v[40:41], v[36:37], v[36:37]
	v_add_f32_e32 v20, v65, v20
	v_pk_add_f32 v[46:47], v[46:47], v[54:55]
	v_add_f32_e32 v20, v40, v20
	v_pk_mul_f32 v[54:55], v[46:47], v[46:47]
	v_add_f32_e32 v20, v41, v20
	v_add_f32_e32 v20, v54, v20
	v_pk_mul_f32 v[50:51], v[38:39], v[38:39]
	v_add_f32_e32 v20, v55, v20
	v_pk_add_f32 v[58:59], v[58:59], v[62:63]
	v_add_f32_e32 v20, v50, v20
	v_pk_mul_f32 v[62:63], v[58:59], v[58:59]
	v_add_f32_e32 v20, v51, v20
	v_add_f32_e32 v20, v63, v20
	v_add_f32_e32 v22, v62, v20
	ds_bpermute_b32 v23, v227, v22
	v_add_f32_e32 v20, 1.0, v25
	v_rcp_f32_e32 v71, v20
	v_lshlrev_b32_e32 v20, 16, v24
	v_and_b32_e32 v21, 0xffff0000, v24
	s_waitcnt lgkmcnt(0)
	v_add_f32_e32 v22, v22, v23
	ds_bpermute_b32 v23, v228, v22
	v_mul_f32_e32 v24, 0xbfb8aa3b, v20
	v_exp_f32_e32 v24, v24
	v_mul_f32_e32 v25, 0xbfb8aa3b, v21
	v_exp_f32_e32 v25, v25
	s_waitcnt lgkmcnt(0)
	v_add_f32_e32 v28, v22, v23
	ds_bpermute_b32 v29, v229, v28
	v_add_f32_e32 v22, 1.0, v24
	v_add_f32_e32 v23, 1.0, v25
	v_rcp_f32_e32 v22, v22
	v_rcp_f32_e32 v23, v23
	s_waitcnt lgkmcnt(0)
	v_add_f32_e32 v24, v28, v29
	v_fmamk_f32 v24, v24, 0x3c000000, v226
	v_mul_f32_e32 v25, 0x4b800000, v24
	v_cmp_gt_f32_e32 vcc, s29, v24
	v_add_f32_e32 v26, 1.0, v26
	v_add_f32_e32 v27, 1.0, v27
	v_cndmask_b32_e32 v24, v24, v25, vcc
	v_rsq_f32_e32 v28, v24
	v_pk_mul_f32 v[20:21], v[22:23], v[20:21]
	v_rcp_f32_e32 v26, v26
	v_rcp_f32_e32 v27, v27
	v_mul_f32_e32 v22, 0x45800000, v28
	v_cndmask_b32_e32 v22, v28, v22, vcc
	v_pk_mul_f32 v[16:17], v[16:17], v[22:23] op_sel_hi:[1,0]
	v_pk_mul_f32 v[18:19], v[18:19], v[22:23] op_sel_hi:[1,0]
	v_pk_mul_f32 v[16:17], v[12:13], v[16:17]
	v_pk_mul_f32 v[24:25], v[26:27], v[66:67]
	v_pk_mul_f32 v[16:17], v[20:21], v[16:17]
	v_pk_mul_f32 v[20:21], v[34:35], v[22:23] op_sel_hi:[1,0]
	v_pk_mul_f32 v[26:27], v[70:71], v[30:31]
	v_pk_mul_f32 v[20:21], v[14:15], v[20:21]
	v_pk_mul_f32 v[18:19], v[8:9], v[18:19]
	v_pk_mul_f32 v[20:21], v[26:27], v[20:21]
	v_pk_mul_f32 v[18:19], v[24:25], v[18:19]
	v_pk_mul_f32 v[24:25], v[52:53], v[22:23] op_sel_hi:[1,0]
	v_pk_mul_f32 v[26:27], v[36:37], v[22:23] op_sel_hi:[1,0]
	v_pk_mul_f32 v[28:29], v[46:47], v[22:23] op_sel_hi:[1,0]
	v_mul_f32_e32 v23, 0xbfb8aa3b, v60
	v_exp_f32_e32 v23, v23
	v_mul_f32_e32 v30, 0xbfb8aa3b, v61
	v_exp_f32_e32 v31, v30
	v_pk_mul_f32 v[24:25], v[10:11], v[24:25]
	v_add_f32_e32 v23, 1.0, v23
	v_rcp_f32_e32 v30, v23
	v_add_f32_e32 v23, 1.0, v31
	v_rcp_f32_e32 v31, v23
	v_pk_mul_f32 v[32:33], v[38:39], v[22:23] op_sel_hi:[1,0]
	v_mul_f32_e32 v23, 0xbfb8aa3b, v57
	v_pk_mul_f32 v[32:33], v[0:1], v[32:33]
	v_pk_mul_f32 v[30:31], v[30:31], v[60:61]
	v_exp_f32_e32 v23, v23
	v_pk_mul_f32 v[30:31], v[30:31], v[32:33]
	v_mul_f32_e32 v32, 0xbfb8aa3b, v56
	v_exp_f32_e32 v32, v32
	v_add_f32_e32 v23, 1.0, v23
	v_rcp_f32_e32 v23, v23
	v_mul_f32_e32 v33, v59, v22
	v_add_f32_e32 v32, 1.0, v32
	v_rcp_f32_e32 v204, v32
	v_mul_f32_e32 v34, v23, v57
	v_mul_f32_e32 v57, v58, v22
	v_ashrrev_i32_e32 v207, 31, v206
	v_pk_mul_f32 v[22:23], v[204:205], v[56:57]
	v_pk_mul_f32 v[24:25], v[48:49], v[24:25]
	v_pk_mul_f32 v[26:27], v[4:5], v[26:27]
	v_pk_mul_f32 v[28:29], v[6:7], v[28:29]
	v_mul_f32_e32 v32, v2, v33
	v_mov_b32_e32 v35, v22
	v_mov_b32_e32 v33, v23
	v_cvt_pk_bf16_f32 v16, v16, v17
	v_cvt_pk_bf16_f32 v17, v20, v21
	v_lshlrev_b64 v[20:21], 11, v[206:207]
	v_pk_mul_f32 v[26:27], v[44:45], v[26:27]
	v_pk_mul_f32 v[28:29], v[42:43], v[28:29]
	v_cvt_pk_bf16_f32 v18, v18, v19
	v_cvt_pk_bf16_f32 v19, v24, v25
	v_lshl_add_u64 v[20:21], v[192:193], 0, v[20:21]
	v_pk_mul_f32 v[22:23], v[34:35], v[32:33]
	global_store_dwordx4 v[20:21], v[16:19], off sc1
	s_nop 1
	v_cvt_pk_bf16_f32 v16, v26, v27
	v_cvt_pk_bf16_f32 v17, v28, v29
	v_cvt_pk_bf16_f32 v18, v30, v31
	v_cvt_pk_bf16_f32 v19, v22, v23
	global_store_dwordx4 v[20:21], v[16:19], off offset:16 sc1
	s_branch .LBB0_991

.LBB0_1066:
	ds_read_b128 v[112:115], v169
	ds_read_b128 v[116:119], v169 offset:1024
	ds_read_b128 v[120:123], v169 offset:2048
	ds_read_b128 v[124:127], v169 offset:3072
	s_add_u32 s18, s56, 0xfffc0080
	s_addc_u32 s62, s57, -1
	s_cmp_eq_u32 s74, 12
	s_cselect_b32 s65, s43, s62
	s_cselect_b32 s64, s68, s18
	s_cselect_b32 s63, s41, s73
	s_cselect_b32 s62, s69, s70
	v_lshl_add_u64 v[164:165], s[56:57], 0, v[152:153]
	s_add_i32 m0, s17, 0xc000
	ds_read_b128 v[160:163], v170
	ds_read_b128 v[172:175], v170 offset:1024
	ds_read_b128 v[176:179], v170 offset:2048
	ds_read_b128 v[180:183], v170 offset:3072
	ds_read_b128 v[184:187], v170 offset:4096
	ds_read_b128 v[188:191], v170 offset:5120
	ds_read_b128 v[192:195], v170 offset:6144
	ds_read_b128 v[196:199], v170 offset:7168
	global_load_lds_dwordx4 v[164:165], off
	v_lshl_add_u64 v[164:165], s[56:57], 0, v[154:155]
	s_add_i32 m0, s17, 0xe000
	s_nop 0
	global_load_lds_dwordx4 v[164:165], off
	s_waitcnt lgkmcnt(8)
	s_barrier
	s_waitcnt lgkmcnt(0)
	s_setprio 1
	s_waitcnt lgkmcnt(0)
	v_mfma_f32_16x16x32_bf16 v[140:143], v[112:115], v[160:163], v[140:143]
	v_mfma_f32_16x16x32_bf16 v[136:139], v[120:123], v[160:163], v[136:139]
	v_mfma_f32_16x16x32_bf16 v[108:111], v[112:115], v[176:179], v[108:111]
	v_mfma_f32_16x16x32_bf16 v[104:107], v[120:123], v[176:179], v[104:107]
	v_mfma_f32_16x16x32_bf16 v[92:95], v[112:115], v[184:187], v[92:95]
	v_mfma_f32_16x16x32_bf16 v[88:91], v[120:123], v[184:187], v[88:91]
	v_mfma_f32_16x16x32_bf16 v[76:79], v[112:115], v[192:195], v[76:79]
	v_mfma_f32_16x16x32_bf16 v[72:75], v[120:123], v[192:195], v[72:75]
	v_mfma_f32_16x16x32_bf16 v[140:143], v[116:119], v[172:175], v[140:143]
	v_mfma_f32_16x16x32_bf16 v[136:139], v[124:127], v[172:175], v[136:139]
	v_mfma_f32_16x16x32_bf16 v[108:111], v[116:119], v[180:183], v[108:111]
	v_mfma_f32_16x16x32_bf16 v[104:107], v[124:127], v[180:183], v[104:107]
	v_mfma_f32_16x16x32_bf16 v[92:95], v[116:119], v[188:191], v[92:95]
	v_mfma_f32_16x16x32_bf16 v[88:91], v[124:127], v[188:191], v[88:91]
	v_mfma_f32_16x16x32_bf16 v[76:79], v[116:119], v[196:199], v[76:79]
	v_mfma_f32_16x16x32_bf16 v[72:75], v[124:127], v[196:199], v[72:75]
	s_setprio 0
	s_barrier
	s_add_i32 s18, s59, s16
	v_lshl_add_u64 v[164:165], s[62:63], 0, v[148:149]
	s_mov_b32 m0, s18
	ds_read_b128 v[200:203], v171
	ds_read_b128 v[204:207], v171 offset:1024
	ds_read_b128 v[208:211], v171 offset:2048
	ds_read_b128 v[212:215], v171 offset:3072
	global_load_lds_dwordx4 v[164:165], off
	v_lshl_add_u64 v[216:217], s[62:63], 0, v[144:145]
	s_add_i32 m0, s18, 0x2000
	s_nop 0
	global_load_lds_dwordx4 v[216:217], off
	s_barrier
	s_waitcnt lgkmcnt(0)
	s_setprio 1
	s_waitcnt lgkmcnt(0)
	v_mfma_f32_16x16x32_bf16 v[132:135], v[200:203], v[160:163], v[132:135]
	v_mfma_f32_16x16x32_bf16 v[128:131], v[208:211], v[160:163], v[128:131]
	v_mfma_f32_16x16x32_bf16 v[100:103], v[200:203], v[176:179], v[100:103]
	v_mfma_f32_16x16x32_bf16 v[96:99], v[208:211], v[176:179], v[96:99]
	v_mfma_f32_16x16x32_bf16 v[84:87], v[200:203], v[184:187], v[84:87]
	v_mfma_f32_16x16x32_bf16 v[80:83], v[208:211], v[184:187], v[80:83]
	v_mfma_f32_16x16x32_bf16 v[68:71], v[200:203], v[192:195], v[68:71]
	v_mfma_f32_16x16x32_bf16 v[64:67], v[208:211], v[192:195], v[64:67]
	v_mfma_f32_16x16x32_bf16 v[132:135], v[204:207], v[172:175], v[132:135]
	v_mfma_f32_16x16x32_bf16 v[128:131], v[212:215], v[172:175], v[128:131]
	v_mfma_f32_16x16x32_bf16 v[100:103], v[204:207], v[180:183], v[100:103]
	v_mfma_f32_16x16x32_bf16 v[96:99], v[212:215], v[180:183], v[96:99]
	v_mfma_f32_16x16x32_bf16 v[84:87], v[204:207], v[188:191], v[84:87]
	v_mfma_f32_16x16x32_bf16 v[80:83], v[212:215], v[188:191], v[80:83]
	v_mfma_f32_16x16x32_bf16 v[68:71], v[204:207], v[196:199], v[68:71]
	v_mfma_f32_16x16x32_bf16 v[64:67], v[212:215], v[196:199], v[64:67]
	s_setprio 0
	s_mov_b32 m0, s17
	v_lshl_add_u64 v[218:219], s[64:65], 0, v[150:151]
	s_barrier
	ds_read_b128 v[160:163], v170 offset:16384
	ds_read_b128 v[172:175], v170 offset:17408
	ds_read_b128 v[176:179], v170 offset:18432
	ds_read_b128 v[180:183], v170 offset:19456
	ds_read_b128 v[184:187], v170 offset:20480
	ds_read_b128 v[188:191], v170 offset:21504
	ds_read_b128 v[192:195], v170 offset:22528
	ds_read_b128 v[196:199], v170 offset:23552
	global_load_lds_dwordx4 v[218:219], off
	v_lshl_add_u64 v[220:221], s[64:65], 0, v[146:147]
	s_mov_b32 m0, s19
	s_nop 0
	global_load_lds_dwordx4 v[220:221], off
	s_barrier
	s_waitcnt lgkmcnt(0)
	s_setprio 1
	s_waitcnt lgkmcnt(0)
	v_mfma_f32_16x16x32_bf16 v[60:63], v[112:115], v[160:163], v[60:63]
	v_mfma_f32_16x16x32_bf16 v[56:59], v[120:123], v[160:163], v[56:59]
	v_mfma_f32_16x16x32_bf16 v[52:55], v[112:115], v[176:179], v[52:55]
	v_mfma_f32_16x16x32_bf16 v[44:47], v[120:123], v[176:179], v[44:47]
	v_mfma_f32_16x16x32_bf16 v[36:39], v[112:115], v[184:187], v[36:39]
	v_mfma_f32_16x16x32_bf16 v[28:31], v[120:123], v[184:187], v[28:31]
	v_mfma_f32_16x16x32_bf16 v[20:23], v[112:115], v[192:195], v[20:23]
	v_mfma_f32_16x16x32_bf16 v[12:15], v[120:123], v[192:195], v[12:15]
	v_mfma_f32_16x16x32_bf16 v[60:63], v[116:119], v[172:175], v[60:63]
	v_mfma_f32_16x16x32_bf16 v[56:59], v[124:127], v[172:175], v[56:59]
	v_mfma_f32_16x16x32_bf16 v[52:55], v[116:119], v[180:183], v[52:55]
	v_mfma_f32_16x16x32_bf16 v[44:47], v[124:127], v[180:183], v[44:47]
	v_mfma_f32_16x16x32_bf16 v[36:39], v[116:119], v[188:191], v[36:39]
	v_mfma_f32_16x16x32_bf16 v[28:31], v[124:127], v[188:191], v[28:31]
	v_mfma_f32_16x16x32_bf16 v[20:23], v[116:119], v[196:199], v[20:23]
	v_mfma_f32_16x16x32_bf16 v[12:15], v[124:127], v[196:199], v[12:15]
	s_setprio 0
	s_barrier
	s_add_u32 s76, s62, 0x40000
	s_addc_u32 s77, s63, 0
	s_add_i32 s18, s66, s16
	v_lshl_add_u64 v[112:113], s[76:77], 0, v[148:149]
	s_mov_b32 m0, s18
	s_nop 0
	global_load_lds_dwordx4 v[112:113], off
	v_lshl_add_u64 v[112:113], s[76:77], 0, v[144:145]
	s_add_i32 m0, s18, 0x2000
	s_nop 0
	global_load_lds_dwordx4 v[112:113], off
	s_waitcnt vmcnt(6)
	s_barrier
	s_setprio 1
	v_mfma_f32_16x16x32_bf16 v[48:51], v[200:203], v[160:163], v[48:51]
	v_mfma_f32_16x16x32_bf16 v[40:43], v[208:211], v[160:163], v[40:43]
	v_mfma_f32_16x16x32_bf16 v[32:35], v[200:203], v[176:179], v[32:35]
	v_mfma_f32_16x16x32_bf16 v[24:27], v[208:211], v[176:179], v[24:27]
	v_mfma_f32_16x16x32_bf16 v[16:19], v[200:203], v[184:187], v[16:19]
	v_mfma_f32_16x16x32_bf16 v[8:11], v[208:211], v[184:187], v[8:11]
	v_mfma_f32_16x16x32_bf16 v[4:7], v[200:203], v[192:195], v[4:7]
	v_mfma_f32_16x16x32_bf16 v[0:3], v[208:211], v[192:195], v[0:3]
	v_mfma_f32_16x16x32_bf16 v[48:51], v[204:207], v[172:175], v[48:51]
	v_mfma_f32_16x16x32_bf16 v[40:43], v[212:215], v[172:175], v[40:43]
	v_mfma_f32_16x16x32_bf16 v[32:35], v[204:207], v[180:183], v[32:35]
	v_mfma_f32_16x16x32_bf16 v[24:27], v[212:215], v[180:183], v[24:27]
	v_mfma_f32_16x16x32_bf16 v[16:19], v[204:207], v[188:191], v[16:19]
	v_mfma_f32_16x16x32_bf16 v[8:11], v[212:215], v[188:191], v[8:11]
	v_mfma_f32_16x16x32_bf16 v[4:7], v[204:207], v[196:199], v[4:7]
	v_mfma_f32_16x16x32_bf16 v[0:3], v[212:215], v[196:199], v[0:3]
	s_setprio 0
	s_add_i32 s18, 0, 0x18000
	v_add_u32_e32 v124, s18, v167
	s_barrier
	ds_read_b128 v[112:115], v124
	ds_read_b128 v[116:119], v124 offset:1024
	ds_read_b128 v[120:123], v124 offset:2048
	ds_read_b128 v[124:127], v124 offset:3072
	s_add_u32 s64, s64, 0x40000
	s_addc_u32 s65, s65, 0
	s_mov_b32 m0, s28
	v_lshl_add_u64 v[200:201], s[64:65], 0, v[150:151]
	ds_read_b128 v[160:163], v170 offset:32768
	ds_read_b128 v[172:175], v170 offset:33792
	ds_read_b128 v[176:179], v170 offset:34816
	ds_read_b128 v[180:183], v170 offset:35840
	ds_read_b128 v[184:187], v170 offset:36864
	ds_read_b128 v[188:191], v170 offset:37888
	ds_read_b128 v[192:195], v170 offset:38912
	ds_read_b128 v[196:199], v170 offset:39936
	global_load_lds_dwordx4 v[200:201], off
	v_lshl_add_u64 v[200:201], s[64:65], 0, v[146:147]
	s_mov_b32 m0, s29
	s_nop 0
	global_load_lds_dwordx4 v[200:201], off
	s_waitcnt lgkmcnt(8)
	s_barrier
	s_waitcnt lgkmcnt(0)
	s_setprio 1
	s_waitcnt lgkmcnt(0)
	v_mfma_f32_16x16x32_bf16 v[140:143], v[112:115], v[160:163], v[140:143]
	v_mfma_f32_16x16x32_bf16 v[136:139], v[120:123], v[160:163], v[136:139]
	v_mfma_f32_16x16x32_bf16 v[108:111], v[112:115], v[176:179], v[108:111]
	v_mfma_f32_16x16x32_bf16 v[104:107], v[120:123], v[176:179], v[104:107]
	v_mfma_f32_16x16x32_bf16 v[92:95], v[112:115], v[184:187], v[92:95]
	v_mfma_f32_16x16x32_bf16 v[88:91], v[120:123], v[184:187], v[88:91]
	v_mfma_f32_16x16x32_bf16 v[76:79], v[112:115], v[192:195], v[76:79]
	v_mfma_f32_16x16x32_bf16 v[72:75], v[120:123], v[192:195], v[72:75]
	v_mfma_f32_16x16x32_bf16 v[140:143], v[116:119], v[172:175], v[140:143]
	v_mfma_f32_16x16x32_bf16 v[136:139], v[124:127], v[172:175], v[136:139]
	v_mfma_f32_16x16x32_bf16 v[108:111], v[116:119], v[180:183], v[108:111]
	v_mfma_f32_16x16x32_bf16 v[104:107], v[124:127], v[180:183], v[104:107]
	v_mfma_f32_16x16x32_bf16 v[92:95], v[116:119], v[188:191], v[92:95]
	v_mfma_f32_16x16x32_bf16 v[88:91], v[124:127], v[188:191], v[88:91]
	v_mfma_f32_16x16x32_bf16 v[76:79], v[116:119], v[196:199], v[76:79]
	v_mfma_f32_16x16x32_bf16 v[72:75], v[124:127], v[196:199], v[72:75]
	s_setprio 0
	s_barrier
	s_add_i32 s64, 0, 0x1c000
	s_add_i32 s18, s18, s16
	v_add_u32_e32 v212, s64, v167
	v_lshl_add_u64 v[164:165], v[164:165], 0, s[0:1]
	s_mov_b32 m0, s18
	ds_read_b128 v[200:203], v212
	ds_read_b128 v[204:207], v212 offset:1024
	ds_read_b128 v[208:211], v212 offset:2048
	ds_read_b128 v[212:215], v212 offset:3072
	global_load_lds_dwordx4 v[164:165], off
	v_lshl_add_u64 v[164:165], v[216:217], 0, s[0:1]
	s_add_i32 m0, s18, 0x2000
	s_nop 0
	global_load_lds_dwordx4 v[164:165], off
	s_barrier
	s_waitcnt lgkmcnt(0)
	s_setprio 1
	s_waitcnt lgkmcnt(0)
	v_mfma_f32_16x16x32_bf16 v[132:135], v[200:203], v[160:163], v[132:135]
	v_mfma_f32_16x16x32_bf16 v[128:131], v[208:211], v[160:163], v[128:131]
	v_mfma_f32_16x16x32_bf16 v[100:103], v[200:203], v[176:179], v[100:103]
	v_mfma_f32_16x16x32_bf16 v[96:99], v[208:211], v[176:179], v[96:99]
	v_mfma_f32_16x16x32_bf16 v[84:87], v[200:203], v[184:187], v[84:87]
	v_mfma_f32_16x16x32_bf16 v[80:83], v[208:211], v[184:187], v[80:83]
	v_mfma_f32_16x16x32_bf16 v[68:71], v[200:203], v[192:195], v[68:71]
	v_mfma_f32_16x16x32_bf16 v[64:67], v[208:211], v[192:195], v[64:67]
	v_mfma_f32_16x16x32_bf16 v[132:135], v[204:207], v[172:175], v[132:135]
	v_mfma_f32_16x16x32_bf16 v[128:131], v[212:215], v[172:175], v[128:131]
	v_mfma_f32_16x16x32_bf16 v[100:103], v[204:207], v[180:183], v[100:103]
	v_mfma_f32_16x16x32_bf16 v[96:99], v[212:215], v[180:183], v[96:99]
	v_mfma_f32_16x16x32_bf16 v[84:87], v[204:207], v[188:191], v[84:87]
	v_mfma_f32_16x16x32_bf16 v[80:83], v[212:215], v[188:191], v[80:83]
	v_mfma_f32_16x16x32_bf16 v[68:71], v[204:207], v[196:199], v[68:71]
	v_mfma_f32_16x16x32_bf16 v[64:67], v[212:215], v[196:199], v[64:67]
	s_setprio 0
	s_mov_b32 m0, s53
	v_lshl_add_u64 v[164:165], v[218:219], 0, s[0:1]
	s_barrier
	ds_read_b128 v[160:163], v170 offset:49152
	ds_read_b128 v[172:175], v170 offset:50176
	ds_read_b128 v[176:179], v170 offset:51200
	ds_read_b128 v[180:183], v170 offset:52224
	ds_read_b128 v[184:187], v170 offset:53248
	ds_read_b128 v[188:191], v170 offset:54272
	ds_read_b128 v[192:195], v170 offset:55296
	ds_read_b128 v[196:199], v170 offset:56320
	global_load_lds_dwordx4 v[164:165], off
	v_lshl_add_u64 v[164:165], v[220:221], 0, s[0:1]
	s_mov_b32 m0, s58
	s_nop 0
	global_load_lds_dwordx4 v[164:165], off
	s_barrier
	s_waitcnt lgkmcnt(0)
	s_setprio 1
	s_waitcnt lgkmcnt(0)
	v_mfma_f32_16x16x32_bf16 v[60:63], v[112:115], v[160:163], v[60:63]
	v_mfma_f32_16x16x32_bf16 v[56:59], v[120:123], v[160:163], v[56:59]
	v_mfma_f32_16x16x32_bf16 v[52:55], v[112:115], v[176:179], v[52:55]
	v_mfma_f32_16x16x32_bf16 v[44:47], v[120:123], v[176:179], v[44:47]
	v_mfma_f32_16x16x32_bf16 v[36:39], v[112:115], v[184:187], v[36:39]
	v_mfma_f32_16x16x32_bf16 v[28:31], v[120:123], v[184:187], v[28:31]
	v_mfma_f32_16x16x32_bf16 v[20:23], v[112:115], v[192:195], v[20:23]
	v_mfma_f32_16x16x32_bf16 v[12:15], v[120:123], v[192:195], v[12:15]
	v_mfma_f32_16x16x32_bf16 v[60:63], v[116:119], v[172:175], v[60:63]
	v_mfma_f32_16x16x32_bf16 v[56:59], v[124:127], v[172:175], v[56:59]
	v_mfma_f32_16x16x32_bf16 v[52:55], v[116:119], v[180:183], v[52:55]
	v_mfma_f32_16x16x32_bf16 v[44:47], v[124:127], v[180:183], v[44:47]
	v_mfma_f32_16x16x32_bf16 v[36:39], v[116:119], v[188:191], v[36:39]
	v_mfma_f32_16x16x32_bf16 v[28:31], v[124:127], v[188:191], v[28:31]
	v_mfma_f32_16x16x32_bf16 v[20:23], v[116:119], v[196:199], v[20:23]
	v_mfma_f32_16x16x32_bf16 v[12:15], v[124:127], v[196:199], v[12:15]
	s_setprio 0
	s_barrier
	s_add_u32 s62, s62, 0x40080
	s_addc_u32 s63, s63, 0
	s_add_i32 s18, s64, s16
	v_lshl_add_u64 v[112:113], s[62:63], 0, v[148:149]
	s_mov_b32 m0, s18
	s_nop 0
	global_load_lds_dwordx4 v[112:113], off
	v_lshl_add_u64 v[112:113], s[62:63], 0, v[144:145]
	s_add_i32 m0, s18, 0x2000
	s_nop 0
	global_load_lds_dwordx4 v[112:113], off
	s_waitcnt vmcnt(6)
	s_barrier
	s_setprio 1
	v_mfma_f32_16x16x32_bf16 v[48:51], v[200:203], v[160:163], v[48:51]
	v_mfma_f32_16x16x32_bf16 v[40:43], v[208:211], v[160:163], v[40:43]
	v_mfma_f32_16x16x32_bf16 v[32:35], v[200:203], v[176:179], v[32:35]
	v_mfma_f32_16x16x32_bf16 v[24:27], v[208:211], v[176:179], v[24:27]
	v_mfma_f32_16x16x32_bf16 v[16:19], v[200:203], v[184:187], v[16:19]
	v_mfma_f32_16x16x32_bf16 v[8:11], v[208:211], v[184:187], v[8:11]
	v_mfma_f32_16x16x32_bf16 v[4:7], v[200:203], v[192:195], v[4:7]
	v_mfma_f32_16x16x32_bf16 v[0:3], v[208:211], v[192:195], v[0:3]
	v_mfma_f32_16x16x32_bf16 v[48:51], v[204:207], v[172:175], v[48:51]
	v_mfma_f32_16x16x32_bf16 v[40:43], v[212:215], v[172:175], v[40:43]
	v_mfma_f32_16x16x32_bf16 v[32:35], v[204:207], v[180:183], v[32:35]
	v_mfma_f32_16x16x32_bf16 v[24:27], v[212:215], v[180:183], v[24:27]
	v_mfma_f32_16x16x32_bf16 v[16:19], v[204:207], v[188:191], v[16:19]
	v_mfma_f32_16x16x32_bf16 v[8:11], v[212:215], v[188:191], v[8:11]
	v_mfma_f32_16x16x32_bf16 v[4:7], v[204:207], v[196:199], v[4:7]
	v_mfma_f32_16x16x32_bf16 v[0:3], v[212:215], v[196:199], v[0:3]
	s_setprio 0
	s_add_i32 s74, s74, 2
	s_add_u32 s56, s56, 0x100
	s_addc_u32 s57, s57, 0
	s_add_u32 s70, s70, 0x100
	s_addc_u32 s73, s73, 0
	s_cmp_gt_u32 s74, 13
	s_barrier
	s_cbranch_scc0 .LBB0_1066
	s_sub_i32 s18, s52, 32
	s_lshr_b32 s18, s18, 2
	s_mulk_i32 s18, 0xc00
	s_addk_i32 s18, 0xc00
	s_cmp_gt_i32 s52, 31
	s_cselect_b32 s56, s18, 0
	s_ashr_i32 s57, s56, 31
	s_lshl_b64 s[56:57], s[56:57], 2
	v_lshl_or_b32 v160, s67, 8, v168
	s_add_u32 s56, s24, s56
	s_addc_u32 s57, s25, s57
	v_ashrrev_i32_e32 v161, 31, v160
	v_lshl_add_u64 v[112:113], v[160:161], 2, s[56:57]
	s_mov_b64 s[56:57], 0x1502000
	s_mov_b32 s18, 0x1502000
	v_lshl_add_u64 v[116:117], v[112:113], 0, s[56:57]
	v_add_co_u32_e32 v112, vcc, s18, v112
	v_lshl_add_u32 v164, s52, 8, v166
	s_nop 0
	v_addc_co_u32_e32 v113, vcc, 0, v113, vcc
	global_load_dwordx4 v[120:123], v[112:113], off
	global_load_dwordx4 v[124:127], v[116:117], off offset:16
	s_nop 0
	global_load_dwordx4 v[112:115], v[116:117], off offset:528
	s_nop 0
	global_load_dwordx4 v[116:119], v[116:117], off offset:512
	v_ashrrev_i32_e32 v165, 31, v164
	v_lshlrev_b64 v[162:163], 11, v[164:165]
	v_lshl_add_u64 v[172:173], s[10:11], 0, v[162:163]
	v_lshlrev_b64 v[162:163], 1, v[160:161]
	v_lshl_add_u64 v[160:161], v[172:173], 0, v[162:163]
	s_mov_b32 s18, 0x40000
	s_mov_b64 s[56:57], 0x40000
	s_mov_b32 s67, s40
	s_mov_b32 s52, s42
	s_mov_b64 s[62:63], s[48:49]
	s_waitcnt vmcnt(0)
	v_pk_mul_f32 v[142:143], v[142:143], v[122:123]
	v_pk_mul_f32 v[140:141], v[140:141], v[120:121]
	v_pk_mul_f32 v[172:173], v[138:139], v[126:127]
	v_pk_mul_f32 v[138:139], v[136:137], v[124:125]
	v_cvt_pk_bf16_f32 v136, v140, v141
	v_cvt_pk_bf16_f32 v137, v142, v143
	v_cvt_pk_bf16_f32 v138, v138, v139
	v_cvt_pk_bf16_f32 v139, v172, v173
	global_store_dwordx4 v[160:161], v[136:139], off sc1
	v_pk_mul_f32 v[134:135], v[134:135], v[118:119]
	v_pk_mul_f32 v[132:133], v[132:133], v[116:117]
	v_pk_mul_f32 v[136:137], v[130:131], v[114:115]
	v_pk_mul_f32 v[130:131], v[128:129], v[112:113]
	v_cvt_pk_bf16_f32 v128, v132, v133
	v_cvt_pk_bf16_f32 v129, v134, v135
	v_cvt_pk_bf16_f32 v130, v130, v131
	v_cvt_pk_bf16_f32 v131, v136, v137
	global_store_dwordx4 v[160:161], v[128:131], off offset:256 sc1
	v_pk_mul_f32 v[110:111], v[110:111], v[122:123]
	v_pk_mul_f32 v[108:109], v[108:109], v[120:121]
	v_or_b32_e32 v128, 16, v164
	v_ashrrev_i32_e32 v129, 31, v128
	v_lshlrev_b64 v[128:129], 11, v[128:129]
	v_lshl_add_u64 v[128:129], s[10:11], 0, v[128:129]
	v_pk_mul_f32 v[130:131], v[106:107], v[126:127]
	v_pk_mul_f32 v[106:107], v[104:105], v[124:125]
	v_lshl_add_u64 v[128:129], v[128:129], 0, v[162:163]
	v_cvt_pk_bf16_f32 v104, v108, v109
	v_cvt_pk_bf16_f32 v105, v110, v111
	v_cvt_pk_bf16_f32 v106, v106, v107
	v_cvt_pk_bf16_f32 v107, v130, v131
	global_store_dwordx4 v[128:129], v[104:107], off sc1
	v_pk_mul_f32 v[102:103], v[102:103], v[118:119]
	v_pk_mul_f32 v[100:101], v[100:101], v[116:117]
	v_pk_mul_f32 v[104:105], v[98:99], v[114:115]
	v_pk_mul_f32 v[98:99], v[96:97], v[112:113]
	v_cvt_pk_bf16_f32 v96, v100, v101
	v_cvt_pk_bf16_f32 v97, v102, v103
	v_cvt_pk_bf16_f32 v98, v98, v99
	v_cvt_pk_bf16_f32 v99, v104, v105
	global_store_dwordx4 v[128:129], v[96:99], off offset:256 sc1
	v_pk_mul_f32 v[94:95], v[94:95], v[122:123]
	v_pk_mul_f32 v[92:93], v[92:93], v[120:121]
	v_or_b32_e32 v96, 32, v164
	v_ashrrev_i32_e32 v97, 31, v96
	v_lshlrev_b64 v[96:97], 11, v[96:97]
	v_lshl_add_u64 v[96:97], s[10:11], 0, v[96:97]
	v_pk_mul_f32 v[98:99], v[90:91], v[126:127]
	v_pk_mul_f32 v[90:91], v[88:89], v[124:125]
	v_lshl_add_u64 v[96:97], v[96:97], 0, v[162:163]
	v_cvt_pk_bf16_f32 v88, v92, v93
	v_cvt_pk_bf16_f32 v89, v94, v95
	v_cvt_pk_bf16_f32 v90, v90, v91
	v_cvt_pk_bf16_f32 v91, v98, v99
	global_store_dwordx4 v[96:97], v[88:91], off sc1
	v_pk_mul_f32 v[86:87], v[86:87], v[118:119]
	v_pk_mul_f32 v[84:85], v[84:85], v[116:117]
	v_pk_mul_f32 v[88:89], v[82:83], v[114:115]
	v_pk_mul_f32 v[82:83], v[80:81], v[112:113]
	v_cvt_pk_bf16_f32 v80, v84, v85
	v_cvt_pk_bf16_f32 v81, v86, v87
	v_cvt_pk_bf16_f32 v82, v82, v83
	v_cvt_pk_bf16_f32 v83, v88, v89
	global_store_dwordx4 v[96:97], v[80:83], off offset:256 sc1
	v_pk_mul_f32 v[78:79], v[78:79], v[122:123]
	v_pk_mul_f32 v[76:77], v[76:77], v[120:121]
	v_or_b32_e32 v80, 48, v164
	v_ashrrev_i32_e32 v81, 31, v80
	v_lshlrev_b64 v[80:81], 11, v[80:81]
	v_lshl_add_u64 v[80:81], s[10:11], 0, v[80:81]
	v_pk_mul_f32 v[82:83], v[74:75], v[126:127]
	v_pk_mul_f32 v[74:75], v[72:73], v[124:125]
	v_lshl_add_u64 v[80:81], v[80:81], 0, v[162:163]
	v_cvt_pk_bf16_f32 v72, v76, v77
	v_cvt_pk_bf16_f32 v73, v78, v79
	v_cvt_pk_bf16_f32 v74, v74, v75
	v_cvt_pk_bf16_f32 v75, v82, v83
	global_store_dwordx4 v[80:81], v[72:75], off sc1
	v_pk_mul_f32 v[70:71], v[70:71], v[118:119]
	v_pk_mul_f32 v[68:69], v[68:69], v[116:117]
	v_pk_mul_f32 v[72:73], v[66:67], v[114:115]
	v_pk_mul_f32 v[66:67], v[64:65], v[112:113]
	v_cvt_pk_bf16_f32 v64, v68, v69
	v_cvt_pk_bf16_f32 v65, v70, v71
	v_cvt_pk_bf16_f32 v66, v66, v67
	v_cvt_pk_bf16_f32 v67, v72, v73
	v_pk_mul_f32 v[60:61], v[60:61], v[120:121]
	global_store_dwordx4 v[80:81], v[64:67], off offset:256 sc1
	v_pk_mul_f32 v[62:63], v[62:63], v[122:123]
	v_pk_mul_f32 v[50:51], v[50:51], v[118:119]
	v_pk_mul_f32 v[66:67], v[58:59], v[126:127]
	v_pk_mul_f32 v[58:59], v[56:57], v[124:125]
	v_cvt_pk_bf16_f32 v56, v60, v61
	v_add_co_u32_e32 v60, vcc, s18, v160
	v_cvt_pk_bf16_f32 v57, v62, v63
	v_cvt_pk_bf16_f32 v58, v58, v59
	v_cvt_pk_bf16_f32 v59, v66, v67
	v_addc_co_u32_e32 v61, vcc, 0, v161, vcc
	global_store_dwordx4 v[60:61], v[56:59], off sc1
	v_pk_mul_f32 v[48:49], v[48:49], v[116:117]
	v_lshl_add_u64 v[64:65], v[160:161], 0, s[56:57]
	v_pk_mul_f32 v[56:57], v[42:43], v[114:115]
	v_pk_mul_f32 v[42:43], v[40:41], v[112:113]
	v_cvt_pk_bf16_f32 v40, v48, v49
	v_cvt_pk_bf16_f32 v41, v50, v51
	v_cvt_pk_bf16_f32 v42, v42, v43
	v_cvt_pk_bf16_f32 v43, v56, v57
	global_store_dwordx4 v[64:65], v[40:43], off offset:256 sc1
	v_pk_mul_f32 v[44:45], v[44:45], v[124:125]
	s_mov_b32 s18, 0x48000
	v_pk_mul_f32 v[42:43], v[54:55], v[122:123]
	v_pk_mul_f32 v[40:41], v[52:53], v[120:121]
	v_pk_mul_f32 v[46:47], v[46:47], v[126:127]
	v_cvt_pk_bf16_f32 v40, v40, v41
	v_cvt_pk_bf16_f32 v41, v42, v43
	v_cvt_pk_bf16_f32 v42, v44, v45
	v_add_co_u32_e32 v44, vcc, s18, v160
	v_cvt_pk_bf16_f32 v43, v46, v47
	s_nop 0
	v_addc_co_u32_e32 v45, vcc, 0, v161, vcc
	s_mov_b64 s[56:57], 0x48000
	global_store_dwordx4 v[44:45], v[40:43], off sc1
	v_pk_mul_f32 v[34:35], v[34:35], v[118:119]
	v_pk_mul_f32 v[32:33], v[32:33], v[116:117]
	v_pk_mul_f32 v[40:41], v[26:27], v[114:115]
	v_pk_mul_f32 v[26:27], v[24:25], v[112:113]
	v_lshl_add_u64 v[48:49], v[160:161], 0, s[56:57]
	v_cvt_pk_bf16_f32 v24, v32, v33
	v_cvt_pk_bf16_f32 v25, v34, v35
	v_cvt_pk_bf16_f32 v26, v26, v27
	v_cvt_pk_bf16_f32 v27, v40, v41
	global_store_dwordx4 v[48:49], v[24:27], off offset:256 sc1
	v_pk_mul_f32 v[28:29], v[28:29], v[124:125]
	s_mov_b32 s18, 0x50000
	v_pk_mul_f32 v[26:27], v[38:39], v[122:123]
	v_pk_mul_f32 v[24:25], v[36:37], v[120:121]
	v_pk_mul_f32 v[30:31], v[30:31], v[126:127]
	v_cvt_pk_bf16_f32 v24, v24, v25
	v_cvt_pk_bf16_f32 v25, v26, v27
	v_cvt_pk_bf16_f32 v26, v28, v29
	v_add_co_u32_e32 v28, vcc, s18, v160
	v_cvt_pk_bf16_f32 v27, v30, v31
	s_nop 0
	v_addc_co_u32_e32 v29, vcc, 0, v161, vcc
	s_mov_b64 s[56:57], 0x50000
	global_store_dwordx4 v[28:29], v[24:27], off sc1
	v_pk_mul_f32 v[18:19], v[18:19], v[118:119]
	v_pk_mul_f32 v[16:17], v[16:17], v[116:117]
	v_pk_mul_f32 v[24:25], v[10:11], v[114:115]
	v_pk_mul_f32 v[10:11], v[8:9], v[112:113]
	v_lshl_add_u64 v[32:33], v[160:161], 0, s[56:57]
	v_cvt_pk_bf16_f32 v8, v16, v17
	v_cvt_pk_bf16_f32 v9, v18, v19
	v_cvt_pk_bf16_f32 v10, v10, v11
	v_cvt_pk_bf16_f32 v11, v24, v25
	global_store_dwordx4 v[32:33], v[8:11], off offset:256 sc1
	v_pk_mul_f32 v[12:13], v[12:13], v[124:125]
	s_mov_b32 s18, 0x58000
	v_pk_mul_f32 v[10:11], v[22:23], v[122:123]
	v_pk_mul_f32 v[8:9], v[20:21], v[120:121]
	v_pk_mul_f32 v[14:15], v[14:15], v[126:127]
	v_cvt_pk_bf16_f32 v8, v8, v9
	v_cvt_pk_bf16_f32 v9, v10, v11
	v_cvt_pk_bf16_f32 v10, v12, v13
	v_add_co_u32_e32 v12, vcc, s18, v160
	v_cvt_pk_bf16_f32 v11, v14, v15
	s_nop 0
	v_addc_co_u32_e32 v13, vcc, 0, v161, vcc
	s_mov_b64 s[56:57], 0x58000
	global_store_dwordx4 v[12:13], v[8:11], off sc1
	v_pk_mul_f32 v[6:7], v[6:7], v[118:119]
	v_pk_mul_f32 v[4:5], v[4:5], v[116:117]
	v_pk_mul_f32 v[8:9], v[2:3], v[114:115]
	v_pk_mul_f32 v[2:3], v[0:1], v[112:113]
	v_lshl_add_u64 v[16:17], v[160:161], 0, s[56:57]
	v_cvt_pk_bf16_f32 v0, v4, v5
	v_cvt_pk_bf16_f32 v1, v6, v7
	v_cvt_pk_bf16_f32 v2, v2, v3
	v_cvt_pk_bf16_f32 v3, v8, v9
	s_and_b64 vcc, exec, s[4:5]
	s_mov_b64 s[56:57], s[46:47]
	global_store_dwordx4 v[16:17], v[0:3], off offset:256 sc1
	s_cbranch_vccz .LBB0_1063
	s_waitcnt vmcnt(0)
	s_cmpk_gt_u32 s3, 0xff
	s_cbranch_scc1 .LBB0_1070
	s_barrier

.Lpi_loop:
	s_ashr_i32 s0, s42, 31
	s_lshr_b32 s0, s0, 26
	s_add_i32 s1, s42, s0
	s_waitcnt vmcnt(3)
	v_mov_b32_e32 v22, v224
	s_and_b32 s0, s1, 0xffffffc0
	s_lshl_b32 s1, s1, 6
	v_readlane_b32 s68, v254, 0
	v_lshlrev_b32_e32 v0, 4, v22
	s_and_b32 s1, s1, 0xfffff000
	v_and_b32_e32 v0, 0xf0, v0
	v_readlane_b32 s69, v254, 1
	s_sub_i32 s4, s43, s1
	v_ashrrev_i32_e32 v23, 4, v22
	v_lshl_add_u64 v[2:3], s[68:69], 0, v[0:1]
	s_ashr_i32 s5, s4, 31
	s_add_i32 s40, s42, 1
	s_waitcnt vmcnt(2)
	v_add_u32_e32 v4, s0, v23
	v_lshl_add_u64 v[6:7], s[4:5], 2, v[2:3]
	s_min_i32 s4, s40, 0x3ff
	v_ashrrev_i32_e32 v5, 31, v4
	s_ashr_i32 s5, s4, 31
	v_lshlrev_b64 v[4:5], 14, v[4:5]
	s_lshr_b32 s5, s5, 26
	v_lshl_add_u64 v[4:5], v[6:7], 0, v[4:5]
	s_add_i32 s5, s4, s5
	v_add_co_u32_e32 v10, vcc, s19, v4
	s_andn2_b32 s5, s5, 63
	s_nop 0
	v_addc_co_u32_e32 v11, vcc, 0, v5, vcc
	s_sub_i32 s4, s4, s5
	global_load_dwordx4 v[6:9], v[4:5], off nt
	s_nop 0
	global_load_dwordx4 v[10:13], v[10:11], off nt
	s_lshl_b32 s4, s4, 6
	v_add_u32_e32 v4, s5, v23
	s_ashr_i32 s5, s4, 31
	v_ashrrev_i32_e32 v5, 31, v4
	v_lshl_add_u64 v[2:3], s[4:5], 2, v[2:3]
	v_lshlrev_b64 v[4:5], 14, v[4:5]
	v_lshl_add_u64 v[2:3], v[2:3], 0, v[4:5]
	global_load_dwordx4 v[14:17], v[2:3], off nt
	v_add_co_u32_e32 v2, vcc, s19, v2
	v_mul_lo_u32 v4, v23, s28
	s_nop 0
	v_addc_co_u32_e32 v3, vcc, 0, v3, vcc
	global_load_dwordx4 v[18:21], v[2:3], off nt
	v_ashrrev_i32_e32 v3, 3, v22
	v_lshlrev_b32_e32 v5, 1, v3
	v_lshlrev_b32_e32 v2, 3, v22
	v_add3_u32 v0, 0, v0, v4
	v_and_b32_e32 v4, 62, v5
	v_subrev_u32_e32 v5, s1, v3
	v_and_b32_e32 v22, 56, v2
	v_lshl_add_u32 v2, v3, 2, 0
	v_lshrrev_b32_e32 v23, 5, v3
	v_add_u32_e32 v5, s43, v5
	v_mad_u32_u24 v2, v22, s28, v2
	v_add_u32_e32 v24, 0x2080, v0
	v_add_u32_e32 v25, 0x2088, v0
	v_add_u32_e32 v26, 0x4100, v0
	v_add_u32_e32 v27, 0x4108, v0
	v_add_u32_e32 v28, 0x6180, v0
	v_add_u32_e32 v29, 0x6188, v0
	v_and_or_b32 v4, v23, 1, v4
	v_cmp_gt_i32_e32 vcc, s29, v5
	s_waitcnt vmcnt(3)
	ds_write2_b32 v0, v6, v7 offset1:1
	ds_write2_b32 v0, v8, v9 offset0:2 offset1:3
	s_waitcnt vmcnt(2)
	ds_write2_b32 v24, v10, v11 offset1:1
	ds_write2_b32 v25, v12, v13 offset1:1
	s_waitcnt vmcnt(1)
	ds_write2_b32 v26, v14, v15 offset1:1
	ds_write2_b32 v27, v16, v17 offset1:1
	s_waitcnt vmcnt(0)
	ds_write2_b32 v28, v18, v19 offset1:1
	ds_write2_b32 v29, v20, v21 offset1:1
	v_lshlrev_b32_e32 v0, 1, v22
	s_waitcnt lgkmcnt(0)
	s_barrier
	s_and_saveexec_b64 s[4:5], vcc
	s_cbranch_execz .Lpi_896
	ds_read2_b32 v[6:7], v2 offset1:65
	ds_read2_b32 v[8:9], v2 offset0:130 offset1:195
	v_add_u32_e32 v12, 0x400, v2
	ds_read2_b32 v[10:11], v12 offset0:4 offset1:69
	ds_read2_b32 v[12:13], v12 offset0:134 offset1:199
	v_and_or_b32 v14, v5, s17, v4
	v_cmp_gt_i32_e32 vcc, s35, v5
	s_waitcnt lgkmcnt(3)
	v_cvt_pk_bf16_f32 v6, v6, v7
	s_waitcnt lgkmcnt(2)
	v_cvt_pk_bf16_f32 v7, v8, v9
	v_cndmask_b32_e32 v14, v5, v14, vcc
	v_ashrrev_i32_e32 v15, 31, v14
	s_waitcnt lgkmcnt(1)
	v_cvt_pk_bf16_f32 v8, v10, v11
	v_lshlrev_b64 v[10:11], 11, v[14:15]
	v_lshl_add_u64 v[10:11], s[46:47], 0, v[10:11]
	s_ashr_i32 s1, s0, 31
	v_lshl_add_u64 v[10:11], s[0:1], 1, v[10:11]
	s_waitcnt lgkmcnt(0)
	v_cvt_pk_bf16_f32 v9, v12, v13
	v_lshl_add_u64 v[10:11], v[10:11], 0, v[0:1]
	global_store_dwordx4 v[10:11], v[6:9], off sc1
.Lpi_896:
	s_or_b64 exec, exec, s[4:5]
	s_ashr_i32 s0, s40, 31
	s_lshr_b32 s0, s0, 26
	s_add_i32 s4, s40, s0
	s_and_b32 s0, s4, 0x3ffffc0
	s_sub_i32 s0, s40, s0
	v_lshl_add_u32 v3, s0, 6, v3
	v_cmp_gt_i32_e32 vcc, s29, v3
	s_and_saveexec_b64 s[0:1], vcc
	s_cbranch_execz .Lpi_next
	v_add_u32_e32 v5, 0x4000, v2
	ds_read2_b32 v[6:7], v5 offset0:64 offset1:129
	v_add_u32_e32 v5, 0x4200, v2
	ds_read2_b32 v[8:9], v5 offset0:66 offset1:131
	v_add_u32_e32 v5, 0x4400, v2
	v_add_u32_e32 v2, 0x4600, v2
	ds_read2_b32 v[12:13], v2 offset0:70 offset1:135
	v_and_or_b32 v2, v3, s17, v4
	v_cmp_gt_i32_e32 vcc, s35, v3
	ds_read2_b32 v[10:11], v5 offset0:68 offset1:133
	s_ashr_i32 s4, s4, 6
	v_cndmask_b32_e32 v14, v3, v2, vcc
	v_ashrrev_i32_e32 v15, 31, v14
	s_lshl_b32 s4, s4, 6
	s_waitcnt lgkmcnt(3)
	v_cvt_pk_bf16_f32 v2, v6, v7
	v_lshlrev_b64 v[6:7], 11, v[14:15]
	v_lshl_add_u64 v[6:7], s[46:47], 0, v[6:7]
	s_ashr_i32 s5, s4, 31
	v_lshl_add_u64 v[6:7], s[4:5], 1, v[6:7]
	s_waitcnt lgkmcnt(2)
	v_cvt_pk_bf16_f32 v3, v8, v9
	s_waitcnt lgkmcnt(0)
	v_cvt_pk_bf16_f32 v4, v10, v11
	v_cvt_pk_bf16_f32 v5, v12, v13
	v_lshl_add_u64 v[6:7], v[6:7], 0, v[0:1]
	global_store_dwordx4 v[6:7], v[2:5], off sc1
	s_branch .Lpi_next

.LBB0_1127:
	s_waitcnt vmcnt(2)
	v_add_co_u32_e32 v4, vcc, s19, v2
	v_mul_hi_i32 v11, v0, s16
	s_nop 0
	v_addc_co_u32_e32 v5, vcc, 0, v3, vcc
	v_add_co_u32_e32 v6, vcc, s28, v2
	v_mul_hi_i32 v1, v0, s3
	s_nop 0
	v_addc_co_u32_e32 v7, vcc, 0, v3, vcc
	v_add_co_u32_e32 v8, vcc, s29, v2
	v_lshrrev_b32_e32 v13, 31, v11
	s_nop 0
	v_addc_co_u32_e32 v9, vcc, 0, v3, vcc
	v_add_co_u32_e32 v10, vcc, s35, v2
	v_ashrrev_i32_e32 v14, 9, v11
	s_nop 0
	v_addc_co_u32_e32 v11, vcc, 0, v3, vcc
	global_load_dword v12, v[2:3], off
	v_add_u32_e32 v1, v1, v0
	global_load_dword v15, v[4:5], off
	global_load_dword v17, v[6:7], off
	s_nop 0
	global_load_dword v8, v[8:9], off
	v_add_co_u32_e32 v4, vcc, s40, v2
	v_add_u32_e32 v9, v14, v13
	v_lshrrev_b32_e32 v7, 31, v1
	v_ashrrev_i32_e32 v1, 13, v1
	v_addc_co_u32_e32 v5, vcc, 0, v3, vcc
	v_mul_i32_i24_e32 v9, 0xc00, v9
	global_load_dword v10, v[10:11], off
	v_add_u32_e32 v1, v1, v7
	global_load_dword v11, v[4:5], off
	v_sub_u32_e32 v4, v0, v9
	v_mad_i32_i24 v4, v1, s17, v4
	v_ashrrev_i32_e32 v5, 31, v4
	v_lshl_add_u64 v[4:5], v[4:5], 2, s[54:55]
	global_load_dword v1, v[4:5], off
	v_add_co_u32_e32 v6, vcc, s41, v2
	v_add_u32_e32 v0, s18, v0
	s_nop 0
	v_addc_co_u32_e32 v7, vcc, 0, v3, vcc
	v_add_co_u32_e32 v4, vcc, 0xd2000, v2
	s_waitcnt vmcnt(0)
	v_add_f32_e32 v1, v1, v12
	v_addc_co_u32_e32 v5, vcc, 0, v3, vcc
	global_load_dword v6, v[6:7], off
	s_nop 0
	global_load_dword v7, v[4:5], off
	v_add_f32_e32 v1, v1, v15
	v_add_f32_e32 v1, v1, v17
	v_add_f32_e32 v1, v1, v8
	v_add_co_u32_e32 v4, vcc, 0xf0000, v2
	v_add_f32_e32 v1, v1, v10
	s_nop 0
	v_addc_co_u32_e32 v5, vcc, 0, v3, vcc
	v_add_f32_e32 v1, v1, v11
	v_cmp_lt_i32_e32 vcc, s42, v0
	v_lshl_add_u64 v[2:3], v[2:3], 0, s[4:5]
	s_or_b64 s[6:7], vcc, s[6:7]
	s_waitcnt vmcnt(1)
	v_add_f32_e32 v1, v1, v6
	s_waitcnt vmcnt(0)
	v_add_f32_e32 v1, v1, v7
	global_store_dword v[4:5], v1, off sc1
	s_andn2_b64 exec, exec, s[6:7]
	s_cbranch_execnz .LBB0_1127

.LBB0_1130:
	s_or_b64 exec, exec, s[40:41]
	v_mov_b32_e32 v60, v45
	v_mov_b32_e32 v61, v41
	v_mov_b32_e32 v58, v44
	v_mov_b32_e32 v59, v40
	v_pk_mul_f32 v[60:61], v[60:61], v[60:61]
	v_mov_b32_e32 v62, v37
	v_pk_fma_f32 v[58:59], v[58:59], v[58:59], v[60:61]
	v_mov_b32_e32 v60, v46
	v_mov_b32_e32 v61, v42
	v_pk_fma_f32 v[58:59], v[60:61], v[60:61], v[58:59]
	v_mov_b32_e32 v60, v47
	v_mov_b32_e32 v61, v43
	v_mov_b32_e32 v63, v33
	v_pk_fma_f32 v[58:59], v[60:61], v[60:61], v[58:59]
	v_mov_b32_e32 v60, v36
	v_mov_b32_e32 v61, v32
	v_pk_mul_f32 v[62:63], v[62:63], v[62:63]
	v_add_f32_e32 v58, v58, v59
	v_pk_fma_f32 v[60:61], v[60:61], v[60:61], v[62:63]
	v_mov_b32_e32 v62, v38
	v_mov_b32_e32 v63, v34
	v_pk_fma_f32 v[60:61], v[62:63], v[62:63], v[60:61]
	v_mov_b32_e32 v62, v39
	v_mov_b32_e32 v63, v35
	v_pk_fma_f32 v[60:61], v[62:63], v[62:63], v[60:61]
	v_lshl_add_u64 v[56:57], v[132:133], 0, v[56:57]
	v_add_f32_e32 v58, v58, v60
	v_add_f32_e32 v58, v58, v61
	ds_bpermute_b32 v59, v228, v58
	v_pk_add_f32 v[60:61], v[20:21], 1.0 op_sel_hi:[1,0]
	s_waitcnt lgkmcnt(0)
	v_add_f32_e32 v58, v58, v59
	ds_bpermute_b32 v59, v229, v58
	s_waitcnt lgkmcnt(0)
	v_add_f32_e32 v58, v58, v59
	ds_bpermute_b32 v59, v230, v58
	s_waitcnt lgkmcnt(0)
	v_add_f32_e32 v58, v58, v59
	ds_bpermute_b32 v59, v231, v58
	s_waitcnt lgkmcnt(0)
	v_add_f32_e32 v58, v58, v59
	ds_bpermute_b32 v59, v232, v58
	s_waitcnt lgkmcnt(0)
	v_add_f32_e32 v58, v58, v59
	ds_bpermute_b32 v59, v233, v58
	s_waitcnt lgkmcnt(0)
	v_add_f32_e32 v58, v58, v59
	v_fmamk_f32 v58, v58, 0x3a800000, v234
	v_mul_f32_e32 v59, 0x4b800000, v58
	v_cmp_gt_f32_e32 vcc, s28, v58
	s_nop 1
	v_cndmask_b32_e32 v58, v58, v59, vcc
	v_rsq_f32_e32 v62, v58
	v_pk_add_f32 v[58:59], v[22:23], 1.0 op_sel_hi:[1,0]
	v_mul_f32_e32 v63, 0x45800000, v62
	v_cndmask_b32_e32 v62, v62, v63, vcc
	v_pk_mul_f32 v[46:47], v[46:47], v[62:63] op_sel_hi:[1,0]
	v_pk_mul_f32 v[44:45], v[44:45], v[62:63] op_sel_hi:[1,0]
	v_pk_mul_f32 v[46:47], v[10:11], v[46:47]
	v_pk_mul_f32 v[44:45], v[8:9], v[44:45]
	v_pk_fma_f32 v[46:47], v[58:59], v[46:47], v[18:19]
	v_pk_fma_f32 v[44:45], v[60:61], v[44:45], v[16:17]
	v_pk_mul_f32 v[42:43], v[42:43], v[62:63] op_sel_hi:[1,0]
	v_cvt_pk_bf16_f32 v44, v44, v45
	v_cvt_pk_bf16_f32 v45, v46, v47
	v_pk_mul_f32 v[40:41], v[40:41], v[62:63] op_sel_hi:[1,0]
	global_store_dwordx2 v[56:57], v[44:45], off sc1
	v_pk_mul_f32 v[40:41], v[0:1], v[40:41]
	v_pk_mul_f32 v[42:43], v[2:3], v[42:43]
	v_pk_add_f32 v[44:45], v[30:31], 1.0 op_sel_hi:[1,0]
	v_pk_add_f32 v[46:47], v[28:29], 1.0 op_sel_hi:[1,0]
	v_pk_fma_f32 v[42:43], v[44:45], v[42:43], v[26:27]
	v_pk_fma_f32 v[40:41], v[46:47], v[40:41], v[24:25]
	v_pk_mul_f32 v[38:39], v[38:39], v[62:63] op_sel_hi:[1,0]
	v_cvt_pk_bf16_f32 v40, v40, v41
	v_cvt_pk_bf16_f32 v41, v42, v43
	v_pk_mul_f32 v[36:37], v[36:37], v[62:63] op_sel_hi:[1,0]
	global_store_dwordx2 v[56:57], v[40:41], off offset:512 sc1
	v_pk_mul_f32 v[36:37], v[4:5], v[36:37]
	v_pk_mul_f32 v[38:39], v[6:7], v[38:39]
	v_pk_add_f32 v[40:41], v[54:55], 1.0 op_sel_hi:[1,0]
	v_pk_add_f32 v[42:43], v[52:53], 1.0 op_sel_hi:[1,0]
	v_pk_fma_f32 v[38:39], v[40:41], v[38:39], v[50:51]
	v_pk_fma_f32 v[36:37], v[42:43], v[36:37], v[48:49]
	v_pk_mul_f32 v[34:35], v[34:35], v[62:63] op_sel_hi:[1,0]
	v_cvt_pk_bf16_f32 v36, v36, v37
	v_cvt_pk_bf16_f32 v37, v38, v39
	v_pk_mul_f32 v[32:33], v[32:33], v[62:63] op_sel_hi:[1,0]
	global_store_dwordx2 v[56:57], v[36:37], off offset:1024 sc1
	v_pk_mul_f32 v[32:33], v[12:13], v[32:33]
	v_pk_mul_f32 v[34:35], v[14:15], v[34:35]
	v_pk_add_f32 v[36:37], v[78:79], 1.0 op_sel_hi:[1,0]
	v_pk_add_f32 v[38:39], v[76:77], 1.0 op_sel_hi:[1,0]
	v_pk_fma_f32 v[34:35], v[36:37], v[34:35], v[74:75]
	v_pk_fma_f32 v[32:33], v[38:39], v[32:33], v[72:73]
	s_nop 0
	v_cvt_pk_bf16_f32 v32, v32, v33
	v_cvt_pk_bf16_f32 v33, v34, v35
	global_store_dwordx2 v[56:57], v[32:33], off offset:1536 sc1

.LBB0_1132:
	s_waitcnt vmcnt(12)
	v_min_i32_e32 v32, v128, v227
	v_add_u32_e32 v34, 0xffffe000, v32
	v_ashrrev_i32_e32 v33, 31, v32
	v_cmp_gt_i32_e32 vcc, s17, v32
	v_mov_b32_e32 v38, s39
	v_mov_b32_e32 v39, s37
	v_cndmask_b32_e32 v35, 0, v33, vcc
	v_cndmask_b32_e32 v34, v34, v32, vcc
	v_mov_b32_e32 v40, s38
	v_mov_b32_e32 v41, s36
	v_cndmask_b32_e32 v37, v38, v39, vcc
	v_cndmask_b32_e32 v36, v40, v41, vcc
	v_lshlrev_b64 v[34:35], 12, v[34:35]
	v_lshl_add_u64 v[34:35], v[36:37], 0, v[34:35]
	v_lshlrev_b64 v[32:33], 11, v[32:33]
	v_lshl_add_u64 v[34:35], v[34:35], 0, v[130:131]
	v_lshl_add_u64 v[32:33], v[134:135], 0, v[32:33]
	v_add_u32_e32 v194, 1, v128
	global_load_dwordx4 v[204:207], v[34:35], off nt
	global_load_dwordx4 v[208:211], v[34:35], off offset:1024 nt
	global_load_dwordx4 v[220:223], v[34:35], off offset:2048 nt
	global_load_dwordx4 v[236:239], v[34:35], off offset:3072 nt
	global_load_dwordx2 v[212:213], v[32:33], off
	global_load_dwordx2 v[214:215], v[32:33], off offset:512
	global_load_dwordx2 v[240:241], v[32:33], off offset:1024
	global_load_dwordx2 v[242:243], v[32:33], off offset:1536
	v_min_i32_e32 v32, v194, v227
	v_ashrrev_i32_e32 v33, 31, v32
	v_add_u32_e32 v34, 0xffffe000, v32
	v_cmp_gt_i32_e32 vcc, s17, v32
	v_add_u32_e32 v184, 2, v128
	v_add_u32_e32 v174, 3, v128
	v_cndmask_b32_e32 v35, 0, v33, vcc
	v_cndmask_b32_e32 v34, v34, v32, vcc
	v_cndmask_b32_e32 v37, v38, v39, vcc
	v_cndmask_b32_e32 v36, v40, v41, vcc
	v_lshlrev_b64 v[34:35], 12, v[34:35]
	v_lshl_add_u64 v[34:35], v[36:37], 0, v[34:35]
	v_lshlrev_b64 v[32:33], 11, v[32:33]
	v_lshl_add_u64 v[34:35], v[34:35], 0, v[130:131]
	v_lshl_add_u64 v[32:33], v[134:135], 0, v[32:33]
	global_load_dwordx4 v[124:127], v[34:35], off nt
	global_load_dwordx4 v[120:123], v[34:35], off offset:1024 nt
	global_load_dwordx4 v[116:119], v[34:35], off offset:2048 nt
	global_load_dwordx4 v[112:115], v[34:35], off offset:3072 nt
	global_load_dwordx2 v[202:203], v[32:33], off
	global_load_dwordx2 v[200:201], v[32:33], off offset:512
	global_load_dwordx2 v[198:199], v[32:33], off offset:1024
	global_load_dwordx2 v[196:197], v[32:33], off offset:1536
	v_min_i32_e32 v32, v184, v227
	v_ashrrev_i32_e32 v33, 31, v32
	v_add_u32_e32 v34, 0xffffe000, v32
	v_cmp_gt_i32_e32 vcc, s17, v32
	v_add_u32_e32 v164, 4, v128
	v_add_u32_e32 v154, 5, v128
	v_cndmask_b32_e32 v35, 0, v33, vcc
	v_cndmask_b32_e32 v34, v34, v32, vcc
	v_cndmask_b32_e32 v37, v38, v39, vcc
	v_cndmask_b32_e32 v36, v40, v41, vcc
	v_lshlrev_b64 v[34:35], 12, v[34:35]
	v_lshl_add_u64 v[34:35], v[36:37], 0, v[34:35]
	v_lshlrev_b64 v[32:33], 11, v[32:33]
	v_lshl_add_u64 v[34:35], v[34:35], 0, v[130:131]
	v_lshl_add_u64 v[32:33], v[134:135], 0, v[32:33]
	global_load_dwordx4 v[108:111], v[34:35], off nt
	global_load_dwordx4 v[104:107], v[34:35], off offset:1024 nt
	global_load_dwordx4 v[100:103], v[34:35], off offset:2048 nt
	global_load_dwordx4 v[96:99], v[34:35], off offset:3072 nt
	global_load_dwordx2 v[192:193], v[32:33], off
	global_load_dwordx2 v[190:191], v[32:33], off offset:512
	global_load_dwordx2 v[188:189], v[32:33], off offset:1024
	global_load_dwordx2 v[186:187], v[32:33], off offset:1536
	v_min_i32_e32 v32, v174, v227
	v_ashrrev_i32_e32 v33, 31, v32
	v_add_u32_e32 v34, 0xffffe000, v32
	v_cmp_gt_i32_e32 vcc, s17, v32
	s_waitcnt vmcnt(32)
	v_min_i32_e32 v156, v154, v227
	v_ashrrev_i32_e32 v157, 31, v156
	v_cndmask_b32_e32 v35, 0, v33, vcc
	v_cndmask_b32_e32 v34, v34, v32, vcc
	v_cndmask_b32_e32 v37, v38, v39, vcc
	v_cndmask_b32_e32 v36, v40, v41, vcc
	v_lshlrev_b64 v[34:35], 12, v[34:35]
	v_lshl_add_u64 v[34:35], v[36:37], 0, v[34:35]
	v_lshlrev_b64 v[32:33], 11, v[32:33]
	v_lshl_add_u64 v[34:35], v[34:35], 0, v[130:131]
	v_lshl_add_u64 v[32:33], v[134:135], 0, v[32:33]
	global_load_dwordx4 v[92:95], v[34:35], off nt
	global_load_dwordx4 v[88:91], v[34:35], off offset:1024 nt
	global_load_dwordx4 v[84:87], v[34:35], off offset:2048 nt
	global_load_dwordx4 v[80:83], v[34:35], off offset:3072 nt
	global_load_dwordx2 v[182:183], v[32:33], off
	global_load_dwordx2 v[180:181], v[32:33], off offset:512
	global_load_dwordx2 v[178:179], v[32:33], off offset:1024
	global_load_dwordx2 v[176:177], v[32:33], off offset:1536
	v_min_i32_e32 v32, v164, v227
	v_ashrrev_i32_e32 v33, 31, v32
	v_add_u32_e32 v34, 0xffffe000, v32
	v_cmp_gt_i32_e32 vcc, s17, v32
	v_add_u32_e32 v129, 0xffffe000, v128
	v_ashrrev_i32_e32 v129, 10, v129
	v_cndmask_b32_e32 v35, 0, v33, vcc
	v_cndmask_b32_e32 v34, v34, v32, vcc
	v_cndmask_b32_e32 v37, v38, v39, vcc
	v_cndmask_b32_e32 v36, v40, v41, vcc
	v_lshlrev_b64 v[34:35], 12, v[34:35]
	v_lshl_add_u64 v[34:35], v[36:37], 0, v[34:35]
	v_lshlrev_b64 v[32:33], 11, v[32:33]
	v_lshl_add_u64 v[34:35], v[34:35], 0, v[130:131]
	v_lshl_add_u64 v[32:33], v[134:135], 0, v[32:33]
	global_load_dwordx4 v[68:71], v[34:35], off nt
	global_load_dwordx4 v[64:67], v[34:35], off offset:1024 nt
	global_load_dwordx4 v[60:63], v[34:35], off offset:2048 nt
	global_load_dwordx4 v[56:59], v[34:35], off offset:3072 nt
	global_load_dwordx2 v[172:173], v[32:33], off
	global_load_dwordx2 v[170:171], v[32:33], off offset:512
	global_load_dwordx2 v[168:169], v[32:33], off offset:1024
	global_load_dwordx2 v[166:167], v[32:33], off offset:1536
	v_add_u32_e32 v32, 0xffffe000, v156
	v_cmp_gt_i32_e32 vcc, s17, v156
	v_add_u32_e32 v129, 1, v129
	s_waitcnt vmcnt(35)
	v_lshlrev_b32_e32 v216, 16, v212
	v_cndmask_b32_e32 v33, 0, v157, vcc
	v_cndmask_b32_e32 v32, v32, v156, vcc
	v_cndmask_b32_e32 v35, v38, v39, vcc
	v_cndmask_b32_e32 v34, v40, v41, vcc
	v_lshlrev_b64 v[32:33], 12, v[32:33]
	v_lshl_add_u64 v[32:33], v[34:35], 0, v[32:33]
	v_lshlrev_b64 v[156:157], 11, v[156:157]
	v_lshl_add_u64 v[32:33], v[32:33], 0, v[130:131]
	v_lshl_add_u64 v[156:157], v[134:135], 0, v[156:157]
	global_load_dwordx4 v[44:47], v[32:33], off nt
	global_load_dwordx4 v[40:43], v[32:33], off offset:1024 nt
	global_load_dwordx4 v[36:39], v[32:33], off offset:2048 nt
	s_nop 0
	global_load_dwordx4 v[32:35], v[32:33], off offset:3072 nt
	s_nop 0
	global_load_dwordx2 v[162:163], v[156:157], off
	global_load_dwordx2 v[160:161], v[156:157], off offset:512
	global_load_dwordx2 v[158:159], v[156:157], off offset:1024
	s_nop 0
	global_load_dwordx2 v[156:157], v[156:157], off offset:1536
	v_and_b32_e32 v217, 0xffff0000, v212
	v_lshlrev_b32_e32 v212, 16, v213
	v_and_b32_e32 v213, 0xffff0000, v213
	v_pk_add_f32 v[216:217], v[204:205], v[216:217]
	s_waitcnt vmcnt(42)
	v_lshlrev_b32_e32 v204, 16, v214
	v_and_b32_e32 v205, 0xffff0000, v214
	v_cmp_lt_i32_e32 vcc, s19, v128
	v_pk_add_f32 v[218:219], v[206:207], v[212:213]
	v_lshlrev_b32_e32 v206, 16, v215
	v_and_b32_e32 v207, 0xffff0000, v215
	v_pk_add_f32 v[212:213], v[208:209], v[204:205]
	s_waitcnt vmcnt(41)
	v_lshlrev_b32_e32 v204, 16, v240
	v_and_b32_e32 v205, 0xffff0000, v240
	v_cndmask_b32_e32 v155, 0, v129, vcc
	v_ashrrev_i32_e32 v129, 31, v128
	v_pk_add_f32 v[214:215], v[210:211], v[206:207]
	v_lshlrev_b32_e32 v206, 16, v241
	v_and_b32_e32 v207, 0xffff0000, v241
	v_pk_add_f32 v[208:209], v[220:221], v[204:205]
	s_waitcnt vmcnt(40)
	v_lshlrev_b32_e32 v204, 16, v242
	v_and_b32_e32 v205, 0xffff0000, v242
	v_lshlrev_b64 v[220:221], 11, v[128:129]
	v_pk_add_f32 v[210:211], v[222:223], v[206:207]
	v_pk_add_f32 v[204:205], v[236:237], v[204:205]
	v_lshl_add_u64 v[222:223], v[134:135], 0, v[220:221]
	v_cvt_pk_bf16_f32 v236, v216, v217
	v_cvt_pk_bf16_f32 v237, v218, v219
	v_lshlrev_b32_e32 v206, 16, v243
	v_and_b32_e32 v207, 0xffff0000, v243
	global_store_dwordx2 v[222:223], v[236:237], off sc1
	v_cvt_pk_bf16_f32 v236, v212, v213
	v_cvt_pk_bf16_f32 v237, v214, v215
	v_pk_add_f32 v[206:207], v[238:239], v[206:207]
	global_store_dwordx2 v[222:223], v[236:237], off offset:512 sc1
	v_cvt_pk_bf16_f32 v236, v208, v209
	v_cvt_pk_bf16_f32 v237, v210, v211
	global_store_dwordx2 v[222:223], v[236:237], off offset:1024 sc1
	v_cvt_pk_bf16_f32 v236, v204, v205
	v_cvt_pk_bf16_f32 v237, v206, v207
	v_cmp_ne_u32_e32 vcc, v155, v235
	global_store_dwordx2 v[222:223], v[236:237], off offset:1536 sc1
	s_and_saveexec_b64 s[6:7], vcc
	s_cbranch_execz .LBB0_1142
	global_load_dwordx4 v[16:19], v[136:137], off
	global_load_dwordx4 v[20:23], v[138:139], off
	v_mad_i64_i32 v[222:223], s[40:41], v155, s16, v[152:153]
	s_mov_b64 s[40:41], 0

.LBB0_1142:
	s_or_b64 exec, exec, s[6:7]
	v_mov_b32_e32 v236, v217
	v_mov_b32_e32 v237, v213
	v_mov_b32_e32 v222, v216
	v_mov_b32_e32 v223, v212
	v_pk_mul_f32 v[236:237], v[236:237], v[236:237]
	v_mov_b32_e32 v238, v209
	v_pk_fma_f32 v[222:223], v[222:223], v[222:223], v[236:237]
	v_mov_b32_e32 v236, v218
	v_mov_b32_e32 v237, v214
	v_pk_fma_f32 v[222:223], v[236:237], v[236:237], v[222:223]
	v_mov_b32_e32 v236, v219
	v_mov_b32_e32 v237, v215
	v_mov_b32_e32 v239, v205
	v_pk_fma_f32 v[222:223], v[236:237], v[236:237], v[222:223]
	v_mov_b32_e32 v236, v208
	v_mov_b32_e32 v237, v204
	v_pk_mul_f32 v[238:239], v[238:239], v[238:239]
	v_add_f32_e32 v129, v222, v223
	v_pk_fma_f32 v[236:237], v[236:237], v[236:237], v[238:239]
	v_mov_b32_e32 v238, v210
	v_mov_b32_e32 v239, v206
	v_pk_fma_f32 v[236:237], v[238:239], v[238:239], v[236:237]
	v_mov_b32_e32 v238, v211
	v_mov_b32_e32 v239, v207
	v_pk_fma_f32 v[236:237], v[238:239], v[238:239], v[236:237]
	v_pk_add_f32 v[222:223], v[20:21], 1.0 op_sel_hi:[1,0]
	v_add_f32_e32 v129, v129, v236
	v_add_f32_e32 v129, v129, v237
	ds_bpermute_b32 v155, v228, v129
	v_lshl_add_u64 v[236:237], v[132:133], 0, v[220:221]
	v_pk_add_f32 v[220:221], v[22:23], 1.0 op_sel_hi:[1,0]
	s_waitcnt lgkmcnt(0)
	v_add_f32_e32 v129, v129, v155
	ds_bpermute_b32 v155, v229, v129
	s_waitcnt lgkmcnt(0)
	v_add_f32_e32 v129, v129, v155
	ds_bpermute_b32 v155, v230, v129
	s_waitcnt lgkmcnt(0)
	v_add_f32_e32 v129, v129, v155
	ds_bpermute_b32 v155, v231, v129
	s_waitcnt lgkmcnt(0)
	v_add_f32_e32 v129, v129, v155
	ds_bpermute_b32 v155, v232, v129
	s_waitcnt lgkmcnt(0)
	v_add_f32_e32 v129, v129, v155
	ds_bpermute_b32 v155, v233, v129
	s_waitcnt lgkmcnt(0)
	v_add_f32_e32 v129, v129, v155
	v_fmamk_f32 v129, v129, 0x3a800000, v234
	v_mul_f32_e32 v155, 0x4b800000, v129
	v_cmp_gt_f32_e32 vcc, s28, v129
	s_nop 1
	v_cndmask_b32_e32 v129, v129, v155, vcc
	v_rsq_f32_e32 v129, v129
	s_nop 0
	v_mul_f32_e32 v155, 0x45800000, v129
	v_cndmask_b32_e32 v238, v129, v155, vcc
	v_pk_mul_f32 v[218:219], v[218:219], v[238:239] op_sel_hi:[1,0]
	v_pk_mul_f32 v[216:217], v[216:217], v[238:239] op_sel_hi:[1,0]
	v_pk_mul_f32 v[218:219], v[10:11], v[218:219]
	v_pk_mul_f32 v[216:217], v[8:9], v[216:217]
	v_pk_fma_f32 v[218:219], v[220:221], v[218:219], v[18:19]
	v_pk_fma_f32 v[216:217], v[222:223], v[216:217], v[16:17]
	v_pk_mul_f32 v[214:215], v[214:215], v[238:239] op_sel_hi:[1,0]
	v_cvt_pk_bf16_f32 v216, v216, v217
	v_cvt_pk_bf16_f32 v217, v218, v219
	v_pk_mul_f32 v[212:213], v[212:213], v[238:239] op_sel_hi:[1,0]
	global_store_dwordx2 v[236:237], v[216:217], off sc1
	v_pk_mul_f32 v[216:217], v[0:1], v[212:213]
	v_pk_mul_f32 v[218:219], v[2:3], v[214:215]
	v_pk_add_f32 v[212:213], v[30:31], 1.0 op_sel_hi:[1,0]
	v_pk_add_f32 v[214:215], v[28:29], 1.0 op_sel_hi:[1,0]
	v_pk_fma_f32 v[218:219], v[212:213], v[218:219], v[26:27]
	v_pk_fma_f32 v[216:217], v[214:215], v[216:217], v[24:25]
	v_pk_mul_f32 v[210:211], v[210:211], v[238:239] op_sel_hi:[1,0]
	v_cvt_pk_bf16_f32 v216, v216, v217
	v_cvt_pk_bf16_f32 v217, v218, v219
	v_pk_mul_f32 v[208:209], v[208:209], v[238:239] op_sel_hi:[1,0]
	global_store_dwordx2 v[236:237], v[216:217], off offset:512 sc1
	v_pk_mul_f32 v[216:217], v[4:5], v[208:209]
	v_pk_mul_f32 v[218:219], v[6:7], v[210:211]
	v_pk_add_f32 v[208:209], v[54:55], 1.0 op_sel_hi:[1,0]
	v_pk_add_f32 v[210:211], v[52:53], 1.0 op_sel_hi:[1,0]
	v_pk_fma_f32 v[218:219], v[208:209], v[218:219], v[50:51]
	v_pk_fma_f32 v[216:217], v[210:211], v[216:217], v[48:49]
	v_pk_mul_f32 v[206:207], v[206:207], v[238:239] op_sel_hi:[1,0]
	v_cvt_pk_bf16_f32 v216, v216, v217
	v_cvt_pk_bf16_f32 v217, v218, v219
	v_pk_mul_f32 v[204:205], v[204:205], v[238:239] op_sel_hi:[1,0]
	global_store_dwordx2 v[236:237], v[216:217], off offset:1024 sc1
	v_pk_mul_f32 v[216:217], v[12:13], v[204:205]
	v_pk_mul_f32 v[218:219], v[14:15], v[206:207]
	v_pk_add_f32 v[204:205], v[78:79], 1.0 op_sel_hi:[1,0]
	v_pk_add_f32 v[206:207], v[76:77], 1.0 op_sel_hi:[1,0]
	v_pk_fma_f32 v[218:219], v[204:205], v[218:219], v[74:75]
	v_pk_fma_f32 v[216:217], v[206:207], v[216:217], v[72:73]
	v_cmp_lt_i32_e32 vcc, v194, v226
	v_cvt_pk_bf16_f32 v216, v216, v217
	v_cvt_pk_bf16_f32 v217, v218, v219
	global_store_dwordx2 v[236:237], v[216:217], off offset:1536 sc1
	s_and_saveexec_b64 s[6:7], vcc
	s_cbranch_execz .LBB0_1167
	s_waitcnt vmcnt(43)
	v_lshlrev_b32_e32 v216, 16, v202
	v_and_b32_e32 v217, 0xffff0000, v202
	v_lshlrev_b32_e32 v202, 16, v203
	v_and_b32_e32 v203, 0xffff0000, v203
	v_pk_add_f32 v[126:127], v[126:127], v[202:203]
	s_waitcnt vmcnt(42)
	v_lshlrev_b32_e32 v202, 16, v200
	v_and_b32_e32 v203, 0xffff0000, v200
	v_lshlrev_b32_e32 v200, 16, v201
	v_and_b32_e32 v201, 0xffff0000, v201
	v_pk_add_f32 v[122:123], v[122:123], v[200:201]
	s_waitcnt vmcnt(41)
	v_lshlrev_b32_e32 v200, 16, v198
	v_and_b32_e32 v201, 0xffff0000, v198
	v_lshlrev_b32_e32 v198, 16, v199
	v_and_b32_e32 v199, 0xffff0000, v199
	v_ashrrev_i32_e32 v195, 31, v194
	v_pk_add_f32 v[124:125], v[124:125], v[216:217]
	v_pk_add_f32 v[118:119], v[118:119], v[198:199]
	s_waitcnt vmcnt(40)
	v_lshlrev_b32_e32 v198, 16, v196
	v_and_b32_e32 v199, 0xffff0000, v196
	v_lshlrev_b32_e32 v196, 16, v197
	v_and_b32_e32 v197, 0xffff0000, v197
	v_add_u32_e32 v129, 0xffffe001, v128
	v_lshlrev_b64 v[194:195], 11, v[194:195]
	v_pk_add_f32 v[120:121], v[120:121], v[202:203]
	v_pk_add_f32 v[114:115], v[114:115], v[196:197]
	v_pk_add_f32 v[112:113], v[112:113], v[198:199]
	v_ashrrev_i32_e32 v129, 10, v129
	v_lshl_add_u64 v[196:197], v[134:135], 0, v[194:195]
	v_cvt_pk_bf16_f32 v198, v124, v125
	v_cvt_pk_bf16_f32 v199, v126, v127
	v_pk_add_f32 v[116:117], v[116:117], v[200:201]
	v_add_u32_e32 v129, 1, v129
	v_cmp_lt_i32_e32 vcc, s29, v128
	global_store_dwordx2 v[196:197], v[198:199], off sc1
	v_cvt_pk_bf16_f32 v198, v120, v121
	v_cvt_pk_bf16_f32 v199, v122, v123
	v_cndmask_b32_e32 v129, 0, v129, vcc
	global_store_dwordx2 v[196:197], v[198:199], off offset:512 sc1
	v_cvt_pk_bf16_f32 v198, v116, v117
	v_cvt_pk_bf16_f32 v199, v118, v119
	global_store_dwordx2 v[196:197], v[198:199], off offset:1024 sc1
	v_cvt_pk_bf16_f32 v198, v112, v113
	v_cvt_pk_bf16_f32 v199, v114, v115
	v_cmp_ne_u32_e32 vcc, v129, v235
	global_store_dwordx2 v[196:197], v[198:199], off offset:1536 sc1
	s_and_saveexec_b64 s[40:41], vcc
	s_cbranch_execz .LBB0_1153
	global_load_dwordx4 v[16:19], v[136:137], off
	global_load_dwordx4 v[20:23], v[138:139], off
	v_mad_i64_i32 v[196:197], s[42:43], v129, s16, v[152:153]
	s_mov_b64 s[42:43], 0

.LBB0_1153:
	s_or_b64 exec, exec, s[40:41]
	v_mov_b32_e32 v198, v125
	v_mov_b32_e32 v199, v121
	v_mov_b32_e32 v196, v124
	v_mov_b32_e32 v197, v120
	v_pk_mul_f32 v[198:199], v[198:199], v[198:199]
	v_mov_b32_e32 v200, v117
	v_pk_fma_f32 v[196:197], v[196:197], v[196:197], v[198:199]
	v_mov_b32_e32 v198, v126
	v_mov_b32_e32 v199, v122
	v_pk_fma_f32 v[196:197], v[198:199], v[198:199], v[196:197]
	v_mov_b32_e32 v198, v127
	v_mov_b32_e32 v199, v123
	v_mov_b32_e32 v201, v113
	v_pk_fma_f32 v[196:197], v[198:199], v[198:199], v[196:197]
	v_mov_b32_e32 v198, v116
	v_mov_b32_e32 v199, v112
	v_pk_mul_f32 v[200:201], v[200:201], v[200:201]
	v_add_f32_e32 v129, v196, v197
	v_pk_fma_f32 v[198:199], v[198:199], v[198:199], v[200:201]
	v_mov_b32_e32 v200, v118
	v_mov_b32_e32 v201, v114
	v_pk_fma_f32 v[198:199], v[200:201], v[200:201], v[198:199]
	v_mov_b32_e32 v200, v119
	v_mov_b32_e32 v201, v115
	v_pk_fma_f32 v[198:199], v[200:201], v[200:201], v[198:199]
	v_lshl_add_u64 v[194:195], v[132:133], 0, v[194:195]
	v_add_f32_e32 v129, v129, v198
	v_add_f32_e32 v129, v129, v199
	ds_bpermute_b32 v155, v228, v129
	s_waitcnt lgkmcnt(0)
	v_add_f32_e32 v129, v129, v155
	ds_bpermute_b32 v155, v229, v129
	s_waitcnt lgkmcnt(0)
	v_add_f32_e32 v129, v129, v155
	ds_bpermute_b32 v155, v230, v129
	s_waitcnt lgkmcnt(0)
	v_add_f32_e32 v129, v129, v155
	ds_bpermute_b32 v155, v231, v129
	s_waitcnt lgkmcnt(0)
	v_add_f32_e32 v129, v129, v155
	ds_bpermute_b32 v155, v232, v129
	s_waitcnt lgkmcnt(0)
	v_add_f32_e32 v129, v129, v155
	ds_bpermute_b32 v155, v233, v129
	s_waitcnt lgkmcnt(0)
	v_add_f32_e32 v129, v129, v155
	v_fmamk_f32 v129, v129, 0x3a800000, v234
	v_mul_f32_e32 v155, 0x4b800000, v129
	v_cmp_gt_f32_e32 vcc, s28, v129
	s_nop 1
	v_cndmask_b32_e32 v129, v129, v155, vcc
	v_rsq_f32_e32 v129, v129
	s_nop 0
	v_mul_f32_e32 v155, 0x45800000, v129
	v_cndmask_b32_e32 v196, v129, v155, vcc
	v_pk_mul_f32 v[126:127], v[126:127], v[196:197] op_sel_hi:[1,0]
	v_pk_mul_f32 v[124:125], v[124:125], v[196:197] op_sel_hi:[1,0]
	v_pk_mul_f32 v[122:123], v[122:123], v[196:197] op_sel_hi:[1,0]
	v_pk_mul_f32 v[120:121], v[120:121], v[196:197] op_sel_hi:[1,0]
	v_pk_mul_f32 v[118:119], v[118:119], v[196:197] op_sel_hi:[1,0]
	v_pk_mul_f32 v[116:117], v[116:117], v[196:197] op_sel_hi:[1,0]
	v_pk_mul_f32 v[114:115], v[114:115], v[196:197] op_sel_hi:[1,0]
	v_pk_mul_f32 v[112:113], v[112:113], v[196:197] op_sel_hi:[1,0]
	v_pk_mul_f32 v[124:125], v[8:9], v[124:125]
	v_pk_mul_f32 v[126:127], v[10:11], v[126:127]
	v_pk_mul_f32 v[120:121], v[0:1], v[120:121]
	v_pk_mul_f32 v[122:123], v[2:3], v[122:123]
	v_pk_mul_f32 v[116:117], v[4:5], v[116:117]
	v_pk_mul_f32 v[118:119], v[6:7], v[118:119]
	v_pk_mul_f32 v[112:113], v[12:13], v[112:113]
	v_pk_mul_f32 v[114:115], v[14:15], v[114:115]
	v_pk_fma_f32 v[126:127], v[220:221], v[126:127], v[18:19]
	v_pk_fma_f32 v[124:125], v[222:223], v[124:125], v[16:17]
	v_pk_fma_f32 v[122:123], v[212:213], v[122:123], v[26:27]
	v_pk_fma_f32 v[120:121], v[214:215], v[120:121], v[24:25]
	v_pk_fma_f32 v[118:119], v[208:209], v[118:119], v[50:51]
	v_pk_fma_f32 v[116:117], v[210:211], v[116:117], v[48:49]
	v_pk_fma_f32 v[114:115], v[204:205], v[114:115], v[74:75]
	v_pk_fma_f32 v[112:113], v[206:207], v[112:113], v[72:73]
	v_cvt_pk_bf16_f32 v124, v124, v125
	v_cvt_pk_bf16_f32 v125, v126, v127
	v_cvt_pk_bf16_f32 v120, v120, v121
	v_cvt_pk_bf16_f32 v121, v122, v123
	v_cvt_pk_bf16_f32 v116, v116, v117
	v_cvt_pk_bf16_f32 v117, v118, v119
	v_cvt_pk_bf16_f32 v112, v112, v113
	v_cvt_pk_bf16_f32 v113, v114, v115
	global_store_dwordx2 v[194:195], v[124:125], off sc1
	global_store_dwordx2 v[194:195], v[120:121], off offset:512 sc1
	global_store_dwordx2 v[194:195], v[116:117], off offset:1024 sc1
	global_store_dwordx2 v[194:195], v[112:113], off offset:1536 sc1
	s_or_b64 exec, exec, s[6:7]
	v_cmp_lt_i32_e32 vcc, v184, v226
	s_and_saveexec_b64 s[6:7], vcc
	s_cbranch_execnz .LBB0_1168

.LBB0_1155:
	s_waitcnt vmcnt(27)
	v_lshlrev_b32_e32 v96, 16, v182
	v_and_b32_e32 v97, 0xffff0000, v182
	v_pk_add_f32 v[92:93], v[92:93], v[96:97]
	s_waitcnt vmcnt(26)
	v_lshlrev_b32_e32 v96, 16, v180
	v_and_b32_e32 v97, 0xffff0000, v180
	v_pk_add_f32 v[88:89], v[88:89], v[96:97]
	s_waitcnt vmcnt(25)
	v_lshlrev_b32_e32 v96, 16, v178
	v_and_b32_e32 v97, 0xffff0000, v178
	v_pk_add_f32 v[84:85], v[84:85], v[96:97]
	s_waitcnt vmcnt(24)
	v_lshlrev_b32_e32 v96, 16, v176
	v_and_b32_e32 v97, 0xffff0000, v176
	v_lshlrev_b32_e32 v98, 16, v183
	v_and_b32_e32 v99, 0xffff0000, v183
	v_pk_add_f32 v[80:81], v[80:81], v[96:97]
	v_add_u32_e32 v96, 0xffffe003, v128
	v_pk_add_f32 v[94:95], v[94:95], v[98:99]
	v_lshlrev_b32_e32 v98, 16, v181
	v_and_b32_e32 v99, 0xffff0000, v181
	v_ashrrev_i32_e32 v96, 10, v96
	v_pk_add_f32 v[90:91], v[90:91], v[98:99]
	v_lshlrev_b32_e32 v98, 16, v179
	v_and_b32_e32 v99, 0xffff0000, v179
	v_add_u32_e32 v96, 1, v96
	v_cmp_lt_i32_e32 vcc, s47, v128
	v_ashrrev_i32_e32 v175, 31, v174
	v_pk_add_f32 v[86:87], v[86:87], v[98:99]
	v_lshlrev_b32_e32 v98, 16, v177
	v_and_b32_e32 v99, 0xffff0000, v177
	v_cndmask_b32_e32 v100, 0, v96, vcc
	v_lshlrev_b64 v[96:97], 11, v[174:175]
	v_pk_add_f32 v[82:83], v[82:83], v[98:99]
	v_lshl_add_u64 v[98:99], v[134:135], 0, v[96:97]
	v_cvt_pk_bf16_f32 v102, v92, v93
	v_cvt_pk_bf16_f32 v103, v94, v95
	global_store_dwordx2 v[98:99], v[102:103], off sc1
	v_cvt_pk_bf16_f32 v102, v88, v89
	v_cvt_pk_bf16_f32 v103, v90, v91
	global_store_dwordx2 v[98:99], v[102:103], off offset:512 sc1
	v_cvt_pk_bf16_f32 v102, v84, v85
	v_cvt_pk_bf16_f32 v103, v86, v87
	global_store_dwordx2 v[98:99], v[102:103], off offset:1024 sc1
	v_cvt_pk_bf16_f32 v102, v80, v81
	v_cvt_pk_bf16_f32 v103, v82, v83
	v_cmp_ne_u32_e32 vcc, v100, v235
	global_store_dwordx2 v[98:99], v[102:103], off offset:1536 sc1
	s_and_saveexec_b64 s[40:41], vcc
	s_cbranch_execz .LBB0_1165
	global_load_dwordx4 v[16:19], v[136:137], off
	global_load_dwordx4 v[20:23], v[138:139], off
	v_mad_i64_i32 v[98:99], s[42:43], v100, s16, v[152:153]
	s_mov_b64 s[42:43], 0

.LBB0_1165:
	s_or_b64 exec, exec, s[40:41]
	v_mov_b32_e32 v100, v93
	v_mov_b32_e32 v101, v89
	v_mov_b32_e32 v98, v92
	v_mov_b32_e32 v99, v88
	v_pk_mul_f32 v[100:101], v[100:101], v[100:101]
	v_mov_b32_e32 v102, v85
	v_pk_fma_f32 v[98:99], v[98:99], v[98:99], v[100:101]
	v_mov_b32_e32 v100, v94
	v_mov_b32_e32 v101, v90
	v_pk_fma_f32 v[98:99], v[100:101], v[100:101], v[98:99]
	v_mov_b32_e32 v100, v95
	v_mov_b32_e32 v101, v91
	v_mov_b32_e32 v103, v81
	v_pk_fma_f32 v[98:99], v[100:101], v[100:101], v[98:99]
	v_mov_b32_e32 v100, v84
	v_mov_b32_e32 v101, v80
	v_pk_mul_f32 v[102:103], v[102:103], v[102:103]
	v_add_f32_e32 v98, v98, v99
	v_pk_fma_f32 v[100:101], v[100:101], v[100:101], v[102:103]
	v_mov_b32_e32 v102, v86
	v_mov_b32_e32 v103, v82
	v_pk_fma_f32 v[100:101], v[102:103], v[102:103], v[100:101]
	v_mov_b32_e32 v102, v87
	v_mov_b32_e32 v103, v83
	v_pk_fma_f32 v[100:101], v[102:103], v[102:103], v[100:101]
	v_lshl_add_u64 v[96:97], v[132:133], 0, v[96:97]
	v_add_f32_e32 v98, v98, v100
	v_add_f32_e32 v98, v98, v101
	ds_bpermute_b32 v99, v228, v98
	v_pk_add_f32 v[100:101], v[20:21], 1.0 op_sel_hi:[1,0]
	s_waitcnt lgkmcnt(0)
	v_add_f32_e32 v98, v98, v99
	ds_bpermute_b32 v99, v229, v98
	s_waitcnt lgkmcnt(0)
	v_add_f32_e32 v98, v98, v99
	ds_bpermute_b32 v99, v230, v98
	s_waitcnt lgkmcnt(0)
	v_add_f32_e32 v98, v98, v99
	ds_bpermute_b32 v99, v231, v98
	s_waitcnt lgkmcnt(0)
	v_add_f32_e32 v98, v98, v99
	ds_bpermute_b32 v99, v232, v98
	s_waitcnt lgkmcnt(0)
	v_add_f32_e32 v98, v98, v99
	ds_bpermute_b32 v99, v233, v98
	s_waitcnt lgkmcnt(0)
	v_add_f32_e32 v98, v98, v99
	v_fmamk_f32 v98, v98, 0x3a800000, v234
	v_mul_f32_e32 v99, 0x4b800000, v98
	v_cmp_gt_f32_e32 vcc, s28, v98
	s_nop 1
	v_cndmask_b32_e32 v98, v98, v99, vcc
	v_rsq_f32_e32 v102, v98
	v_pk_add_f32 v[98:99], v[22:23], 1.0 op_sel_hi:[1,0]
	v_mul_f32_e32 v103, 0x45800000, v102
	v_cndmask_b32_e32 v102, v102, v103, vcc
	v_pk_mul_f32 v[94:95], v[94:95], v[102:103] op_sel_hi:[1,0]
	v_pk_mul_f32 v[92:93], v[92:93], v[102:103] op_sel_hi:[1,0]
	v_pk_mul_f32 v[94:95], v[10:11], v[94:95]
	v_pk_mul_f32 v[92:93], v[8:9], v[92:93]
	v_pk_fma_f32 v[94:95], v[98:99], v[94:95], v[18:19]
	v_pk_fma_f32 v[92:93], v[100:101], v[92:93], v[16:17]
	v_pk_mul_f32 v[90:91], v[90:91], v[102:103] op_sel_hi:[1,0]
	v_cvt_pk_bf16_f32 v92, v92, v93
	v_cvt_pk_bf16_f32 v93, v94, v95
	v_pk_mul_f32 v[88:89], v[88:89], v[102:103] op_sel_hi:[1,0]
	global_store_dwordx2 v[96:97], v[92:93], off sc1
	v_pk_mul_f32 v[88:89], v[0:1], v[88:89]
	v_pk_mul_f32 v[90:91], v[2:3], v[90:91]
	v_pk_add_f32 v[92:93], v[30:31], 1.0 op_sel_hi:[1,0]
	v_pk_add_f32 v[94:95], v[28:29], 1.0 op_sel_hi:[1,0]
	v_pk_fma_f32 v[90:91], v[92:93], v[90:91], v[26:27]
	v_pk_fma_f32 v[88:89], v[94:95], v[88:89], v[24:25]
	v_pk_mul_f32 v[86:87], v[86:87], v[102:103] op_sel_hi:[1,0]
	v_cvt_pk_bf16_f32 v88, v88, v89
	v_cvt_pk_bf16_f32 v89, v90, v91
	v_pk_mul_f32 v[84:85], v[84:85], v[102:103] op_sel_hi:[1,0]
	global_store_dwordx2 v[96:97], v[88:89], off offset:512 sc1
	v_pk_mul_f32 v[84:85], v[4:5], v[84:85]
	v_pk_mul_f32 v[86:87], v[6:7], v[86:87]
	v_pk_add_f32 v[88:89], v[54:55], 1.0 op_sel_hi:[1,0]
	v_pk_add_f32 v[90:91], v[52:53], 1.0 op_sel_hi:[1,0]
	v_pk_fma_f32 v[86:87], v[88:89], v[86:87], v[50:51]
	v_pk_fma_f32 v[84:85], v[90:91], v[84:85], v[48:49]
	v_pk_mul_f32 v[82:83], v[82:83], v[102:103] op_sel_hi:[1,0]
	v_cvt_pk_bf16_f32 v84, v84, v85
	v_cvt_pk_bf16_f32 v85, v86, v87
	v_pk_mul_f32 v[80:81], v[80:81], v[102:103] op_sel_hi:[1,0]
	global_store_dwordx2 v[96:97], v[84:85], off offset:1024 sc1
	v_pk_mul_f32 v[80:81], v[12:13], v[80:81]
	v_pk_mul_f32 v[82:83], v[14:15], v[82:83]
	v_pk_add_f32 v[84:85], v[78:79], 1.0 op_sel_hi:[1,0]
	v_pk_add_f32 v[86:87], v[76:77], 1.0 op_sel_hi:[1,0]
	v_pk_fma_f32 v[82:83], v[84:85], v[82:83], v[74:75]
	v_pk_fma_f32 v[80:81], v[86:87], v[80:81], v[72:73]
	s_nop 0
	v_cvt_pk_bf16_f32 v80, v80, v81
	v_cvt_pk_bf16_f32 v81, v82, v83
	global_store_dwordx2 v[96:97], v[80:81], off offset:1536 sc1
	s_or_b64 exec, exec, s[6:7]
	v_cmp_lt_i32_e32 vcc, v164, v226
	s_and_saveexec_b64 s[6:7], vcc
	s_cbranch_execnz .LBB0_1180

.LBB0_1168:
	s_waitcnt vmcnt(35)
	v_lshlrev_b32_e32 v112, 16, v192
	v_and_b32_e32 v113, 0xffff0000, v192
	v_pk_add_f32 v[108:109], v[108:109], v[112:113]
	s_waitcnt vmcnt(34)
	v_lshlrev_b32_e32 v112, 16, v190
	v_and_b32_e32 v113, 0xffff0000, v190
	v_pk_add_f32 v[104:105], v[104:105], v[112:113]
	s_waitcnt vmcnt(33)
	v_lshlrev_b32_e32 v112, 16, v188
	v_and_b32_e32 v113, 0xffff0000, v188
	v_pk_add_f32 v[100:101], v[100:101], v[112:113]
	s_waitcnt vmcnt(32)
	v_lshlrev_b32_e32 v112, 16, v186
	v_and_b32_e32 v113, 0xffff0000, v186
	v_lshlrev_b32_e32 v114, 16, v193
	v_and_b32_e32 v115, 0xffff0000, v193
	v_pk_add_f32 v[96:97], v[96:97], v[112:113]
	v_add_u32_e32 v112, 0xffffe002, v128
	v_pk_add_f32 v[110:111], v[110:111], v[114:115]
	v_lshlrev_b32_e32 v114, 16, v191
	v_and_b32_e32 v115, 0xffff0000, v191
	v_ashrrev_i32_e32 v112, 10, v112
	v_pk_add_f32 v[106:107], v[106:107], v[114:115]
	v_lshlrev_b32_e32 v114, 16, v189
	v_and_b32_e32 v115, 0xffff0000, v189
	v_add_u32_e32 v112, 1, v112
	v_cmp_lt_i32_e32 vcc, s46, v128
	v_ashrrev_i32_e32 v185, 31, v184
	v_pk_add_f32 v[102:103], v[102:103], v[114:115]
	v_lshlrev_b32_e32 v114, 16, v187
	v_and_b32_e32 v115, 0xffff0000, v187
	v_cndmask_b32_e32 v116, 0, v112, vcc
	v_lshlrev_b64 v[112:113], 11, v[184:185]
	v_pk_add_f32 v[98:99], v[98:99], v[114:115]
	v_lshl_add_u64 v[114:115], v[134:135], 0, v[112:113]
	v_cvt_pk_bf16_f32 v118, v108, v109
	v_cvt_pk_bf16_f32 v119, v110, v111
	global_store_dwordx2 v[114:115], v[118:119], off sc1
	v_cvt_pk_bf16_f32 v118, v104, v105
	v_cvt_pk_bf16_f32 v119, v106, v107
	global_store_dwordx2 v[114:115], v[118:119], off offset:512 sc1
	v_cvt_pk_bf16_f32 v118, v100, v101
	v_cvt_pk_bf16_f32 v119, v102, v103
	global_store_dwordx2 v[114:115], v[118:119], off offset:1024 sc1
	v_cvt_pk_bf16_f32 v118, v96, v97
	v_cvt_pk_bf16_f32 v119, v98, v99
	v_cmp_ne_u32_e32 vcc, v116, v235
	global_store_dwordx2 v[114:115], v[118:119], off offset:1536 sc1
	s_and_saveexec_b64 s[40:41], vcc
	s_cbranch_execz .LBB0_1178
	global_load_dwordx4 v[16:19], v[136:137], off
	global_load_dwordx4 v[20:23], v[138:139], off
	v_mad_i64_i32 v[114:115], s[42:43], v116, s16, v[152:153]
	s_mov_b64 s[42:43], 0

.LBB0_1178:
	s_or_b64 exec, exec, s[40:41]
	v_mov_b32_e32 v116, v109
	v_mov_b32_e32 v117, v105
	v_mov_b32_e32 v114, v108
	v_mov_b32_e32 v115, v104
	v_pk_mul_f32 v[116:117], v[116:117], v[116:117]
	v_mov_b32_e32 v118, v101
	v_pk_fma_f32 v[114:115], v[114:115], v[114:115], v[116:117]
	v_mov_b32_e32 v116, v110
	v_mov_b32_e32 v117, v106
	v_pk_fma_f32 v[114:115], v[116:117], v[116:117], v[114:115]
	v_mov_b32_e32 v116, v111
	v_mov_b32_e32 v117, v107
	v_mov_b32_e32 v119, v97
	v_pk_fma_f32 v[114:115], v[116:117], v[116:117], v[114:115]
	v_mov_b32_e32 v116, v100
	v_mov_b32_e32 v117, v96
	v_pk_mul_f32 v[118:119], v[118:119], v[118:119]
	v_add_f32_e32 v114, v114, v115
	v_pk_fma_f32 v[116:117], v[116:117], v[116:117], v[118:119]
	v_mov_b32_e32 v118, v102
	v_mov_b32_e32 v119, v98
	v_pk_fma_f32 v[116:117], v[118:119], v[118:119], v[116:117]
	v_mov_b32_e32 v118, v103
	v_mov_b32_e32 v119, v99
	v_pk_fma_f32 v[116:117], v[118:119], v[118:119], v[116:117]
	v_lshl_add_u64 v[112:113], v[132:133], 0, v[112:113]
	v_add_f32_e32 v114, v114, v116
	v_add_f32_e32 v114, v114, v117
	ds_bpermute_b32 v115, v228, v114
	v_pk_add_f32 v[116:117], v[20:21], 1.0 op_sel_hi:[1,0]
	s_waitcnt lgkmcnt(0)
	v_add_f32_e32 v114, v114, v115
	ds_bpermute_b32 v115, v229, v114
	s_waitcnt lgkmcnt(0)
	v_add_f32_e32 v114, v114, v115
	ds_bpermute_b32 v115, v230, v114
	s_waitcnt lgkmcnt(0)
	v_add_f32_e32 v114, v114, v115
	ds_bpermute_b32 v115, v231, v114
	s_waitcnt lgkmcnt(0)
	v_add_f32_e32 v114, v114, v115
	ds_bpermute_b32 v115, v232, v114
	s_waitcnt lgkmcnt(0)
	v_add_f32_e32 v114, v114, v115
	ds_bpermute_b32 v115, v233, v114
	s_waitcnt lgkmcnt(0)
	v_add_f32_e32 v114, v114, v115
	v_fmamk_f32 v114, v114, 0x3a800000, v234
	v_mul_f32_e32 v115, 0x4b800000, v114
	v_cmp_gt_f32_e32 vcc, s28, v114
	s_nop 1
	v_cndmask_b32_e32 v114, v114, v115, vcc
	v_rsq_f32_e32 v118, v114
	v_pk_add_f32 v[114:115], v[22:23], 1.0 op_sel_hi:[1,0]
	v_mul_f32_e32 v119, 0x45800000, v118
	v_cndmask_b32_e32 v118, v118, v119, vcc
	v_pk_mul_f32 v[110:111], v[110:111], v[118:119] op_sel_hi:[1,0]
	v_pk_mul_f32 v[108:109], v[108:109], v[118:119] op_sel_hi:[1,0]
	v_pk_mul_f32 v[110:111], v[10:11], v[110:111]
	v_pk_mul_f32 v[108:109], v[8:9], v[108:109]
	v_pk_fma_f32 v[110:111], v[114:115], v[110:111], v[18:19]
	v_pk_fma_f32 v[108:109], v[116:117], v[108:109], v[16:17]
	v_pk_mul_f32 v[106:107], v[106:107], v[118:119] op_sel_hi:[1,0]
	v_cvt_pk_bf16_f32 v108, v108, v109
	v_cvt_pk_bf16_f32 v109, v110, v111
	v_pk_mul_f32 v[104:105], v[104:105], v[118:119] op_sel_hi:[1,0]
	global_store_dwordx2 v[112:113], v[108:109], off sc1
	v_pk_mul_f32 v[104:105], v[0:1], v[104:105]
	v_pk_mul_f32 v[106:107], v[2:3], v[106:107]
	v_pk_add_f32 v[108:109], v[30:31], 1.0 op_sel_hi:[1,0]
	v_pk_add_f32 v[110:111], v[28:29], 1.0 op_sel_hi:[1,0]
	v_pk_fma_f32 v[106:107], v[108:109], v[106:107], v[26:27]
	v_pk_fma_f32 v[104:105], v[110:111], v[104:105], v[24:25]
	v_pk_mul_f32 v[102:103], v[102:103], v[118:119] op_sel_hi:[1,0]
	v_cvt_pk_bf16_f32 v104, v104, v105
	v_cvt_pk_bf16_f32 v105, v106, v107
	v_pk_mul_f32 v[100:101], v[100:101], v[118:119] op_sel_hi:[1,0]
	global_store_dwordx2 v[112:113], v[104:105], off offset:512 sc1
	v_pk_mul_f32 v[100:101], v[4:5], v[100:101]
	v_pk_mul_f32 v[102:103], v[6:7], v[102:103]
	v_pk_add_f32 v[104:105], v[54:55], 1.0 op_sel_hi:[1,0]
	v_pk_add_f32 v[106:107], v[52:53], 1.0 op_sel_hi:[1,0]
	v_pk_fma_f32 v[102:103], v[104:105], v[102:103], v[50:51]
	v_pk_fma_f32 v[100:101], v[106:107], v[100:101], v[48:49]
	v_pk_mul_f32 v[98:99], v[98:99], v[118:119] op_sel_hi:[1,0]
	v_cvt_pk_bf16_f32 v100, v100, v101
	v_cvt_pk_bf16_f32 v101, v102, v103
	v_pk_mul_f32 v[96:97], v[96:97], v[118:119] op_sel_hi:[1,0]
	global_store_dwordx2 v[112:113], v[100:101], off offset:1024 sc1
	v_pk_mul_f32 v[96:97], v[12:13], v[96:97]
	v_pk_mul_f32 v[98:99], v[14:15], v[98:99]
	v_pk_add_f32 v[100:101], v[78:79], 1.0 op_sel_hi:[1,0]
	v_pk_add_f32 v[102:103], v[76:77], 1.0 op_sel_hi:[1,0]
	v_pk_fma_f32 v[98:99], v[100:101], v[98:99], v[74:75]
	v_pk_fma_f32 v[96:97], v[102:103], v[96:97], v[72:73]
	s_nop 0
	v_cvt_pk_bf16_f32 v96, v96, v97
	v_cvt_pk_bf16_f32 v97, v98, v99
	global_store_dwordx2 v[112:113], v[96:97], off offset:1536 sc1
	s_or_b64 exec, exec, s[6:7]
	v_cmp_lt_i32_e32 vcc, v174, v226
	s_and_saveexec_b64 s[6:7], vcc
	s_cbranch_execnz .LBB0_1155

.LBB0_1180:
	s_waitcnt vmcnt(19)
	v_lshlrev_b32_e32 v80, 16, v172
	v_and_b32_e32 v81, 0xffff0000, v172
	v_pk_add_f32 v[68:69], v[68:69], v[80:81]
	s_waitcnt vmcnt(18)
	v_lshlrev_b32_e32 v80, 16, v170
	v_and_b32_e32 v81, 0xffff0000, v170
	v_pk_add_f32 v[64:65], v[64:65], v[80:81]
	s_waitcnt vmcnt(17)
	v_lshlrev_b32_e32 v80, 16, v168
	v_and_b32_e32 v81, 0xffff0000, v168
	v_pk_add_f32 v[60:61], v[60:61], v[80:81]
	s_waitcnt vmcnt(16)
	v_lshlrev_b32_e32 v80, 16, v166
	v_and_b32_e32 v81, 0xffff0000, v166
	v_lshlrev_b32_e32 v82, 16, v173
	v_and_b32_e32 v83, 0xffff0000, v173
	v_pk_add_f32 v[56:57], v[56:57], v[80:81]
	v_add_u32_e32 v80, 0xffffe004, v128
	v_pk_add_f32 v[70:71], v[70:71], v[82:83]
	v_lshlrev_b32_e32 v82, 16, v171
	v_and_b32_e32 v83, 0xffff0000, v171
	v_ashrrev_i32_e32 v80, 10, v80
	v_pk_add_f32 v[66:67], v[66:67], v[82:83]
	v_lshlrev_b32_e32 v82, 16, v169
	v_and_b32_e32 v83, 0xffff0000, v169
	v_add_u32_e32 v80, 1, v80
	v_cmp_lt_i32_e32 vcc, s48, v128
	v_ashrrev_i32_e32 v165, 31, v164
	v_pk_add_f32 v[62:63], v[62:63], v[82:83]
	v_lshlrev_b32_e32 v82, 16, v167
	v_and_b32_e32 v83, 0xffff0000, v167
	v_cndmask_b32_e32 v84, 0, v80, vcc
	v_lshlrev_b64 v[80:81], 11, v[164:165]
	v_pk_add_f32 v[58:59], v[58:59], v[82:83]
	v_lshl_add_u64 v[82:83], v[134:135], 0, v[80:81]
	v_cvt_pk_bf16_f32 v86, v68, v69
	v_cvt_pk_bf16_f32 v87, v70, v71
	global_store_dwordx2 v[82:83], v[86:87], off sc1
	v_cvt_pk_bf16_f32 v86, v64, v65
	v_cvt_pk_bf16_f32 v87, v66, v67
	global_store_dwordx2 v[82:83], v[86:87], off offset:512 sc1
	v_cvt_pk_bf16_f32 v86, v60, v61
	v_cvt_pk_bf16_f32 v87, v62, v63
	global_store_dwordx2 v[82:83], v[86:87], off offset:1024 sc1
	v_cvt_pk_bf16_f32 v86, v56, v57
	v_cvt_pk_bf16_f32 v87, v58, v59
	v_cmp_ne_u32_e32 vcc, v84, v235
	global_store_dwordx2 v[82:83], v[86:87], off offset:1536 sc1
	s_and_saveexec_b64 s[40:41], vcc
	s_cbranch_execz .LBB0_1190
	global_load_dwordx4 v[16:19], v[136:137], off
	global_load_dwordx4 v[20:23], v[138:139], off
	v_mad_i64_i32 v[82:83], s[42:43], v84, s16, v[152:153]
	s_mov_b64 s[42:43], 0

.LBB0_1190:
	s_or_b64 exec, exec, s[40:41]
	v_mov_b32_e32 v84, v69
	v_mov_b32_e32 v85, v65
	v_mov_b32_e32 v82, v68
	v_mov_b32_e32 v83, v64
	v_pk_mul_f32 v[84:85], v[84:85], v[84:85]
	v_mov_b32_e32 v86, v61
	v_pk_fma_f32 v[82:83], v[82:83], v[82:83], v[84:85]
	v_mov_b32_e32 v84, v70
	v_mov_b32_e32 v85, v66
	v_pk_fma_f32 v[82:83], v[84:85], v[84:85], v[82:83]
	v_mov_b32_e32 v84, v71
	v_mov_b32_e32 v85, v67
	v_mov_b32_e32 v87, v57
	v_pk_fma_f32 v[82:83], v[84:85], v[84:85], v[82:83]
	v_mov_b32_e32 v84, v60
	v_mov_b32_e32 v85, v56
	v_pk_mul_f32 v[86:87], v[86:87], v[86:87]
	v_add_f32_e32 v82, v82, v83
	v_pk_fma_f32 v[84:85], v[84:85], v[84:85], v[86:87]
	v_mov_b32_e32 v86, v62
	v_mov_b32_e32 v87, v58
	v_pk_fma_f32 v[84:85], v[86:87], v[86:87], v[84:85]
	v_mov_b32_e32 v86, v63
	v_mov_b32_e32 v87, v59
	v_pk_fma_f32 v[84:85], v[86:87], v[86:87], v[84:85]
	v_lshl_add_u64 v[80:81], v[132:133], 0, v[80:81]
	v_add_f32_e32 v82, v82, v84
	v_add_f32_e32 v82, v82, v85
	ds_bpermute_b32 v83, v228, v82
	v_pk_add_f32 v[84:85], v[20:21], 1.0 op_sel_hi:[1,0]
	s_waitcnt lgkmcnt(0)
	v_add_f32_e32 v82, v82, v83
	ds_bpermute_b32 v83, v229, v82
	s_waitcnt lgkmcnt(0)
	v_add_f32_e32 v82, v82, v83
	ds_bpermute_b32 v83, v230, v82
	s_waitcnt lgkmcnt(0)
	v_add_f32_e32 v82, v82, v83
	ds_bpermute_b32 v83, v231, v82
	s_waitcnt lgkmcnt(0)
	v_add_f32_e32 v82, v82, v83
	ds_bpermute_b32 v83, v232, v82
	s_waitcnt lgkmcnt(0)
	v_add_f32_e32 v82, v82, v83
	ds_bpermute_b32 v83, v233, v82
	s_waitcnt lgkmcnt(0)
	v_add_f32_e32 v82, v82, v83
	v_fmamk_f32 v82, v82, 0x3a800000, v234
	v_mul_f32_e32 v83, 0x4b800000, v82
	v_cmp_gt_f32_e32 vcc, s28, v82
	s_nop 1
	v_cndmask_b32_e32 v82, v82, v83, vcc
	v_rsq_f32_e32 v86, v82
	v_pk_add_f32 v[82:83], v[22:23], 1.0 op_sel_hi:[1,0]
	v_mul_f32_e32 v87, 0x45800000, v86
	v_cndmask_b32_e32 v86, v86, v87, vcc
	v_pk_mul_f32 v[70:71], v[70:71], v[86:87] op_sel_hi:[1,0]
	v_pk_mul_f32 v[68:69], v[68:69], v[86:87] op_sel_hi:[1,0]
	v_pk_mul_f32 v[70:71], v[10:11], v[70:71]
	v_pk_mul_f32 v[68:69], v[8:9], v[68:69]
	v_pk_fma_f32 v[70:71], v[82:83], v[70:71], v[18:19]
	v_pk_fma_f32 v[68:69], v[84:85], v[68:69], v[16:17]
	v_pk_mul_f32 v[66:67], v[66:67], v[86:87] op_sel_hi:[1,0]
	v_cvt_pk_bf16_f32 v68, v68, v69
	v_cvt_pk_bf16_f32 v69, v70, v71
	v_pk_mul_f32 v[64:65], v[64:65], v[86:87] op_sel_hi:[1,0]
	global_store_dwordx2 v[80:81], v[68:69], off sc1
	v_pk_mul_f32 v[64:65], v[0:1], v[64:65]
	v_pk_mul_f32 v[66:67], v[2:3], v[66:67]
	v_pk_add_f32 v[68:69], v[30:31], 1.0 op_sel_hi:[1,0]
	v_pk_add_f32 v[70:71], v[28:29], 1.0 op_sel_hi:[1,0]
	v_pk_fma_f32 v[66:67], v[68:69], v[66:67], v[26:27]
	v_pk_fma_f32 v[64:65], v[70:71], v[64:65], v[24:25]
	v_pk_mul_f32 v[62:63], v[62:63], v[86:87] op_sel_hi:[1,0]
	v_cvt_pk_bf16_f32 v64, v64, v65
	v_cvt_pk_bf16_f32 v65, v66, v67
	v_pk_mul_f32 v[60:61], v[60:61], v[86:87] op_sel_hi:[1,0]
	global_store_dwordx2 v[80:81], v[64:65], off offset:512 sc1
	v_pk_mul_f32 v[60:61], v[4:5], v[60:61]
	v_pk_mul_f32 v[62:63], v[6:7], v[62:63]
	v_pk_add_f32 v[64:65], v[54:55], 1.0 op_sel_hi:[1,0]
	v_pk_add_f32 v[66:67], v[52:53], 1.0 op_sel_hi:[1,0]
	v_pk_fma_f32 v[62:63], v[64:65], v[62:63], v[50:51]
	v_pk_fma_f32 v[60:61], v[66:67], v[60:61], v[48:49]
	v_pk_mul_f32 v[58:59], v[58:59], v[86:87] op_sel_hi:[1,0]
	v_cvt_pk_bf16_f32 v60, v60, v61
	v_cvt_pk_bf16_f32 v61, v62, v63
	v_pk_mul_f32 v[56:57], v[56:57], v[86:87] op_sel_hi:[1,0]
	global_store_dwordx2 v[80:81], v[60:61], off offset:1024 sc1
	v_pk_mul_f32 v[56:57], v[12:13], v[56:57]
	v_pk_mul_f32 v[58:59], v[14:15], v[58:59]
	v_pk_add_f32 v[60:61], v[78:79], 1.0 op_sel_hi:[1,0]
	v_pk_add_f32 v[62:63], v[76:77], 1.0 op_sel_hi:[1,0]
	v_pk_fma_f32 v[58:59], v[60:61], v[58:59], v[74:75]
	v_pk_fma_f32 v[56:57], v[62:63], v[56:57], v[72:73]
	s_nop 0
	v_cvt_pk_bf16_f32 v56, v56, v57
	v_cvt_pk_bf16_f32 v57, v58, v59
	global_store_dwordx2 v[80:81], v[56:57], off offset:1536 sc1
	s_or_b64 exec, exec, s[6:7]
	v_cmp_lt_i32_e32 vcc, v154, v226
	s_and_saveexec_b64 s[6:7], vcc
	s_cbranch_execz .LBB0_1131
.LBB0_1191:
	s_waitcnt vmcnt(11)
	v_lshlrev_b32_e32 v56, 16, v162
	v_and_b32_e32 v57, 0xffff0000, v162
	v_pk_add_f32 v[44:45], v[44:45], v[56:57]
	s_waitcnt vmcnt(10)
	v_lshlrev_b32_e32 v56, 16, v160
	v_and_b32_e32 v57, 0xffff0000, v160
	v_pk_add_f32 v[40:41], v[40:41], v[56:57]
	s_waitcnt vmcnt(9)
	v_lshlrev_b32_e32 v56, 16, v158
	v_and_b32_e32 v57, 0xffff0000, v158
	v_pk_add_f32 v[36:37], v[36:37], v[56:57]
	s_waitcnt vmcnt(8)
	v_lshlrev_b32_e32 v56, 16, v156
	v_and_b32_e32 v57, 0xffff0000, v156
	v_lshlrev_b32_e32 v58, 16, v163
	v_and_b32_e32 v59, 0xffff0000, v163
	v_pk_add_f32 v[32:33], v[32:33], v[56:57]
	v_add_u32_e32 v56, 0xffffe005, v128
	v_pk_add_f32 v[46:47], v[46:47], v[58:59]
	v_lshlrev_b32_e32 v58, 16, v161
	v_and_b32_e32 v59, 0xffff0000, v161
	v_ashrrev_i32_e32 v56, 10, v56
	v_pk_add_f32 v[42:43], v[42:43], v[58:59]
	v_lshlrev_b32_e32 v58, 16, v159
	v_and_b32_e32 v59, 0xffff0000, v159
	v_add_u32_e32 v56, 1, v56
	v_cmp_lt_i32_e32 vcc, s49, v128
	v_ashrrev_i32_e32 v155, 31, v154
	v_pk_add_f32 v[38:39], v[38:39], v[58:59]
	v_lshlrev_b32_e32 v58, 16, v157
	v_and_b32_e32 v59, 0xffff0000, v157
	v_cndmask_b32_e32 v60, 0, v56, vcc
	v_lshlrev_b64 v[56:57], 11, v[154:155]
	v_pk_add_f32 v[34:35], v[34:35], v[58:59]
	v_lshl_add_u64 v[58:59], v[134:135], 0, v[56:57]
	v_cvt_pk_bf16_f32 v62, v44, v45
	v_cvt_pk_bf16_f32 v63, v46, v47
	global_store_dwordx2 v[58:59], v[62:63], off sc1
	v_cvt_pk_bf16_f32 v62, v40, v41
	v_cvt_pk_bf16_f32 v63, v42, v43
	global_store_dwordx2 v[58:59], v[62:63], off offset:512 sc1
	v_cvt_pk_bf16_f32 v62, v36, v37
	v_cvt_pk_bf16_f32 v63, v38, v39
	global_store_dwordx2 v[58:59], v[62:63], off offset:1024 sc1
	v_cvt_pk_bf16_f32 v62, v32, v33
	v_cvt_pk_bf16_f32 v63, v34, v35
	v_cmp_ne_u32_e32 vcc, v60, v235
	global_store_dwordx2 v[58:59], v[62:63], off offset:1536 sc1
	s_and_saveexec_b64 s[40:41], vcc
	s_cbranch_execz .LBB0_1130
	global_load_dwordx4 v[16:19], v[136:137], off
	global_load_dwordx4 v[20:23], v[138:139], off
	v_mad_i64_i32 v[58:59], s[42:43], v60, s16, v[152:153]
	s_mov_b64 s[42:43], 0

.LBB0_1260:
	v_pk_mul_f32 v[4:5], v[150:151], v[4:5]
	v_pk_mul_f32 v[6:7], v[150:151], v[6:7]
	v_pk_mul_f32 v[10:11], v[150:151], v[0:1]
	v_pk_mul_f32 v[12:13], v[150:151], v[2:3]
	v_lshl_add_u64 v[8:9], v[64:65], 0, s[42:43]
	v_cvt_pk_bf16_f32 v0, v4, v5
	v_cvt_pk_bf16_f32 v1, v6, v7
	v_cvt_pk_bf16_f32 v2, v10, v11
	v_cvt_pk_bf16_f32 v3, v12, v13
	s_and_b64 vcc, exec, s[4:5]
	s_mov_b32 s54, s46
	s_mov_b32 s6, s48
	s_mov_b64 s[62:63], s[52:53]
	s_mov_b64 s[56:57], s[50:51]
	global_store_dwordx4 v[8:9], v[0:3], off offset:256 sc1
	s_cbranch_vccnz .LBB0_1297

.LBB0_1267:
	s_and_b32 s18, s54, -4
	s_cmp_eq_u32 s18, 4
	s_cselect_b64 vcc, -1, 0
	v_or_b32_e32 v152, s47, v156
	v_cndmask_b32_e32 v150, 1.0, v165, vcc
	v_pk_mul_f32 v[124:125], v[150:151], v[124:125] op_sel_hi:[0,1]
	v_pk_mul_f32 v[120:121], v[150:151], v[120:121] op_sel_hi:[0,1]
	v_ashrrev_i32_e32 v153, 31, v152
	v_lshl_or_b32 v154, s54, 8, v158
	v_pk_mul_f32 v[166:167], v[150:151], v[122:123] op_sel_hi:[0,1]
	v_cvt_pk_bf16_f32 v122, v124, v125
	v_cvt_pk_bf16_f32 v124, v120, v121
	v_lshlrev_b64 v[120:121], 13, v[152:153]
	v_ashrrev_i32_e32 v155, 31, v154
	v_pk_mul_f32 v[126:127], v[150:151], v[126:127] op_sel_hi:[0,1]
	v_lshl_add_u64 v[120:121], s[60:61], 0, v[120:121]
	v_cvt_pk_bf16_f32 v123, v126, v127
	v_cvt_pk_bf16_f32 v125, v166, v167
	v_lshl_add_u64 v[120:121], v[154:155], 1, v[120:121]
	s_and_b64 vcc, exec, s[6:7]
	global_store_dwordx4 v[120:121], v[122:125], off sc1
	s_cbranch_vccnz .LBB0_1269
	s_nop 0
	v_mov_b32_e32 v122, s35
	v_cndmask_b32_e64 v122, v159, v122, s[0:1]
	v_lshlrev_b32_e32 v136, 7, v122
	v_lshl_add_u64 v[122:123], v[138:139], 0, v[136:137]
	v_lshl_add_u64 v[126:127], v[140:141], 0, v[136:137]
	global_load_dwordx4 v[122:125], v[122:123], off
	s_nop 0
	global_load_dwordx4 v[166:169], v[126:127], off
	s_waitcnt vmcnt(0)
	v_pk_mul_f32 v[126:127], v[116:117], v[122:123]
	v_pk_mul_f32 v[170:171], v[116:117], v[166:167] op_sel:[1,0] op_sel_hi:[0,0]
	v_pk_mul_f32 v[166:167], v[118:119], v[166:167] op_sel:[1,1] op_sel_hi:[0,1]
	v_pk_mul_f32 v[172:173], v[112:113], v[168:169] op_sel:[1,0] op_sel_hi:[0,0]
	v_mov_b32_e32 v168, v125
	v_mul_f32_e32 v136, v115, v169
	v_mul_f32_e32 v174, v115, v125
	v_pk_fma_f32 v[116:117], v[116:117], v[122:123], v[170:171] op_sel_hi:[1,0,1]
	v_pk_fma_f32 v[176:177], v[118:119], v[122:123], v[166:167] op_sel:[0,1,0] neg_lo:[0,0,1] neg_hi:[0,0,1]
	v_pk_fma_f32 v[118:119], v[118:119], v[122:123], v[166:167] op_sel:[0,1,0]
	v_pk_fma_f32 v[122:123], v[112:113], v[124:125], v[172:173] op_sel_hi:[1,0,1] neg_lo:[0,0,1] neg_hi:[0,0,1]
	v_pk_fma_f32 v[112:113], v[112:113], v[124:125], v[172:173] op_sel_hi:[1,0,1]
	v_mov_b32_e32 v124, v169
	v_pk_fma_f32 v[166:167], v[114:115], v[168:169], v[136:137] op_sel_hi:[1,1,0] neg_lo:[0,0,1] neg_hi:[0,0,1]
	v_pk_fma_f32 v[124:125], v[114:115], v[124:125], v[174:175] op_sel_hi:[1,1,0]
	v_sub_f32_e32 v116, v126, v170
	v_mov_b32_e32 v118, v176
	v_mov_b32_e32 v112, v122
	v_mov_b32_e32 v114, v166
	v_mov_b32_e32 v115, v124
.LBB0_1269:
	v_mov_b32_e32 v151, v150
	v_or_b32_e32 v122, 16, v152
	v_pk_mul_f32 v[116:117], v[150:151], v[116:117]
	v_pk_mul_f32 v[112:113], v[150:151], v[112:113]
	v_ashrrev_i32_e32 v123, 31, v122
	v_pk_mul_f32 v[124:125], v[150:151], v[114:115]
	v_cvt_pk_bf16_f32 v114, v116, v117
	v_cvt_pk_bf16_f32 v116, v112, v113
	v_lshlrev_b64 v[112:113], 13, v[122:123]
	v_pk_mul_f32 v[118:119], v[150:151], v[118:119]
	v_lshl_add_u64 v[112:113], s[60:61], 0, v[112:113]
	v_cvt_pk_bf16_f32 v115, v118, v119
	v_cvt_pk_bf16_f32 v117, v124, v125
	v_lshl_add_u64 v[112:113], v[154:155], 1, v[112:113]
	s_and_b64 vcc, exec, s[6:7]
	global_store_dwordx4 v[112:113], v[114:117], off sc1
	s_cbranch_vccnz .LBB0_1271
	s_nop 0
	v_mov_b32_e32 v114, s35
	v_cndmask_b32_e64 v114, v160, v114, s[0:1]
	v_lshlrev_b32_e32 v136, 7, v114
	v_lshl_add_u64 v[114:115], v[138:139], 0, v[136:137]
	v_lshl_add_u64 v[118:119], v[140:141], 0, v[136:137]
	global_load_dwordx4 v[114:117], v[114:115], off
	s_nop 0
	global_load_dwordx4 v[122:125], v[118:119], off
	s_waitcnt vmcnt(0)
	v_pk_mul_f32 v[118:119], v[108:109], v[114:115]
	v_pk_mul_f32 v[126:127], v[108:109], v[122:123] op_sel:[1,0] op_sel_hi:[0,0]
	v_pk_mul_f32 v[122:123], v[110:111], v[122:123] op_sel:[1,1] op_sel_hi:[0,1]
	v_pk_mul_f32 v[166:167], v[104:105], v[124:125] op_sel:[1,0] op_sel_hi:[0,0]
	v_mov_b32_e32 v124, v117
	v_mul_f32_e32 v136, v107, v125
	v_mul_f32_e32 v168, v107, v117
	v_pk_fma_f32 v[108:109], v[108:109], v[114:115], v[126:127] op_sel_hi:[1,0,1]
	v_pk_fma_f32 v[170:171], v[110:111], v[114:115], v[122:123] op_sel:[0,1,0] neg_lo:[0,0,1] neg_hi:[0,0,1]
	v_pk_fma_f32 v[110:111], v[110:111], v[114:115], v[122:123] op_sel:[0,1,0]
	v_pk_fma_f32 v[114:115], v[104:105], v[116:117], v[166:167] op_sel_hi:[1,0,1] neg_lo:[0,0,1] neg_hi:[0,0,1]
	v_pk_fma_f32 v[104:105], v[104:105], v[116:117], v[166:167] op_sel_hi:[1,0,1]
	v_mov_b32_e32 v116, v125
	v_pk_fma_f32 v[122:123], v[106:107], v[124:125], v[136:137] op_sel_hi:[1,1,0] neg_lo:[0,0,1] neg_hi:[0,0,1]
	v_pk_fma_f32 v[116:117], v[106:107], v[116:117], v[168:169] op_sel_hi:[1,1,0]
	v_sub_f32_e32 v108, v118, v126
	v_mov_b32_e32 v110, v170
	v_mov_b32_e32 v104, v114
	v_mov_b32_e32 v106, v122
	v_mov_b32_e32 v107, v116
.LBB0_1271:
	s_nop 0
	v_or_b32_e32 v114, 32, v152
	v_pk_mul_f32 v[108:109], v[150:151], v[108:109]
	v_pk_mul_f32 v[104:105], v[150:151], v[104:105]
	v_ashrrev_i32_e32 v115, 31, v114
	v_pk_mul_f32 v[116:117], v[150:151], v[106:107]
	v_cvt_pk_bf16_f32 v106, v108, v109
	v_cvt_pk_bf16_f32 v108, v104, v105
	v_lshlrev_b64 v[104:105], 13, v[114:115]
	v_pk_mul_f32 v[110:111], v[150:151], v[110:111]
	v_lshl_add_u64 v[104:105], s[60:61], 0, v[104:105]
	v_cvt_pk_bf16_f32 v107, v110, v111
	v_cvt_pk_bf16_f32 v109, v116, v117
	v_lshl_add_u64 v[104:105], v[154:155], 1, v[104:105]
	s_and_b64 vcc, exec, s[6:7]
	global_store_dwordx4 v[104:105], v[106:109], off sc1
	s_cbranch_vccnz .LBB0_1273
	s_nop 0
	v_mov_b32_e32 v106, s35
	v_cndmask_b32_e64 v106, v161, v106, s[0:1]
	v_lshlrev_b32_e32 v136, 7, v106
	v_lshl_add_u64 v[106:107], v[138:139], 0, v[136:137]
	v_lshl_add_u64 v[110:111], v[140:141], 0, v[136:137]
	global_load_dwordx4 v[106:109], v[106:107], off
	s_nop 0
	global_load_dwordx4 v[114:117], v[110:111], off
	s_waitcnt vmcnt(0)
	v_pk_mul_f32 v[110:111], v[100:101], v[106:107]
	v_pk_mul_f32 v[118:119], v[100:101], v[114:115] op_sel:[1,0] op_sel_hi:[0,0]
	v_pk_mul_f32 v[114:115], v[102:103], v[114:115] op_sel:[1,1] op_sel_hi:[0,1]
	v_pk_mul_f32 v[122:123], v[96:97], v[116:117] op_sel:[1,0] op_sel_hi:[0,0]
	v_mov_b32_e32 v116, v109
	v_mul_f32_e32 v124, v99, v117
	v_mul_f32_e32 v126, v99, v109
	v_pk_fma_f32 v[100:101], v[100:101], v[106:107], v[118:119] op_sel_hi:[1,0,1]
	v_pk_fma_f32 v[166:167], v[102:103], v[106:107], v[114:115] op_sel:[0,1,0] neg_lo:[0,0,1] neg_hi:[0,0,1]
	v_pk_fma_f32 v[102:103], v[102:103], v[106:107], v[114:115] op_sel:[0,1,0]
	v_pk_fma_f32 v[106:107], v[96:97], v[108:109], v[122:123] op_sel_hi:[1,0,1] neg_lo:[0,0,1] neg_hi:[0,0,1]
	v_pk_fma_f32 v[96:97], v[96:97], v[108:109], v[122:123] op_sel_hi:[1,0,1]
	v_mov_b32_e32 v108, v117
	v_pk_fma_f32 v[114:115], v[98:99], v[116:117], v[124:125] op_sel_hi:[1,1,0] neg_lo:[0,0,1] neg_hi:[0,0,1]
	v_pk_fma_f32 v[108:109], v[98:99], v[108:109], v[126:127] op_sel_hi:[1,1,0]
	v_sub_f32_e32 v100, v110, v118
	v_mov_b32_e32 v102, v166
	v_mov_b32_e32 v96, v106
	v_mov_b32_e32 v98, v114
	v_mov_b32_e32 v99, v108
.LBB0_1273:
	s_nop 0
	v_or_b32_e32 v106, 48, v152
	v_pk_mul_f32 v[100:101], v[150:151], v[100:101]
	v_pk_mul_f32 v[96:97], v[150:151], v[96:97]
	v_ashrrev_i32_e32 v107, 31, v106
	v_pk_mul_f32 v[108:109], v[150:151], v[98:99]
	v_cvt_pk_bf16_f32 v98, v100, v101
	v_cvt_pk_bf16_f32 v100, v96, v97
	v_lshlrev_b64 v[96:97], 13, v[106:107]
	v_pk_mul_f32 v[102:103], v[150:151], v[102:103]
	v_lshl_add_u64 v[96:97], s[60:61], 0, v[96:97]
	v_cvt_pk_bf16_f32 v99, v102, v103
	v_cvt_pk_bf16_f32 v101, v108, v109
	v_lshl_add_u64 v[96:97], v[154:155], 1, v[96:97]
	global_store_dwordx4 v[96:97], v[98:101], off sc1
	s_and_b64 vcc, exec, s[6:7]
	s_nop 0
	v_add_u32_e32 v98, 0x80, v152
	v_bfe_u32 v100, v98, 6, 4
	v_cndmask_b32_e64 v99, v156, v100, s[0:1]
	v_lshlrev_b32_e32 v136, 7, v99
	s_cbranch_vccnz .LBB0_1275
	v_lshl_add_u64 v[102:103], v[138:139], 0, v[136:137]
	v_lshl_add_u64 v[110:111], v[140:141], 0, v[136:137]
	global_load_dwordx4 v[106:109], v[102:103], off
	global_load_dwordx4 v[114:117], v[110:111], off
	s_waitcnt vmcnt(0)
	v_pk_mul_f32 v[102:103], v[92:93], v[106:107]
	v_pk_mul_f32 v[110:111], v[92:93], v[114:115] op_sel:[1,0] op_sel_hi:[0,0]
	v_pk_mul_f32 v[114:115], v[94:95], v[114:115] op_sel:[1,1] op_sel_hi:[0,1]
	v_pk_mul_f32 v[118:119], v[88:89], v[116:117] op_sel:[1,0] op_sel_hi:[0,0]
	v_mov_b32_e32 v116, v109
	v_mul_f32_e32 v122, v91, v117
	v_mul_f32_e32 v124, v91, v109
	v_pk_fma_f32 v[92:93], v[92:93], v[106:107], v[110:111] op_sel_hi:[1,0,1]
	v_pk_fma_f32 v[126:127], v[94:95], v[106:107], v[114:115] op_sel:[0,1,0] neg_lo:[0,0,1] neg_hi:[0,0,1]
	v_pk_fma_f32 v[94:95], v[94:95], v[106:107], v[114:115] op_sel:[0,1,0]
	v_pk_fma_f32 v[106:107], v[88:89], v[108:109], v[118:119] op_sel_hi:[1,0,1] neg_lo:[0,0,1] neg_hi:[0,0,1]
	v_pk_fma_f32 v[88:89], v[88:89], v[108:109], v[118:119] op_sel_hi:[1,0,1]
	v_mov_b32_e32 v108, v117
	v_pk_fma_f32 v[114:115], v[90:91], v[116:117], v[122:123] op_sel_hi:[1,1,0] neg_lo:[0,0,1] neg_hi:[0,0,1]
	v_pk_fma_f32 v[108:109], v[90:91], v[108:109], v[124:125] op_sel_hi:[1,1,0]
	v_sub_f32_e32 v92, v102, v110
	v_mov_b32_e32 v94, v126
	v_mov_b32_e32 v88, v106
	v_mov_b32_e32 v90, v114
	v_mov_b32_e32 v91, v108
.LBB0_1275:
	v_pk_mul_f32 v[92:93], v[150:151], v[92:93]
	v_pk_mul_f32 v[94:95], v[150:151], v[94:95]
	v_pk_mul_f32 v[88:89], v[150:151], v[88:89]
	v_ashrrev_i32_e32 v99, 31, v98
	v_cvt_pk_bf16_f32 v92, v92, v93
	v_cvt_pk_bf16_f32 v93, v94, v95
	v_cvt_pk_bf16_f32 v94, v88, v89
	v_lshlrev_b64 v[88:89], 13, v[98:99]
	v_pk_mul_f32 v[90:91], v[150:151], v[90:91]
	v_lshl_add_u64 v[88:89], s[60:61], 0, v[88:89]
	v_cvt_pk_bf16_f32 v95, v90, v91
	v_lshl_add_u64 v[90:91], v[154:155], 1, v[88:89]
	v_cndmask_b32_e64 v88, v159, v100, s[0:1]
	s_and_b64 vcc, exec, s[6:7]
	v_lshlrev_b32_e32 v88, 7, v88
	global_store_dwordx4 v[90:91], v[92:95], off sc1
	s_cbranch_vccnz .LBB0_1277
	v_mov_b32_e32 v89, v137
	v_lshl_add_u64 v[92:93], v[138:139], 0, v[88:89]
	v_lshl_add_u64 v[98:99], v[140:141], 0, v[88:89]
	global_load_dwordx4 v[92:95], v[92:93], off
	s_nop 0
	global_load_dwordx4 v[106:109], v[98:99], off
	s_waitcnt vmcnt(0)
	v_pk_mul_f32 v[98:99], v[84:85], v[92:93]
	v_pk_mul_f32 v[102:103], v[84:85], v[106:107] op_sel:[1,0] op_sel_hi:[0,0]
	v_pk_mul_f32 v[106:107], v[86:87], v[106:107] op_sel:[1,1] op_sel_hi:[0,1]
	v_pk_mul_f32 v[110:111], v[80:81], v[108:109] op_sel:[1,0] op_sel_hi:[0,0]
	v_mov_b32_e32 v108, v95
	v_mul_f32_e32 v114, v83, v109
	v_mul_f32_e32 v116, v83, v95
	v_pk_fma_f32 v[84:85], v[84:85], v[92:93], v[102:103] op_sel_hi:[1,0,1]
	v_pk_fma_f32 v[118:119], v[86:87], v[92:93], v[106:107] op_sel:[0,1,0] neg_lo:[0,0,1] neg_hi:[0,0,1]
	v_pk_fma_f32 v[86:87], v[86:87], v[92:93], v[106:107] op_sel:[0,1,0]
	v_pk_fma_f32 v[92:93], v[80:81], v[94:95], v[110:111] op_sel_hi:[1,0,1] neg_lo:[0,0,1] neg_hi:[0,0,1]
	v_pk_fma_f32 v[80:81], v[80:81], v[94:95], v[110:111] op_sel_hi:[1,0,1]
	v_mov_b32_e32 v94, v109
	v_pk_fma_f32 v[106:107], v[82:83], v[108:109], v[114:115] op_sel_hi:[1,1,0] neg_lo:[0,0,1] neg_hi:[0,0,1]
	v_pk_fma_f32 v[94:95], v[82:83], v[94:95], v[116:117] op_sel_hi:[1,1,0]
	v_sub_f32_e32 v84, v98, v102
	v_mov_b32_e32 v86, v118
	v_mov_b32_e32 v80, v92
	v_mov_b32_e32 v82, v106
	v_mov_b32_e32 v83, v94
.LBB0_1277:
	v_pk_mul_f32 v[84:85], v[150:151], v[84:85]
	v_pk_mul_f32 v[80:81], v[150:151], v[80:81]
	v_pk_mul_f32 v[92:93], v[150:151], v[82:83]
	v_cvt_pk_bf16_f32 v82, v84, v85
	v_cvt_pk_bf16_f32 v84, v80, v81
	v_lshlrev_b64 v[80:81], 13, v[152:153]
	v_lshl_add_u64 v[80:81], s[60:61], 0, v[80:81]
	v_pk_mul_f32 v[86:87], v[150:151], v[86:87]
	v_lshl_add_u64 v[80:81], v[154:155], 1, v[80:81]
	v_cvt_pk_bf16_f32 v83, v86, v87
	v_add_co_u32_e32 v86, vcc, 0x120000, v80
	v_cvt_pk_bf16_f32 v85, v92, v93
	s_nop 0
	v_addc_co_u32_e32 v87, vcc, 0, v81, vcc
	global_store_dwordx4 v[86:87], v[82:85], off sc1
	s_and_b64 vcc, exec, s[6:7]
	s_nop 0
	v_cndmask_b32_e64 v82, v160, v100, s[0:1]
	v_lshlrev_b32_e32 v82, 7, v82
	s_cbranch_vccnz .LBB0_1279
	v_mov_b32_e32 v83, v137
	v_lshl_add_u64 v[84:85], v[138:139], 0, v[82:83]
	v_lshl_add_u64 v[92:93], v[140:141], 0, v[82:83]
	global_load_dwordx4 v[84:87], v[84:85], off
	s_nop 0
	global_load_dwordx4 v[92:95], v[92:93], off
	s_waitcnt vmcnt(0)
	v_pk_mul_f32 v[98:99], v[76:77], v[84:85]
	v_pk_mul_f32 v[102:103], v[76:77], v[92:93] op_sel:[1,0] op_sel_hi:[0,0]
	v_pk_mul_f32 v[92:93], v[78:79], v[92:93] op_sel:[1,1] op_sel_hi:[0,1]
	v_pk_mul_f32 v[106:107], v[72:73], v[94:95] op_sel:[1,0] op_sel_hi:[0,0]
	v_mov_b32_e32 v94, v87
	v_mul_f32_e32 v108, v75, v95
	v_mul_f32_e32 v110, v75, v87
	v_pk_fma_f32 v[76:77], v[76:77], v[84:85], v[102:103] op_sel_hi:[1,0,1]
	v_pk_fma_f32 v[114:115], v[78:79], v[84:85], v[92:93] op_sel:[0,1,0] neg_lo:[0,0,1] neg_hi:[0,0,1]
	v_pk_fma_f32 v[78:79], v[78:79], v[84:85], v[92:93] op_sel:[0,1,0]
	v_pk_fma_f32 v[84:85], v[72:73], v[86:87], v[106:107] op_sel_hi:[1,0,1] neg_lo:[0,0,1] neg_hi:[0,0,1]
	v_pk_fma_f32 v[72:73], v[72:73], v[86:87], v[106:107] op_sel_hi:[1,0,1]
	v_mov_b32_e32 v86, v95
	v_pk_fma_f32 v[92:93], v[74:75], v[94:95], v[108:109] op_sel_hi:[1,1,0] neg_lo:[0,0,1] neg_hi:[0,0,1]
	v_pk_fma_f32 v[86:87], v[74:75], v[86:87], v[110:111] op_sel_hi:[1,1,0]
	v_sub_f32_e32 v76, v98, v102
	v_mov_b32_e32 v78, v114
	v_mov_b32_e32 v72, v84
	v_mov_b32_e32 v74, v92
	v_mov_b32_e32 v75, v86
.LBB0_1279:
	v_pk_mul_f32 v[76:77], v[150:151], v[76:77]
	v_pk_mul_f32 v[78:79], v[150:151], v[78:79]
	v_pk_mul_f32 v[84:85], v[150:151], v[72:73]
	v_pk_mul_f32 v[86:87], v[150:151], v[74:75]
	v_cvt_pk_bf16_f32 v72, v76, v77
	v_add_co_u32_e32 v76, vcc, 0x140000, v80
	v_cvt_pk_bf16_f32 v73, v78, v79
	v_cvt_pk_bf16_f32 v74, v84, v85
	v_cvt_pk_bf16_f32 v75, v86, v87
	v_addc_co_u32_e32 v77, vcc, 0, v81, vcc
	global_store_dwordx4 v[76:77], v[72:75], off sc1
	s_and_b64 vcc, exec, s[6:7]
	s_nop 0
	v_cndmask_b32_e64 v72, v161, v100, s[0:1]
	v_lshlrev_b32_e32 v72, 7, v72
	s_cbranch_vccnz .LBB0_1281
	v_mov_b32_e32 v73, v137
	v_lshl_add_u64 v[74:75], v[138:139], 0, v[72:73]
	v_lshl_add_u64 v[78:79], v[140:141], 0, v[72:73]
	global_load_dwordx4 v[74:77], v[74:75], off
	s_nop 0
	global_load_dwordx4 v[84:87], v[78:79], off
	s_waitcnt vmcnt(0)
	v_pk_mul_f32 v[78:79], v[68:69], v[74:75]
	v_pk_mul_f32 v[92:93], v[68:69], v[84:85] op_sel:[1,0] op_sel_hi:[0,0]
	v_pk_mul_f32 v[84:85], v[70:71], v[84:85] op_sel:[1,1] op_sel_hi:[0,1]
	v_pk_mul_f32 v[94:95], v[64:65], v[86:87] op_sel:[1,0] op_sel_hi:[0,0]
	v_mov_b32_e32 v86, v77
	v_mul_f32_e32 v98, v67, v87
	v_mul_f32_e32 v100, v67, v77
	v_pk_fma_f32 v[68:69], v[68:69], v[74:75], v[92:93] op_sel_hi:[1,0,1]
	v_pk_fma_f32 v[102:103], v[70:71], v[74:75], v[84:85] op_sel:[0,1,0] neg_lo:[0,0,1] neg_hi:[0,0,1]
	v_pk_fma_f32 v[70:71], v[70:71], v[74:75], v[84:85] op_sel:[0,1,0]
	v_pk_fma_f32 v[74:75], v[64:65], v[76:77], v[94:95] op_sel_hi:[1,0,1] neg_lo:[0,0,1] neg_hi:[0,0,1]
	v_pk_fma_f32 v[64:65], v[64:65], v[76:77], v[94:95] op_sel_hi:[1,0,1]
	v_mov_b32_e32 v76, v87
	v_pk_fma_f32 v[84:85], v[66:67], v[86:87], v[98:99] op_sel_hi:[1,1,0] neg_lo:[0,0,1] neg_hi:[0,0,1]
	v_pk_fma_f32 v[76:77], v[66:67], v[76:77], v[100:101] op_sel_hi:[1,1,0]
	v_sub_f32_e32 v68, v78, v92
	v_mov_b32_e32 v70, v102
	v_mov_b32_e32 v64, v74
	v_mov_b32_e32 v66, v84
	v_mov_b32_e32 v67, v76
.LBB0_1281:
	v_pk_mul_f32 v[68:69], v[150:151], v[68:69]
	v_pk_mul_f32 v[64:65], v[150:151], v[64:65]
	v_pk_mul_f32 v[74:75], v[150:151], v[66:67]
	v_cvt_pk_bf16_f32 v66, v68, v69
	v_cvt_pk_bf16_f32 v68, v64, v65
	v_lshlrev_b64 v[64:65], 13, v[152:153]
	v_lshl_add_u64 v[64:65], s[60:61], 0, v[64:65]
	v_pk_mul_f32 v[70:71], v[150:151], v[70:71]
	v_lshl_add_u64 v[64:65], v[154:155], 1, v[64:65]
	v_cvt_pk_bf16_f32 v67, v70, v71
	v_add_co_u32_e32 v70, vcc, 0x160000, v64
	v_cvt_pk_bf16_f32 v69, v74, v75
	s_nop 0
	v_addc_co_u32_e32 v71, vcc, 0, v65, vcc
	s_and_b64 vcc, exec, s[6:7]
	global_store_dwordx4 v[70:71], v[66:69], off sc1
	s_cbranch_vccnz .LBB0_1283
	s_nop 0
	v_mov_b32_e32 v66, s35
	v_cndmask_b32_e64 v66, v156, v66, s[0:1]
	v_lshlrev_b32_e32 v66, 7, v66
	v_mov_b32_e32 v67, v137
	v_lshl_add_u64 v[68:69], v[138:139], 0, v[66:67]
	v_lshl_add_u64 v[70:71], v[140:141], 0, v[66:67]
	global_load_dwordx4 v[66:69], v[68:69], off
	s_nop 0
	global_load_dwordx4 v[74:77], v[70:71], off
	s_waitcnt vmcnt(0)
	v_pk_mul_f32 v[70:71], v[60:61], v[66:67]
	v_pk_mul_f32 v[78:79], v[60:61], v[74:75] op_sel:[1,0] op_sel_hi:[0,0]
	v_pk_mul_f32 v[74:75], v[62:63], v[74:75] op_sel:[1,1] op_sel_hi:[0,1]
	v_pk_mul_f32 v[84:85], v[56:57], v[76:77] op_sel:[1,0] op_sel_hi:[0,0]
	v_mov_b32_e32 v76, v69
	v_mul_f32_e32 v86, v59, v77
	v_mul_f32_e32 v92, v59, v69
	v_pk_fma_f32 v[60:61], v[60:61], v[66:67], v[78:79] op_sel_hi:[1,0,1]
	v_pk_fma_f32 v[94:95], v[62:63], v[66:67], v[74:75] op_sel:[0,1,0] neg_lo:[0,0,1] neg_hi:[0,0,1]
	v_pk_fma_f32 v[62:63], v[62:63], v[66:67], v[74:75] op_sel:[0,1,0]
	v_pk_fma_f32 v[66:67], v[56:57], v[68:69], v[84:85] op_sel_hi:[1,0,1] neg_lo:[0,0,1] neg_hi:[0,0,1]
	v_pk_fma_f32 v[56:57], v[56:57], v[68:69], v[84:85] op_sel_hi:[1,0,1]
	v_mov_b32_e32 v68, v77
	v_pk_fma_f32 v[74:75], v[58:59], v[76:77], v[86:87] op_sel_hi:[1,1,0] neg_lo:[0,0,1] neg_hi:[0,0,1]
	v_pk_fma_f32 v[68:69], v[58:59], v[68:69], v[92:93] op_sel_hi:[1,1,0]
	v_sub_f32_e32 v60, v70, v78
	v_mov_b32_e32 v62, v94
	v_mov_b32_e32 v56, v66
	v_mov_b32_e32 v58, v74
	v_mov_b32_e32 v59, v68
.LBB0_1283:
	v_pk_mul_f32 v[60:61], v[150:151], v[60:61]
	v_pk_mul_f32 v[62:63], v[150:151], v[62:63]
	v_pk_mul_f32 v[66:67], v[150:151], v[56:57]
	v_pk_mul_f32 v[68:69], v[150:151], v[58:59]
	v_cvt_pk_bf16_f32 v56, v60, v61
	v_cvt_pk_bf16_f32 v57, v62, v63
	v_cvt_pk_bf16_f32 v58, v66, v67
	v_cvt_pk_bf16_f32 v59, v68, v69
	s_and_b64 vcc, exec, s[6:7]
	global_store_dwordx4 v[120:121], v[56:59], off offset:256 sc1
	s_cbranch_vccnz .LBB0_1285
	s_nop 0
	v_mov_b32_e32 v56, s35
	v_cndmask_b32_e64 v56, v159, v56, s[0:1]
	v_lshlrev_b32_e32 v56, 7, v56
	v_mov_b32_e32 v57, v137
	v_lshl_add_u64 v[58:59], v[138:139], 0, v[56:57]
	v_lshl_add_u64 v[60:61], v[140:141], 0, v[56:57]
	global_load_dwordx4 v[56:59], v[58:59], off
	s_nop 0
	global_load_dwordx4 v[60:63], v[60:61], off
	s_waitcnt vmcnt(0)
	v_pk_mul_f32 v[66:67], v[52:53], v[56:57]
	v_pk_mul_f32 v[68:69], v[52:53], v[60:61] op_sel:[1,0] op_sel_hi:[0,0]
	v_pk_mul_f32 v[60:61], v[54:55], v[60:61] op_sel:[1,1] op_sel_hi:[0,1]
	v_pk_mul_f32 v[70:71], v[48:49], v[62:63] op_sel:[1,0] op_sel_hi:[0,0]
	v_mov_b32_e32 v62, v59
	v_mul_f32_e32 v74, v51, v63
	v_mul_f32_e32 v76, v51, v59
	v_pk_fma_f32 v[52:53], v[52:53], v[56:57], v[68:69] op_sel_hi:[1,0,1]
	v_pk_fma_f32 v[78:79], v[54:55], v[56:57], v[60:61] op_sel:[0,1,0] neg_lo:[0,0,1] neg_hi:[0,0,1]
	v_pk_fma_f32 v[54:55], v[54:55], v[56:57], v[60:61] op_sel:[0,1,0]
	v_pk_fma_f32 v[56:57], v[48:49], v[58:59], v[70:71] op_sel_hi:[1,0,1] neg_lo:[0,0,1] neg_hi:[0,0,1]
	v_pk_fma_f32 v[48:49], v[48:49], v[58:59], v[70:71] op_sel_hi:[1,0,1]
	v_mov_b32_e32 v58, v63
	v_pk_fma_f32 v[60:61], v[50:51], v[62:63], v[74:75] op_sel_hi:[1,1,0] neg_lo:[0,0,1] neg_hi:[0,0,1]
	v_pk_fma_f32 v[58:59], v[50:51], v[58:59], v[76:77] op_sel_hi:[1,1,0]
	v_sub_f32_e32 v52, v66, v68
	v_mov_b32_e32 v54, v78
	v_mov_b32_e32 v48, v56
	v_mov_b32_e32 v50, v60
	v_mov_b32_e32 v51, v58
.LBB0_1285:
	v_pk_mul_f32 v[52:53], v[150:151], v[52:53]
	v_pk_mul_f32 v[54:55], v[150:151], v[54:55]
	v_pk_mul_f32 v[56:57], v[150:151], v[48:49]
	v_pk_mul_f32 v[58:59], v[150:151], v[50:51]
	v_cvt_pk_bf16_f32 v48, v52, v53
	v_cvt_pk_bf16_f32 v49, v54, v55
	v_cvt_pk_bf16_f32 v50, v56, v57
	v_cvt_pk_bf16_f32 v51, v58, v59
	s_and_b64 vcc, exec, s[6:7]
	global_store_dwordx4 v[112:113], v[48:51], off offset:256 sc1
	s_cbranch_vccnz .LBB0_1287
	s_nop 0
	v_mov_b32_e32 v48, s35
	v_cndmask_b32_e64 v48, v160, v48, s[0:1]
	v_lshlrev_b32_e32 v48, 7, v48
	v_mov_b32_e32 v49, v137
	v_lshl_add_u64 v[50:51], v[138:139], 0, v[48:49]
	v_lshl_add_u64 v[52:53], v[140:141], 0, v[48:49]
	global_load_dwordx4 v[48:51], v[50:51], off
	s_nop 0
	global_load_dwordx4 v[52:55], v[52:53], off
	s_waitcnt vmcnt(0)
	v_pk_mul_f32 v[56:57], v[44:45], v[48:49]
	v_pk_mul_f32 v[58:59], v[44:45], v[52:53] op_sel:[1,0] op_sel_hi:[0,0]
	v_pk_mul_f32 v[52:53], v[46:47], v[52:53] op_sel:[1,1] op_sel_hi:[0,1]
	v_pk_mul_f32 v[60:61], v[40:41], v[54:55] op_sel:[1,0] op_sel_hi:[0,0]
	v_mov_b32_e32 v54, v51
	v_mul_f32_e32 v62, v43, v55
	v_mul_f32_e32 v66, v43, v51
	v_pk_fma_f32 v[44:45], v[44:45], v[48:49], v[58:59] op_sel_hi:[1,0,1]
	v_pk_fma_f32 v[68:69], v[46:47], v[48:49], v[52:53] op_sel:[0,1,0] neg_lo:[0,0,1] neg_hi:[0,0,1]
	v_pk_fma_f32 v[46:47], v[46:47], v[48:49], v[52:53] op_sel:[0,1,0]
	v_pk_fma_f32 v[48:49], v[40:41], v[50:51], v[60:61] op_sel_hi:[1,0,1] neg_lo:[0,0,1] neg_hi:[0,0,1]
	v_pk_fma_f32 v[40:41], v[40:41], v[50:51], v[60:61] op_sel_hi:[1,0,1]
	v_mov_b32_e32 v50, v55
	v_pk_fma_f32 v[52:53], v[42:43], v[54:55], v[62:63] op_sel_hi:[1,1,0] neg_lo:[0,0,1] neg_hi:[0,0,1]
	v_pk_fma_f32 v[50:51], v[42:43], v[50:51], v[66:67] op_sel_hi:[1,1,0]
	v_sub_f32_e32 v44, v56, v58
	v_mov_b32_e32 v46, v68
	v_mov_b32_e32 v40, v48
	v_mov_b32_e32 v42, v52
	v_mov_b32_e32 v43, v50
.LBB0_1287:
	v_pk_mul_f32 v[44:45], v[150:151], v[44:45]
	v_pk_mul_f32 v[46:47], v[150:151], v[46:47]
	v_pk_mul_f32 v[48:49], v[150:151], v[40:41]
	v_pk_mul_f32 v[50:51], v[150:151], v[42:43]
	v_cvt_pk_bf16_f32 v40, v44, v45
	v_cvt_pk_bf16_f32 v41, v46, v47
	v_cvt_pk_bf16_f32 v42, v48, v49
	v_cvt_pk_bf16_f32 v43, v50, v51
	s_and_b64 vcc, exec, s[6:7]
	global_store_dwordx4 v[104:105], v[40:43], off offset:256 sc1
	s_cbranch_vccnz .LBB0_1289
	s_nop 0
	v_mov_b32_e32 v40, s35
	v_cndmask_b32_e64 v40, v161, v40, s[0:1]
	v_lshlrev_b32_e32 v40, 7, v40
	v_mov_b32_e32 v41, v137
	v_lshl_add_u64 v[42:43], v[138:139], 0, v[40:41]
	v_lshl_add_u64 v[44:45], v[140:141], 0, v[40:41]
	global_load_dwordx4 v[40:43], v[42:43], off
	s_nop 0
	global_load_dwordx4 v[44:47], v[44:45], off
	s_waitcnt vmcnt(0)
	v_pk_mul_f32 v[48:49], v[36:37], v[40:41]
	v_pk_mul_f32 v[50:51], v[36:37], v[44:45] op_sel:[1,0] op_sel_hi:[0,0]
	v_pk_mul_f32 v[44:45], v[38:39], v[44:45] op_sel:[1,1] op_sel_hi:[0,1]
	v_pk_mul_f32 v[52:53], v[32:33], v[46:47] op_sel:[1,0] op_sel_hi:[0,0]
	v_mov_b32_e32 v46, v43
	v_mul_f32_e32 v54, v35, v47
	v_mul_f32_e32 v56, v35, v43
	v_pk_fma_f32 v[36:37], v[36:37], v[40:41], v[50:51] op_sel_hi:[1,0,1]
	v_pk_fma_f32 v[58:59], v[38:39], v[40:41], v[44:45] op_sel:[0,1,0] neg_lo:[0,0,1] neg_hi:[0,0,1]
	v_pk_fma_f32 v[38:39], v[38:39], v[40:41], v[44:45] op_sel:[0,1,0]
	v_pk_fma_f32 v[40:41], v[32:33], v[42:43], v[52:53] op_sel_hi:[1,0,1] neg_lo:[0,0,1] neg_hi:[0,0,1]
	v_pk_fma_f32 v[32:33], v[32:33], v[42:43], v[52:53] op_sel_hi:[1,0,1]
	v_mov_b32_e32 v42, v47
	v_pk_fma_f32 v[44:45], v[34:35], v[46:47], v[54:55] op_sel_hi:[1,1,0] neg_lo:[0,0,1] neg_hi:[0,0,1]
	v_pk_fma_f32 v[42:43], v[34:35], v[42:43], v[56:57] op_sel_hi:[1,1,0]
	v_sub_f32_e32 v36, v48, v50
	v_mov_b32_e32 v38, v58
	v_mov_b32_e32 v32, v40
	v_mov_b32_e32 v34, v44
	v_mov_b32_e32 v35, v42
.LBB0_1289:
	v_pk_mul_f32 v[36:37], v[150:151], v[36:37]
	v_pk_mul_f32 v[38:39], v[150:151], v[38:39]
	v_pk_mul_f32 v[40:41], v[150:151], v[32:33]
	v_pk_mul_f32 v[42:43], v[150:151], v[34:35]
	v_cvt_pk_bf16_f32 v32, v36, v37
	v_cvt_pk_bf16_f32 v33, v38, v39
	v_cvt_pk_bf16_f32 v34, v40, v41
	v_cvt_pk_bf16_f32 v35, v42, v43
	s_and_b64 vcc, exec, s[6:7]
	global_store_dwordx4 v[96:97], v[32:35], off offset:256 sc1
	s_cbranch_vccnz .LBB0_1291
	s_nop 0
	v_lshl_add_u64 v[32:33], v[138:139], 0, v[136:137]
	v_lshl_add_u64 v[36:37], v[140:141], 0, v[136:137]
	global_load_dwordx4 v[32:35], v[32:33], off
	s_nop 0
	global_load_dwordx4 v[36:39], v[36:37], off
	s_waitcnt vmcnt(0)
	v_pk_mul_f32 v[40:41], v[28:29], v[32:33]
	v_pk_mul_f32 v[42:43], v[28:29], v[36:37] op_sel:[1,0] op_sel_hi:[0,0]
	v_pk_mul_f32 v[36:37], v[30:31], v[36:37] op_sel:[1,1] op_sel_hi:[0,1]
	v_pk_mul_f32 v[44:45], v[24:25], v[38:39] op_sel:[1,0] op_sel_hi:[0,0]
	v_mov_b32_e32 v38, v35
	v_mul_f32_e32 v46, v27, v39
	v_mul_f32_e32 v48, v27, v35
	v_pk_fma_f32 v[28:29], v[28:29], v[32:33], v[42:43] op_sel_hi:[1,0,1]
	v_pk_fma_f32 v[50:51], v[30:31], v[32:33], v[36:37] op_sel:[0,1,0] neg_lo:[0,0,1] neg_hi:[0,0,1]
	v_pk_fma_f32 v[30:31], v[30:31], v[32:33], v[36:37] op_sel:[0,1,0]
	v_pk_fma_f32 v[32:33], v[24:25], v[34:35], v[44:45] op_sel_hi:[1,0,1] neg_lo:[0,0,1] neg_hi:[0,0,1]
	v_pk_fma_f32 v[24:25], v[24:25], v[34:35], v[44:45] op_sel_hi:[1,0,1]
	v_mov_b32_e32 v34, v39
	v_pk_fma_f32 v[36:37], v[26:27], v[38:39], v[46:47] op_sel_hi:[1,1,0] neg_lo:[0,0,1] neg_hi:[0,0,1]
	v_pk_fma_f32 v[34:35], v[26:27], v[34:35], v[48:49] op_sel_hi:[1,1,0]
	v_sub_f32_e32 v28, v40, v42
	v_mov_b32_e32 v30, v50
	v_mov_b32_e32 v24, v32
	v_mov_b32_e32 v26, v36
	v_mov_b32_e32 v27, v34
.LBB0_1291:
	v_pk_mul_f32 v[28:29], v[150:151], v[28:29]
	v_pk_mul_f32 v[30:31], v[150:151], v[30:31]
	v_pk_mul_f32 v[32:33], v[150:151], v[24:25]
	v_pk_mul_f32 v[34:35], v[150:151], v[26:27]
	v_cvt_pk_bf16_f32 v24, v28, v29
	v_cvt_pk_bf16_f32 v25, v30, v31
	v_cvt_pk_bf16_f32 v26, v32, v33
	v_cvt_pk_bf16_f32 v27, v34, v35
	s_and_b64 vcc, exec, s[6:7]
	global_store_dwordx4 v[90:91], v[24:27], off offset:256 sc1
	s_cbranch_vccnz .LBB0_1293
	v_mov_b32_e32 v89, v137
	v_lshl_add_u64 v[24:25], v[138:139], 0, v[88:89]
	v_lshl_add_u64 v[28:29], v[140:141], 0, v[88:89]
	global_load_dwordx4 v[24:27], v[24:25], off
	s_nop 0
	global_load_dwordx4 v[28:31], v[28:29], off
	s_waitcnt vmcnt(0)
	v_pk_mul_f32 v[32:33], v[20:21], v[24:25]
	v_pk_mul_f32 v[34:35], v[20:21], v[28:29] op_sel:[1,0] op_sel_hi:[0,0]
	v_pk_mul_f32 v[28:29], v[22:23], v[28:29] op_sel:[1,1] op_sel_hi:[0,1]
	v_pk_mul_f32 v[36:37], v[16:17], v[30:31] op_sel:[1,0] op_sel_hi:[0,0]
	v_mov_b32_e32 v30, v27
	v_mul_f32_e32 v38, v19, v31
	v_mul_f32_e32 v40, v19, v27
	v_pk_fma_f32 v[20:21], v[20:21], v[24:25], v[34:35] op_sel_hi:[1,0,1]
	v_pk_fma_f32 v[42:43], v[22:23], v[24:25], v[28:29] op_sel:[0,1,0] neg_lo:[0,0,1] neg_hi:[0,0,1]
	v_pk_fma_f32 v[22:23], v[22:23], v[24:25], v[28:29] op_sel:[0,1,0]
	v_pk_fma_f32 v[24:25], v[16:17], v[26:27], v[36:37] op_sel_hi:[1,0,1] neg_lo:[0,0,1] neg_hi:[0,0,1]
	v_pk_fma_f32 v[16:17], v[16:17], v[26:27], v[36:37] op_sel_hi:[1,0,1]
	v_mov_b32_e32 v26, v31
	v_pk_fma_f32 v[28:29], v[18:19], v[30:31], v[38:39] op_sel_hi:[1,1,0] neg_lo:[0,0,1] neg_hi:[0,0,1]
	v_pk_fma_f32 v[26:27], v[18:19], v[26:27], v[40:41] op_sel_hi:[1,1,0]
	v_sub_f32_e32 v20, v32, v34
	v_mov_b32_e32 v22, v42
	v_mov_b32_e32 v16, v24
	v_mov_b32_e32 v18, v28
	v_mov_b32_e32 v19, v26
.LBB0_1293:
	v_pk_mul_f32 v[20:21], v[150:151], v[20:21]
	v_pk_mul_f32 v[22:23], v[150:151], v[22:23]
	v_pk_mul_f32 v[26:27], v[150:151], v[16:17]
	v_pk_mul_f32 v[28:29], v[150:151], v[18:19]
	v_lshl_add_u64 v[24:25], v[80:81], 0, s[38:39]
	v_cvt_pk_bf16_f32 v16, v20, v21
	v_cvt_pk_bf16_f32 v17, v22, v23
	v_cvt_pk_bf16_f32 v18, v26, v27
	v_cvt_pk_bf16_f32 v19, v28, v29
	s_and_b64 vcc, exec, s[6:7]
	global_store_dwordx4 v[24:25], v[16:19], off offset:256 sc1
	s_cbranch_vccnz .LBB0_1295
	v_mov_b32_e32 v83, v137
	v_lshl_add_u64 v[16:17], v[138:139], 0, v[82:83]
	v_lshl_add_u64 v[20:21], v[140:141], 0, v[82:83]
	global_load_dwordx4 v[16:19], v[16:17], off
	s_nop 0
	global_load_dwordx4 v[20:23], v[20:21], off
	s_waitcnt vmcnt(0)
	v_pk_mul_f32 v[24:25], v[12:13], v[16:17]
	v_pk_mul_f32 v[26:27], v[12:13], v[20:21] op_sel:[1,0] op_sel_hi:[0,0]
	v_pk_mul_f32 v[20:21], v[14:15], v[20:21] op_sel:[1,1] op_sel_hi:[0,1]
	v_pk_mul_f32 v[28:29], v[8:9], v[22:23] op_sel:[1,0] op_sel_hi:[0,0]
	v_mov_b32_e32 v22, v19
	v_mul_f32_e32 v30, v11, v23
	v_mul_f32_e32 v32, v11, v19
	v_pk_fma_f32 v[12:13], v[12:13], v[16:17], v[26:27] op_sel_hi:[1,0,1]
	v_pk_fma_f32 v[34:35], v[14:15], v[16:17], v[20:21] op_sel:[0,1,0] neg_lo:[0,0,1] neg_hi:[0,0,1]
	v_pk_fma_f32 v[14:15], v[14:15], v[16:17], v[20:21] op_sel:[0,1,0]
	v_pk_fma_f32 v[16:17], v[8:9], v[18:19], v[28:29] op_sel_hi:[1,0,1] neg_lo:[0,0,1] neg_hi:[0,0,1]
	v_pk_fma_f32 v[8:9], v[8:9], v[18:19], v[28:29] op_sel_hi:[1,0,1]
	v_mov_b32_e32 v18, v23
	v_pk_fma_f32 v[20:21], v[10:11], v[22:23], v[30:31] op_sel_hi:[1,1,0] neg_lo:[0,0,1] neg_hi:[0,0,1]
	v_pk_fma_f32 v[18:19], v[10:11], v[18:19], v[32:33] op_sel_hi:[1,1,0]
	v_sub_f32_e32 v12, v24, v26
	v_mov_b32_e32 v14, v34
	v_mov_b32_e32 v8, v16
	v_mov_b32_e32 v10, v20
	v_mov_b32_e32 v11, v18
.LBB0_1295:
	v_pk_mul_f32 v[12:13], v[150:151], v[12:13]
	v_pk_mul_f32 v[14:15], v[150:151], v[14:15]
	v_pk_mul_f32 v[18:19], v[150:151], v[8:9]
	v_pk_mul_f32 v[20:21], v[150:151], v[10:11]
	v_lshl_add_u64 v[16:17], v[80:81], 0, s[40:41]
	v_cvt_pk_bf16_f32 v8, v12, v13
	v_cvt_pk_bf16_f32 v9, v14, v15
	v_cvt_pk_bf16_f32 v10, v18, v19
	v_cvt_pk_bf16_f32 v11, v20, v21
	s_and_b64 vcc, exec, s[6:7]
	global_store_dwordx4 v[16:17], v[8:11], off offset:256 sc1
	s_cbranch_vccnz .LBB0_1260
	v_mov_b32_e32 v73, v137
	v_lshl_add_u64 v[8:9], v[138:139], 0, v[72:73]
	v_lshl_add_u64 v[12:13], v[140:141], 0, v[72:73]
	global_load_dwordx4 v[8:11], v[8:9], off
	s_nop 0
	global_load_dwordx4 v[12:15], v[12:13], off
	s_waitcnt vmcnt(0)
	v_pk_mul_f32 v[16:17], v[4:5], v[8:9]
	v_pk_mul_f32 v[18:19], v[4:5], v[12:13] op_sel:[1,0] op_sel_hi:[0,0]
	v_pk_mul_f32 v[12:13], v[6:7], v[12:13] op_sel:[1,1] op_sel_hi:[0,1]
	v_pk_mul_f32 v[20:21], v[0:1], v[14:15] op_sel:[1,0] op_sel_hi:[0,0]
	v_mov_b32_e32 v14, v11
	v_mul_f32_e32 v22, v3, v15
	v_mul_f32_e32 v24, v3, v11
	v_pk_fma_f32 v[4:5], v[4:5], v[8:9], v[18:19] op_sel_hi:[1,0,1]
	v_pk_fma_f32 v[26:27], v[6:7], v[8:9], v[12:13] op_sel:[0,1,0] neg_lo:[0,0,1] neg_hi:[0,0,1]
	v_pk_fma_f32 v[6:7], v[6:7], v[8:9], v[12:13] op_sel:[0,1,0]
	v_pk_fma_f32 v[8:9], v[0:1], v[10:11], v[20:21] op_sel_hi:[1,0,1] neg_lo:[0,0,1] neg_hi:[0,0,1]
	v_pk_fma_f32 v[0:1], v[0:1], v[10:11], v[20:21] op_sel_hi:[1,0,1]
	v_mov_b32_e32 v10, v15
	v_pk_fma_f32 v[12:13], v[2:3], v[14:15], v[22:23] op_sel_hi:[1,1,0] neg_lo:[0,0,1] neg_hi:[0,0,1]
	v_pk_fma_f32 v[10:11], v[2:3], v[10:11], v[24:25] op_sel_hi:[1,1,0]
	v_sub_f32_e32 v4, v16, v18
	v_mov_b32_e32 v6, v26
	v_mov_b32_e32 v0, v8
	v_mov_b32_e32 v2, v12
	v_mov_b32_e32 v3, v10
	s_branch .LBB0_1260

.LBB0_1370:
	s_add_i32 s1, s57, -1
	s_waitcnt vmcnt(7)
	ds_write_b128 v175, v[72:75]
	ds_write_b128 v175, v[68:71] offset:8704
	ds_write_b128 v175, v[64:67] offset:17408
	v_cndmask_b32_e32 v65, v180, v173, vcc
	v_xor_b32_e32 v66, 0xffffffef, v173
	v_xor_b32_e32 v70, 0xffffffcf, v173
	s_min_u32 s18, s1, s0
	v_add_u32_e32 v69, 48, v173
	v_xor_b32_e32 v67, 0xffffffdf, v173
	v_add_u32_e32 v71, s55, v66
	v_add_u32_e32 v66, s56, v65
	v_add_u32_e32 v70, s55, v70
	v_lshl_add_u32 v73, s18, 5, v174
	v_add_u32_e32 v64, 16, v173
	v_add_u32_e32 v68, 32, v173
	v_add_u32_e32 v65, s55, v67
	v_ashrrev_i32_e32 v67, 31, v66
	v_cndmask_b32_e32 v69, v70, v69, vcc
	v_xad_u32 v70, v73, -1, s55
	v_cndmask_b32_e32 v71, v71, v64, vcc
	v_cndmask_b32_e32 v68, v65, v68, vcc
	v_lshlrev_b64 v[64:65], 11, v[66:67]
	v_cndmask_b32_e32 v67, v70, v73, vcc
	s_min_u32 s42, s57, s0
	v_lshl_add_u64 v[242:243], v[170:171], 0, v[64:65]
	v_add_u32_e32 v64, s56, v67
	v_lshl_add_u32 v72, s42, 5, v174
	v_ashrrev_i32_e32 v65, 31, v64
	v_cvt_pk_bf16_f32 v60, v44, v45
	v_cvt_pk_bf16_f32 v61, v46, v47
	v_cvt_pk_bf16_f32 v62, v40, v41
	v_cvt_pk_bf16_f32 v63, v42, v43
	v_xad_u32 v74, v72, -1, s55
	v_lshlrev_b64 v[64:65], 13, v[64:65]
	v_cndmask_b32_e32 v66, v74, v72, vcc
	v_or_b32_e32 v64, v64, v181
	v_add_u32_e32 v238, s56, v68
	v_add_u32_e32 v240, s56, v69
	v_add_u32_e32 v244, s56, v66
	v_lshl_add_u64 v[66:67], s[36:37], 0, v[64:65]
	v_lshl_add_u64 v[68:69], s[38:39], 0, v[64:65]
	v_lshl_add_u64 v[64:65], s[40:41], 0, v[64:65]
	v_add_u32_e32 v0, 0x1000, v178
	v_add_u32_e32 v1, 0x2000, v179
	v_add_u32_e32 v182, 0x3000, v179
	v_add_u32_e32 v236, s56, v71
	global_load_dwordx4 v[72:75], v[66:67], off
	s_nop 0
	global_load_dwordx4 v[68:71], v[68:69], off
	s_nop 0
	global_load_dwordx4 v[64:67], v[64:65], off
	s_waitcnt lgkmcnt(0)
	s_barrier
	ds_read_b64 v[188:189], v178
	ds_read_b64 v[190:191], v178 offset:32
	ds_read_b64 v[192:193], v0 offset:256
	ds_read_b64 v[194:195], v0 offset:288
	ds_read_b64 v[196:197], v0 offset:320
	ds_read_b64 v[198:199], v0 offset:352
	ds_read_b64 v[200:201], v1 offset:512
	ds_read_b64 v[202:203], v1 offset:544
	ds_read_b64 v[204:205], v182 offset:768
	ds_read_b64 v[206:207], v182 offset:800
	ds_read_b64_tr_b16 v[210:211], v176 offset:13056
	ds_read_b64_tr_b16 v[212:213], v177 offset:17408
	ds_read_b64_tr_b16 v[214:215], v177 offset:21760
	ds_read_b64_tr_b16 v[208:209], v176 offset:8704
	ds_read_b64_tr_b16 v[216:217], v176 offset:8736
	ds_read_b64_tr_b16 v[220:221], v176 offset:8768
	ds_read_b64_tr_b16 v[222:223], v176 offset:13120
	ds_read_b64_tr_b16 v[218:219], v176 offset:13088
	ds_read_b64_tr_b16 v[230:231], v176 offset:8928
	s_waitcnt lgkmcnt(7)
	v_lshlrev_b32_e32 v232, 16, v212
	v_and_b32_e32 v233, 0xffff0000, v212
	v_lshlrev_b32_e32 v234, 16, v213
	v_and_b32_e32 v235, 0xffff0000, v213
	s_waitcnt lgkmcnt(6)
	v_lshlrev_b32_e32 v246, 16, v214
	v_and_b32_e32 v247, 0xffff0000, v214
	v_lshlrev_b32_e32 v248, 16, v215
	v_and_b32_e32 v249, 0xffff0000, v215
	v_mov_b32_e32 v159, v158
	v_mfma_f32_16x16x32_bf16 v[226:229], v[60:63], v[192:195], 0
	v_mul_f32_e64 v232, v150, v232
	v_mul_f32_e64 v233, v151, v233
	v_pk_mul_f32 v[234:235], v[152:153], v[234:235]
	v_pk_mul_f32 v[44:45], v[164:165], v[44:45]
	v_mfma_f32_16x16x32_bf16 v[60:63], v[60:63], v[188:191], 0
	v_mul_f32_e64 v46, v158, v46
	v_mul_f32_e64 v47, v159, v47
	v_pk_mul_f32 v[40:41], v[164:165], v[40:41]
	v_pk_mul_f32 v[42:43], v[158:159], v[42:43]
	v_mfma_f32_16x16x32_bf16 v[188:191], v[200:203], v[188:191], 0
	v_cvt_pk_bf16_f32 v52, v36, v37
	v_cvt_pk_bf16_f32 v53, v38, v39
	v_cvt_pk_bf16_f32 v54, v32, v33
	v_mfma_f32_16x16x32_bf16 v[200:203], v[200:203], v[192:195], 0
	v_cvt_pk_bf16_f32 v55, v34, v35
	v_cvt_pk_bf16_f32 v56, v28, v29
	v_cvt_pk_bf16_f32 v57, v30, v31
	v_mfma_f32_16x16x32_bf16 v[192:195], v[204:207], v[192:195], 0
	v_mul_f32_e64 v206, v154, v246
	v_mul_f32_e64 v207, v155, v247
	v_pk_mul_f32 v[246:247], v[156:157], v[248:249]
	v_cvt_pk_bf16_f32 v204, v232, v233
	v_cvt_pk_bf16_f32 v205, v234, v235
	v_cvt_pk_bf16_f32 v206, v206, v207
	v_cvt_pk_bf16_f32 v207, v246, v247
	v_pk_mul_f32 v[36:37], v[164:165], v[36:37]
	v_pk_mul_f32 v[32:33], v[164:165], v[32:33]
	s_waitcnt lgkmcnt(5)
	v_mfma_f32_16x16x32_bf16 v[44:47], v[208:211], v[204:207], v[44:47]
	ds_read_b64_tr_b16 v[210:211], v176 offset:13152
	ds_read_b64_tr_b16 v[208:209], v176 offset:8800
	ds_read_b64_tr_b16 v[232:233], v176 offset:8832
	v_pk_mul_f32 v[28:29], v[164:165], v[28:29]
	v_pk_mul_f32 v[38:39], v[158:159], v[38:39]
	s_waitcnt lgkmcnt(4)
	v_mfma_f32_16x16x32_bf16 v[40:43], v[216:219], v[204:207], v[40:43]
	ds_read_b64_tr_b16 v[216:217], v176 offset:8864
	ds_read_b64_tr_b16 v[234:235], v176 offset:13184
	ds_read_b64_tr_b16 v[218:219], v176 offset:13216
	v_pk_mul_f32 v[34:35], v[158:159], v[34:35]
	v_pk_mul_f32 v[30:31], v[158:159], v[30:31]
	v_mfma_f32_16x16x32_bf16 v[36:39], v[220:223], v[204:207], v[36:39]
	v_ashrrev_i32_e32 v245, 31, v244
	v_ashrrev_i32_e32 v237, 31, v236
	v_cvt_pk_bf16_f32 v58, v24, v25
	s_waitcnt lgkmcnt(4)
	v_mfma_f32_16x16x32_bf16 v[32:35], v[208:211], v[204:207], v[32:35]
	ds_read_b64_tr_b16 v[208:209], v176 offset:8896
	ds_read_b64_tr_b16 v[210:211], v176 offset:13248
	v_cvt_pk_bf16_f32 v59, v26, v27
	s_waitcnt lgkmcnt(3)
	v_mfma_f32_16x16x32_bf16 v[220:223], v[232:235], v[204:207], v[28:31]
	ds_read_b64_tr_b16 v[232:233], v176 offset:13280
	v_cvt_pk_bf16_f32 v48, v20, v21
	v_cvt_pk_bf16_f32 v49, v22, v23
	v_lshlrev_b64 v[28:29], 13, v[244:245]
	v_cvt_pk_bf16_f32 v50, v16, v17
	v_cvt_pk_bf16_f32 v51, v18, v19
	v_pk_mul_f32 v[24:25], v[164:165], v[24:25]
	v_pk_mul_f32 v[20:21], v[164:165], v[20:21]
	v_pk_mul_f32 v[16:17], v[164:165], v[16:17]
	v_pk_mul_f32 v[26:27], v[158:159], v[26:27]
	v_pk_mul_f32 v[22:23], v[158:159], v[22:23]
	v_pk_mul_f32 v[18:19], v[158:159], v[18:19]
	v_ashrrev_i32_e32 v239, 31, v238
	v_ashrrev_i32_e32 v241, 31, v240
	v_lshlrev_b64 v[236:237], 11, v[236:237]
	v_or_b32_e32 v28, v28, v181
	v_lshlrev_b64 v[246:247], 11, v[238:239]
	v_lshlrev_b64 v[248:249], 11, v[240:241]
	s_waitcnt lgkmcnt(3)
	v_mfma_f32_16x16x32_bf16 v[216:219], v[216:219], v[204:207], v[24:27]
	v_lshl_add_u64 v[234:235], v[170:171], 0, v[236:237]
	v_lshl_add_u64 v[236:237], s[36:37], 0, v[28:29]
	v_lshl_add_u64 v[238:239], s[38:39], 0, v[28:29]
	s_waitcnt lgkmcnt(1)
	v_mfma_f32_16x16x32_bf16 v[208:211], v[208:211], v[204:207], v[20:23]
	ds_read_b64 v[24:25], v1 offset:576
	ds_read_b64 v[26:27], v1 offset:608
	v_lshl_add_u64 v[240:241], s[40:41], 0, v[28:29]
	ds_read_b64 v[28:29], v182 offset:832
	ds_read_b64 v[30:31], v182 offset:864
	s_waitcnt lgkmcnt(4)
	v_mfma_f32_16x16x32_bf16 v[204:207], v[230:233], v[204:207], v[16:19]
	v_mov_b32_e32 v3, v2
	v_add_u32_e32 v183, 0x6000, v178
	v_add_u32_e32 v184, 0x7000, v178
	ds_read_b64 v[16:17], v178 offset:64
	ds_read_b64 v[18:19], v178 offset:96
	v_mfma_f32_16x16x32_bf16 v[226:229], v[52:55], v[196:199], v[226:229]
	v_add_u32_e32 v185, 0x8800, v179
	v_add_u32_e32 v186, 0x9800, v179
	s_add_i32 s57, s57, 2
	s_waitcnt lgkmcnt(0)
	v_mfma_f32_16x16x32_bf16 v[20:23], v[52:55], v[16:19], v[60:63]
	ds_read_b64 v[52:53], v0 offset:384
	ds_read_b64 v[54:55], v0 offset:416
	s_nop 1
	ds_read_b64 v[60:61], v178 offset:128
	ds_read_b64 v[62:63], v178 offset:160
	v_add_u32_e32 v173, 64, v173
	v_subrev_u32_e32 v180, 64, v180
	v_mfma_f32_16x16x32_bf16 v[16:19], v[24:27], v[16:19], v[188:191]
	s_cmp_ge_u32 s1, s58
	v_mfma_f32_16x16x32_bf16 v[24:27], v[24:27], v[196:199], v[200:203]
	v_mfma_f32_16x16x32_bf16 v[28:31], v[28:31], v[196:199], v[192:195]
	s_nop 2
	ds_read_b64 v[192:193], v1 offset:640
	ds_read_b64 v[194:195], v1 offset:672
	ds_read_b64 v[196:197], v178 offset:192
	ds_read_b64 v[198:199], v178 offset:224
	ds_read_b64 v[200:201], v0 offset:448
	ds_read_b64 v[202:203], v0 offset:480
	s_waitcnt lgkmcnt(8)
	v_mfma_f32_16x16x32_bf16 v[188:191], v[56:59], v[52:55], v[226:229]
	s_waitcnt lgkmcnt(6)
	v_mfma_f32_16x16x32_bf16 v[20:23], v[56:59], v[60:63], v[20:23]
	ds_read_b64 v[56:57], v182 offset:896
	ds_read_b64 v[58:59], v182 offset:928
	ds_read_b64 v[226:227], v1 offset:704
	ds_read_b64 v[228:229], v1 offset:736
	ds_read_b64 v[230:231], v182 offset:960
	ds_read_b64 v[232:233], v182 offset:992
	s_waitcnt vmcnt(5)
	ds_write_b128 v175, v[12:15] offset:26112
	ds_write_b128 v175, v[8:11] offset:34816
	ds_write_b128 v175, v[4:7] offset:43520
	s_waitcnt lgkmcnt(13)
	v_mfma_f32_16x16x32_bf16 v[16:19], v[192:195], v[60:63], v[16:19]
	v_mfma_f32_16x16x32_bf16 v[4:7], v[192:195], v[52:55], v[24:27]
	s_waitcnt lgkmcnt(7)
	v_mfma_f32_16x16x32_bf16 v[8:11], v[56:59], v[52:55], v[28:31]
	s_nop 0
	v_cvt_pk_bf16_f32 v24, v44, v45
	v_cvt_pk_bf16_f32 v25, v46, v47
	v_cvt_pk_bf16_f32 v26, v40, v41
	s_waitcnt lgkmcnt(5)
	v_mfma_f32_16x16x32_bf16 v[16:19], v[226:229], v[196:199], v[16:19]
	v_mul_f32_e64 v28, v164, v44
	v_mul_f32_e64 v29, v165, v45
	v_cvt_pk_bf16_f32 v27, v42, v43
	v_pk_mul_f32 v[30:31], v[158:159], v[46:47]
	v_mfma_f32_16x16x32_bf16 v[4:7], v[226:229], v[200:203], v[4:7]
	v_cvt_pk_bf16_f32 v52, v36, v37
	s_nop 1
	v_pk_mul_f32 v[18:19], v[146:147], v[18:19]
	v_pk_mul_f32 v[0:1], v[142:143], v[16:17]
	s_waitcnt lgkmcnt(3)
	v_mfma_f32_16x16x32_bf16 v[8:11], v[230:233], v[200:203], v[8:11]
	v_cvt_pk_bf16_f32 v0, v0, v1
	v_pk_mul_f32 v[6:7], v[148:149], v[6:7]
	v_pk_mul_f32 v[4:5], v[144:145], v[4:5]
	v_cvt_pk_bf16_f32 v1, v18, v19
	v_cvt_pk_bf16_f32 v4, v4, v5
	s_nop 2
	v_pk_mul_f32 v[16:17], v[146:147], v[10:11]
	v_pk_mul_f32 v[44:45], v[142:143], v[8:9]
	v_cvt_pk_bf16_f32 v5, v6, v7
	v_cvt_pk_bf16_f32 v6, v44, v45
	v_cvt_pk_bf16_f32 v7, v16, v17
	v_mfma_f32_16x16x32_bf16 v[12:15], v[48:51], v[200:203], v[188:191]
	v_cvt_pk_bf16_f32 v53, v38, v39
	v_pk_mul_f32 v[38:39], v[158:159], v[38:39]
	v_pk_mul_f32 v[36:37], v[164:165], v[36:37]
	v_mfma_f32_16x16x32_bf16 v[20:23], v[48:51], v[196:199], v[20:23]
	v_cvt_pk_bf16_f32 v54, v32, v33
	v_cvt_pk_bf16_f32 v55, v34, v35
	v_pk_mul_f32 v[42:43], v[158:159], v[42:43]
	v_mfma_f32_16x16x32_bf16 v[8:11], v[212:215], v[0:3], 0
	v_mul_f32_e64 v40, v164, v40
	v_mul_f32_e64 v41, v165, v41
	v_pk_mul_f32 v[34:35], v[158:159], v[34:35]
	v_pk_mul_f32 v[32:33], v[164:165], v[32:33]
	v_mfma_f32_16x16x32_bf16 v[4:7], v[212:215], v[4:7], 0
	v_mul_f32_e64 v50, v158, v222
	v_mul_f32_e64 v51, v159, v223
	s_nop 0
	v_pk_fma_f32 v[8:9], v[162:163], v[20:21], v[8:9]
	v_pk_mul_f32 v[48:49], v[164:165], v[220:221]
	v_cvt_pk_bf16_f32 v8, v8, v9
	v_cvt_pk_bf16_f32 v56, v220, v221
	s_nop 0
	v_pk_fma_f32 v[0:1], v[166:167], v[14:15], v[6:7]
	v_pk_fma_f32 v[6:7], v[168:169], v[22:23], v[10:11]
	v_pk_fma_f32 v[4:5], v[160:161], v[12:13], v[4:5]
	v_cvt_pk_bf16_f32 v9, v6, v7
	v_cvt_pk_bf16_f32 v4, v4, v5
	v_cvt_pk_bf16_f32 v5, v0, v1
	global_store_dwordx2 v[242:243], v[8:9], off sc1
	global_store_dwordx2 v[234:235], v[4:5], off sc1
	global_load_dwordx4 v[12:15], v[236:237], off
	s_nop 0
	global_load_dwordx4 v[8:11], v[238:239], off
	global_load_dwordx4 v[4:7], v[240:241], off
	s_waitcnt lgkmcnt(0)
	s_barrier
	ds_read_b64 v[16:17], v183 offset:1536
	ds_read_b64 v[18:19], v183 offset:1568
	ds_read_b64 v[20:21], v184 offset:1792
	ds_read_b64 v[22:23], v184 offset:1824
	ds_read_b64 v[60:61], v184 offset:1856
	ds_read_b64 v[62:63], v184 offset:1888
	ds_read_b64 v[44:45], v185
	ds_read_b64 v[46:47], v185 offset:32
	ds_read_b64 v[188:189], v186 offset:256
	ds_read_b64 v[190:191], v186 offset:288
	ds_read_b64_tr_b16 v[194:195], v176 offset:39168
	ds_read_b64_tr_b16 v[196:197], v177 offset:43520
	ds_read_b64_tr_b16 v[198:199], v177 offset:47872
	ds_read_b64_tr_b16 v[192:193], v176 offset:34816
	ds_read_b64_tr_b16 v[200:201], v176 offset:34848
	ds_read_b64_tr_b16 v[212:213], v176 offset:34880
	ds_read_b64_tr_b16 v[214:215], v176 offset:39232
	s_waitcnt lgkmcnt(13)
	v_mfma_f32_16x16x32_bf16 v[226:229], v[24:27], v[20:23], 0
	s_waitcnt lgkmcnt(5)
	v_lshlrev_b32_e32 v0, 16, v196
	v_and_b32_e32 v1, 0xffff0000, v196
	v_pk_mul_f32 v[0:1], v[150:151], v[0:1]
	v_mfma_f32_16x16x32_bf16 v[234:237], v[24:27], v[16:19], 0
	v_lshlrev_b32_e32 v24, 16, v197
	v_and_b32_e32 v25, 0xffff0000, v197
	v_pk_mul_f32 v[24:25], v[152:153], v[24:25]
	v_mfma_f32_16x16x32_bf16 v[238:241], v[44:47], v[16:19], 0
	s_waitcnt lgkmcnt(4)
	v_lshlrev_b32_e32 v16, 16, v198
	v_and_b32_e32 v17, 0xffff0000, v198
	v_lshlrev_b32_e32 v18, 16, v199
	v_and_b32_e32 v19, 0xffff0000, v199
	v_mfma_f32_16x16x32_bf16 v[242:245], v[44:47], v[20:23], 0
	ds_read_b64_tr_b16 v[202:203], v176 offset:39200
	ds_read_b64_tr_b16 v[230:231], v176 offset:35040
	v_cvt_pk_bf16_f32 v57, v222, v223
	v_cvt_pk_bf16_f32 v58, v216, v217
	v_mfma_f32_16x16x32_bf16 v[188:191], v[188:191], v[20:23], 0
	v_mul_f32_e64 v20, v154, v16
	v_mul_f32_e64 v21, v155, v17
	v_pk_mul_f32 v[22:23], v[156:157], v[18:19]
	v_cvt_pk_bf16_f32 v16, v0, v1
	v_cvt_pk_bf16_f32 v17, v24, v25
	v_cvt_pk_bf16_f32 v18, v20, v21
	v_cvt_pk_bf16_f32 v19, v22, v23
	ds_read_b64_tr_b16 v[22:23], v176 offset:39264
	ds_read_b64_tr_b16 v[20:21], v176 offset:34912
	ds_read_b64_tr_b16 v[24:25], v176 offset:34944
	s_waitcnt lgkmcnt(8)
	v_mfma_f32_16x16x32_bf16 v[44:47], v[192:195], v[16:19], v[28:31]
	ds_read_b64_tr_b16 v[192:193], v176 offset:34976
	ds_read_b64_tr_b16 v[26:27], v176 offset:39296
	ds_read_b64_tr_b16 v[194:195], v176 offset:39328
	ds_read_b64_tr_b16 v[232:233], v176 offset:39392
	v_cvt_pk_bf16_f32 v59, v218, v219
	s_waitcnt lgkmcnt(9)
	v_mfma_f32_16x16x32_bf16 v[36:39], v[212:215], v[16:19], v[36:39]
	ds_read_b64_tr_b16 v[212:213], v176 offset:35008
	ds_read_b64_tr_b16 v[214:215], v176 offset:39360
	s_waitcnt lgkmcnt(10)
	v_mfma_f32_16x16x32_bf16 v[40:43], v[200:203], v[16:19], v[40:43]
	v_mul_f32_e64 v202, v158, v218
	v_mul_f32_e64 v203, v159, v219
	v_pk_mul_f32 v[200:201], v[164:165], v[216:217]
	ds_read_b64 v[216:217], v183 offset:1664
	ds_read_b64 v[218:219], v183 offset:1696
	s_waitcnt lgkmcnt(9)
	v_mfma_f32_16x16x32_bf16 v[32:35], v[20:23], v[16:19], v[32:35]
	v_mul_f32_e64 v22, v158, v210
	v_mul_f32_e64 v23, v159, v211
	v_pk_mul_f32 v[20:21], v[164:165], v[208:209]
	s_waitcnt lgkmcnt(6)
	v_mfma_f32_16x16x32_bf16 v[28:31], v[24:27], v[16:19], v[48:51]
	s_waitcnt lgkmcnt(5)
	v_mfma_f32_16x16x32_bf16 v[24:27], v[192:195], v[16:19], v[200:203]
	ds_read_b64 v[192:193], v185 offset:64
	ds_read_b64 v[194:195], v185 offset:96
	v_pk_mul_f32 v[50:51], v[158:159], v[206:207]
	v_pk_mul_f32 v[48:49], v[164:165], v[204:205]
	s_waitcnt lgkmcnt(4)
	v_mfma_f32_16x16x32_bf16 v[20:23], v[212:215], v[16:19], v[20:23]
	ds_read_b64 v[212:213], v186 offset:320
	ds_read_b64 v[214:215], v186 offset:352
	v_cvt_pk_bf16_f32 v202, v204, v205
	v_cvt_pk_bf16_f32 v203, v206, v207
	v_mfma_f32_16x16x32_bf16 v[16:19], v[230:233], v[16:19], v[48:51]
	ds_read_b64 v[204:205], v183 offset:1728
	ds_read_b64 v[206:207], v183 offset:1760
	v_cvt_pk_bf16_f32 v200, v208, v209
	v_cvt_pk_bf16_f32 v201, v210, v211
	ds_read_b64 v[48:49], v183 offset:1600
	ds_read_b64 v[50:51], v183 offset:1632
	v_mfma_f32_16x16x32_bf16 v[226:229], v[52:55], v[60:63], v[226:229]
	s_waitcnt lgkmcnt(0)
	v_mfma_f32_16x16x32_bf16 v[52:55], v[52:55], v[48:51], v[234:237]
	v_mfma_f32_16x16x32_bf16 v[48:51], v[192:195], v[48:51], v[238:241]
	v_mfma_f32_16x16x32_bf16 v[192:195], v[192:195], v[60:63], v[242:245]
	v_mfma_f32_16x16x32_bf16 v[60:63], v[212:215], v[60:63], v[188:191]
	s_nop 2
	ds_read_b64 v[188:189], v184 offset:1920
	ds_read_b64 v[190:191], v184 offset:1952
	s_waitcnt lgkmcnt(0)
	v_mfma_f32_16x16x32_bf16 v[212:215], v[56:59], v[188:191], v[226:229]
	v_mfma_f32_16x16x32_bf16 v[52:55], v[56:59], v[216:219], v[52:55]
	ds_read_b64 v[56:57], v185 offset:128
	ds_read_b64 v[58:59], v185 offset:160
	s_waitcnt lgkmcnt(0)
	v_mfma_f32_16x16x32_bf16 v[48:51], v[56:59], v[216:219], v[48:51]
	v_mfma_f32_16x16x32_bf16 v[56:59], v[56:59], v[188:191], v[192:195]
	s_nop 2
	ds_read_b64 v[192:193], v186 offset:384
	ds_read_b64 v[194:195], v186 offset:416
	s_waitcnt lgkmcnt(0)
	v_mfma_f32_16x16x32_bf16 v[60:63], v[192:195], v[188:191], v[60:63]
	ds_read_b64 v[188:189], v184 offset:1984
	ds_read_b64 v[190:191], v184 offset:2016
	ds_read_b64 v[182:183], v185 offset:192
	ds_read_b64 v[184:185], v185 offset:224
	s_waitcnt lgkmcnt(0)
	v_mfma_f32_16x16x32_bf16 v[48:51], v[182:185], v[204:207], v[48:51]
	s_nop 7
	v_pk_mul_f32 v[50:51], v[146:147], v[50:51]
	v_mfma_f32_16x16x32_bf16 v[56:59], v[182:185], v[188:191], v[56:59]
	ds_read_b64 v[182:183], v186 offset:448
	ds_read_b64 v[184:185], v186 offset:480
	v_pk_mul_f32 v[0:1], v[142:143], v[48:49]
	s_waitcnt lgkmcnt(0)
	v_mfma_f32_16x16x32_bf16 v[60:63], v[182:185], v[188:191], v[60:63]
	s_nop 3
	v_mul_f32_e64 v182, v148, v58
	v_mul_f32_e64 v183, v149, v59
	v_pk_mul_f32 v[48:49], v[144:145], v[56:57]
	v_cvt_pk_bf16_f32 v0, v0, v1
	v_pk_mul_f32 v[62:63], v[146:147], v[62:63]
	v_pk_mul_f32 v[60:61], v[142:143], v[60:61]
	v_cvt_pk_bf16_f32 v1, v50, v51
	v_cvt_pk_bf16_f32 v48, v48, v49
	v_cvt_pk_bf16_f32 v49, v182, v183
	v_cvt_pk_bf16_f32 v50, v60, v61
	v_cvt_pk_bf16_f32 v51, v62, v63
	v_mfma_f32_16x16x32_bf16 v[192:195], v[200:203], v[188:191], v[212:215]
	v_mfma_f32_16x16x32_bf16 v[52:55], v[200:203], v[204:207], v[52:55]
	v_lshl_add_u64 v[200:201], v[170:171], 0, v[246:247]
	v_lshl_add_u64 v[202:203], v[170:171], 0, v[248:249]
	v_mfma_f32_16x16x32_bf16 v[56:59], v[196:199], v[0:3], 0
	v_mfma_f32_16x16x32_bf16 v[48:51], v[196:199], v[48:51], 0
	s_nop 6
	v_fma_f32 v52, v162, v52, v56
	v_fma_f32 v53, v163, v53, v57
	v_pk_fma_f32 v[0:1], v[166:167], v[194:195], v[50:51]
	v_pk_fma_f32 v[50:51], v[168:169], v[54:55], v[58:59]
	v_pk_fma_f32 v[48:49], v[160:161], v[192:193], v[48:49]
	v_cvt_pk_bf16_f32 v52, v52, v53
	v_cvt_pk_bf16_f32 v53, v50, v51
	v_cvt_pk_bf16_f32 v48, v48, v49
	v_cvt_pk_bf16_f32 v49, v0, v1
	global_store_dwordx2 v[200:201], v[52:53], off sc1
	global_store_dwordx2 v[202:203], v[48:49], off sc1
	s_cbranch_scc0 .LBB0_1370
	s_andn2_b64 vcc, exec, s[6:7]
	s_cbranch_vccnz .LBB0_1354
	s_add_u32 s0, s28, s14
	s_addc_u32 s1, s29, s15
	v_lshl_add_u64 v[0:1], v[112:113], 2, s[0:1]
	s_waitcnt vmcnt(2)
	v_lshl_add_u64 v[4:5], v[0:1], 0, v[76:77]
	global_store_dword v[4:5], v44, off nt
	v_lshl_add_u64 v[4:5], v[0:1], 0, v[78:79]
	global_store_dword v[4:5], v45, off nt
	v_lshl_add_u64 v[4:5], v[0:1], 0, v[80:81]
	global_store_dword v[4:5], v46, off nt
	v_lshl_add_u64 v[4:5], v[0:1], 0, v[82:83]
	global_store_dword v[4:5], v47, off nt
	v_lshl_add_u64 v[4:5], v[0:1], 0, v[84:85]
	global_store_dword v[4:5], v40, off nt
	v_lshl_add_u64 v[4:5], v[0:1], 0, v[86:87]
	global_store_dword v[4:5], v41, off nt
	v_lshl_add_u64 v[4:5], v[0:1], 0, v[88:89]
	global_store_dword v[4:5], v42, off nt
	v_lshl_add_u64 v[4:5], v[0:1], 0, v[90:91]
	global_store_dword v[4:5], v43, off nt
	v_lshl_add_u64 v[4:5], v[0:1], 0, v[92:93]
	global_store_dword v[4:5], v36, off nt
	v_lshl_add_u64 v[4:5], v[0:1], 0, v[94:95]
	global_store_dword v[4:5], v37, off nt
	v_lshl_add_u64 v[4:5], v[0:1], 0, v[96:97]
	global_store_dword v[4:5], v38, off nt
	v_lshl_add_u64 v[4:5], v[0:1], 0, v[98:99]
	global_store_dword v[4:5], v39, off nt
	v_lshl_add_u64 v[4:5], v[0:1], 0, v[100:101]
	global_store_dword v[4:5], v32, off nt
	v_lshl_add_u64 v[4:5], v[0:1], 0, v[102:103]
	global_store_dword v[4:5], v33, off nt
	v_lshl_add_u64 v[4:5], v[0:1], 0, v[104:105]
	global_store_dword v[4:5], v34, off nt
	v_lshl_add_u64 v[4:5], v[0:1], 0, v[106:107]
	global_store_dword v[4:5], v35, off nt
	v_lshl_add_u64 v[4:5], v[0:1], 0, v[108:109]
	global_store_dword v[4:5], v28, off nt
	v_lshl_add_u64 v[4:5], v[0:1], 0, v[110:111]
	global_store_dword v[4:5], v29, off nt
	v_lshl_add_u64 v[4:5], v[0:1], 0, v[138:139]
	global_store_dword v[4:5], v30, off nt
	v_lshl_add_u64 v[4:5], v[0:1], 0, v[136:137]
	global_store_dword v[4:5], v31, off nt
	v_lshl_add_u64 v[4:5], v[0:1], 0, v[134:135]
	global_store_dword v[4:5], v24, off nt
	v_lshl_add_u64 v[4:5], v[0:1], 0, v[132:133]
	global_store_dword v[4:5], v25, off nt
	v_lshl_add_u64 v[4:5], v[0:1], 0, v[130:131]
	global_store_dword v[4:5], v26, off nt
	v_lshl_add_u64 v[4:5], v[0:1], 0, v[128:129]
	global_store_dword v[4:5], v27, off nt
	v_lshl_add_u64 v[4:5], v[0:1], 0, v[126:127]
	global_store_dword v[4:5], v20, off nt
	v_lshl_add_u64 v[4:5], v[0:1], 0, v[124:125]
	global_store_dword v[4:5], v21, off nt
	v_lshl_add_u64 v[4:5], v[0:1], 0, v[122:123]
	global_store_dword v[4:5], v22, off nt
	v_lshl_add_u64 v[4:5], v[0:1], 0, v[120:121]
	global_store_dword v[4:5], v23, off nt
	v_lshl_add_u64 v[4:5], v[0:1], 0, v[118:119]
	global_store_dword v[4:5], v16, off nt
	v_lshl_add_u64 v[4:5], v[0:1], 0, v[116:117]
	global_store_dword v[4:5], v17, off nt
	v_lshl_add_u64 v[4:5], v[0:1], 0, v[114:115]
	v_lshl_add_u64 v[0:1], v[0:1], 0, v[140:141]
	global_store_dword v[4:5], v18, off nt
	global_store_dword v[0:1], v19, off nt
	s_branch .LBB0_1354

.LBB0_1429:
	v_ashrrev_i32_e32 v17, 31, v16
	v_lshlrev_b64 v[18:19], 13, v[16:17]
	v_lshl_add_u64 v[18:19], s[60:61], 0, v[18:19]
	v_lshl_add_u64 v[18:19], v[18:19], 0, v[148:149]
	v_lshlrev_b64 v[168:169], 11, v[16:17]
	v_lshl_add_u64 v[20:21], v[18:19], 0, s[6:7]
	v_lshl_add_u64 v[22:23], v[152:153], 0, v[168:169]
	s_waitcnt vmcnt(3)
	v_lshl_add_u64 v[24:25], v[154:155], 0, v[168:169]
	v_add_co_u32_e32 v18, vcc, s19, v18
	global_load_dwordx4 v[180:183], v[22:23], off offset:16
	global_load_dwordx4 v[140:143], v[24:25], off
	v_addc_co_u32_e32 v19, vcc, 0, v19, vcc
	global_load_dwordx4 v[184:187], v[24:25], off offset:16
	global_load_dwordx4 v[136:139], v[18:19], off offset:2048
	global_load_dwordx4 v[144:147], v[22:23], off
	global_load_dwordx4 v[188:191], v[20:21], off offset:16
	v_add_u32_e32 v166, s33, v16
	v_min_i32_e32 v18, 0x2fff, v166
	v_ashrrev_i32_e32 v19, 31, v18
	v_lshlrev_b64 v[20:21], 13, v[18:19]
	v_lshl_add_u64 v[20:21], s[60:61], 0, v[20:21]
	v_lshl_add_u64 v[20:21], v[20:21], 0, v[148:149]
	v_lshlrev_b64 v[18:19], 11, v[18:19]
	v_lshl_add_u64 v[22:23], v[20:21], 0, s[6:7]
	v_lshl_add_u64 v[24:25], v[152:153], 0, v[18:19]
	v_lshl_add_u64 v[18:19], v[154:155], 0, v[18:19]
	v_add_co_u32_e32 v20, vcc, s19, v20
	v_add_u32_e32 v164, s16, v16
	global_load_dwordx4 v[124:127], v[24:25], off offset:16
	global_load_dwordx4 v[116:119], v[18:19], off
	v_addc_co_u32_e32 v21, vcc, 0, v21, vcc
	global_load_dwordx4 v[128:131], v[18:19], off offset:16
	global_load_dwordx4 v[112:115], v[20:21], off offset:2048
	global_load_dwordx4 v[120:123], v[24:25], off
	global_load_dwordx4 v[132:135], v[22:23], off offset:16
	v_min_i32_e32 v18, 0x2fff, v164
	v_ashrrev_i32_e32 v19, 31, v18
	v_lshlrev_b64 v[20:21], 13, v[18:19]
	v_lshl_add_u64 v[20:21], s[60:61], 0, v[20:21]
	v_lshl_add_u64 v[20:21], v[20:21], 0, v[148:149]
	v_lshlrev_b64 v[18:19], 11, v[18:19]
	v_lshl_add_u64 v[22:23], v[20:21], 0, s[6:7]
	v_lshl_add_u64 v[24:25], v[152:153], 0, v[18:19]
	v_lshl_add_u64 v[18:19], v[154:155], 0, v[18:19]
	v_add_co_u32_e32 v20, vcc, s19, v20
	v_add_u32_e32 v162, s71, v16
	global_load_dwordx4 v[100:103], v[24:25], off offset:16
	global_load_dwordx4 v[92:95], v[18:19], off
	v_addc_co_u32_e32 v21, vcc, 0, v21, vcc
	global_load_dwordx4 v[104:107], v[18:19], off offset:16
	global_load_dwordx4 v[88:91], v[20:21], off offset:2048
	global_load_dwordx4 v[96:99], v[24:25], off
	global_load_dwordx4 v[108:111], v[22:23], off offset:16
	v_min_i32_e32 v18, 0x2fff, v162
	v_ashrrev_i32_e32 v19, 31, v18
	v_lshlrev_b64 v[20:21], 13, v[18:19]
	v_lshl_add_u64 v[20:21], s[60:61], 0, v[20:21]
	v_lshl_add_u64 v[20:21], v[20:21], 0, v[148:149]
	v_lshlrev_b64 v[18:19], 11, v[18:19]
	v_lshl_add_u64 v[22:23], v[20:21], 0, s[6:7]
	v_lshl_add_u64 v[24:25], v[152:153], 0, v[18:19]
	v_lshl_add_u64 v[18:19], v[154:155], 0, v[18:19]
	v_add_co_u32_e32 v20, vcc, s19, v20
	v_add_u32_e32 v160, s17, v16
	global_load_dwordx4 v[76:79], v[24:25], off offset:16
	global_load_dwordx4 v[68:71], v[18:19], off
	v_addc_co_u32_e32 v21, vcc, 0, v21, vcc
	global_load_dwordx4 v[80:83], v[18:19], off offset:16
	global_load_dwordx4 v[64:67], v[20:21], off offset:2048
	global_load_dwordx4 v[72:75], v[24:25], off
	global_load_dwordx4 v[84:87], v[22:23], off offset:16
	v_min_i32_e32 v18, 0x2fff, v160
	v_ashrrev_i32_e32 v19, 31, v18
	v_lshlrev_b64 v[20:21], 13, v[18:19]
	v_lshl_add_u64 v[20:21], s[60:61], 0, v[20:21]
	v_add_u32_e32 v158, s72, v16
	v_lshl_add_u64 v[20:21], v[20:21], 0, v[148:149]
	v_lshlrev_b64 v[18:19], 11, v[18:19]
	v_min_i32_e32 v16, 0x2fff, v158
	v_lshl_add_u64 v[22:23], v[20:21], 0, s[6:7]
	v_lshl_add_u64 v[24:25], v[152:153], 0, v[18:19]
	v_lshl_add_u64 v[18:19], v[154:155], 0, v[18:19]
	v_add_co_u32_e32 v20, vcc, s19, v20
	v_ashrrev_i32_e32 v17, 31, v16
	global_load_dwordx4 v[56:59], v[24:25], off offset:16
	global_load_dwordx4 v[44:47], v[18:19], off
	v_addc_co_u32_e32 v21, vcc, 0, v21, vcc
	global_load_dwordx4 v[52:55], v[18:19], off offset:16
	global_load_dwordx4 v[40:43], v[20:21], off offset:2048
	global_load_dwordx4 v[48:51], v[24:25], off
	global_load_dwordx4 v[60:63], v[22:23], off offset:16
	v_lshlrev_b64 v[18:19], 13, v[16:17]
	v_lshl_add_u64 v[18:19], s[60:61], 0, v[18:19]
	v_lshl_add_u64 v[18:19], v[18:19], 0, v[148:149]
	s_waitcnt vmcnt(32)
	v_lshl_add_u64 v[36:37], v[18:19], 0, s[6:7]
	v_lshlrev_b64 v[16:17], 11, v[16:17]
	v_add_co_u32_e32 v18, vcc, s19, v18
	v_lshl_add_u64 v[24:25], v[152:153], 0, v[16:17]
	s_waitcnt vmcnt(29)
	v_lshlrev_b32_e32 v175, 16, v183
	s_waitcnt vmcnt(27)
	v_lshlrev_b32_e32 v173, 16, v187
	v_and_b32_e32 v172, 0xffff0000, v187
	v_and_b32_e32 v174, 0xffff0000, v183
	s_waitcnt vmcnt(24)
	v_and_b32_e32 v170, 0xffff0000, v191
	v_lshlrev_b32_e32 v3, 16, v191
	v_pk_add_f32 v[172:173], v[172:173], v[174:175]
	v_lshlrev_b32_e32 v174, 16, v190
	v_and_b32_e32 v175, 0xffff0000, v190
	v_lshlrev_b32_e32 v190, 16, v186
	v_and_b32_e32 v191, 0xffff0000, v186
	v_lshlrev_b32_e32 v186, 16, v182
	v_and_b32_e32 v187, 0xffff0000, v182
	v_pk_add_f32 v[182:183], v[186:187], v[190:191]
	v_lshlrev_b32_e32 v190, 16, v189
	v_and_b32_e32 v191, 0xffff0000, v189
	v_mul_f32_e32 v156, 0xbfb8aa3b, v190
	v_exp_f32_e32 v156, v156
	v_mul_f32_e32 v159, 0xbfb8aa3b, v191
	v_exp_f32_e32 v159, v159
	v_lshl_add_u64 v[16:17], v[154:155], 0, v[16:17]
	v_add_f32_e32 v156, 1.0, v156
	v_rcp_f32_e32 v198, v156
	v_add_f32_e32 v156, 1.0, v159
	v_rcp_f32_e32 v199, v156
	v_addc_co_u32_e32 v19, vcc, 0, v19, vcc
	global_load_dwordx4 v[32:35], v[24:25], off offset:16
	global_load_dwordx4 v[20:23], v[16:17], off
	v_pk_mul_f32 v[190:191], v[198:199], v[190:191]
	v_lshlrev_b32_e32 v198, 16, v188
	v_and_b32_e32 v199, 0xffff0000, v188
	v_mul_f32_e32 v156, 0xbfb8aa3b, v198
	v_exp_f32_e32 v156, v156
	v_mul_f32_e32 v159, 0xbfb8aa3b, v199
	v_exp_f32_e32 v159, v159
	global_load_dwordx4 v[28:31], v[16:17], off offset:16
	s_nop 0
	global_load_dwordx4 v[16:19], v[18:19], off offset:2048
	s_nop 0
	global_load_dwordx4 v[24:27], v[24:25], off
	s_nop 0
	global_load_dwordx4 v[36:39], v[36:37], off offset:16
	v_add_f32_e32 v156, 1.0, v156
	v_rcp_f32_e32 v200, v156
	v_add_f32_e32 v156, 1.0, v159
	v_rcp_f32_e32 v201, v156
	v_lshlrev_b32_e32 v194, 16, v185
	v_and_b32_e32 v195, 0xffff0000, v185
	v_lshlrev_b32_e32 v188, 16, v184
	v_and_b32_e32 v189, 0xffff0000, v184
	v_lshlrev_b32_e32 v184, 16, v180
	v_and_b32_e32 v185, 0xffff0000, v180
	v_lshlrev_b32_e32 v196, 16, v181
	v_and_b32_e32 v197, 0xffff0000, v181
	v_pk_add_f32 v[180:181], v[184:185], v[188:189]
	v_pk_mul_f32 v[188:189], v[200:201], v[198:199]
	v_lshlrev_b32_e32 v198, 16, v139
	v_and_b32_e32 v199, 0xffff0000, v139
	v_mul_f32_e32 v139, 0xbfb8aa3b, v198
	v_lshlrev_b32_e32 v200, 16, v143
	v_and_b32_e32 v201, 0xffff0000, v143
	v_exp_f32_e32 v139, v139
	v_mul_f32_e32 v143, 0xbfb8aa3b, v199
	v_exp_f32_e32 v143, v143
	v_lshlrev_b32_e32 v208, 16, v141
	v_add_f32_e32 v139, 1.0, v139
	v_rcp_f32_e32 v204, v139
	v_add_f32_e32 v139, 1.0, v143
	v_rcp_f32_e32 v205, v139
	v_and_b32_e32 v209, 0xffff0000, v141
	v_lshlrev_b32_e32 v214, 16, v140
	v_and_b32_e32 v215, 0xffff0000, v140
	v_lshlrev_b32_e32 v140, 16, v144
	v_and_b32_e32 v141, 0xffff0000, v144
	v_lshlrev_b32_e32 v210, 16, v145
	v_and_b32_e32 v211, 0xffff0000, v145
	v_pk_add_f32 v[140:141], v[140:141], v[214:215]
	v_pk_mul_f32 v[198:199], v[204:205], v[198:199]
	v_lshlrev_b32_e32 v204, 16, v138
	v_and_b32_e32 v205, 0xffff0000, v138
	v_lshlrev_b32_e32 v138, 16, v142
	v_and_b32_e32 v139, 0xffff0000, v142
	v_lshlrev_b32_e32 v142, 16, v146
	v_and_b32_e32 v143, 0xffff0000, v146
	v_pk_add_f32 v[208:209], v[210:211], v[208:209]
	v_pk_mul_f32 v[144:145], v[140:141], v[140:141]
	v_pk_add_f32 v[138:139], v[142:143], v[138:139]
	v_mul_f32_e32 v142, 0xbfb8aa3b, v204
	v_pk_mul_f32 v[210:211], v[208:209], v[208:209]
	v_add_f32_e32 v144, v144, v145
	v_exp_f32_e32 v146, v142
	v_mul_f32_e32 v142, 0xbfb8aa3b, v205
	v_add_f32_e32 v144, v210, v144
	v_lshlrev_b32_e32 v202, 16, v147
	v_and_b32_e32 v203, 0xffff0000, v147
	v_exp_f32_e32 v147, v142
	v_pk_mul_f32 v[142:143], v[138:139], v[138:139]
	v_add_f32_e32 v144, v211, v144
	v_pk_add_f32 v[200:201], v[202:203], v[200:201]
	v_add_f32_e32 v142, v142, v144
	v_pk_mul_f32 v[202:203], v[200:201], v[200:201]
	v_add_f32_e32 v142, v143, v142
	v_add_f32_e32 v142, v202, v142
	v_pk_mul_f32 v[184:185], v[180:181], v[180:181]
	v_add_f32_e32 v142, v203, v142
	v_pk_add_f32 v[194:195], v[196:197], v[194:195]
	v_add_f32_e32 v142, v184, v142
	v_pk_mul_f32 v[196:197], v[194:195], v[194:195]
	v_lshlrev_b32_e32 v206, 16, v137
	v_add_f32_e32 v142, v185, v142
	v_and_b32_e32 v207, 0xffff0000, v137
	v_mul_f32_e32 v137, 0xbfb8aa3b, v206
	v_add_f32_e32 v142, v196, v142
	v_pk_mul_f32 v[186:187], v[182:183], v[182:183]
	v_exp_f32_e32 v137, v137
	v_add_f32_e32 v142, v197, v142
	v_add_f32_e32 v142, v186, v142
	v_pk_mul_f32 v[192:193], v[172:173], v[172:173]
	v_add_f32_e32 v142, v187, v142
	v_add_f32_e32 v142, v193, v142
	v_add_f32_e32 v137, 1.0, v137
	v_add_f32_e32 v144, v192, v142
	v_rcp_f32_e32 v212, v137
	v_mul_f32_e32 v137, 0xbfb8aa3b, v207
	ds_bpermute_b32 v145, v177, v144
	v_exp_f32_e32 v137, v137
	v_lshlrev_b32_e32 v142, 16, v136
	v_and_b32_e32 v143, 0xffff0000, v136
	v_add_f32_e32 v146, 1.0, v146
	v_add_f32_e32 v137, 1.0, v137
	s_waitcnt lgkmcnt(0)
	v_add_f32_e32 v136, v144, v145
	v_rcp_f32_e32 v213, v137
	ds_bpermute_b32 v137, v178, v136
	v_mul_f32_e32 v144, 0xbfb8aa3b, v142
	v_exp_f32_e32 v144, v144
	v_mul_f32_e32 v145, 0xbfb8aa3b, v143
	v_exp_f32_e32 v145, v145
	s_waitcnt lgkmcnt(0)
	v_add_f32_e32 v156, v136, v137
	ds_bpermute_b32 v159, v179, v156
	v_add_f32_e32 v136, 1.0, v144
	v_add_f32_e32 v137, 1.0, v145
	v_rcp_f32_e32 v136, v136
	v_rcp_f32_e32 v137, v137
	s_waitcnt lgkmcnt(0)
	v_add_f32_e32 v144, v156, v159
	v_fmamk_f32 v144, v144, 0x3c000000, v176
	v_mul_f32_e32 v145, 0x4b800000, v144
	v_cmp_gt_f32_e32 vcc, s29, v144
	v_add_f32_e32 v147, 1.0, v147
	v_pk_mul_f32 v[136:137], v[136:137], v[142:143]
	v_cndmask_b32_e32 v144, v144, v145, vcc
	v_rsq_f32_e32 v156, v144
	v_rcp_f32_e32 v146, v146
	v_rcp_f32_e32 v147, v147
	v_mul_f32_e32 v142, 0x45800000, v156
	v_cndmask_b32_e32 v142, v156, v142, vcc
	v_pk_mul_f32 v[140:141], v[140:141], v[142:143] op_sel_hi:[1,0]
	v_pk_mul_f32 v[138:139], v[138:139], v[142:143] op_sel_hi:[1,0]
	v_pk_mul_f32 v[140:141], v[12:13], v[140:141]
	v_pk_mul_f32 v[144:145], v[146:147], v[204:205]
	v_pk_mul_f32 v[136:137], v[136:137], v[140:141]
	v_pk_mul_f32 v[140:141], v[208:209], v[142:143] op_sel_hi:[1,0]
	v_pk_mul_f32 v[146:147], v[212:213], v[206:207]
	v_pk_mul_f32 v[140:141], v[14:15], v[140:141]
	v_pk_mul_f32 v[138:139], v[8:9], v[138:139]
	v_pk_mul_f32 v[140:141], v[146:147], v[140:141]
	v_pk_mul_f32 v[138:139], v[144:145], v[138:139]
	v_pk_mul_f32 v[144:145], v[200:201], v[142:143] op_sel_hi:[1,0]
	v_pk_mul_f32 v[146:147], v[180:181], v[142:143] op_sel_hi:[1,0]
	v_pk_mul_f32 v[180:181], v[194:195], v[142:143] op_sel_hi:[1,0]
	v_mul_f32_e32 v143, 0xbfb8aa3b, v174
	v_exp_f32_e32 v143, v143
	v_mul_f32_e32 v156, 0xbfb8aa3b, v175
	v_exp_f32_e32 v156, v156
	v_mul_f32_e32 v171, v172, v142
	v_add_f32_e32 v143, 1.0, v143
	v_rcp_f32_e32 v184, v143
	v_add_f32_e32 v143, 1.0, v156
	v_rcp_f32_e32 v185, v143
	v_pk_mul_f32 v[182:183], v[182:183], v[142:143] op_sel_hi:[1,0]
	v_mul_f32_e32 v143, 0xbfb8aa3b, v3
	v_mul_f32_e32 v156, 0xbfb8aa3b, v170
	v_exp_f32_e32 v143, v143
	v_exp_f32_e32 v156, v156
	v_pk_mul_f32 v[144:145], v[10:11], v[144:145]
	v_pk_mul_f32 v[182:183], v[0:1], v[182:183]
	v_add_f32_e32 v143, 1.0, v143
	v_add_f32_e32 v156, 1.0, v156
	v_rcp_f32_e32 v143, v143
	v_rcp_f32_e32 v156, v156
	v_pk_mul_f32 v[174:175], v[184:185], v[174:175]
	v_mul_f32_e32 v159, v173, v142
	v_mul_f32_e32 v184, v143, v3
	v_pk_mul_f32 v[142:143], v[156:157], v[170:171]
	v_pk_mul_f32 v[144:145], v[198:199], v[144:145]
	v_pk_mul_f32 v[146:147], v[4:5], v[146:147]
	v_pk_mul_f32 v[180:181], v[6:7], v[180:181]
	v_pk_mul_f32 v[174:175], v[174:175], v[182:183]
	v_mul_f32_e32 v182, v2, v159
	v_mov_b32_e32 v185, v142
	v_mov_b32_e32 v183, v143
	v_pk_mul_f32 v[146:147], v[188:189], v[146:147]
	v_pk_mul_f32 v[180:181], v[190:191], v[180:181]
	v_cvt_pk_bf16_f32 v136, v136, v137
	v_cvt_pk_bf16_f32 v137, v140, v141
	v_cvt_pk_bf16_f32 v138, v138, v139
	v_cvt_pk_bf16_f32 v139, v144, v145
	v_lshl_add_u64 v[140:141], v[150:151], 0, v[168:169]
	v_pk_mul_f32 v[142:143], v[184:185], v[182:183]
	global_store_dwordx4 v[140:141], v[136:139], off sc1
	v_cmp_gt_i32_e32 vcc, s3, v166
	s_nop 0
	v_cvt_pk_bf16_f32 v136, v146, v147
	v_cvt_pk_bf16_f32 v137, v180, v181
	v_cvt_pk_bf16_f32 v138, v174, v175
	v_cvt_pk_bf16_f32 v139, v142, v143
	global_store_dwordx4 v[140:141], v[136:139], off offset:16 sc1
	s_and_saveexec_b64 s[14:15], vcc
	s_cbranch_execz .LBB0_1431
	s_waitcnt vmcnt(29)
	v_lshlrev_b32_e32 v139, 16, v131
	v_lshlrev_b32_e32 v141, 16, v127
	v_and_b32_e32 v138, 0xffff0000, v131
	v_and_b32_e32 v140, 0xffff0000, v127
	s_waitcnt vmcnt(26)
	v_and_b32_e32 v136, 0xffff0000, v135
	v_lshlrev_b32_e32 v3, 16, v135
	v_pk_add_f32 v[138:139], v[138:139], v[140:141]
	v_lshlrev_b32_e32 v140, 16, v134
	v_and_b32_e32 v141, 0xffff0000, v134
	v_lshlrev_b32_e32 v134, 16, v130
	v_and_b32_e32 v135, 0xffff0000, v130
	v_lshlrev_b32_e32 v130, 16, v126
	v_and_b32_e32 v131, 0xffff0000, v126
	v_pk_add_f32 v[126:127], v[130:131], v[134:135]
	v_lshlrev_b32_e32 v134, 16, v133
	v_and_b32_e32 v135, 0xffff0000, v133
	v_lshlrev_b32_e32 v144, 16, v129
	v_and_b32_e32 v145, 0xffff0000, v129
	v_mul_f32_e32 v129, 0xbfb8aa3b, v134
	v_exp_f32_e32 v129, v129
	v_mul_f32_e32 v133, 0xbfb8aa3b, v135
	v_exp_f32_e32 v133, v133
	v_lshlrev_b32_e32 v146, 16, v125
	v_add_f32_e32 v129, 1.0, v129
	v_rcp_f32_e32 v168, v129
	v_add_f32_e32 v129, 1.0, v133
	v_rcp_f32_e32 v169, v129
	v_and_b32_e32 v147, 0xffff0000, v125
	v_and_b32_e32 v133, 0xffff0000, v128
	v_lshlrev_b32_e32 v182, 16, v117
	v_pk_mul_f32 v[134:135], v[168:169], v[134:135]
	v_lshlrev_b32_e32 v168, 16, v132
	v_and_b32_e32 v169, 0xffff0000, v132
	v_mul_f32_e32 v125, 0xbfb8aa3b, v168
	v_lshlrev_b32_e32 v132, 16, v128
	v_exp_f32_e32 v125, v125
	v_mul_f32_e32 v128, 0xbfb8aa3b, v169
	v_exp_f32_e32 v129, v128
	v_lshlrev_b32_e32 v128, 16, v124
	v_add_f32_e32 v125, 1.0, v125
	v_rcp_f32_e32 v170, v125
	v_add_f32_e32 v125, 1.0, v129
	v_rcp_f32_e32 v171, v125
	v_and_b32_e32 v129, 0xffff0000, v124
	v_pk_add_f32 v[124:125], v[128:129], v[132:133]
	v_and_b32_e32 v183, 0xffff0000, v117
	v_pk_mul_f32 v[132:133], v[170:171], v[168:169]
	v_lshlrev_b32_e32 v168, 16, v115
	v_and_b32_e32 v169, 0xffff0000, v115
	v_mul_f32_e32 v115, 0xbfb8aa3b, v168
	v_lshlrev_b32_e32 v170, 16, v119
	v_and_b32_e32 v171, 0xffff0000, v119
	v_exp_f32_e32 v115, v115
	v_mul_f32_e32 v119, 0xbfb8aa3b, v169
	v_exp_f32_e32 v119, v119
	v_lshlrev_b32_e32 v188, 16, v116
	v_add_f32_e32 v115, 1.0, v115
	v_rcp_f32_e32 v174, v115
	v_add_f32_e32 v115, 1.0, v119
	v_rcp_f32_e32 v175, v115
	v_and_b32_e32 v189, 0xffff0000, v116
	v_lshlrev_b32_e32 v116, 16, v120
	v_and_b32_e32 v117, 0xffff0000, v120
	v_lshlrev_b32_e32 v184, 16, v121
	v_and_b32_e32 v185, 0xffff0000, v121
	v_pk_add_f32 v[116:117], v[116:117], v[188:189]
	v_pk_mul_f32 v[168:169], v[174:175], v[168:169]
	v_lshlrev_b32_e32 v174, 16, v114
	v_and_b32_e32 v175, 0xffff0000, v114
	v_lshlrev_b32_e32 v114, 16, v118
	v_and_b32_e32 v115, 0xffff0000, v118
	v_lshlrev_b32_e32 v118, 16, v122
	v_and_b32_e32 v119, 0xffff0000, v122
	v_pk_add_f32 v[182:183], v[184:185], v[182:183]
	v_pk_mul_f32 v[120:121], v[116:117], v[116:117]
	v_pk_add_f32 v[114:115], v[118:119], v[114:115]
	v_mul_f32_e32 v118, 0xbfb8aa3b, v174
	v_pk_mul_f32 v[184:185], v[182:183], v[182:183]
	v_add_f32_e32 v120, v120, v121
	v_exp_f32_e32 v122, v118
	v_mul_f32_e32 v118, 0xbfb8aa3b, v175
	v_add_f32_e32 v120, v184, v120
	v_lshlrev_b32_e32 v172, 16, v123
	v_and_b32_e32 v173, 0xffff0000, v123
	v_exp_f32_e32 v123, v118
	v_pk_mul_f32 v[118:119], v[114:115], v[114:115]
	v_add_f32_e32 v120, v185, v120
	v_pk_add_f32 v[170:171], v[172:173], v[170:171]
	v_add_f32_e32 v118, v118, v120
	v_pk_mul_f32 v[172:173], v[170:171], v[170:171]
	v_add_f32_e32 v118, v119, v118
	v_add_f32_e32 v118, v172, v118
	v_pk_mul_f32 v[128:129], v[124:125], v[124:125]
	v_add_f32_e32 v118, v173, v118
	v_pk_add_f32 v[144:145], v[146:147], v[144:145]
	v_add_f32_e32 v118, v128, v118
	v_pk_mul_f32 v[146:147], v[144:145], v[144:145]
	v_lshlrev_b32_e32 v180, 16, v113
	v_add_f32_e32 v118, v129, v118
	v_and_b32_e32 v181, 0xffff0000, v113
	v_mul_f32_e32 v113, 0xbfb8aa3b, v180
	v_add_f32_e32 v118, v146, v118
	v_pk_mul_f32 v[130:131], v[126:127], v[126:127]
	v_exp_f32_e32 v113, v113
	v_add_f32_e32 v118, v147, v118
	v_add_f32_e32 v118, v130, v118
	v_pk_mul_f32 v[142:143], v[138:139], v[138:139]
	v_add_f32_e32 v118, v131, v118
	v_add_f32_e32 v118, v143, v118
	v_add_f32_e32 v113, 1.0, v113
	v_add_f32_e32 v120, v142, v118
	v_rcp_f32_e32 v186, v113
	v_mul_f32_e32 v113, 0xbfb8aa3b, v181
	ds_bpermute_b32 v121, v177, v120
	v_exp_f32_e32 v113, v113
	v_lshlrev_b32_e32 v118, 16, v112
	v_and_b32_e32 v119, 0xffff0000, v112
	v_add_f32_e32 v122, 1.0, v122
	v_add_f32_e32 v113, 1.0, v113
	s_waitcnt lgkmcnt(0)
	v_add_f32_e32 v112, v120, v121
	v_rcp_f32_e32 v187, v113
	ds_bpermute_b32 v113, v178, v112
	v_mul_f32_e32 v120, 0xbfb8aa3b, v118
	v_exp_f32_e32 v120, v120
	v_mul_f32_e32 v121, 0xbfb8aa3b, v119
	v_exp_f32_e32 v121, v121
	s_waitcnt lgkmcnt(0)
	v_add_f32_e32 v128, v112, v113
	ds_bpermute_b32 v129, v179, v128
	v_add_f32_e32 v112, 1.0, v120
	v_add_f32_e32 v113, 1.0, v121
	v_rcp_f32_e32 v112, v112
	v_rcp_f32_e32 v113, v113
	s_waitcnt lgkmcnt(0)
	v_add_f32_e32 v120, v128, v129
	v_fmamk_f32 v120, v120, 0x3c000000, v176
	v_mul_f32_e32 v121, 0x4b800000, v120
	v_cmp_gt_f32_e32 vcc, s29, v120
	v_add_f32_e32 v123, 1.0, v123
	v_pk_mul_f32 v[112:113], v[112:113], v[118:119]
	v_cndmask_b32_e32 v120, v120, v121, vcc
	v_rsq_f32_e32 v128, v120
	v_rcp_f32_e32 v122, v122
	v_rcp_f32_e32 v123, v123
	v_ashrrev_i32_e32 v167, 31, v166
	v_mul_f32_e32 v118, 0x45800000, v128
	v_cndmask_b32_e32 v118, v128, v118, vcc
	v_pk_mul_f32 v[116:117], v[116:117], v[118:119] op_sel_hi:[1,0]
	v_pk_mul_f32 v[114:115], v[114:115], v[118:119] op_sel_hi:[1,0]
	v_pk_mul_f32 v[116:117], v[12:13], v[116:117]
	v_pk_mul_f32 v[120:121], v[122:123], v[174:175]
	v_pk_mul_f32 v[112:113], v[112:113], v[116:117]
	v_pk_mul_f32 v[116:117], v[182:183], v[118:119] op_sel_hi:[1,0]
	v_pk_mul_f32 v[122:123], v[186:187], v[180:181]
	v_pk_mul_f32 v[116:117], v[14:15], v[116:117]
	v_pk_mul_f32 v[114:115], v[8:9], v[114:115]
	v_pk_mul_f32 v[116:117], v[122:123], v[116:117]
	v_pk_mul_f32 v[114:115], v[120:121], v[114:115]
	v_pk_mul_f32 v[120:121], v[170:171], v[118:119] op_sel_hi:[1,0]
	v_pk_mul_f32 v[122:123], v[124:125], v[118:119] op_sel_hi:[1,0]
	v_pk_mul_f32 v[124:125], v[144:145], v[118:119] op_sel_hi:[1,0]
	v_mul_f32_e32 v119, 0xbfb8aa3b, v140
	v_exp_f32_e32 v119, v119
	v_mul_f32_e32 v128, 0xbfb8aa3b, v141
	v_exp_f32_e32 v129, v128
	v_mul_f32_e32 v137, v138, v118
	v_add_f32_e32 v119, 1.0, v119
	v_rcp_f32_e32 v128, v119
	v_add_f32_e32 v119, 1.0, v129
	v_rcp_f32_e32 v129, v119
	v_pk_mul_f32 v[126:127], v[126:127], v[118:119] op_sel_hi:[1,0]
	v_mul_f32_e32 v119, 0xbfb8aa3b, v3
	v_pk_mul_f32 v[126:127], v[0:1], v[126:127]
	v_pk_mul_f32 v[128:129], v[128:129], v[140:141]
	v_exp_f32_e32 v119, v119
	v_pk_mul_f32 v[126:127], v[128:129], v[126:127]
	v_mul_f32_e32 v128, 0xbfb8aa3b, v136
	v_exp_f32_e32 v128, v128
	v_add_f32_e32 v119, 1.0, v119
	v_rcp_f32_e32 v119, v119
	v_pk_mul_f32 v[120:121], v[10:11], v[120:121]
	v_add_f32_e32 v128, 1.0, v128
	v_rcp_f32_e32 v156, v128
	v_mul_f32_e32 v129, v139, v118
	v_mul_f32_e32 v130, v119, v3
	v_pk_mul_f32 v[120:121], v[168:169], v[120:121]
	v_pk_mul_f32 v[118:119], v[156:157], v[136:137]
	v_pk_mul_f32 v[122:123], v[4:5], v[122:123]
	v_pk_mul_f32 v[124:125], v[6:7], v[124:125]
	v_mul_f32_e32 v128, v2, v129
	v_mov_b32_e32 v131, v118
	v_mov_b32_e32 v129, v119
	v_cvt_pk_bf16_f32 v112, v112, v113
	v_cvt_pk_bf16_f32 v113, v116, v117
	v_lshlrev_b64 v[116:117], 11, v[166:167]
	v_pk_mul_f32 v[122:123], v[132:133], v[122:123]
	v_pk_mul_f32 v[124:125], v[134:135], v[124:125]
	v_cvt_pk_bf16_f32 v114, v114, v115
	v_cvt_pk_bf16_f32 v115, v120, v121
	v_lshl_add_u64 v[116:117], v[150:151], 0, v[116:117]
	v_pk_mul_f32 v[118:119], v[130:131], v[128:129]
	global_store_dwordx4 v[116:117], v[112:115], off sc1
	s_nop 1
	v_cvt_pk_bf16_f32 v112, v122, v123
	v_cvt_pk_bf16_f32 v113, v124, v125
	v_cvt_pk_bf16_f32 v114, v126, v127
	v_cvt_pk_bf16_f32 v115, v118, v119
	global_store_dwordx4 v[116:117], v[112:115], off offset:16 sc1
.LBB0_1431:
	s_or_b64 exec, exec, s[14:15]
	v_add_u32_e32 v3, s33, v166
	v_cmp_gt_i32_e32 vcc, s3, v3
	s_and_saveexec_b64 s[14:15], vcc
	s_cbranch_execz .LBB0_1433
	s_waitcnt vmcnt(23)
	v_lshlrev_b32_e32 v115, 16, v107
	v_lshlrev_b32_e32 v117, 16, v103
	v_and_b32_e32 v114, 0xffff0000, v107
	v_and_b32_e32 v116, 0xffff0000, v103
	s_waitcnt vmcnt(20)
	v_and_b32_e32 v112, 0xffff0000, v111
	v_lshlrev_b32_e32 v113, 16, v111
	v_pk_add_f32 v[114:115], v[114:115], v[116:117]
	v_lshlrev_b32_e32 v116, 16, v110
	v_and_b32_e32 v117, 0xffff0000, v110
	v_lshlrev_b32_e32 v110, 16, v106
	v_and_b32_e32 v111, 0xffff0000, v106
	v_lshlrev_b32_e32 v106, 16, v102
	v_and_b32_e32 v107, 0xffff0000, v102
	v_pk_add_f32 v[102:103], v[106:107], v[110:111]
	v_lshlrev_b32_e32 v110, 16, v109
	v_and_b32_e32 v111, 0xffff0000, v109
	v_lshlrev_b32_e32 v120, 16, v105
	v_and_b32_e32 v121, 0xffff0000, v105
	v_mul_f32_e32 v105, 0xbfb8aa3b, v110
	v_exp_f32_e32 v105, v105
	v_mul_f32_e32 v109, 0xbfb8aa3b, v111
	v_exp_f32_e32 v109, v109
	v_lshlrev_b32_e32 v122, 16, v101
	v_add_f32_e32 v105, 1.0, v105
	v_rcp_f32_e32 v124, v105
	v_add_f32_e32 v105, 1.0, v109
	v_rcp_f32_e32 v125, v105
	v_and_b32_e32 v123, 0xffff0000, v101
	v_and_b32_e32 v109, 0xffff0000, v104
	v_lshlrev_b32_e32 v134, 16, v93
	v_pk_mul_f32 v[110:111], v[124:125], v[110:111]
	v_lshlrev_b32_e32 v124, 16, v108
	v_and_b32_e32 v125, 0xffff0000, v108
	v_mul_f32_e32 v101, 0xbfb8aa3b, v124
	v_lshlrev_b32_e32 v108, 16, v104
	v_exp_f32_e32 v101, v101
	v_mul_f32_e32 v104, 0xbfb8aa3b, v125
	v_exp_f32_e32 v105, v104
	v_lshlrev_b32_e32 v104, 16, v100
	v_add_f32_e32 v101, 1.0, v101
	v_rcp_f32_e32 v126, v101
	v_add_f32_e32 v101, 1.0, v105
	v_rcp_f32_e32 v127, v101
	v_and_b32_e32 v105, 0xffff0000, v100
	v_pk_add_f32 v[100:101], v[104:105], v[108:109]
	v_and_b32_e32 v135, 0xffff0000, v93
	v_pk_mul_f32 v[108:109], v[126:127], v[124:125]
	v_lshlrev_b32_e32 v124, 16, v91
	v_and_b32_e32 v125, 0xffff0000, v91
	v_mul_f32_e32 v91, 0xbfb8aa3b, v124
	v_lshlrev_b32_e32 v126, 16, v95
	v_and_b32_e32 v127, 0xffff0000, v95
	v_exp_f32_e32 v91, v91
	v_mul_f32_e32 v95, 0xbfb8aa3b, v125
	v_exp_f32_e32 v95, v95
	v_lshlrev_b32_e32 v140, 16, v92
	v_add_f32_e32 v91, 1.0, v91
	v_rcp_f32_e32 v130, v91
	v_add_f32_e32 v91, 1.0, v95
	v_rcp_f32_e32 v131, v91
	v_and_b32_e32 v141, 0xffff0000, v92
	v_lshlrev_b32_e32 v92, 16, v96
	v_and_b32_e32 v93, 0xffff0000, v96
	v_lshlrev_b32_e32 v136, 16, v97
	v_and_b32_e32 v137, 0xffff0000, v97
	v_pk_add_f32 v[92:93], v[92:93], v[140:141]
	v_pk_mul_f32 v[124:125], v[130:131], v[124:125]
	v_lshlrev_b32_e32 v130, 16, v90
	v_and_b32_e32 v131, 0xffff0000, v90
	v_lshlrev_b32_e32 v90, 16, v94
	v_and_b32_e32 v91, 0xffff0000, v94
	v_lshlrev_b32_e32 v94, 16, v98
	v_and_b32_e32 v95, 0xffff0000, v98
	v_pk_add_f32 v[134:135], v[136:137], v[134:135]
	v_pk_mul_f32 v[96:97], v[92:93], v[92:93]
	v_pk_add_f32 v[90:91], v[94:95], v[90:91]
	v_mul_f32_e32 v94, 0xbfb8aa3b, v130
	v_pk_mul_f32 v[136:137], v[134:135], v[134:135]
	v_add_f32_e32 v96, v96, v97
	v_exp_f32_e32 v98, v94
	v_mul_f32_e32 v94, 0xbfb8aa3b, v131
	v_add_f32_e32 v96, v136, v96
	v_lshlrev_b32_e32 v128, 16, v99
	v_and_b32_e32 v129, 0xffff0000, v99
	v_exp_f32_e32 v99, v94
	v_pk_mul_f32 v[94:95], v[90:91], v[90:91]
	v_add_f32_e32 v96, v137, v96
	v_pk_add_f32 v[126:127], v[128:129], v[126:127]
	v_add_f32_e32 v94, v94, v96
	v_pk_mul_f32 v[128:129], v[126:127], v[126:127]
	v_add_f32_e32 v94, v95, v94
	v_add_f32_e32 v94, v128, v94
	v_pk_mul_f32 v[104:105], v[100:101], v[100:101]
	v_add_f32_e32 v94, v129, v94
	v_pk_add_f32 v[120:121], v[122:123], v[120:121]
	v_add_f32_e32 v94, v104, v94
	v_pk_mul_f32 v[122:123], v[120:121], v[120:121]
	v_lshlrev_b32_e32 v132, 16, v89
	v_add_f32_e32 v94, v105, v94
	v_and_b32_e32 v133, 0xffff0000, v89
	v_mul_f32_e32 v89, 0xbfb8aa3b, v132
	v_add_f32_e32 v94, v122, v94
	v_pk_mul_f32 v[106:107], v[102:103], v[102:103]
	v_exp_f32_e32 v89, v89
	v_add_f32_e32 v94, v123, v94
	v_add_f32_e32 v94, v106, v94
	v_pk_mul_f32 v[118:119], v[114:115], v[114:115]
	v_add_f32_e32 v94, v107, v94
	v_add_f32_e32 v94, v119, v94
	v_add_f32_e32 v89, 1.0, v89
	v_add_f32_e32 v96, v118, v94
	v_rcp_f32_e32 v138, v89
	v_mul_f32_e32 v89, 0xbfb8aa3b, v133
	ds_bpermute_b32 v97, v177, v96
	v_exp_f32_e32 v89, v89
	v_lshlrev_b32_e32 v94, 16, v88
	v_and_b32_e32 v95, 0xffff0000, v88
	v_add_f32_e32 v98, 1.0, v98
	v_add_f32_e32 v89, 1.0, v89
	s_waitcnt lgkmcnt(0)
	v_add_f32_e32 v88, v96, v97
	v_rcp_f32_e32 v139, v89
	ds_bpermute_b32 v89, v178, v88
	v_mul_f32_e32 v96, 0xbfb8aa3b, v94
	v_exp_f32_e32 v96, v96
	v_mul_f32_e32 v97, 0xbfb8aa3b, v95
	v_exp_f32_e32 v97, v97
	s_waitcnt lgkmcnt(0)
	v_add_f32_e32 v104, v88, v89
	ds_bpermute_b32 v105, v179, v104
	v_add_f32_e32 v88, 1.0, v96
	v_add_f32_e32 v89, 1.0, v97
	v_rcp_f32_e32 v88, v88
	v_rcp_f32_e32 v89, v89
	s_waitcnt lgkmcnt(0)
	v_add_f32_e32 v96, v104, v105
	v_fmamk_f32 v96, v96, 0x3c000000, v176
	v_mul_f32_e32 v97, 0x4b800000, v96
	v_cmp_gt_f32_e32 vcc, s29, v96
	v_add_f32_e32 v99, 1.0, v99
	v_pk_mul_f32 v[88:89], v[88:89], v[94:95]
	v_cndmask_b32_e32 v96, v96, v97, vcc
	v_rsq_f32_e32 v104, v96
	v_rcp_f32_e32 v98, v98
	v_rcp_f32_e32 v99, v99
	v_ashrrev_i32_e32 v165, 31, v164
	v_mul_f32_e32 v94, 0x45800000, v104
	v_cndmask_b32_e32 v94, v104, v94, vcc
	v_pk_mul_f32 v[92:93], v[92:93], v[94:95] op_sel_hi:[1,0]
	v_pk_mul_f32 v[90:91], v[90:91], v[94:95] op_sel_hi:[1,0]
	v_pk_mul_f32 v[92:93], v[12:13], v[92:93]
	v_pk_mul_f32 v[96:97], v[98:99], v[130:131]
	v_pk_mul_f32 v[88:89], v[88:89], v[92:93]
	v_pk_mul_f32 v[92:93], v[134:135], v[94:95] op_sel_hi:[1,0]
	v_pk_mul_f32 v[98:99], v[138:139], v[132:133]
	v_pk_mul_f32 v[92:93], v[14:15], v[92:93]
	v_pk_mul_f32 v[90:91], v[8:9], v[90:91]
	v_pk_mul_f32 v[92:93], v[98:99], v[92:93]
	v_pk_mul_f32 v[90:91], v[96:97], v[90:91]
	v_pk_mul_f32 v[96:97], v[126:127], v[94:95] op_sel_hi:[1,0]
	v_pk_mul_f32 v[98:99], v[100:101], v[94:95] op_sel_hi:[1,0]
	v_pk_mul_f32 v[100:101], v[120:121], v[94:95] op_sel_hi:[1,0]
	v_mul_f32_e32 v95, 0xbfb8aa3b, v116
	v_exp_f32_e32 v95, v95
	v_mul_f32_e32 v104, 0xbfb8aa3b, v117
	v_exp_f32_e32 v105, v104
	v_pk_mul_f32 v[96:97], v[10:11], v[96:97]
	v_add_f32_e32 v95, 1.0, v95
	v_rcp_f32_e32 v104, v95
	v_add_f32_e32 v95, 1.0, v105
	v_rcp_f32_e32 v105, v95
	v_pk_mul_f32 v[102:103], v[102:103], v[94:95] op_sel_hi:[1,0]
	v_mul_f32_e32 v95, 0xbfb8aa3b, v113
	v_pk_mul_f32 v[102:103], v[0:1], v[102:103]
	v_pk_mul_f32 v[104:105], v[104:105], v[116:117]
	v_exp_f32_e32 v95, v95
	v_pk_mul_f32 v[102:103], v[104:105], v[102:103]
	v_mul_f32_e32 v104, 0xbfb8aa3b, v112
	v_exp_f32_e32 v104, v104
	v_add_f32_e32 v95, 1.0, v95
	v_rcp_f32_e32 v95, v95
	v_mul_f32_e32 v105, v115, v94
	v_add_f32_e32 v104, 1.0, v104
	v_rcp_f32_e32 v156, v104
	v_mul_f32_e32 v106, v95, v113
	v_mul_f32_e32 v113, v114, v94
	v_pk_mul_f32 v[96:97], v[124:125], v[96:97]
	v_pk_mul_f32 v[94:95], v[156:157], v[112:113]
	v_pk_mul_f32 v[98:99], v[4:5], v[98:99]
	v_pk_mul_f32 v[100:101], v[6:7], v[100:101]
	v_mul_f32_e32 v104, v2, v105
	v_mov_b32_e32 v107, v94
	v_mov_b32_e32 v105, v95
	v_cvt_pk_bf16_f32 v88, v88, v89
	v_cvt_pk_bf16_f32 v89, v92, v93
	v_lshlrev_b64 v[92:93], 11, v[164:165]
	v_pk_mul_f32 v[98:99], v[108:109], v[98:99]
	v_pk_mul_f32 v[100:101], v[110:111], v[100:101]
	v_cvt_pk_bf16_f32 v90, v90, v91
	v_cvt_pk_bf16_f32 v91, v96, v97
	v_lshl_add_u64 v[92:93], v[150:151], 0, v[92:93]
	v_pk_mul_f32 v[94:95], v[106:107], v[104:105]
	global_store_dwordx4 v[92:93], v[88:91], off sc1
	s_nop 1
	v_cvt_pk_bf16_f32 v88, v98, v99
	v_cvt_pk_bf16_f32 v89, v100, v101
	v_cvt_pk_bf16_f32 v90, v102, v103
	v_cvt_pk_bf16_f32 v91, v94, v95
	global_store_dwordx4 v[92:93], v[88:91], off offset:16 sc1
.LBB0_1433:
	s_or_b64 exec, exec, s[14:15]
	v_add_u32_e32 v3, s33, v3
	v_cmp_gt_i32_e32 vcc, s3, v3
	s_and_saveexec_b64 s[14:15], vcc
	s_cbranch_execz .LBB0_1435
	s_waitcnt vmcnt(17)
	v_lshlrev_b32_e32 v91, 16, v83
	v_lshlrev_b32_e32 v93, 16, v79
	v_and_b32_e32 v90, 0xffff0000, v83
	v_and_b32_e32 v92, 0xffff0000, v79
	s_waitcnt vmcnt(14)
	v_and_b32_e32 v88, 0xffff0000, v87
	v_lshlrev_b32_e32 v89, 16, v87
	v_pk_add_f32 v[90:91], v[90:91], v[92:93]
	v_lshlrev_b32_e32 v92, 16, v86
	v_and_b32_e32 v93, 0xffff0000, v86
	v_lshlrev_b32_e32 v86, 16, v82
	v_and_b32_e32 v87, 0xffff0000, v82
	v_lshlrev_b32_e32 v82, 16, v78
	v_and_b32_e32 v83, 0xffff0000, v78
	v_pk_add_f32 v[78:79], v[82:83], v[86:87]
	v_lshlrev_b32_e32 v86, 16, v85
	v_and_b32_e32 v87, 0xffff0000, v85
	v_lshlrev_b32_e32 v96, 16, v81
	v_and_b32_e32 v97, 0xffff0000, v81
	v_mul_f32_e32 v81, 0xbfb8aa3b, v86
	v_exp_f32_e32 v81, v81
	v_mul_f32_e32 v85, 0xbfb8aa3b, v87
	v_exp_f32_e32 v85, v85
	v_lshlrev_b32_e32 v98, 16, v77
	v_add_f32_e32 v81, 1.0, v81
	v_rcp_f32_e32 v100, v81
	v_add_f32_e32 v81, 1.0, v85
	v_rcp_f32_e32 v101, v81
	v_and_b32_e32 v99, 0xffff0000, v77
	v_and_b32_e32 v85, 0xffff0000, v80
	v_lshlrev_b32_e32 v110, 16, v69
	v_pk_mul_f32 v[86:87], v[100:101], v[86:87]
	v_lshlrev_b32_e32 v100, 16, v84
	v_and_b32_e32 v101, 0xffff0000, v84
	v_mul_f32_e32 v77, 0xbfb8aa3b, v100
	v_lshlrev_b32_e32 v84, 16, v80
	v_exp_f32_e32 v77, v77
	v_mul_f32_e32 v80, 0xbfb8aa3b, v101
	v_exp_f32_e32 v81, v80
	v_lshlrev_b32_e32 v80, 16, v76
	v_add_f32_e32 v77, 1.0, v77
	v_rcp_f32_e32 v102, v77
	v_add_f32_e32 v77, 1.0, v81
	v_rcp_f32_e32 v103, v77
	v_and_b32_e32 v81, 0xffff0000, v76
	v_pk_add_f32 v[76:77], v[80:81], v[84:85]
	v_and_b32_e32 v111, 0xffff0000, v69
	v_pk_mul_f32 v[84:85], v[102:103], v[100:101]
	v_lshlrev_b32_e32 v100, 16, v67
	v_and_b32_e32 v101, 0xffff0000, v67
	v_mul_f32_e32 v67, 0xbfb8aa3b, v100
	v_lshlrev_b32_e32 v102, 16, v71
	v_and_b32_e32 v103, 0xffff0000, v71
	v_exp_f32_e32 v67, v67
	v_mul_f32_e32 v71, 0xbfb8aa3b, v101
	v_exp_f32_e32 v71, v71
	v_lshlrev_b32_e32 v116, 16, v68
	v_add_f32_e32 v67, 1.0, v67
	v_rcp_f32_e32 v106, v67
	v_add_f32_e32 v67, 1.0, v71
	v_rcp_f32_e32 v107, v67
	v_and_b32_e32 v117, 0xffff0000, v68
	v_lshlrev_b32_e32 v68, 16, v72
	v_and_b32_e32 v69, 0xffff0000, v72
	v_lshlrev_b32_e32 v112, 16, v73
	v_and_b32_e32 v113, 0xffff0000, v73
	v_pk_add_f32 v[68:69], v[68:69], v[116:117]
	v_pk_mul_f32 v[100:101], v[106:107], v[100:101]
	v_lshlrev_b32_e32 v106, 16, v66
	v_and_b32_e32 v107, 0xffff0000, v66
	v_lshlrev_b32_e32 v66, 16, v70
	v_and_b32_e32 v67, 0xffff0000, v70
	v_lshlrev_b32_e32 v70, 16, v74
	v_and_b32_e32 v71, 0xffff0000, v74
	v_pk_add_f32 v[110:111], v[112:113], v[110:111]
	v_pk_mul_f32 v[72:73], v[68:69], v[68:69]
	v_pk_add_f32 v[66:67], v[70:71], v[66:67]
	v_mul_f32_e32 v70, 0xbfb8aa3b, v106
	v_pk_mul_f32 v[112:113], v[110:111], v[110:111]
	v_add_f32_e32 v72, v72, v73
	v_exp_f32_e32 v74, v70
	v_mul_f32_e32 v70, 0xbfb8aa3b, v107
	v_add_f32_e32 v72, v112, v72
	v_lshlrev_b32_e32 v104, 16, v75
	v_and_b32_e32 v105, 0xffff0000, v75
	v_exp_f32_e32 v75, v70
	v_pk_mul_f32 v[70:71], v[66:67], v[66:67]
	v_add_f32_e32 v72, v113, v72
	v_pk_add_f32 v[102:103], v[104:105], v[102:103]
	v_add_f32_e32 v70, v70, v72
	v_pk_mul_f32 v[104:105], v[102:103], v[102:103]
	v_add_f32_e32 v70, v71, v70
	v_add_f32_e32 v70, v104, v70
	v_pk_mul_f32 v[80:81], v[76:77], v[76:77]
	v_add_f32_e32 v70, v105, v70
	v_pk_add_f32 v[96:97], v[98:99], v[96:97]
	v_add_f32_e32 v70, v80, v70
	v_pk_mul_f32 v[98:99], v[96:97], v[96:97]
	v_lshlrev_b32_e32 v108, 16, v65
	v_add_f32_e32 v70, v81, v70
	v_and_b32_e32 v109, 0xffff0000, v65
	v_mul_f32_e32 v65, 0xbfb8aa3b, v108
	v_add_f32_e32 v70, v98, v70
	v_pk_mul_f32 v[82:83], v[78:79], v[78:79]
	v_exp_f32_e32 v65, v65
	v_add_f32_e32 v70, v99, v70
	v_add_f32_e32 v70, v82, v70
	v_pk_mul_f32 v[94:95], v[90:91], v[90:91]
	v_add_f32_e32 v70, v83, v70
	v_add_f32_e32 v70, v95, v70
	v_add_f32_e32 v65, 1.0, v65
	v_add_f32_e32 v72, v94, v70
	v_rcp_f32_e32 v114, v65
	v_mul_f32_e32 v65, 0xbfb8aa3b, v109
	ds_bpermute_b32 v73, v177, v72
	v_exp_f32_e32 v65, v65
	v_lshlrev_b32_e32 v70, 16, v64
	v_and_b32_e32 v71, 0xffff0000, v64
	v_add_f32_e32 v74, 1.0, v74
	v_add_f32_e32 v65, 1.0, v65
	s_waitcnt lgkmcnt(0)
	v_add_f32_e32 v64, v72, v73
	v_rcp_f32_e32 v115, v65
	ds_bpermute_b32 v65, v178, v64
	v_mul_f32_e32 v72, 0xbfb8aa3b, v70
	v_exp_f32_e32 v72, v72
	v_mul_f32_e32 v73, 0xbfb8aa3b, v71
	v_exp_f32_e32 v73, v73
	s_waitcnt lgkmcnt(0)
	v_add_f32_e32 v80, v64, v65
	ds_bpermute_b32 v81, v179, v80
	v_add_f32_e32 v64, 1.0, v72
	v_add_f32_e32 v65, 1.0, v73
	v_rcp_f32_e32 v64, v64
	v_rcp_f32_e32 v65, v65
	s_waitcnt lgkmcnt(0)
	v_add_f32_e32 v72, v80, v81
	v_fmamk_f32 v72, v72, 0x3c000000, v176
	v_mul_f32_e32 v73, 0x4b800000, v72
	v_cmp_gt_f32_e32 vcc, s29, v72
	v_add_f32_e32 v75, 1.0, v75
	v_pk_mul_f32 v[64:65], v[64:65], v[70:71]
	v_cndmask_b32_e32 v72, v72, v73, vcc
	v_rsq_f32_e32 v80, v72
	v_rcp_f32_e32 v74, v74
	v_rcp_f32_e32 v75, v75
	v_ashrrev_i32_e32 v163, 31, v162
	v_mul_f32_e32 v70, 0x45800000, v80
	v_cndmask_b32_e32 v70, v80, v70, vcc
	v_pk_mul_f32 v[68:69], v[68:69], v[70:71] op_sel_hi:[1,0]
	v_pk_mul_f32 v[66:67], v[66:67], v[70:71] op_sel_hi:[1,0]
	v_pk_mul_f32 v[68:69], v[12:13], v[68:69]
	v_pk_mul_f32 v[72:73], v[74:75], v[106:107]
	v_pk_mul_f32 v[64:65], v[64:65], v[68:69]
	v_pk_mul_f32 v[68:69], v[110:111], v[70:71] op_sel_hi:[1,0]
	v_pk_mul_f32 v[74:75], v[114:115], v[108:109]
	v_pk_mul_f32 v[68:69], v[14:15], v[68:69]
	v_pk_mul_f32 v[66:67], v[8:9], v[66:67]
	v_pk_mul_f32 v[68:69], v[74:75], v[68:69]
	v_pk_mul_f32 v[66:67], v[72:73], v[66:67]
	v_pk_mul_f32 v[72:73], v[102:103], v[70:71] op_sel_hi:[1,0]
	v_pk_mul_f32 v[74:75], v[76:77], v[70:71] op_sel_hi:[1,0]
	v_pk_mul_f32 v[76:77], v[96:97], v[70:71] op_sel_hi:[1,0]
	v_mul_f32_e32 v71, 0xbfb8aa3b, v92
	v_exp_f32_e32 v71, v71
	v_mul_f32_e32 v80, 0xbfb8aa3b, v93
	v_exp_f32_e32 v81, v80
	v_pk_mul_f32 v[72:73], v[10:11], v[72:73]
	v_add_f32_e32 v71, 1.0, v71
	v_rcp_f32_e32 v80, v71
	v_add_f32_e32 v71, 1.0, v81
	v_rcp_f32_e32 v81, v71
	v_pk_mul_f32 v[78:79], v[78:79], v[70:71] op_sel_hi:[1,0]
	v_mul_f32_e32 v71, 0xbfb8aa3b, v89
	v_pk_mul_f32 v[78:79], v[0:1], v[78:79]
	v_pk_mul_f32 v[80:81], v[80:81], v[92:93]
	v_exp_f32_e32 v71, v71
	v_pk_mul_f32 v[78:79], v[80:81], v[78:79]
	v_mul_f32_e32 v80, 0xbfb8aa3b, v88
	v_exp_f32_e32 v80, v80
	v_add_f32_e32 v71, 1.0, v71
	v_rcp_f32_e32 v71, v71
	v_mul_f32_e32 v81, v91, v70
	v_add_f32_e32 v80, 1.0, v80
	v_rcp_f32_e32 v156, v80
	v_mul_f32_e32 v82, v71, v89
	v_mul_f32_e32 v89, v90, v70
	v_pk_mul_f32 v[72:73], v[100:101], v[72:73]
	v_pk_mul_f32 v[70:71], v[156:157], v[88:89]
	v_pk_mul_f32 v[74:75], v[4:5], v[74:75]
	v_pk_mul_f32 v[76:77], v[6:7], v[76:77]
	v_mul_f32_e32 v80, v2, v81
	v_mov_b32_e32 v83, v70
	v_mov_b32_e32 v81, v71
	v_cvt_pk_bf16_f32 v64, v64, v65
	v_cvt_pk_bf16_f32 v65, v68, v69
	v_lshlrev_b64 v[68:69], 11, v[162:163]
	v_pk_mul_f32 v[74:75], v[84:85], v[74:75]
	v_pk_mul_f32 v[76:77], v[86:87], v[76:77]
	v_cvt_pk_bf16_f32 v66, v66, v67
	v_cvt_pk_bf16_f32 v67, v72, v73
	v_lshl_add_u64 v[68:69], v[150:151], 0, v[68:69]
	v_pk_mul_f32 v[70:71], v[82:83], v[80:81]
	global_store_dwordx4 v[68:69], v[64:67], off sc1
	s_nop 1
	v_cvt_pk_bf16_f32 v64, v74, v75
	v_cvt_pk_bf16_f32 v65, v76, v77
	v_cvt_pk_bf16_f32 v66, v78, v79
	v_cvt_pk_bf16_f32 v67, v70, v71
	global_store_dwordx4 v[68:69], v[64:67], off offset:16 sc1
.LBB0_1435:
	s_or_b64 exec, exec, s[14:15]
	v_add_u32_e32 v3, s33, v3
	v_cmp_gt_i32_e32 vcc, s3, v3
	s_and_saveexec_b64 s[14:15], vcc
	s_cbranch_execz .LBB0_1437
	s_waitcnt vmcnt(11)
	v_and_b32_e32 v69, 0xffff0000, v55
	v_and_b32_e32 v68, 0xffff0000, v59
	s_waitcnt vmcnt(8)
	v_lshlrev_b32_e32 v65, 16, v63
	v_and_b32_e32 v64, 0xffff0000, v63
	v_lshlrev_b32_e32 v63, 16, v59
	v_pk_add_f32 v[68:69], v[68:69], 0 op_sel_hi:[1,0]
	v_add_f32_e32 v67, 0, v63
	v_mov_b32_e32 v66, v68
	v_mov_b32_e32 v70, v69
	v_lshlrev_b32_e32 v68, 16, v62
	v_and_b32_e32 v69, 0xffff0000, v62
	v_lshlrev_b32_e32 v62, 16, v58
	v_and_b32_e32 v63, 0xffff0000, v58
	v_lshlrev_b32_e32 v55, 16, v55
	v_pk_add_f32 v[58:59], v[62:63], 0 op_sel_hi:[1,0]
	v_lshlrev_b32_e32 v62, 16, v54
	v_and_b32_e32 v63, 0xffff0000, v54
	v_add_f32_e32 v71, 0, v55
	v_pk_add_f32 v[54:55], v[62:63], 0 op_sel_hi:[1,0]
	v_lshlrev_b32_e32 v62, 16, v61
	v_and_b32_e32 v63, 0xffff0000, v61
	v_lshlrev_b32_e32 v72, 16, v57
	v_and_b32_e32 v73, 0xffff0000, v57
	v_mul_f32_e32 v57, 0xbfb8aa3b, v62
	v_exp_f32_e32 v57, v57
	v_mul_f32_e32 v61, 0xbfb8aa3b, v63
	v_exp_f32_e32 v61, v61
	v_lshlrev_b32_e32 v74, 16, v53
	v_and_b32_e32 v75, 0xffff0000, v53
	v_add_f32_e32 v53, 1.0, v57
	v_rcp_f32_e32 v76, v53
	v_add_f32_e32 v53, 1.0, v61
	v_rcp_f32_e32 v77, v53
	v_and_b32_e32 v61, 0xffff0000, v56
	v_and_b32_e32 v79, 0xffff0000, v51
	v_lshlrev_b32_e32 v92, 16, v48
	v_pk_mul_f32 v[62:63], v[76:77], v[62:63]
	v_lshlrev_b32_e32 v76, 16, v60
	v_and_b32_e32 v77, 0xffff0000, v60
	v_lshlrev_b32_e32 v60, 16, v56
	v_pk_add_f32 v[56:57], v[60:61], 0 op_sel_hi:[1,0]
	v_mul_f32_e32 v53, 0xbfb8aa3b, v76
	v_mul_f32_e32 v61, 0xbfb8aa3b, v77
	v_exp_f32_e32 v53, v53
	v_exp_f32_e32 v78, v61
	v_lshlrev_b32_e32 v60, 16, v52
	v_and_b32_e32 v61, 0xffff0000, v52
	v_add_f32_e32 v52, 1.0, v53
	v_add_f32_e32 v53, 1.0, v78
	v_rcp_f32_e32 v52, v52
	v_rcp_f32_e32 v53, v53
	v_lshlrev_b32_e32 v78, 16, v51
	v_and_b32_e32 v93, 0xffff0000, v48
	v_lshlrev_b32_e32 v86, 16, v49
	v_pk_mul_f32 v[52:53], v[52:53], v[76:77]
	v_lshlrev_b32_e32 v76, 16, v43
	v_and_b32_e32 v77, 0xffff0000, v43
	v_mul_f32_e32 v43, 0xbfb8aa3b, v76
	v_exp_f32_e32 v43, v43
	v_mul_f32_e32 v51, 0xbfb8aa3b, v77
	v_exp_f32_e32 v51, v51
	v_and_b32_e32 v87, 0xffff0000, v49
	v_add_f32_e32 v43, 1.0, v43
	v_rcp_f32_e32 v82, v43
	v_add_f32_e32 v43, 1.0, v51
	v_rcp_f32_e32 v83, v43
	v_pk_add_f32 v[48:49], v[92:93], 0 op_sel_hi:[1,0]
	v_lshlrev_b32_e32 v92, 16, v44
	v_and_b32_e32 v93, 0xffff0000, v44
	v_lshlrev_b32_e32 v88, 16, v45
	v_and_b32_e32 v89, 0xffff0000, v45
	v_pk_add_f32 v[44:45], v[92:93], 0 op_sel_hi:[1,0]
	v_pk_mul_f32 v[76:77], v[82:83], v[76:77]
	v_lshlrev_b32_e32 v82, 16, v42
	v_and_b32_e32 v83, 0xffff0000, v42
	v_lshlrev_b32_e32 v42, 16, v50
	v_and_b32_e32 v43, 0xffff0000, v50
	v_lshlrev_b32_e32 v50, 16, v46
	v_and_b32_e32 v51, 0xffff0000, v46
	v_pk_add_f32 v[86:87], v[86:87], 0 op_sel_hi:[1,0]
	v_pk_add_f32 v[88:89], v[88:89], 0 op_sel_hi:[1,0]
	v_pk_add_f32 v[44:45], v[48:49], v[44:45]
	v_lshlrev_b32_e32 v80, 16, v47
	v_and_b32_e32 v81, 0xffff0000, v47
	v_pk_add_f32 v[42:43], v[42:43], 0 op_sel_hi:[1,0]
	v_pk_add_f32 v[46:47], v[50:51], 0 op_sel_hi:[1,0]
	v_pk_add_f32 v[86:87], v[86:87], v[88:89]
	v_pk_mul_f32 v[48:49], v[44:45], v[44:45]
	v_pk_add_f32 v[42:43], v[42:43], v[46:47]
	v_mul_f32_e32 v46, 0xbfb8aa3b, v82
	v_pk_mul_f32 v[88:89], v[86:87], v[86:87]
	v_add_f32_e32 v48, v48, v49
	v_exp_f32_e32 v50, v46
	v_mul_f32_e32 v46, 0xbfb8aa3b, v83
	v_add_f32_e32 v48, v88, v48
	v_pk_add_f32 v[78:79], v[78:79], 0 op_sel_hi:[1,0]
	v_pk_add_f32 v[80:81], v[80:81], 0 op_sel_hi:[1,0]
	v_exp_f32_e32 v51, v46
	v_pk_mul_f32 v[46:47], v[42:43], v[42:43]
	v_add_f32_e32 v48, v89, v48
	v_pk_add_f32 v[78:79], v[78:79], v[80:81]
	v_add_f32_e32 v46, v46, v48
	v_pk_add_f32 v[60:61], v[60:61], 0 op_sel_hi:[1,0]
	v_pk_mul_f32 v[80:81], v[78:79], v[78:79]
	v_add_f32_e32 v46, v47, v46
	v_pk_add_f32 v[56:57], v[56:57], v[60:61]
	v_add_f32_e32 v46, v80, v46
	v_pk_add_f32 v[72:73], v[72:73], 0 op_sel_hi:[1,0]
	v_pk_add_f32 v[74:75], v[74:75], 0 op_sel_hi:[1,0]
	v_pk_mul_f32 v[60:61], v[56:57], v[56:57]
	v_add_f32_e32 v46, v81, v46
	v_pk_add_f32 v[72:73], v[72:73], v[74:75]
	v_add_f32_e32 v46, v60, v46
	v_pk_mul_f32 v[74:75], v[72:73], v[72:73]
	v_lshlrev_b32_e32 v84, 16, v41
	v_add_f32_e32 v46, v61, v46
	v_pk_add_f32 v[54:55], v[58:59], v[54:55]
	v_and_b32_e32 v85, 0xffff0000, v41
	v_mul_f32_e32 v41, 0xbfb8aa3b, v84
	v_add_f32_e32 v46, v74, v46
	v_pk_mul_f32 v[58:59], v[54:55], v[54:55]
	v_exp_f32_e32 v41, v41
	v_add_f32_e32 v46, v75, v46
	v_pk_add_f32 v[66:67], v[66:67], v[70:71]
	v_add_f32_e32 v46, v58, v46
	v_pk_mul_f32 v[70:71], v[66:67], v[66:67]
	v_add_f32_e32 v46, v59, v46
	v_add_f32_e32 v46, v71, v46
	v_add_f32_e32 v41, 1.0, v41
	v_add_f32_e32 v48, v70, v46
	v_rcp_f32_e32 v90, v41
	v_mul_f32_e32 v41, 0xbfb8aa3b, v85
	ds_bpermute_b32 v49, v177, v48
	v_exp_f32_e32 v41, v41
	v_lshlrev_b32_e32 v46, 16, v40
	v_and_b32_e32 v47, 0xffff0000, v40
	v_add_f32_e32 v50, 1.0, v50
	v_add_f32_e32 v41, 1.0, v41
	s_waitcnt lgkmcnt(0)
	v_add_f32_e32 v40, v48, v49
	v_rcp_f32_e32 v91, v41
	ds_bpermute_b32 v41, v178, v40
	v_mul_f32_e32 v48, 0xbfb8aa3b, v46
	v_exp_f32_e32 v48, v48
	v_mul_f32_e32 v49, 0xbfb8aa3b, v47
	v_exp_f32_e32 v49, v49
	s_waitcnt lgkmcnt(0)
	v_add_f32_e32 v58, v40, v41
	ds_bpermute_b32 v59, v179, v58
	v_add_f32_e32 v40, 1.0, v48
	v_add_f32_e32 v41, 1.0, v49
	v_rcp_f32_e32 v40, v40
	v_rcp_f32_e32 v41, v41
	s_waitcnt lgkmcnt(0)
	v_add_f32_e32 v48, v58, v59
	v_fmamk_f32 v48, v48, 0x3c000000, v176
	v_mul_f32_e32 v49, 0x4b800000, v48
	v_cmp_gt_f32_e32 vcc, s29, v48
	v_add_f32_e32 v51, 1.0, v51
	v_pk_mul_f32 v[40:41], v[40:41], v[46:47]
	v_cndmask_b32_e32 v48, v48, v49, vcc
	v_rsq_f32_e32 v58, v48
	v_rcp_f32_e32 v50, v50
	v_rcp_f32_e32 v51, v51
	v_ashrrev_i32_e32 v161, 31, v160
	v_mul_f32_e32 v46, 0x45800000, v58
	v_cndmask_b32_e32 v46, v58, v46, vcc
	v_pk_mul_f32 v[44:45], v[44:45], v[46:47] op_sel_hi:[1,0]
	v_pk_mul_f32 v[48:49], v[50:51], v[82:83]
	v_pk_mul_f32 v[44:45], v[12:13], v[44:45]
	v_pk_mul_f32 v[50:51], v[90:91], v[84:85]
	v_pk_mul_f32 v[40:41], v[40:41], v[44:45]
	v_pk_mul_f32 v[44:45], v[86:87], v[46:47] op_sel_hi:[1,0]
	v_pk_mul_f32 v[42:43], v[42:43], v[46:47] op_sel_hi:[1,0]
	v_pk_mul_f32 v[44:45], v[14:15], v[44:45]
	v_pk_mul_f32 v[42:43], v[8:9], v[42:43]
	v_pk_mul_f32 v[44:45], v[50:51], v[44:45]
	v_pk_mul_f32 v[50:51], v[56:57], v[46:47] op_sel_hi:[1,0]
	v_pk_mul_f32 v[42:43], v[48:49], v[42:43]
	v_pk_mul_f32 v[50:51], v[4:5], v[50:51]
	v_pk_mul_f32 v[48:49], v[78:79], v[46:47] op_sel_hi:[1,0]
	v_pk_mul_f32 v[50:51], v[52:53], v[50:51]
	v_pk_mul_f32 v[52:53], v[72:73], v[46:47] op_sel_hi:[1,0]
	v_mul_f32_e32 v47, 0xbfb8aa3b, v68
	v_exp_f32_e32 v47, v47
	v_mul_f32_e32 v56, 0xbfb8aa3b, v69
	v_exp_f32_e32 v57, v56
	v_pk_mul_f32 v[48:49], v[10:11], v[48:49]
	v_add_f32_e32 v47, 1.0, v47
	v_rcp_f32_e32 v56, v47
	v_add_f32_e32 v47, 1.0, v57
	v_rcp_f32_e32 v57, v47
	v_pk_mul_f32 v[54:55], v[54:55], v[46:47] op_sel_hi:[1,0]
	v_mul_f32_e32 v47, 0xbfb8aa3b, v65
	v_pk_mul_f32 v[54:55], v[0:1], v[54:55]
	v_pk_mul_f32 v[56:57], v[56:57], v[68:69]
	v_exp_f32_e32 v47, v47
	v_pk_mul_f32 v[54:55], v[56:57], v[54:55]
	v_mul_f32_e32 v56, 0xbfb8aa3b, v64
	v_exp_f32_e32 v56, v56
	v_add_f32_e32 v47, 1.0, v47
	v_rcp_f32_e32 v47, v47
	v_mul_f32_e32 v57, v67, v46
	v_add_f32_e32 v56, 1.0, v56
	v_rcp_f32_e32 v156, v56
	v_mul_f32_e32 v58, v47, v65
	v_mul_f32_e32 v65, v66, v46
	v_pk_mul_f32 v[48:49], v[76:77], v[48:49]
	v_pk_mul_f32 v[46:47], v[156:157], v[64:65]
	v_pk_mul_f32 v[52:53], v[6:7], v[52:53]
	v_mul_f32_e32 v56, v2, v57
	v_mov_b32_e32 v59, v46
	v_mov_b32_e32 v57, v47
	v_cvt_pk_bf16_f32 v40, v40, v41
	v_cvt_pk_bf16_f32 v41, v44, v45
	v_lshlrev_b64 v[44:45], 11, v[160:161]
	v_pk_mul_f32 v[52:53], v[62:63], v[52:53]
	v_cvt_pk_bf16_f32 v42, v42, v43
	v_cvt_pk_bf16_f32 v43, v48, v49
	v_lshl_add_u64 v[44:45], v[150:151], 0, v[44:45]
	v_pk_mul_f32 v[46:47], v[58:59], v[56:57]
	global_store_dwordx4 v[44:45], v[40:43], off sc1
	s_nop 1
	v_cvt_pk_bf16_f32 v40, v50, v51
	v_cvt_pk_bf16_f32 v41, v52, v53
	v_cvt_pk_bf16_f32 v42, v54, v55
	v_cvt_pk_bf16_f32 v43, v46, v47
	global_store_dwordx4 v[44:45], v[40:43], off offset:16 sc1
.LBB0_1437:
	s_or_b64 exec, exec, s[14:15]
	v_add_u32_e32 v3, s33, v3
	v_cmp_gt_i32_e32 vcc, s3, v3
	s_and_saveexec_b64 s[14:15], vcc
	s_cbranch_execz .LBB0_1428
	s_waitcnt vmcnt(5)
	v_and_b32_e32 v45, 0xffff0000, v31
	v_and_b32_e32 v44, 0xffff0000, v35
	s_waitcnt vmcnt(2)
	v_lshlrev_b32_e32 v41, 16, v39
	v_and_b32_e32 v40, 0xffff0000, v39
	v_lshlrev_b32_e32 v39, 16, v35
	v_pk_add_f32 v[44:45], v[44:45], 0 op_sel_hi:[1,0]
	v_add_f32_e32 v43, 0, v39
	v_mov_b32_e32 v42, v44
	v_mov_b32_e32 v46, v45
	v_lshlrev_b32_e32 v44, 16, v38
	v_and_b32_e32 v45, 0xffff0000, v38
	v_lshlrev_b32_e32 v38, 16, v34
	v_and_b32_e32 v39, 0xffff0000, v34
	v_lshlrev_b32_e32 v31, 16, v31
	v_pk_add_f32 v[34:35], v[38:39], 0 op_sel_hi:[1,0]
	v_lshlrev_b32_e32 v38, 16, v30
	v_and_b32_e32 v39, 0xffff0000, v30
	v_add_f32_e32 v47, 0, v31
	v_pk_add_f32 v[30:31], v[38:39], 0 op_sel_hi:[1,0]
	v_lshlrev_b32_e32 v38, 16, v37
	v_and_b32_e32 v39, 0xffff0000, v37
	v_lshlrev_b32_e32 v48, 16, v33
	v_and_b32_e32 v49, 0xffff0000, v33
	v_mul_f32_e32 v33, 0xbfb8aa3b, v38
	v_exp_f32_e32 v33, v33
	v_mul_f32_e32 v37, 0xbfb8aa3b, v39
	v_exp_f32_e32 v37, v37
	v_lshlrev_b32_e32 v50, 16, v29
	v_and_b32_e32 v51, 0xffff0000, v29
	v_add_f32_e32 v29, 1.0, v33
	v_rcp_f32_e32 v52, v29
	v_add_f32_e32 v29, 1.0, v37
	v_rcp_f32_e32 v53, v29
	v_and_b32_e32 v37, 0xffff0000, v32
	v_and_b32_e32 v55, 0xffff0000, v27
	v_lshlrev_b32_e32 v68, 16, v24
	v_pk_mul_f32 v[38:39], v[52:53], v[38:39]
	v_lshlrev_b32_e32 v52, 16, v36
	v_and_b32_e32 v53, 0xffff0000, v36
	v_lshlrev_b32_e32 v36, 16, v32
	v_pk_add_f32 v[32:33], v[36:37], 0 op_sel_hi:[1,0]
	v_mul_f32_e32 v29, 0xbfb8aa3b, v52
	v_mul_f32_e32 v37, 0xbfb8aa3b, v53
	v_exp_f32_e32 v29, v29
	v_exp_f32_e32 v54, v37
	v_lshlrev_b32_e32 v36, 16, v28
	v_and_b32_e32 v37, 0xffff0000, v28
	v_add_f32_e32 v28, 1.0, v29
	v_add_f32_e32 v29, 1.0, v54
	v_rcp_f32_e32 v28, v28
	v_rcp_f32_e32 v29, v29
	v_lshlrev_b32_e32 v54, 16, v27
	v_and_b32_e32 v69, 0xffff0000, v24
	v_lshlrev_b32_e32 v62, 16, v25
	v_pk_mul_f32 v[28:29], v[28:29], v[52:53]
	v_lshlrev_b32_e32 v52, 16, v19
	v_and_b32_e32 v53, 0xffff0000, v19
	v_mul_f32_e32 v19, 0xbfb8aa3b, v52
	v_exp_f32_e32 v19, v19
	v_mul_f32_e32 v27, 0xbfb8aa3b, v53
	v_exp_f32_e32 v27, v27
	v_and_b32_e32 v63, 0xffff0000, v25
	v_add_f32_e32 v19, 1.0, v19
	v_rcp_f32_e32 v58, v19
	v_add_f32_e32 v19, 1.0, v27
	v_rcp_f32_e32 v59, v19
	v_pk_add_f32 v[24:25], v[68:69], 0 op_sel_hi:[1,0]
	v_lshlrev_b32_e32 v68, 16, v20
	v_and_b32_e32 v69, 0xffff0000, v20
	v_lshlrev_b32_e32 v64, 16, v21
	v_and_b32_e32 v65, 0xffff0000, v21
	v_pk_add_f32 v[20:21], v[68:69], 0 op_sel_hi:[1,0]
	v_pk_mul_f32 v[52:53], v[58:59], v[52:53]
	v_lshlrev_b32_e32 v58, 16, v18
	v_and_b32_e32 v59, 0xffff0000, v18
	v_lshlrev_b32_e32 v18, 16, v26
	v_and_b32_e32 v19, 0xffff0000, v26
	v_lshlrev_b32_e32 v26, 16, v22
	v_and_b32_e32 v27, 0xffff0000, v22
	v_pk_add_f32 v[62:63], v[62:63], 0 op_sel_hi:[1,0]
	v_pk_add_f32 v[64:65], v[64:65], 0 op_sel_hi:[1,0]
	v_pk_add_f32 v[20:21], v[24:25], v[20:21]
	v_lshlrev_b32_e32 v56, 16, v23
	v_and_b32_e32 v57, 0xffff0000, v23
	v_pk_add_f32 v[18:19], v[18:19], 0 op_sel_hi:[1,0]
	v_pk_add_f32 v[22:23], v[26:27], 0 op_sel_hi:[1,0]
	v_pk_add_f32 v[62:63], v[62:63], v[64:65]
	v_pk_mul_f32 v[24:25], v[20:21], v[20:21]
	v_pk_add_f32 v[18:19], v[18:19], v[22:23]
	v_mul_f32_e32 v22, 0xbfb8aa3b, v58
	v_pk_mul_f32 v[64:65], v[62:63], v[62:63]
	v_add_f32_e32 v24, v24, v25
	v_exp_f32_e32 v26, v22
	v_mul_f32_e32 v22, 0xbfb8aa3b, v59
	v_add_f32_e32 v24, v64, v24
	v_pk_add_f32 v[54:55], v[54:55], 0 op_sel_hi:[1,0]
	v_pk_add_f32 v[56:57], v[56:57], 0 op_sel_hi:[1,0]
	v_exp_f32_e32 v27, v22
	v_pk_mul_f32 v[22:23], v[18:19], v[18:19]
	v_add_f32_e32 v24, v65, v24
	v_pk_add_f32 v[54:55], v[54:55], v[56:57]
	v_add_f32_e32 v22, v22, v24
	v_pk_add_f32 v[36:37], v[36:37], 0 op_sel_hi:[1,0]
	v_pk_mul_f32 v[56:57], v[54:55], v[54:55]
	v_add_f32_e32 v22, v23, v22
	v_pk_add_f32 v[32:33], v[32:33], v[36:37]
	v_add_f32_e32 v22, v56, v22
	v_pk_add_f32 v[48:49], v[48:49], 0 op_sel_hi:[1,0]
	v_pk_add_f32 v[50:51], v[50:51], 0 op_sel_hi:[1,0]
	v_pk_mul_f32 v[36:37], v[32:33], v[32:33]
	v_add_f32_e32 v22, v57, v22
	v_pk_add_f32 v[48:49], v[48:49], v[50:51]
	v_add_f32_e32 v22, v36, v22
	v_pk_mul_f32 v[50:51], v[48:49], v[48:49]
	v_lshlrev_b32_e32 v60, 16, v17
	v_add_f32_e32 v22, v37, v22
	v_pk_add_f32 v[30:31], v[34:35], v[30:31]
	v_and_b32_e32 v61, 0xffff0000, v17
	v_mul_f32_e32 v17, 0xbfb8aa3b, v60
	v_add_f32_e32 v22, v50, v22
	v_pk_mul_f32 v[34:35], v[30:31], v[30:31]
	v_exp_f32_e32 v17, v17
	v_add_f32_e32 v22, v51, v22
	v_pk_add_f32 v[42:43], v[42:43], v[46:47]
	v_add_f32_e32 v22, v34, v22
	v_pk_mul_f32 v[46:47], v[42:43], v[42:43]
	v_add_f32_e32 v22, v35, v22
	v_add_f32_e32 v22, v47, v22
	v_add_f32_e32 v17, 1.0, v17
	v_add_f32_e32 v24, v46, v22
	v_rcp_f32_e32 v66, v17
	v_mul_f32_e32 v17, 0xbfb8aa3b, v61
	ds_bpermute_b32 v25, v177, v24
	v_exp_f32_e32 v17, v17
	v_lshlrev_b32_e32 v22, 16, v16
	v_and_b32_e32 v23, 0xffff0000, v16
	v_add_f32_e32 v26, 1.0, v26
	v_add_f32_e32 v17, 1.0, v17
	s_waitcnt lgkmcnt(0)
	v_add_f32_e32 v16, v24, v25
	v_rcp_f32_e32 v67, v17
	ds_bpermute_b32 v17, v178, v16
	v_mul_f32_e32 v24, 0xbfb8aa3b, v22
	v_exp_f32_e32 v24, v24
	v_mul_f32_e32 v25, 0xbfb8aa3b, v23
	v_exp_f32_e32 v25, v25
	s_waitcnt lgkmcnt(0)
	v_add_f32_e32 v34, v16, v17
	ds_bpermute_b32 v35, v179, v34
	v_add_f32_e32 v16, 1.0, v24
	v_add_f32_e32 v17, 1.0, v25
	v_rcp_f32_e32 v16, v16
	v_rcp_f32_e32 v17, v17
	s_waitcnt lgkmcnt(0)
	v_add_f32_e32 v24, v34, v35
	v_fmamk_f32 v24, v24, 0x3c000000, v176
	v_mul_f32_e32 v25, 0x4b800000, v24
	v_cmp_gt_f32_e32 vcc, s29, v24
	v_add_f32_e32 v27, 1.0, v27
	v_pk_mul_f32 v[16:17], v[16:17], v[22:23]
	v_cndmask_b32_e32 v24, v24, v25, vcc
	v_rsq_f32_e32 v34, v24
	v_rcp_f32_e32 v26, v26
	v_rcp_f32_e32 v27, v27
	v_ashrrev_i32_e32 v159, 31, v158
	v_mul_f32_e32 v22, 0x45800000, v34
	v_cndmask_b32_e32 v22, v34, v22, vcc
	v_pk_mul_f32 v[20:21], v[20:21], v[22:23] op_sel_hi:[1,0]
	v_pk_mul_f32 v[24:25], v[26:27], v[58:59]
	v_pk_mul_f32 v[20:21], v[12:13], v[20:21]
	v_pk_mul_f32 v[26:27], v[66:67], v[60:61]
	v_pk_mul_f32 v[16:17], v[16:17], v[20:21]
	v_pk_mul_f32 v[20:21], v[62:63], v[22:23] op_sel_hi:[1,0]
	v_pk_mul_f32 v[18:19], v[18:19], v[22:23] op_sel_hi:[1,0]
	v_pk_mul_f32 v[20:21], v[14:15], v[20:21]
	v_pk_mul_f32 v[18:19], v[8:9], v[18:19]
	v_pk_mul_f32 v[20:21], v[26:27], v[20:21]
	v_pk_mul_f32 v[26:27], v[32:33], v[22:23] op_sel_hi:[1,0]
	v_pk_mul_f32 v[18:19], v[24:25], v[18:19]
	v_pk_mul_f32 v[26:27], v[4:5], v[26:27]
	v_pk_mul_f32 v[24:25], v[54:55], v[22:23] op_sel_hi:[1,0]
	v_pk_mul_f32 v[26:27], v[28:29], v[26:27]
	v_pk_mul_f32 v[28:29], v[48:49], v[22:23] op_sel_hi:[1,0]
	v_mul_f32_e32 v23, 0xbfb8aa3b, v44
	v_exp_f32_e32 v23, v23
	v_mul_f32_e32 v32, 0xbfb8aa3b, v45
	v_exp_f32_e32 v33, v32
	v_pk_mul_f32 v[24:25], v[10:11], v[24:25]
	v_add_f32_e32 v23, 1.0, v23
	v_rcp_f32_e32 v32, v23
	v_add_f32_e32 v23, 1.0, v33
	v_rcp_f32_e32 v33, v23
	v_pk_mul_f32 v[30:31], v[30:31], v[22:23] op_sel_hi:[1,0]
	v_mul_f32_e32 v23, 0xbfb8aa3b, v41
	v_pk_mul_f32 v[30:31], v[0:1], v[30:31]
	v_pk_mul_f32 v[32:33], v[32:33], v[44:45]
	v_exp_f32_e32 v23, v23
	v_pk_mul_f32 v[30:31], v[32:33], v[30:31]
	v_mul_f32_e32 v32, 0xbfb8aa3b, v40
	v_exp_f32_e32 v32, v32
	v_add_f32_e32 v23, 1.0, v23
	v_rcp_f32_e32 v23, v23
	v_mul_f32_e32 v33, v43, v22
	v_add_f32_e32 v32, 1.0, v32
	v_rcp_f32_e32 v156, v32
	v_mul_f32_e32 v34, v23, v41
	v_mul_f32_e32 v41, v42, v22
	v_pk_mul_f32 v[24:25], v[52:53], v[24:25]
	v_pk_mul_f32 v[22:23], v[156:157], v[40:41]
	v_pk_mul_f32 v[28:29], v[6:7], v[28:29]
	v_mul_f32_e32 v32, v2, v33
	v_mov_b32_e32 v35, v22
	v_mov_b32_e32 v33, v23
	v_cvt_pk_bf16_f32 v16, v16, v17
	v_cvt_pk_bf16_f32 v17, v20, v21
	v_lshlrev_b64 v[20:21], 11, v[158:159]
	v_pk_mul_f32 v[28:29], v[38:39], v[28:29]
	v_cvt_pk_bf16_f32 v18, v18, v19
	v_cvt_pk_bf16_f32 v19, v24, v25
	v_lshl_add_u64 v[20:21], v[150:151], 0, v[20:21]
	v_pk_mul_f32 v[22:23], v[34:35], v[32:33]
	global_store_dwordx4 v[20:21], v[16:19], off sc1
	s_nop 1
	v_cvt_pk_bf16_f32 v16, v26, v27
	v_cvt_pk_bf16_f32 v17, v28, v29
	v_cvt_pk_bf16_f32 v18, v30, v31
	v_cvt_pk_bf16_f32 v19, v22, v23
	global_store_dwordx4 v[20:21], v[16:19], off offset:16 sc1
	s_branch .LBB0_1428

.LBB0_1499:
	ds_read_b128 v[128:131], v163
	ds_read_b128 v[132:135], v163 offset:1024
	ds_read_b128 v[136:139], v163 offset:2048
	ds_read_b128 v[140:143], v163 offset:3072
	s_add_u32 s18, s52, 0xfffc0080
	s_addc_u32 s54, s53, -1
	s_cmp_eq_u32 s71, 12
	s_cselect_b32 s57, s45, s54
	s_cselect_b32 s56, s67, s18
	s_cselect_b32 s55, s43, s70
	s_cselect_b32 s54, s68, s69
	v_lshl_add_u64 v[198:199], s[52:53], 0, v[152:153]
	s_add_i32 m0, s17, 0xc000
	ds_read_b128 v[166:169], v164
	ds_read_b128 v[170:173], v164 offset:1024
	ds_read_b128 v[174:177], v164 offset:2048
	ds_read_b128 v[178:181], v164 offset:3072
	ds_read_b128 v[182:185], v164 offset:4096
	ds_read_b128 v[186:189], v164 offset:5120
	ds_read_b128 v[190:193], v164 offset:6144
	ds_read_b128 v[194:197], v164 offset:7168
	global_load_lds_dwordx4 v[198:199], off
	v_lshl_add_u64 v[198:199], s[52:53], 0, v[154:155]
	s_add_i32 m0, s17, 0xe000
	s_nop 0
	global_load_lds_dwordx4 v[198:199], off
	s_waitcnt lgkmcnt(8)
	s_barrier
	s_waitcnt lgkmcnt(0)
	s_setprio 1
	s_waitcnt lgkmcnt(0)
	v_mfma_f32_16x16x32_bf16 v[124:127], v[128:131], v[166:169], v[124:127]
	v_mfma_f32_16x16x32_bf16 v[120:123], v[136:139], v[166:169], v[120:123]
	v_mfma_f32_16x16x32_bf16 v[116:119], v[128:131], v[174:177], v[116:119]
	v_mfma_f32_16x16x32_bf16 v[112:115], v[136:139], v[174:177], v[112:115]
	v_mfma_f32_16x16x32_bf16 v[108:111], v[128:131], v[182:185], v[108:111]
	v_mfma_f32_16x16x32_bf16 v[100:103], v[136:139], v[182:185], v[100:103]
	v_mfma_f32_16x16x32_bf16 v[76:79], v[128:131], v[190:193], v[76:79]
	v_mfma_f32_16x16x32_bf16 v[72:75], v[136:139], v[190:193], v[72:75]
	v_mfma_f32_16x16x32_bf16 v[124:127], v[132:135], v[170:173], v[124:127]
	v_mfma_f32_16x16x32_bf16 v[120:123], v[140:143], v[170:173], v[120:123]
	v_mfma_f32_16x16x32_bf16 v[116:119], v[132:135], v[178:181], v[116:119]
	v_mfma_f32_16x16x32_bf16 v[112:115], v[140:143], v[178:181], v[112:115]
	v_mfma_f32_16x16x32_bf16 v[108:111], v[132:135], v[186:189], v[108:111]
	v_mfma_f32_16x16x32_bf16 v[100:103], v[140:143], v[186:189], v[100:103]
	v_mfma_f32_16x16x32_bf16 v[76:79], v[132:135], v[194:197], v[76:79]
	v_mfma_f32_16x16x32_bf16 v[72:75], v[140:143], v[194:197], v[72:75]
	s_setprio 0
	s_barrier
	s_add_i32 s18, s59, s16
	v_lshl_add_u64 v[214:215], s[54:55], 0, v[148:149]
	s_mov_b32 m0, s18
	ds_read_b128 v[198:201], v165
	ds_read_b128 v[202:205], v165 offset:1024
	ds_read_b128 v[206:209], v165 offset:2048
	ds_read_b128 v[210:213], v165 offset:3072
	global_load_lds_dwordx4 v[214:215], off
	v_lshl_add_u64 v[216:217], s[54:55], 0, v[144:145]
	s_add_i32 m0, s18, 0x2000
	s_nop 0
	global_load_lds_dwordx4 v[216:217], off
	s_barrier
	s_waitcnt lgkmcnt(0)
	s_setprio 1
	s_waitcnt lgkmcnt(0)
	v_mfma_f32_16x16x32_bf16 v[104:107], v[198:201], v[166:169], v[104:107]
	v_mfma_f32_16x16x32_bf16 v[96:99], v[206:209], v[166:169], v[96:99]
	v_mfma_f32_16x16x32_bf16 v[92:95], v[198:201], v[174:177], v[92:95]
	v_mfma_f32_16x16x32_bf16 v[88:91], v[206:209], v[174:177], v[88:91]
	v_mfma_f32_16x16x32_bf16 v[84:87], v[198:201], v[182:185], v[84:87]
	v_mfma_f32_16x16x32_bf16 v[80:83], v[206:209], v[182:185], v[80:83]
	v_mfma_f32_16x16x32_bf16 v[68:71], v[198:201], v[190:193], v[68:71]
	v_mfma_f32_16x16x32_bf16 v[64:67], v[206:209], v[190:193], v[64:67]
	v_mfma_f32_16x16x32_bf16 v[104:107], v[202:205], v[170:173], v[104:107]
	v_mfma_f32_16x16x32_bf16 v[96:99], v[210:213], v[170:173], v[96:99]
	v_mfma_f32_16x16x32_bf16 v[92:95], v[202:205], v[178:181], v[92:95]
	v_mfma_f32_16x16x32_bf16 v[88:91], v[210:213], v[178:181], v[88:91]
	v_mfma_f32_16x16x32_bf16 v[84:87], v[202:205], v[186:189], v[84:87]
	v_mfma_f32_16x16x32_bf16 v[80:83], v[210:213], v[186:189], v[80:83]
	v_mfma_f32_16x16x32_bf16 v[68:71], v[202:205], v[194:197], v[68:71]
	v_mfma_f32_16x16x32_bf16 v[64:67], v[210:213], v[194:197], v[64:67]
	s_setprio 0
	s_mov_b32 m0, s17
	v_lshl_add_u64 v[218:219], s[56:57], 0, v[150:151]
	s_barrier
	ds_read_b128 v[166:169], v164 offset:16384
	ds_read_b128 v[170:173], v164 offset:17408
	ds_read_b128 v[174:177], v164 offset:18432
	ds_read_b128 v[178:181], v164 offset:19456
	ds_read_b128 v[182:185], v164 offset:20480
	ds_read_b128 v[186:189], v164 offset:21504
	ds_read_b128 v[190:193], v164 offset:22528
	ds_read_b128 v[194:197], v164 offset:23552
	global_load_lds_dwordx4 v[218:219], off
	v_lshl_add_u64 v[220:221], s[56:57], 0, v[146:147]
	s_mov_b32 m0, s19
	s_nop 0
	global_load_lds_dwordx4 v[220:221], off
	s_barrier
	s_waitcnt lgkmcnt(0)
	s_setprio 1
	s_waitcnt lgkmcnt(0)
	v_mfma_f32_16x16x32_bf16 v[60:63], v[128:131], v[166:169], v[60:63]
	v_mfma_f32_16x16x32_bf16 v[56:59], v[136:139], v[166:169], v[56:59]
	v_mfma_f32_16x16x32_bf16 v[52:55], v[128:131], v[174:177], v[52:55]
	v_mfma_f32_16x16x32_bf16 v[44:47], v[136:139], v[174:177], v[44:47]
	v_mfma_f32_16x16x32_bf16 v[36:39], v[128:131], v[182:185], v[36:39]
	v_mfma_f32_16x16x32_bf16 v[28:31], v[136:139], v[182:185], v[28:31]
	v_mfma_f32_16x16x32_bf16 v[20:23], v[128:131], v[190:193], v[20:23]
	v_mfma_f32_16x16x32_bf16 v[12:15], v[136:139], v[190:193], v[12:15]
	v_mfma_f32_16x16x32_bf16 v[60:63], v[132:135], v[170:173], v[60:63]
	v_mfma_f32_16x16x32_bf16 v[56:59], v[140:143], v[170:173], v[56:59]
	v_mfma_f32_16x16x32_bf16 v[52:55], v[132:135], v[178:181], v[52:55]
	v_mfma_f32_16x16x32_bf16 v[44:47], v[140:143], v[178:181], v[44:47]
	v_mfma_f32_16x16x32_bf16 v[36:39], v[132:135], v[186:189], v[36:39]
	v_mfma_f32_16x16x32_bf16 v[28:31], v[140:143], v[186:189], v[28:31]
	v_mfma_f32_16x16x32_bf16 v[20:23], v[132:135], v[194:197], v[20:23]
	v_mfma_f32_16x16x32_bf16 v[12:15], v[140:143], v[194:197], v[12:15]
	s_setprio 0
	s_barrier
	s_add_u32 s72, s54, 0x40000
	s_addc_u32 s73, s55, 0
	s_add_i32 s18, s60, s16
	v_lshl_add_u64 v[128:129], s[72:73], 0, v[148:149]
	s_mov_b32 m0, s18
	s_nop 0
	global_load_lds_dwordx4 v[128:129], off
	v_lshl_add_u64 v[128:129], s[72:73], 0, v[144:145]
	s_add_i32 m0, s18, 0x2000
	s_nop 0
	global_load_lds_dwordx4 v[128:129], off
	s_waitcnt vmcnt(6)
	s_barrier
	s_setprio 1
	v_mfma_f32_16x16x32_bf16 v[48:51], v[198:201], v[166:169], v[48:51]
	v_mfma_f32_16x16x32_bf16 v[40:43], v[206:209], v[166:169], v[40:43]
	v_mfma_f32_16x16x32_bf16 v[32:35], v[198:201], v[174:177], v[32:35]
	v_mfma_f32_16x16x32_bf16 v[24:27], v[206:209], v[174:177], v[24:27]
	v_mfma_f32_16x16x32_bf16 v[16:19], v[198:201], v[182:185], v[16:19]
	v_mfma_f32_16x16x32_bf16 v[8:11], v[206:209], v[182:185], v[8:11]
	v_mfma_f32_16x16x32_bf16 v[4:7], v[198:201], v[190:193], v[4:7]
	v_mfma_f32_16x16x32_bf16 v[0:3], v[206:209], v[190:193], v[0:3]
	v_mfma_f32_16x16x32_bf16 v[48:51], v[202:205], v[170:173], v[48:51]
	v_mfma_f32_16x16x32_bf16 v[40:43], v[210:213], v[170:173], v[40:43]
	v_mfma_f32_16x16x32_bf16 v[32:35], v[202:205], v[178:181], v[32:35]
	v_mfma_f32_16x16x32_bf16 v[24:27], v[210:213], v[178:181], v[24:27]
	v_mfma_f32_16x16x32_bf16 v[16:19], v[202:205], v[186:189], v[16:19]
	v_mfma_f32_16x16x32_bf16 v[8:11], v[210:213], v[186:189], v[8:11]
	v_mfma_f32_16x16x32_bf16 v[4:7], v[202:205], v[194:197], v[4:7]
	v_mfma_f32_16x16x32_bf16 v[0:3], v[210:213], v[194:197], v[0:3]
	s_setprio 0
	s_add_i32 s18, 0, 0x18000
	v_add_u32_e32 v140, s18, v161
	s_barrier
	ds_read_b128 v[128:131], v140
	ds_read_b128 v[132:135], v140 offset:1024
	ds_read_b128 v[136:139], v140 offset:2048
	ds_read_b128 v[140:143], v140 offset:3072
	s_add_u32 s56, s56, 0x40000
	s_addc_u32 s57, s57, 0
	s_mov_b32 m0, s28
	v_lshl_add_u64 v[198:199], s[56:57], 0, v[150:151]
	ds_read_b128 v[166:169], v164 offset:32768
	ds_read_b128 v[170:173], v164 offset:33792
	ds_read_b128 v[174:177], v164 offset:34816
	ds_read_b128 v[178:181], v164 offset:35840
	ds_read_b128 v[182:185], v164 offset:36864
	ds_read_b128 v[186:189], v164 offset:37888
	ds_read_b128 v[190:193], v164 offset:38912
	ds_read_b128 v[194:197], v164 offset:39936
	global_load_lds_dwordx4 v[198:199], off
	v_lshl_add_u64 v[198:199], s[56:57], 0, v[146:147]
	s_mov_b32 m0, s29
	s_nop 0
	global_load_lds_dwordx4 v[198:199], off
	s_waitcnt lgkmcnt(8)
	s_barrier
	s_waitcnt lgkmcnt(0)
	s_setprio 1
	s_waitcnt lgkmcnt(0)
	v_mfma_f32_16x16x32_bf16 v[124:127], v[128:131], v[166:169], v[124:127]
	v_mfma_f32_16x16x32_bf16 v[120:123], v[136:139], v[166:169], v[120:123]
	v_mfma_f32_16x16x32_bf16 v[116:119], v[128:131], v[174:177], v[116:119]
	v_mfma_f32_16x16x32_bf16 v[112:115], v[136:139], v[174:177], v[112:115]
	v_mfma_f32_16x16x32_bf16 v[108:111], v[128:131], v[182:185], v[108:111]
	v_mfma_f32_16x16x32_bf16 v[100:103], v[136:139], v[182:185], v[100:103]
	v_mfma_f32_16x16x32_bf16 v[76:79], v[128:131], v[190:193], v[76:79]
	v_mfma_f32_16x16x32_bf16 v[72:75], v[136:139], v[190:193], v[72:75]
	v_mfma_f32_16x16x32_bf16 v[124:127], v[132:135], v[170:173], v[124:127]
	v_mfma_f32_16x16x32_bf16 v[120:123], v[140:143], v[170:173], v[120:123]
	v_mfma_f32_16x16x32_bf16 v[116:119], v[132:135], v[178:181], v[116:119]
	v_mfma_f32_16x16x32_bf16 v[112:115], v[140:143], v[178:181], v[112:115]
	v_mfma_f32_16x16x32_bf16 v[108:111], v[132:135], v[186:189], v[108:111]
	v_mfma_f32_16x16x32_bf16 v[100:103], v[140:143], v[186:189], v[100:103]
	v_mfma_f32_16x16x32_bf16 v[76:79], v[132:135], v[194:197], v[76:79]
	v_mfma_f32_16x16x32_bf16 v[72:75], v[140:143], v[194:197], v[72:75]
	s_setprio 0
	s_barrier
	s_add_i32 s56, 0, 0x1c000
	s_add_i32 s18, s18, s16
	v_add_u32_e32 v210, s56, v161
	v_lshl_add_u64 v[214:215], v[214:215], 0, s[12:13]
	s_mov_b32 m0, s18
	ds_read_b128 v[198:201], v210
	ds_read_b128 v[202:205], v210 offset:1024
	ds_read_b128 v[206:209], v210 offset:2048
	ds_read_b128 v[210:213], v210 offset:3072
	global_load_lds_dwordx4 v[214:215], off
	v_lshl_add_u64 v[214:215], v[216:217], 0, s[12:13]
	s_add_i32 m0, s18, 0x2000
	s_nop 0
	global_load_lds_dwordx4 v[214:215], off
	s_barrier
	s_waitcnt lgkmcnt(0)
	s_setprio 1
	s_waitcnt lgkmcnt(0)
	v_mfma_f32_16x16x32_bf16 v[104:107], v[198:201], v[166:169], v[104:107]
	v_mfma_f32_16x16x32_bf16 v[96:99], v[206:209], v[166:169], v[96:99]
	v_mfma_f32_16x16x32_bf16 v[92:95], v[198:201], v[174:177], v[92:95]
	v_mfma_f32_16x16x32_bf16 v[88:91], v[206:209], v[174:177], v[88:91]
	v_mfma_f32_16x16x32_bf16 v[84:87], v[198:201], v[182:185], v[84:87]
	v_mfma_f32_16x16x32_bf16 v[80:83], v[206:209], v[182:185], v[80:83]
	v_mfma_f32_16x16x32_bf16 v[68:71], v[198:201], v[190:193], v[68:71]
	v_mfma_f32_16x16x32_bf16 v[64:67], v[206:209], v[190:193], v[64:67]
	v_mfma_f32_16x16x32_bf16 v[104:107], v[202:205], v[170:173], v[104:107]
	v_mfma_f32_16x16x32_bf16 v[96:99], v[210:213], v[170:173], v[96:99]
	v_mfma_f32_16x16x32_bf16 v[92:95], v[202:205], v[178:181], v[92:95]
	v_mfma_f32_16x16x32_bf16 v[88:91], v[210:213], v[178:181], v[88:91]
	v_mfma_f32_16x16x32_bf16 v[84:87], v[202:205], v[186:189], v[84:87]
	v_mfma_f32_16x16x32_bf16 v[80:83], v[210:213], v[186:189], v[80:83]
	v_mfma_f32_16x16x32_bf16 v[68:71], v[202:205], v[194:197], v[68:71]
	v_mfma_f32_16x16x32_bf16 v[64:67], v[210:213], v[194:197], v[64:67]
	s_setprio 0
	s_mov_b32 m0, s51
	v_lshl_add_u64 v[214:215], v[218:219], 0, s[12:13]
	s_barrier
	ds_read_b128 v[166:169], v164 offset:49152
	ds_read_b128 v[170:173], v164 offset:50176
	ds_read_b128 v[174:177], v164 offset:51200
	ds_read_b128 v[178:181], v164 offset:52224
	ds_read_b128 v[182:185], v164 offset:53248
	ds_read_b128 v[186:189], v164 offset:54272
	ds_read_b128 v[190:193], v164 offset:55296
	ds_read_b128 v[194:197], v164 offset:56320
	global_load_lds_dwordx4 v[214:215], off
	v_lshl_add_u64 v[214:215], v[220:221], 0, s[12:13]
	s_mov_b32 m0, s58
	s_nop 0
	global_load_lds_dwordx4 v[214:215], off
	s_barrier
	s_waitcnt lgkmcnt(0)
	s_setprio 1
	s_waitcnt lgkmcnt(0)
	v_mfma_f32_16x16x32_bf16 v[60:63], v[128:131], v[166:169], v[60:63]
	v_mfma_f32_16x16x32_bf16 v[56:59], v[136:139], v[166:169], v[56:59]
	v_mfma_f32_16x16x32_bf16 v[52:55], v[128:131], v[174:177], v[52:55]
	v_mfma_f32_16x16x32_bf16 v[44:47], v[136:139], v[174:177], v[44:47]
	v_mfma_f32_16x16x32_bf16 v[36:39], v[128:131], v[182:185], v[36:39]
	v_mfma_f32_16x16x32_bf16 v[28:31], v[136:139], v[182:185], v[28:31]
	v_mfma_f32_16x16x32_bf16 v[20:23], v[128:131], v[190:193], v[20:23]
	v_mfma_f32_16x16x32_bf16 v[12:15], v[136:139], v[190:193], v[12:15]
	v_mfma_f32_16x16x32_bf16 v[60:63], v[132:135], v[170:173], v[60:63]
	v_mfma_f32_16x16x32_bf16 v[56:59], v[140:143], v[170:173], v[56:59]
	v_mfma_f32_16x16x32_bf16 v[52:55], v[132:135], v[178:181], v[52:55]
	v_mfma_f32_16x16x32_bf16 v[44:47], v[140:143], v[178:181], v[44:47]
	v_mfma_f32_16x16x32_bf16 v[36:39], v[132:135], v[186:189], v[36:39]
	v_mfma_f32_16x16x32_bf16 v[28:31], v[140:143], v[186:189], v[28:31]
	v_mfma_f32_16x16x32_bf16 v[20:23], v[132:135], v[194:197], v[20:23]
	v_mfma_f32_16x16x32_bf16 v[12:15], v[140:143], v[194:197], v[12:15]
	s_setprio 0
	s_barrier
	s_add_u32 s54, s54, 0x40080
	s_addc_u32 s55, s55, 0
	s_add_i32 s18, s56, s16
	v_lshl_add_u64 v[128:129], s[54:55], 0, v[148:149]
	s_mov_b32 m0, s18
	s_nop 0
	global_load_lds_dwordx4 v[128:129], off
	v_lshl_add_u64 v[128:129], s[54:55], 0, v[144:145]
	s_add_i32 m0, s18, 0x2000
	s_nop 0
	global_load_lds_dwordx4 v[128:129], off
	s_waitcnt vmcnt(6)
	s_barrier
	s_setprio 1
	v_mfma_f32_16x16x32_bf16 v[48:51], v[198:201], v[166:169], v[48:51]
	v_mfma_f32_16x16x32_bf16 v[40:43], v[206:209], v[166:169], v[40:43]
	v_mfma_f32_16x16x32_bf16 v[32:35], v[198:201], v[174:177], v[32:35]
	v_mfma_f32_16x16x32_bf16 v[24:27], v[206:209], v[174:177], v[24:27]
	v_mfma_f32_16x16x32_bf16 v[16:19], v[198:201], v[182:185], v[16:19]
	v_mfma_f32_16x16x32_bf16 v[8:11], v[206:209], v[182:185], v[8:11]
	v_mfma_f32_16x16x32_bf16 v[4:7], v[198:201], v[190:193], v[4:7]
	v_mfma_f32_16x16x32_bf16 v[0:3], v[206:209], v[190:193], v[0:3]
	v_mfma_f32_16x16x32_bf16 v[48:51], v[202:205], v[170:173], v[48:51]
	v_mfma_f32_16x16x32_bf16 v[40:43], v[210:213], v[170:173], v[40:43]
	v_mfma_f32_16x16x32_bf16 v[32:35], v[202:205], v[178:181], v[32:35]
	v_mfma_f32_16x16x32_bf16 v[24:27], v[210:213], v[178:181], v[24:27]
	v_mfma_f32_16x16x32_bf16 v[16:19], v[202:205], v[186:189], v[16:19]
	v_mfma_f32_16x16x32_bf16 v[8:11], v[210:213], v[186:189], v[8:11]
	v_mfma_f32_16x16x32_bf16 v[4:7], v[202:205], v[194:197], v[4:7]
	v_mfma_f32_16x16x32_bf16 v[0:3], v[210:213], v[194:197], v[0:3]
	s_setprio 0
	s_add_i32 s71, s71, 2
	s_add_u32 s52, s52, 0x100
	s_addc_u32 s53, s53, 0
	s_add_u32 s69, s69, 0x100
	s_addc_u32 s70, s70, 0
	s_cmp_gt_u32 s71, 13
	s_barrier
	s_cbranch_scc0 .LBB0_1499
	s_sub_i32 s18, s50, 32
	s_lshr_b32 s18, s18, 2
	s_mulk_i32 s18, 0xc00
	s_addk_i32 s18, 0xc00
	s_cmp_gt_i32 s50, 31
	s_cselect_b32 s52, s18, 0
	s_ashr_i32 s53, s52, 31
	s_lshl_b64 s[52:53], s[52:53], 2
	v_lshl_or_b32 v166, s66, 8, v162
	s_add_u32 s52, s24, s52
	s_addc_u32 s53, s25, s53
	v_ashrrev_i32_e32 v167, 31, v166
	v_lshl_add_u64 v[128:129], v[166:167], 2, s[52:53]
	v_add_co_u32_e32 v130, vcc, s61, v128
	v_lshl_add_u32 v168, s50, 8, v160
	s_nop 0
	v_addc_co_u32_e32 v131, vcc, 0, v129, vcc
	global_load_dwordx4 v[140:143], v[130:131], off
	v_lshl_add_u64 v[128:129], v[128:129], 0, s[14:15]
	global_load_dwordx4 v[136:139], v[128:129], off offset:16
	global_load_dwordx4 v[132:135], v[128:129], off offset:512
	s_nop 0
	global_load_dwordx4 v[128:131], v[128:129], off offset:528
	v_ashrrev_i32_e32 v169, 31, v168
	v_or_b32_e32 v170, 16, v168
	v_or_b32_e32 v172, 32, v168
	v_or_b32_e32 v174, 48, v168
	v_lshlrev_b64 v[168:169], 11, v[168:169]
	v_ashrrev_i32_e32 v171, 31, v170
	v_ashrrev_i32_e32 v173, 31, v172
	v_lshlrev_b64 v[166:167], 1, v[166:167]
	v_ashrrev_i32_e32 v175, 31, v174
	v_lshl_add_u64 v[168:169], s[4:5], 0, v[168:169]
	v_lshlrev_b64 v[170:171], 11, v[170:171]
	v_lshlrev_b64 v[172:173], 11, v[172:173]
	v_lshlrev_b64 v[174:175], 11, v[174:175]
	v_lshl_add_u64 v[168:169], v[168:169], 0, v[166:167]
	v_lshl_add_u64 v[170:171], s[4:5], 0, v[170:171]
	v_lshl_add_u64 v[172:173], s[4:5], 0, v[172:173]
	v_lshl_add_u64 v[170:171], v[170:171], 0, v[166:167]
	v_lshl_add_u64 v[172:173], v[172:173], 0, v[166:167]
	s_mov_b32 s66, s42
	s_mov_b32 s50, s44
	s_mov_b64 s[54:55], s[48:49]
	s_mov_b64 s[52:53], s[46:47]
	s_waitcnt vmcnt(0)
	v_pk_mul_f32 v[122:123], v[122:123], v[138:139]
	v_pk_mul_f32 v[126:127], v[126:127], v[142:143]
	v_pk_mul_f32 v[124:125], v[124:125], v[140:141]
	v_pk_mul_f32 v[120:121], v[120:121], v[136:137]
	v_pk_mul_f32 v[106:107], v[106:107], v[134:135]
	v_pk_mul_f32 v[104:105], v[104:105], v[132:133]
	v_pk_mul_f32 v[98:99], v[98:99], v[130:131]
	v_pk_mul_f32 v[96:97], v[96:97], v[128:129]
	v_pk_mul_f32 v[118:119], v[118:119], v[142:143]
	v_pk_mul_f32 v[116:117], v[116:117], v[140:141]
	v_pk_mul_f32 v[114:115], v[114:115], v[138:139]
	v_pk_mul_f32 v[112:113], v[112:113], v[136:137]
	v_pk_mul_f32 v[94:95], v[94:95], v[134:135]
	v_pk_mul_f32 v[92:93], v[92:93], v[132:133]
	v_pk_mul_f32 v[176:177], v[90:91], v[130:131]
	v_pk_mul_f32 v[178:179], v[88:89], v[128:129]
	v_pk_mul_f32 v[110:111], v[110:111], v[142:143]
	v_pk_mul_f32 v[108:109], v[108:109], v[140:141]
	v_pk_mul_f32 v[102:103], v[102:103], v[138:139]
	v_pk_mul_f32 v[100:101], v[100:101], v[136:137]
	v_pk_mul_f32 v[180:181], v[86:87], v[134:135]
	v_pk_mul_f32 v[182:183], v[84:85], v[132:133]
	v_pk_mul_f32 v[184:185], v[82:83], v[130:131]
	v_pk_mul_f32 v[186:187], v[80:81], v[128:129]
	v_cvt_pk_bf16_f32 v80, v124, v125
	v_cvt_pk_bf16_f32 v81, v126, v127
	v_cvt_pk_bf16_f32 v82, v120, v121
	v_cvt_pk_bf16_f32 v83, v122, v123
	v_cvt_pk_bf16_f32 v84, v104, v105
	v_cvt_pk_bf16_f32 v85, v106, v107
	v_cvt_pk_bf16_f32 v86, v96, v97
	v_cvt_pk_bf16_f32 v87, v98, v99
	v_cvt_pk_bf16_f32 v88, v116, v117
	v_cvt_pk_bf16_f32 v89, v118, v119
	v_cvt_pk_bf16_f32 v90, v112, v113
	v_cvt_pk_bf16_f32 v91, v114, v115
	v_cvt_pk_bf16_f32 v92, v92, v93
	v_cvt_pk_bf16_f32 v93, v94, v95
	v_cvt_pk_bf16_f32 v94, v178, v179
	v_cvt_pk_bf16_f32 v95, v176, v177
	v_cvt_pk_bf16_f32 v96, v108, v109
	v_cvt_pk_bf16_f32 v97, v110, v111
	v_cvt_pk_bf16_f32 v98, v100, v101
	v_cvt_pk_bf16_f32 v99, v102, v103
	v_cvt_pk_bf16_f32 v100, v182, v183
	v_cvt_pk_bf16_f32 v101, v180, v181
	v_cvt_pk_bf16_f32 v102, v186, v187
	v_cvt_pk_bf16_f32 v103, v184, v185
	global_store_dwordx4 v[168:169], v[80:83], off sc1
	global_store_dwordx4 v[168:169], v[84:87], off offset:256 sc1
	global_store_dwordx4 v[170:171], v[88:91], off sc1
	global_store_dwordx4 v[170:171], v[92:95], off offset:256 sc1
	global_store_dwordx4 v[172:173], v[96:99], off sc1
	global_store_dwordx4 v[172:173], v[100:103], off offset:256 sc1
	v_lshl_add_u64 v[80:81], s[4:5], 0, v[174:175]
	v_pk_mul_f32 v[78:79], v[78:79], v[142:143]
	v_pk_mul_f32 v[76:77], v[76:77], v[140:141]
	v_pk_mul_f32 v[82:83], v[74:75], v[138:139]
	v_pk_mul_f32 v[74:75], v[72:73], v[136:137]
	v_lshl_add_u64 v[80:81], v[80:81], 0, v[166:167]
	v_cvt_pk_bf16_f32 v72, v76, v77
	v_cvt_pk_bf16_f32 v73, v78, v79
	v_cvt_pk_bf16_f32 v74, v74, v75
	v_cvt_pk_bf16_f32 v75, v82, v83
	global_store_dwordx4 v[80:81], v[72:75], off sc1
	v_pk_mul_f32 v[70:71], v[70:71], v[134:135]
	v_pk_mul_f32 v[68:69], v[68:69], v[132:133]
	v_pk_mul_f32 v[72:73], v[66:67], v[130:131]
	v_pk_mul_f32 v[66:67], v[64:65], v[128:129]
	v_cvt_pk_bf16_f32 v64, v68, v69
	v_cvt_pk_bf16_f32 v65, v70, v71
	v_cvt_pk_bf16_f32 v66, v66, v67
	v_cvt_pk_bf16_f32 v67, v72, v73
	v_pk_mul_f32 v[60:61], v[60:61], v[140:141]
	global_store_dwordx4 v[80:81], v[64:67], off offset:256 sc1
	v_pk_mul_f32 v[62:63], v[62:63], v[142:143]
	v_pk_mul_f32 v[50:51], v[50:51], v[134:135]
	v_pk_mul_f32 v[66:67], v[58:59], v[138:139]
	v_pk_mul_f32 v[58:59], v[56:57], v[136:137]
	v_cvt_pk_bf16_f32 v56, v60, v61
	v_add_co_u32_e32 v60, vcc, s62, v168
	v_cvt_pk_bf16_f32 v57, v62, v63
	v_cvt_pk_bf16_f32 v58, v58, v59
	v_cvt_pk_bf16_f32 v59, v66, v67
	v_addc_co_u32_e32 v61, vcc, 0, v169, vcc
	global_store_dwordx4 v[60:61], v[56:59], off sc1
	v_pk_mul_f32 v[48:49], v[48:49], v[132:133]
	v_lshl_add_u64 v[64:65], v[168:169], 0, s[6:7]
	v_pk_mul_f32 v[56:57], v[42:43], v[130:131]
	v_pk_mul_f32 v[42:43], v[40:41], v[128:129]
	v_cvt_pk_bf16_f32 v40, v48, v49
	v_cvt_pk_bf16_f32 v41, v50, v51
	v_cvt_pk_bf16_f32 v42, v42, v43
	v_cvt_pk_bf16_f32 v43, v56, v57
	global_store_dwordx4 v[64:65], v[40:43], off offset:256 sc1
	v_pk_mul_f32 v[44:45], v[44:45], v[136:137]
	v_pk_mul_f32 v[46:47], v[46:47], v[138:139]
	v_pk_mul_f32 v[42:43], v[54:55], v[142:143]
	v_pk_mul_f32 v[40:41], v[52:53], v[140:141]
	v_pk_mul_f32 v[34:35], v[34:35], v[134:135]
	v_cvt_pk_bf16_f32 v40, v40, v41
	v_cvt_pk_bf16_f32 v41, v42, v43
	v_cvt_pk_bf16_f32 v42, v44, v45
	v_add_co_u32_e32 v44, vcc, s63, v168
	v_cvt_pk_bf16_f32 v43, v46, v47
	s_nop 0
	v_addc_co_u32_e32 v45, vcc, 0, v169, vcc
	global_store_dwordx4 v[44:45], v[40:43], off sc1
	v_pk_mul_f32 v[32:33], v[32:33], v[132:133]
	v_lshl_add_u64 v[48:49], v[168:169], 0, s[36:37]
	v_pk_mul_f32 v[40:41], v[26:27], v[130:131]
	v_pk_mul_f32 v[26:27], v[24:25], v[128:129]
	v_cvt_pk_bf16_f32 v24, v32, v33
	v_cvt_pk_bf16_f32 v25, v34, v35
	v_cvt_pk_bf16_f32 v26, v26, v27
	v_cvt_pk_bf16_f32 v27, v40, v41
	global_store_dwordx4 v[48:49], v[24:27], off offset:256 sc1
	v_pk_mul_f32 v[28:29], v[28:29], v[136:137]
	v_pk_mul_f32 v[30:31], v[30:31], v[138:139]
	v_pk_mul_f32 v[26:27], v[38:39], v[142:143]
	v_pk_mul_f32 v[24:25], v[36:37], v[140:141]
	v_pk_mul_f32 v[18:19], v[18:19], v[134:135]
	v_cvt_pk_bf16_f32 v24, v24, v25
	v_cvt_pk_bf16_f32 v25, v26, v27
	v_cvt_pk_bf16_f32 v26, v28, v29
	v_add_co_u32_e32 v28, vcc, s64, v168
	v_cvt_pk_bf16_f32 v27, v30, v31
	s_nop 0
	v_addc_co_u32_e32 v29, vcc, 0, v169, vcc
	global_store_dwordx4 v[28:29], v[24:27], off sc1
	v_pk_mul_f32 v[16:17], v[16:17], v[132:133]
	v_lshl_add_u64 v[32:33], v[168:169], 0, s[38:39]
	v_pk_mul_f32 v[24:25], v[10:11], v[130:131]
	v_pk_mul_f32 v[10:11], v[8:9], v[128:129]
	v_cvt_pk_bf16_f32 v8, v16, v17
	v_cvt_pk_bf16_f32 v9, v18, v19
	v_cvt_pk_bf16_f32 v10, v10, v11
	v_cvt_pk_bf16_f32 v11, v24, v25
	global_store_dwordx4 v[32:33], v[8:11], off offset:256 sc1
	v_pk_mul_f32 v[12:13], v[12:13], v[136:137]
	v_pk_mul_f32 v[14:15], v[14:15], v[138:139]
	v_pk_mul_f32 v[10:11], v[22:23], v[142:143]
	v_pk_mul_f32 v[8:9], v[20:21], v[140:141]
	v_pk_mul_f32 v[6:7], v[6:7], v[134:135]
	v_cvt_pk_bf16_f32 v8, v8, v9
	v_cvt_pk_bf16_f32 v9, v10, v11
	v_cvt_pk_bf16_f32 v10, v12, v13
	v_add_co_u32_e32 v12, vcc, s65, v168
	v_cvt_pk_bf16_f32 v11, v14, v15
	s_nop 0
	v_addc_co_u32_e32 v13, vcc, 0, v169, vcc
	global_store_dwordx4 v[12:13], v[8:11], off sc1
	v_pk_mul_f32 v[4:5], v[4:5], v[132:133]
	v_lshl_add_u64 v[16:17], v[168:169], 0, s[40:41]
	v_pk_mul_f32 v[8:9], v[2:3], v[130:131]
	v_pk_mul_f32 v[2:3], v[0:1], v[128:129]
	v_cvt_pk_bf16_f32 v0, v4, v5
	v_cvt_pk_bf16_f32 v1, v6, v7
	v_cvt_pk_bf16_f32 v2, v2, v3
	v_cvt_pk_bf16_f32 v3, v8, v9
	s_and_b64 vcc, exec, s[0:1]
	global_store_dwordx4 v[16:17], v[0:3], off offset:256 sc1
	s_cbranch_vccz .LBB0_1496
	s_waitcnt vmcnt(0)
	s_cmpk_gt_u32 s3, 0xff
	s_cbranch_scc1 .LBB0_1503
	s_barrier
